# g16 + all v_pk_{fma,mul,add}_f32 un-packed into scalar f32 pairs (packed f32 is slower beside partner-wave MFMAs); bit-identical math
# baseline (speedup 1.0000x reference)
; DI void phase0(const Params& p, int bid, int nblk, unsigned char* smem) {
;     ...
; #pragma unroll 4
;       for (int kk = 0; kk < 128; ++kk) {
;         const float w = p.ada_w[(size_t)(kc * 128 + kk) * 6144 + n];
; #pragma unroll
;         for (int b = 0; b < 32; ++b) acc[b] += sc[b * 128 + kk] * w;
;       }
.LBB0_30:
	v_lshl_add_u64 v[38:39], v[10:11], 0, s[4:5]
	v_add_co_u32_e32 v176, vcc, s33, v38
	global_load_dword v174, v[38:39], off
	s_nop 0
	v_addc_co_u32_e32 v177, vcc, 0, v39, vcc
	v_add_co_u32_e32 v178, vcc, s34, v38
	v_mov_b32_e32 v170, s24
	s_nop 0
	v_addc_co_u32_e32 v179, vcc, 0, v39, vcc
	v_add_co_u32_e32 v38, vcc, s35, v38
	ds_read_b128 v[46:49], v170
	ds_read_b128 v[50:53], v170 offset:512
	ds_read_b128 v[54:57], v170 offset:1024
	ds_read_b128 v[58:61], v170 offset:1536
	ds_read_b128 v[62:65], v170 offset:2048
	ds_read_b128 v[66:69], v170 offset:2560
	ds_read_b128 v[70:73], v170 offset:3072
	ds_read_b128 v[74:77], v170 offset:3584
	ds_read_b128 v[78:81], v170 offset:4096
	ds_read_b128 v[82:85], v170 offset:4608
	ds_read_b128 v[86:89], v170 offset:5120
	ds_read_b128 v[90:93], v170 offset:5632
	ds_read_b128 v[94:97], v170 offset:6144
	ds_read_b128 v[98:101], v170 offset:6656
	ds_read_b128 v[102:105], v170 offset:7168
	ds_read_b128 v[106:109], v170 offset:7680
	ds_read_b128 v[110:113], v170 offset:8192
	ds_read_b128 v[114:117], v170 offset:8704
	ds_read_b128 v[118:121], v170 offset:9216
	ds_read_b128 v[122:125], v170 offset:9728
	ds_read_b128 v[126:129], v170 offset:10240
	ds_read_b128 v[130:133], v170 offset:10752
	ds_read_b128 v[134:137], v170 offset:11264
	ds_read_b128 v[138:141], v170 offset:11776
	ds_read_b128 v[142:145], v170 offset:12288
	ds_read_b128 v[146:149], v170 offset:12800
	ds_read_b128 v[150:153], v170 offset:13312
	ds_read_b128 v[154:157], v170 offset:13824
	ds_read_b128 v[158:161], v170 offset:14336
	ds_read_b128 v[162:165], v170 offset:14848
	ds_read_b128 v[166:169], v170 offset:15360
	ds_read_b128 v[170:173], v170 offset:15872
	v_addc_co_u32_e32 v39, vcc, 0, v39, vcc
	global_load_dword v176, v[176:177], off
	s_nop 0
	global_load_dword v178, v[178:179], off
	s_nop 0
	global_load_dword v38, v[38:39], off
	s_waitcnt lgkmcnt(14)
	v_mov_b32_e32 v180, v46
	v_mov_b32_e32 v181, v50
	v_mov_b32_e32 v182, v54
	v_mov_b32_e32 v183, v58
	v_mov_b32_e32 v184, v62
	v_mov_b32_e32 v185, v66
	v_mov_b32_e32 v186, v70
	v_mov_b32_e32 v187, v74
	v_mov_b32_e32 v188, v78
	v_mov_b32_e32 v189, v82
	v_mov_b32_e32 v190, v86
	v_mov_b32_e32 v191, v90
	v_mov_b32_e32 v192, v94
	v_mov_b32_e32 v193, v98
	v_mov_b32_e32 v194, v102
	v_mov_b32_e32 v195, v106
	v_mov_b32_e32 v196, v110
	v_mov_b32_e32 v197, v114
	s_waitcnt lgkmcnt(13)
	v_mov_b32_e32 v198, v118
	s_waitcnt lgkmcnt(12)
	v_mov_b32_e32 v199, v122
	s_waitcnt lgkmcnt(11)
	v_mov_b32_e32 v200, v126
	s_waitcnt lgkmcnt(10)
	v_mov_b32_e32 v201, v130
	s_waitcnt lgkmcnt(9)
	v_mov_b32_e32 v202, v134
	s_waitcnt lgkmcnt(8)
	v_mov_b32_e32 v203, v138
	s_waitcnt lgkmcnt(7)
	v_mov_b32_e32 v204, v142
	s_waitcnt lgkmcnt(6)
	v_mov_b32_e32 v205, v146
	s_waitcnt lgkmcnt(5)
	v_mov_b32_e32 v206, v150
	s_waitcnt lgkmcnt(4)
	v_mov_b32_e32 v207, v154
	s_waitcnt lgkmcnt(3)
	v_mov_b32_e32 v208, v158
	s_waitcnt lgkmcnt(2)
	v_mov_b32_e32 v209, v162
	s_waitcnt lgkmcnt(1)
	v_mov_b32_e32 v210, v166
	s_waitcnt lgkmcnt(0)
	v_mov_b32_e32 v211, v170
	v_mov_b32_e32 v50, v47
	v_mov_b32_e32 v58, v55
	v_mov_b32_e32 v66, v63
	v_mov_b32_e32 v74, v71
	v_mov_b32_e32 v82, v79
	v_mov_b32_e32 v90, v87
	v_mov_b32_e32 v98, v95
	v_mov_b32_e32 v106, v103
	v_mov_b32_e32 v114, v111
	v_mov_b32_e32 v122, v119
	v_mov_b32_e32 v130, v127
	v_mov_b32_e32 v138, v135
	v_mov_b32_e32 v146, v143
	v_mov_b32_e32 v154, v151
	v_mov_b32_e32 v162, v159
	v_mov_b32_e32 v170, v167
	s_add_u32 s4, s4, 0x18000
	v_mov_b32_e32 v46, v48
	v_mov_b32_e32 v47, v52
	v_mov_b32_e32 v54, v56
	v_mov_b32_e32 v55, v60
	v_mov_b32_e32 v62, v64
	v_mov_b32_e32 v63, v68
	v_mov_b32_e32 v70, v72
	v_mov_b32_e32 v71, v76
	v_mov_b32_e32 v78, v80
	v_mov_b32_e32 v79, v84
	v_mov_b32_e32 v86, v88
	v_mov_b32_e32 v87, v92
	v_mov_b32_e32 v94, v96
	v_mov_b32_e32 v95, v100
	v_mov_b32_e32 v102, v104
	v_mov_b32_e32 v103, v108
	v_mov_b32_e32 v110, v112
	s_waitcnt vmcnt(3)
	v_fma_f32 v36, v174, v180, v36
	v_fma_f32 v37, v174, v181, v37
	v_fma_f32 v34, v174, v182, v34
	v_fma_f32 v35, v174, v183, v35
	v_fma_f32 v32, v174, v184, v32
	v_fma_f32 v33, v174, v185, v33
	v_fma_f32 v30, v174, v186, v30
	v_fma_f32 v31, v174, v187, v31
	v_fma_f32 v28, v174, v188, v28
	v_fma_f32 v29, v174, v189, v29
	v_fma_f32 v26, v174, v190, v26
	v_fma_f32 v27, v174, v191, v27
	v_fma_f32 v24, v174, v192, v24
	v_fma_f32 v25, v174, v193, v25
	v_fma_f32 v22, v174, v194, v22
	v_fma_f32 v23, v174, v195, v23
	v_fma_f32 v20, v174, v196, v20
	v_fma_f32 v21, v174, v197, v21
	v_fma_f32 v18, v174, v198, v18
	v_fma_f32 v19, v174, v199, v19
	v_fma_f32 v16, v174, v200, v16
	v_fma_f32 v17, v174, v201, v17
	v_fma_f32 v14, v174, v202, v14
	v_fma_f32 v15, v174, v203, v15
	v_fma_f32 v12, v174, v204, v12
	v_fma_f32 v13, v174, v205, v13
	v_fma_f32 v8, v174, v206, v8
	v_fma_f32 v9, v174, v207, v9
	v_fma_f32 v6, v174, v208, v6
	v_fma_f32 v7, v174, v209, v7
	v_fma_f32 v0, v174, v210, v0
	v_fma_f32 v1, v174, v211, v1
	v_mov_b32_e32 v111, v116
	v_mov_b32_e32 v118, v120
	v_mov_b32_e32 v119, v124
	v_mov_b32_e32 v126, v128
	v_mov_b32_e32 v127, v132
	v_mov_b32_e32 v134, v136
	v_mov_b32_e32 v135, v140
	v_mov_b32_e32 v142, v144
	v_mov_b32_e32 v143, v148
	v_mov_b32_e32 v150, v152
	v_mov_b32_e32 v151, v156
	v_mov_b32_e32 v158, v160
	v_mov_b32_e32 v159, v164
	v_mov_b32_e32 v166, v168
	v_mov_b32_e32 v167, v172
	s_waitcnt vmcnt(2)
; DI void phase0(const Params& p, int bid, int nblk, unsigned char* smem) {
;     ...
; #pragma unroll 4
;       for (int kk = 0; kk < 128; ++kk) {
;         const float w = p.ada_w[(size_t)(kc * 128 + kk) * 6144 + n];
; #pragma unroll
;         for (int b = 0; b < 32; ++b) acc[b] += sc[b * 128 + kk] * w;
;       }
	v_fma_f32 v36, v176, v50, v36
	v_fma_f32 v37, v176, v51, v37
	v_fma_f32 v34, v176, v58, v34
	v_fma_f32 v35, v176, v59, v35
	v_fma_f32 v32, v176, v66, v32
	v_fma_f32 v33, v176, v67, v33
	v_fma_f32 v30, v176, v74, v30
	v_fma_f32 v31, v176, v75, v31
	v_fma_f32 v28, v176, v82, v28
	v_fma_f32 v29, v176, v83, v29
	v_fma_f32 v26, v176, v90, v26
	v_fma_f32 v27, v176, v91, v27
	v_fma_f32 v24, v176, v98, v24
	v_fma_f32 v25, v176, v99, v25
	v_fma_f32 v22, v176, v106, v22
	v_fma_f32 v23, v176, v107, v23
	v_fma_f32 v20, v176, v114, v20
	v_fma_f32 v21, v176, v115, v21
	v_fma_f32 v18, v176, v122, v18
	v_fma_f32 v19, v176, v123, v19
	v_fma_f32 v16, v176, v130, v16
	v_fma_f32 v17, v176, v131, v17
	v_fma_f32 v14, v176, v138, v14
	v_fma_f32 v15, v176, v139, v15
	v_fma_f32 v12, v176, v146, v12
	v_fma_f32 v13, v176, v147, v13
	v_fma_f32 v8, v176, v154, v8
	v_fma_f32 v9, v176, v155, v9
	v_fma_f32 v6, v176, v162, v6
	v_fma_f32 v7, v176, v163, v7
	v_fma_f32 v0, v176, v170, v0
	v_fma_f32 v1, v176, v171, v1
	s_addc_u32 s5, s5, 0
	s_add_i32 s24, s24, 16
	v_mov_b32_e32 v52, v49
	v_mov_b32_e32 v60, v57
	v_mov_b32_e32 v68, v65
	v_mov_b32_e32 v76, v73
	v_mov_b32_e32 v84, v81
	v_mov_b32_e32 v92, v89
	v_mov_b32_e32 v100, v97
	v_mov_b32_e32 v108, v105
	v_mov_b32_e32 v116, v113
	v_mov_b32_e32 v124, v121
	v_mov_b32_e32 v132, v129
	v_mov_b32_e32 v140, v137
	v_mov_b32_e32 v148, v145
	v_mov_b32_e32 v156, v153
	v_mov_b32_e32 v164, v161
	v_mov_b32_e32 v172, v169
	s_waitcnt vmcnt(1)
	v_fma_f32 v36, v178, v46, v36
	v_fma_f32 v37, v178, v47, v37
	v_fma_f32 v34, v178, v54, v34
	v_fma_f32 v35, v178, v55, v35
	v_fma_f32 v32, v178, v62, v32
	v_fma_f32 v33, v178, v63, v33
	v_fma_f32 v30, v178, v70, v30
	v_fma_f32 v31, v178, v71, v31
	v_fma_f32 v28, v178, v78, v28
	v_fma_f32 v29, v178, v79, v29
	v_fma_f32 v26, v178, v86, v26
	v_fma_f32 v27, v178, v87, v27
	v_fma_f32 v24, v178, v94, v24
	v_fma_f32 v25, v178, v95, v25
	v_fma_f32 v22, v178, v102, v22
	v_fma_f32 v23, v178, v103, v23
	v_fma_f32 v20, v178, v110, v20
	v_fma_f32 v21, v178, v111, v21
	v_fma_f32 v18, v178, v118, v18
	v_fma_f32 v19, v178, v119, v19
	v_fma_f32 v16, v178, v126, v16
	v_fma_f32 v17, v178, v127, v17
	v_fma_f32 v14, v178, v134, v14
	v_fma_f32 v15, v178, v135, v15
	v_fma_f32 v12, v178, v142, v12
	v_fma_f32 v13, v178, v143, v13
	v_fma_f32 v8, v178, v150, v8
	v_fma_f32 v9, v178, v151, v9
	v_fma_f32 v6, v178, v158, v6
	v_fma_f32 v7, v178, v159, v7
	v_fma_f32 v0, v178, v166, v0
	v_fma_f32 v1, v178, v167, v1
	s_cmp_eq_u32 s4, 0x300000
	s_waitcnt vmcnt(0)
	v_fma_f32 v36, v38, v52, v36
	v_fma_f32 v37, v38, v53, v37
	v_fma_f32 v34, v38, v60, v34
	v_fma_f32 v35, v38, v61, v35
	v_fma_f32 v32, v38, v68, v32
	v_fma_f32 v33, v38, v69, v33
	v_fma_f32 v30, v38, v76, v30
	v_fma_f32 v31, v38, v77, v31
	v_fma_f32 v28, v38, v84, v28
	v_fma_f32 v29, v38, v85, v29
	v_fma_f32 v26, v38, v92, v26
	v_fma_f32 v27, v38, v93, v27
	v_fma_f32 v24, v38, v100, v24
	v_fma_f32 v25, v38, v101, v25
	v_fma_f32 v22, v38, v108, v22
	v_fma_f32 v23, v38, v109, v23
	v_fma_f32 v20, v38, v116, v20
	v_fma_f32 v21, v38, v117, v21
	v_fma_f32 v18, v38, v124, v18
	v_fma_f32 v19, v38, v125, v19
	v_fma_f32 v16, v38, v132, v16
	v_fma_f32 v17, v38, v133, v17
	v_fma_f32 v14, v38, v140, v14
	v_fma_f32 v15, v38, v141, v15
	v_fma_f32 v12, v38, v148, v12
	v_fma_f32 v13, v38, v149, v13
	v_fma_f32 v8, v38, v156, v8
	v_fma_f32 v9, v38, v157, v9
	v_fma_f32 v6, v38, v164, v6
	v_fma_f32 v7, v38, v165, v7
	v_fma_f32 v0, v38, v172, v0
	v_fma_f32 v1, v38, v173, v1
	s_cbranch_scc0 .LBB0_30
; DI void phase0(const Params& p, int bid, int nblk, unsigned char* smem) {
;     ...
;       float* mp = (float*)(p.ws + OFF_MODP);
; #pragma unroll
;       for (int b = 0; b < 32; ++b) mp[(size_t)(kc * 32 + b) * 6144 + n] = acc[b];
	s_lshl_b32 s24, s26, 5
	v_lshl_add_u64 v[2:3], v[2:3], 2, s[6:7]
	v_mad_i64_i32 v[10:11], s[4:5], s24, v45, v[2:3]
	s_or_b32 s4, s24, 1
	global_store_dword v[10:11], v36, off
	v_mad_i64_i32 v[10:11], s[4:5], s4, v45, v[2:3]
	s_or_b32 s4, s24, 2
	global_store_dword v[10:11], v37, off
	v_mad_i64_i32 v[10:11], s[4:5], s4, v45, v[2:3]
	s_or_b32 s4, s24, 3
	global_store_dword v[10:11], v34, off
	v_mad_i64_i32 v[10:11], s[4:5], s4, v45, v[2:3]
	s_or_b32 s4, s24, 4
	global_store_dword v[10:11], v35, off
	v_mad_i64_i32 v[10:11], s[4:5], s4, v45, v[2:3]
	s_or_b32 s4, s24, 5
	global_store_dword v[10:11], v32, off
	v_mad_i64_i32 v[10:11], s[4:5], s4, v45, v[2:3]
	s_or_b32 s4, s24, 6
	global_store_dword v[10:11], v33, off
	v_mad_i64_i32 v[10:11], s[4:5], s4, v45, v[2:3]
	s_or_b32 s4, s24, 7
	global_store_dword v[10:11], v30, off
	v_mad_i64_i32 v[10:11], s[4:5], s4, v45, v[2:3]
	s_or_b32 s4, s24, 8
	global_store_dword v[10:11], v31, off
	v_mad_i64_i32 v[10:11], s[4:5], s4, v45, v[2:3]
	s_or_b32 s4, s24, 9
	global_store_dword v[10:11], v28, off
	v_mad_i64_i32 v[10:11], s[4:5], s4, v45, v[2:3]
	s_or_b32 s4, s24, 10
	global_store_dword v[10:11], v29, off
	v_mad_i64_i32 v[10:11], s[4:5], s4, v45, v[2:3]
	s_or_b32 s4, s24, 11
	global_store_dword v[10:11], v26, off
	v_mad_i64_i32 v[10:11], s[4:5], s4, v45, v[2:3]
	s_or_b32 s4, s24, 12
	global_store_dword v[10:11], v27, off
	v_mad_i64_i32 v[10:11], s[4:5], s4, v45, v[2:3]
	s_or_b32 s4, s24, 13
	global_store_dword v[10:11], v24, off
	v_mad_i64_i32 v[10:11], s[4:5], s4, v45, v[2:3]
	s_or_b32 s4, s24, 14
	global_store_dword v[10:11], v25, off
	v_mad_i64_i32 v[10:11], s[4:5], s4, v45, v[2:3]
	s_or_b32 s4, s24, 15
	global_store_dword v[10:11], v22, off
	v_mad_i64_i32 v[10:11], s[4:5], s4, v45, v[2:3]
	s_or_b32 s4, s24, 16
	global_store_dword v[10:11], v23, off
	v_mad_i64_i32 v[10:11], s[4:5], s4, v45, v[2:3]
	s_or_b32 s4, s24, 17
	global_store_dword v[10:11], v20, off
	v_mad_i64_i32 v[10:11], s[4:5], s4, v45, v[2:3]
	s_or_b32 s4, s24, 18
	global_store_dword v[10:11], v21, off
	v_mad_i64_i32 v[10:11], s[4:5], s4, v45, v[2:3]
	s_or_b32 s4, s24, 19
	global_store_dword v[10:11], v18, off
	v_mad_i64_i32 v[10:11], s[4:5], s4, v45, v[2:3]
	s_or_b32 s4, s24, 20
	global_store_dword v[10:11], v19, off
	v_mad_i64_i32 v[10:11], s[4:5], s4, v45, v[2:3]
	s_or_b32 s4, s24, 21
	global_store_dword v[10:11], v16, off
	v_mad_i64_i32 v[10:11], s[4:5], s4, v45, v[2:3]
	s_or_b32 s4, s24, 22
	global_store_dword v[10:11], v17, off
	v_mad_i64_i32 v[10:11], s[4:5], s4, v45, v[2:3]
	s_or_b32 s4, s24, 23
	global_store_dword v[10:11], v14, off
	v_mad_i64_i32 v[10:11], s[4:5], s4, v45, v[2:3]
	s_or_b32 s4, s24, 24
	global_store_dword v[10:11], v15, off
	v_mad_i64_i32 v[10:11], s[4:5], s4, v45, v[2:3]
	s_or_b32 s4, s24, 25
	global_store_dword v[10:11], v12, off
	v_mad_i64_i32 v[10:11], s[4:5], s4, v45, v[2:3]
	s_or_b32 s4, s24, 26
	global_store_dword v[10:11], v13, off
	v_mad_i64_i32 v[10:11], s[4:5], s4, v45, v[2:3]
	s_or_b32 s4, s24, 27
	global_store_dword v[10:11], v8, off
	v_mad_i64_i32 v[10:11], s[4:5], s4, v45, v[2:3]
	s_or_b32 s4, s24, 28
	global_store_dword v[10:11], v9, off
	v_mad_i64_i32 v[8:9], s[4:5], s4, v45, v[2:3]
	s_or_b32 s4, s24, 29
	global_store_dword v[8:9], v6, off
	v_mad_i64_i32 v[8:9], s[4:5], s4, v45, v[2:3]
	s_or_b32 s4, s24, 30
	global_store_dword v[8:9], v7, off
	v_mad_i64_i32 v[6:7], s[4:5], s4, v45, v[2:3]
	s_or_b32 s4, s24, 31
	s_nop 0
	v_mad_i64_i32 v[2:3], s[4:5], s4, v45, v[2:3]
	global_store_dword v[6:7], v0, off
	global_store_dword v[2:3], v1, off
	s_branch .LBB0_20

; template <bool PARTIAL> DI float modval(const Params& p, int b, int n) {
;   if (PARTIAL) {
;     const float* mp = (const float*)(p.ws + OFF_MODP);
;     float s = p.ada_b[n];
; #pragma unroll
;     for (int kc = 0; kc < 8; ++kc) s += mp[(size_t)(kc * 32 + b) * 6144 + n];
;     return s;
; template <bool FIRST> DI void norm_pass(const Params& p, const float* __restrict__ src, const u16* __restrict__ srcb, const float* __restrict__ g, int shift_off, int scale_off,
;                                         int bid, int nblk, unsigned char* smem) {
;     ...
;     for (int k = tid; k < 1024; k += 256) {
;       gs[k] = g[k] * (1.0f + modval<FIRST>(p, b, scale_off + k));
;       sh[k] = modval<FIRST>(p, b, shift_off + k);
;     }
.LBB0_198:
	v_ashrrev_i32_e32 v5, 31, v1
	v_mov_b32_e32 v4, v1
	v_ashrrev_i32_e32 v7, 31, v0
	v_mov_b32_e32 v6, v0
	v_lshlrev_b64 v[6:7], 2, v[6:7]
	v_lshlrev_b64 v[4:5], 2, v[4:5]
	v_lshl_add_u64 v[8:9], s[88:89], 0, v[6:7]
	v_lshl_add_u64 v[10:11], s[88:89], 0, v[4:5]
	v_lshl_add_u64 v[14:15], v[6:7], 0, s[14:15]
	v_lshl_add_u64 v[12:13], v[4:5], 0, s[14:15]
	v_lshl_add_u64 v[16:17], s[86:87], 0, v[6:7]
	global_load_dword v8, v[8:9], off
	s_nop 0
	global_load_dword v9, v[10:11], off
	v_lshl_add_u64 v[10:11], s[86:87], 0, v[14:15]
	v_lshl_add_u64 v[18:19], s[86:87], 0, v[4:5]
	v_lshl_add_u64 v[20:21], s[86:87], 0, v[12:13]
	global_load_dword v16, v[16:17], off
	s_nop 0
	global_load_dword v17, v[18:19], off
	s_nop 0
	global_load_dword v10, v[10:11], off
	s_nop 0
	global_load_dword v11, v[20:21], off
	v_lshl_add_u64 v[6:7], s[8:9], 0, v[6:7]
	v_lshl_add_u64 v[4:5], s[8:9], 0, v[4:5]
	v_lshl_add_u64 v[14:15], s[8:9], 0, v[14:15]
	v_lshl_add_u64 v[12:13], s[8:9], 0, v[12:13]
	v_lshl_add_u64 v[18:19], v[6:7], 0, s[20:21]
	v_lshl_add_u64 v[22:23], v[4:5], 0, s[20:21]
	v_lshl_add_u64 v[24:25], v[6:7], 0, s[24:25]
	v_lshl_add_u64 v[26:27], v[4:5], 0, s[24:25]
	v_lshl_add_u64 v[28:29], v[6:7], 0, s[26:27]
	v_lshl_add_u64 v[30:31], v[4:5], 0, s[26:27]
	v_lshl_add_u64 v[32:33], v[6:7], 0, s[28:29]
	v_lshl_add_u64 v[34:35], v[4:5], 0, s[28:29]
	v_lshl_add_u64 v[36:37], v[6:7], 0, s[30:31]
	v_lshl_add_u64 v[38:39], v[4:5], 0, s[30:31]
	v_lshl_add_u64 v[40:41], v[6:7], 0, s[34:35]
	v_lshl_add_u64 v[42:43], v[4:5], 0, s[34:35]
	v_lshl_add_u64 v[44:45], v[6:7], 0, s[36:37]
	v_lshl_add_u64 v[6:7], v[6:7], 0, s[44:45]
	v_lshl_add_u64 v[20:21], v[14:15], 0, s[20:21]
	v_lshl_add_u64 v[50:51], v[14:15], 0, s[24:25]
	v_lshl_add_u64 v[54:55], v[14:15], 0, s[26:27]
	v_lshl_add_u64 v[58:59], v[14:15], 0, s[28:29]
	v_lshl_add_u64 v[62:63], v[14:15], 0, s[30:31]
	v_lshl_add_u64 v[94:95], v[14:15], 0, s[34:35]
	v_lshl_add_u64 v[108:109], v[14:15], 0, s[36:37]
	v_lshl_add_u64 v[14:15], v[14:15], 0, s[44:45]
	v_lshl_add_u64 v[46:47], v[4:5], 0, s[36:37]
	v_lshl_add_u64 v[4:5], v[4:5], 0, s[44:45]
	v_lshl_add_u64 v[48:49], v[12:13], 0, s[20:21]
	v_lshl_add_u64 v[52:53], v[12:13], 0, s[24:25]
	v_lshl_add_u64 v[56:57], v[12:13], 0, s[26:27]
	v_lshl_add_u64 v[60:61], v[12:13], 0, s[28:29]
	v_lshl_add_u64 v[92:93], v[12:13], 0, s[30:31]
	v_lshl_add_u64 v[106:107], v[12:13], 0, s[34:35]
	v_lshl_add_u64 v[110:111], v[12:13], 0, s[36:37]
	v_lshl_add_u64 v[12:13], v[12:13], 0, s[44:45]
	global_load_dword v18, v[18:19], off
	s_nop 0
	global_load_dword v19, v[22:23], off
	s_nop 0
	global_load_dword v22, v[24:25], off
	global_load_dword v23, v[26:27], off
	s_nop 0
	global_load_dword v24, v[28:29], off
	global_load_dword v25, v[30:31], off
	global_load_dword v26, v[32:33], off
	global_load_dword v27, v[34:35], off
	s_nop 0
	global_load_dword v28, v[36:37], off
	global_load_dword v29, v[38:39], off
	global_load_dword v30, v[40:41], off
	global_load_dword v31, v[42:43], off
	global_load_dword v32, v[44:45], off
	global_load_dword v33, v[46:47], off
	s_nop 0
	global_load_dword v6, v[6:7], off
	s_nop 0
	global_load_dword v20, v[20:21], off
	s_nop 0
	global_load_dword v21, v[48:49], off
	global_load_dword v34, v[50:51], off
	global_load_dword v35, v[52:53], off
	global_load_dword v36, v[54:55], off
	global_load_dword v37, v[56:57], off
	global_load_dword v38, v[58:59], off
	global_load_dword v39, v[60:61], off
	global_load_dword v40, v[62:63], off
	global_load_dword v41, v[92:93], off
	global_load_dword v42, v[94:95], off
	global_load_dword v43, v[106:107], off
	global_load_dword v44, v[108:109], off
	global_load_dword v45, v[110:111], off
	s_nop 0
	global_load_dword v14, v[14:15], off
	s_nop 0
	global_load_dword v15, v[12:13], off
	global_load_dword v7, v[4:5], off
	v_add_u32_e32 v2, -2, v2
	v_cmp_eq_u32_e32 vcc, 0, v2
	v_add_u32_e32 v1, 0x200, v1
	v_add_u32_e32 v0, 0x200, v0
	s_or_b64 s[46:47], vcc, s[46:47]
	s_waitcnt vmcnt(30)
	v_add_f32_e64 v4, v16, v18
	v_add_f32_e64 v5, v17, v19
	s_waitcnt vmcnt(28)
	v_add_f32_e64 v4, v4, v22
	v_add_f32_e64 v5, v5, v23
	s_waitcnt vmcnt(26)
	v_add_f32_e64 v4, v4, v24
	v_add_f32_e64 v5, v5, v25
	s_waitcnt vmcnt(24)
	v_add_f32_e64 v4, v4, v26
	v_add_f32_e64 v5, v5, v27
	s_waitcnt vmcnt(22)
	v_add_f32_e64 v4, v4, v28
	v_add_f32_e64 v5, v5, v29
	s_waitcnt vmcnt(20)
	v_add_f32_e64 v4, v4, v30
	v_add_f32_e64 v5, v5, v31
	s_waitcnt vmcnt(18)
	v_add_f32_e64 v4, v4, v32
	v_add_f32_e64 v5, v5, v33
	s_waitcnt vmcnt(15)
	v_add_f32_e64 v10, v10, v20
	v_add_f32_e64 v11, v11, v21
	s_waitcnt vmcnt(13)
	v_add_f32_e64 v10, v10, v34
	v_add_f32_e64 v11, v11, v35
	s_waitcnt vmcnt(11)
	v_add_f32_e64 v10, v10, v36
	v_add_f32_e64 v11, v11, v37
	s_waitcnt vmcnt(9)
	v_add_f32_e64 v10, v10, v38
	v_add_f32_e64 v11, v11, v39
	s_waitcnt vmcnt(7)
	v_add_f32_e64 v10, v10, v40
	v_add_f32_e64 v11, v11, v41
	s_waitcnt vmcnt(5)
	v_add_f32_e64 v10, v10, v42
	v_add_f32_e64 v11, v11, v43
	s_waitcnt vmcnt(3)
	v_add_f32_e64 v10, v10, v44
	v_add_f32_e64 v11, v11, v45
	s_waitcnt vmcnt(0)
	v_add_f32_e64 v4, v4, v6
	v_add_f32_e64 v5, v5, v7
	v_add_f32_e64 v6, v10, v14
	v_add_f32_e64 v7, v11, v15
	ds_write2st64_b32 v3, v4, v5 offset0:16 offset1:20
	v_add_f32_e64 v4, v6, 1.0
	v_add_f32_e64 v5, v7, 1.0
	s_nop 0
	v_mul_f32_e64 v4, v8, v4
	v_mul_f32_e64 v5, v9, v5
	ds_write2st64_b32 v3, v4, v5 offset1:4
	v_add_u32_e32 v3, 0x800, v3
	s_andn2_b64 exec, exec, s[46:47]
	s_cbranch_execnz .LBB0_198
	s_or_b64 exec, exec, s[46:47]
	s_mov_b64 s[24:25], 0
	s_and_saveexec_b64 s[26:27], s[6:7]
	s_mov_b64 s[24:25], exec
	s_or_b64 exec, exec, s[26:27]
	s_orn2_b64 s[24:25], s[24:25], exec
	v_mov_b32_e32 v0, v103
	v_mov_b32_e32 v2, v69

; DI void store4(u16* dst, f32x4 v) { uint2 w; w.x = cvtpk(v[0], v[1]); w.y = cvtpk(v[2], v[3]); *(uint2*)dst = w; }
; template <bool FIRST> DI void norm_pass(const Params& p, const float* __restrict__ src, const u16* __restrict__ srcb, const float* __restrict__ g, int shift_off, int scale_off,
;                                         int bid, int nblk, unsigned char* smem) {
;     ...
;     for (int r = 0; r < 32; ++r) {
;       const size_t row = row0 + r;
;       if (r + 1 < 32) ldrow(nv, row + 1);
;       float ss = 0.f;
; #pragma unroll
;       for (int i = 0; i < 4; ++i) ss += v[i].x * v[i].x + v[i].y * v[i].y + v[i].z * v[i].z + v[i].w * v[i].w;
; #pragma unroll
;       for (int o = 32; o >= 1; o >>= 1) ss += __shfl_xor(ss, o);
;       const float rstd = rsqrtf(ss * (1.0f / 1024.0f) + 1e-6f);
; #pragma unroll
;       for (int i = 0; i < 4; ++i) {
;         const int k = (lane + 64 * i) * 4;
;         const float4 gg = *(const float4*)(gs + k), hh = *(const float4*)(sh + k);
;         f32x4 o = {v[i].x * rstd * gg.x + hh.x, v[i].y * rstd * gg.y + hh.y, v[i].z * rstd * gg.z + hh.z, v[i].w * rstd * gg.w + hh.w};
;         store4(dst + ((size_t)(k >> 5) * Tn + row) * 32 + (k & 31), o);
;       }
; #pragma unroll
;       for (int i = 0; i < 4; ++i) v[i] = nv[i];
;     }
.LBB0_206:
	global_load_dwordx4 v[44:47], v[94:95], off offset:-2048
	global_load_dwordx4 v[36:39], v[94:95], off offset:-1024
	global_load_dwordx4 v[40:43], v[94:95], off
	global_load_dwordx4 v[48:51], v[94:95], off offset:1024
	s_waitcnt vmcnt(6)
	v_mov_b32_e32 v106, v52
	v_mov_b32_e32 v107, v32
	v_mov_b32_e32 v108, v53
	v_mov_b32_e32 v109, v33
	s_waitcnt vmcnt(4)
	v_mov_b32_e32 v114, v60
	v_mov_b32_e32 v115, v56
	v_mul_f32_e64 v106, v106, v106
	v_mul_f32_e64 v107, v107, v107
	v_mov_b32_e32 v110, v54
	v_mov_b32_e32 v111, v34
	v_mov_b32_e32 v116, v61
	v_mov_b32_e32 v117, v57
	v_mul_f32_e64 v114, v114, v114
	v_mul_f32_e64 v115, v115, v115
	v_fma_f32 v106, v108, v108, v106
	v_fma_f32 v107, v109, v109, v107
	v_mov_b32_e32 v112, v55
	v_mov_b32_e32 v113, v35
	v_mov_b32_e32 v118, v62
	v_mov_b32_e32 v119, v58
	v_fma_f32 v108, v116, v116, v114
	v_fma_f32 v109, v117, v117, v115
	v_fma_f32 v106, v110, v110, v106
	v_fma_f32 v107, v111, v111, v107
	v_mov_b32_e32 v120, v63
	v_mov_b32_e32 v121, v59
	v_fma_f32 v108, v118, v118, v108
	v_fma_f32 v109, v119, v119, v109
	v_fma_f32 v106, v112, v112, v106
	v_fma_f32 v107, v113, v113, v107
	v_fma_f32 v108, v120, v120, v108
	v_fma_f32 v109, v121, v121, v109
	v_add_f32_e32 v106, v106, v107
	v_add_f32_e32 v106, v109, v106
	v_add_f32_e32 v106, v108, v106
	ds_bpermute_b32 v107, v96, v106
	v_lshl_add_u64 v[122:123], v[82:83], 0, s[18:19]
	v_add_co_u32_e32 v122, vcc, s49, v122
	v_lshl_add_u64 v[124:125], v[84:85], 0, s[18:19]
	s_waitcnt lgkmcnt(0)
	v_add_f32_e32 v106, v106, v107
	ds_bpermute_b32 v107, v97, v106
	v_addc_co_u32_e32 v123, vcc, 0, v123, vcc
	v_add_co_u32_e32 v124, vcc, s49, v124
	s_waitcnt lgkmcnt(0)
	v_add_f32_e32 v106, v106, v107
	ds_bpermute_b32 v107, v98, v106
	v_lshl_add_u64 v[126:127], v[86:87], 0, s[18:19]
	v_addc_co_u32_e32 v125, vcc, 0, v125, vcc
	v_add_co_u32_e32 v126, vcc, s49, v126
	s_waitcnt lgkmcnt(0)
	v_add_f32_e32 v106, v106, v107
	ds_bpermute_b32 v107, v99, v106
	v_lshl_add_u64 v[128:129], v[88:89], 0, s[18:19]
	v_addc_co_u32_e32 v127, vcc, 0, v127, vcc
	v_add_co_u32_e32 v128, vcc, s49, v128
	s_waitcnt lgkmcnt(0)
	v_add_f32_e32 v106, v106, v107
	ds_bpermute_b32 v107, v100, v106
	v_addc_co_u32_e32 v129, vcc, 0, v129, vcc
	s_add_u32 s18, s18, 64
	s_addc_u32 s19, s19, 0
	s_waitcnt lgkmcnt(0)
	v_add_f32_e32 v106, v106, v107
	ds_bpermute_b32 v107, v101, v106
	v_lshl_add_u64 v[94:95], v[94:95], 0, s[14:15]
	s_cmpk_eq_i32 s18, 0x7c0
	s_waitcnt lgkmcnt(0)
	v_add_f32_e32 v106, v106, v107
	v_fmamk_f32 v106, v106, 0x3a800000, v105
	v_mul_f32_e32 v107, 0x4b800000, v106
	v_cmp_gt_f32_e32 vcc, s48, v106
	s_nop 1
	v_cndmask_b32_e32 v106, v106, v107, vcc
	v_rsq_f32_e32 v106, v106
	s_nop 0
	v_mul_f32_e32 v107, 0x45800000, v106
	v_cndmask_b32_e32 v106, v106, v107, vcc
	v_mul_f32_e64 v32, v32, v106
	v_mul_f32_e64 v33, v33, v106
	v_mul_f32_e64 v34, v34, v106
	v_mul_f32_e64 v35, v35, v106
	v_mul_f32_e64 v52, v52, v106
	v_mul_f32_e64 v53, v53, v106
	v_mul_f32_e64 v54, v54, v106
	v_mul_f32_e64 v55, v55, v106
	v_mul_f32_e64 v56, v56, v106
	v_mul_f32_e64 v57, v57, v106
	v_mul_f32_e64 v58, v58, v106
	v_mul_f32_e64 v59, v59, v106
	v_mul_f32_e64 v60, v60, v106
	v_mul_f32_e64 v61, v61, v106
	v_mul_f32_e64 v62, v62, v106
	v_mul_f32_e64 v63, v63, v106
	v_fma_f32 v32, v0, v32, v20
	v_fma_f32 v33, v1, v33, v21
	v_fma_f32 v34, v2, v34, v22
	v_fma_f32 v35, v3, v35, v23
	v_fma_f32 v52, v52, v4, v16
	v_fma_f32 v53, v53, v5, v17
	v_fma_f32 v54, v54, v6, v18
	v_fma_f32 v55, v55, v7, v19
	v_fma_f32 v56, v56, v8, v28
	v_fma_f32 v57, v57, v9, v29
	v_fma_f32 v58, v58, v10, v30
	v_fma_f32 v59, v59, v11, v31
	v_fma_f32 v60, v60, v12, v24
	v_fma_f32 v61, v61, v13, v25
	v_fma_f32 v62, v62, v14, v26
	v_fma_f32 v63, v63, v15, v27
	v_cvt_pk_bf16_f32 v32, v32, v33
	v_cvt_pk_bf16_f32 v33, v34, v35
	v_cvt_pk_bf16_f32 v34, v52, v53
	v_cvt_pk_bf16_f32 v35, v54, v55
	v_cvt_pk_bf16_f32 v52, v56, v57
	v_cvt_pk_bf16_f32 v53, v58, v59
	v_cvt_pk_bf16_f32 v54, v60, v61
	v_cvt_pk_bf16_f32 v55, v62, v63
	global_store_dwordx2 v[122:123], v[32:33], off offset:2048
	global_store_dwordx2 v[124:125], v[34:35], off offset:2048
	global_store_dwordx2 v[126:127], v[52:53], off offset:2048
	global_store_dwordx2 v[128:129], v[54:55], off offset:2048
	s_waitcnt vmcnt(7)
	v_mov_b64_e32 v[32:33], v[44:45]
	v_mov_b64_e32 v[34:35], v[46:47]
	s_waitcnt vmcnt(6)
	v_mov_b64_e32 v[52:53], v[36:37]
	v_mov_b64_e32 v[54:55], v[38:39]
	s_waitcnt vmcnt(5)
	v_mov_b64_e32 v[56:57], v[40:41]
	v_mov_b64_e32 v[58:59], v[42:43]
	s_waitcnt vmcnt(4)
	v_mov_b64_e32 v[60:61], v[48:49]
	v_mov_b64_e32 v[62:63], v[50:51]
	s_cbranch_scc0 .LBB0_206
; DI void store4(u16* dst, f32x4 v) { uint2 w; w.x = cvtpk(v[0], v[1]); w.y = cvtpk(v[2], v[3]); *(uint2*)dst = w; }
; template <bool FIRST> DI void norm_pass(const Params& p, const float* __restrict__ src, const u16* __restrict__ srcb, const float* __restrict__ g, int shift_off, int scale_off,
;                                         int bid, int nblk, unsigned char* smem) {
;     ...
;     for (int r = 0; r < 32; ++r) {
;       const size_t row = row0 + r;
;       if (r + 1 < 32) ldrow(nv, row + 1);
;       float ss = 0.f;
; #pragma unroll
;       for (int i = 0; i < 4; ++i) ss += v[i].x * v[i].x + v[i].y * v[i].y + v[i].z * v[i].z + v[i].w * v[i].w;
; #pragma unroll
;       for (int o = 32; o >= 1; o >>= 1) ss += __shfl_xor(ss, o);
;       const float rstd = rsqrtf(ss * (1.0f / 1024.0f) + 1e-6f);
; #pragma unroll
;       for (int i = 0; i < 4; ++i) {
;         const int k = (lane + 64 * i) * 4;
;         const float4 gg = *(const float4*)(gs + k), hh = *(const float4*)(sh + k);
;         f32x4 o = {v[i].x * rstd * gg.x + hh.x, v[i].y * rstd * gg.y + hh.y, v[i].z * rstd * gg.z + hh.z, v[i].w * rstd * gg.w + hh.w};
;         store4(dst + ((size_t)(k >> 5) * Tn + row) * 32 + (k & 31), o);
;       }
; #pragma unroll
;       for (int i = 0; i < 4; ++i) v[i] = nv[i];
;     }
;   }
	v_mov_b32_e32 v34, v45
	v_mov_b32_e32 v35, v37
	v_mov_b32_e32 v32, v44
	v_mov_b32_e32 v33, v36
	v_mul_f32_e64 v34, v34, v34
	v_mul_f32_e64 v35, v35, v35
	v_mov_b32_e32 v52, v41
	v_fma_f32 v32, v32, v32, v34
	v_fma_f32 v33, v33, v33, v35
	v_mov_b32_e32 v34, v46
	v_mov_b32_e32 v35, v38
	v_fma_f32 v32, v34, v34, v32
	v_fma_f32 v33, v35, v35, v33
	v_mov_b32_e32 v34, v47
	v_mov_b32_e32 v35, v39
	v_mov_b32_e32 v53, v49
	v_fma_f32 v32, v34, v34, v32
	v_fma_f32 v33, v35, v35, v33
	v_mov_b32_e32 v34, v40
	v_mov_b32_e32 v35, v48
	v_mul_f32_e64 v52, v52, v52
	v_mul_f32_e64 v53, v53, v53
	v_add_f32_e32 v32, v32, v33
	v_fma_f32 v34, v34, v34, v52
	v_fma_f32 v35, v35, v35, v53
	v_mov_b32_e32 v52, v42
	v_mov_b32_e32 v53, v50
	v_fma_f32 v34, v52, v52, v34
	v_fma_f32 v35, v53, v53, v35
	v_mov_b32_e32 v52, v43
	v_mov_b32_e32 v53, v51
	v_fma_f32 v34, v52, v52, v34
	v_fma_f32 v35, v53, v53, v35
	s_add_i32 s16, s16, s92
	v_add_f32_e32 v32, v32, v34
	v_add_f32_e32 v32, v32, v35
	ds_bpermute_b32 v33, v96, v32
	v_lshl_add_u64 v[82:83], v[82:83], 0, s[10:11]
	v_lshl_add_u64 v[84:85], v[84:85], 0, s[10:11]
	v_lshl_add_u64 v[86:87], v[86:87], 0, s[10:11]
	v_lshl_add_u64 v[88:89], v[88:89], 0, s[10:11]
	s_waitcnt lgkmcnt(0)
	v_add_f32_e32 v32, v32, v33
	ds_bpermute_b32 v33, v97, v32
	s_cmpk_gt_i32 s16, 0x1ff
	v_lshl_add_u64 v[90:91], v[90:91], 0, s[12:13]
	s_waitcnt lgkmcnt(0)
	v_add_f32_e32 v32, v32, v33
	ds_bpermute_b32 v33, v98, v32
	s_waitcnt lgkmcnt(0)
	v_add_f32_e32 v32, v32, v33
	ds_bpermute_b32 v33, v99, v32
	s_waitcnt lgkmcnt(0)
	v_add_f32_e32 v32, v32, v33
	ds_bpermute_b32 v33, v100, v32
	s_waitcnt lgkmcnt(0)
	v_add_f32_e32 v32, v32, v33
	ds_bpermute_b32 v33, v101, v32
	s_waitcnt lgkmcnt(0)
	v_add_f32_e32 v32, v32, v33
	v_fmamk_f32 v32, v32, 0x3a800000, v105
	v_mul_f32_e32 v33, 0x4b800000, v32
	v_cmp_gt_f32_e32 vcc, s48, v32
	s_nop 1
	v_cndmask_b32_e32 v32, v32, v33, vcc
	v_rsq_f32_e32 v52, v32
	v_lshlrev_b64 v[32:33], 6, v[92:93]
	v_lshl_add_u64 v[32:33], v[72:73], 0, v[32:33]
	v_lshl_add_u64 v[34:35], v[32:33], 0, v[74:75]
	v_mul_f32_e32 v53, 0x45800000, v52
	v_cndmask_b32_e32 v52, v52, v53, vcc
	v_mul_f32_e64 v44, v44, v52
	v_mul_f32_e64 v45, v45, v52
	v_mul_f32_e64 v46, v46, v52
	v_mul_f32_e64 v47, v47, v52
	v_fma_f32 v0, v0, v44, v20
	v_fma_f32 v1, v1, v45, v21
	v_fma_f32 v2, v2, v46, v22
	v_fma_f32 v3, v3, v47, v23
	v_mul_f32_e64 v36, v36, v52
	v_mul_f32_e64 v37, v37, v52
	v_cvt_pk_bf16_f32 v0, v0, v1
	v_cvt_pk_bf16_f32 v1, v2, v3
	v_mul_f32_e64 v2, v38, v52
	v_mul_f32_e64 v3, v39, v52
	global_store_dwordx2 v[34:35], v[0:1], off offset:1984
	v_fma_f32 v0, v4, v36, v16
	v_fma_f32 v1, v5, v37, v17
	v_fma_f32 v2, v6, v2, v18
	v_fma_f32 v3, v7, v3, v19
	v_lshl_add_u64 v[4:5], v[32:33], 0, v[76:77]
	v_cvt_pk_bf16_f32 v0, v0, v1
	v_cvt_pk_bf16_f32 v1, v2, v3
	global_store_dwordx2 v[4:5], v[0:1], off offset:1984
	v_mul_f32_e64 v0, v40, v52
	v_mul_f32_e64 v1, v41, v52
	v_mul_f32_e64 v2, v42, v52
	v_mul_f32_e64 v3, v43, v52
	v_fma_f32 v0, v8, v0, v28
	v_fma_f32 v1, v9, v1, v29
	v_fma_f32 v2, v10, v2, v30
	v_fma_f32 v3, v11, v3, v31
	v_lshl_add_u64 v[4:5], v[32:33], 0, v[78:79]
	v_cvt_pk_bf16_f32 v0, v0, v1
	v_cvt_pk_bf16_f32 v1, v2, v3
	global_store_dwordx2 v[4:5], v[0:1], off offset:1984
	v_mul_f32_e64 v0, v48, v52
	v_mul_f32_e64 v1, v49, v52
	v_mul_f32_e64 v2, v50, v52
	v_mul_f32_e64 v3, v51, v52
	v_fma_f32 v0, v12, v0, v24
	v_fma_f32 v1, v13, v1, v25
	v_fma_f32 v2, v14, v2, v26
	v_fma_f32 v3, v15, v3, v27
	v_lshl_add_u64 v[4:5], v[32:33], 0, v[80:81]
	v_cvt_pk_bf16_f32 v0, v0, v1
	v_cvt_pk_bf16_f32 v1, v2, v3
	global_store_dwordx2 v[4:5], v[0:1], off offset:1984
	s_cbranch_scc0 .LBB0_195

; DI void rope4(f32x4& a, f32x4& b, const float* __restrict__ cs, int t, int lq) {
;   const f32x4 c01 = *(const f32x4*)(cs + (size_t)t * 32 + lq * 8), c23 = *(const f32x4*)(cs + (size_t)t * 32 + lq * 8 + 4);
;   const float cv[4] = {c01[0], c01[2], c23[0], c23[2]}, sv[4] = {c01[1], c01[3], c23[1], c23[3]};
; #pragma unroll
;   for (int j = 0; j < 4; ++j) {
;     const float x1 = a[j], x2 = b[j];
;     a[j] = x1 * cv[j] - x2 * sv[j];
;     b[j] = x2 * cv[j] + x1 * sv[j];
;   }
; }
; DI void phase1(const Params& p, const Sched& sched, unsigned char* smem) {
;     ...
;       if (tn == 23 && wf == 0) {
; #pragma unroll
;         for (int ni = 0; ni < 8; ++ni) { const int t = tb + ni * 16 + lr; rope4(acc[0][ni], acc[1][ni], p.out, t, lq); }
;       }
.LBB0_279:
	s_cmp_eq_u32 s61, 23
	s_cselect_b64 s[26:27], -1, 0
	v_cmp_gt_u32_e32 vcc, s44, v161
	s_and_b64 s[28:29], s[26:27], vcc
	s_and_saveexec_b64 s[26:27], s[28:29]
	s_cbranch_execz .LBB0_267
	v_or_b32_e32 v136, s60, v160
	v_ashrrev_i32_e32 v137, 31, v136
	v_lshlrev_b64 v[128:129], 7, v[136:137]
	v_lshl_add_u64 v[128:129], s[40:41], 0, v[128:129]
	v_lshlrev_b32_e32 v152, 2, v158
	v_lshl_add_u64 v[132:133], v[128:129], 0, v[152:153]
	global_load_dwordx4 v[128:131], v[132:133], off
	global_load_dwordx4 v[138:141], v[132:133], off offset:16
	v_or_b32_e32 v132, 16, v136
	v_ashrrev_i32_e32 v133, 31, v132
	v_lshlrev_b64 v[132:133], 7, v[132:133]
	v_lshl_add_u64 v[132:133], s[40:41], 0, v[132:133]
	v_lshl_add_u64 v[132:133], v[132:133], 0, v[152:153]
	global_load_dwordx4 v[142:145], v[132:133], off
	global_load_dwordx4 v[146:149], v[132:133], off offset:16
	v_or_b32_e32 v132, 32, v136
	v_ashrrev_i32_e32 v133, 31, v132
	v_lshlrev_b64 v[132:133], 7, v[132:133]
	v_lshl_add_u64 v[132:133], s[40:41], 0, v[132:133]
	v_lshl_add_u64 v[150:151], v[132:133], 0, v[152:153]
	global_load_dwordx4 v[132:135], v[150:151], off
	global_load_dwordx4 v[154:157], v[150:151], off offset:16
	v_or_b32_e32 v150, 48, v136
	v_ashrrev_i32_e32 v151, 31, v150
	v_lshlrev_b64 v[150:151], 7, v[150:151]
	v_or_b32_e32 v162, 64, v136
	v_or_b32_e32 v170, 0x50, v136
	v_lshl_add_u64 v[150:151], s[40:41], 0, v[150:151]
	v_ashrrev_i32_e32 v163, 31, v162
	v_ashrrev_i32_e32 v171, 31, v170
	v_lshl_add_u64 v[150:151], v[150:151], 0, v[152:153]
	v_lshlrev_b64 v[172:173], 7, v[162:163]
	global_load_dwordx4 v[162:165], v[150:151], off offset:16
	global_load_dwordx4 v[166:169], v[150:151], off
	v_lshlrev_b64 v[150:151], 7, v[170:171]
	v_lshl_add_u64 v[170:171], s[40:41], 0, v[172:173]
	v_lshl_add_u64 v[150:151], s[40:41], 0, v[150:151]
	v_lshl_add_u64 v[174:175], v[170:171], 0, v[152:153]
	v_lshl_add_u64 v[150:151], v[150:151], 0, v[152:153]
	global_load_dwordx4 v[170:173], v[174:175], off offset:16
	s_nop 0
	global_load_dwordx4 v[174:177], v[174:175], off
	s_nop 0
	global_load_dwordx4 v[178:181], v[150:151], off offset:16
	global_load_dwordx4 v[182:185], v[150:151], off
	s_waitcnt vmcnt(11)
	v_mov_b32_e32 v150, v128
	v_mov_b32_e32 v151, v130
	v_mov_b32_e32 v130, v129
	s_waitcnt vmcnt(10)
	v_mul_f32_e32 v128, v126, v138
	v_mul_f32_e32 v186, v82, v139
	v_mul_f32_e32 v138, v82, v138
	v_mul_f32_e32 v188, v126, v139
	v_mov_b32_e32 v82, v127
	v_mov_b32_e32 v126, v83
	v_mul_f32_e64 v190, v80, v130
	v_mul_f32_e64 v191, v81, v131
	v_mul_f32_e64 v80, v80, v150
	v_mul_f32_e64 v81, v81, v151
	v_mul_f32_e64 v82, v82, v140
	v_mul_f32_e64 v83, v83, v141
	v_mul_f32_e64 v140, v126, v140
	v_mul_f32_e64 v141, v127, v141
	s_waitcnt vmcnt(9)
	v_mov_b32_e32 v192, v142
	s_waitcnt vmcnt(8)
	v_mul_f32_e32 v142, v122, v146
	v_mul_f32_e32 v196, v122, v147
	v_mov_b32_e32 v122, v75
	v_mul_f32_e32 v194, v74, v147
	v_mul_f32_e32 v146, v74, v146
	v_mov_b32_e32 v74, v123
	v_mov_b32_e32 v189, v141
	v_mov_b32_e32 v139, v140
	v_fma_f32 v80, v124, v130, v80
	v_fma_f32 v81, v125, v131, v81
	v_mul_f32_e64 v130, v122, v148
	v_mul_f32_e64 v131, v123, v149
	v_mov_b32_e32 v129, v82
	v_mov_b32_e32 v187, v83
	v_mul_f32_e64 v74, v74, v148
	v_mul_f32_e64 v75, v75, v149
	v_add_f32_e64 v82, v188, v138
	v_add_f32_e64 v83, v189, v139
	v_mov_b32_e32 v197, v131
	v_mov_b32_e32 v147, v130
	v_or_b32_e32 v138, 0x60, v136
	v_mov_b32_e32 v193, v144
	v_mov_b32_e32 v144, v143
	s_waitcnt vmcnt(7)
	v_mov_b32_e32 v198, v132
	v_mov_b32_e32 v199, v134
	v_mov_b32_e32 v134, v133
	v_mov_b32_e32 v143, v74
	v_mov_b32_e32 v195, v75
	v_add_f32_e64 v74, v196, v146
	v_add_f32_e64 v75, v197, v147
	s_waitcnt vmcnt(6)
	v_mul_f32_e32 v146, v66, v155
	v_mul_f32_e32 v148, v66, v154
	v_mov_b32_e32 v66, v119
	v_ashrrev_i32_e32 v139, 31, v138
	v_fma_f32 v126, v124, v150, -v190
	v_fma_f32 v127, v125, v151, -v191
	v_mul_f32_e64 v124, v72, v144
	v_mul_f32_e64 v125, v73, v145
	v_mul_f32_e64 v72, v72, v192
	v_mul_f32_e64 v73, v73, v193
	v_mul_f32_e64 v132, v64, v134
	v_mul_f32_e64 v133, v65, v135
	v_mul_f32_e64 v64, v64, v198
	v_mul_f32_e64 v65, v65, v199
	v_mul_f32_e64 v130, v66, v156
	v_mul_f32_e64 v131, v67, v157
	v_lshlrev_b64 v[138:139], 7, v[138:139]
	v_fma_f32 v122, v120, v192, -v124
	v_fma_f32 v123, v121, v193, -v125
	v_fma_f32 v72, v120, v144, v72
	v_fma_f32 v73, v121, v145, v73
	v_mov_b32_e32 v121, v130
	v_lshl_add_u64 v[138:139], s[40:41], 0, v[138:139]
	v_mov_b32_e32 v147, v131
	v_fma_f32 v130, v116, v198, -v132
	v_fma_f32 v131, v117, v199, -v133
	v_fma_f32 v64, v116, v134, v64
	v_fma_f32 v65, v117, v135, v65
	v_or_b32_e32 v116, 0x70, v136
	v_add_f32_e64 v124, v142, -v194
	v_add_f32_e64 v125, v143, -v195
	v_lshl_add_u64 v[142:143], v[138:139], 0, v[152:153]
	v_ashrrev_i32_e32 v117, 31, v116
	global_load_dwordx4 v[138:141], v[142:143], off offset:16
	s_nop 0
	global_load_dwordx4 v[142:145], v[142:143], off
	v_lshlrev_b64 v[116:117], 7, v[116:117]
	v_lshl_add_u64 v[116:117], s[40:41], 0, v[116:117]
	v_mul_f32_e32 v120, v118, v154
	v_mul_f32_e32 v150, v118, v155
	v_mov_b32_e32 v118, v67
	v_lshl_add_u64 v[132:133], v[116:117], 0, v[152:153]
	v_mul_f32_e64 v66, v118, v156
	v_mul_f32_e64 v67, v119, v157
	global_load_dwordx4 v[116:119], v[132:133], off offset:16
	s_nop 0
	global_load_dwordx4 v[132:135], v[132:133], off
	v_mov_b32_e32 v151, v67
	v_mov_b32_e32 v149, v66
	v_add_f32_e64 v66, v150, v148
	v_add_f32_e64 v67, v151, v149
	s_waitcnt vmcnt(9)
; DI void rope4(f32x4& a, f32x4& b, const float* __restrict__ cs, int t, int lq) {
;   const f32x4 c01 = *(const f32x4*)(cs + (size_t)t * 32 + lq * 8), c23 = *(const f32x4*)(cs + (size_t)t * 32 + lq * 8 + 4);
;   const float cv[4] = {c01[0], c01[2], c23[0], c23[2]}, sv[4] = {c01[1], c01[3], c23[1], c23[3]};
; #pragma unroll
;   for (int j = 0; j < 4; ++j) {
;     const float x1 = a[j], x2 = b[j];
;     a[j] = x1 * cv[j] - x2 * sv[j];
;     b[j] = x2 * cv[j] + x1 * sv[j];
;   }
; }
	v_mul_f32_e32 v136, v114, v162
	v_mul_f32_e32 v150, v70, v163
	v_mul_f32_e32 v154, v70, v162
	v_mul_f32_e32 v156, v114, v163
	v_mov_b32_e32 v70, v115
	v_mov_b32_e32 v114, v71
	v_add_f32_e64 v120, v120, -v146
	v_add_f32_e64 v121, v121, -v147
	s_waitcnt vmcnt(8)
	v_mov_b32_e32 v147, v168
	v_mov_b32_e32 v168, v167
	v_mul_f32_e64 v162, v70, v164
	v_mul_f32_e64 v163, v71, v165
	v_mul_f32_e64 v70, v114, v164
	v_mul_f32_e64 v71, v115, v165
	v_mov_b32_e32 v146, v166
	v_mul_f32_e64 v148, v68, v168
	v_mul_f32_e64 v149, v69, v169
	v_mov_b32_e32 v137, v162
	v_mov_b32_e32 v151, v163
	v_mov_b32_e32 v157, v71
	v_mov_b32_e32 v155, v70
	v_mul_f32_e64 v68, v68, v146
	v_mul_f32_e64 v69, v69, v147
	v_fma_f32 v146, v112, v146, -v148
	v_fma_f32 v147, v113, v147, -v149
	v_add_f32_e64 v136, v136, -v150
	v_add_f32_e64 v137, v137, -v151
	v_add_f32_e64 v70, v156, v154
	v_add_f32_e64 v71, v157, v155
	s_waitcnt vmcnt(7)
	v_mul_f32_e32 v148, v110, v170
	v_mul_f32_e32 v150, v78, v171
	v_mul_f32_e32 v154, v78, v170
	v_mul_f32_e32 v156, v110, v171
	v_mov_b32_e32 v78, v111
	v_mov_b32_e32 v110, v79
	v_fma_f32 v68, v112, v168, v68
	v_fma_f32 v69, v113, v169, v69
	s_waitcnt vmcnt(6)
	v_mov_b32_e32 v113, v176
	v_mov_b32_e32 v176, v175
	v_mul_f32_e64 v162, v78, v172
	v_mul_f32_e64 v163, v79, v173
	v_mul_f32_e64 v78, v110, v172
	v_mul_f32_e64 v79, v111, v173
	v_mov_b32_e32 v112, v174
	v_mul_f32_e64 v114, v76, v176
	v_mul_f32_e64 v115, v77, v177
	v_mov_b32_e32 v149, v162
	v_mov_b32_e32 v151, v163
	v_mov_b32_e32 v157, v79
	v_mov_b32_e32 v155, v78
	v_mul_f32_e64 v76, v76, v112
	v_mul_f32_e64 v77, v77, v113
	v_fma_f32 v112, v108, v112, -v114
	v_fma_f32 v113, v109, v113, -v115
	v_add_f32_e64 v114, v148, -v150
	v_add_f32_e64 v115, v149, -v151
	v_add_f32_e64 v78, v156, v154
	v_add_f32_e64 v79, v157, v155
	s_waitcnt vmcnt(5)
	v_mul_f32_e32 v150, v86, v179
	v_mul_f32_e32 v154, v86, v178
	v_mov_b32_e32 v86, v107
	v_fma_f32 v76, v108, v176, v76
	v_fma_f32 v77, v109, v177, v77
	s_waitcnt vmcnt(4)
	v_mov_b32_e32 v108, v182
	v_mov_b32_e32 v109, v184
	v_mov_b32_e32 v184, v183
	v_mul_f32_e32 v148, v106, v178
	v_mul_f32_e32 v156, v106, v179
	v_mul_f32_e64 v162, v86, v180
	v_mul_f32_e64 v163, v87, v181
	v_mov_b32_e32 v106, v87
	v_mul_f32_e64 v110, v84, v184
	v_mul_f32_e64 v111, v85, v185
	v_mul_f32_e64 v84, v84, v108
	v_mul_f32_e64 v85, v85, v109
	v_mov_b32_e32 v149, v162
	v_mov_b32_e32 v151, v163
	v_mul_f32_e64 v86, v106, v180
	v_mul_f32_e64 v87, v107, v181
	v_fma_f32 v108, v104, v108, -v110
	v_fma_f32 v109, v105, v109, -v111
	v_add_f32_e64 v110, v148, -v150
	v_add_f32_e64 v111, v149, -v151
	v_mov_b32_e32 v157, v87
	v_mov_b32_e32 v155, v86
	v_fma_f32 v84, v104, v184, v84
	v_fma_f32 v85, v105, v185, v85
	v_add_f32_e64 v86, v156, v154
	v_add_f32_e64 v87, v157, v155
	v_add_f32_e64 v128, v128, -v186
	v_add_f32_e64 v129, v129, -v187
	s_waitcnt vmcnt(3)
	v_mul_f32_e32 v148, v90, v139
	s_waitcnt vmcnt(2)
	v_mov_b32_e32 v104, v142
	v_mul_f32_e32 v142, v102, v138
	v_mul_f32_e32 v138, v90, v138
	v_mul_f32_e32 v150, v102, v139
	v_mov_b32_e32 v90, v103
	v_mov_b32_e32 v102, v91
	v_mov_b32_e32 v105, v144
	v_mov_b32_e32 v144, v143
	v_mul_f32_e64 v154, v90, v140
	v_mul_f32_e64 v155, v91, v141
	v_mul_f32_e64 v90, v102, v140
	v_mul_f32_e64 v91, v103, v141
	v_mul_f32_e64 v106, v88, v144
	v_mul_f32_e64 v107, v89, v145
	v_mul_f32_e64 v88, v88, v104
	v_mul_f32_e64 v89, v89, v105
	v_mov_b32_e32 v151, v91
	v_mov_b32_e32 v139, v90
	v_mov_b32_e32 v143, v154
	v_mov_b32_e32 v149, v155
	v_fma_f32 v104, v100, v104, -v106
	v_fma_f32 v105, v101, v105, -v107
	v_fma_f32 v88, v100, v144, v88
	v_fma_f32 v89, v101, v145, v89
	v_add_f32_e64 v90, v150, v138
	v_add_f32_e64 v91, v151, v139
	s_waitcnt vmcnt(0)
	v_mov_b32_e32 v100, v132
	v_mul_f32_e32 v132, v98, v116
	v_mul_f32_e32 v138, v94, v117
	v_mul_f32_e32 v116, v94, v116
	v_mov_b32_e32 v94, v99
	v_add_f32_e64 v106, v142, -v148
	v_add_f32_e64 v107, v143, -v149
	v_mov_b32_e32 v101, v134
	v_mov_b32_e32 v134, v133
	v_mul_f32_e32 v140, v98, v117
	v_mul_f32_e64 v142, v94, v118
	v_mul_f32_e64 v143, v95, v119
	v_mov_b32_e32 v98, v95
	v_mul_f32_e64 v102, v92, v134
	v_mul_f32_e64 v103, v93, v135
	v_mov_b32_e32 v133, v142
	v_mov_b32_e32 v139, v143
	v_mul_f32_e64 v94, v98, v118
	v_mul_f32_e64 v95, v99, v119
	v_mul_f32_e64 v92, v92, v100
	v_mul_f32_e64 v93, v93, v101
	v_fma_f32 v100, v96, v100, -v102
	v_fma_f32 v101, v97, v101, -v103
	v_add_f32_e64 v102, v132, -v138
	v_add_f32_e64 v103, v133, -v139
	v_mov_b32_e32 v141, v95
	v_mov_b32_e32 v117, v94
	v_fma_f32 v92, v96, v134, v92
	v_fma_f32 v93, v97, v135, v93
	v_add_f32_e64 v94, v140, v116
	v_add_f32_e64 v95, v141, v117
	v_mov_b32_e32 v96, v100
	v_mov_b32_e32 v97, v101
	v_mov_b32_e32 v98, v102
	v_mov_b32_e32 v99, v103
	v_mov_b32_e32 v100, v104
	v_mov_b32_e32 v101, v105
	v_mov_b32_e32 v102, v106
	v_mov_b32_e32 v103, v107
	v_mov_b32_e32 v104, v108
	v_mov_b32_e32 v105, v109
	v_mov_b32_e32 v106, v110
	v_mov_b32_e32 v107, v111
	v_mov_b32_e32 v108, v112
	v_mov_b32_e32 v109, v113
	v_mov_b32_e32 v110, v114
	v_mov_b32_e32 v111, v115
	v_mov_b32_e32 v112, v146
	v_mov_b32_e32 v113, v147
	v_mov_b32_e32 v114, v136
	v_mov_b32_e32 v115, v137
	v_mov_b32_e32 v116, v130
	v_mov_b32_e32 v117, v131
	v_mov_b32_e32 v118, v120
	v_mov_b32_e32 v119, v121
	v_mov_b32_e32 v120, v122
	v_mov_b32_e32 v121, v123
	v_mov_b32_e32 v122, v124
	v_mov_b32_e32 v123, v125
	v_mov_b32_e32 v124, v126
	v_mov_b32_e32 v125, v127
	v_mov_b32_e32 v126, v128
	v_mov_b32_e32 v127, v129
	s_branch .LBB0_267

; DI int tidx() { int t = __builtin_amdgcn_workitem_id_x(); asm volatile("" : "+v"(t)); return t; }
; DI float bflo(unsigned w) { return __uint_as_float(w << 16); }
; DI float bfhi(unsigned w) { return __uint_as_float(w & 0xffff0000u); }
;   DI unsigned rowoff(int r, int sch) const { const int g = r & 3, bc = r >> 2, b = bc / NCMP, c = bc - b * NCMP; return (unsigned)(b * Sn + c * 16) * 512u + g * 64 + sch; }
; template <class XL, class EP>
; DI void gemm_tile_k128(const u16* __restrict__ W, int ldw, int f0, int t0, int K, XL xl, EP ep, unsigned char* smem) {
;     ...
;   const unsigned wbyte = (((unsigned)(sch >> 5) * ldw + f0 + srow * 8) * 32u + (sch & 31)) * 2u;
;   const unsigned xbyte = xl.rowoff(t0 + srow * 8, sch) * 2u;
;   const int xrs = xl.rstride();
;   for (int kb = 0; kb < K; kb += 128) {
;     u32x4 wr[8], xr[8];
;     const char* wb = (const char*)(W + (size_t)(kb >> 5) * ldw * 32);
;     const char* xb = (const char*)xl.kbase(kb);
; #pragma unroll
;     for (int i = 0; i < 8; ++i) { wr[i] = *(const u32x4*)(wb + wbyte + i * 64); xr[i] = *(const u32x4*)(xb + xbyte + i * xrs); }
; DI void row_rstd(const u16* X, int ld, int K, int t0, float* rs) {
;   const int r = tidx() & 127;
;   const u16* xp = X + (size_t)(t0 + r) * ld;
;   float ss = 0.f;
;   for (int k = 0; k < K; k += 8) {
;     const u32x4 w = *(const u32x4*)(xp + k);
;     const float a0 = bflo(w.x), a1 = bfhi(w.x), a2 = bflo(w.y), a3 = bfhi(w.y), a4 = bflo(w.z), a5 = bfhi(w.z), a6 = bflo(w.w), a7 = bfhi(w.w);
;     ss += a0 * a0 + a1 * a1 + a2 * a2 + a3 * a3 + a4 * a4 + a5 * a5 + a6 * a6 + a7 * a7;
;   }
;   rs[r] = rsqrtf(ss / (float)K + 1e-6f);
; }
; DI void phase2(const Params& p, int bid, int nblk, unsigned char* smem) {
;     ...
;       const int r = tile - n_c1 - n_kvu, tm = r / 6, tn = r % 6, t0 = tm * 128;
;       const u16* X = (const u16*)(p.ws + OFF_MQ);
;       __syncthreads();
;       row_rstd(X, 256, 256, t0, rs);
;       XPlain xl{X, 256};
;       u16* qu = (u16*)(p.ws + OFF_QU);
;       gemm_tile_k128((const u16*)(p.ws + OFF_WUQ), 768, tn * 128, t0, 256, xl, [&](f32x4 (&acc)[4][4], int fb, int tb, int lr, int lq, int wf, int wt) {
.LBB0_339:
	global_load_dwordx4 v[4:7], v[0:1], off offset:-48
	global_load_dwordx4 v[8:11], v[0:1], off offset:-32
	global_load_dwordx4 v[12:15], v[0:1], off offset:-16
	global_load_dwordx4 v[16:19], v[0:1], off
	s_add_i32 s1, s1, 32
	v_lshl_add_u64 v[0:1], v[0:1], 0, 64
	s_cmpk_lt_u32 s1, 0xf8
	s_waitcnt vmcnt(3)
	v_lshlrev_b32_e32 v20, 16, v4
	v_and_b32_e32 v21, 0xffff0000, v4
	v_and_b32_e32 v4, 0xffff0000, v5
	v_lshlrev_b32_e32 v5, 16, v5
	s_waitcnt vmcnt(2)
	v_lshlrev_b32_e32 v24, 16, v8
	v_and_b32_e32 v25, 0xffff0000, v8
	v_mul_f32_e64 v20, v20, v20
	v_mul_f32_e64 v21, v21, v21
	v_and_b32_e32 v8, 0xffff0000, v9
	v_lshlrev_b32_e32 v9, 16, v9
	s_waitcnt vmcnt(1)
	v_lshlrev_b32_e32 v28, 16, v12
	v_and_b32_e32 v29, 0xffff0000, v12
	v_mul_f32_e64 v4, v4, v4
	v_mul_f32_e64 v5, v5, v5
	v_mul_f32_e64 v24, v24, v24
	v_mul_f32_e64 v25, v25, v25
	v_add_f32_e32 v20, v20, v21
	v_and_b32_e32 v22, 0xffff0000, v6
	v_lshlrev_b32_e32 v23, 16, v6
	v_and_b32_e32 v12, 0xffff0000, v13
	v_lshlrev_b32_e32 v13, 16, v13
	s_waitcnt vmcnt(0)
	v_lshlrev_b32_e32 v32, 16, v16
	v_and_b32_e32 v33, 0xffff0000, v16
	v_mul_f32_e64 v8, v8, v8
	v_mul_f32_e64 v9, v9, v9
	v_mul_f32_e64 v28, v28, v28
	v_mul_f32_e64 v29, v29, v29
	v_add_f32_e32 v21, v24, v25
	v_add_f32_e32 v5, v5, v20
	v_and_b32_e32 v26, 0xffff0000, v10
	v_lshlrev_b32_e32 v27, 16, v10
	v_and_b32_e32 v16, 0xffff0000, v17
	v_lshlrev_b32_e32 v17, 16, v17
	v_mul_f32_e64 v22, v22, v22
	v_mul_f32_e64 v23, v23, v23
	v_mul_f32_e64 v12, v12, v12
	v_mul_f32_e64 v13, v13, v13
	v_mul_f32_e64 v32, v32, v32
	v_mul_f32_e64 v33, v33, v33
	v_add_f32_e32 v24, v28, v29
	v_add_f32_e32 v9, v9, v21
	v_add_f32_e32 v4, v4, v5
	v_and_b32_e32 v6, 0xffff0000, v7
	v_lshlrev_b32_e32 v7, 16, v7
	v_and_b32_e32 v30, 0xffff0000, v14
	v_lshlrev_b32_e32 v31, 16, v14
	v_mul_f32_e64 v26, v26, v26
	v_mul_f32_e64 v27, v27, v27
	v_mul_f32_e64 v16, v16, v16
	v_mul_f32_e64 v17, v17, v17
	v_add_f32_e32 v25, v32, v33
	v_add_f32_e32 v13, v13, v24
	v_add_f32_e32 v5, v8, v9
	v_add_f32_e32 v4, v23, v4
	v_and_b32_e32 v10, 0xffff0000, v11
	v_lshlrev_b32_e32 v11, 16, v11
	v_and_b32_e32 v34, 0xffff0000, v18
	v_lshlrev_b32_e32 v35, 16, v18
	v_mul_f32_e64 v6, v6, v6
	v_mul_f32_e64 v7, v7, v7
	v_mul_f32_e64 v30, v30, v30
	v_mul_f32_e64 v31, v31, v31
	v_add_f32_e32 v17, v17, v25
	v_add_f32_e32 v8, v12, v13
	v_add_f32_e32 v5, v27, v5
	v_add_f32_e32 v4, v22, v4
	v_and_b32_e32 v14, 0xffff0000, v15
	v_lshlrev_b32_e32 v15, 16, v15
	v_mul_f32_e64 v10, v10, v10
	v_mul_f32_e64 v11, v11, v11
	v_mul_f32_e64 v34, v34, v34
	v_mul_f32_e64 v35, v35, v35
	v_add_f32_e32 v9, v16, v17
	v_add_f32_e32 v8, v31, v8
	v_add_f32_e32 v5, v26, v5
	v_add_f32_e32 v4, v7, v4
	v_and_b32_e32 v18, 0xffff0000, v19
	v_lshlrev_b32_e32 v19, 16, v19
	v_mul_f32_e64 v14, v14, v14
	v_mul_f32_e64 v15, v15, v15
	v_add_f32_e32 v9, v35, v9
	v_add_f32_e32 v8, v30, v8
	v_add_f32_e32 v5, v11, v5
	v_add_f32_e32 v4, v6, v4
	v_mul_f32_e64 v18, v18, v18
	v_mul_f32_e64 v19, v19, v19
	v_add_f32_e32 v9, v34, v9
	v_add_f32_e32 v7, v15, v8
	v_add_f32_e32 v5, v10, v5
	v_add_f32_e32 v3, v3, v4
	v_add_f32_e32 v8, v19, v9
	v_add_f32_e32 v6, v14, v7
	v_add_f32_e32 v3, v3, v5
	v_add_f32_e32 v7, v18, v8
	v_add_f32_e32 v3, v3, v6
	v_add_f32_e32 v3, v3, v7
	s_cbranch_scc1 .LBB0_339
	v_fmamk_f32 v0, v3, 0x3b800000, v84
	v_mul_f32_e32 v1, 0x4b800000, v0
	v_cmp_gt_f32_e32 vcc, s35, v0
	s_mul_i32 s1, s7, 6
	v_mov_b32_e32 v65, v218
	v_cndmask_b32_e32 v0, v0, v1, vcc
	v_rsq_f32_e32 v0, v0
	s_sub_i32 s0, s0, s1
	s_lshl_b32 s21, s0, 7
	s_and_b32 s1, s21, 0xff80
	v_mul_f32_e32 v1, 0x45800000, v0
	v_cndmask_b32_e32 v0, v0, v1, vcc
	v_lshl_or_b32 v1, v2, 2, v85
	ds_write_b32 v1, v0
	s_nop 0
	v_lshlrev_b32_e32 v0, 3, v65
	v_and_b32_e32 v1, 0x78, v0
	v_bfe_u32 v0, v0, 5, 2
	v_ashrrev_i32_e32 v69, 1, v65
	v_mul_u32_u24_e32 v0, 0x300, v0
	v_and_b32_e32 v71, -8, v69
	v_lshlrev_b32_e32 v2, 4, v65
	v_add3_u32 v0, v71, s1, v0
	v_and_b32_e32 v2, 48, v2
	v_lshl_or_b32 v80, v0, 6, v2
	v_add_u32_e32 v0, s20, v71
	v_lshlrev_b32_e32 v64, 1, v1
	v_lshl_or_b32 v138, v0, 9, v64
	global_load_dwordx4 v[0:3], v138, s[8:9]
	global_load_dwordx4 v[4:7], v138, s[8:9] offset:512
	global_load_dwordx4 v[8:11], v138, s[8:9] offset:1024
	global_load_dwordx4 v[12:15], v138, s[8:9] offset:1536
	global_load_dwordx4 v[16:19], v138, s[8:9] offset:2048
	global_load_dwordx4 v[20:23], v138, s[8:9] offset:2560
	global_load_dwordx4 v[24:27], v138, s[8:9] offset:3072
	global_load_dwordx4 v[28:31], v80, s[2:3]
	global_load_dwordx4 v[32:35], v80, s[2:3] offset:64
	global_load_dwordx4 v[36:39], v80, s[2:3] offset:128
	global_load_dwordx4 v[40:43], v80, s[2:3] offset:192
	global_load_dwordx4 v[44:47], v80, s[2:3] offset:256
	global_load_dwordx4 v[48:51], v80, s[2:3] offset:320
	global_load_dwordx4 v[52:55], v80, s[2:3] offset:384
	global_load_dwordx4 v[56:59], v80, s[2:3] offset:448
	global_load_dwordx4 v[60:63], v138, s[8:9] offset:3584
	v_and_b32_e32 v146, 64, v65
	v_and_b32_e32 v147, 15, v65
	v_lshrrev_b32_e32 v67, 1, v65
	v_and_b32_e32 v66, 0x4f, v65
	v_and_b32_e32 v68, 0xffffffc0, v69
	v_or_b32_e32 v65, 7, v69
	v_mul_lo_u32 v71, v71, s36
	v_and_b32_e32 v67, 24, v67
	v_or_b32_e32 v69, v68, v147
	v_or_b32_e32 v142, v64, v71
	v_mad_u64_u32 v[78:79], s[4:5], v65, s36, v[64:65]
	v_lshlrev_b32_e32 v70, 1, v67
	v_lshl_add_u64 v[82:83], s[2:3], 0, v[80:81]
	s_waitcnt lgkmcnt(0)
	s_barrier
; DI f32x4 mfma16(bf16x8 a, bf16x8 b, f32x4 c) { return __builtin_amdgcn_mfma_f32_16x16x32_bf16(a, b, c, 0, 0, 0); }
; template <class XL, class EP>
; DI void gemm_tile_k128(const u16* __restrict__ W, int ldw, int f0, int t0, int K, XL xl, EP ep, unsigned char* smem) {
;     ...
;     __syncthreads();
; #pragma unroll
;     for (int i = 0; i < 8; ++i) { *(u32x4*)(Ws + (srow * 8 + i) * LST + sch) = wr[i]; *(u32x4*)(Xs + (srow * 8 + i) * LST + sch) = xr[i]; }
;     __syncthreads();
;     __builtin_amdgcn_s_setprio(1);
; #pragma unroll
;     for (int ks = 0; ks < 4; ++ks) {
;       bf16x8 a[4];
; #pragma unroll
;       for (int mi = 0; mi < 4; ++mi) a[mi] = *(const bf16x8*)(Ws + (wf * 64 + mi * 16 + lr) * LST + ks * 32 + lq * 8);
; #pragma unroll
;       for (int ni = 0; ni < 4; ++ni) {
;         const bf16x8 b = *(const bf16x8*)(Xs + (wt * 64 + ni * 16 + lr) * LST + ks * 32 + lq * 8);
; #pragma unroll
;         for (int mi = 0; mi < 4; ++mi) acc[mi][ni] = mfma16(a[mi], b, acc[mi][ni]);
;       }
;     }
	s_waitcnt vmcnt(15)
	ds_write_b128 v142, v[0:3] offset:36864
	s_waitcnt vmcnt(14)
	ds_write_b128 v142, v[4:7] offset:37152
	s_waitcnt vmcnt(13)
	ds_write_b128 v142, v[8:11] offset:37440
	s_waitcnt vmcnt(12)
	ds_write_b128 v142, v[12:15] offset:37728
	s_waitcnt vmcnt(11)
	ds_write_b128 v142, v[16:19] offset:38016
	s_waitcnt vmcnt(10)
	ds_write_b128 v142, v[20:23] offset:38304
	s_waitcnt vmcnt(9)
	ds_write_b128 v142, v[24:27] offset:38592
	s_waitcnt vmcnt(8)
	ds_write_b128 v142, v[28:31]
	s_waitcnt vmcnt(7)
	ds_write_b128 v142, v[32:35] offset:288
	s_waitcnt vmcnt(6)
	ds_write_b128 v142, v[36:39] offset:576
	s_waitcnt vmcnt(5)
	ds_write_b128 v142, v[40:43] offset:864
	s_waitcnt vmcnt(4)
	ds_write_b128 v142, v[44:47] offset:1152
	s_waitcnt vmcnt(3)
	ds_write_b128 v142, v[48:51] offset:1440
	s_waitcnt vmcnt(2)
	ds_write_b128 v142, v[52:55] offset:1728
	s_waitcnt vmcnt(1)
	ds_write_b128 v78, v[56:59]
	s_waitcnt vmcnt(0)
	ds_write_b128 v78, v[60:63] offset:36864
	s_waitcnt lgkmcnt(0)
	s_barrier
	s_setprio 1
	v_mad_u64_u32 v[0:1], s[4:5], v69, s36, v[70:71]
	ds_read_b128 v[2:5], v0
	v_mul_u32_u24_e32 v1, 0x90, v66
	v_lshl_add_u32 v1, v1, 1, v70
	ds_read_b128 v[6:9], v1 offset:36864
	ds_read_b128 v[10:13], v0 offset:64
	ds_read_b128 v[14:17], v1 offset:36928
	ds_read_b128 v[22:25], v0 offset:4608
	ds_read_b128 v[26:29], v0 offset:4672
	ds_read_b128 v[34:37], v0 offset:9216
	ds_read_b128 v[38:41], v0 offset:9280
	ds_read_b128 v[46:49], v0 offset:13824
	ds_read_b128 v[50:53], v0 offset:13888
	ds_read_b128 v[54:57], v1 offset:41472
	ds_read_b128 v[58:61], v1 offset:41536
	ds_read_b128 v[86:89], v1 offset:46080
	ds_read_b128 v[90:93], v1 offset:46144
	ds_read_b128 v[106:109], v1 offset:50688
	ds_read_b128 v[110:113], v1 offset:50752
	s_waitcnt lgkmcnt(14)
	v_mfma_f32_16x16x32_bf16 v[18:21], v[2:5], v[6:9], 0
	s_waitcnt lgkmcnt(11)
	v_mfma_f32_16x16x32_bf16 v[30:33], v[22:25], v[6:9], 0
	s_waitcnt lgkmcnt(9)
	v_mfma_f32_16x16x32_bf16 v[42:45], v[34:37], v[6:9], 0
	s_waitcnt lgkmcnt(7)
	v_mfma_f32_16x16x32_bf16 v[6:9], v[46:49], v[6:9], 0
	s_waitcnt lgkmcnt(5)
	v_mfma_f32_16x16x32_bf16 v[62:65], v[2:5], v[54:57], 0
	v_mfma_f32_16x16x32_bf16 v[70:73], v[22:25], v[54:57], 0
	v_mfma_f32_16x16x32_bf16 v[74:77], v[34:37], v[54:57], 0
	v_mfma_f32_16x16x32_bf16 v[54:57], v[46:49], v[54:57], 0
	s_waitcnt lgkmcnt(3)
	v_mfma_f32_16x16x32_bf16 v[94:97], v[2:5], v[86:89], 0
	v_mfma_f32_16x16x32_bf16 v[98:101], v[22:25], v[86:89], 0
	s_waitcnt lgkmcnt(1)
	v_mfma_f32_16x16x32_bf16 v[2:5], v[2:5], v[106:109], 0
	v_mfma_f32_16x16x32_bf16 v[22:25], v[22:25], v[106:109], 0
	v_mfma_f32_16x16x32_bf16 v[18:21], v[10:13], v[14:17], v[18:21]
	v_mfma_f32_16x16x32_bf16 v[30:33], v[26:29], v[14:17], v[30:33]
	v_mfma_f32_16x16x32_bf16 v[42:45], v[38:41], v[14:17], v[42:45]
	v_mfma_f32_16x16x32_bf16 v[6:9], v[50:53], v[14:17], v[6:9]
	v_mfma_f32_16x16x32_bf16 v[14:17], v[10:13], v[58:61], v[62:65]
	v_mfma_f32_16x16x32_bf16 v[62:65], v[26:29], v[58:61], v[70:73]
	v_mfma_f32_16x16x32_bf16 v[70:73], v[38:41], v[58:61], v[74:77]
	v_mfma_f32_16x16x32_bf16 v[54:57], v[50:53], v[58:61], v[54:57]
	v_mfma_f32_16x16x32_bf16 v[58:61], v[10:13], v[90:93], v[94:97]
	v_mfma_f32_16x16x32_bf16 v[74:77], v[26:29], v[90:93], v[98:101]
	s_waitcnt lgkmcnt(0)
	v_mfma_f32_16x16x32_bf16 v[2:5], v[10:13], v[110:113], v[2:5]
	v_mfma_f32_16x16x32_bf16 v[10:13], v[26:29], v[110:113], v[22:25]
	ds_read_b128 v[26:29], v0 offset:128
	v_mfma_f32_16x16x32_bf16 v[102:105], v[34:37], v[86:89], 0
	v_mfma_f32_16x16x32_bf16 v[86:89], v[46:49], v[86:89], 0
	v_mfma_f32_16x16x32_bf16 v[34:37], v[34:37], v[106:109], 0
	v_mfma_f32_16x16x32_bf16 v[46:49], v[46:49], v[106:109], 0
	v_mfma_f32_16x16x32_bf16 v[94:97], v[38:41], v[90:93], v[102:105]
	v_mfma_f32_16x16x32_bf16 v[86:89], v[50:53], v[90:93], v[86:89]
	v_mfma_f32_16x16x32_bf16 v[22:25], v[38:41], v[110:113], v[34:37]
	v_mfma_f32_16x16x32_bf16 v[34:37], v[50:53], v[110:113], v[46:49]
	ds_read_b128 v[38:41], v1 offset:36992
	s_nop 2
	ds_read_b128 v[46:49], v0 offset:192
	ds_read_b128 v[50:53], v1 offset:37056
	ds_read_b128 v[90:93], v0 offset:4736
	ds_read_b128 v[98:101], v0 offset:4800
	ds_read_b128 v[102:105], v0 offset:9344
	ds_read_b128 v[106:109], v0 offset:9408
	ds_read_b128 v[110:113], v0 offset:13952
	ds_read_b128 v[114:117], v0 offset:14016
	s_waitcnt lgkmcnt(8)
	v_mfma_f32_16x16x32_bf16 v[18:21], v[26:29], v[38:41], v[18:21]
	s_waitcnt lgkmcnt(5)
	v_mfma_f32_16x16x32_bf16 v[30:33], v[90:93], v[38:41], v[30:33]
	s_waitcnt lgkmcnt(3)
	v_mfma_f32_16x16x32_bf16 v[42:45], v[102:105], v[38:41], v[42:45]
	s_waitcnt lgkmcnt(1)
	v_mfma_f32_16x16x32_bf16 v[6:9], v[110:113], v[38:41], v[6:9]
	ds_read_b128 v[38:41], v1 offset:41600
	ds_read_b128 v[118:121], v1 offset:41664
	s_waitcnt lgkmcnt(1)
	v_mfma_f32_16x16x32_bf16 v[14:17], v[26:29], v[38:41], v[14:17]
	v_mfma_f32_16x16x32_bf16 v[62:65], v[90:93], v[38:41], v[62:65]
	v_mfma_f32_16x16x32_bf16 v[70:73], v[102:105], v[38:41], v[70:73]
	v_mfma_f32_16x16x32_bf16 v[38:41], v[110:113], v[38:41], v[54:57]
	s_nop 2
	ds_read_b128 v[54:57], v1 offset:46208
	ds_read_b128 v[122:125], v1 offset:46272
	s_waitcnt lgkmcnt(1)
	v_mfma_f32_16x16x32_bf16 v[58:61], v[26:29], v[54:57], v[58:61]
	v_mfma_f32_16x16x32_bf16 v[74:77], v[90:93], v[54:57], v[74:77]
	v_mfma_f32_16x16x32_bf16 v[94:97], v[102:105], v[54:57], v[94:97]
	v_mfma_f32_16x16x32_bf16 v[54:57], v[110:113], v[54:57], v[86:89]
	s_nop 2
	ds_read_b128 v[86:89], v1 offset:50816
	ds_read_b128 v[126:129], v1 offset:50880
	s_waitcnt lgkmcnt(1)
; DI f32x4 mfma16(bf16x8 a, bf16x8 b, f32x4 c) { return __builtin_amdgcn_mfma_f32_16x16x32_bf16(a, b, c, 0, 0, 0); }
; template <class XL, class EP>
; DI void gemm_tile_k128(const u16* __restrict__ W, int ldw, int f0, int t0, int K, XL xl, EP ep, unsigned char* smem) {
;     ...
;   for (int kb = 0; kb < K; kb += 128) {
;     u32x4 wr[8], xr[8];
;     const char* wb = (const char*)(W + (size_t)(kb >> 5) * ldw * 32);
;     const char* xb = (const char*)xl.kbase(kb);
; #pragma unroll
;     for (int i = 0; i < 8; ++i) { wr[i] = *(const u32x4*)(wb + wbyte + i * 64); xr[i] = *(const u32x4*)(xb + xbyte + i * xrs); }
;     __syncthreads();
; #pragma unroll
;     for (int i = 0; i < 8; ++i) { *(u32x4*)(Ws + (srow * 8 + i) * LST + sch) = wr[i]; *(u32x4*)(Xs + (srow * 8 + i) * LST + sch) = xr[i]; }
;     __syncthreads();
;     __builtin_amdgcn_s_setprio(1);
; #pragma unroll
;     for (int ks = 0; ks < 4; ++ks) {
;       bf16x8 a[4];
; #pragma unroll
;       for (int mi = 0; mi < 4; ++mi) a[mi] = *(const bf16x8*)(Ws + (wf * 64 + mi * 16 + lr) * LST + ks * 32 + lq * 8);
; #pragma unroll
;       for (int ni = 0; ni < 4; ++ni) {
;         const bf16x8 b = *(const bf16x8*)(Xs + (wt * 64 + ni * 16 + lr) * LST + ks * 32 + lq * 8);
; #pragma unroll
;         for (int mi = 0; mi < 4; ++mi) acc[mi][ni] = mfma16(a[mi], b, acc[mi][ni]);
;       }
;     }
	v_mfma_f32_16x16x32_bf16 v[2:5], v[26:29], v[86:89], v[2:5]
	v_mfma_f32_16x16x32_bf16 v[10:13], v[90:93], v[86:89], v[10:13]
	v_mfma_f32_16x16x32_bf16 v[22:25], v[102:105], v[86:89], v[22:25]
	v_mfma_f32_16x16x32_bf16 v[26:29], v[110:113], v[86:89], v[34:37]
	v_mfma_f32_16x16x32_bf16 v[18:21], v[46:49], v[50:53], v[18:21]
	v_mfma_f32_16x16x32_bf16 v[30:33], v[98:101], v[50:53], v[30:33]
	v_mfma_f32_16x16x32_bf16 v[34:37], v[106:109], v[50:53], v[42:45]
	v_mfma_f32_16x16x32_bf16 v[6:9], v[114:117], v[50:53], v[6:9]
	v_mfma_f32_16x16x32_bf16 v[14:17], v[46:49], v[118:121], v[14:17]
	v_mfma_f32_16x16x32_bf16 v[42:45], v[98:101], v[118:121], v[62:65]
	v_mfma_f32_16x16x32_bf16 v[50:53], v[106:109], v[118:121], v[70:73]
	v_mfma_f32_16x16x32_bf16 v[38:41], v[114:117], v[118:121], v[38:41]
	v_mfma_f32_16x16x32_bf16 v[58:61], v[46:49], v[122:125], v[58:61]
	v_mfma_f32_16x16x32_bf16 v[62:65], v[98:101], v[122:125], v[74:77]
	v_mfma_f32_16x16x32_bf16 v[54:57], v[114:117], v[122:125], v[54:57]
	s_waitcnt lgkmcnt(0)
	v_mfma_f32_16x16x32_bf16 v[2:5], v[46:49], v[126:129], v[2:5]
	v_mfma_f32_16x16x32_bf16 v[10:13], v[98:101], v[126:129], v[10:13]
	v_mfma_f32_16x16x32_bf16 v[22:25], v[106:109], v[126:129], v[22:25]
	v_mfma_f32_16x16x32_bf16 v[26:29], v[114:117], v[126:129], v[26:29]
	v_mfma_f32_16x16x32_bf16 v[70:73], v[106:109], v[122:125], v[94:97]
	s_setprio 0
	v_add_co_u32_e32 v82, vcc, s37, v82
	s_nop 1
	v_addc_co_u32_e32 v83, vcc, 0, v83, vcc
	global_load_dwordx4 v[46:49], v138, s[8:9] offset:256
	global_load_dwordx4 v[74:77], v138, s[8:9] offset:768
	global_load_dwordx4 v[86:89], v138, s[8:9] offset:1280
	global_load_dwordx4 v[90:93], v138, s[8:9] offset:1792
	global_load_dwordx4 v[94:97], v138, s[8:9] offset:2304
	global_load_dwordx4 v[98:101], v138, s[8:9] offset:2816
	global_load_dwordx4 v[102:105], v138, s[8:9] offset:3328
	global_load_dwordx4 v[106:109], v[82:83], off
	global_load_dwordx4 v[110:113], v[82:83], off offset:64
	global_load_dwordx4 v[114:117], v[82:83], off offset:128
	global_load_dwordx4 v[118:121], v[82:83], off offset:192
	global_load_dwordx4 v[122:125], v[82:83], off offset:256
	global_load_dwordx4 v[126:129], v[82:83], off offset:320
	global_load_dwordx4 v[130:133], v[82:83], off offset:384
	global_load_dwordx4 v[134:137], v[82:83], off offset:448
	s_nop 0
	global_load_dwordx4 v[138:141], v138, s[8:9] offset:3840
	s_barrier
	s_waitcnt vmcnt(15)
	ds_write_b128 v142, v[46:49] offset:36864
	s_waitcnt vmcnt(14)
	ds_write_b128 v142, v[74:77] offset:37152
	s_waitcnt vmcnt(13)
	ds_write_b128 v142, v[86:89] offset:37440
	s_waitcnt vmcnt(12)
	ds_write_b128 v142, v[90:93] offset:37728
	s_waitcnt vmcnt(11)
	ds_write_b128 v142, v[94:97] offset:38016
	s_waitcnt vmcnt(10)
	ds_write_b128 v142, v[98:101] offset:38304
	s_waitcnt vmcnt(9)
	ds_write_b128 v142, v[102:105] offset:38592
	s_waitcnt vmcnt(8)
	ds_write_b128 v142, v[106:109]
	s_waitcnt vmcnt(7)
	ds_write_b128 v142, v[110:113] offset:288
	s_waitcnt vmcnt(6)
	ds_write_b128 v142, v[114:117] offset:576
	s_waitcnt vmcnt(5)
	ds_write_b128 v142, v[118:121] offset:864
	s_waitcnt vmcnt(4)
	ds_write_b128 v142, v[122:125] offset:1152
	s_waitcnt vmcnt(3)
	ds_write_b128 v142, v[126:129] offset:1440
	s_waitcnt vmcnt(2)
	ds_write_b128 v142, v[130:133] offset:1728
	s_waitcnt vmcnt(1)
	ds_write_b128 v78, v[134:137]
	s_waitcnt vmcnt(0)
	ds_write_b128 v78, v[138:141] offset:36864
	s_waitcnt lgkmcnt(0)
	s_barrier
	s_setprio 1
	ds_read_b128 v[46:49], v0
	ds_read_b128 v[74:77], v1 offset:36864
	ds_read_b128 v[86:89], v0 offset:64
	ds_read_b128 v[90:93], v1 offset:36928
	ds_read_b128 v[94:97], v0 offset:4608
	ds_read_b128 v[98:101], v0 offset:4672
	ds_read_b128 v[102:105], v0 offset:9216
	ds_read_b128 v[106:109], v0 offset:9280
	ds_read_b128 v[110:113], v0 offset:13824
	ds_read_b128 v[114:117], v0 offset:13888
	s_waitcnt lgkmcnt(8)
	v_mfma_f32_16x16x32_bf16 v[18:21], v[46:49], v[74:77], v[18:21]
	s_waitcnt lgkmcnt(5)
	v_mfma_f32_16x16x32_bf16 v[30:33], v[94:97], v[74:77], v[30:33]
	s_waitcnt lgkmcnt(3)
	v_mfma_f32_16x16x32_bf16 v[34:37], v[102:105], v[74:77], v[34:37]
	s_waitcnt lgkmcnt(1)
	v_mfma_f32_16x16x32_bf16 v[6:9], v[110:113], v[74:77], v[6:9]
	ds_read_b128 v[74:77], v1 offset:41472
	ds_read_b128 v[118:121], v1 offset:41536
	s_waitcnt lgkmcnt(1)
	v_mfma_f32_16x16x32_bf16 v[14:17], v[46:49], v[74:77], v[14:17]
	v_mfma_f32_16x16x32_bf16 v[42:45], v[94:97], v[74:77], v[42:45]
	v_mfma_f32_16x16x32_bf16 v[50:53], v[102:105], v[74:77], v[50:53]
	v_mfma_f32_16x16x32_bf16 v[38:41], v[110:113], v[74:77], v[38:41]
	ds_read_b128 v[74:77], v1 offset:46080
	ds_read_b128 v[122:125], v1 offset:46144
	s_waitcnt lgkmcnt(1)
	v_mfma_f32_16x16x32_bf16 v[58:61], v[46:49], v[74:77], v[58:61]
	v_mfma_f32_16x16x32_bf16 v[62:65], v[94:97], v[74:77], v[62:65]
	v_mfma_f32_16x16x32_bf16 v[70:73], v[102:105], v[74:77], v[70:73]
	v_mfma_f32_16x16x32_bf16 v[54:57], v[110:113], v[74:77], v[54:57]
	ds_read_b128 v[74:77], v1 offset:50688
	ds_read_b128 v[126:129], v1 offset:50752
	s_waitcnt lgkmcnt(1)
	v_mfma_f32_16x16x32_bf16 v[2:5], v[46:49], v[74:77], v[2:5]
	v_mfma_f32_16x16x32_bf16 v[46:49], v[106:109], v[118:121], v[50:53]
	v_mfma_f32_16x16x32_bf16 v[50:53], v[86:89], v[122:125], v[58:61]
	v_mfma_f32_16x16x32_bf16 v[58:61], v[98:101], v[122:125], v[62:65]
	v_mfma_f32_16x16x32_bf16 v[62:65], v[106:109], v[122:125], v[70:73]
	s_nop 2
	ds_read_b128 v[70:73], v0 offset:128
	v_mfma_f32_16x16x32_bf16 v[10:13], v[94:97], v[74:77], v[10:13]
	v_mfma_f32_16x16x32_bf16 v[22:25], v[102:105], v[74:77], v[22:25]
	v_mfma_f32_16x16x32_bf16 v[26:29], v[110:113], v[74:77], v[26:29]
	v_mfma_f32_16x16x32_bf16 v[18:21], v[86:89], v[90:93], v[18:21]
	v_mfma_f32_16x16x32_bf16 v[30:33], v[98:101], v[90:93], v[30:33]
	v_mfma_f32_16x16x32_bf16 v[34:37], v[106:109], v[90:93], v[34:37]
	v_mfma_f32_16x16x32_bf16 v[6:9], v[114:117], v[90:93], v[6:9]
	v_mfma_f32_16x16x32_bf16 v[14:17], v[86:89], v[118:121], v[14:17]
	v_mfma_f32_16x16x32_bf16 v[42:45], v[98:101], v[118:121], v[42:45]
	v_mfma_f32_16x16x32_bf16 v[38:41], v[114:117], v[118:121], v[38:41]
	v_mfma_f32_16x16x32_bf16 v[54:57], v[114:117], v[122:125], v[54:57]
	s_waitcnt lgkmcnt(1)
; DI void rope4(f32x4& a, f32x4& b, const float* __restrict__ cs, int t, int lq) {
;   const f32x4 c01 = *(const f32x4*)(cs + (size_t)t * 32 + lq * 8), c23 = *(const f32x4*)(cs + (size_t)t * 32 + lq * 8 + 4);
;   const float cv[4] = {c01[0], c01[2], c23[0], c23[2]}, sv[4] = {c01[1], c01[3], c23[1], c23[3]};
; #pragma unroll
;   for (int j = 0; j < 4; ++j) {
;     const float x1 = a[j], x2 = b[j];
;     a[j] = x1 * cv[j] - x2 * sv[j];
;     b[j] = x2 * cv[j] + x1 * sv[j];
;   }
; }
; DI void phase2(const Params& p, int bid, int nblk, unsigned char* smem) {
;     ...
;       gemm_tile_k128((const u16*)(p.ws + OFF_WUQ), 768, tn * 128, t0, 256, xl, [&](f32x4 (&acc)[4][4], int fb, int tb, int lr, int lq, int wf, int wt) {
; #pragma unroll
;         for (int ni = 0; ni < 4; ++ni) {
;           const int t = tb + ni * 16 + lr; const float sc = rs[t - t0];
; #pragma unroll
;           for (int mi = 0; mi < 4; ++mi) acc[mi][ni] = acc[mi][ni] * sc;
;           if (tn >= 4) { rope4(acc[0][ni], acc[1][ni], p.out, t, lq); rope4(acc[2][ni], acc[3][ni], p.out, t, lq); }
;         }
	v_mfma_f32_16x16x32_bf16 v[2:5], v[86:89], v[126:129], v[2:5]
	ds_read_b128 v[74:77], v1 offset:36992
	ds_read_b128 v[86:89], v0 offset:192
	ds_read_b128 v[90:93], v1 offset:37056
	v_mfma_f32_16x16x32_bf16 v[10:13], v[98:101], v[126:129], v[10:13]
	ds_read_b128 v[94:97], v0 offset:4736
	ds_read_b128 v[98:101], v0 offset:4800
	v_mfma_f32_16x16x32_bf16 v[22:25], v[106:109], v[126:129], v[22:25]
	ds_read_b128 v[102:105], v0 offset:9344
	ds_read_b128 v[106:109], v0 offset:9408
	v_mfma_f32_16x16x32_bf16 v[26:29], v[114:117], v[126:129], v[26:29]
	ds_read_b128 v[110:113], v0 offset:13952
	ds_read_b128 v[114:117], v0 offset:14016
	s_waitcnt lgkmcnt(8)
	v_mfma_f32_16x16x32_bf16 v[18:21], v[70:73], v[74:77], v[18:21]
	s_waitcnt lgkmcnt(5)
	v_mfma_f32_16x16x32_bf16 v[30:33], v[94:97], v[74:77], v[30:33]
	s_waitcnt lgkmcnt(3)
	v_mfma_f32_16x16x32_bf16 v[34:37], v[102:105], v[74:77], v[34:37]
	s_waitcnt lgkmcnt(1)
	v_mfma_f32_16x16x32_bf16 v[6:9], v[110:113], v[74:77], v[6:9]
	ds_read_b128 v[74:77], v1 offset:41600
	ds_read_b128 v[118:121], v1 offset:41664
	s_waitcnt lgkmcnt(1)
	v_mfma_f32_16x16x32_bf16 v[14:17], v[70:73], v[74:77], v[14:17]
	v_mfma_f32_16x16x32_bf16 v[122:125], v[94:97], v[74:77], v[42:45]
	v_mfma_f32_16x16x32_bf16 v[126:129], v[102:105], v[74:77], v[46:49]
	v_mfma_f32_16x16x32_bf16 v[74:77], v[110:113], v[74:77], v[38:41]
	s_nop 2
	ds_read_b128 v[38:41], v1 offset:46208
	ds_read_b128 v[130:133], v1 offset:46272
	s_waitcnt lgkmcnt(1)
	v_mfma_f32_16x16x32_bf16 v[48:51], v[70:73], v[38:41], v[50:53]
	v_mfma_f32_16x16x32_bf16 v[58:61], v[94:97], v[38:41], v[58:61]
	v_mfma_f32_16x16x32_bf16 v[62:65], v[102:105], v[38:41], v[62:65]
	v_mfma_f32_16x16x32_bf16 v[52:55], v[110:113], v[38:41], v[54:57]
	ds_read_b128 v[38:41], v1 offset:50816
	ds_read_b128 v[134:137], v1 offset:50880
	s_waitcnt lgkmcnt(1)
	v_mfma_f32_16x16x32_bf16 v[0:3], v[70:73], v[38:41], v[2:5]
	v_mfma_f32_16x16x32_bf16 v[70:73], v[94:97], v[38:41], v[10:13]
	v_mfma_f32_16x16x32_bf16 v[94:97], v[102:105], v[38:41], v[22:25]
	v_mfma_f32_16x16x32_bf16 v[102:105], v[110:113], v[38:41], v[26:29]
	v_mfma_f32_16x16x32_bf16 v[110:113], v[86:89], v[90:93], v[18:21]
	v_mfma_f32_16x16x32_bf16 v[138:141], v[98:101], v[90:93], v[30:33]
	v_mfma_f32_16x16x32_bf16 v[142:145], v[106:109], v[90:93], v[34:37]
	v_mfma_f32_16x16x32_bf16 v[90:93], v[114:117], v[90:93], v[6:9]
	v_mfma_f32_16x16x32_bf16 v[44:47], v[86:89], v[118:121], v[14:17]
	v_mfma_f32_16x16x32_bf16 v[40:43], v[98:101], v[118:121], v[122:125]
	v_mfma_f32_16x16x32_bf16 v[36:39], v[106:109], v[118:121], v[126:129]
	v_mfma_f32_16x16x32_bf16 v[32:35], v[114:117], v[118:121], v[74:77]
	v_mfma_f32_16x16x32_bf16 v[28:31], v[86:89], v[130:133], v[48:51]
	v_mfma_f32_16x16x32_bf16 v[24:27], v[98:101], v[130:133], v[58:61]
	v_mfma_f32_16x16x32_bf16 v[20:23], v[106:109], v[130:133], v[62:65]
	v_mfma_f32_16x16x32_bf16 v[16:19], v[114:117], v[130:133], v[52:55]
	s_waitcnt lgkmcnt(0)
	v_mfma_f32_16x16x32_bf16 v[12:15], v[86:89], v[134:137], v[0:3]
	v_mfma_f32_16x16x32_bf16 v[8:11], v[98:101], v[134:137], v[70:73]
	v_mfma_f32_16x16x32_bf16 v[4:7], v[106:109], v[134:137], v[94:97]
	v_mfma_f32_16x16x32_bf16 v[0:3], v[114:117], v[134:137], v[102:105]
	s_setprio 0
	v_or3_b32 v69, v146, s20, v147
	v_subrev_u32_e32 v48, s20, v69
	v_lshl_add_u32 v48, v48, 2, v85
	ds_read_b32 v48, v48
	s_and_b32 s0, s0, 0xffff
	s_cmp_gt_u32 s0, 3
	s_cselect_b64 s[4:5], -1, 0
	s_cmp_lt_u32 s0, 4
	s_waitcnt lgkmcnt(0)
	v_mul_f32_e64 v62, v112, v48
	v_mul_f32_e64 v63, v113, v48
	v_mul_f32_e64 v60, v110, v48
	v_mul_f32_e64 v61, v111, v48
	v_mul_f32_e64 v56, v140, v48
	v_mul_f32_e64 v57, v141, v48
	v_mul_f32_e64 v54, v138, v48
	v_mul_f32_e64 v55, v139, v48
	v_mul_f32_e64 v58, v144, v48
	v_mul_f32_e64 v59, v145, v48
	v_mul_f32_e64 v52, v142, v48
	v_mul_f32_e64 v53, v143, v48
	v_mul_f32_e64 v50, v92, v48
	v_mul_f32_e64 v51, v93, v48
	v_mul_f32_e64 v49, v91, v48
	v_mul_f32_e64 v48, v90, v48
	v_lshlrev_b32_e32 v64, 2, v67
	s_cbranch_scc1 .LBB0_342
	v_lshlrev_b32_e32 v80, 7, v69
	v_lshl_add_u64 v[70:71], s[40:41], 0, v[80:81]
	v_mov_b32_e32 v65, v81
	v_lshl_add_u64 v[74:75], v[70:71], 0, v[64:65]
	global_load_dwordx4 v[70:73], v[74:75], off
	s_nop 0
	global_load_dwordx4 v[74:77], v[74:75], off offset:16
	s_waitcnt vmcnt(1)
	v_mov_b32_e32 v78, v70
	v_mov_b32_e32 v79, v72
	v_mov_b32_e32 v72, v71
	s_waitcnt vmcnt(0)
	v_mul_f32_e32 v70, v62, v74
	v_mul_f32_e32 v82, v56, v75
	v_mul_f32_e32 v86, v56, v74
	v_mul_f32_e32 v88, v62, v75
	v_mov_b32_e32 v56, v63
	v_mov_b32_e32 v62, v57
	v_mul_f32_e32 v90, v58, v74
	v_mul_f32_e32 v92, v50, v75
	v_mul_f32_e32 v74, v50, v74
	v_mul_f32_e32 v94, v58, v75
	v_mov_b32_e32 v50, v59
	v_mov_b32_e32 v58, v51
	v_mul_f32_e64 v96, v54, v72
	v_mul_f32_e64 v97, v55, v73
	v_mul_f32_e64 v54, v54, v78
	v_mul_f32_e64 v55, v55, v79
	v_mul_f32_e64 v56, v56, v76
	v_mul_f32_e64 v57, v57, v77
	v_mul_f32_e64 v62, v62, v76
	v_mul_f32_e64 v63, v63, v77
	v_mul_f32_e64 v98, v48, v72
	v_mul_f32_e64 v99, v49, v73
	v_mul_f32_e64 v50, v50, v76
	v_mul_f32_e64 v51, v51, v77
	v_mul_f32_e64 v58, v58, v76
	v_mul_f32_e64 v59, v59, v77
	v_mul_f32_e64 v48, v48, v78
	v_mul_f32_e64 v49, v49, v79
	v_mov_b32_e32 v71, v56
	v_mov_b32_e32 v83, v57
	v_fma_f32 v76, v60, v78, -v96
	v_fma_f32 v77, v61, v79, -v97
	v_mov_b32_e32 v89, v63
	v_mov_b32_e32 v87, v62
	v_fma_f32 v54, v60, v72, v54
	v_fma_f32 v55, v61, v73, v55
	v_mov_b32_e32 v91, v50
	v_mov_b32_e32 v93, v51
	v_fma_f32 v60, v52, v78, -v98
	v_fma_f32 v61, v53, v79, -v99
	v_mov_b32_e32 v95, v59
	v_mov_b32_e32 v75, v58
	v_fma_f32 v48, v52, v72, v48
	v_fma_f32 v49, v53, v73, v49
	v_add_f32_e64 v62, v70, -v82
	v_add_f32_e64 v63, v71, -v83
	v_add_f32_e64 v56, v88, v86
	v_add_f32_e64 v57, v89, v87
	v_add_f32_e64 v58, v90, -v92
	v_add_f32_e64 v59, v91, -v93
	v_add_f32_e64 v50, v94, v74
	v_add_f32_e64 v51, v95, v75
	v_mov_b32_e32 v52, v60
	v_mov_b32_e32 v53, v61
	v_mov_b32_e32 v60, v76
	v_mov_b32_e32 v61, v77
; DI void phase2(const Params& p, int bid, int nblk, unsigned char* smem) {
;     ...
;         for (int ni = 0; ni < 4; ++ni) {
;           const int t = tb + ni * 16 + lr; const float sc = rs[t - t0];
; #pragma unroll
;           for (int mi = 0; mi < 4; ++mi) acc[mi][ni] = acc[mi][ni] * sc;
;           if (tn >= 4) { rope4(acc[0][ni], acc[1][ni], p.out, t, lq); rope4(acc[2][ni], acc[3][ni], p.out, t, lq); }
;         }
.LBB0_342:
	v_or_b32_e32 v65, 16, v69
	v_subrev_u32_e32 v70, s20, v65
	v_lshl_add_u32 v70, v70, 2, v85
	ds_read_b32 v70, v70
	s_andn2_b64 vcc, exec, s[4:5]
	s_waitcnt lgkmcnt(0)
	v_mul_f32_e64 v46, v46, v70
	v_mul_f32_e64 v47, v47, v70
	v_mul_f32_e64 v44, v44, v70
	v_mul_f32_e64 v45, v45, v70
	v_mul_f32_e64 v42, v42, v70
	v_mul_f32_e64 v43, v43, v70
	v_mul_f32_e64 v40, v40, v70
	v_mul_f32_e64 v41, v41, v70
	v_mul_f32_e64 v38, v38, v70
	v_mul_f32_e64 v39, v39, v70
	v_mul_f32_e64 v36, v36, v70
	v_mul_f32_e64 v37, v37, v70
	v_mul_f32_e64 v34, v34, v70
	v_mul_f32_e64 v35, v35, v70
	v_cndmask_b32_e64 v71, 0, 1, s[4:5]
	v_cmp_ne_u32_e64 s[0:1], 1, v71
	v_mul_f32_e64 v32, v32, v70
	v_mul_f32_e64 v33, v33, v70
	s_cbranch_vccnz .LBB0_344
	v_lshlrev_b32_e32 v80, 7, v65
	v_lshl_add_u64 v[70:71], s[40:41], 0, v[80:81]
	v_mov_b32_e32 v65, v81
	v_lshl_add_u64 v[74:75], v[70:71], 0, v[64:65]
	global_load_dwordx4 v[70:73], v[74:75], off
	s_nop 0
	global_load_dwordx4 v[74:77], v[74:75], off offset:16
	s_waitcnt vmcnt(1)
	v_mov_b32_e32 v78, v70
	v_mov_b32_e32 v79, v72
	v_mov_b32_e32 v72, v71
	s_waitcnt vmcnt(0)
	v_mul_f32_e32 v70, v46, v74
	v_mul_f32_e32 v82, v42, v75
	v_mul_f32_e32 v86, v42, v74
	v_mul_f32_e32 v88, v46, v75
	v_mov_b32_e32 v42, v47
	v_mov_b32_e32 v46, v43
	v_mul_f32_e32 v90, v38, v74
	v_mul_f32_e32 v92, v34, v75
	v_mul_f32_e32 v74, v34, v74
	v_mul_f32_e32 v94, v38, v75
	v_mov_b32_e32 v34, v39
	v_mov_b32_e32 v38, v35
	v_mul_f32_e64 v96, v40, v72
	v_mul_f32_e64 v97, v41, v73
	v_mul_f32_e64 v40, v40, v78
	v_mul_f32_e64 v41, v41, v79
	v_mul_f32_e64 v42, v42, v76
	v_mul_f32_e64 v43, v43, v77
	v_mul_f32_e64 v46, v46, v76
	v_mul_f32_e64 v47, v47, v77
	v_mul_f32_e64 v98, v32, v72
	v_mul_f32_e64 v99, v33, v73
	v_mul_f32_e64 v34, v34, v76
	v_mul_f32_e64 v35, v35, v77
	v_mul_f32_e64 v38, v38, v76
	v_mul_f32_e64 v39, v39, v77
	v_mul_f32_e64 v32, v32, v78
	v_mul_f32_e64 v33, v33, v79
	v_mov_b32_e32 v71, v42
	v_mov_b32_e32 v83, v43
	v_fma_f32 v76, v44, v78, -v96
	v_fma_f32 v77, v45, v79, -v97
	v_mov_b32_e32 v89, v47
	v_mov_b32_e32 v87, v46
	v_fma_f32 v40, v44, v72, v40
	v_fma_f32 v41, v45, v73, v41
	v_mov_b32_e32 v91, v34
	v_mov_b32_e32 v93, v35
	v_fma_f32 v44, v36, v78, -v98
	v_fma_f32 v45, v37, v79, -v99
	v_mov_b32_e32 v95, v39
	v_mov_b32_e32 v75, v38
	v_fma_f32 v32, v36, v72, v32
	v_fma_f32 v33, v37, v73, v33
	v_add_f32_e64 v46, v70, -v82
	v_add_f32_e64 v47, v71, -v83
	v_add_f32_e64 v42, v88, v86
	v_add_f32_e64 v43, v89, v87
	v_add_f32_e64 v38, v90, -v92
	v_add_f32_e64 v39, v91, -v93
	v_add_f32_e64 v34, v94, v74
	v_add_f32_e64 v35, v95, v75
	v_mov_b32_e32 v36, v44
	v_mov_b32_e32 v37, v45
	v_mov_b32_e32 v44, v76
	v_mov_b32_e32 v45, v77
; DI void phase2(const Params& p, int bid, int nblk, unsigned char* smem) {
;     ...
;         for (int ni = 0; ni < 4; ++ni) {
;           const int t = tb + ni * 16 + lr; const float sc = rs[t - t0];
; #pragma unroll
;           for (int mi = 0; mi < 4; ++mi) acc[mi][ni] = acc[mi][ni] * sc;
;           if (tn >= 4) { rope4(acc[0][ni], acc[1][ni], p.out, t, lq); rope4(acc[2][ni], acc[3][ni], p.out, t, lq); }
;         }
.LBB0_344:
	v_or_b32_e32 v65, 32, v69
	v_subrev_u32_e32 v70, s20, v65
	v_lshl_add_u32 v70, v70, 2, v85
	ds_read_b32 v70, v70
	s_and_b64 vcc, exec, s[0:1]
	s_waitcnt lgkmcnt(0)
	v_mul_f32_e64 v30, v30, v70
	v_mul_f32_e64 v31, v31, v70
	v_mul_f32_e64 v28, v28, v70
	v_mul_f32_e64 v29, v29, v70
	v_mul_f32_e64 v26, v26, v70
	v_mul_f32_e64 v27, v27, v70
	v_mul_f32_e64 v24, v24, v70
	v_mul_f32_e64 v25, v25, v70
	v_mul_f32_e64 v22, v22, v70
	v_mul_f32_e64 v23, v23, v70
	v_mul_f32_e64 v20, v20, v70
	v_mul_f32_e64 v21, v21, v70
	v_mul_f32_e64 v18, v18, v70
	v_mul_f32_e64 v19, v19, v70
	v_mul_f32_e64 v16, v16, v70
	v_mul_f32_e64 v17, v17, v70
	s_cbranch_vccnz .LBB0_346
	v_lshlrev_b32_e32 v80, 7, v65
	v_lshl_add_u64 v[70:71], s[40:41], 0, v[80:81]
	v_mov_b32_e32 v65, v81
	v_lshl_add_u64 v[74:75], v[70:71], 0, v[64:65]
	global_load_dwordx4 v[70:73], v[74:75], off
	s_nop 0
	global_load_dwordx4 v[74:77], v[74:75], off offset:16
	s_waitcnt vmcnt(1)
	v_mov_b32_e32 v78, v70
	v_mov_b32_e32 v79, v72
	v_mov_b32_e32 v72, v71
	s_waitcnt vmcnt(0)
	v_mul_f32_e32 v70, v30, v74
	v_mul_f32_e32 v82, v26, v75
	v_mul_f32_e32 v86, v26, v74
	v_mul_f32_e32 v88, v30, v75
	v_mov_b32_e32 v26, v31
	v_mov_b32_e32 v30, v27
	v_mul_f32_e32 v90, v22, v74
	v_mul_f32_e32 v92, v18, v75
	v_mul_f32_e32 v74, v18, v74
	v_mul_f32_e32 v94, v22, v75
	v_mov_b32_e32 v18, v23
	v_mov_b32_e32 v22, v19
	v_mul_f32_e64 v96, v24, v72
	v_mul_f32_e64 v97, v25, v73
	v_mul_f32_e64 v24, v24, v78
	v_mul_f32_e64 v25, v25, v79
	v_mul_f32_e64 v26, v26, v76
	v_mul_f32_e64 v27, v27, v77
	v_mul_f32_e64 v30, v30, v76
	v_mul_f32_e64 v31, v31, v77
	v_mul_f32_e64 v98, v16, v72
	v_mul_f32_e64 v99, v17, v73
	v_mul_f32_e64 v18, v18, v76
	v_mul_f32_e64 v19, v19, v77
	v_mul_f32_e64 v22, v22, v76
	v_mul_f32_e64 v23, v23, v77
	v_mul_f32_e64 v16, v16, v78
	v_mul_f32_e64 v17, v17, v79
	v_mov_b32_e32 v71, v26
	v_mov_b32_e32 v83, v27
	v_fma_f32 v76, v28, v78, -v96
	v_fma_f32 v77, v29, v79, -v97
	v_mov_b32_e32 v89, v31
	v_mov_b32_e32 v87, v30
	v_fma_f32 v24, v28, v72, v24
	v_fma_f32 v25, v29, v73, v25
	v_mov_b32_e32 v91, v18
	v_mov_b32_e32 v93, v19
	v_fma_f32 v28, v20, v78, -v98
	v_fma_f32 v29, v21, v79, -v99
	v_mov_b32_e32 v95, v23
	v_mov_b32_e32 v75, v22
	v_fma_f32 v16, v20, v72, v16
	v_fma_f32 v17, v21, v73, v17
	v_add_f32_e64 v30, v70, -v82
	v_add_f32_e64 v31, v71, -v83
	v_add_f32_e64 v26, v88, v86
	v_add_f32_e64 v27, v89, v87
	v_add_f32_e64 v22, v90, -v92
	v_add_f32_e64 v23, v91, -v93
	v_add_f32_e64 v18, v94, v74
	v_add_f32_e64 v19, v95, v75
	v_mov_b32_e32 v20, v28
	v_mov_b32_e32 v21, v29
	v_mov_b32_e32 v28, v76
	v_mov_b32_e32 v29, v77
.LBB0_346:
	v_or_b32_e32 v65, 48, v69
	v_subrev_u32_e32 v69, s20, v65
	v_lshl_add_u32 v69, v69, 2, v85
	ds_read_b32 v70, v69
	s_and_b64 vcc, exec, s[0:1]
	s_waitcnt lgkmcnt(0)
	v_mul_f32_e64 v14, v14, v70
	v_mul_f32_e64 v15, v15, v70
	v_mul_f32_e64 v12, v12, v70
	v_mul_f32_e64 v13, v13, v70
	v_mul_f32_e64 v10, v10, v70
	v_mul_f32_e64 v11, v11, v70
	v_mul_f32_e64 v8, v8, v70
	v_mul_f32_e64 v9, v9, v70
	v_mul_f32_e64 v6, v6, v70
	v_mul_f32_e64 v7, v7, v70
	v_mul_f32_e64 v4, v4, v70
	v_mul_f32_e64 v5, v5, v70
	v_mul_f32_e64 v2, v2, v70
	v_mul_f32_e64 v3, v3, v70
	v_mul_f32_e64 v0, v0, v70
	v_mul_f32_e64 v1, v1, v70
	s_cbranch_vccnz .LBB0_348
	v_lshlrev_b32_e32 v80, 7, v65
	v_lshl_add_u64 v[70:71], s[40:41], 0, v[80:81]
	v_mov_b32_e32 v65, v81
	v_lshl_add_u64 v[64:65], v[70:71], 0, v[64:65]
	global_load_dwordx4 v[70:73], v[64:65], off
	global_load_dwordx4 v[74:77], v[64:65], off offset:16
	s_waitcnt vmcnt(1)
	v_mov_b32_e32 v64, v70
	v_mov_b32_e32 v65, v72
	v_mov_b32_e32 v72, v71
	s_waitcnt vmcnt(0)
	v_mul_f32_e32 v70, v14, v74
	v_mul_f32_e32 v78, v10, v75
	v_mul_f32_e32 v82, v10, v74
	v_mul_f32_e32 v86, v14, v75
	v_mov_b32_e32 v10, v15
	v_mov_b32_e32 v14, v11
	v_mul_f32_e32 v88, v6, v74
	v_mul_f32_e32 v90, v2, v75
	v_mul_f32_e32 v74, v2, v74
	v_mul_f32_e32 v92, v6, v75
	v_mov_b32_e32 v2, v7
	v_mov_b32_e32 v6, v3
	v_mul_f32_e64 v94, v8, v72
	v_mul_f32_e64 v95, v9, v73
	v_mul_f32_e64 v8, v8, v64
	v_mul_f32_e64 v9, v9, v65
	v_mul_f32_e64 v10, v10, v76
	v_mul_f32_e64 v11, v11, v77
	v_mul_f32_e64 v14, v14, v76
	v_mul_f32_e64 v15, v15, v77
	v_mul_f32_e64 v96, v0, v72
	v_mul_f32_e64 v97, v1, v73
	v_mul_f32_e64 v2, v2, v76
	v_mul_f32_e64 v3, v3, v77
	v_mul_f32_e64 v6, v6, v76
	v_mul_f32_e64 v7, v7, v77
	v_mul_f32_e64 v0, v0, v64
	v_mul_f32_e64 v1, v1, v65
	v_mov_b32_e32 v71, v10
	v_mov_b32_e32 v79, v11
	v_fma_f32 v76, v12, v64, -v94
	v_fma_f32 v77, v13, v65, -v95
	v_mov_b32_e32 v87, v15
	v_mov_b32_e32 v83, v14
	v_fma_f32 v8, v12, v72, v8
	v_fma_f32 v9, v13, v73, v9
	v_mov_b32_e32 v89, v2
	v_mov_b32_e32 v91, v3
	v_fma_f32 v12, v4, v64, -v96
	v_fma_f32 v13, v5, v65, -v97
	v_mov_b32_e32 v93, v7
	v_mov_b32_e32 v75, v6
	v_fma_f32 v0, v4, v72, v0
	v_fma_f32 v1, v5, v73, v1
	v_add_f32_e64 v14, v70, -v78
	v_add_f32_e64 v15, v71, -v79
	v_add_f32_e64 v10, v86, v82
	v_add_f32_e64 v11, v87, v83
	v_add_f32_e64 v6, v88, -v90
	v_add_f32_e64 v7, v89, -v91
	v_add_f32_e64 v2, v92, v74
	v_add_f32_e64 v3, v93, v75
	v_mov_b32_e32 v4, v12
	v_mov_b32_e32 v5, v13
	v_mov_b32_e32 v12, v76
	v_mov_b32_e32 v13, v77

; DI int tidx() { int t = __builtin_amdgcn_workitem_id_x(); asm volatile("" : "+v"(t)); return t; }
; DI float bflo(unsigned w) { return __uint_as_float(w << 16); }
; DI float bfhi(unsigned w) { return __uint_as_float(w & 0xffff0000u); }
;   DI unsigned rowoff(int r, int sch) const { const int g = r & 3, bc = r >> 2, b = bc / NCMP, c = bc - b * NCMP; return (unsigned)(b * Sn + c * 16) * 512u + g * 64 + sch; }
; template <class XL, class EP>
; DI void gemm_tile_k128(const u16* __restrict__ W, int ldw, int f0, int t0, int K, XL xl, EP ep, unsigned char* smem) {
;     ...
;   const unsigned wbyte = (((unsigned)(sch >> 5) * ldw + f0 + srow * 8) * 32u + (sch & 31)) * 2u;
;   const unsigned xbyte = xl.rowoff(t0 + srow * 8, sch) * 2u;
;   const int xrs = xl.rstride();
;   for (int kb = 0; kb < K; kb += 128) {
;     u32x4 wr[8], xr[8];
;     const char* wb = (const char*)(W + (size_t)(kb >> 5) * ldw * 32);
;     const char* xb = (const char*)xl.kbase(kb);
; #pragma unroll
;     for (int i = 0; i < 8; ++i) { wr[i] = *(const u32x4*)(wb + wbyte + i * 64); xr[i] = *(const u32x4*)(xb + xbyte + i * xrs); }
; DI void row_rstd(const u16* X, int ld, int K, int t0, float* rs) {
;   const int r = tidx() & 127;
;   const u16* xp = X + (size_t)(t0 + r) * ld;
;   float ss = 0.f;
;   for (int k = 0; k < K; k += 8) {
;     const u32x4 w = *(const u32x4*)(xp + k);
;     const float a0 = bflo(w.x), a1 = bfhi(w.x), a2 = bflo(w.y), a3 = bfhi(w.y), a4 = bflo(w.z), a5 = bfhi(w.z), a6 = bflo(w.w), a7 = bfhi(w.w);
;     ss += a0 * a0 + a1 * a1 + a2 * a2 + a3 * a3 + a4 * a4 + a5 * a5 + a6 * a6 + a7 * a7;
;   }
;   rs[r] = rsqrtf(ss / (float)K + 1e-6f);
; }
; DI void phase2(const Params& p, int bid, int nblk, unsigned char* smem) {
;     ...
;       const int r = tile - n_c1, tm = r / 12, tn = r % 12, t0 = tm * 128;
;       const u16* X = (const u16*)(p.ws + OFF_MKV);
;       __syncthreads();
;       row_rstd(X, 256, 128, t0, rs);
;       XPlain xl{X, 256};
;       u16* kvu = (u16*)(p.ws + OFF_KVU);
;       gemm_tile_k128((const u16*)(p.ws + OFF_WUKV), 1536, tn * 128, t0, 128, xl, [&](f32x4 (&acc)[4][4], int fb, int tb, int lr, int lq, int wf, int wt) {
.LBB0_351:
	global_load_dwordx4 v[4:7], v[0:1], off offset:-48
	global_load_dwordx4 v[8:11], v[0:1], off offset:-32
	global_load_dwordx4 v[12:15], v[0:1], off offset:-16
	global_load_dwordx4 v[16:19], v[0:1], off
	s_add_i32 s5, s5, 32
	v_lshl_add_u64 v[0:1], v[0:1], 0, 64
	s_cmpk_lt_u32 s5, 0x78
	s_waitcnt vmcnt(3)
	v_lshlrev_b32_e32 v20, 16, v4
	v_and_b32_e32 v21, 0xffff0000, v4
	v_and_b32_e32 v4, 0xffff0000, v5
	v_lshlrev_b32_e32 v5, 16, v5
	s_waitcnt vmcnt(2)
	v_lshlrev_b32_e32 v24, 16, v8
	v_and_b32_e32 v25, 0xffff0000, v8
	v_mul_f32_e64 v20, v20, v20
	v_mul_f32_e64 v21, v21, v21
	v_and_b32_e32 v8, 0xffff0000, v9
	v_lshlrev_b32_e32 v9, 16, v9
	s_waitcnt vmcnt(1)
	v_lshlrev_b32_e32 v28, 16, v12
	v_and_b32_e32 v29, 0xffff0000, v12
	v_mul_f32_e64 v4, v4, v4
	v_mul_f32_e64 v5, v5, v5
	v_mul_f32_e64 v24, v24, v24
	v_mul_f32_e64 v25, v25, v25
	v_add_f32_e32 v20, v20, v21
	v_and_b32_e32 v22, 0xffff0000, v6
	v_lshlrev_b32_e32 v23, 16, v6
	v_and_b32_e32 v12, 0xffff0000, v13
	v_lshlrev_b32_e32 v13, 16, v13
	s_waitcnt vmcnt(0)
	v_lshlrev_b32_e32 v32, 16, v16
	v_and_b32_e32 v33, 0xffff0000, v16
	v_mul_f32_e64 v8, v8, v8
	v_mul_f32_e64 v9, v9, v9
	v_mul_f32_e64 v28, v28, v28
	v_mul_f32_e64 v29, v29, v29
	v_add_f32_e32 v21, v24, v25
	v_add_f32_e32 v5, v5, v20
	v_and_b32_e32 v26, 0xffff0000, v10
	v_lshlrev_b32_e32 v27, 16, v10
	v_and_b32_e32 v16, 0xffff0000, v17
	v_lshlrev_b32_e32 v17, 16, v17
	v_mul_f32_e64 v22, v22, v22
	v_mul_f32_e64 v23, v23, v23
	v_mul_f32_e64 v12, v12, v12
	v_mul_f32_e64 v13, v13, v13
	v_mul_f32_e64 v32, v32, v32
	v_mul_f32_e64 v33, v33, v33
	v_add_f32_e32 v24, v28, v29
	v_add_f32_e32 v9, v9, v21
	v_add_f32_e32 v4, v4, v5
	v_and_b32_e32 v6, 0xffff0000, v7
	v_lshlrev_b32_e32 v7, 16, v7
	v_and_b32_e32 v30, 0xffff0000, v14
	v_lshlrev_b32_e32 v31, 16, v14
	v_mul_f32_e64 v26, v26, v26
	v_mul_f32_e64 v27, v27, v27
	v_mul_f32_e64 v16, v16, v16
	v_mul_f32_e64 v17, v17, v17
	v_add_f32_e32 v25, v32, v33
	v_add_f32_e32 v13, v13, v24
	v_add_f32_e32 v5, v8, v9
	v_add_f32_e32 v4, v23, v4
	v_and_b32_e32 v10, 0xffff0000, v11
	v_lshlrev_b32_e32 v11, 16, v11
	v_and_b32_e32 v34, 0xffff0000, v18
	v_lshlrev_b32_e32 v35, 16, v18
	v_mul_f32_e64 v6, v6, v6
	v_mul_f32_e64 v7, v7, v7
	v_mul_f32_e64 v30, v30, v30
	v_mul_f32_e64 v31, v31, v31
	v_add_f32_e32 v17, v17, v25
	v_add_f32_e32 v8, v12, v13
	v_add_f32_e32 v5, v27, v5
	v_add_f32_e32 v4, v22, v4
	v_and_b32_e32 v14, 0xffff0000, v15
	v_lshlrev_b32_e32 v15, 16, v15
	v_mul_f32_e64 v10, v10, v10
	v_mul_f32_e64 v11, v11, v11
	v_mul_f32_e64 v34, v34, v34
	v_mul_f32_e64 v35, v35, v35
	v_add_f32_e32 v9, v16, v17
	v_add_f32_e32 v8, v31, v8
	v_add_f32_e32 v5, v26, v5
	v_add_f32_e32 v4, v7, v4
	v_and_b32_e32 v18, 0xffff0000, v19
	v_lshlrev_b32_e32 v19, 16, v19
	v_mul_f32_e64 v14, v14, v14
	v_mul_f32_e64 v15, v15, v15
	v_add_f32_e32 v9, v35, v9
	v_add_f32_e32 v8, v30, v8
	v_add_f32_e32 v5, v11, v5
	v_add_f32_e32 v4, v6, v4
	v_mul_f32_e64 v18, v18, v18
	v_mul_f32_e64 v19, v19, v19
	v_add_f32_e32 v9, v34, v9
	v_add_f32_e32 v7, v15, v8
	v_add_f32_e32 v5, v10, v5
	v_add_f32_e32 v3, v3, v4
	v_add_f32_e32 v8, v19, v9
	v_add_f32_e32 v6, v14, v7
	v_add_f32_e32 v3, v3, v5
	v_add_f32_e32 v7, v18, v8
	v_add_f32_e32 v3, v3, v6
	v_add_f32_e32 v3, v3, v7
	s_cbranch_scc1 .LBB0_351
	v_fmamk_f32 v0, v3, 0x3c000000, v84
	v_mul_f32_e32 v1, 0x4b800000, v0
	v_cmp_gt_f32_e32 vcc, s35, v0
	s_mul_i32 s5, s0, 12
	v_mov_b32_e32 v65, v218
	v_cndmask_b32_e32 v0, v0, v1, vcc
	v_rsq_f32_e32 v0, v0
	s_sub_i32 s1, s1, s5
	s_lshl_b32 s1, s1, 7
	s_and_b32 s1, s1, 0xff80
	v_mul_f32_e32 v1, 0x45800000, v0
	v_cndmask_b32_e32 v0, v0, v1, vcc
	v_lshl_or_b32 v1, v2, 2, v85
	ds_write_b32 v1, v0
	s_nop 0
	v_lshlrev_b32_e32 v0, 3, v65
	v_and_b32_e32 v1, 0x78, v0
	v_bfe_u32 v0, v0, 5, 2
	v_ashrrev_i32_e32 v66, 1, v65
	v_mul_u32_u24_e32 v0, 0x600, v0
	v_and_b32_e32 v67, -8, v66
	v_lshlrev_b32_e32 v2, 4, v65
	v_add3_u32 v0, v67, s1, v0
	v_and_b32_e32 v2, 48, v2
	v_lshl_or_b32 v56, v0, 6, v2
	v_add_u32_e32 v0, s4, v67
	v_lshlrev_b32_e32 v64, 1, v1
	v_lshl_or_b32 v60, v0, 9, v64
	global_load_dwordx4 v[0:3], v60, s[10:11]
	global_load_dwordx4 v[4:7], v60, s[10:11] offset:512
	global_load_dwordx4 v[8:11], v60, s[10:11] offset:1024
	global_load_dwordx4 v[12:15], v60, s[10:11] offset:1536
	global_load_dwordx4 v[16:19], v60, s[10:11] offset:2048
	global_load_dwordx4 v[20:23], v60, s[10:11] offset:2560
	global_load_dwordx4 v[24:27], v60, s[10:11] offset:3072
	global_load_dwordx4 v[28:31], v56, s[12:13]
	global_load_dwordx4 v[32:35], v56, s[12:13] offset:64
	global_load_dwordx4 v[36:39], v56, s[12:13] offset:128
	global_load_dwordx4 v[40:43], v56, s[12:13] offset:192
	global_load_dwordx4 v[44:47], v56, s[12:13] offset:256
	global_load_dwordx4 v[48:51], v56, s[12:13] offset:320
	global_load_dwordx4 v[52:55], v56, s[12:13] offset:384
	s_nop 0
	global_load_dwordx4 v[56:59], v56, s[12:13] offset:448
	s_nop 0
	global_load_dwordx4 v[60:63], v60, s[10:11] offset:3584
	v_and_b32_e32 v122, 0xffffffc0, v66
	v_lshrrev_b32_e32 v68, 1, v65
	v_and_b32_e32 v80, 0x4f, v65
	v_and_or_b32 v69, v65, 15, v122
	v_mul_lo_u32 v65, v67, s36
	v_and_b32_e32 v123, 24, v68
	v_or_b32_e32 v68, 7, v66
	v_or_b32_e32 v67, v64, v65
	v_lshlrev_b32_e32 v66, 1, v123
	v_mad_u64_u32 v[64:65], s[4:5], v68, s36, v[64:65]
	s_waitcnt lgkmcnt(0)
	s_barrier
; DI f32x4 mfma16(bf16x8 a, bf16x8 b, f32x4 c) { return __builtin_amdgcn_mfma_f32_16x16x32_bf16(a, b, c, 0, 0, 0); }
; template <class XL, class EP>
; DI void gemm_tile_k128(const u16* __restrict__ W, int ldw, int f0, int t0, int K, XL xl, EP ep, unsigned char* smem) {
;     ...
;     __syncthreads();
; #pragma unroll
;     for (int i = 0; i < 8; ++i) { *(u32x4*)(Ws + (srow * 8 + i) * LST + sch) = wr[i]; *(u32x4*)(Xs + (srow * 8 + i) * LST + sch) = xr[i]; }
;     __syncthreads();
;     __builtin_amdgcn_s_setprio(1);
; #pragma unroll
;     for (int ks = 0; ks < 4; ++ks) {
;       bf16x8 a[4];
; #pragma unroll
;       for (int mi = 0; mi < 4; ++mi) a[mi] = *(const bf16x8*)(Ws + (wf * 64 + mi * 16 + lr) * LST + ks * 32 + lq * 8);
; #pragma unroll
;       for (int ni = 0; ni < 4; ++ni) {
;         const bf16x8 b = *(const bf16x8*)(Xs + (wt * 64 + ni * 16 + lr) * LST + ks * 32 + lq * 8);
; #pragma unroll
;         for (int mi = 0; mi < 4; ++mi) acc[mi][ni] = mfma16(a[mi], b, acc[mi][ni]);
;       }
;     }
	s_waitcnt vmcnt(15)
	ds_write_b128 v67, v[0:3] offset:36864
	s_waitcnt vmcnt(14)
	ds_write_b128 v67, v[4:7] offset:37152
	s_waitcnt vmcnt(13)
	ds_write_b128 v67, v[8:11] offset:37440
	s_waitcnt vmcnt(12)
	ds_write_b128 v67, v[12:15] offset:37728
	s_waitcnt vmcnt(11)
	ds_write_b128 v67, v[16:19] offset:38016
	s_waitcnt vmcnt(10)
	ds_write_b128 v67, v[20:23] offset:38304
	s_waitcnt vmcnt(9)
	ds_write_b128 v67, v[24:27] offset:38592
	s_waitcnt vmcnt(8)
	ds_write_b128 v67, v[28:31]
	s_waitcnt vmcnt(7)
	ds_write_b128 v67, v[32:35] offset:288
	s_waitcnt vmcnt(6)
	ds_write_b128 v67, v[36:39] offset:576
	s_waitcnt vmcnt(5)
	ds_write_b128 v67, v[40:43] offset:864
	s_waitcnt vmcnt(4)
	ds_write_b128 v67, v[44:47] offset:1152
	s_waitcnt vmcnt(3)
	ds_write_b128 v67, v[48:51] offset:1440
	s_waitcnt vmcnt(2)
	ds_write_b128 v67, v[52:55] offset:1728
	s_waitcnt vmcnt(1)
	ds_write_b128 v64, v[56:59]
	s_waitcnt vmcnt(0)
	ds_write_b128 v64, v[60:63] offset:36864
	s_waitcnt lgkmcnt(0)
	s_barrier
	s_setprio 1
	v_mad_u64_u32 v[82:83], s[4:5], v69, s36, v[66:67]
	ds_read_b128 v[0:3], v82
	v_mul_u32_u24_e32 v4, 0x90, v80
	v_lshl_add_u32 v83, v4, 1, v66
	ds_read_b128 v[4:7], v83 offset:36864
	ds_read_b128 v[8:11], v82 offset:64
	ds_read_b128 v[12:15], v83 offset:36928
	ds_read_b128 v[20:23], v82 offset:4608
	ds_read_b128 v[24:27], v82 offset:4672
	ds_read_b128 v[32:35], v82 offset:9216
	ds_read_b128 v[36:39], v82 offset:9280
	ds_read_b128 v[44:47], v82 offset:13824
	ds_read_b128 v[48:51], v82 offset:13888
	ds_read_b128 v[52:55], v83 offset:41472
	ds_read_b128 v[56:59], v83 offset:41536
	ds_read_b128 v[72:75], v83 offset:46080
	ds_read_b128 v[76:79], v83 offset:46144
	ds_read_b128 v[98:101], v83 offset:50688
	ds_read_b128 v[102:105], v83 offset:50752
	s_waitcnt lgkmcnt(14)
	v_mfma_f32_16x16x32_bf16 v[16:19], v[0:3], v[4:7], 0
	s_waitcnt lgkmcnt(11)
	v_mfma_f32_16x16x32_bf16 v[28:31], v[20:23], v[4:7], 0
	s_waitcnt lgkmcnt(9)
	v_mfma_f32_16x16x32_bf16 v[40:43], v[32:35], v[4:7], 0
	s_waitcnt lgkmcnt(7)
	v_mfma_f32_16x16x32_bf16 v[4:7], v[44:47], v[4:7], 0
	s_waitcnt lgkmcnt(5)
	v_mfma_f32_16x16x32_bf16 v[60:63], v[0:3], v[52:55], 0
	v_mfma_f32_16x16x32_bf16 v[64:67], v[20:23], v[52:55], 0
	v_mfma_f32_16x16x32_bf16 v[68:71], v[32:35], v[52:55], 0
	v_mfma_f32_16x16x32_bf16 v[52:55], v[44:47], v[52:55], 0
	s_waitcnt lgkmcnt(3)
	v_mfma_f32_16x16x32_bf16 v[86:89], v[0:3], v[72:75], 0
	v_mfma_f32_16x16x32_bf16 v[90:93], v[20:23], v[72:75], 0
	s_waitcnt lgkmcnt(1)
	v_mfma_f32_16x16x32_bf16 v[0:3], v[0:3], v[98:101], 0
	v_mfma_f32_16x16x32_bf16 v[20:23], v[20:23], v[98:101], 0
	v_mfma_f32_16x16x32_bf16 v[16:19], v[8:11], v[12:15], v[16:19]
	v_mfma_f32_16x16x32_bf16 v[28:31], v[24:27], v[12:15], v[28:31]
	v_mfma_f32_16x16x32_bf16 v[40:43], v[36:39], v[12:15], v[40:43]
	v_mfma_f32_16x16x32_bf16 v[4:7], v[48:51], v[12:15], v[4:7]
	v_mfma_f32_16x16x32_bf16 v[12:15], v[8:11], v[56:59], v[60:63]
	v_mfma_f32_16x16x32_bf16 v[60:63], v[24:27], v[56:59], v[64:67]
	v_mfma_f32_16x16x32_bf16 v[64:67], v[36:39], v[56:59], v[68:71]
	v_mfma_f32_16x16x32_bf16 v[52:55], v[48:51], v[56:59], v[52:55]
	v_mfma_f32_16x16x32_bf16 v[56:59], v[8:11], v[76:79], v[86:89]
	v_mfma_f32_16x16x32_bf16 v[68:71], v[24:27], v[76:79], v[90:93]
	s_waitcnt lgkmcnt(0)
	v_mfma_f32_16x16x32_bf16 v[0:3], v[8:11], v[102:105], v[0:3]
	v_mfma_f32_16x16x32_bf16 v[8:11], v[24:27], v[102:105], v[20:23]
	ds_read_b128 v[24:27], v82 offset:128
	v_mfma_f32_16x16x32_bf16 v[94:97], v[32:35], v[72:75], 0
	v_mfma_f32_16x16x32_bf16 v[72:75], v[44:47], v[72:75], 0
	v_mfma_f32_16x16x32_bf16 v[32:35], v[32:35], v[98:101], 0
	v_mfma_f32_16x16x32_bf16 v[44:47], v[44:47], v[98:101], 0
	v_mfma_f32_16x16x32_bf16 v[86:89], v[36:39], v[76:79], v[94:97]
	v_mfma_f32_16x16x32_bf16 v[72:75], v[48:51], v[76:79], v[72:75]
	v_mfma_f32_16x16x32_bf16 v[20:23], v[36:39], v[102:105], v[32:35]
	v_mfma_f32_16x16x32_bf16 v[32:35], v[48:51], v[102:105], v[44:47]
	ds_read_b128 v[36:39], v83 offset:36992
	s_nop 2
	ds_read_b128 v[44:47], v82 offset:192
	ds_read_b128 v[48:51], v83 offset:37056
	ds_read_b128 v[76:79], v82 offset:4736
	ds_read_b128 v[90:93], v82 offset:4800
	ds_read_b128 v[94:97], v82 offset:9344
	ds_read_b128 v[98:101], v82 offset:9408
	ds_read_b128 v[102:105], v82 offset:13952
	ds_read_b128 v[106:109], v82 offset:14016
	s_waitcnt lgkmcnt(8)
	v_mfma_f32_16x16x32_bf16 v[16:19], v[24:27], v[36:39], v[16:19]
	s_waitcnt lgkmcnt(5)
	v_mfma_f32_16x16x32_bf16 v[28:31], v[76:79], v[36:39], v[28:31]
	s_waitcnt lgkmcnt(3)
	v_mfma_f32_16x16x32_bf16 v[40:43], v[94:97], v[36:39], v[40:43]
	s_waitcnt lgkmcnt(1)
	v_mfma_f32_16x16x32_bf16 v[4:7], v[102:105], v[36:39], v[4:7]
	ds_read_b128 v[36:39], v83 offset:41600
	ds_read_b128 v[110:113], v83 offset:41664
	s_waitcnt lgkmcnt(1)
	v_mfma_f32_16x16x32_bf16 v[12:15], v[24:27], v[36:39], v[12:15]
	v_mfma_f32_16x16x32_bf16 v[60:63], v[76:79], v[36:39], v[60:63]
	v_mfma_f32_16x16x32_bf16 v[64:67], v[94:97], v[36:39], v[64:67]
	v_mfma_f32_16x16x32_bf16 v[36:39], v[102:105], v[36:39], v[52:55]
	s_nop 2
	ds_read_b128 v[52:55], v83 offset:46208
	ds_read_b128 v[114:117], v83 offset:46272
	s_waitcnt lgkmcnt(1)
	v_mfma_f32_16x16x32_bf16 v[56:59], v[24:27], v[52:55], v[56:59]
	v_mfma_f32_16x16x32_bf16 v[68:71], v[76:79], v[52:55], v[68:71]
	v_mfma_f32_16x16x32_bf16 v[86:89], v[94:97], v[52:55], v[86:89]
	v_mfma_f32_16x16x32_bf16 v[52:55], v[102:105], v[52:55], v[72:75]
	s_nop 2
	ds_read_b128 v[72:75], v83 offset:50816
	ds_read_b128 v[118:121], v83 offset:50880
	s_waitcnt lgkmcnt(1)
; DI void store4(u16* dst, f32x4 v) { uint2 w; w.x = cvtpk(v[0], v[1]); w.y = cvtpk(v[2], v[3]); *(uint2*)dst = w; }
; DI void epi_store128(const f32x4 (&acc)[4][4], unsigned char* smem, u16* dst, int ld, int wf, int wt, int lr, int lq) {
;   constexpr int EST = 136;
;   u16* Ls = (u16*)smem;
;   __syncthreads();
; #pragma unroll
;   for (int mi = 0; mi < 4; ++mi)
; #pragma unroll
;     for (int ni = 0; ni < 4; ++ni) store4(Ls + (wt * 64 + ni * 16 + lr) * EST + wf * 64 + mi * 16 + lq * 4, acc[mi][ni]);
;   __syncthreads();
; DI void phase2(const Params& p, int bid, int nblk, unsigned char* smem) {
;     ...
;       gemm_tile_k128((const u16*)(p.ws + OFF_WUKV), 1536, tn * 128, t0, 128, xl, [&](f32x4 (&acc)[4][4], int fb, int tb, int lr, int lq, int wf, int wt) {
; #pragma unroll
;         for (int ni = 0; ni < 4; ++ni) {
;           const int t = tb + ni * 16 + lr; const float sc = rs[t - t0];
; #pragma unroll
;           for (int mi = 0; mi < 4; ++mi) acc[mi][ni] = acc[mi][ni] * sc;
;         }
;         epi_store128(acc, smem, kvu + (size_t)t0 * 1536 + tn * 128, 1536, wf, wt, lr, lq);
	v_mfma_f32_16x16x32_bf16 v[0:3], v[24:27], v[72:75], v[0:3]
	v_mfma_f32_16x16x32_bf16 v[8:11], v[76:79], v[72:75], v[8:11]
	v_mfma_f32_16x16x32_bf16 v[20:23], v[94:97], v[72:75], v[20:23]
	v_mfma_f32_16x16x32_bf16 v[24:27], v[102:105], v[72:75], v[32:35]
	v_mfma_f32_16x16x32_bf16 v[16:19], v[44:47], v[48:51], v[16:19]
	v_mfma_f32_16x16x32_bf16 v[28:31], v[90:93], v[48:51], v[28:31]
	v_mfma_f32_16x16x32_bf16 v[32:35], v[98:101], v[48:51], v[40:43]
	v_mfma_f32_16x16x32_bf16 v[4:7], v[106:109], v[48:51], v[4:7]
	v_mfma_f32_16x16x32_bf16 v[12:15], v[44:47], v[110:113], v[12:15]
	v_mfma_f32_16x16x32_bf16 v[40:43], v[90:93], v[110:113], v[60:63]
	v_mfma_f32_16x16x32_bf16 v[48:51], v[98:101], v[110:113], v[64:67]
	v_mfma_f32_16x16x32_bf16 v[36:39], v[106:109], v[110:113], v[36:39]
	v_mfma_f32_16x16x32_bf16 v[56:59], v[44:47], v[114:117], v[56:59]
	v_mfma_f32_16x16x32_bf16 v[60:63], v[90:93], v[114:117], v[68:71]
	v_mfma_f32_16x16x32_bf16 v[64:67], v[98:101], v[114:117], v[86:89]
	v_mfma_f32_16x16x32_bf16 v[52:55], v[106:109], v[114:117], v[52:55]
	s_waitcnt lgkmcnt(0)
	v_mfma_f32_16x16x32_bf16 v[0:3], v[44:47], v[118:121], v[0:3]
	v_mfma_f32_16x16x32_bf16 v[8:11], v[90:93], v[118:121], v[8:11]
	v_mfma_f32_16x16x32_bf16 v[20:23], v[98:101], v[118:121], v[20:23]
	v_mfma_f32_16x16x32_bf16 v[24:27], v[106:109], v[118:121], v[24:27]
	s_setprio 0
	v_lshlrev_b32_e32 v45, 2, v80
	v_or_b32_e32 v44, 0x12000, v45
	v_or_b32_e32 v46, 0x12040, v45
	ds_read_b32 v44, v44
	v_or_b32_e32 v47, 0x12080, v45
	v_or_b32_e32 v45, 0x120c0, v45
	ds_read_b32 v46, v46
	ds_read_b32 v68, v47
	ds_read_b32 v70, v45
	s_waitcnt lgkmcnt(0)
	v_mul_f32_e64 v18, v18, v44
	v_mul_f32_e64 v19, v19, v44
	v_mul_f32_e64 v16, v16, v44
	v_mul_f32_e64 v17, v17, v44
	v_mul_f32_e64 v30, v30, v44
	v_mul_f32_e64 v31, v31, v44
	v_mul_f32_e64 v28, v28, v44
	v_mul_f32_e64 v29, v29, v44
	v_mul_f32_e64 v34, v34, v44
	v_mul_f32_e64 v35, v35, v44
	v_mul_f32_e64 v32, v32, v44
	v_mul_f32_e64 v33, v33, v44
	v_mul_f32_e64 v6, v6, v44
	v_mul_f32_e64 v7, v7, v44
	v_mul_f32_e64 v4, v4, v44
	v_mul_f32_e64 v5, v5, v44
	v_mul_f32_e64 v44, v50, v46
	v_mul_f32_e64 v45, v51, v46
	v_mul_f32_e64 v50, v56, v68
	v_mul_f32_e64 v51, v57, v68
	v_mul_f32_e64 v56, v62, v68
	v_mul_f32_e64 v57, v63, v68
	v_mul_f32_e64 v62, v64, v68
	v_mul_f32_e64 v63, v65, v68
	v_mul_f32_e64 v2, v2, v70
	v_mul_f32_e64 v3, v3, v70
	v_mul_f32_e64 v0, v0, v70
	v_mul_f32_e64 v1, v1, v70
	v_lshl_or_b32 v64, v122, 1, v123
	v_mul_u32_u24_e32 v65, 0x88, v80
	v_mul_f32_e64 v14, v14, v46
	v_mul_f32_e64 v15, v15, v46
	v_mul_f32_e64 v12, v12, v46
	v_mul_f32_e64 v13, v13, v46
	v_mul_f32_e64 v42, v42, v46
	v_mul_f32_e64 v43, v43, v46
	v_mul_f32_e64 v40, v40, v46
	v_mul_f32_e64 v41, v41, v46
	v_lshl_add_u32 v64, v65, 1, v64
	v_cvt_pk_bf16_f32 v16, v16, v17
	v_cvt_pk_bf16_f32 v17, v18, v19
	v_cvt_pk_bf16_f32 v0, v0, v1
	v_cvt_pk_bf16_f32 v1, v2, v3
	v_cvt_pk_bf16_f32 v2, v28, v29
	v_cvt_pk_bf16_f32 v3, v30, v31
	v_mul_f32_e64 v48, v48, v46
	v_mul_f32_e64 v49, v49, v46
	v_mul_f32_e64 v38, v38, v46
	v_mul_f32_e64 v39, v39, v46
	v_mul_f32_e64 v36, v36, v46
	v_mul_f32_e64 v37, v37, v46
	v_mul_f32_e64 v46, v58, v68
	v_mul_f32_e64 v47, v59, v68
	v_mul_f32_e64 v58, v60, v68
	v_mul_f32_e64 v59, v61, v68
	s_barrier
; DI int tidx() { int t = __builtin_amdgcn_workitem_id_x(); asm volatile("" : "+v"(t)); return t; }
; DI void store4(u16* dst, f32x4 v) { uint2 w; w.x = cvtpk(v[0], v[1]); w.y = cvtpk(v[2], v[3]); *(uint2*)dst = w; }
; DI void epi_store128(const f32x4 (&acc)[4][4], unsigned char* smem, u16* dst, int ld, int wf, int wt, int lr, int lq) {
;   constexpr int EST = 136;
;   u16* Ls = (u16*)smem;
;   __syncthreads();
; #pragma unroll
;   for (int mi = 0; mi < 4; ++mi)
; #pragma unroll
;     for (int ni = 0; ni < 4; ++ni) store4(Ls + (wt * 64 + ni * 16 + lr) * EST + wf * 64 + mi * 16 + lq * 4, acc[mi][ni]);
;   __syncthreads();
;   const int tid = tidx();
; #pragma unroll
;   for (int i = 0; i < 8; ++i) {
;     const int c = tid + 256 * i, row = c >> 4, ch = (c & 15) * 8;
;     *(u32x4*)(dst + (size_t)row * ld + ch) = *(const u32x4*)(Ls + row * EST + ch);
;   }
	v_cvt_pk_bf16_f32 v12, v12, v13
	v_cvt_pk_bf16_f32 v13, v14, v15
	ds_write2_b64 v64, v[16:17], v[2:3] offset1:4
	v_cvt_pk_bf16_f32 v2, v40, v41
	v_cvt_pk_bf16_f32 v3, v42, v43
	v_add_u32_e32 v16, 0x1000, v64
	v_mul_f32_e64 v10, v10, v70
	v_mul_f32_e64 v11, v11, v70
	v_mul_f32_e64 v8, v8, v70
	v_mul_f32_e64 v9, v9, v70
	v_cvt_pk_bf16_f32 v14, v50, v51
	v_cvt_pk_bf16_f32 v15, v46, v47
	ds_write2_b64 v16, v[12:13], v[2:3] offset0:32 offset1:36
	v_cvt_pk_bf16_f32 v2, v58, v59
	v_cvt_pk_bf16_f32 v3, v56, v57
	v_add_u32_e32 v12, 0x2000, v64
	ds_write2_b64 v12, v[14:15], v[2:3] offset0:64 offset1:68
	v_cvt_pk_bf16_f32 v2, v8, v9
	v_cvt_pk_bf16_f32 v3, v10, v11
	v_add_u32_e32 v13, 0x3000, v64
	ds_write2_b64 v13, v[0:1], v[2:3] offset0:96 offset1:100
	v_cvt_pk_bf16_f32 v0, v32, v33
	v_cvt_pk_bf16_f32 v1, v34, v35
	v_cvt_pk_bf16_f32 v4, v4, v5
	v_cvt_pk_bf16_f32 v5, v6, v7
	v_mul_f32_e64 v60, v66, v68
	v_mul_f32_e64 v61, v67, v68
	v_mul_f32_e64 v54, v54, v68
	v_mul_f32_e64 v55, v55, v68
	v_mul_f32_e64 v52, v52, v68
	v_mul_f32_e64 v53, v53, v68
	s_mul_i32 s0, s0, 0x60000
	v_cvt_pk_bf16_f32 v2, v48, v49
	v_cvt_pk_bf16_f32 v3, v44, v45
	ds_write2_b64 v64, v[0:1], v[4:5] offset0:8 offset1:12
	v_cvt_pk_bf16_f32 v0, v36, v37
	v_cvt_pk_bf16_f32 v1, v38, v39
	v_mul_f32_e64 v22, v22, v70
	v_mul_f32_e64 v23, v23, v70
	v_mul_f32_e64 v20, v20, v70
	v_mul_f32_e64 v21, v21, v70
	v_mul_f32_e64 v26, v26, v70
	v_mul_f32_e64 v27, v27, v70
	v_mul_f32_e64 v24, v24, v70
	v_mul_f32_e64 v25, v25, v70
	s_add_u32 s0, s22, s0
	v_cvt_pk_bf16_f32 v8, v62, v63
	v_cvt_pk_bf16_f32 v9, v60, v61
	ds_write2_b64 v16, v[2:3], v[0:1] offset0:40 offset1:44
	v_cvt_pk_bf16_f32 v0, v52, v53
	v_cvt_pk_bf16_f32 v1, v54, v55
	s_addc_u32 s4, s23, 0
	s_lshl_b32 s1, s1, 1
	v_cvt_pk_bf16_f32 v10, v20, v21
	v_cvt_pk_bf16_f32 v11, v22, v23
	ds_write2_b64 v12, v[8:9], v[0:1] offset0:72 offset1:76
	v_cvt_pk_bf16_f32 v0, v24, v25
	v_cvt_pk_bf16_f32 v1, v26, v27
	v_mov_b32_e32 v12, v218
	s_add_u32 s0, s0, s1
	ds_write2_b64 v13, v[10:11], v[0:1] offset0:104 offset1:108
	s_waitcnt lgkmcnt(0)
	s_barrier
	s_addc_u32 s1, s4, 0
	v_lshlrev_b32_e32 v0, 4, v12
	v_and_b32_e32 v80, 0xf0, v0
	v_ashrrev_i32_e32 v10, 4, v12
	v_add_u32_e32 v4, 0x100, v12
	v_lshl_add_u64 v[8:9], s[0:1], 0, v[80:81]
	v_mad_u64_u32 v[0:1], s[0:1], v10, s44, v[80:81]
	v_ashrrev_i32_e32 v13, 4, v4
	ds_read_b128 v[0:3], v0
	v_mad_u64_u32 v[4:5], s[0:1], v13, s44, v[80:81]
	ds_read_b128 v[4:7], v4
	v_mad_i64_i32 v[10:11], s[0:1], v10, s46, v[8:9]
	s_waitcnt lgkmcnt(1)
	global_store_dwordx4 v[10:11], v[0:3], off
	s_nop 1
	v_mad_i64_i32 v[0:1], s[0:1], v13, s46, v[8:9]
	s_waitcnt lgkmcnt(0)
	global_store_dwordx4 v[0:1], v[4:7], off
	v_add_u32_e32 v0, 0x200, v12
	v_ashrrev_i32_e32 v10, 4, v0
	v_add_u32_e32 v4, 0x300, v12
	v_mad_u64_u32 v[0:1], s[0:1], v10, s44, v[80:81]
	v_ashrrev_i32_e32 v13, 4, v4
	ds_read_b128 v[0:3], v0
	v_mad_u64_u32 v[4:5], s[0:1], v13, s44, v[80:81]
	ds_read_b128 v[4:7], v4
	v_mad_i64_i32 v[10:11], s[0:1], v10, s46, v[8:9]
	s_waitcnt lgkmcnt(1)
	global_store_dwordx4 v[10:11], v[0:3], off
	s_nop 1
	v_mad_i64_i32 v[0:1], s[0:1], v13, s46, v[8:9]
	s_waitcnt lgkmcnt(0)
	global_store_dwordx4 v[0:1], v[4:7], off
	v_add_u32_e32 v0, 0x400, v12
	v_ashrrev_i32_e32 v10, 4, v0
	v_add_u32_e32 v4, 0x500, v12
	v_mad_u64_u32 v[0:1], s[0:1], v10, s44, v[80:81]
	v_ashrrev_i32_e32 v13, 4, v4
	ds_read_b128 v[0:3], v0
	v_mad_u64_u32 v[4:5], s[0:1], v13, s44, v[80:81]
	ds_read_b128 v[4:7], v4
	v_mad_i64_i32 v[10:11], s[0:1], v10, s46, v[8:9]
	s_waitcnt lgkmcnt(1)
	global_store_dwordx4 v[10:11], v[0:3], off
	s_nop 1
	v_mad_i64_i32 v[0:1], s[0:1], v13, s46, v[8:9]
	s_waitcnt lgkmcnt(0)
	global_store_dwordx4 v[0:1], v[4:7], off
	v_add_u32_e32 v0, 0x600, v12
	v_ashrrev_i32_e32 v10, 4, v0
	v_add_u32_e32 v4, 0x700, v12
	v_mad_u64_u32 v[0:1], s[0:1], v10, s44, v[80:81]
	v_ashrrev_i32_e32 v12, 4, v4
	ds_read_b128 v[0:3], v0
	v_mad_u64_u32 v[4:5], s[0:1], v12, s44, v[80:81]
	ds_read_b128 v[4:7], v4
	v_mad_i64_i32 v[10:11], s[0:1], v10, s46, v[8:9]
	s_waitcnt lgkmcnt(1)
	global_store_dwordx4 v[10:11], v[0:3], off
	s_nop 1
	v_mad_i64_i32 v[0:1], s[0:1], v12, s46, v[8:9]
	s_waitcnt lgkmcnt(0)
	global_store_dwordx4 v[0:1], v[4:7], off

; template <int NI, class XL, class EP>
; DI void gemm_tile(const u16* __restrict__ W, int ldw, int f0, int t0, int K, XL xl, EP ep, unsigned char* smem) {
;     ...
;   auto gload = [&](int it) {
;     const int k = it * 32;
;     const char* wb = (const char*)(W + (size_t)(k >> 5) * ldw * 32);
;     const char* xb = (const char*)xl.kbase(k);
; #pragma unroll
;     for (int i = 0; i < 2; ++i) wr[i] = *(const u32x4*)(wb + wbyte + i * 64);
; #pragma unroll
;     for (int i = 0; i < XR; ++i) xr[i] = *(const u32x4*)(xb + xbyte + i * xrs);
;   };
;   auto lstore = [&](int buf) {
;     u16* Ws = S0 + buf * BUF; u16* Xs = Ws + 128 * LST;
; #pragma unroll
;     for (int i = 0; i < 2; ++i) *(u32x4*)(Ws + (srow * 2 + i) * LST + sch) = wr[i];
; #pragma unroll
;     for (int i = 0; i < XR; ++i) *(u32x4*)(Xs + (srow * XR + i) * LST + sch) = xr[i];
;   };
;   gload(0);
;   __syncthreads();
;   lstore(0);
;   __syncthreads();
;   if (nk > 1) gload(1);
;   for (int it = 0; it < nk; ++it) {
;     const u16* Ws = S0 + (it & 1) * BUF; const u16* Xs = Ws + 128 * LST;
;     __builtin_amdgcn_s_setprio(1);
;     bf16x8 a[4];
; #pragma unroll
;     for (int mi = 0; mi < 4; ++mi) a[mi] = *(const bf16x8*)(Ws + (wf * 64 + mi * 16 + lr) * LST + lq * 8);
; #pragma unroll
;     for (int ni = 0; ni < NI; ++ni) {
;       const bf16x8 b = *(const bf16x8*)(Xs + (wt * (NI * 16) + ni * 16 + lr) * LST + lq * 8);
; #pragma unroll
;       for (int mi = 0; mi < 4; ++mi) acc[mi][ni] = mfma16(a[mi], b, acc[mi][ni]);
;     }
;     __builtin_amdgcn_sched_group_barrier(0x100, 6, 0);
; #pragma unroll
;     for (int ni = 0; ni < NI; ++ni) { __builtin_amdgcn_sched_group_barrier(0x008, 4, 0); if (ni + 2 < NI) __builtin_amdgcn_sched_group_barrier(0x100, 1, 0); }
;     __builtin_amdgcn_s_setprio(0);
;     if (it + 1 < nk) lstore((it + 1) & 1);
;     if (it + 2 < nk) gload(it + 2);
;     __syncthreads();
;   }
; DI void phase2(const Params& p, int bid, int nblk, unsigned char* smem) {
;     ...
;       const int kv = tile / 254, r = tile % 254, tm = r >> 1, tn = r & 1;
;       const u16* W = (const u16*)(p.ws + (kv ? OFF_W1V : OFF_W1K));
;       XCmp xl{(const u16*)(p.ws + OFF_KVC), kv * 256};
;       const float* b1 = (const float*)(p.ws + OFF_B1) + kv * 256;
;       u16* hid = (u16*)(p.ws + OFF_HID) + (size_t)kv * CROWS * 256;
.LBB0_356:
	s_bitcmp1_b32 s21, 0
	s_cselect_b32 s54, 0, 0x6000
	s_setprio 1
	v_or_b32_e32 v98, s54, v92
	v_lshl_add_u32 v110, v93, 1, v98
	ds_read_b128 v[94:97], v110
	v_lshl_add_u32 v118, v91, 1, v98
	ds_read_b128 v[98:101], v110 offset:1536
	ds_read_b128 v[106:109], v110 offset:3072
	ds_read_b128 v[110:113], v110 offset:4608
	ds_read_b128 v[102:105], v118 offset:12288
	ds_read_b128 v[114:117], v118 offset:13824
	s_waitcnt lgkmcnt(1)
	v_mfma_f32_16x16x32_bf16 v[76:79], v[94:97], v[102:105], v[76:79]
	v_mfma_f32_16x16x32_bf16 v[68:71], v[98:101], v[102:105], v[68:71]
	v_mfma_f32_16x16x32_bf16 v[52:55], v[106:109], v[102:105], v[52:55]
	v_mfma_f32_16x16x32_bf16 v[36:39], v[110:113], v[102:105], v[36:39]
	ds_read_b128 v[102:105], v118 offset:15360
	s_waitcnt lgkmcnt(1)
	v_mfma_f32_16x16x32_bf16 v[72:75], v[94:97], v[114:117], v[72:75]
	v_mfma_f32_16x16x32_bf16 v[60:63], v[98:101], v[114:117], v[60:63]
	v_mfma_f32_16x16x32_bf16 v[44:47], v[106:109], v[114:117], v[44:47]
	v_mfma_f32_16x16x32_bf16 v[28:31], v[110:113], v[114:117], v[28:31]
	ds_read_b128 v[114:117], v118 offset:16896
	s_waitcnt lgkmcnt(1)
	v_mfma_f32_16x16x32_bf16 v[64:67], v[94:97], v[102:105], v[64:67]
	v_mfma_f32_16x16x32_bf16 v[48:51], v[98:101], v[102:105], v[48:51]
	v_mfma_f32_16x16x32_bf16 v[32:35], v[106:109], v[102:105], v[32:35]
	v_mfma_f32_16x16x32_bf16 v[20:23], v[110:113], v[102:105], v[20:23]
	s_waitcnt lgkmcnt(0)
	v_mfma_f32_16x16x32_bf16 v[56:59], v[94:97], v[114:117], v[56:59]
	v_mfma_f32_16x16x32_bf16 v[40:43], v[98:101], v[114:117], v[40:43]
	v_mfma_f32_16x16x32_bf16 v[24:27], v[106:109], v[114:117], v[24:27]
	v_mfma_f32_16x16x32_bf16 v[16:19], v[110:113], v[114:117], v[16:19]
	s_setprio 0
	s_cselect_b32 s54, 0x6000, 0
	s_and_b32 s55, s33, 0xfc00
	s_and_b32 s56, s53, 32
	v_add_u32_e32 v94, s54, v90
	s_add_u32 s54, s4, s55
	s_addc_u32 s55, s5, 0
	s_lshl_b32 s56, s56, 1
	s_add_u32 s54, s54, s56
	s_addc_u32 s55, s55, 0
	s_waitcnt vmcnt(0)
	ds_write_b128 v94, v[8:11] offset:12384
	v_lshl_add_u64 v[8:9], s[54:55], 0, v[80:81]
	ds_write_b128 v94, v[4:7]
	ds_write_b128 v94, v[0:3] offset:96
	ds_write_b128 v94, v[12:15] offset:12288
	global_load_dwordx4 v[4:7], v[82:83], off
	global_load_dwordx4 v[0:3], v[82:83], off offset:64
	global_load_dwordx4 v[12:15], v[8:9], off
	s_addk_i32 s33, 0x200
	global_load_dwordx4 v[8:11], v[8:9], off offset:128
	s_add_i32 s53, s53, 32
	s_add_i32 s21, s21, 1
	v_lshl_add_u64 v[82:83], v[82:83], 0, s[18:19]
	s_cmp_lg_u32 s21, 63
	s_waitcnt lgkmcnt(0)
	s_barrier
	s_cbranch_scc1 .LBB0_356
	s_lshl_b64 s[0:1], s[0:1], 2
	s_add_u32 s0, s26, s0
	s_addc_u32 s1, s27, s1
	s_mul_hi_i32 s4, s20, 0x7f0000
	s_mul_i32 s20, s20, 0x7f0000
	s_setprio 1
	v_lshl_add_u32 v80, v93, 1, v92
	ds_read_b128 v[94:97], v80
	ds_read_b128 v[98:101], v80 offset:1536
	ds_read_b128 v[106:109], v80 offset:3072
	ds_read_b128 v[110:113], v80 offset:4608
	v_lshl_add_u32 v82, v91, 1, v92
	ds_read_b128 v[102:105], v82 offset:12288
	ds_read_b128 v[114:117], v82 offset:13824
	s_waitcnt lgkmcnt(1)
	v_mfma_f32_16x16x32_bf16 v[76:79], v[94:97], v[102:105], v[76:79]
	v_mfma_f32_16x16x32_bf16 v[68:71], v[98:101], v[102:105], v[68:71]
	v_mfma_f32_16x16x32_bf16 v[52:55], v[106:109], v[102:105], v[52:55]
	v_mfma_f32_16x16x32_bf16 v[36:39], v[110:113], v[102:105], v[36:39]
	ds_read_b128 v[102:105], v82 offset:15360
	s_waitcnt lgkmcnt(1)
	v_mfma_f32_16x16x32_bf16 v[72:75], v[94:97], v[114:117], v[72:75]
	v_mfma_f32_16x16x32_bf16 v[118:121], v[98:101], v[114:117], v[60:63]
	v_mfma_f32_16x16x32_bf16 v[122:125], v[106:109], v[114:117], v[44:47]
	v_mfma_f32_16x16x32_bf16 v[114:117], v[110:113], v[114:117], v[28:31]
	s_nop 2
	ds_read_b128 v[28:31], v82 offset:16896
	s_waitcnt lgkmcnt(1)
	v_mfma_f32_16x16x32_bf16 v[64:67], v[94:97], v[102:105], v[64:67]
	v_mfma_f32_16x16x32_bf16 v[48:51], v[98:101], v[102:105], v[48:51]
	v_mfma_f32_16x16x32_bf16 v[32:35], v[106:109], v[102:105], v[32:35]
	v_mfma_f32_16x16x32_bf16 v[102:105], v[110:113], v[102:105], v[20:23]
	s_waitcnt lgkmcnt(0)
	v_mfma_f32_16x16x32_bf16 v[92:95], v[94:97], v[28:31], v[56:59]
	v_mfma_f32_16x16x32_bf16 v[96:99], v[98:101], v[28:31], v[40:43]
	v_mfma_f32_16x16x32_bf16 v[106:109], v[106:109], v[28:31], v[24:27]
	v_mfma_f32_16x16x32_bf16 v[110:113], v[110:113], v[28:31], v[16:19]
	s_setprio 0
	s_add_u32 s20, s28, s20
	s_waitcnt vmcnt(3)
	ds_write_b128 v90, v[4:7] offset:24576
	s_waitcnt vmcnt(2)
	ds_write_b128 v90, v[0:3] offset:24672
	s_waitcnt vmcnt(1)
	ds_write_b128 v90, v[12:15] offset:36864
	s_waitcnt vmcnt(0)
	ds_write_b128 v90, v[8:11] offset:36960
	s_waitcnt lgkmcnt(0)
	s_barrier
	s_addc_u32 s21, s29, s4
	s_setprio 1
	ds_read_b128 v[0:3], v80 offset:24576
	ds_read_b128 v[16:19], v80 offset:26112
	ds_read_b128 v[126:129], v80 offset:27648
	ds_read_b128 v[130:133], v80 offset:29184
	ds_read_b128 v[4:7], v82 offset:36864
	ds_read_b128 v[8:11], v82 offset:38400
	s_waitcnt lgkmcnt(1)
	v_mfma_f32_16x16x32_bf16 v[76:79], v[0:3], v[4:7], v[76:79]
	v_mfma_f32_16x16x32_bf16 v[44:47], v[16:19], v[4:7], v[68:71]
	v_mfma_f32_16x16x32_bf16 v[28:31], v[126:129], v[4:7], v[52:55]
	v_mfma_f32_16x16x32_bf16 v[12:15], v[130:133], v[4:7], v[36:39]
	ds_read_b128 v[4:7], v82 offset:39936
	s_waitcnt lgkmcnt(1)
	v_mfma_f32_16x16x32_bf16 v[60:63], v[0:3], v[8:11], v[72:75]
	v_mfma_f32_16x16x32_bf16 v[40:43], v[16:19], v[8:11], v[118:121]
	v_mfma_f32_16x16x32_bf16 v[24:27], v[126:129], v[8:11], v[122:125]
	v_mfma_f32_16x16x32_bf16 v[8:11], v[130:133], v[8:11], v[114:117]
	ds_read_b128 v[52:55], v82 offset:41472
	s_waitcnt lgkmcnt(1)
	v_mfma_f32_16x16x32_bf16 v[56:59], v[0:3], v[4:7], v[64:67]
	v_mfma_f32_16x16x32_bf16 v[36:39], v[16:19], v[4:7], v[48:51]
	v_mfma_f32_16x16x32_bf16 v[20:23], v[126:129], v[4:7], v[32:35]
	v_mfma_f32_16x16x32_bf16 v[4:7], v[130:133], v[4:7], v[102:105]
	s_waitcnt lgkmcnt(0)
	v_mfma_f32_16x16x32_bf16 v[48:51], v[0:3], v[52:55], v[92:95]
	v_mfma_f32_16x16x32_bf16 v[32:35], v[16:19], v[52:55], v[96:99]
	v_mfma_f32_16x16x32_bf16 v[16:19], v[126:129], v[52:55], v[106:109]
	v_mfma_f32_16x16x32_bf16 v[0:3], v[130:133], v[52:55], v[110:113]
	s_setprio 0
	v_add_u32_e32 v72, s7, v89
	v_lshl_or_b32 v66, v86, 2, v72
	v_ashrrev_i32_e32 v67, 31, v66
	v_lshl_add_u64 v[68:69], v[66:67], 2, s[0:1]
	s_barrier
; DI void store4(u16* dst, f32x4 v) { uint2 w; w.x = cvtpk(v[0], v[1]); w.y = cvtpk(v[2], v[3]); *(uint2*)dst = w; }
; DI void phase2(const Params& p, int bid, int nblk, unsigned char* smem) {
;     ...
;       gemm_tile<4>(W, 256, tn * 128, tm * 128, 2048, xl, [&](f32x4 (&acc)[4][4], int fb, int tb, int lr, int lq, int wf, int wt) {
; #pragma unroll
;         for (int mi = 0; mi < 4; ++mi) {
;           const int f = fb + mi * 16 + lq * 4; const float4 bb = *(const float4*)(b1 + f);
; #pragma unroll
;           for (int ni = 0; ni < 4; ++ni) {
;             const int t = tb + ni * 16 + lr; f32x4 v = acc[mi][ni]; v[0] += bb.x; v[1] += bb.y; v[2] += bb.z; v[3] += bb.w;
; #pragma unroll
;             for (int j = 0; j < 4; ++j) { const float xx = v[j]; const float u = 0.7978845608028654f * (xx + 0.044715f * xx * xx * xx); const float th = 1.0f - 2.0f / (__expf(2.0f * u) + 1.0f); v[j] = 0.5f * xx * (1.0f + th); }
;             store4(hid + ((size_t)(f >> 5) * CROWS + t) * 32 + (f & 31), v);
;           }
	global_load_dwordx4 v[52:55], v[68:69], off
	v_and_b32_e32 v64, 64, v87
	v_or3_b32 v64, v64, s6, v88
	v_ashrrev_i32_e32 v67, 5, v72
	v_ashrrev_i32_e32 v65, 31, v64
	v_mad_i64_i32 v[70:71], s[0:1], v67, s52, v[64:65]
	v_lshlrev_b64 v[70:71], 6, v[70:71]
	v_lshl_add_u64 v[70:71], s[20:21], 0, v[70:71]
	s_waitcnt vmcnt(0)
	v_add_f32_e64 v74, v76, v52
	v_add_f32_e64 v75, v77, v53
	v_add_f32_e64 v76, v78, v54
	v_add_f32_e64 v77, v79, v55
	v_mul_f32_e32 v73, 0x3d372713, v74
	v_mul_f32_e32 v80, 0x3d372713, v75
	v_mul_f32_e32 v87, 0x3d372713, v76
	v_mul_f32_e32 v73, v74, v73
	v_mul_f32_e32 v80, v75, v80
	v_mul_f32_e64 v78, v74, 0.5
	v_mul_f32_e64 v79, v75, 0.5
	v_mul_f32_e32 v87, v76, v87
	v_fma_f32 v73, v74, v73, v74
	v_fma_f32 v74, v75, v80, v75
	v_mul_f32_e32 v88, 0x3d372713, v77
	v_fma_f32 v75, v76, v87, v76
	v_mul_f32_e32 v73, 0x3f4c422a, v73
	v_mul_f32_e32 v74, 0x3f4c422a, v74
	v_mul_f32_e32 v88, v77, v88
	v_mul_f32_e32 v75, 0x3f4c422a, v75
	v_add_f32_e32 v73, v73, v73
	v_add_f32_e32 v74, v74, v74
	v_mul_f32_e64 v82, v76, 0.5
	v_mul_f32_e64 v83, v77, 0.5
	v_fma_f32 v76, v77, v88, v77
	v_add_f32_e32 v75, v75, v75
	v_mul_f32_e32 v73, 0x3fb8aa3b, v73
	v_mul_f32_e32 v77, 0x3fb8aa3b, v74
	v_mul_f32_e32 v80, 0x3fb8aa3b, v75
	v_exp_f32_e32 v74, v73
	v_exp_f32_e32 v75, v77
	v_mul_f32_e32 v76, 0x3f4c422a, v76
	v_add_f32_e32 v76, v76, v76
	v_mul_f32_e32 v87, 0x3fb8aa3b, v76
	v_add_f32_e64 v74, v74, 1.0
	v_add_f32_e64 v75, v75, 1.0
	v_exp_f32_e32 v76, v80
	v_add_f32_e64 v60, v60, v52
	v_add_f32_e64 v61, v61, v53
	v_exp_f32_e32 v77, v87
	v_mul_f32_e32 v89, 0x3d372713, v60
	v_mul_f32_e32 v73, v60, v89
	s_mov_b64 vcc, s[0:1]
	v_fma_f32 v73, v60, v73, v60
	v_rcp_f32_e32 v75, v75
	s_nop 0
	v_add_f32_e32 v75, v75, v75
	v_add_f32_e64 v76, v76, 1.0
	v_add_f32_e64 v77, v77, 1.0
	v_rcp_f32_e32 v74, v74
	s_nop 0
	v_add_f32_e32 v74, v74, v74
	v_mul_f32_e32 v73, 0x3f4c422a, v73
	v_add_f32_e64 v74, -v74, 1.0
	v_add_f32_e64 v75, -v75, 1.0
	v_add_f32_e32 v73, v73, v73
	v_add_f32_e64 v74, v74, 1.0
	v_add_f32_e64 v75, v75, 1.0
	v_mul_f32_e32 v73, 0x3fb8aa3b, v73
	v_mul_f32_e64 v74, v78, v74
	v_mul_f32_e64 v75, v79, v75
	v_exp_f32_e32 v78, v73
	v_mul_f32_e32 v73, 0x3d372713, v61
	v_mul_f32_e32 v73, v61, v73
	v_fma_f32 v73, v61, v73, v61
	v_mul_f32_e32 v73, 0x3f4c422a, v73
	v_add_f32_e32 v73, v73, v73
	v_mul_f32_e32 v73, 0x3fb8aa3b, v73
	v_exp_f32_e32 v79, v73
	s_mov_b64 vcc, s[4:5]
	s_mov_b64 vcc, s[6:7]
	v_rcp_f32_e32 v77, v77
	s_nop 0
	v_add_f32_e32 v77, v77, v77
	v_add_f32_e64 v78, v78, 1.0
	v_add_f32_e64 v79, v79, 1.0
	v_rcp_f32_e32 v76, v76
	s_nop 0
	v_add_f32_e32 v76, v76, v76
	v_add_f32_e64 v76, -v76, 1.0
	v_add_f32_e64 v77, -v77, 1.0
	v_lshlrev_b32_e32 v80, 3, v86
	v_add_f32_e64 v76, v76, 1.0
	v_add_f32_e64 v77, v77, 1.0
	v_cvt_pk_bf16_f32 v74, v74, v75
	v_mul_f32_e64 v76, v82, v76
	v_mul_f32_e64 v77, v83, v77
	v_lshl_add_u64 v[82:83], v[70:71], 0, v[80:81]
	v_cvt_pk_bf16_f32 v75, v76, v77
	global_store_dwordx2 v[82:83], v[74:75], off
	v_rcp_f32_e32 v75, v79
	s_nop 0
	v_add_f32_e32 v75, v75, v75
	v_add_f32_e64 v62, v62, v54
	v_add_f32_e64 v63, v63, v55
	v_mul_f32_e32 v74, 0x3d372713, v62
	v_mul_f32_e32 v74, v62, v74
	v_fma_f32 v74, v62, v74, v62
	v_mul_f32_e32 v74, 0x3f4c422a, v74
	v_add_f32_e32 v74, v74, v74
	v_mul_f32_e32 v74, 0x3fb8aa3b, v74
	v_exp_f32_e32 v76, v74
	v_mul_f32_e32 v74, 0x3d372713, v63
	v_mul_f32_e32 v74, v63, v74
	v_fma_f32 v74, v63, v74, v63
	v_mul_f32_e32 v74, 0x3f4c422a, v74
	v_add_f32_e32 v74, v74, v74
	v_mul_f32_e32 v74, 0x3fb8aa3b, v74
	v_exp_f32_e32 v77, v74
	v_rcp_f32_e32 v74, v78
	s_nop 0
	v_add_f32_e32 v74, v74, v74
	v_add_f32_e64 v74, -v74, 1.0
	v_add_f32_e64 v75, -v75, 1.0
	v_add_f32_e64 v76, v76, 1.0
	v_add_f32_e64 v77, v77, 1.0
	v_mul_f32_e64 v60, v60, 0.5
	v_mul_f32_e64 v61, v61, 0.5
	v_add_f32_e64 v74, v74, 1.0
	v_add_f32_e64 v75, v75, 1.0
	v_add_f32_e64 v56, v56, v52
	v_add_f32_e64 v57, v57, v53
	v_mul_f32_e64 v74, v60, v74
	v_mul_f32_e64 v75, v61, v75
	v_rcp_f32_e32 v61, v77
	s_nop 0
	v_add_f32_e32 v61, v61, v61
	v_mul_f32_e64 v62, v62, 0.5
	v_mul_f32_e64 v63, v63, 0.5
	v_mul_f32_e32 v73, 0x3d372713, v56
	v_mul_f32_e32 v73, v56, v73
	v_fma_f32 v73, v56, v73, v56
	v_mul_f32_e32 v73, 0x3f4c422a, v73
	v_add_f32_e32 v73, v73, v73
	v_mul_f32_e32 v73, 0x3fb8aa3b, v73
	v_exp_f32_e32 v78, v73
	v_mul_f32_e32 v73, 0x3d372713, v57
	v_mul_f32_e32 v73, v57, v73
	v_fma_f32 v73, v57, v73, v57
	v_mul_f32_e32 v73, 0x3f4c422a, v73
	v_add_f32_e32 v73, v73, v73
	v_mul_f32_e32 v73, 0x3fb8aa3b, v73
	v_exp_f32_e32 v79, v73
	v_rcp_f32_e32 v60, v76
	s_nop 0
	v_add_f32_e32 v60, v60, v60
	v_add_f32_e64 v60, -v60, 1.0
	v_add_f32_e64 v61, -v61, 1.0
	v_cvt_pk_bf16_f32 v74, v74, v75
	v_add_f32_e64 v60, v60, 1.0
	v_add_f32_e64 v61, v61, 1.0
	v_add_f32_e64 v78, v78, 1.0
	v_add_f32_e64 v79, v79, 1.0
	v_mul_f32_e64 v76, v62, v60
	v_mul_f32_e64 v77, v63, v61
	v_or_b32_e32 v60, 16, v64
	v_ashrrev_i32_e32 v61, 31, v60
	v_mad_i64_i32 v[62:63], s[0:1], v67, s52, v[60:61]
	v_lshlrev_b64 v[62:63], 6, v[62:63]
	v_lshl_add_u64 v[62:63], s[20:21], 0, v[62:63]
	v_lshl_add_u64 v[82:83], v[62:63], 0, v[80:81]
	v_cvt_pk_bf16_f32 v75, v76, v77
	global_store_dwordx2 v[82:83], v[74:75], off
	v_rcp_f32_e32 v75, v79
	s_nop 0
	v_add_f32_e32 v75, v75, v75
	v_add_f32_e64 v58, v58, v54
	v_add_f32_e64 v59, v59, v55
	v_mul_f32_e32 v74, 0x3d372713, v58
	v_mul_f32_e32 v74, v58, v74
	v_fma_f32 v74, v58, v74, v58
	v_mul_f32_e32 v74, 0x3f4c422a, v74
	v_add_f32_e32 v74, v74, v74
	v_mul_f32_e32 v74, 0x3fb8aa3b, v74
	v_exp_f32_e32 v76, v74
	v_mul_f32_e32 v74, 0x3d372713, v59
	v_mul_f32_e32 v74, v59, v74
	v_fma_f32 v74, v59, v74, v59
	v_mul_f32_e32 v74, 0x3f4c422a, v74
	v_add_f32_e32 v74, v74, v74
; DI void store4(u16* dst, f32x4 v) { uint2 w; w.x = cvtpk(v[0], v[1]); w.y = cvtpk(v[2], v[3]); *(uint2*)dst = w; }
; DI void phase2(const Params& p, int bid, int nblk, unsigned char* smem) {
;     ...
;         for (int mi = 0; mi < 4; ++mi) {
;           const int f = fb + mi * 16 + lq * 4; const float4 bb = *(const float4*)(b1 + f);
; #pragma unroll
;           for (int ni = 0; ni < 4; ++ni) {
;             const int t = tb + ni * 16 + lr; f32x4 v = acc[mi][ni]; v[0] += bb.x; v[1] += bb.y; v[2] += bb.z; v[3] += bb.w;
; #pragma unroll
;             for (int j = 0; j < 4; ++j) { const float xx = v[j]; const float u = 0.7978845608028654f * (xx + 0.044715f * xx * xx * xx); const float th = 1.0f - 2.0f / (__expf(2.0f * u) + 1.0f); v[j] = 0.5f * xx * (1.0f + th); }
;             store4(hid + ((size_t)(f >> 5) * CROWS + t) * 32 + (f & 31), v);
;           }
	v_mul_f32_e32 v74, 0x3fb8aa3b, v74
	v_exp_f32_e32 v77, v74
	v_rcp_f32_e32 v74, v78
	s_nop 0
	v_add_f32_e32 v74, v74, v74
	v_add_f32_e64 v74, -v74, 1.0
	v_add_f32_e64 v75, -v75, 1.0
	v_add_f32_e64 v76, v76, 1.0
	v_add_f32_e64 v77, v77, 1.0
	v_mul_f32_e64 v56, v56, 0.5
	v_mul_f32_e64 v57, v57, 0.5
	v_add_f32_e64 v74, v74, 1.0
	v_add_f32_e64 v75, v75, 1.0
	v_add_f32_e64 v48, v48, v52
	v_add_f32_e64 v49, v49, v53
	v_mul_f32_e64 v74, v56, v74
	v_mul_f32_e64 v75, v57, v75
	v_rcp_f32_e32 v57, v77
	s_nop 0
	v_add_f32_e32 v57, v57, v57
	v_mul_f32_e32 v52, 0x3d372713, v48
	v_mul_f32_e32 v53, 0x3d372713, v49
	v_mul_f32_e32 v52, v48, v52
	v_mul_f32_e32 v53, v49, v53
	v_fma_f32 v52, v48, v52, v48
	v_fma_f32 v53, v49, v53, v49
	v_mul_f32_e32 v52, 0x3f4c422a, v52
	v_mul_f32_e32 v53, 0x3f4c422a, v53
	v_add_f32_e32 v52, v52, v52
	v_add_f32_e32 v53, v53, v53
	v_mul_f32_e32 v52, 0x3fb8aa3b, v52
	v_mul_f32_e32 v53, 0x3fb8aa3b, v53
	v_exp_f32_e32 v52, v52
	v_exp_f32_e32 v53, v53
	v_rcp_f32_e32 v56, v76
	s_nop 0
	v_add_f32_e32 v56, v56, v56
	v_add_f32_e64 v56, -v56, 1.0
	v_add_f32_e64 v57, -v57, 1.0
	v_mul_f32_e64 v58, v58, 0.5
	v_mul_f32_e64 v59, v59, 0.5
	v_add_f32_e64 v56, v56, 1.0
	v_add_f32_e64 v57, v57, 1.0
	v_add_f32_e64 v52, v52, 1.0
	v_add_f32_e64 v53, v53, 1.0
	v_mul_f32_e64 v76, v58, v56
	v_mul_f32_e64 v77, v59, v57
	v_or_b32_e32 v56, 32, v64
	v_ashrrev_i32_e32 v57, 31, v56
	v_mad_i64_i32 v[58:59], s[0:1], v67, s52, v[56:57]
	v_lshlrev_b64 v[58:59], 6, v[58:59]
	v_lshl_add_u64 v[58:59], s[20:21], 0, v[58:59]
	v_lshl_add_u64 v[78:79], v[58:59], 0, v[80:81]
	v_cvt_pk_bf16_f32 v74, v74, v75
	v_cvt_pk_bf16_f32 v75, v76, v77
	global_store_dwordx2 v[78:79], v[74:75], off
	v_add_f32_e64 v50, v50, v54
	v_add_f32_e64 v51, v51, v55
	v_mul_f32_e32 v54, 0x3d372713, v50
	v_mul_f32_e32 v55, 0x3d372713, v51
	v_mul_f32_e32 v54, v50, v54
	v_mul_f32_e32 v55, v51, v55
	v_fma_f32 v54, v50, v54, v50
	v_fma_f32 v55, v51, v55, v51
	v_mul_f32_e32 v54, 0x3f4c422a, v54
	v_mul_f32_e32 v55, 0x3f4c422a, v55
	v_rcp_f32_e32 v53, v53
	s_nop 0
	v_add_f32_e32 v53, v53, v53
	v_add_f32_e32 v54, v54, v54
	v_add_f32_e32 v55, v55, v55
	v_mul_f32_e32 v54, 0x3fb8aa3b, v54
	v_mul_f32_e32 v55, 0x3fb8aa3b, v55
	v_exp_f32_e32 v54, v54
	v_exp_f32_e32 v55, v55
	s_nop 0
	v_add_f32_e64 v54, v54, 1.0
	v_add_f32_e64 v55, v55, 1.0
	v_rcp_f32_e32 v52, v52
	s_nop 0
	v_add_f32_e32 v52, v52, v52
	v_add_f32_e64 v52, -v52, 1.0
	v_add_f32_e64 v53, -v53, 1.0
	v_mul_f32_e64 v48, v48, 0.5
	v_mul_f32_e64 v49, v49, 0.5
	v_add_f32_e64 v52, v52, 1.0
	v_add_f32_e64 v53, v53, 1.0
	v_mul_f32_e64 v50, v50, 0.5
	v_mul_f32_e64 v51, v51, 0.5
	v_mul_f32_e64 v48, v48, v52
	v_mul_f32_e64 v49, v49, v53
	v_rcp_f32_e32 v53, v55
	s_nop 0
	v_add_f32_e32 v53, v53, v53
	v_cvt_pk_bf16_f32 v48, v48, v49
	v_rcp_f32_e32 v52, v54
	s_nop 0
	v_add_f32_e32 v52, v52, v52
	v_add_f32_e64 v52, -v52, 1.0
	v_add_f32_e64 v53, -v53, 1.0
	v_bitop3_b32 v78, v66, 28, 16 bitop3:0xc8
	v_add_f32_e64 v52, v52, 1.0
	v_add_f32_e64 v53, v53, 1.0
	s_nop 0
	v_mul_f32_e64 v50, v50, v52
	v_mul_f32_e64 v51, v51, v53
	v_or_b32_e32 v52, 48, v64
	v_ashrrev_i32_e32 v53, 31, v52
	v_mad_i64_i32 v[54:55], s[0:1], v67, s52, v[52:53]
	v_lshlrev_b64 v[54:55], 6, v[54:55]
	v_lshl_add_u64 v[54:55], s[20:21], 0, v[54:55]
	v_lshl_add_u64 v[74:75], v[54:55], 0, v[80:81]
	v_cvt_pk_bf16_f32 v49, v50, v51
	global_store_dwordx2 v[74:75], v[48:49], off
	global_load_dwordx4 v[48:51], v[68:69], off offset:64
	s_waitcnt vmcnt(0)
	v_add_f32_e64 v44, v44, v48
	v_add_f32_e64 v45, v45, v49
	s_nop 0
	v_mul_f32_e32 v67, 0x3d372713, v44
	v_mul_f32_e32 v67, v44, v67
	v_fma_f32 v67, v44, v67, v44
	v_mul_f32_e32 v67, 0x3f4c422a, v67
	v_add_f32_e32 v67, v67, v67
	v_mul_f32_e32 v67, 0x3fb8aa3b, v67
	v_exp_f32_e32 v74, v67
	v_mul_f32_e32 v67, 0x3d372713, v45
	v_mul_f32_e32 v67, v45, v67
	v_fma_f32 v67, v45, v67, v45
	v_mul_f32_e32 v67, 0x3f4c422a, v67
	v_add_f32_e32 v67, v67, v67
	v_mul_f32_e32 v67, 0x3fb8aa3b, v67
	v_exp_f32_e32 v75, v67
	v_add_f32_e64 v46, v46, v50
	v_add_f32_e64 v47, v47, v51
	v_mul_f32_e64 v44, v44, 0.5
	v_mul_f32_e64 v45, v45, 0.5
	v_add_f32_e64 v42, v42, v50
	v_add_f32_e64 v43, v43, v51
	v_add_f32_e64 v74, v74, 1.0
	v_add_f32_e64 v75, v75, 1.0
	v_add_f32_e64 v36, v36, v48
	v_add_f32_e64 v37, v37, v49
	v_add_f32_e64 v38, v38, v50
	v_add_f32_e64 v39, v39, v51
	v_add_f32_e64 v32, v32, v48
	v_add_f32_e64 v33, v33, v49
	v_add_f32_e64 v34, v34, v50
	v_add_f32_e64 v35, v35, v51
	v_rcp_f32_e32 v75, v75
	s_nop 0
	v_add_f32_e32 v75, v75, v75
	v_mul_f32_e32 v76, 0x3d372713, v46
	v_mul_f32_e32 v77, 0x3d372713, v47
	v_mul_f32_e32 v76, v46, v76
	v_mul_f32_e32 v77, v47, v77
	v_fma_f32 v76, v46, v76, v46
	v_fma_f32 v77, v47, v77, v47
	v_mul_f32_e32 v76, 0x3f4c422a, v76
	v_mul_f32_e32 v77, 0x3f4c422a, v77
	v_add_f32_e32 v76, v76, v76
	v_add_f32_e32 v77, v77, v77
	v_mul_f32_e32 v76, 0x3fb8aa3b, v76
	v_mul_f32_e32 v77, 0x3fb8aa3b, v77
	v_exp_f32_e32 v76, v76
	v_exp_f32_e32 v77, v77
	v_rcp_f32_e32 v74, v74
	s_nop 0
	v_add_f32_e32 v74, v74, v74
	v_add_f32_e64 v74, -v74, 1.0
	v_add_f32_e64 v75, -v75, 1.0
	v_add_f32_e64 v76, v76, 1.0
	v_add_f32_e64 v77, v77, 1.0
	v_add_f32_e64 v74, v74, 1.0
	v_add_f32_e64 v75, v75, 1.0
	v_mul_f32_e64 v44, v44, v74
	v_mul_f32_e64 v45, v45, v75
	v_mul_f32_e64 v46, v46, 0.5
	v_mul_f32_e64 v47, v47, 0.5
	v_cvt_pk_bf16_f32 v44, v44, v45
	v_rcp_f32_e32 v75, v77
	s_nop 0
	v_add_f32_e32 v75, v75, v75
	v_rcp_f32_e32 v74, v76
	s_nop 0
	v_add_f32_e32 v74, v74, v74
	v_add_f32_e64 v74, -v74, 1.0
	v_add_f32_e64 v75, -v75, 1.0
	s_nop 0
	v_add_f32_e64 v74, v74, 1.0
	v_add_f32_e64 v75, v75, 1.0
	s_nop 0
	v_mul_f32_e64 v46, v46, v74
	v_mul_f32_e64 v47, v47, v75
; DI void store4(u16* dst, f32x4 v) { uint2 w; w.x = cvtpk(v[0], v[1]); w.y = cvtpk(v[2], v[3]); *(uint2*)dst = w; }
; DI void phase2(const Params& p, int bid, int nblk, unsigned char* smem) {
;     ...
;         for (int mi = 0; mi < 4; ++mi) {
;           const int f = fb + mi * 16 + lq * 4; const float4 bb = *(const float4*)(b1 + f);
; #pragma unroll
;           for (int ni = 0; ni < 4; ++ni) {
;             const int t = tb + ni * 16 + lr; f32x4 v = acc[mi][ni]; v[0] += bb.x; v[1] += bb.y; v[2] += bb.z; v[3] += bb.w;
; #pragma unroll
;             for (int j = 0; j < 4; ++j) { const float xx = v[j]; const float u = 0.7978845608028654f * (xx + 0.044715f * xx * xx * xx); const float th = 1.0f - 2.0f / (__expf(2.0f * u) + 1.0f); v[j] = 0.5f * xx * (1.0f + th); }
;             store4(hid + ((size_t)(f >> 5) * CROWS + t) * 32 + (f & 31), v);
;           }
	v_add_f32_e64 v74, v40, v48
	v_add_f32_e64 v75, v41, v49
	v_mov_b32_e32 v41, v81
	v_mul_f32_e32 v40, 0x3d372713, v74
	v_mul_f32_e32 v40, v74, v40
	v_fma_f32 v40, v74, v40, v74
	v_mul_f32_e32 v40, 0x3f4c422a, v40
	v_add_f32_e32 v40, v40, v40
	v_mul_f32_e32 v40, 0x3fb8aa3b, v40
	v_exp_f32_e32 v76, v40
	v_mul_f32_e32 v40, 0x3d372713, v75
	v_mul_f32_e32 v40, v75, v40
	v_fma_f32 v40, v75, v40, v75
	v_mul_f32_e32 v40, 0x3f4c422a, v40
	v_add_f32_e32 v40, v40, v40
	v_mul_f32_e32 v40, 0x3fb8aa3b, v40
	v_exp_f32_e32 v77, v40
	v_lshlrev_b32_e32 v40, 1, v78
	v_lshl_add_u64 v[70:71], v[70:71], 0, v[40:41]
	v_cvt_pk_bf16_f32 v45, v46, v47
	v_add_f32_e64 v76, v76, 1.0
	v_add_f32_e64 v77, v77, 1.0
	global_store_dwordx2 v[70:71], v[44:45], off
	s_nop 0
	v_rcp_f32_e32 v45, v77
	s_nop 0
	v_add_f32_e32 v45, v45, v45
	v_mul_f32_e32 v46, 0x3d372713, v42
	v_mul_f32_e32 v47, 0x3d372713, v43
	v_mul_f32_e32 v46, v42, v46
	v_mul_f32_e32 v47, v43, v47
	v_fma_f32 v46, v42, v46, v42
	v_fma_f32 v47, v43, v47, v43
	v_mul_f32_e32 v46, 0x3f4c422a, v46
	v_mul_f32_e32 v47, 0x3f4c422a, v47
	v_add_f32_e32 v46, v46, v46
	v_add_f32_e32 v47, v47, v47
	v_mul_f32_e32 v46, 0x3fb8aa3b, v46
	v_mul_f32_e32 v47, 0x3fb8aa3b, v47
	v_exp_f32_e32 v46, v46
	v_exp_f32_e32 v47, v47
	v_rcp_f32_e32 v44, v76
	s_nop 0
	v_add_f32_e32 v44, v44, v44
	v_add_f32_e64 v44, -v44, 1.0
	v_add_f32_e64 v45, -v45, 1.0
	v_add_f32_e64 v46, v46, 1.0
	v_add_f32_e64 v47, v47, 1.0
	v_mul_f32_e64 v70, v74, 0.5
	v_mul_f32_e64 v71, v75, 0.5
	v_add_f32_e64 v44, v44, 1.0
	v_add_f32_e64 v45, v45, 1.0
	v_mul_f32_e64 v42, v42, 0.5
	v_mul_f32_e64 v43, v43, 0.5
	v_mul_f32_e64 v44, v70, v44
	v_mul_f32_e64 v45, v71, v45
	v_rcp_f32_e32 v47, v47
	s_nop 0
	v_add_f32_e32 v47, v47, v47
	v_cvt_pk_bf16_f32 v44, v44, v45
	v_rcp_f32_e32 v46, v46
	s_nop 0
	v_add_f32_e32 v46, v46, v46
	v_mul_f32_e32 v67, 0x3d372713, v36
	v_mul_f32_e32 v67, v36, v67
	v_fma_f32 v67, v36, v67, v36
	v_mul_f32_e32 v67, 0x3f4c422a, v67
	v_add_f32_e32 v67, v67, v67
	v_mul_f32_e32 v67, 0x3fb8aa3b, v67
	v_exp_f32_e32 v70, v67
	v_mul_f32_e32 v67, 0x3d372713, v37
	v_mul_f32_e32 v67, v37, v67
	v_fma_f32 v67, v37, v67, v37
	v_mul_f32_e32 v67, 0x3f4c422a, v67
	v_add_f32_e32 v67, v67, v67
	v_mul_f32_e32 v67, 0x3fb8aa3b, v67
	v_exp_f32_e32 v71, v67
	v_add_f32_e64 v46, -v46, 1.0
	v_add_f32_e64 v47, -v47, 1.0
	v_mul_f32_e64 v36, v36, 0.5
	v_mul_f32_e64 v37, v37, 0.5
	v_add_f32_e64 v46, v46, 1.0
	v_add_f32_e64 v47, v47, 1.0
	s_nop 0
	v_mul_f32_e64 v42, v42, v46
	v_mul_f32_e64 v43, v43, v47
	v_lshl_add_u64 v[46:47], v[62:63], 0, v[40:41]
	v_add_f32_e64 v62, v70, 1.0
	v_add_f32_e64 v63, v71, 1.0
	v_cvt_pk_bf16_f32 v45, v42, v43
	global_store_dwordx2 v[46:47], v[44:45], off
	v_rcp_f32_e32 v43, v63
	s_nop 0
	v_add_f32_e32 v43, v43, v43
	v_mul_f32_e32 v44, 0x3d372713, v38
	v_mul_f32_e32 v45, 0x3d372713, v39
	v_mul_f32_e32 v44, v38, v44
	v_mul_f32_e32 v45, v39, v45
	v_fma_f32 v44, v38, v44, v38
	v_fma_f32 v45, v39, v45, v39
	v_mul_f32_e32 v44, 0x3f4c422a, v44
	v_mul_f32_e32 v45, 0x3f4c422a, v45
	v_add_f32_e32 v44, v44, v44
	v_add_f32_e32 v45, v45, v45
	v_mul_f32_e32 v44, 0x3fb8aa3b, v44
	v_mul_f32_e32 v45, 0x3fb8aa3b, v45
	v_exp_f32_e32 v44, v44
	v_exp_f32_e32 v45, v45
	v_rcp_f32_e32 v42, v62
	s_nop 0
	v_add_f32_e32 v42, v42, v42
	v_add_f32_e64 v42, -v42, 1.0
	v_add_f32_e64 v43, -v43, 1.0
	v_add_f32_e64 v44, v44, 1.0
	v_add_f32_e64 v45, v45, 1.0
	v_add_f32_e64 v42, v42, 1.0
	v_add_f32_e64 v43, v43, 1.0
	v_mul_f32_e64 v36, v36, v42
	v_mul_f32_e64 v37, v37, v43
	v_mul_f32_e64 v38, v38, 0.5
	v_mul_f32_e64 v39, v39, 0.5
	v_cvt_pk_bf16_f32 v36, v36, v37
	v_rcp_f32_e32 v43, v45
	s_nop 0
	v_add_f32_e32 v43, v43, v43
	v_rcp_f32_e32 v42, v44
	s_nop 0
	v_add_f32_e32 v42, v42, v42
	v_mul_f32_e32 v44, 0x3d372713, v32
	v_mul_f32_e32 v45, 0x3d372713, v33
	v_mul_f32_e32 v44, v32, v44
	v_mul_f32_e32 v45, v33, v45
	v_fma_f32 v44, v32, v44, v32
	v_fma_f32 v45, v33, v45, v33
	v_mul_f32_e32 v44, 0x3f4c422a, v44
	v_mul_f32_e32 v45, 0x3f4c422a, v45
	v_add_f32_e32 v44, v44, v44
	v_add_f32_e32 v45, v45, v45
	v_mul_f32_e32 v44, 0x3fb8aa3b, v44
	v_mul_f32_e32 v45, 0x3fb8aa3b, v45
	v_exp_f32_e32 v44, v44
	v_exp_f32_e32 v45, v45
	v_add_f32_e64 v42, -v42, 1.0
	v_add_f32_e64 v43, -v43, 1.0
	v_mul_f32_e64 v32, v32, 0.5
	v_mul_f32_e64 v33, v33, 0.5
	v_add_f32_e64 v42, v42, 1.0
	v_add_f32_e64 v43, v43, 1.0
	v_add_f32_e64 v44, v44, 1.0
	v_add_f32_e64 v45, v45, 1.0
	v_mul_f32_e64 v38, v38, v42
	v_mul_f32_e64 v39, v39, v43
	v_lshl_add_u64 v[42:43], v[58:59], 0, v[40:41]
	v_cvt_pk_bf16_f32 v37, v38, v39
	global_store_dwordx2 v[42:43], v[36:37], off
	v_rcp_f32_e32 v37, v45
	s_nop 0
	v_add_f32_e32 v37, v37, v37
	v_mul_f32_e32 v38, 0x3d372713, v34
	v_mul_f32_e32 v39, 0x3d372713, v35
	v_mul_f32_e32 v38, v34, v38
	v_mul_f32_e32 v39, v35, v39
	v_fma_f32 v38, v34, v38, v34
	v_fma_f32 v39, v35, v39, v35
	v_mul_f32_e32 v38, 0x3f4c422a, v38
	v_mul_f32_e32 v39, 0x3f4c422a, v39
	v_add_f32_e32 v38, v38, v38
	v_add_f32_e32 v39, v39, v39
	v_mul_f32_e32 v38, 0x3fb8aa3b, v38
	v_mul_f32_e32 v39, 0x3fb8aa3b, v39
	v_exp_f32_e32 v38, v38
	v_exp_f32_e32 v39, v39
	v_rcp_f32_e32 v36, v44
	s_nop 0
	v_add_f32_e32 v36, v36, v36
	v_add_f32_e64 v36, -v36, 1.0
	v_add_f32_e64 v37, -v37, 1.0
	v_add_f32_e64 v38, v38, 1.0
	v_add_f32_e64 v39, v39, 1.0
	v_add_f32_e64 v36, v36, 1.0
	v_add_f32_e64 v37, v37, 1.0
	v_mul_f32_e64 v32, v32, v36
	v_mul_f32_e64 v33, v33, v37
	v_mul_f32_e64 v34, v34, 0.5
	v_mul_f32_e64 v35, v35, 0.5
	v_cvt_pk_bf16_f32 v32, v32, v33
	v_rcp_f32_e32 v37, v39
	s_nop 0
	v_add_f32_e32 v37, v37, v37
	v_rcp_f32_e32 v36, v38
	s_nop 0
	v_add_f32_e32 v36, v36, v36
	v_add_f32_e64 v36, -v36, 1.0
	v_add_f32_e64 v37, -v37, 1.0
	s_nop 0
	v_add_f32_e64 v36, v36, 1.0
	v_add_f32_e64 v37, v37, 1.0
	s_nop 0
	v_mul_f32_e64 v34, v34, v36
	v_mul_f32_e64 v35, v35, v37
	v_lshl_add_u64 v[36:37], v[54:55], 0, v[40:41]
	v_cvt_pk_bf16_f32 v33, v34, v35
	global_store_dwordx2 v[36:37], v[32:33], off
	global_load_dwordx4 v[32:35], v[68:69], off offset:128
	v_or_b32_e32 v40, 32, v72
	v_ashrrev_i32_e32 v40, 5, v40
	s_waitcnt vmcnt(0)
; DI void store4(u16* dst, f32x4 v) { uint2 w; w.x = cvtpk(v[0], v[1]); w.y = cvtpk(v[2], v[3]); *(uint2*)dst = w; }
; DI void phase2(const Params& p, int bid, int nblk, unsigned char* smem) {
;     ...
;         for (int mi = 0; mi < 4; ++mi) {
;           const int f = fb + mi * 16 + lq * 4; const float4 bb = *(const float4*)(b1 + f);
; #pragma unroll
;           for (int ni = 0; ni < 4; ++ni) {
;             const int t = tb + ni * 16 + lr; f32x4 v = acc[mi][ni]; v[0] += bb.x; v[1] += bb.y; v[2] += bb.z; v[3] += bb.w;
; #pragma unroll
;             for (int j = 0; j < 4; ++j) { const float xx = v[j]; const float u = 0.7978845608028654f * (xx + 0.044715f * xx * xx * xx); const float th = 1.0f - 2.0f / (__expf(2.0f * u) + 1.0f); v[j] = 0.5f * xx * (1.0f + th); }
;             store4(hid + ((size_t)(f >> 5) * CROWS + t) * 32 + (f & 31), v);
;           }
	v_add_f32_e64 v28, v28, v32
	v_add_f32_e64 v29, v29, v33
	s_nop 0
	v_mul_f32_e32 v36, 0x3d372713, v28
	v_mul_f32_e32 v37, 0x3d372713, v29
	v_mul_f32_e32 v36, v28, v36
	v_mul_f32_e32 v37, v29, v37
	v_fma_f32 v36, v28, v36, v28
	v_fma_f32 v37, v29, v37, v29
	v_mul_f32_e32 v36, 0x3f4c422a, v36
	v_mul_f32_e32 v37, 0x3f4c422a, v37
	v_add_f32_e32 v36, v36, v36
	v_add_f32_e32 v37, v37, v37
	v_mul_f32_e32 v36, 0x3fb8aa3b, v36
	v_mul_f32_e32 v37, 0x3fb8aa3b, v37
	v_exp_f32_e32 v36, v36
	v_exp_f32_e32 v37, v37
	v_add_f32_e64 v30, v30, v34
	v_add_f32_e64 v31, v31, v35
	v_mul_f32_e64 v28, v28, 0.5
	v_mul_f32_e64 v29, v29, 0.5
	v_add_f32_e64 v24, v24, v32
	v_add_f32_e64 v25, v25, v33
	v_add_f32_e64 v36, v36, 1.0
	v_add_f32_e64 v37, v37, 1.0
	v_add_f32_e64 v26, v26, v34
	v_add_f32_e64 v27, v27, v35
	v_add_f32_e64 v20, v20, v32
	v_add_f32_e64 v21, v21, v33
	v_add_f32_e64 v22, v22, v34
	v_add_f32_e64 v23, v23, v35
	v_add_f32_e64 v16, v16, v32
	v_add_f32_e64 v17, v17, v33
	v_rcp_f32_e32 v37, v37
	s_nop 0
	v_add_f32_e32 v37, v37, v37
	v_add_f32_e64 v18, v18, v34
	v_add_f32_e64 v19, v19, v35
	v_mul_f32_e32 v38, 0x3d372713, v30
	v_mul_f32_e32 v39, 0x3d372713, v31
	v_mul_f32_e32 v38, v30, v38
	v_mul_f32_e32 v39, v31, v39
	v_fma_f32 v38, v30, v38, v30
	v_fma_f32 v39, v31, v39, v31
	v_mul_f32_e32 v38, 0x3f4c422a, v38
	v_mul_f32_e32 v39, 0x3f4c422a, v39
	v_add_f32_e32 v38, v38, v38
	v_add_f32_e32 v39, v39, v39
	v_mul_f32_e32 v38, 0x3fb8aa3b, v38
	v_mul_f32_e32 v39, 0x3fb8aa3b, v39
	v_exp_f32_e32 v38, v38
	v_exp_f32_e32 v39, v39
	v_rcp_f32_e32 v36, v36
	s_nop 0
	v_add_f32_e32 v36, v36, v36
	v_add_f32_e64 v36, -v36, 1.0
	v_add_f32_e64 v37, -v37, 1.0
	v_add_f32_e64 v38, v38, 1.0
	v_add_f32_e64 v39, v39, 1.0
	v_add_f32_e64 v36, v36, 1.0
	v_add_f32_e64 v37, v37, 1.0
	v_mul_f32_e64 v28, v28, v36
	v_mul_f32_e64 v29, v29, v37
	v_mul_f32_e64 v30, v30, 0.5
	v_mul_f32_e64 v31, v31, 0.5
	v_cvt_pk_bf16_f32 v28, v28, v29
	v_rcp_f32_e32 v37, v39
	s_nop 0
	v_add_f32_e32 v37, v37, v37
	v_rcp_f32_e32 v36, v38
	s_nop 0
	v_add_f32_e32 v36, v36, v36
	v_mul_f32_e32 v38, 0x3d372713, v24
	v_mul_f32_e32 v39, 0x3d372713, v25
	v_mul_f32_e32 v38, v24, v38
	v_mul_f32_e32 v39, v25, v39
	v_fma_f32 v38, v24, v38, v24
	v_fma_f32 v39, v25, v39, v25
	v_mul_f32_e32 v38, 0x3f4c422a, v38
	v_mul_f32_e32 v39, 0x3f4c422a, v39
	v_add_f32_e32 v38, v38, v38
	v_add_f32_e32 v39, v39, v39
	v_mul_f32_e32 v38, 0x3fb8aa3b, v38
	v_mul_f32_e32 v39, 0x3fb8aa3b, v39
	v_exp_f32_e32 v38, v38
	v_exp_f32_e32 v39, v39
	v_add_f32_e64 v36, -v36, 1.0
	v_add_f32_e64 v37, -v37, 1.0
	v_mul_f32_e64 v24, v24, 0.5
	v_mul_f32_e64 v25, v25, 0.5
	v_add_f32_e64 v36, v36, 1.0
	v_add_f32_e64 v37, v37, 1.0
	v_add_f32_e64 v38, v38, 1.0
	v_add_f32_e64 v39, v39, 1.0
	v_mul_f32_e64 v30, v30, v36
	v_mul_f32_e64 v31, v31, v37
	v_mad_i64_i32 v[36:37], s[0:1], v40, s52, v[64:65]
	v_lshlrev_b64 v[36:37], 6, v[36:37]
	v_lshl_add_u64 v[36:37], s[20:21], 0, v[36:37]
	v_lshl_add_u64 v[36:37], v[36:37], 0, v[80:81]
	v_cvt_pk_bf16_f32 v29, v30, v31
	global_store_dwordx2 v[36:37], v[28:29], off
	v_rcp_f32_e32 v29, v39
	s_nop 0
	v_add_f32_e32 v29, v29, v29
	v_mul_f32_e32 v30, 0x3d372713, v26
	v_mul_f32_e32 v31, 0x3d372713, v27
	v_mul_f32_e32 v30, v26, v30
	v_mul_f32_e32 v31, v27, v31
	v_fma_f32 v30, v26, v30, v26
	v_fma_f32 v31, v27, v31, v27
	v_mul_f32_e32 v30, 0x3f4c422a, v30
	v_mul_f32_e32 v31, 0x3f4c422a, v31
	v_add_f32_e32 v30, v30, v30
	v_add_f32_e32 v31, v31, v31
	v_mul_f32_e32 v30, 0x3fb8aa3b, v30
	v_mul_f32_e32 v31, 0x3fb8aa3b, v31
	v_exp_f32_e32 v30, v30
	v_exp_f32_e32 v31, v31
	v_rcp_f32_e32 v28, v38
	s_nop 0
	v_add_f32_e32 v28, v28, v28
	v_add_f32_e64 v28, -v28, 1.0
	v_add_f32_e64 v29, -v29, 1.0
	v_add_f32_e64 v30, v30, 1.0
	v_add_f32_e64 v31, v31, 1.0
	v_add_f32_e64 v28, v28, 1.0
	v_add_f32_e64 v29, v29, 1.0
	v_mul_f32_e64 v24, v24, v28
	v_mul_f32_e64 v25, v25, v29
	v_mul_f32_e64 v26, v26, 0.5
	v_mul_f32_e64 v27, v27, 0.5
	v_cvt_pk_bf16_f32 v24, v24, v25
	v_rcp_f32_e32 v29, v31
	s_nop 0
	v_add_f32_e32 v29, v29, v29
	v_rcp_f32_e32 v28, v30
	s_nop 0
	v_add_f32_e32 v28, v28, v28
	v_mul_f32_e32 v30, 0x3d372713, v20
	v_mul_f32_e32 v31, 0x3d372713, v21
	v_mul_f32_e32 v30, v20, v30
	v_mul_f32_e32 v31, v21, v31
	v_fma_f32 v30, v20, v30, v20
	v_fma_f32 v31, v21, v31, v21
	v_mul_f32_e32 v30, 0x3f4c422a, v30
	v_mul_f32_e32 v31, 0x3f4c422a, v31
	v_add_f32_e32 v30, v30, v30
	v_add_f32_e32 v31, v31, v31
	v_mul_f32_e32 v30, 0x3fb8aa3b, v30
	v_mul_f32_e32 v31, 0x3fb8aa3b, v31
	v_exp_f32_e32 v30, v30
	v_exp_f32_e32 v31, v31
	v_add_f32_e64 v28, -v28, 1.0
	v_add_f32_e64 v29, -v29, 1.0
	v_mul_f32_e64 v20, v20, 0.5
	v_mul_f32_e64 v21, v21, 0.5
	v_add_f32_e64 v28, v28, 1.0
	v_add_f32_e64 v29, v29, 1.0
	v_add_f32_e64 v30, v30, 1.0
	v_add_f32_e64 v31, v31, 1.0
	v_mul_f32_e64 v26, v26, v28
	v_mul_f32_e64 v27, v27, v29
	v_mad_i64_i32 v[28:29], s[0:1], v40, s52, v[60:61]
	v_lshlrev_b64 v[28:29], 6, v[28:29]
	v_lshl_add_u64 v[28:29], s[20:21], 0, v[28:29]
	v_lshl_add_u64 v[28:29], v[28:29], 0, v[80:81]
	v_cvt_pk_bf16_f32 v25, v26, v27
	global_store_dwordx2 v[28:29], v[24:25], off
	v_rcp_f32_e32 v25, v31
	s_nop 0
	v_add_f32_e32 v25, v25, v25
	v_mul_f32_e32 v26, 0x3d372713, v22
	v_mul_f32_e32 v27, 0x3d372713, v23
	v_mul_f32_e32 v26, v22, v26
	v_mul_f32_e32 v27, v23, v27
	v_fma_f32 v26, v22, v26, v22
	v_fma_f32 v27, v23, v27, v23
	v_mul_f32_e32 v26, 0x3f4c422a, v26
	v_mul_f32_e32 v27, 0x3f4c422a, v27
	v_add_f32_e32 v26, v26, v26
	v_add_f32_e32 v27, v27, v27
	v_mul_f32_e32 v26, 0x3fb8aa3b, v26
	v_mul_f32_e32 v27, 0x3fb8aa3b, v27
	v_exp_f32_e32 v26, v26
	v_exp_f32_e32 v27, v27
	v_rcp_f32_e32 v24, v30
	s_nop 0
	v_add_f32_e32 v24, v24, v24
	v_add_f32_e64 v24, -v24, 1.0
; DI void store4(u16* dst, f32x4 v) { uint2 w; w.x = cvtpk(v[0], v[1]); w.y = cvtpk(v[2], v[3]); *(uint2*)dst = w; }
; DI void phase2(const Params& p, int bid, int nblk, unsigned char* smem) {
;     ...
;         for (int mi = 0; mi < 4; ++mi) {
;           const int f = fb + mi * 16 + lq * 4; const float4 bb = *(const float4*)(b1 + f);
; #pragma unroll
;           for (int ni = 0; ni < 4; ++ni) {
;             const int t = tb + ni * 16 + lr; f32x4 v = acc[mi][ni]; v[0] += bb.x; v[1] += bb.y; v[2] += bb.z; v[3] += bb.w;
; #pragma unroll
;             for (int j = 0; j < 4; ++j) { const float xx = v[j]; const float u = 0.7978845608028654f * (xx + 0.044715f * xx * xx * xx); const float th = 1.0f - 2.0f / (__expf(2.0f * u) + 1.0f); v[j] = 0.5f * xx * (1.0f + th); }
;             store4(hid + ((size_t)(f >> 5) * CROWS + t) * 32 + (f & 31), v);
;           }
	v_add_f32_e64 v25, -v25, 1.0
	v_add_f32_e64 v26, v26, 1.0
	v_add_f32_e64 v27, v27, 1.0
	v_add_f32_e64 v24, v24, 1.0
	v_add_f32_e64 v25, v25, 1.0
	v_mul_f32_e64 v20, v20, v24
	v_mul_f32_e64 v21, v21, v25
	v_mul_f32_e64 v22, v22, 0.5
	v_mul_f32_e64 v23, v23, 0.5
	v_cvt_pk_bf16_f32 v20, v20, v21
	v_rcp_f32_e32 v25, v27
	s_nop 0
	v_add_f32_e32 v25, v25, v25
	v_rcp_f32_e32 v24, v26
	s_nop 0
	v_add_f32_e32 v24, v24, v24
	v_mul_f32_e32 v26, 0x3d372713, v16
	v_mul_f32_e32 v27, 0x3d372713, v17
	v_mul_f32_e32 v26, v16, v26
	v_mul_f32_e32 v27, v17, v27
	v_fma_f32 v26, v16, v26, v16
	v_fma_f32 v27, v17, v27, v17
	v_mul_f32_e32 v26, 0x3f4c422a, v26
	v_mul_f32_e32 v27, 0x3f4c422a, v27
	v_add_f32_e32 v26, v26, v26
	v_add_f32_e32 v27, v27, v27
	v_mul_f32_e32 v26, 0x3fb8aa3b, v26
	v_mul_f32_e32 v27, 0x3fb8aa3b, v27
	v_exp_f32_e32 v26, v26
	v_exp_f32_e32 v27, v27
	v_add_f32_e64 v24, -v24, 1.0
	v_add_f32_e64 v25, -v25, 1.0
	v_mul_f32_e64 v16, v16, 0.5
	v_mul_f32_e64 v17, v17, 0.5
	v_add_f32_e64 v24, v24, 1.0
	v_add_f32_e64 v25, v25, 1.0
	v_add_f32_e64 v26, v26, 1.0
	v_add_f32_e64 v27, v27, 1.0
	v_mul_f32_e64 v22, v22, v24
	v_mul_f32_e64 v23, v23, v25
	v_mad_i64_i32 v[24:25], s[0:1], v40, s52, v[56:57]
	v_lshlrev_b64 v[24:25], 6, v[24:25]
	v_lshl_add_u64 v[24:25], s[20:21], 0, v[24:25]
	v_lshl_add_u64 v[24:25], v[24:25], 0, v[80:81]
	v_cvt_pk_bf16_f32 v21, v22, v23
	global_store_dwordx2 v[24:25], v[20:21], off
	v_rcp_f32_e32 v21, v27
	s_nop 0
	v_add_f32_e32 v21, v21, v21
	v_mul_f32_e32 v22, 0x3d372713, v18
	v_mul_f32_e32 v23, 0x3d372713, v19
	v_mul_f32_e32 v22, v18, v22
	v_mul_f32_e32 v23, v19, v23
	v_fma_f32 v22, v18, v22, v18
	v_fma_f32 v23, v19, v23, v19
	v_mul_f32_e32 v22, 0x3f4c422a, v22
	v_mul_f32_e32 v23, 0x3f4c422a, v23
	v_add_f32_e32 v22, v22, v22
	v_add_f32_e32 v23, v23, v23
	v_mul_f32_e32 v22, 0x3fb8aa3b, v22
	v_mul_f32_e32 v23, 0x3fb8aa3b, v23
	v_exp_f32_e32 v22, v22
	v_exp_f32_e32 v23, v23
	v_rcp_f32_e32 v20, v26
	s_nop 0
	v_add_f32_e32 v20, v20, v20
	v_add_f32_e64 v20, -v20, 1.0
	v_add_f32_e64 v21, -v21, 1.0
	v_add_f32_e64 v22, v22, 1.0
	v_add_f32_e64 v23, v23, 1.0
	v_add_f32_e64 v20, v20, 1.0
	v_add_f32_e64 v21, v21, 1.0
	v_mul_f32_e64 v16, v16, v20
	v_mul_f32_e64 v17, v17, v21
	v_mul_f32_e64 v18, v18, 0.5
	v_mul_f32_e64 v19, v19, 0.5
	v_cvt_pk_bf16_f32 v16, v16, v17
	v_rcp_f32_e32 v21, v23
	s_nop 0
	v_add_f32_e32 v21, v21, v21
	v_rcp_f32_e32 v20, v22
	s_nop 0
	v_add_f32_e32 v20, v20, v20
	v_add_f32_e64 v20, -v20, 1.0
	v_add_f32_e64 v21, -v21, 1.0
	v_or_b32_e32 v24, 48, v66
	v_add_f32_e64 v20, v20, 1.0
	v_add_f32_e64 v21, v21, 1.0
	v_bitop3_b32 v25, v66, 28, 48 bitop3:0xc8
	v_mul_f32_e64 v18, v18, v20
	v_mul_f32_e64 v19, v19, v21
	v_mad_i64_i32 v[20:21], s[0:1], v40, s52, v[52:53]
	v_lshlrev_b64 v[20:21], 6, v[20:21]
	v_lshl_add_u64 v[20:21], s[20:21], 0, v[20:21]
	v_lshl_add_u64 v[20:21], v[20:21], 0, v[80:81]
	v_cvt_pk_bf16_f32 v17, v18, v19
	global_store_dwordx2 v[20:21], v[16:17], off
	global_load_dwordx4 v[16:19], v[68:69], off offset:192
	v_ashrrev_i32_e32 v24, 5, v24
	v_lshlrev_b32_e32 v80, 1, v25
	s_waitcnt vmcnt(0)
	v_add_f32_e64 v12, v12, v16
	v_add_f32_e64 v13, v13, v17
	s_nop 0
	v_mul_f32_e32 v20, 0x3d372713, v12
	v_mul_f32_e32 v21, 0x3d372713, v13
	v_mul_f32_e32 v20, v12, v20
	v_mul_f32_e32 v21, v13, v21
	v_fma_f32 v20, v12, v20, v12
	v_fma_f32 v21, v13, v21, v13
	v_mul_f32_e32 v20, 0x3f4c422a, v20
	v_mul_f32_e32 v21, 0x3f4c422a, v21
	v_add_f32_e32 v20, v20, v20
	v_add_f32_e32 v21, v21, v21
	v_mul_f32_e32 v20, 0x3fb8aa3b, v20
	v_mul_f32_e32 v21, 0x3fb8aa3b, v21
	v_exp_f32_e32 v20, v20
	v_exp_f32_e32 v21, v21
	v_add_f32_e64 v14, v14, v18
	v_add_f32_e64 v15, v15, v19
	v_mul_f32_e64 v12, v12, 0.5
	v_mul_f32_e64 v13, v13, 0.5
	v_add_f32_e64 v8, v8, v16
	v_add_f32_e64 v9, v9, v17
	v_add_f32_e64 v20, v20, 1.0
	v_add_f32_e64 v21, v21, 1.0
	v_add_f32_e64 v10, v10, v18
	v_add_f32_e64 v11, v11, v19
	v_add_f32_e64 v4, v4, v16
	v_add_f32_e64 v5, v5, v17
	v_add_f32_e64 v6, v6, v18
	v_add_f32_e64 v7, v7, v19
	v_add_f32_e64 v0, v0, v16
	v_add_f32_e64 v1, v1, v17
	v_rcp_f32_e32 v21, v21
	s_nop 0
	v_add_f32_e32 v21, v21, v21
	v_add_f32_e64 v2, v2, v18
	v_add_f32_e64 v3, v3, v19
	v_mul_f32_e32 v22, 0x3d372713, v14
	v_mul_f32_e32 v23, 0x3d372713, v15
	v_mul_f32_e32 v22, v14, v22
	v_mul_f32_e32 v23, v15, v23
	v_fma_f32 v22, v14, v22, v14
	v_fma_f32 v23, v15, v23, v15
	v_mul_f32_e32 v22, 0x3f4c422a, v22
	v_mul_f32_e32 v23, 0x3f4c422a, v23
	v_add_f32_e32 v22, v22, v22
	v_add_f32_e32 v23, v23, v23
	v_mul_f32_e32 v22, 0x3fb8aa3b, v22
	v_mul_f32_e32 v23, 0x3fb8aa3b, v23
	v_exp_f32_e32 v22, v22
	v_exp_f32_e32 v23, v23
	v_rcp_f32_e32 v20, v20
	s_nop 0
	v_add_f32_e32 v20, v20, v20
	v_add_f32_e64 v20, -v20, 1.0
	v_add_f32_e64 v21, -v21, 1.0
	v_add_f32_e64 v22, v22, 1.0
	v_add_f32_e64 v23, v23, 1.0
	v_add_f32_e64 v20, v20, 1.0
	v_add_f32_e64 v21, v21, 1.0
	v_mul_f32_e64 v12, v12, v20
	v_mul_f32_e64 v13, v13, v21
	v_mul_f32_e64 v14, v14, 0.5
	v_mul_f32_e64 v15, v15, 0.5
	v_cvt_pk_bf16_f32 v12, v12, v13
	v_rcp_f32_e32 v21, v23
	s_nop 0
	v_add_f32_e32 v21, v21, v21
	v_rcp_f32_e32 v20, v22
	s_nop 0
	v_add_f32_e32 v20, v20, v20
	v_mul_f32_e32 v22, 0x3d372713, v8
	v_mul_f32_e32 v23, 0x3d372713, v9
	v_mul_f32_e32 v22, v8, v22
	v_mul_f32_e32 v23, v9, v23
	v_fma_f32 v22, v8, v22, v8
	v_fma_f32 v23, v9, v23, v9
	v_mul_f32_e32 v22, 0x3f4c422a, v22
	v_mul_f32_e32 v23, 0x3f4c422a, v23
	v_add_f32_e32 v22, v22, v22
	v_add_f32_e32 v23, v23, v23
	v_mul_f32_e32 v22, 0x3fb8aa3b, v22
	v_mul_f32_e32 v23, 0x3fb8aa3b, v23
	v_exp_f32_e32 v22, v22
	v_exp_f32_e32 v23, v23
	v_add_f32_e64 v20, -v20, 1.0
	v_add_f32_e64 v21, -v21, 1.0
	v_mul_f32_e64 v8, v8, 0.5
	v_mul_f32_e64 v9, v9, 0.5
; DI void store4(u16* dst, f32x4 v) { uint2 w; w.x = cvtpk(v[0], v[1]); w.y = cvtpk(v[2], v[3]); *(uint2*)dst = w; }
; DI void phase2(const Params& p, int bid, int nblk, unsigned char* smem) {
;     ...
;       gemm_tile<4>(W, 256, tn * 128, tm * 128, 2048, xl, [&](f32x4 (&acc)[4][4], int fb, int tb, int lr, int lq, int wf, int wt) {
; #pragma unroll
;         for (int mi = 0; mi < 4; ++mi) {
;           const int f = fb + mi * 16 + lq * 4; const float4 bb = *(const float4*)(b1 + f);
; #pragma unroll
;           for (int ni = 0; ni < 4; ++ni) {
;             const int t = tb + ni * 16 + lr; f32x4 v = acc[mi][ni]; v[0] += bb.x; v[1] += bb.y; v[2] += bb.z; v[3] += bb.w;
; #pragma unroll
;             for (int j = 0; j < 4; ++j) { const float xx = v[j]; const float u = 0.7978845608028654f * (xx + 0.044715f * xx * xx * xx); const float th = 1.0f - 2.0f / (__expf(2.0f * u) + 1.0f); v[j] = 0.5f * xx * (1.0f + th); }
;             store4(hid + ((size_t)(f >> 5) * CROWS + t) * 32 + (f & 31), v);
;           }
;         }
;       }, smem);
	v_add_f32_e64 v20, v20, 1.0
	v_add_f32_e64 v21, v21, 1.0
	v_add_f32_e64 v22, v22, 1.0
	v_add_f32_e64 v23, v23, 1.0
	v_mul_f32_e64 v14, v14, v20
	v_mul_f32_e64 v15, v15, v21
	v_mad_i64_i32 v[20:21], s[0:1], v24, s52, v[64:65]
	v_lshlrev_b64 v[20:21], 6, v[20:21]
	v_lshl_add_u64 v[20:21], s[20:21], 0, v[20:21]
	v_lshl_add_u64 v[20:21], v[20:21], 0, v[80:81]
	v_cvt_pk_bf16_f32 v13, v14, v15
	global_store_dwordx2 v[20:21], v[12:13], off
	v_rcp_f32_e32 v13, v23
	s_nop 0
	v_add_f32_e32 v13, v13, v13
	v_mul_f32_e32 v14, 0x3d372713, v10
	v_mul_f32_e32 v15, 0x3d372713, v11
	v_mul_f32_e32 v14, v10, v14
	v_mul_f32_e32 v15, v11, v15
	v_fma_f32 v14, v10, v14, v10
	v_fma_f32 v15, v11, v15, v11
	v_mul_f32_e32 v14, 0x3f4c422a, v14
	v_mul_f32_e32 v15, 0x3f4c422a, v15
	v_add_f32_e32 v14, v14, v14
	v_add_f32_e32 v15, v15, v15
	v_mul_f32_e32 v14, 0x3fb8aa3b, v14
	v_mul_f32_e32 v15, 0x3fb8aa3b, v15
	v_exp_f32_e32 v14, v14
	v_exp_f32_e32 v15, v15
	v_rcp_f32_e32 v12, v22
	s_nop 0
	v_add_f32_e32 v12, v12, v12
	v_add_f32_e64 v12, -v12, 1.0
	v_add_f32_e64 v13, -v13, 1.0
	v_add_f32_e64 v14, v14, 1.0
	v_add_f32_e64 v15, v15, 1.0
	v_add_f32_e64 v12, v12, 1.0
	v_add_f32_e64 v13, v13, 1.0
	v_mul_f32_e64 v8, v8, v12
	v_mul_f32_e64 v9, v9, v13
	v_mul_f32_e64 v10, v10, 0.5
	v_mul_f32_e64 v11, v11, 0.5
	v_cvt_pk_bf16_f32 v8, v8, v9
	v_rcp_f32_e32 v13, v15
	s_nop 0
	v_add_f32_e32 v13, v13, v13
	v_rcp_f32_e32 v12, v14
	s_nop 0
	v_add_f32_e32 v12, v12, v12
	v_mul_f32_e32 v14, 0x3d372713, v4
	v_mul_f32_e32 v15, 0x3d372713, v5
	v_mul_f32_e32 v14, v4, v14
	v_mul_f32_e32 v15, v5, v15
	v_fma_f32 v14, v4, v14, v4
	v_fma_f32 v15, v5, v15, v5
	v_mul_f32_e32 v14, 0x3f4c422a, v14
	v_mul_f32_e32 v15, 0x3f4c422a, v15
	v_add_f32_e32 v14, v14, v14
	v_add_f32_e32 v15, v15, v15
	v_mul_f32_e32 v14, 0x3fb8aa3b, v14
	v_mul_f32_e32 v15, 0x3fb8aa3b, v15
	v_exp_f32_e32 v14, v14
	v_exp_f32_e32 v15, v15
	v_add_f32_e64 v12, -v12, 1.0
	v_add_f32_e64 v13, -v13, 1.0
	v_mul_f32_e64 v4, v4, 0.5
	v_mul_f32_e64 v5, v5, 0.5
	v_add_f32_e64 v12, v12, 1.0
	v_add_f32_e64 v13, v13, 1.0
	v_add_f32_e64 v14, v14, 1.0
	v_add_f32_e64 v15, v15, 1.0
	v_mul_f32_e64 v10, v10, v12
	v_mul_f32_e64 v11, v11, v13
	v_mad_i64_i32 v[12:13], s[0:1], v24, s52, v[60:61]
	v_lshlrev_b64 v[12:13], 6, v[12:13]
	v_lshl_add_u64 v[12:13], s[20:21], 0, v[12:13]
	v_lshl_add_u64 v[12:13], v[12:13], 0, v[80:81]
	v_cvt_pk_bf16_f32 v9, v10, v11
	global_store_dwordx2 v[12:13], v[8:9], off
	v_rcp_f32_e32 v9, v15
	s_nop 0
	v_add_f32_e32 v9, v9, v9
	v_mul_f32_e32 v10, 0x3d372713, v6
	v_mul_f32_e32 v11, 0x3d372713, v7
	v_mul_f32_e32 v10, v6, v10
	v_mul_f32_e32 v11, v7, v11
	v_fma_f32 v10, v6, v10, v6
	v_fma_f32 v11, v7, v11, v7
	v_mul_f32_e32 v10, 0x3f4c422a, v10
	v_mul_f32_e32 v11, 0x3f4c422a, v11
	v_add_f32_e32 v10, v10, v10
	v_add_f32_e32 v11, v11, v11
	v_mul_f32_e32 v10, 0x3fb8aa3b, v10
	v_mul_f32_e32 v11, 0x3fb8aa3b, v11
	v_exp_f32_e32 v10, v10
	v_exp_f32_e32 v11, v11
	v_rcp_f32_e32 v8, v14
	s_nop 0
	v_add_f32_e32 v8, v8, v8
	v_add_f32_e64 v8, -v8, 1.0
	v_add_f32_e64 v9, -v9, 1.0
	v_add_f32_e64 v10, v10, 1.0
	v_add_f32_e64 v11, v11, 1.0
	v_add_f32_e64 v8, v8, 1.0
	v_add_f32_e64 v9, v9, 1.0
	v_mul_f32_e64 v4, v4, v8
	v_mul_f32_e64 v5, v5, v9
	v_mul_f32_e64 v6, v6, 0.5
	v_mul_f32_e64 v7, v7, 0.5
	v_cvt_pk_bf16_f32 v4, v4, v5
	v_rcp_f32_e32 v9, v11
	s_nop 0
	v_add_f32_e32 v9, v9, v9
	v_rcp_f32_e32 v8, v10
	s_nop 0
	v_add_f32_e32 v8, v8, v8
	v_mul_f32_e32 v10, 0x3d372713, v0
	v_mul_f32_e32 v11, 0x3d372713, v1
	v_mul_f32_e32 v10, v0, v10
	v_mul_f32_e32 v11, v1, v11
	v_fma_f32 v10, v0, v10, v0
	v_fma_f32 v11, v1, v11, v1
	v_mul_f32_e32 v10, 0x3f4c422a, v10
	v_mul_f32_e32 v11, 0x3f4c422a, v11
	v_add_f32_e32 v10, v10, v10
	v_add_f32_e32 v11, v11, v11
	v_mul_f32_e32 v10, 0x3fb8aa3b, v10
	v_mul_f32_e32 v11, 0x3fb8aa3b, v11
	v_exp_f32_e32 v10, v10
	v_exp_f32_e32 v11, v11
	v_add_f32_e64 v8, -v8, 1.0
	v_add_f32_e64 v9, -v9, 1.0
	v_mul_f32_e64 v0, v0, 0.5
	v_mul_f32_e64 v1, v1, 0.5
	v_add_f32_e64 v8, v8, 1.0
	v_add_f32_e64 v9, v9, 1.0
	v_add_f32_e64 v10, v10, 1.0
	v_add_f32_e64 v11, v11, 1.0
	v_mul_f32_e64 v6, v6, v8
	v_mul_f32_e64 v7, v7, v9
	v_mad_i64_i32 v[8:9], s[0:1], v24, s52, v[56:57]
	v_lshlrev_b64 v[8:9], 6, v[8:9]
	v_lshl_add_u64 v[8:9], s[20:21], 0, v[8:9]
	v_lshl_add_u64 v[8:9], v[8:9], 0, v[80:81]
	v_cvt_pk_bf16_f32 v5, v6, v7
	global_store_dwordx2 v[8:9], v[4:5], off
	v_rcp_f32_e32 v5, v11
	s_nop 0
	v_add_f32_e32 v5, v5, v5
	v_mul_f32_e32 v6, 0x3d372713, v2
	v_mul_f32_e32 v7, 0x3d372713, v3
	v_mul_f32_e32 v6, v2, v6
	v_mul_f32_e32 v7, v3, v7
	v_fma_f32 v6, v2, v6, v2
	v_fma_f32 v7, v3, v7, v3
	v_mul_f32_e32 v6, 0x3f4c422a, v6
	v_mul_f32_e32 v7, 0x3f4c422a, v7
	v_add_f32_e32 v6, v6, v6
	v_add_f32_e32 v7, v7, v7
	v_mul_f32_e32 v6, 0x3fb8aa3b, v6
	v_mul_f32_e32 v7, 0x3fb8aa3b, v7
	v_exp_f32_e32 v6, v6
	v_exp_f32_e32 v7, v7
	v_rcp_f32_e32 v4, v10
	s_nop 0
	v_add_f32_e32 v4, v4, v4
	v_add_f32_e64 v4, -v4, 1.0
	v_add_f32_e64 v5, -v5, 1.0
	v_add_f32_e64 v6, v6, 1.0
	v_add_f32_e64 v7, v7, 1.0
	v_add_f32_e64 v4, v4, 1.0
	v_add_f32_e64 v5, v5, 1.0
	v_mul_f32_e64 v0, v0, v4
	v_mul_f32_e64 v1, v1, v5
	v_mul_f32_e64 v2, v2, 0.5
	v_mul_f32_e64 v3, v3, 0.5
	v_cvt_pk_bf16_f32 v0, v0, v1
	v_rcp_f32_e32 v5, v7
	s_nop 0
	v_add_f32_e32 v5, v5, v5
	v_rcp_f32_e32 v4, v6
	s_nop 0
	v_add_f32_e32 v4, v4, v4
	v_add_f32_e64 v4, -v4, 1.0
	v_add_f32_e64 v5, -v5, 1.0
	s_nop 0
	v_add_f32_e64 v4, v4, 1.0
	v_add_f32_e64 v5, v5, 1.0
	s_nop 0
	v_mul_f32_e64 v2, v2, v4
	v_mul_f32_e64 v3, v3, v5
	v_mad_i64_i32 v[4:5], s[0:1], v24, s52, v[52:53]
	v_lshlrev_b64 v[4:5], 6, v[4:5]
	v_lshl_add_u64 v[4:5], s[20:21], 0, v[4:5]
	v_lshl_add_u64 v[4:5], v[4:5], 0, v[80:81]
	v_cvt_pk_bf16_f32 v1, v2, v3
	global_store_dwordx2 v[4:5], v[0:1], off
	s_branch .LBB0_335

; DI float sigmoidf_(float x) { return 1.0f / (1.0f + __expf(-x)); }
; DI void store4(u16* dst, f32x4 v) { uint2 w; w.x = cvtpk(v[0], v[1]); w.y = cvtpk(v[2], v[3]); *(uint2*)dst = w; }
; DI f32x4 load4bf(const u16* src) { uint2 w = *(const uint2*)src; return (f32x4){bflo(w.x), bfhi(w.x), bflo(w.y), bfhi(w.y)}; }
; DI void mla_item(const Params& p, int it, unsigned char* smem, u16* mb_out) {
;     ...
;   const u16* mb = (const u16*)(p.ws + OFF_MB);
; #pragma unroll
;   for (int nt = 0; nt < 2; ++nt) {
;     float lt = l[nt]; lt += __shfl_xor(lt, 16); lt += __shfl_xor(lt, 32);
;     const float inv = 1.0f / lt;
;     const size_t t = tb0 + q0 + wave * 32 + nt * 16 + lr;
; #pragma unroll
;     for (int dt = 0; dt < 8; ++dt) {
;       const size_t oidx = t * 1024 + hp * 128 + dt * 16 + lq * 4;
;       const f32x4 gm = load4bf(mb + oidx);
;       const f32x4 ov = (dt < 4) ? Oa[dt & 3][nt] : Ob[dt & 3][nt];
;       f32x4 o;
; #pragma unroll
;       for (int j = 0; j < 4; ++j) o[j] = sigmoidf_(gm[j]) * ov[j] * inv;
;       store4(mb_out + oidx, o);
;     }
;   }
.LBB0_418:
	v_lshl_add_u32 v0, s72, 7, v100
	s_waitcnt vmcnt(7)
	v_lshlrev_b64 v[68:69], 11, v[170:171]
	v_lshl_add_u64 v[2:3], s[2:3], 0, v[68:69]
	v_lshlrev_b64 v[70:71], 1, v[0:1]
	v_lshl_add_u64 v[2:3], v[2:3], 0, v[70:71]
	global_load_dwordx2 v[74:75], v[2:3], off
	s_waitcnt vmcnt(7)
	v_and_b32_e32 v72, 64, v220
	v_xor_b32_e32 v0, 16, v220
	v_add_u32_e32 v72, 64, v72
	v_cmp_lt_i32_e32 vcc, v0, v72
	v_xor_b32_e32 v73, 32, v220
	v_or_b32_e32 v68, 0x8000, v68
	v_cndmask_b32_e32 v0, v220, v0, vcc
	s_waitcnt vmcnt(6)
	v_lshlrev_b32_e32 v79, 2, v0
	ds_bpermute_b32 v0, v79, v169
	v_cmp_lt_i32_e32 vcc, v73, v72
	s_add_i32 s71, s71, s92
	s_waitcnt lgkmcnt(0)
	v_add_f32_e32 v0, v169, v0
	v_cndmask_b32_e32 v72, v220, v73, vcc
	v_lshlrev_b32_e32 v78, 2, v72
	ds_bpermute_b32 v72, v78, v0
	s_waitcnt lgkmcnt(0)
	v_add_f32_e32 v0, v0, v72
	global_load_dwordx2 v[76:77], v[2:3], off offset:32
	global_load_dwordx2 v[80:81], v[2:3], off offset:64
	global_load_dwordx2 v[72:73], v[2:3], off offset:96
	s_waitcnt vmcnt(8)
	s_waitcnt vmcnt(7)
	v_rcp_f32_e32 v0, v0
	s_waitcnt vmcnt(3)
	v_lshlrev_b32_e32 v82, 16, v74
	v_and_b32_e32 v74, 0xffff0000, v74
	v_lshlrev_b32_e32 v83, 16, v75
	v_and_b32_e32 v75, 0xffff0000, v75
	v_mul_f32_e32 v82, 0xbfb8aa3b, v82
	v_mul_f32_e32 v87, 0xbfb8aa3b, v74
	v_mul_f32_e32 v88, 0xbfb8aa3b, v75
	v_exp_f32_e32 v74, v82
	v_exp_f32_e32 v75, v87
	v_mul_f32_e32 v83, 0xbfb8aa3b, v83
	v_exp_f32_e32 v82, v83
	v_exp_f32_e32 v83, v88
	v_add_f32_e64 v74, v74, 1.0
	v_add_f32_e64 v75, v75, 1.0
	v_add_f32_e64 v82, v82, 1.0
	v_add_f32_e64 v83, v83, 1.0
	s_mov_b64 vcc, s[0:1]
	v_rcp_f32_e32 v75, v75
	s_mov_b64 vcc, s[4:5]
	v_rcp_f32_e32 v74, v74
	s_mov_b64 vcc, s[6:7]
	v_mul_f32_e64 v64, v64, v74
	v_mul_f32_e64 v65, v65, v75
	v_rcp_f32_e32 v75, v83
	v_rcp_f32_e32 v74, v82
	s_nop 0
	v_mul_f32_e64 v66, v66, v74
	v_mul_f32_e64 v67, v67, v75
	s_waitcnt vmcnt(2)
	v_lshlrev_b32_e32 v74, 16, v76
	v_and_b32_e32 v75, 0xffff0000, v76
	v_mul_f32_e32 v74, 0xbfb8aa3b, v74
	v_mul_f32_e32 v75, 0xbfb8aa3b, v75
	v_exp_f32_e32 v74, v74
	v_exp_f32_e32 v75, v75
	v_mul_f32_e64 v64, v0, v64
	v_mul_f32_e64 v65, v0, v65
	v_mul_f32_e64 v66, v0, v66
	v_mul_f32_e64 v67, v0, v67
	v_cvt_pk_bf16_f32 v64, v64, v65
	v_cvt_pk_bf16_f32 v65, v66, v67
	v_add_f32_e64 v66, v74, 1.0
	v_add_f32_e64 v67, v75, 1.0
	global_store_dwordx2 v[2:3], v[64:65], off
	v_lshlrev_b32_e32 v64, 16, v77
	v_and_b32_e32 v76, 0xffff0000, v77
	v_mul_f32_e32 v64, 0xbfb8aa3b, v64
	v_rcp_f32_e32 v65, v67
	v_exp_f32_e32 v74, v64
	v_mul_f32_e32 v64, 0xbfb8aa3b, v76
	v_exp_f32_e32 v75, v64
	v_rcp_f32_e32 v64, v66
	v_add_f32_e64 v74, v74, 1.0
	v_add_f32_e64 v75, v75, 1.0
	v_mul_f32_e64 v60, v60, v64
	v_mul_f32_e64 v61, v61, v65
	v_mul_f32_e64 v60, v0, v60
	v_mul_f32_e64 v61, v0, v61
	v_cvt_pk_bf16_f32 v60, v60, v61
	v_rcp_f32_e32 v65, v75
	v_rcp_f32_e32 v64, v74
	s_nop 0
	v_mul_f32_e64 v62, v62, v64
	v_mul_f32_e64 v63, v63, v65
	s_waitcnt vmcnt(2)
	v_lshlrev_b32_e32 v64, 16, v80
	v_and_b32_e32 v65, 0xffff0000, v80
	v_mul_f32_e32 v64, 0xbfb8aa3b, v64
	v_mul_f32_e32 v65, 0xbfb8aa3b, v65
	v_exp_f32_e32 v64, v64
	v_exp_f32_e32 v65, v65
	v_mul_f32_e64 v62, v0, v62
	v_mul_f32_e64 v63, v0, v63
	v_cvt_pk_bf16_f32 v61, v62, v63
	global_store_dwordx2 v[2:3], v[60:61], off offset:32
	v_add_f32_e64 v62, v64, 1.0
	v_add_f32_e64 v63, v65, 1.0
	v_lshlrev_b32_e32 v60, 16, v81
	v_and_b32_e32 v66, 0xffff0000, v81
	v_mul_f32_e32 v60, 0xbfb8aa3b, v60
	v_rcp_f32_e32 v61, v63
	v_exp_f32_e32 v64, v60
	v_mul_f32_e32 v60, 0xbfb8aa3b, v66
	v_exp_f32_e32 v65, v60
	v_rcp_f32_e32 v60, v62
	v_add_f32_e64 v64, v64, 1.0
	v_add_f32_e64 v65, v65, 1.0
	v_mul_f32_e64 v56, v56, v60
	v_mul_f32_e64 v57, v57, v61
	v_mul_f32_e64 v60, v0, v56
	v_mul_f32_e64 v61, v0, v57
	v_cvt_pk_bf16_f32 v60, v60, v61
	v_rcp_f32_e32 v57, v65
	v_rcp_f32_e32 v56, v64
	s_nop 0
	v_mul_f32_e64 v58, v58, v56
	v_mul_f32_e64 v59, v59, v57
	global_load_dwordx2 v[56:57], v[2:3], off offset:128
	s_waitcnt vmcnt(3)
	v_lshlrev_b32_e32 v62, 16, v72
	v_and_b32_e32 v63, 0xffff0000, v72
	v_mul_f32_e32 v62, 0xbfb8aa3b, v62
	v_mul_f32_e32 v63, 0xbfb8aa3b, v63
	v_exp_f32_e32 v62, v62
	v_exp_f32_e32 v63, v63
	v_mul_f32_e64 v58, v0, v58
	v_mul_f32_e64 v59, v0, v59
	v_cvt_pk_bf16_f32 v61, v58, v59
	global_store_dwordx2 v[2:3], v[60:61], off offset:64
	v_add_f32_e64 v58, v62, 1.0
	v_add_f32_e64 v59, v63, 1.0
	v_lshlrev_b32_e32 v60, 16, v73
	v_and_b32_e32 v61, 0xffff0000, v73
	v_mul_f32_e32 v60, 0xbfb8aa3b, v60
	v_mul_f32_e32 v61, 0xbfb8aa3b, v61
	v_rcp_f32_e32 v59, v59
	v_exp_f32_e32 v60, v60
	v_exp_f32_e32 v61, v61
	s_nop 0
	v_add_f32_e64 v60, v60, 1.0
	v_add_f32_e64 v61, v61, 1.0
	v_rcp_f32_e32 v58, v58
	s_nop 0
	v_mul_f32_e64 v52, v52, v58
	v_mul_f32_e64 v53, v53, v59
	v_rcp_f32_e32 v59, v61
	v_mul_f32_e64 v52, v0, v52
	v_mul_f32_e64 v53, v0, v53
	v_rcp_f32_e32 v58, v60
	s_nop 0
	v_mul_f32_e64 v54, v54, v58
	v_mul_f32_e64 v55, v55, v59
	global_load_dwordx2 v[58:59], v[2:3], off offset:160
	global_load_dwordx2 v[60:61], v[2:3], off offset:192
	global_load_dwordx2 v[62:63], v[2:3], off offset:224
	v_mul_f32_e64 v54, v0, v54
	v_mul_f32_e64 v55, v0, v55
	v_cvt_pk_bf16_f32 v52, v52, v53
	v_cvt_pk_bf16_f32 v53, v54, v55
	global_store_dwordx2 v[2:3], v[52:53], off offset:96
	s_waitcnt vmcnt(5)
; DI float sigmoidf_(float x) { return 1.0f / (1.0f + __expf(-x)); }
; DI void store4(u16* dst, f32x4 v) { uint2 w; w.x = cvtpk(v[0], v[1]); w.y = cvtpk(v[2], v[3]); *(uint2*)dst = w; }
; DI f32x4 load4bf(const u16* src) { uint2 w = *(const uint2*)src; return (f32x4){bflo(w.x), bfhi(w.x), bflo(w.y), bfhi(w.y)}; }
; DI void mla_item(const Params& p, int it, unsigned char* smem, u16* mb_out) {
;     ...
;   for (int nt = 0; nt < 2; ++nt) {
;     float lt = l[nt]; lt += __shfl_xor(lt, 16); lt += __shfl_xor(lt, 32);
;     const float inv = 1.0f / lt;
;     const size_t t = tb0 + q0 + wave * 32 + nt * 16 + lr;
; #pragma unroll
;     for (int dt = 0; dt < 8; ++dt) {
;       const size_t oidx = t * 1024 + hp * 128 + dt * 16 + lq * 4;
;       const f32x4 gm = load4bf(mb + oidx);
;       const f32x4 ov = (dt < 4) ? Oa[dt & 3][nt] : Ob[dt & 3][nt];
;       f32x4 o;
; #pragma unroll
;       for (int j = 0; j < 4; ++j) o[j] = sigmoidf_(gm[j]) * ov[j] * inv;
;       store4(mb_out + oidx, o);
;     }
;   }
	v_lshlrev_b32_e32 v64, 16, v56
	v_and_b32_e32 v56, 0xffff0000, v56
	v_mul_f32_e32 v64, 0xbfb8aa3b, v64
	v_mul_f32_e32 v56, 0xbfb8aa3b, v56
	v_exp_f32_e32 v64, v64
	v_exp_f32_e32 v65, v56
	v_lshlrev_b32_e32 v52, 16, v57
	v_and_b32_e32 v57, 0xffff0000, v57
	v_mul_f32_e32 v52, 0xbfb8aa3b, v52
	v_add_f32_e64 v54, v64, 1.0
	v_add_f32_e64 v55, v65, 1.0
	s_nop 0
	s_nop 0
	v_rcp_f32_e32 v53, v55
	v_exp_f32_e32 v56, v52
	v_mul_f32_e32 v52, 0xbfb8aa3b, v57
	v_exp_f32_e32 v57, v52
	v_rcp_f32_e32 v52, v54
	v_add_f32_e64 v56, v56, 1.0
	v_add_f32_e64 v57, v57, 1.0
	v_mul_f32_e64 v48, v48, v52
	v_mul_f32_e64 v49, v49, v53
	v_mul_f32_e64 v48, v0, v48
	v_mul_f32_e64 v49, v0, v49
	v_cvt_pk_bf16_f32 v48, v48, v49
	v_rcp_f32_e32 v53, v57
	v_rcp_f32_e32 v52, v56
	s_nop 0
	v_mul_f32_e64 v50, v50, v52
	v_mul_f32_e64 v51, v51, v53
	s_waitcnt vmcnt(3)
	v_lshlrev_b32_e32 v52, 16, v58
	v_and_b32_e32 v53, 0xffff0000, v58
	v_mul_f32_e32 v52, 0xbfb8aa3b, v52
	v_mul_f32_e32 v53, 0xbfb8aa3b, v53
	v_exp_f32_e32 v52, v52
	v_exp_f32_e32 v53, v53
	v_mul_f32_e64 v50, v0, v50
	v_mul_f32_e64 v51, v0, v51
	v_cvt_pk_bf16_f32 v49, v50, v51
	global_store_dwordx2 v[2:3], v[48:49], off offset:128
	v_add_f32_e64 v50, v52, 1.0
	v_add_f32_e64 v51, v53, 1.0
	v_lshlrev_b32_e32 v48, 16, v59
	v_and_b32_e32 v54, 0xffff0000, v59
	v_mul_f32_e32 v48, 0xbfb8aa3b, v48
	v_rcp_f32_e32 v49, v51
	v_exp_f32_e32 v52, v48
	v_mul_f32_e32 v48, 0xbfb8aa3b, v54
	v_exp_f32_e32 v53, v48
	v_rcp_f32_e32 v48, v50
	v_add_f32_e64 v52, v52, 1.0
	v_add_f32_e64 v53, v53, 1.0
	v_mul_f32_e64 v44, v44, v48
	v_mul_f32_e64 v45, v45, v49
	v_mul_f32_e64 v44, v0, v44
	v_mul_f32_e64 v45, v0, v45
	v_cvt_pk_bf16_f32 v44, v44, v45
	v_rcp_f32_e32 v49, v53
	v_rcp_f32_e32 v48, v52
	s_nop 0
	v_mul_f32_e64 v46, v46, v48
	v_mul_f32_e64 v47, v47, v49
	s_waitcnt vmcnt(3)
	v_lshlrev_b32_e32 v48, 16, v60
	v_and_b32_e32 v49, 0xffff0000, v60
	v_mul_f32_e32 v48, 0xbfb8aa3b, v48
	v_mul_f32_e32 v49, 0xbfb8aa3b, v49
	v_exp_f32_e32 v48, v48
	v_exp_f32_e32 v49, v49
	v_mul_f32_e64 v46, v0, v46
	v_mul_f32_e64 v47, v0, v47
	v_cvt_pk_bf16_f32 v45, v46, v47
	global_store_dwordx2 v[2:3], v[44:45], off offset:160
	v_add_f32_e64 v46, v48, 1.0
	v_add_f32_e64 v47, v49, 1.0
	v_lshlrev_b32_e32 v44, 16, v61
	v_and_b32_e32 v50, 0xffff0000, v61
	v_mul_f32_e32 v44, 0xbfb8aa3b, v44
	v_rcp_f32_e32 v45, v47
	v_exp_f32_e32 v48, v44
	v_mul_f32_e32 v44, 0xbfb8aa3b, v50
	v_exp_f32_e32 v49, v44
	v_rcp_f32_e32 v44, v46
	v_add_f32_e64 v48, v48, 1.0
	v_add_f32_e64 v49, v49, 1.0
	v_mul_f32_e64 v40, v40, v44
	v_mul_f32_e64 v41, v41, v45
	v_mul_f32_e64 v40, v0, v40
	v_mul_f32_e64 v41, v0, v41
	v_cvt_pk_bf16_f32 v40, v40, v41
	v_rcp_f32_e32 v45, v49
	v_rcp_f32_e32 v44, v48
	s_nop 0
	v_mul_f32_e64 v42, v42, v44
	v_mul_f32_e64 v43, v43, v45
	s_waitcnt vmcnt(3)
	v_lshlrev_b32_e32 v44, 16, v62
	v_and_b32_e32 v45, 0xffff0000, v62
	v_mul_f32_e32 v44, 0xbfb8aa3b, v44
	v_mul_f32_e32 v45, 0xbfb8aa3b, v45
	v_exp_f32_e32 v44, v44
	v_exp_f32_e32 v45, v45
	v_mul_f32_e64 v42, v0, v42
	v_mul_f32_e64 v43, v0, v43
	v_cvt_pk_bf16_f32 v41, v42, v43
	global_store_dwordx2 v[2:3], v[40:41], off offset:192
	v_add_f32_e64 v44, v44, 1.0
	v_add_f32_e64 v45, v45, 1.0
	v_lshlrev_b32_e32 v48, 16, v63
	v_and_b32_e32 v49, 0xffff0000, v63
	v_lshl_add_u64 v[40:41], s[2:3], 0, v[68:69]
	v_lshl_add_u64 v[40:41], v[40:41], 0, v[70:71]
	global_load_dwordx2 v[42:43], v[40:41], off
	v_rcp_f32_e32 v45, v45
	v_mul_f32_e32 v46, 0xbfb8aa3b, v48
	v_mul_f32_e32 v47, 0xbfb8aa3b, v49
	v_exp_f32_e32 v46, v46
	v_exp_f32_e32 v47, v47
	v_rcp_f32_e32 v44, v44
	v_add_f32_e64 v46, v46, 1.0
	v_add_f32_e64 v47, v47, 1.0
	v_mul_f32_e64 v36, v36, v44
	v_mul_f32_e64 v37, v37, v45
	v_mul_f32_e64 v36, v0, v36
	v_mul_f32_e64 v37, v0, v37
	v_cvt_pk_bf16_f32 v36, v36, v37
	v_rcp_f32_e32 v45, v47
	ds_bpermute_b32 v47, v79, v168
	s_waitcnt lgkmcnt(0)
	v_add_f32_e32 v47, v168, v47
	ds_bpermute_b32 v48, v78, v47
	v_rcp_f32_e32 v44, v46
	s_nop 0
	v_mul_f32_e64 v38, v38, v44
	v_mul_f32_e64 v39, v39, v45
	s_waitcnt vmcnt(0)
	v_lshlrev_b32_e32 v44, 16, v42
	v_mul_f32_e64 v38, v0, v38
	v_mul_f32_e64 v39, v0, v39
	s_waitcnt lgkmcnt(0)
	v_add_f32_e32 v0, v47, v48
	v_cvt_pk_bf16_f32 v37, v38, v39
	global_store_dwordx2 v[2:3], v[36:37], off offset:224
	global_load_dwordx2 v[2:3], v[40:41], off offset:32
	global_load_dwordx2 v[38:39], v[40:41], off offset:64
	global_load_dwordx2 v[36:37], v[40:41], off offset:96
	v_and_b32_e32 v42, 0xffff0000, v42
	v_mul_f32_e32 v44, 0xbfb8aa3b, v44
	v_mul_f32_e32 v42, 0xbfb8aa3b, v42
	v_exp_f32_e32 v44, v44
	v_exp_f32_e32 v45, v42
	v_rcp_f32_e32 v0, v0
	v_add_f32_e64 v44, v44, 1.0
	v_add_f32_e64 v45, v45, 1.0
	v_lshlrev_b32_e32 v42, 16, v43
	v_and_b32_e32 v48, 0xffff0000, v43
	v_mul_f32_e32 v42, 0xbfb8aa3b, v42
	v_rcp_f32_e32 v43, v45
	v_exp_f32_e32 v46, v42
	v_mul_f32_e32 v42, 0xbfb8aa3b, v48
	v_exp_f32_e32 v47, v42
	v_rcp_f32_e32 v42, v44
	v_add_f32_e64 v46, v46, 1.0
	v_add_f32_e64 v47, v47, 1.0
	v_mul_f32_e64 v32, v32, v42
	v_mul_f32_e64 v33, v33, v43
	v_mul_f32_e64 v32, v0, v32
	v_mul_f32_e64 v33, v0, v33
	v_cvt_pk_bf16_f32 v32, v32, v33
	v_rcp_f32_e32 v43, v47
	v_rcp_f32_e32 v42, v46
	s_nop 0
	v_mul_f32_e64 v34, v34, v42
	v_mul_f32_e64 v35, v35, v43
	s_waitcnt vmcnt(2)
; DI float sigmoidf_(float x) { return 1.0f / (1.0f + __expf(-x)); }
; DI void store4(u16* dst, f32x4 v) { uint2 w; w.x = cvtpk(v[0], v[1]); w.y = cvtpk(v[2], v[3]); *(uint2*)dst = w; }
; DI f32x4 load4bf(const u16* src) { uint2 w = *(const uint2*)src; return (f32x4){bflo(w.x), bfhi(w.x), bflo(w.y), bfhi(w.y)}; }
; DI void mla_item(const Params& p, int it, unsigned char* smem, u16* mb_out) {
;     ...
;   for (int nt = 0; nt < 2; ++nt) {
;     float lt = l[nt]; lt += __shfl_xor(lt, 16); lt += __shfl_xor(lt, 32);
;     const float inv = 1.0f / lt;
;     const size_t t = tb0 + q0 + wave * 32 + nt * 16 + lr;
; #pragma unroll
;     for (int dt = 0; dt < 8; ++dt) {
;       const size_t oidx = t * 1024 + hp * 128 + dt * 16 + lq * 4;
;       const f32x4 gm = load4bf(mb + oidx);
;       const f32x4 ov = (dt < 4) ? Oa[dt & 3][nt] : Ob[dt & 3][nt];
;       f32x4 o;
; #pragma unroll
;       for (int j = 0; j < 4; ++j) o[j] = sigmoidf_(gm[j]) * ov[j] * inv;
;       store4(mb_out + oidx, o);
;     }
;   }
	v_lshlrev_b32_e32 v42, 16, v2
	v_and_b32_e32 v2, 0xffff0000, v2
	v_mul_f32_e32 v42, 0xbfb8aa3b, v42
	v_mul_f32_e32 v2, 0xbfb8aa3b, v2
	v_exp_f32_e32 v42, v42
	v_exp_f32_e32 v43, v2
	v_mul_f32_e64 v34, v0, v34
	v_mul_f32_e64 v35, v0, v35
	v_cvt_pk_bf16_f32 v33, v34, v35
	global_store_dwordx2 v[40:41], v[32:33], off
	v_add_f32_e64 v34, v42, 1.0
	v_add_f32_e64 v35, v43, 1.0
	v_lshlrev_b32_e32 v32, 16, v3
	v_and_b32_e32 v33, 0xffff0000, v3
	v_mul_f32_e32 v32, 0xbfb8aa3b, v32
	v_mul_f32_e32 v33, 0xbfb8aa3b, v33
	v_rcp_f32_e32 v3, v35
	v_exp_f32_e32 v32, v32
	v_exp_f32_e32 v33, v33
	s_nop 0
	v_add_f32_e64 v32, v32, 1.0
	v_add_f32_e64 v33, v33, 1.0
	v_rcp_f32_e32 v2, v34
	s_nop 0
	v_mul_f32_e64 v2, v28, v2
	v_mul_f32_e64 v3, v29, v3
	v_rcp_f32_e32 v29, v33
	v_mul_f32_e64 v2, v0, v2
	v_mul_f32_e64 v3, v0, v3
	v_rcp_f32_e32 v28, v32
	s_nop 0
	v_mul_f32_e64 v28, v30, v28
	v_mul_f32_e64 v29, v31, v29
	s_waitcnt vmcnt(2)
	v_lshlrev_b32_e32 v30, 16, v38
	v_and_b32_e32 v31, 0xffff0000, v38
	v_mul_f32_e32 v30, 0xbfb8aa3b, v30
	v_mul_f32_e32 v31, 0xbfb8aa3b, v31
	v_exp_f32_e32 v30, v30
	v_exp_f32_e32 v31, v31
	v_mul_f32_e64 v28, v0, v28
	v_mul_f32_e64 v29, v0, v29
	v_cvt_pk_bf16_f32 v2, v2, v3
	v_cvt_pk_bf16_f32 v3, v28, v29
	v_add_f32_e64 v28, v30, 1.0
	v_add_f32_e64 v29, v31, 1.0
	global_store_dwordx2 v[40:41], v[2:3], off offset:32
	v_lshlrev_b32_e32 v2, 16, v39
	v_and_b32_e32 v32, 0xffff0000, v39
	v_mul_f32_e32 v2, 0xbfb8aa3b, v2
	v_rcp_f32_e32 v3, v29
	v_exp_f32_e32 v30, v2
	v_mul_f32_e32 v2, 0xbfb8aa3b, v32
	v_exp_f32_e32 v31, v2
	v_rcp_f32_e32 v2, v28
	v_add_f32_e64 v30, v30, 1.0
	v_add_f32_e64 v31, v31, 1.0
	v_mul_f32_e64 v2, v24, v2
	v_mul_f32_e64 v3, v25, v3
	v_mul_f32_e64 v24, v0, v2
	v_mul_f32_e64 v25, v0, v3
	v_cvt_pk_bf16_f32 v24, v24, v25
	v_rcp_f32_e32 v3, v31
	s_waitcnt vmcnt(2)
	v_lshlrev_b32_e32 v28, 16, v36
	v_and_b32_e32 v29, 0xffff0000, v36
	v_rcp_f32_e32 v2, v30
	v_mul_f32_e32 v28, 0xbfb8aa3b, v28
	v_mul_f32_e32 v29, 0xbfb8aa3b, v29
	v_mul_f32_e64 v26, v26, v2
	v_mul_f32_e64 v27, v27, v3
	global_load_dwordx2 v[2:3], v[40:41], off offset:128
	v_exp_f32_e32 v28, v28
	v_exp_f32_e32 v29, v29
	v_mul_f32_e64 v26, v0, v26
	v_mul_f32_e64 v27, v0, v27
	v_cvt_pk_bf16_f32 v25, v26, v27
	global_store_dwordx2 v[40:41], v[24:25], off offset:64
	v_add_f32_e64 v26, v28, 1.0
	v_add_f32_e64 v27, v29, 1.0
	v_lshlrev_b32_e32 v24, 16, v37
	v_and_b32_e32 v30, 0xffff0000, v37
	v_mul_f32_e32 v24, 0xbfb8aa3b, v24
	v_rcp_f32_e32 v25, v27
	v_exp_f32_e32 v28, v24
	v_mul_f32_e32 v24, 0xbfb8aa3b, v30
	v_exp_f32_e32 v29, v24
	v_rcp_f32_e32 v24, v26
	v_add_f32_e64 v28, v28, 1.0
	v_add_f32_e64 v29, v29, 1.0
	v_mul_f32_e64 v20, v20, v24
	v_mul_f32_e64 v21, v21, v25
	v_mul_f32_e64 v20, v0, v20
	v_mul_f32_e64 v21, v0, v21
	v_cvt_pk_bf16_f32 v20, v20, v21
	v_rcp_f32_e32 v25, v29
	v_rcp_f32_e32 v24, v28
	s_nop 0
	v_mul_f32_e64 v22, v22, v24
	v_mul_f32_e64 v23, v23, v25
	global_load_dwordx2 v[24:25], v[40:41], off offset:160
	global_load_dwordx2 v[26:27], v[40:41], off offset:192
	global_load_dwordx2 v[28:29], v[40:41], off offset:224
	v_mul_f32_e64 v22, v0, v22
	v_mul_f32_e64 v23, v0, v23
	v_cvt_pk_bf16_f32 v21, v22, v23
	global_store_dwordx2 v[40:41], v[20:21], off offset:96
	s_waitcnt vmcnt(5)
; DI float sigmoidf_(float x) { return 1.0f / (1.0f + __expf(-x)); }
; DI void store4(u16* dst, f32x4 v) { uint2 w; w.x = cvtpk(v[0], v[1]); w.y = cvtpk(v[2], v[3]); *(uint2*)dst = w; }
; DI f32x4 load4bf(const u16* src) { uint2 w = *(const uint2*)src; return (f32x4){bflo(w.x), bfhi(w.x), bflo(w.y), bfhi(w.y)}; }
; DI void mla_item(const Params& p, int it, unsigned char* smem, u16* mb_out) {
;     ...
;   for (int nt = 0; nt < 2; ++nt) {
;     float lt = l[nt]; lt += __shfl_xor(lt, 16); lt += __shfl_xor(lt, 32);
;     const float inv = 1.0f / lt;
;     const size_t t = tb0 + q0 + wave * 32 + nt * 16 + lr;
; #pragma unroll
;     for (int dt = 0; dt < 8; ++dt) {
;       const size_t oidx = t * 1024 + hp * 128 + dt * 16 + lq * 4;
;       const f32x4 gm = load4bf(mb + oidx);
;       const f32x4 ov = (dt < 4) ? Oa[dt & 3][nt] : Ob[dt & 3][nt];
;       f32x4 o;
; #pragma unroll
;       for (int j = 0; j < 4; ++j) o[j] = sigmoidf_(gm[j]) * ov[j] * inv;
;       store4(mb_out + oidx, o);
;     }
;   }
; DI void phase3(const Params& p, int bid, int nblk, unsigned char* smem, u16* mb_out) {
;     ...
;   for (int it = bid; it < 4096; it += nblk) { mla_item(p, it, smem, mb_out); __syncthreads(); }
	v_lshlrev_b32_e32 v30, 16, v2
	v_and_b32_e32 v2, 0xffff0000, v2
	v_mul_f32_e32 v30, 0xbfb8aa3b, v30
	v_mul_f32_e32 v2, 0xbfb8aa3b, v2
	v_exp_f32_e32 v30, v30
	v_exp_f32_e32 v31, v2
	v_lshlrev_b32_e32 v20, 16, v3
	v_and_b32_e32 v21, 0xffff0000, v3
	v_mul_f32_e32 v20, 0xbfb8aa3b, v20
	v_add_f32_e64 v22, v30, 1.0
	v_add_f32_e64 v23, v31, 1.0
	v_mul_f32_e32 v21, 0xbfb8aa3b, v21
	v_exp_f32_e32 v20, v20
	v_exp_f32_e32 v21, v21
	v_rcp_f32_e32 v3, v23
	v_add_f32_e64 v20, v20, 1.0
	v_add_f32_e64 v21, v21, 1.0
	v_rcp_f32_e32 v2, v22
	s_nop 0
	v_mul_f32_e64 v2, v16, v2
	v_mul_f32_e64 v3, v17, v3
	v_rcp_f32_e32 v17, v21
	v_mul_f32_e64 v2, v0, v2
	v_mul_f32_e64 v3, v0, v3
	v_rcp_f32_e32 v16, v20
	s_nop 0
	v_mul_f32_e64 v16, v18, v16
	v_mul_f32_e64 v17, v19, v17
	s_waitcnt vmcnt(3)
	v_lshlrev_b32_e32 v18, 16, v24
	v_and_b32_e32 v19, 0xffff0000, v24
	v_mul_f32_e32 v18, 0xbfb8aa3b, v18
	v_mul_f32_e32 v19, 0xbfb8aa3b, v19
	v_exp_f32_e32 v18, v18
	v_exp_f32_e32 v19, v19
	v_mul_f32_e64 v16, v0, v16
	v_mul_f32_e64 v17, v0, v17
	v_cvt_pk_bf16_f32 v2, v2, v3
	v_cvt_pk_bf16_f32 v3, v16, v17
	v_add_f32_e64 v16, v18, 1.0
	v_add_f32_e64 v17, v19, 1.0
	global_store_dwordx2 v[40:41], v[2:3], off offset:128
	v_lshlrev_b32_e32 v2, 16, v25
	v_and_b32_e32 v20, 0xffff0000, v25
	v_mul_f32_e32 v2, 0xbfb8aa3b, v2
	v_rcp_f32_e32 v3, v17
	v_exp_f32_e32 v18, v2
	v_mul_f32_e32 v2, 0xbfb8aa3b, v20
	v_exp_f32_e32 v19, v2
	v_rcp_f32_e32 v2, v16
	v_add_f32_e64 v18, v18, 1.0
	v_add_f32_e64 v19, v19, 1.0
	v_mul_f32_e64 v2, v12, v2
	v_mul_f32_e64 v3, v13, v3
	v_mul_f32_e64 v2, v0, v2
	v_mul_f32_e64 v3, v0, v3
	v_cvt_pk_bf16_f32 v2, v2, v3
	v_rcp_f32_e32 v13, v19
	v_rcp_f32_e32 v12, v18
	s_nop 0
	v_mul_f32_e64 v12, v14, v12
	v_mul_f32_e64 v13, v15, v13
	s_waitcnt vmcnt(3)
	v_lshlrev_b32_e32 v14, 16, v26
	v_and_b32_e32 v15, 0xffff0000, v26
	v_mul_f32_e32 v14, 0xbfb8aa3b, v14
	v_mul_f32_e32 v15, 0xbfb8aa3b, v15
	v_exp_f32_e32 v14, v14
	v_exp_f32_e32 v15, v15
	v_mul_f32_e64 v12, v0, v12
	v_mul_f32_e64 v13, v0, v13
	v_cvt_pk_bf16_f32 v3, v12, v13
	global_store_dwordx2 v[40:41], v[2:3], off offset:160
	v_add_f32_e64 v12, v14, 1.0
	v_add_f32_e64 v13, v15, 1.0
	v_lshlrev_b32_e32 v2, 16, v27
	v_and_b32_e32 v16, 0xffff0000, v27
	v_mul_f32_e32 v2, 0xbfb8aa3b, v2
	v_rcp_f32_e32 v3, v13
	v_exp_f32_e32 v14, v2
	v_mul_f32_e32 v2, 0xbfb8aa3b, v16
	v_exp_f32_e32 v15, v2
	v_rcp_f32_e32 v2, v12
	v_add_f32_e64 v14, v14, 1.0
	v_add_f32_e64 v15, v15, 1.0
	v_mul_f32_e64 v2, v8, v2
	v_mul_f32_e64 v3, v9, v3
	v_mul_f32_e64 v2, v0, v2
	v_mul_f32_e64 v3, v0, v3
	v_cvt_pk_bf16_f32 v2, v2, v3
	v_rcp_f32_e32 v9, v15
	v_rcp_f32_e32 v8, v14
	s_nop 0
	v_mul_f32_e64 v8, v10, v8
	v_mul_f32_e64 v9, v11, v9
	s_waitcnt vmcnt(3)
	v_lshlrev_b32_e32 v10, 16, v28
	v_and_b32_e32 v11, 0xffff0000, v28
	v_mul_f32_e32 v10, 0xbfb8aa3b, v10
	v_mul_f32_e32 v11, 0xbfb8aa3b, v11
	v_exp_f32_e32 v10, v10
	v_exp_f32_e32 v11, v11
	v_mul_f32_e64 v8, v0, v8
	v_mul_f32_e64 v9, v0, v9
	v_cvt_pk_bf16_f32 v3, v8, v9
	global_store_dwordx2 v[40:41], v[2:3], off offset:192
	v_add_f32_e64 v8, v10, 1.0
	v_add_f32_e64 v9, v11, 1.0
	v_lshlrev_b32_e32 v2, 16, v29
	v_and_b32_e32 v12, 0xffff0000, v29
	v_mul_f32_e32 v2, 0xbfb8aa3b, v2
	v_rcp_f32_e32 v3, v9
	v_exp_f32_e32 v10, v2
	v_mul_f32_e32 v2, 0xbfb8aa3b, v12
	v_exp_f32_e32 v11, v2
	v_rcp_f32_e32 v2, v8
	v_add_f32_e64 v10, v10, 1.0
	v_add_f32_e64 v11, v11, 1.0
	v_mul_f32_e64 v2, v4, v2
	v_mul_f32_e64 v3, v5, v3
	v_mul_f32_e64 v2, v0, v2
	v_mul_f32_e64 v3, v0, v3
	v_cvt_pk_bf16_f32 v2, v2, v3
	v_rcp_f32_e32 v5, v11
	v_readlane_b32 s0, v245, 23
	v_rcp_f32_e32 v4, v10
	s_nop 0
	v_mul_f32_e64 v4, v6, v4
	v_mul_f32_e64 v5, v7, v5
	s_add_i32 s70, s70, s0
	v_mul_f32_e64 v4, v0, v4
	v_mul_f32_e64 v5, v0, v5
	v_cvt_pk_bf16_f32 v3, v4, v5
	s_cmpk_lt_i32 s71, 0x1000
	global_store_dwordx2 v[40:41], v[2:3], off offset:224
	s_barrier
	v_readlane_b32 s1, v245, 24
	s_cbranch_scc0 .LBB0_463

; DI float ex2(float x) { return __builtin_amdgcn_exp2f(x); }
; DI f32x4 mfma16(bf16x8 a, bf16x8 b, f32x4 c) { return __builtin_amdgcn_mfma_f32_16x16x32_bf16(a, b, c, 0, 0, 0); }
; template <int NT> DI void softmax_fast(f32x4 (&S)[4][NT], float (&m)[NT], float (&l)[NT], float (&alpha)[NT], bf16x8 (&pb)[2][NT], float sc2, const float (&bias)[NT]) {
; #pragma unroll
;   for (int nt = 0; nt < NT; ++nt) {
;     float mxr = S[0][nt][0];
; #pragma unroll
;     for (int mt = 0; mt < 4; ++mt)
; #pragma unroll
;       for (int j = 0; j < 4; ++j) mxr = fmaxf(mxr, S[mt][nt][j]);
;     mxr = fmaxf(mxr, __shfl_xor(mxr, 16)); mxr = fmaxf(mxr, __shfl_xor(mxr, 32));
;     const float mx = (bias[nt] > -1e29f) ? (mxr * sc2 + bias[nt]) : -1e30f;
;     const float mn = (mx > m[nt] + 8.0f) ? mx : m[nt];
;     alpha[nt] = ex2(m[nt] - mn); m[nt] = mn;
;     const float c = bias[nt] - ((mn < -1e29f) ? 0.f : mn);
;     float sum = 0.f;
; DI void mla_item(const Params& p, int it, unsigned char* smem, u16* mb_out) {
;     ...
;     if (k0 <= qw0 + 31) {
;       f32x4 S[4][2];
; #pragma unroll
;       for (int mt = 0; mt < 4; ++mt) { S[mt][0] = (f32x4){0.f, 0.f, 0.f, 0.f}; S[mt][1] = (f32x4){0.f, 0.f, 0.f, 0.f}; }
;       __builtin_amdgcn_s_setprio(1);
; #pragma unroll
;       for (int mt = 0; mt < 4; ++mt)
; #pragma unroll
;         for (int ks = 0; ks < 3; ++ks) {
;           const bf16x8 a = *(const bf16x8*)(Ks + (mt * 16 + lr) * KST + ks * 32 + lq * 8);
;           S[mt][0] = mfma16(a, qf[0][ks], S[mt][0]); S[mt][1] = mfma16(a, qf[1][ks], S[mt][1]);
;         }
;       __builtin_amdgcn_sched_group_barrier(0x100, 3, 0);
; #pragma unroll
;       for (int i = 0; i < 12; ++i) { __builtin_amdgcn_sched_group_barrier(0x008, 2, 0); if (i + 3 < 12) __builtin_amdgcn_sched_group_barrier(0x100, 1, 0); }
;       __builtin_amdgcn_s_setprio(0);
;       float alpha[2]; bf16x8 pb[2][2];
;       if (k0 + 63 <= qw0) {
;         const float zb[2] = {0.f, 0.f};
;         softmax_fast<2>(S, m, l, alpha, pb, sc2, zb);
.LBB0_455:
	s_sub_i32 s8, s75, 63
	v_cmp_le_i32_e32 vcc, s8, v224
	s_and_saveexec_b64 s[60:61], vcc
	s_cbranch_execz .LBB0_440
	s_setprio 1
	ds_read_b128 v[120:123], v0
	ds_read_b128 v[124:127], v0 offset:64
	ds_read_b128 v[128:131], v0 offset:128
	s_waitcnt lgkmcnt(2)
	v_mfma_f32_16x16x32_bf16 v[132:135], v[120:123], v[68:71], 0
	v_mfma_f32_16x16x32_bf16 v[120:123], v[120:123], v[80:83], 0
	ds_read_b128 v[136:139], v0 offset:3584
	s_waitcnt lgkmcnt(2)
	v_mfma_f32_16x16x32_bf16 v[132:135], v[124:127], v[72:75], v[132:135]
	v_mfma_f32_16x16x32_bf16 v[120:123], v[124:127], v[84:87], v[120:123]
	ds_read_b128 v[124:127], v0 offset:3648
	s_waitcnt lgkmcnt(2)
	v_mfma_f32_16x16x32_bf16 v[160:163], v[128:131], v[76:79], v[132:135]
	v_mfma_f32_16x16x32_bf16 v[144:147], v[128:131], v[88:91], v[120:123]
	s_nop 3
	ds_read_b128 v[120:123], v0 offset:3712
	s_waitcnt lgkmcnt(2)
	v_mfma_f32_16x16x32_bf16 v[128:131], v[136:139], v[68:71], 0
	v_mfma_f32_16x16x32_bf16 v[132:135], v[136:139], v[80:83], 0
	ds_read_b128 v[136:139], v0 offset:7168
	s_waitcnt lgkmcnt(2)
	v_mfma_f32_16x16x32_bf16 v[128:131], v[124:127], v[72:75], v[128:131]
	v_mfma_f32_16x16x32_bf16 v[124:127], v[124:127], v[84:87], v[132:135]
	s_nop 3
	ds_read_b128 v[132:135], v0 offset:7232
	s_waitcnt lgkmcnt(2)
	v_mfma_f32_16x16x32_bf16 v[156:159], v[120:123], v[76:79], v[128:131]
	v_mfma_f32_16x16x32_bf16 v[140:143], v[120:123], v[88:91], v[124:127]
	ds_read_b128 v[120:123], v0 offset:7296
	s_waitcnt lgkmcnt(2)
	v_mfma_f32_16x16x32_bf16 v[124:127], v[136:139], v[68:71], 0
	v_mfma_f32_16x16x32_bf16 v[128:131], v[136:139], v[80:83], 0
	ds_read_b128 v[136:139], v0 offset:10752
	s_waitcnt lgkmcnt(2)
	v_mfma_f32_16x16x32_bf16 v[124:127], v[132:135], v[72:75], v[124:127]
	v_mfma_f32_16x16x32_bf16 v[128:131], v[132:135], v[84:87], v[128:131]
	ds_read_b128 v[132:135], v0 offset:10816
	s_waitcnt lgkmcnt(2)
	v_mfma_f32_16x16x32_bf16 v[152:155], v[120:123], v[76:79], v[124:127]
	v_mfma_f32_16x16x32_bf16 v[128:131], v[120:123], v[88:91], v[128:131]
	ds_read_b128 v[120:123], v0 offset:10880
	s_waitcnt lgkmcnt(2)
	v_mfma_f32_16x16x32_bf16 v[124:127], v[136:139], v[68:71], 0
	v_mfma_f32_16x16x32_bf16 v[136:139], v[136:139], v[80:83], 0
	s_waitcnt lgkmcnt(1)
	v_mfma_f32_16x16x32_bf16 v[124:127], v[132:135], v[72:75], v[124:127]
	v_mfma_f32_16x16x32_bf16 v[132:135], v[132:135], v[84:87], v[136:139]
	s_waitcnt lgkmcnt(0)
	v_mfma_f32_16x16x32_bf16 v[148:151], v[120:123], v[76:79], v[124:127]
	v_mfma_f32_16x16x32_bf16 v[136:139], v[120:123], v[88:91], v[132:135]
	s_setprio 0
	v_cmp_le_i32_e32 vcc, s75, v223
	s_and_saveexec_b64 s[8:9], vcc
	s_xor_b64 s[8:9], exec, s[8:9]
	s_cbranch_execz .LBB0_458
	v_and_b32_e32 v121, 64, v220
	v_xor_b32_e32 v120, 16, v220
	v_add_u32_e32 v121, 64, v121
	v_cmp_lt_i32_e32 vcc, v120, v121
	v_xor_b32_e32 v122, 32, v220
	v_max_f32_e32 v123, v160, v160
	v_cndmask_b32_e32 v120, v220, v120, vcc
	v_cmp_lt_i32_e32 vcc, v122, v121
	v_max_f32_e32 v124, v145, v145
	v_max_f32_e32 v125, v144, v144
	v_cndmask_b32_e32 v121, v220, v122, vcc
	v_max_f32_e32 v122, v161, v161
	v_max_f32_e32 v122, v123, v122
	v_max_f32_e32 v124, v125, v124
	v_max3_f32 v122, v122, v162, v163
	v_max3_f32 v124, v124, v146, v147
	v_max3_f32 v122, v122, v156, v157
	v_max3_f32 v124, v124, v140, v141
	v_max3_f32 v122, v122, v158, v159
	v_max3_f32 v124, v124, v142, v143
	v_max3_f32 v122, v122, v152, v153
	v_max3_f32 v124, v124, v128, v129
	v_max3_f32 v122, v122, v154, v155
	v_max3_f32 v124, v124, v130, v131
	v_max3_f32 v122, v122, v148, v149
	v_max3_f32 v124, v124, v136, v137
	v_lshlrev_b32_e32 v120, 2, v120
	v_max3_f32 v122, v122, v150, v151
	v_max3_f32 v124, v124, v138, v139
	ds_bpermute_b32 v123, v120, v122
	ds_bpermute_b32 v120, v120, v124
	v_lshlrev_b32_e32 v121, 2, v121
	s_waitcnt lgkmcnt(1)
	v_max_f32_e32 v123, v123, v123
	s_waitcnt lgkmcnt(0)
	v_max_f32_e32 v120, v120, v120
	v_max_f32_e32 v122, v122, v123
	v_max_f32_e32 v124, v124, v120
	ds_bpermute_b32 v123, v121, v122
	ds_bpermute_b32 v121, v121, v124
	s_waitcnt lgkmcnt(1)
	v_max_f32_e32 v120, v123, v123
	s_waitcnt lgkmcnt(0)
	v_max_f32_e32 v121, v121, v121
	v_max_f32_e32 v120, v122, v120
	v_max_f32_e32 v121, v124, v121
	v_add_f32_e64 v122, v206, s52
	v_add_f32_e64 v123, v207, s52
	v_mul_f32_e64 v124, v120, s54
	v_mul_f32_e64 v125, v121, s54
	v_fma_f32 v120, v120, s54, 0
	v_fma_f32 v121, v121, s54, 0
	v_cmp_gt_f32_e32 vcc, v125, v123
	s_nop 1
	v_cndmask_b32_e32 v205, v207, v121, vcc
	v_cmp_gt_f32_e32 vcc, v124, v122
	s_nop 1
	v_cndmask_b32_e32 v204, v206, v120, vcc
	v_sub_f32_e32 v120, 0, v204
	v_cmp_ngt_f32_e32 vcc, s69, v204
	v_add_f32_e64 v132, v206, -v204
	v_add_f32_e64 v133, v207, -v205
	s_nop 0
	v_cndmask_b32_e32 v120, 0, v120, vcc
	v_fmamk_f32 v121, v160, 0x3e16c740, v120
	v_exp_f32_e32 v135, v121
	v_fmamk_f32 v121, v161, 0x3e16c740, v120
	v_exp_f32_e32 v161, v121
	v_fmamk_f32 v121, v162, 0x3e16c740, v120
	v_exp_f32_e32 v207, v121
	v_fmamk_f32 v121, v163, 0x3e16c740, v120
	v_exp_f32_e32 v163, v121
	v_fmamk_f32 v121, v156, 0x3e16c740, v120
	v_exp_f32_e32 v239, v121
	v_fmamk_f32 v121, v157, 0x3e16c740, v120
	v_exp_f32_e32 v157, v121
	v_fmamk_f32 v121, v158, 0x3e16c740, v120
	v_exp_f32_e32 v241, v121
	v_fmamk_f32 v121, v159, 0x3e16c740, v120
	v_exp_f32_e32 v159, v121
	v_fmamk_f32 v121, v152, 0x3e16c740, v120
	v_exp_f32_e32 v209, v121
	v_fmamk_f32 v121, v153, 0x3e16c740, v120
	v_exp_f32_e32 v153, v121
	v_fmamk_f32 v121, v154, 0x3e16c740, v120
	v_exp_f32_e32 v213, v132
	v_exp_f32_e32 v211, v121
	v_fmamk_f32 v121, v155, 0x3e16c740, v120
	v_sub_f32_e32 v132, 0, v205
	v_cmp_ngt_f32_e32 vcc, s69, v205
	v_exp_f32_e32 v155, v121
	v_fmamk_f32 v121, v148, 0x3e16c740, v120
; DI float ex2(float x) { return __builtin_amdgcn_exp2f(x); }
; template <int NT> DI void softmax_fast(f32x4 (&S)[4][NT], float (&m)[NT], float (&l)[NT], float (&alpha)[NT], bf16x8 (&pb)[2][NT], float sc2, const float (&bias)[NT]) {
;     ...
;     float sum = 0.f;
; #pragma unroll
;     for (int mt = 0; mt < 4; ++mt)
; #pragma unroll
;       for (int j = 0; j < 4; ++j) { const float pv = ex2(S[mt][nt][j] * sc2 + c); sum += pv; S[mt][nt][j] = pv; }
;     l[nt] = l[nt] * alpha[nt] + sum;
;     pb[0][nt] = pack8(S[0][nt], S[1][nt]);
;     pb[1][nt] = pack8(S[2][nt], S[3][nt]);
;   }
; DI void mla_item(const Params& p, int it, unsigned char* smem, u16* mb_out) {
;     ...
;       } else {
;         const int dq = qw0 + lr - k0 - lq * 4;
;         softmax_step<2>(S, m, l, alpha, pb, [&](int mt, int j, int nt, float raw) {
;           return ((dq + nt * 16) - (mt * 16 + j) >= 0) ? raw * sc2 : -1e30f;
;         });
	v_cndmask_b32_e32 v148, 0, v132, vcc
	v_fmamk_f32 v132, v144, 0x3e16c740, v148
	v_exp_f32_e32 v134, v132
	v_fmamk_f32 v132, v145, 0x3e16c740, v148
	v_exp_f32_e32 v160, v132
	v_fmamk_f32 v132, v146, 0x3e16c740, v148
	v_exp_f32_e32 v206, v132
	v_fmamk_f32 v132, v147, 0x3e16c740, v148
	v_exp_f32_e32 v162, v132
	v_fmamk_f32 v132, v140, 0x3e16c740, v148
	v_exp_f32_e32 v238, v132
	v_fmamk_f32 v132, v141, 0x3e16c740, v148
	v_exp_f32_e32 v156, v132
	v_fmamk_f32 v132, v142, 0x3e16c740, v148
	v_exp_f32_e32 v240, v132
	v_fmamk_f32 v132, v143, 0x3e16c740, v148
	v_exp_f32_e32 v212, v133
	v_exp_f32_e32 v158, v132
	v_add_f32_e64 v132, v134, 0
	v_add_f32_e64 v133, v135, 0
	v_fmamk_f32 v128, v128, 0x3e16c740, v148
	v_add_f32_e64 v132, v160, v132
	v_add_f32_e64 v133, v161, v133
	v_exp_f32_e32 v208, v128
	v_add_f32_e64 v132, v206, v132
	v_add_f32_e64 v133, v207, v133
	v_exp_f32_e32 v243, v121
	v_add_f32_e64 v132, v162, v132
	v_add_f32_e64 v133, v163, v133
	v_fmamk_f32 v121, v149, 0x3e16c740, v120
	v_add_f32_e64 v132, v238, v132
	v_add_f32_e64 v133, v239, v133
	v_exp_f32_e32 v149, v121
	v_add_f32_e64 v132, v156, v132
	v_add_f32_e64 v133, v157, v133
	v_fmamk_f32 v121, v150, 0x3e16c740, v120
	v_add_f32_e64 v132, v240, v132
	v_add_f32_e64 v133, v241, v133
	v_fmac_f32_e32 v120, 0x3e16c740, v151
	v_add_f32_e64 v132, v158, v132
	v_add_f32_e64 v133, v159, v133
	v_fmamk_f32 v128, v129, 0x3e16c740, v148
	v_exp_f32_e32 v151, v120
	v_cvt_pk_bf16_f32 v120, v209, v153
	v_add_f32_e64 v132, v208, v132
	v_add_f32_e64 v133, v209, v133
	v_exp_f32_e32 v209, v128
	v_fmamk_f32 v128, v130, 0x3e16c740, v148
	v_exp_f32_e32 v210, v128
	v_fmamk_f32 v128, v131, 0x3e16c740, v148
	v_exp_f32_e32 v154, v128
	v_fmamk_f32 v128, v136, 0x3e16c740, v148
	v_exp_f32_e32 v216, v128
	v_fmamk_f32 v128, v137, 0x3e16c740, v148
	v_exp_f32_e32 v217, v128
	v_fmamk_f32 v128, v138, 0x3e16c740, v148
	v_mov_b32_e32 v152, v209
	v_exp_f32_e32 v214, v128
	v_add_f32_e64 v128, v152, v132
	v_add_f32_e64 v129, v153, v133
	v_exp_f32_e32 v215, v121
	v_fmac_f32_e32 v148, 0x3e16c740, v139
	v_add_f32_e64 v128, v210, v128
	v_add_f32_e64 v129, v211, v129
	v_exp_f32_e32 v150, v148
	v_add_f32_e64 v128, v154, v128
	v_add_f32_e64 v129, v155, v129
	v_mov_b32_e32 v242, v216
	v_add_f32_e64 v128, v242, v128
	v_add_f32_e64 v129, v243, v129
	v_mov_b32_e32 v148, v217
	v_add_f32_e64 v128, v148, v128
	v_add_f32_e64 v129, v149, v129
	v_cvt_pk_bf16_f32 v124, v135, v161
	v_add_f32_e64 v128, v214, v128
	v_add_f32_e64 v129, v215, v129
	v_cvt_pk_bf16_f32 v125, v207, v163
	v_add_f32_e64 v128, v150, v128
	v_add_f32_e64 v129, v151, v129
	v_cvt_pk_bf16_f32 v126, v239, v157
	v_cvt_pk_bf16_f32 v127, v241, v159
	v_cvt_pk_bf16_f32 v121, v211, v155
	v_cvt_pk_bf16_f32 v122, v243, v149
	v_cvt_pk_bf16_f32 v123, v215, v151
	v_fma_f32 v168, v168, v212, v128
	v_fma_f32 v169, v169, v213, v129
	v_cvt_pk_bf16_f32 v132, v134, v160
	v_cvt_pk_bf16_f32 v133, v206, v162
	v_cvt_pk_bf16_f32 v134, v238, v156
	v_cvt_pk_bf16_f32 v135, v240, v158
	v_mov_b32_e32 v211, v154
	v_mov_b32_e32 v215, v150
.LBB0_458:
	s_andn2_saveexec_b64 s[62:63], s[8:9]
	s_cbranch_execz .LBB0_460
	v_mul_f32_e32 v133, 0x3e16c740, v158
	v_cmp_gt_i32_e64 s[18:19], 18, v229
	v_cmp_gt_i32_e64 s[20:21], 19, v229
	v_mul_f32_e32 v127, 0x3e16c740, v156
	v_cndmask_b32_e64 v134, v133, v166, s[18:19]
	v_mul_f32_e32 v133, 0x3e16c740, v159
	v_cndmask_b32_e64 v156, v133, v166, s[20:21]
	v_mul_f32_e32 v133, 0x3e16c740, v152
	v_cmp_gt_i32_e64 s[22:23], 32, v229
	v_cmp_gt_i32_e64 s[24:25], 33, v229
	v_cmp_gt_i32_e64 s[26:27], 34, v229
	v_cndmask_b32_e64 v152, v133, v166, s[22:23]
	v_mul_f32_e32 v133, 0x3e16c740, v153
	v_cndmask_b32_e64 v153, v133, v166, s[24:25]
	v_mul_f32_e32 v133, 0x3e16c740, v154
	v_cndmask_b32_e64 v154, v133, v166, s[26:27]
	v_mul_f32_e32 v133, 0x3e16c740, v155
	v_cmp_gt_i32_e64 s[28:29], 35, v229
	v_cmp_lt_i32_e64 s[30:31], 47, v229
	v_mul_f32_e32 v132, 0x3e16c740, v157
	v_cndmask_b32_e64 v155, v133, v166, s[28:29]
	v_mul_f32_e32 v133, 0x3e16c740, v148
	v_cndmask_b32_e64 v148, v166, v133, s[30:31]
	v_mul_f32_e32 v133, 0x3e16c740, v149
	v_cmp_lt_i32_e64 s[30:31], 48, v229
	v_and_b32_e32 v121, 64, v220
	v_xor_b32_e32 v120, 16, v220
	v_cndmask_b32_e64 v157, v166, v133, s[30:31]
	v_mul_f32_e32 v133, 0x3e16c740, v150
	v_cmp_lt_i32_e64 s[30:31], 49, v229
	v_add_u32_e32 v121, 64, v121
	v_cmp_lt_i32_e32 vcc, v120, v121
	v_cndmask_b32_e64 v150, v166, v133, s[30:31]
	v_mul_f32_e32 v133, 0x3e16c740, v151
	v_cmp_lt_i32_e64 s[30:31], 50, v229
	v_xor_b32_e32 v122, 32, v220
	v_mul_f32_e32 v135, 0x3e16c740, v144
	v_cndmask_b32_e64 v158, v166, v133, s[30:31]
	s_movk_i32 s30, 0xffef
	v_cmp_lt_i32_e64 s[30:31], s30, v229
	v_cndmask_b32_e32 v120, v220, v120, vcc
	v_cmp_lt_i32_e32 vcc, v122, v121
	v_cndmask_b32_e64 v144, v166, v135, s[30:31]
	v_mul_f32_e32 v135, 0x3e16c740, v145
	v_cmp_lt_i32_e64 s[30:31], -16, v229
	v_cndmask_b32_e32 v121, v220, v122, vcc
	v_mul_f32_e32 v122, 0x3e16c740, v160
	v_cmp_gt_i32_e32 vcc, 0, v229
	v_mul_f32_e32 v123, 0x3e16c740, v161
	v_cmp_gt_i32_e64 s[8:9], 1, v229
	v_cndmask_b32_e64 v159, v166, v135, s[30:31]
	v_mul_f32_e32 v145, 0x3e16c740, v146
	v_cmp_lt_i32_e64 s[30:31], -15, v229
	v_cndmask_b32_e32 v122, v122, v166, vcc
	v_cndmask_b32_e64 v123, v123, v166, s[8:9]
	v_mul_f32_e32 v125, 0x3e16c740, v162
	v_cmp_gt_i32_e64 s[10:11], 2, v229
	v_mul_f32_e32 v126, 0x3e16c740, v163
	v_cmp_gt_i32_e64 s[12:13], 3, v229
	v_cmp_gt_i32_e64 s[14:15], 16, v229
	v_cndmask_b32_e64 v146, v166, v145, s[30:31]
	v_mul_f32_e32 v145, 0x3e16c740, v147
	v_cmp_lt_i32_e64 s[30:31], -14, v229
	v_mul_f32_e32 v141, 0x3e16c740, v141
	v_mul_f32_e32 v128, 0x3e16c740, v128
	v_max3_f32 v124, v122, s68, v123
; DI float ex2(float x) { return __builtin_amdgcn_exp2f(x); }
; template <int NT, class F> DI void softmax_step(f32x4 (&S)[4][NT], float (&m)[NT], float (&l)[NT], float (&alpha)[NT], bf16x8 (&pb)[2][NT], F f) {
; #pragma unroll
;   for (int nt = 0; nt < NT; ++nt) {
;     float mx = -1e30f;
; #pragma unroll
;     for (int mt = 0; mt < 4; ++mt)
; #pragma unroll
;       for (int j = 0; j < 4; ++j) { const float s2 = f(mt, j, nt, S[mt][nt][j]); S[mt][nt][j] = s2; mx = fmaxf(mx, s2); }
;     mx = fmaxf(mx, __shfl_xor(mx, 16)); mx = fmaxf(mx, __shfl_xor(mx, 32));
;     const float mn = (mx > m[nt] + 8.0f) ? mx : m[nt];
;     alpha[nt] = ex2(m[nt] - mn); m[nt] = mn;
;     const float mexp = (mn < -1e29f) ? 0.f : mn;
;     float sum = 0.f;
; #pragma unroll
;     for (int mt = 0; mt < 4; ++mt)
; #pragma unroll
;       for (int j = 0; j < 4; ++j) { const float pv = ex2(S[mt][nt][j] - mexp); sum += pv; S[mt][nt][j] = pv; }
;     l[nt] = l[nt] * alpha[nt] + sum;
;     pb[0][nt] = pack8(S[0][nt], S[1][nt]);
;     pb[1][nt] = pack8(S[2][nt], S[3][nt]);
;   }
; }
	v_cndmask_b32_e64 v125, v125, v166, s[10:11]
	v_cndmask_b32_e64 v126, v126, v166, s[12:13]
	v_cmp_gt_i32_e64 s[16:17], 17, v229
	v_max3_f32 v135, v144, s68, v159
	v_cndmask_b32_e64 v160, v166, v145, s[30:31]
	v_mul_f32_e32 v140, 0x3e16c740, v140
	v_cndmask_b32_e64 v161, v141, v166, s[8:9]
	v_mul_f32_e32 v141, 0x3e16c740, v142
	v_cndmask_b32_e64 v163, v128, v166, s[14:15]
	v_mul_f32_e32 v128, 0x3e16c740, v129
	v_mul_f32_e32 v129, 0x3e16c740, v130
	v_max3_f32 v124, v124, v125, v126
	v_cndmask_b32_e64 v127, v127, v166, s[14:15]
	v_cndmask_b32_e64 v132, v132, v166, s[16:17]
	v_max3_f32 v135, v135, v146, v160
	v_cndmask_b32_e32 v140, v140, v166, vcc
	v_cndmask_b32_e64 v142, v141, v166, s[10:11]
	v_mul_f32_e32 v141, 0x3e16c740, v143
	v_cndmask_b32_e64 v210, v129, v166, s[18:19]
	v_mul_f32_e32 v129, 0x3e16c740, v131
	v_max3_f32 v124, v124, v127, v132
	v_max3_f32 v135, v135, v140, v161
	v_cndmask_b32_e64 v162, v141, v166, s[12:13]
	v_cndmask_b32_e64 v214, v129, v166, s[20:21]
	v_mul_f32_e32 v129, 0x3e16c740, v136
	v_max3_f32 v124, v124, v134, v156
	v_max3_f32 v135, v135, v142, v162
	v_cndmask_b32_e64 v167, v128, v166, s[16:17]
	v_cndmask_b32_e64 v216, v129, v166, s[22:23]
	v_mul_f32_e32 v129, 0x3e16c740, v137
	v_max3_f32 v124, v124, v152, v153
	v_max3_f32 v128, v135, v163, v167
	v_cndmask_b32_e64 v217, v129, v166, s[24:25]
	v_mul_f32_e32 v129, 0x3e16c740, v138
	v_max3_f32 v124, v124, v154, v155
	v_max3_f32 v128, v128, v210, v214
	v_cndmask_b32_e64 v237, v129, v166, s[26:27]
	v_mul_f32_e32 v129, 0x3e16c740, v139
	v_max3_f32 v124, v124, v148, v157
	v_max3_f32 v128, v128, v216, v217
	v_cndmask_b32_e64 v238, v129, v166, s[28:29]
	v_lshlrev_b32_e32 v120, 2, v120
	v_max3_f32 v124, v124, v150, v158
	v_max3_f32 v128, v128, v237, v238
	ds_bpermute_b32 v133, v120, v124
	ds_bpermute_b32 v120, v120, v128
	v_lshlrev_b32_e32 v121, 2, v121
	s_waitcnt lgkmcnt(1)
	v_max_f32_e32 v129, v133, v133
	s_waitcnt lgkmcnt(0)
	v_max_f32_e32 v120, v120, v120
	v_max_f32_e32 v124, v124, v129
	v_max_f32_e32 v128, v128, v120
	ds_bpermute_b32 v129, v121, v124
	ds_bpermute_b32 v130, v121, v128
	s_waitcnt lgkmcnt(1)
	v_max_f32_e32 v120, v129, v129
	s_waitcnt lgkmcnt(0)
	v_max_f32_e32 v129, v130, v130
	v_max_f32_e32 v124, v124, v120
	v_add_f32_e64 v120, v206, s52
	v_add_f32_e64 v121, v207, s52
	v_max_f32_e32 v128, v128, v129
	v_cmp_gt_f32_e32 vcc, v128, v121
	s_nop 1
	v_cndmask_b32_e32 v205, v207, v128, vcc
	v_cmp_gt_f32_e32 vcc, v124, v120
	s_nop 1
	v_cndmask_b32_e32 v204, v206, v124, vcc
	v_cmp_ngt_f32_e32 vcc, s69, v204
	v_add_f32_e64 v128, v206, -v204
	v_add_f32_e64 v129, v207, -v205
	s_nop 0
	v_cndmask_b32_e32 v120, 0, v204, vcc
	v_sub_f32_e32 v121, v122, v120
	v_exp_f32_e32 v131, v121
	v_sub_f32_e32 v121, v123, v120
	v_exp_f32_e32 v133, v121
	v_sub_f32_e32 v121, v125, v120
	v_exp_f32_e32 v135, v121
	v_sub_f32_e32 v121, v126, v120
	v_exp_f32_e32 v137, v121
	v_sub_f32_e32 v121, v127, v120
	v_exp_f32_e32 v139, v121
	v_sub_f32_e32 v121, v132, v120
	v_exp_f32_e32 v141, v121
	v_sub_f32_e32 v121, v134, v120
	v_exp_f32_e32 v143, v121
	v_sub_f32_e32 v121, v156, v120
	v_exp_f32_e32 v145, v121
	v_sub_f32_e32 v121, v152, v120
	v_exp_f32_e32 v209, v121
	v_sub_f32_e32 v121, v153, v120
	v_exp_f32_e32 v147, v121
	v_sub_f32_e32 v121, v154, v120
	v_exp_f32_e32 v211, v121
	v_sub_f32_e32 v121, v155, v120
	v_exp_f32_e32 v149, v121
	v_sub_f32_e32 v121, v148, v120
	v_exp_f32_e32 v151, v121
	v_sub_f32_e32 v121, v157, v120
	v_cmp_ngt_f32_e32 vcc, s69, v205
	v_exp_f32_e32 v153, v121
	v_sub_f32_e32 v121, v150, v120
	v_cndmask_b32_e32 v150, 0, v205, vcc
	v_exp_f32_e32 v213, v128
	v_sub_f32_e32 v128, v144, v150
	v_exp_f32_e32 v130, v128
	v_sub_f32_e32 v128, v159, v150
	v_exp_f32_e32 v132, v128
	v_sub_f32_e32 v128, v146, v150
	v_exp_f32_e32 v134, v128
	v_sub_f32_e32 v128, v160, v150
	v_exp_f32_e32 v136, v128
	v_sub_f32_e32 v128, v140, v150
	v_exp_f32_e32 v138, v128
	v_sub_f32_e32 v128, v161, v150
	v_exp_f32_e32 v140, v128
	v_sub_f32_e32 v128, v142, v150
	v_exp_f32_e32 v142, v128
	v_sub_f32_e32 v128, v162, v150
	v_exp_f32_e32 v144, v128
	v_sub_f32_e32 v128, v163, v150
	v_exp_f32_e32 v212, v129
	v_exp_f32_e32 v208, v128
	v_add_f32_e64 v128, v130, 0
	v_add_f32_e64 v129, v131, 0
	v_sub_f32_e32 v120, v158, v120
	v_add_f32_e64 v128, v132, v128
	v_add_f32_e64 v129, v133, v129
	v_cvt_pk_bf16_f32 v124, v131, v133
	v_add_f32_e64 v128, v134, v128
	v_add_f32_e64 v129, v135, v129
	v_sub_f32_e32 v131, v167, v150
	v_add_f32_e64 v128, v136, v128
	v_add_f32_e64 v129, v137, v129
	v_exp_f32_e32 v155, v120
	v_add_f32_e64 v128, v138, v128
	v_add_f32_e64 v129, v139, v129
	v_cvt_pk_bf16_f32 v120, v209, v147
	v_add_f32_e64 v128, v140, v128
	v_add_f32_e64 v129, v141, v129
	v_exp_f32_e32 v215, v121
	v_add_f32_e64 v128, v142, v128
	v_add_f32_e64 v129, v143, v129
	v_cvt_pk_bf16_f32 v125, v135, v137
	v_add_f32_e64 v128, v144, v128
	v_add_f32_e64 v129, v145, v129
	v_cvt_pk_bf16_f32 v126, v139, v141
	v_add_f32_e64 v128, v208, v128
	v_add_f32_e64 v129, v209, v129
	v_exp_f32_e32 v209, v131
	v_sub_f32_e32 v131, v210, v150
	v_exp_f32_e32 v210, v131
	v_sub_f32_e32 v131, v214, v150
	v_exp_f32_e32 v148, v131
	v_sub_f32_e32 v131, v216, v150
	v_exp_f32_e32 v216, v131
	v_sub_f32_e32 v131, v217, v150
	v_exp_f32_e32 v217, v131
	v_mov_b32_e32 v146, v209
	v_sub_f32_e32 v131, v237, v150
	v_add_f32_e64 v128, v146, v128
	v_add_f32_e64 v129, v147, v129
	v_exp_f32_e32 v214, v131
	v_sub_f32_e32 v131, v238, v150
	v_add_f32_e64 v128, v210, v128
	v_add_f32_e64 v129, v211, v129
	v_exp_f32_e32 v154, v131
	v_add_f32_e64 v128, v148, v128
	v_add_f32_e64 v129, v149, v129
	v_mov_b32_e32 v150, v216
	v_add_f32_e64 v128, v150, v128
	v_add_f32_e64 v129, v151, v129
	v_mov_b32_e32 v152, v217
	v_add_f32_e64 v128, v152, v128
	v_add_f32_e64 v129, v153, v129
	v_cvt_pk_bf16_f32 v127, v143, v145
	v_add_f32_e64 v128, v214, v128
	v_add_f32_e64 v129, v215, v129
	v_cvt_pk_bf16_f32 v121, v211, v149
	v_add_f32_e64 v128, v154, v128
	v_add_f32_e64 v129, v155, v129
	v_cvt_pk_bf16_f32 v122, v151, v153
	v_cvt_pk_bf16_f32 v123, v215, v155
	v_fma_f32 v168, v168, v212, v128
	v_fma_f32 v169, v169, v213, v129
	v_cvt_pk_bf16_f32 v132, v130, v132
	v_cvt_pk_bf16_f32 v133, v134, v136
	v_cvt_pk_bf16_f32 v134, v138, v140
	v_cvt_pk_bf16_f32 v135, v142, v144
	v_mov_b32_e32 v211, v148
	v_mov_b32_e32 v215, v154
; DI void mla_item(const Params& p, int it, unsigned char* smem, u16* mb_out) {
;     ...
;       if (__any((alpha[0] != 1.0f) || (alpha[1] != 1.0f))) {
; #pragma unroll
;         for (int dt = 0; dt < 4; ++dt) { Oa[dt][0] = Oa[dt][0] * alpha[0]; Oa[dt][1] = Oa[dt][1] * alpha[1]; Ob[dt][0] = Ob[dt][0] * alpha[0]; Ob[dt][1] = Ob[dt][1] * alpha[1]; }
;       }
.LBB0_460:
	s_or_b64 exec, exec, s[62:63]
	v_cmp_neq_f32_e32 vcc, 1.0, v213
	v_cmp_neq_f32_e64 s[8:9], 1.0, v212
	s_or_b64 vcc, vcc, s[8:9]
	s_cbranch_vccz .LBB0_439
	v_mov_b32_e32 v128, v213
	v_mul_f32_e64 v66, v66, v128
	v_mul_f32_e64 v67, v67, v128
	v_mul_f32_e64 v64, v64, v128
	v_mul_f32_e64 v65, v65, v128
	v_mul_f32_e64 v34, v34, v212
	v_mul_f32_e64 v35, v35, v212
	v_mul_f32_e64 v32, v32, v212
	v_mul_f32_e64 v33, v33, v212
	v_mul_f32_e64 v50, v50, v128
	v_mul_f32_e64 v51, v51, v128
	v_mul_f32_e64 v48, v48, v128
	v_mul_f32_e64 v49, v49, v128
	v_mul_f32_e64 v18, v18, v212
	v_mul_f32_e64 v19, v19, v212
	v_mul_f32_e64 v16, v16, v212
	v_mul_f32_e64 v17, v17, v212
	v_mul_f32_e64 v62, v62, v128
	v_mul_f32_e64 v63, v63, v128
	v_mul_f32_e64 v60, v60, v128
	v_mul_f32_e64 v61, v61, v128
	v_mul_f32_e64 v30, v30, v212
	v_mul_f32_e64 v31, v31, v212
	v_mul_f32_e64 v28, v28, v212
	v_mul_f32_e64 v29, v29, v212
	v_mul_f32_e64 v46, v46, v128
	v_mul_f32_e64 v47, v47, v128
	v_mul_f32_e64 v44, v44, v128
	v_mul_f32_e64 v45, v45, v128
	v_mul_f32_e64 v14, v14, v212
	v_mul_f32_e64 v15, v15, v212
	v_mul_f32_e64 v12, v12, v212
	v_mul_f32_e64 v13, v13, v212
	v_mul_f32_e64 v58, v58, v128
	v_mul_f32_e64 v59, v59, v128
	v_mul_f32_e64 v56, v56, v128
	v_mul_f32_e64 v57, v57, v128
	v_mul_f32_e64 v26, v26, v212
	v_mul_f32_e64 v27, v27, v212
	v_mul_f32_e64 v24, v24, v212
	v_mul_f32_e64 v25, v25, v212
	v_mul_f32_e64 v42, v42, v128
	v_mul_f32_e64 v43, v43, v128
	v_mul_f32_e64 v40, v40, v128
	v_mul_f32_e64 v41, v41, v128
	v_mul_f32_e64 v10, v10, v212
	v_mul_f32_e64 v11, v11, v212
	v_mul_f32_e64 v8, v8, v212
	v_mul_f32_e64 v9, v9, v212
	v_mul_f32_e64 v54, v54, v128
	v_mul_f32_e64 v55, v55, v128
	v_mul_f32_e64 v52, v52, v128
	v_mul_f32_e64 v53, v53, v128
	v_mul_f32_e64 v22, v22, v212
	v_mul_f32_e64 v23, v23, v212
	v_mul_f32_e64 v20, v20, v212
	v_mul_f32_e64 v21, v21, v212
	v_mul_f32_e64 v38, v38, v128
	v_mul_f32_e64 v39, v39, v128
	v_mul_f32_e64 v36, v36, v128
	v_mul_f32_e64 v37, v37, v128
	v_mul_f32_e64 v6, v6, v212
	v_mul_f32_e64 v7, v7, v212
	v_mul_f32_e64 v4, v4, v212
	v_mul_f32_e64 v5, v5, v212
	s_branch .LBB0_439

; DI void cmp_item(const Params& p, int it, unsigned char* smem) {
;     ...
;   for (int e = tid; e < 512; e += 256) { const int hh = e >> 7, d = e & 127; bt[e] = p.rel[t5_bucket(d) * 16 + g * 4 + hh] * LOG2E; }
.LBB0_525:
	v_add_u32_e32 v11, 0x200, v0
	v_add_u32_e32 v12, 0x200, v1
	v_ashrrev_i32_e32 v9, 7, v1
	v_ashrrev_i32_e32 v8, 7, v0
	v_add_u32_e32 v13, 0x400, v0
	v_add_u32_e32 v14, 0x400, v1
	v_add_u32_e32 v15, 0x600, v0
	v_add_u32_e32 v16, 0x600, v1
	v_ashrrev_i32_e32 v17, 7, v12
	v_ashrrev_i32_e32 v12, 7, v11
	v_add_u32_e32 v8, v3, v8
	v_add_u32_e32 v10, v3, v9
	v_ashrrev_i32_e32 v18, 7, v14
	v_ashrrev_i32_e32 v13, 7, v13
	v_ashrrev_i32_e32 v19, 7, v16
	v_ashrrev_i32_e32 v15, 7, v15
	v_add_u32_e32 v12, v3, v12
	v_add_u32_e32 v14, v3, v17
	v_ashrrev_i32_e32 v11, 31, v10
	v_ashrrev_i32_e32 v9, 31, v8
	v_add_u32_e32 v16, v3, v13
	v_add_u32_e32 v18, v3, v18
	v_add_u32_e32 v20, v3, v15
	v_add_u32_e32 v22, v3, v19
	v_ashrrev_i32_e32 v15, 31, v14
	v_ashrrev_i32_e32 v13, 31, v12
	v_lshl_add_u64 v[8:9], v[8:9], 2, s[82:83]
	v_lshl_add_u64 v[10:11], v[10:11], 2, s[82:83]
	v_ashrrev_i32_e32 v19, 31, v18
	v_ashrrev_i32_e32 v17, 31, v16
	v_ashrrev_i32_e32 v23, 31, v22
	v_ashrrev_i32_e32 v21, 31, v20
	v_lshl_add_u64 v[12:13], v[12:13], 2, s[82:83]
	v_lshl_add_u64 v[14:15], v[14:15], 2, s[82:83]
	v_lshl_add_u64 v[16:17], v[16:17], 2, s[82:83]
	v_lshl_add_u64 v[18:19], v[18:19], 2, s[82:83]
	v_lshl_add_u64 v[20:21], v[20:21], 2, s[82:83]
	v_lshl_add_u64 v[22:23], v[22:23], 2, s[82:83]
	global_load_dword v24, v[8:9], off
	global_load_dword v25, v[10:11], off
	s_nop 0
	global_load_dword v10, v[12:13], off
	global_load_dword v11, v[14:15], off
	s_nop 0
	global_load_dword v12, v[16:17], off
	global_load_dword v13, v[18:19], off
	global_load_dword v14, v[20:21], off
	global_load_dword v15, v[22:23], off
	v_add_u32_e32 v6, -4, v6
	s_add_i32 s10, s10, 8
	v_cmp_eq_u32_e32 vcc, 0, v6
	v_add_u32_e32 v1, 0x800, v1
	v_add_u32_e32 v0, 0x800, v0
	v_mov_b32_e32 v8, s10
	s_or_b64 s[8:9], vcc, s[8:9]
	s_waitcnt vmcnt(6)
	v_mul_f32_e64 v16, v24, s12
	v_mul_f32_e64 v17, v25, s12
	ds_write2st64_b32 v7, v16, v17 offset1:4
	s_waitcnt vmcnt(4)
	v_mul_f32_e64 v10, v10, s12
	v_mul_f32_e64 v11, v11, s12
	s_waitcnt vmcnt(2)
	v_mul_f32_e64 v12, v12, s12
	v_mul_f32_e64 v13, v13, s12
	s_waitcnt vmcnt(0)
	v_mul_f32_e64 v14, v14, s12
	v_mul_f32_e64 v15, v15, s12
	ds_write2st64_b32 v7, v10, v11 offset0:8 offset1:12
	ds_write2st64_b32 v7, v12, v13 offset0:16 offset1:20
	ds_write2st64_b32 v7, v14, v15 offset0:24 offset1:28
	v_add_u32_e32 v7, 0x2000, v7
	s_andn2_b64 exec, exec, s[8:9]
	s_cbranch_execnz .LBB0_525
	s_or_b64 exec, exec, s[8:9]
	s_mov_b32 s10, 0x3fb8aa3b

; DI void cmp_item(const Params& p, int it, unsigned char* smem) {
;     ...
;   for (int e = tid; e < 512; e += 256) { const int hh = e >> 7, d = e & 127; bt[e] = p.rel[t5_bucket(d) * 16 + g * 4 + hh] * LOG2E; }
.LBB0_529:
	v_ashrrev_i32_e32 v8, 7, v0
	v_ashrrev_i32_e32 v7, 7, v1
	v_add_u32_e32 v8, v3, v8
	v_add_u32_e32 v10, v3, v7
	v_ashrrev_i32_e32 v9, 31, v8
	v_ashrrev_i32_e32 v11, 31, v10
	v_lshl_add_u64 v[8:9], v[8:9], 2, s[82:83]
	v_lshl_add_u64 v[10:11], v[10:11], 2, s[82:83]
	global_load_dword v8, v[8:9], off
	s_nop 0
	global_load_dword v9, v[10:11], off
	v_add_u32_e32 v5, -1, v5
	v_cmp_eq_u32_e32 vcc, 0, v5
	v_add_u32_e32 v1, 0x200, v1
	v_add_u32_e32 v0, 0x200, v0
	s_or_b64 s[8:9], vcc, s[8:9]
	s_waitcnt vmcnt(0)
	v_mul_f32_e64 v8, v8, s10
	v_mul_f32_e64 v9, v9, s10
	ds_write2st64_b32 v6, v8, v9 offset1:4
	v_add_u32_e32 v6, 0x800, v6
	s_andn2_b64 exec, exec, s[8:9]
	s_cbranch_execnz .LBB0_529

; DI float ex2(float x) { return __builtin_amdgcn_exp2f(x); }
; DI void cmp_item(const Params& p, int it, unsigned char* smem) {
;     ...
;     mx = fmaxf(mx, __shfl_xor(mx, 16)); mx = fmaxf(mx, __shfl_xor(mx, 32));
;     float sum = 0.f;
; #pragma unroll
;     for (int mt = 0; mt < 8; ++mt)
; #pragma unroll
;       for (int j = 0; j < 4; ++j) { const float s2 = S[mt][j]; const float pv = (s2 > -1e29f) ? ex2(s2 - mx) : 0.f; S[mt][j] = pv; sum += pv; }
;     sum += __shfl_xor(sum, 16); sum += __shfl_xor(sum, 32);
.LBB0_535:
	s_or_b64 exec, exec, vcc
	s_nop 1
	ds_bpermute_b32 v12, v40, v36
	v_max_f32_e32 v13, v36, v36
	v_cmp_lt_f32_e32 vcc, s33, v0
	s_waitcnt lgkmcnt(0)
	v_max_f32_e32 v12, v12, v12
	v_max_f32_e32 v12, v13, v12
	ds_bpermute_b32 v13, v91, v12
	s_waitcnt lgkmcnt(0)
	v_max_f32_e32 v13, v13, v13
	v_max_f32_e32 v36, v12, v13
	v_sub_f32_e32 v12, v0, v36
	v_sub_f32_e32 v13, v1, v36
	v_exp_f32_e32 v12, v12
	v_sub_f32_e32 v14, v2, v36
	v_exp_f32_e32 v13, v13
	v_exp_f32_e32 v14, v14
	v_sub_f32_e32 v15, v3, v36
	v_cndmask_b32_e32 v0, 0, v12, vcc
	v_cmp_lt_f32_e32 vcc, s33, v1
	v_exp_f32_e32 v15, v15
	v_add_f32_e32 v12, 0, v0
	v_cndmask_b32_e32 v1, 0, v13, vcc
	v_cmp_lt_f32_e32 vcc, s33, v2
	v_sub_f32_e32 v13, v4, v36
	v_exp_f32_e32 v13, v13
	v_cndmask_b32_e32 v2, 0, v14, vcc
	v_sub_f32_e32 v14, v5, v36
	v_exp_f32_e32 v14, v14
	v_cmp_lt_f32_e32 vcc, s33, v3
	v_add_f32_e32 v12, v1, v12
	v_add_f32_e32 v12, v2, v12
	v_cndmask_b32_e32 v3, 0, v15, vcc
	v_cmp_lt_f32_e32 vcc, s33, v4
	v_add_f32_e32 v12, v3, v12
	s_nop 0
	v_cndmask_b32_e32 v4, 0, v13, vcc
	v_cmp_lt_f32_e32 vcc, s33, v5
	v_sub_f32_e32 v13, v6, v36
	v_exp_f32_e32 v13, v13
	v_cndmask_b32_e32 v5, 0, v14, vcc
	v_sub_f32_e32 v14, v7, v36
	v_exp_f32_e32 v14, v14
	v_add_f32_e32 v12, v4, v12
	v_cmp_lt_f32_e32 vcc, s33, v6
	v_add_f32_e32 v12, v5, v12
	s_nop 0
	v_cndmask_b32_e32 v6, 0, v13, vcc
	v_cmp_lt_f32_e32 vcc, s33, v7
	v_add_f32_e32 v12, v6, v12
	s_nop 0
	v_cndmask_b32_e32 v7, 0, v14, vcc
	v_add_f32_e32 v13, v7, v12
	v_sub_f32_e32 v12, v16, v36
	v_exp_f32_e32 v12, v12
	v_sub_f32_e32 v14, v17, v36
	v_exp_f32_e32 v14, v14
	v_cmp_lt_f32_e32 vcc, s33, v16
	v_sub_f32_e32 v16, v19, v36
	v_exp_f32_e32 v16, v16
	v_cndmask_b32_e32 v12, 0, v12, vcc
	v_cmp_lt_f32_e32 vcc, s33, v17
	v_add_f32_e32 v15, v12, v13
	s_nop 0
	v_cndmask_b32_e32 v13, 0, v14, vcc
	v_sub_f32_e32 v14, v18, v36
	v_exp_f32_e32 v14, v14
	v_cmp_lt_f32_e32 vcc, s33, v18
	v_add_f32_e32 v15, v13, v15
	v_sub_f32_e32 v18, v21, v36
	v_cndmask_b32_e32 v14, 0, v14, vcc
	v_cmp_lt_f32_e32 vcc, s33, v19
	v_add_f32_e32 v17, v14, v15
	v_exp_f32_e32 v18, v18
	v_cndmask_b32_e32 v15, 0, v16, vcc
	v_sub_f32_e32 v16, v20, v36
	v_exp_f32_e32 v16, v16
	v_cmp_lt_f32_e32 vcc, s33, v20
	v_add_f32_e32 v17, v15, v17
	v_sub_f32_e32 v20, v23, v36
	v_cndmask_b32_e32 v16, 0, v16, vcc
	v_cmp_lt_f32_e32 vcc, s33, v21
	v_add_f32_e32 v19, v16, v17
	v_exp_f32_e32 v20, v20
	v_cndmask_b32_e32 v17, 0, v18, vcc
	v_sub_f32_e32 v18, v22, v36
	v_exp_f32_e32 v18, v18
	v_cmp_lt_f32_e32 vcc, s33, v22
	v_add_f32_e32 v19, v17, v19
	v_sub_f32_e32 v22, v25, v36
	v_cndmask_b32_e32 v18, 0, v18, vcc
	v_cmp_lt_f32_e32 vcc, s33, v23
	v_add_f32_e32 v21, v18, v19
	v_exp_f32_e32 v22, v22
	v_cndmask_b32_e32 v19, 0, v20, vcc
	v_sub_f32_e32 v20, v24, v36
	v_exp_f32_e32 v20, v20
	v_cmp_lt_f32_e32 vcc, s33, v24
	v_add_f32_e32 v21, v19, v21
	v_sub_f32_e32 v24, v27, v36
	v_cndmask_b32_e32 v20, 0, v20, vcc
	v_cmp_lt_f32_e32 vcc, s33, v25
	v_add_f32_e32 v23, v20, v21
	v_exp_f32_e32 v24, v24
	v_cndmask_b32_e32 v21, 0, v22, vcc
	v_sub_f32_e32 v22, v26, v36
	v_exp_f32_e32 v22, v22
	v_cmp_lt_f32_e32 vcc, s33, v26
	v_add_f32_e32 v23, v21, v23
	v_sub_f32_e32 v26, v29, v36
	v_cndmask_b32_e32 v22, 0, v22, vcc
	v_cmp_lt_f32_e32 vcc, s33, v27
	v_add_f32_e32 v25, v22, v23
	v_exp_f32_e32 v26, v26
	v_cndmask_b32_e32 v23, 0, v24, vcc
	v_sub_f32_e32 v24, v28, v36
	v_exp_f32_e32 v24, v24
	v_cmp_lt_f32_e32 vcc, s33, v28
	v_add_f32_e32 v25, v23, v25
	v_sub_f32_e32 v28, v31, v36
	v_cndmask_b32_e32 v24, 0, v24, vcc
	v_cmp_lt_f32_e32 vcc, s33, v29
	v_add_f32_e32 v27, v24, v25
	v_exp_f32_e32 v28, v28
	v_cndmask_b32_e32 v25, 0, v26, vcc
	v_sub_f32_e32 v26, v30, v36
	v_exp_f32_e32 v26, v26
	v_cmp_lt_f32_e32 vcc, s33, v30
	v_add_f32_e32 v27, v25, v27
	v_sub_f32_e32 v30, v33, v36
	v_cndmask_b32_e32 v26, 0, v26, vcc
	v_cmp_lt_f32_e32 vcc, s33, v31
	v_add_f32_e32 v29, v26, v27
	v_exp_f32_e32 v30, v30
	v_cndmask_b32_e32 v27, 0, v28, vcc
	v_sub_f32_e32 v28, v32, v36
	v_exp_f32_e32 v28, v28
	v_cmp_lt_f32_e32 vcc, s33, v32
	v_add_f32_e32 v29, v27, v29
	v_sub_f32_e32 v32, v35, v36
	v_cndmask_b32_e32 v28, 0, v28, vcc
	v_cmp_lt_f32_e32 vcc, s33, v33
	v_add_f32_e32 v31, v28, v29
	v_exp_f32_e32 v32, v32
	v_cndmask_b32_e32 v29, 0, v30, vcc
	v_sub_f32_e32 v30, v34, v36
	v_exp_f32_e32 v30, v30
	v_cmp_lt_f32_e32 vcc, s33, v34
	v_add_f32_e32 v31, v29, v31
	v_sub_f32_e32 v34, v9, v36
	v_cndmask_b32_e32 v30, 0, v30, vcc
	v_cmp_lt_f32_e32 vcc, s33, v35
	v_add_f32_e32 v33, v30, v31
	v_exp_f32_e32 v34, v34
	v_cndmask_b32_e32 v31, 0, v32, vcc
	v_add_f32_e32 v32, v31, v33
	v_sub_f32_e32 v33, v8, v36
	v_exp_f32_e32 v33, v33
	v_cmp_lt_f32_e32 vcc, s33, v8
	s_nop 1
	v_cndmask_b32_e32 v8, 0, v33, vcc
	v_cmp_lt_f32_e32 vcc, s33, v9
	v_sub_f32_e32 v33, v10, v36
	v_exp_f32_e32 v33, v33
	v_cndmask_b32_e32 v9, 0, v34, vcc
	v_sub_f32_e32 v34, v11, v36
	v_exp_f32_e32 v34, v34
	v_add_f32_e32 v32, v8, v32
	v_cmp_lt_f32_e32 vcc, s33, v10
	v_add_f32_e32 v32, v9, v32
	s_nop 0
	v_cndmask_b32_e32 v10, 0, v33, vcc
	v_cmp_lt_f32_e32 vcc, s33, v11
	v_add_f32_e32 v32, v10, v32
	s_nop 0
	v_cndmask_b32_e32 v11, 0, v34, vcc
	v_add_f32_e32 v32, v11, v32
	ds_bpermute_b32 v33, v40, v32
	s_waitcnt lgkmcnt(0)
	v_add_f32_e32 v32, v32, v33
	ds_bpermute_b32 v33, v91, v32
	s_waitcnt lgkmcnt(0)
; DI float bf2f(u16 v) { return __uint_as_float(((unsigned)v) << 16); }
; DI float sigmoidf_(float x) { return 1.0f / (1.0f + __expf(-x)); }
; DI void store4(u16* dst, f32x4 v) { uint2 w; w.x = cvtpk(v[0], v[1]); w.y = cvtpk(v[2], v[3]); *(uint2*)dst = w; }
; DI void cmp_item(const Params& p, int it, unsigned char* smem) {
;     ...
;     const float inv = sum > 0.f ? 1.0f / sum : 0.f;
; #pragma unroll
;     for (int mt = 0; mt < 8; ++mt) { S[mt] = S[mt] * inv; Ps[mt] = Ps[mt] + S[mt]; }
;     f32x4 O[4][1];
; #pragma unroll
;     for (int dt = 0; dt < 4; ++dt) O[dt][0] = (f32x4){0.f, 0.f, 0.f, 0.f};
;     __builtin_amdgcn_s_setprio(1);
; #pragma unroll
;     for (int kk = 0; kk < 4; ++kk) { bf16x8 pb[1]; pb[0] = pack8(S[2 * kk], S[2 * kk + 1]); pv32<1, KST>(O, Vs, kk * 32, 0, pb, lr, lq); }
;     __builtin_amdgcn_s_setprio(0);
;     const float g0 = sigmoidf_(bf2f(mkv[t * 256 + 160 + h * 3 + 0]));
; #pragma unroll
;     for (int dt = 0; dt < 4; ++dt) store4(abuf + t * 1024 + h * 64 + dt * 16 + lq * 4, O[dt][0] * g0);
	v_add_f32_e32 v32, v32, v33
	s_nop 0
	v_rcp_f32_e32 v33, v32
	v_cmp_lt_f32_e32 vcc, 0, v32
	s_nop 1
	v_cndmask_b32_e32 v32, 0, v33, vcc
	v_fma_f32 v52, v2, v32, v52
	v_fma_f32 v53, v3, v32, v53
	v_fma_f32 v50, v0, v32, v50
	v_fma_f32 v51, v1, v32, v51
	v_fma_f32 v54, v6, v32, v54
	v_fma_f32 v55, v7, v32, v55
	v_fma_f32 v56, v4, v32, v56
	v_fma_f32 v57, v5, v32, v57
	v_fma_f32 v58, v14, v32, v58
	v_fma_f32 v59, v15, v32, v59
	v_fma_f32 v62, v12, v32, v62
	v_fma_f32 v63, v13, v32, v63
	v_fma_f32 v60, v18, v32, v60
	v_fma_f32 v61, v19, v32, v61
	v_fma_f32 v64, v16, v32, v64
	v_fma_f32 v65, v17, v32, v65
	v_fma_f32 v66, v22, v32, v66
	v_fma_f32 v67, v23, v32, v67
	v_fma_f32 v70, v20, v32, v70
	v_fma_f32 v71, v21, v32, v71
	v_fma_f32 v68, v26, v32, v68
	v_fma_f32 v69, v27, v32, v69
	v_fma_f32 v72, v24, v32, v72
	v_fma_f32 v73, v25, v32, v73
	v_fma_f32 v74, v30, v32, v74
	v_fma_f32 v75, v31, v32, v75
	v_fma_f32 v78, v28, v32, v78
	v_fma_f32 v79, v29, v32, v79
	v_fma_f32 v76, v10, v32, v76
	v_fma_f32 v77, v11, v32, v77
	v_fma_f32 v80, v8, v32, v80
	v_fma_f32 v81, v9, v32, v81
	v_mul_f32_e64 v34, v2, v32
	v_mul_f32_e64 v35, v3, v32
	v_mul_f32_e64 v36, v0, v32
	v_mul_f32_e64 v37, v1, v32
	v_mul_f32_e64 v38, v6, v32
	v_mul_f32_e64 v39, v7, v32
	v_mul_f32_e64 v2, v4, v32
	v_mul_f32_e64 v3, v5, v32
	v_mul_f32_e64 v134, v14, v32
	v_mul_f32_e64 v135, v15, v32
	v_mul_f32_e64 v136, v12, v32
	v_mul_f32_e64 v137, v13, v32
	v_mul_f32_e64 v138, v18, v32
	v_mul_f32_e64 v139, v19, v32
	v_mul_f32_e64 v140, v16, v32
	v_mul_f32_e64 v141, v17, v32
	v_mul_f32_e64 v142, v22, v32
	v_mul_f32_e64 v143, v23, v32
	v_mul_f32_e64 v144, v20, v32
	v_mul_f32_e64 v145, v21, v32
	v_mul_f32_e64 v146, v26, v32
	v_mul_f32_e64 v147, v27, v32
	v_mul_f32_e64 v148, v24, v32
	v_mul_f32_e64 v149, v25, v32
	v_mul_f32_e64 v150, v30, v32
	v_mul_f32_e64 v151, v31, v32
	v_mul_f32_e64 v152, v28, v32
	v_mul_f32_e64 v153, v29, v32
	v_mul_f32_e64 v154, v10, v32
	v_mul_f32_e64 v155, v11, v32
	v_mul_f32_e64 v156, v8, v32
	v_mul_f32_e64 v157, v9, v32
	s_setprio 1
	v_cvt_pk_bf16_f32 v0, v36, v37
	v_cvt_pk_bf16_f32 v1, v34, v35
	v_cvt_pk_bf16_f32 v2, v2, v3
	v_cvt_pk_bf16_f32 v3, v38, v39
	ds_read_b64_tr_b16 v[16:17], v97
	ds_read_b64_tr_b16 v[18:19], v97 offset:0xa00
	ds_read_b64_tr_b16 v[12:13], v97 offset:32
	ds_read_b64_tr_b16 v[14:15], v97 offset:0xa20
	ds_read_b64_tr_b16 v[8:9], v97 offset:64
	ds_read_b64_tr_b16 v[10:11], v97 offset:0xa40
	ds_read_b64_tr_b16 v[4:5], v97 offset:96
	ds_read_b64_tr_b16 v[6:7], v97 offset:0xa60
	s_waitcnt lgkmcnt(0)
	ds_read_b64_tr_b16 v[32:33], v98
	ds_read_b64_tr_b16 v[34:35], v98 offset:0xa00
	ds_read_b64_tr_b16 v[28:29], v98 offset:32
	ds_read_b64_tr_b16 v[30:31], v98 offset:0xa20
	ds_read_b64_tr_b16 v[24:25], v98 offset:64
	ds_read_b64_tr_b16 v[26:27], v98 offset:0xa40
	ds_read_b64_tr_b16 v[20:21], v98 offset:96
	ds_read_b64_tr_b16 v[22:23], v98 offset:0xa60
	s_waitcnt lgkmcnt(0)
	s_nop 1
	v_mfma_f32_16x16x32_bf16 v[16:19], v[16:19], v[0:3], 0
	v_mfma_f32_16x16x32_bf16 v[12:15], v[12:15], v[0:3], 0
	v_mfma_f32_16x16x32_bf16 v[8:11], v[8:11], v[0:3], 0
	v_mfma_f32_16x16x32_bf16 v[0:3], v[4:7], v[0:3], 0
	v_cvt_pk_bf16_f32 v4, v136, v137
	v_cvt_pk_bf16_f32 v5, v134, v135
	v_cvt_pk_bf16_f32 v6, v140, v141
	v_cvt_pk_bf16_f32 v7, v138, v139
	s_nop 1
	v_mfma_f32_16x16x32_bf16 v[16:19], v[32:35], v[4:7], v[16:19]
	v_mfma_f32_16x16x32_bf16 v[12:15], v[28:31], v[4:7], v[12:15]
	v_mfma_f32_16x16x32_bf16 v[8:11], v[24:27], v[4:7], v[8:11]
	v_mfma_f32_16x16x32_bf16 v[0:3], v[20:23], v[4:7], v[0:3]
	v_cvt_pk_bf16_f32 v4, v144, v145
	v_cvt_pk_bf16_f32 v5, v142, v143
	v_cvt_pk_bf16_f32 v6, v148, v149
	v_cvt_pk_bf16_f32 v7, v146, v147
	ds_read_b64_tr_b16 v[32:33], v99
	ds_read_b64_tr_b16 v[34:35], v99 offset:0xa00
	ds_read_b64_tr_b16 v[28:29], v99 offset:32
	ds_read_b64_tr_b16 v[30:31], v99 offset:0xa20
	ds_read_b64_tr_b16 v[24:25], v99 offset:64
	ds_read_b64_tr_b16 v[26:27], v99 offset:0xa40
	ds_read_b64_tr_b16 v[20:21], v99 offset:96
	ds_read_b64_tr_b16 v[22:23], v99 offset:0xa60
	s_waitcnt lgkmcnt(0)
	s_nop 1
	v_mfma_f32_16x16x32_bf16 v[16:19], v[32:35], v[4:7], v[16:19]
	v_mfma_f32_16x16x32_bf16 v[12:15], v[28:31], v[4:7], v[12:15]
	v_mfma_f32_16x16x32_bf16 v[8:11], v[24:27], v[4:7], v[8:11]
	v_mfma_f32_16x16x32_bf16 v[0:3], v[20:23], v[4:7], v[0:3]
	v_cvt_pk_bf16_f32 v4, v152, v153
	v_cvt_pk_bf16_f32 v5, v150, v151
	v_cvt_pk_bf16_f32 v6, v156, v157
	v_cvt_pk_bf16_f32 v7, v154, v155
	ds_read_b64_tr_b16 v[32:33], v100
	ds_read_b64_tr_b16 v[34:35], v100 offset:0xa00
	ds_read_b64_tr_b16 v[28:29], v100 offset:32
	ds_read_b64_tr_b16 v[30:31], v100 offset:0xa20
	ds_read_b64_tr_b16 v[24:25], v100 offset:64
	ds_read_b64_tr_b16 v[26:27], v100 offset:0xa40
	ds_read_b64_tr_b16 v[20:21], v100 offset:96
	ds_read_b64_tr_b16 v[22:23], v100 offset:0xa60
	s_waitcnt lgkmcnt(0)
	s_nop 1
	v_mfma_f32_16x16x32_bf16 v[16:19], v[32:35], v[4:7], v[16:19]
	v_mfma_f32_16x16x32_bf16 v[12:15], v[28:31], v[4:7], v[12:15]
	v_mfma_f32_16x16x32_bf16 v[8:11], v[24:27], v[4:7], v[8:11]
	v_mfma_f32_16x16x32_bf16 v[0:3], v[20:23], v[4:7], v[0:3]
	s_setprio 0
	v_lshl_add_u64 v[4:5], s[42:43], 0, v[82:83]
	global_load_ushort v4, v[4:5], off
	s_addk_i32 s97, 0x200
	v_lshl_add_u64 v[82:83], v[82:83], 0, 6
	v_lshl_add_u64 v[46:47], v[46:47], 0, s[94:95]
	s_cmpk_eq_i32 s97, 0x800
	s_waitcnt vmcnt(0)
	v_lshlrev_b32_e32 v4, 16, v4
	v_mul_f32_e32 v4, 0xbfb8aa3b, v4
	v_exp_f32_e32 v4, v4
	s_nop 0
	v_add_f32_e32 v4, 1.0, v4
	v_div_scale_f32 v5, s[4:5], v4, v4, 1.0
	v_rcp_f32_e32 v6, v5
	s_nop 0
	v_fma_f32 v7, -v5, v6, 1.0
	v_fmac_f32_e32 v6, v7, v6
	v_div_scale_f32 v7, vcc, 1.0, v4, 1.0
	v_mul_f32_e32 v20, v7, v6
	v_fma_f32 v21, -v5, v20, v7
	v_fmac_f32_e32 v20, v21, v6
	v_fma_f32 v5, -v5, v20, v7
	v_div_fmas_f32 v5, v5, v6, v20
	v_rcp_f32_e32 v4, v4
	s_nop 0
	v_mul_f32_e64 v18, v18, v4
	v_mul_f32_e64 v19, v19, v4
	v_mul_f32_e64 v16, v16, v4
	v_mul_f32_e64 v17, v17, v4
	v_mul_f32_e64 v14, v14, v4
	v_mul_f32_e64 v15, v15, v4
	v_mul_f32_e64 v12, v12, v4
	v_mul_f32_e64 v13, v13, v4
	v_mul_f32_e64 v10, v10, v4
	v_mul_f32_e64 v11, v11, v4
	v_mul_f32_e64 v8, v8, v4
	v_mul_f32_e64 v9, v9, v4
	v_mul_f32_e64 v2, v2, v4
	v_mul_f32_e64 v3, v3, v4
	v_mul_f32_e64 v0, v0, v4
	v_mul_f32_e64 v1, v1, v4
	v_lshl_add_u64 v[6:7], s[42:43], 0, v[48:49]
	v_cvt_pk_bf16_f32 v16, v16, v17
	v_cvt_pk_bf16_f32 v17, v18, v19
	v_cvt_pk_bf16_f32 v12, v12, v13
	v_cvt_pk_bf16_f32 v13, v14, v15
	v_cvt_pk_bf16_f32 v8, v8, v9
	v_cvt_pk_bf16_f32 v9, v10, v11
	v_cvt_pk_bf16_f32 v0, v0, v1
	v_cvt_pk_bf16_f32 v1, v2, v3
	v_lshl_add_u64 v[48:49], v[48:49], 0, s[94:95]
	global_store_dwordx2 v[6:7], v[16:17], off offset:-64
	global_store_dwordx2 v[6:7], v[12:13], off offset:-32
	global_store_dwordx2 v[6:7], v[8:9], off
	global_store_dwordx2 v[6:7], v[0:1], off offset:32
	s_cbranch_scc1 .LBB0_632

; DI void cmp_item(const Params& p, int it, unsigned char* smem) {
;     ...
;       if ((s0 + wave * 16) - (mt * 256 + 271) >= 113) {
;         const float bf = bt[hh * 128 + 127];
; #pragma unroll
;         for (int j = 0; j < 4; ++j) { const float s2 = s[j] * sc2 + bf; s[j] = s2; mx = fmaxf(mx, s2); }
.LBB0_546:
	s_andn2_saveexec_b64 vcc, vcc
	s_cbranch_execz .LBB0_548
	s_nop 0
	v_mov_b32_e32 v0, s97
	ds_read_b32 v2, v0 offset:41468
	s_mov_b32 s4, 0xf149f2ca
	s_waitcnt lgkmcnt(0)
	v_fma_f32 v0, v4, s96, v2
	v_fma_f32 v1, v5, s96, v2
	s_nop 0
	v_max3_f32 v4, v0, s4, v1
	v_fma_f32 v3, v7, s96, v2
	v_fma_f32 v2, v6, s96, v2
	s_nop 0
	v_max3_f32 v20, v4, v2, v3

; DI void cmp_item(const Params& p, int it, unsigned char* smem) {
;     ...
;       if ((s0 + wave * 16) - (mt * 256 + 271) >= 113) {
;         const float bf = bt[hh * 128 + 127];
; #pragma unroll
;         for (int j = 0; j < 4; ++j) { const float s2 = s[j] * sc2 + bf; s[j] = s2; mx = fmaxf(mx, s2); }
.LBB0_558:
	s_andn2_saveexec_b64 vcc, vcc
	s_cbranch_execz .LBB0_560
	s_nop 0
	v_mov_b32_e32 v4, s97
	ds_read_b32 v6, v4 offset:41468
	s_waitcnt lgkmcnt(0)
	v_fma_f32 v4, v16, s96, v6
	v_fma_f32 v5, v17, s96, v6
	s_nop 0
	v_max3_f32 v16, v20, v4, v5
	v_fma_f32 v7, v19, s96, v6
	v_fma_f32 v6, v18, s96, v6
	s_nop 0
	v_max3_f32 v24, v16, v6, v7

; DI void cmp_item(const Params& p, int it, unsigned char* smem) {
;     ...
;       if ((s0 + wave * 16) - (mt * 256 + 271) >= 113) {
;         const float bf = bt[hh * 128 + 127];
; #pragma unroll
;         for (int j = 0; j < 4; ++j) { const float s2 = s[j] * sc2 + bf; s[j] = s2; mx = fmaxf(mx, s2); }
.LBB0_570:
	s_andn2_saveexec_b64 vcc, vcc
	s_cbranch_execz .LBB0_572
	s_nop 0
	v_mov_b32_e32 v16, s97
	ds_read_b32 v18, v16 offset:41468
	s_waitcnt lgkmcnt(0)
	v_fma_f32 v16, v20, s96, v18
	v_fma_f32 v17, v21, s96, v18
	s_nop 0
	v_max3_f32 v20, v24, v16, v17
	v_fma_f32 v19, v23, s96, v18
	v_fma_f32 v18, v22, s96, v18
	s_nop 0
	v_max3_f32 v28, v20, v18, v19

; DI void cmp_item(const Params& p, int it, unsigned char* smem) {
;     ...
;       if ((s0 + wave * 16) - (mt * 256 + 271) >= 113) {
;         const float bf = bt[hh * 128 + 127];
; #pragma unroll
;         for (int j = 0; j < 4; ++j) { const float s2 = s[j] * sc2 + bf; s[j] = s2; mx = fmaxf(mx, s2); }
.LBB0_582:
	s_andn2_saveexec_b64 vcc, vcc
	s_cbranch_execz .LBB0_584
	s_nop 0
	v_mov_b32_e32 v20, s97
	ds_read_b32 v22, v20 offset:41468
	s_waitcnt lgkmcnt(0)
	v_fma_f32 v20, v24, s96, v22
	v_fma_f32 v21, v25, s96, v22
	s_nop 0
	v_max3_f32 v24, v28, v20, v21
	v_fma_f32 v23, v27, s96, v22
	v_fma_f32 v22, v26, s96, v22
	s_nop 0
	v_max3_f32 v32, v24, v22, v23

; DI void cmp_item(const Params& p, int it, unsigned char* smem) {
;     ...
;       if ((s0 + wave * 16) - (mt * 256 + 271) >= 113) {
;         const float bf = bt[hh * 128 + 127];
; #pragma unroll
;         for (int j = 0; j < 4; ++j) { const float s2 = s[j] * sc2 + bf; s[j] = s2; mx = fmaxf(mx, s2); }
.LBB0_594:
	s_andn2_saveexec_b64 vcc, vcc
	s_cbranch_execz .LBB0_596
	s_nop 0
	v_mov_b32_e32 v24, s97
	ds_read_b32 v26, v24 offset:41468
	s_waitcnt lgkmcnt(0)
	v_fma_f32 v24, v28, s96, v26
	v_fma_f32 v25, v29, s96, v26
	s_nop 0
	v_max3_f32 v28, v32, v24, v25
	v_fma_f32 v27, v31, s96, v26
	v_fma_f32 v26, v30, s96, v26
	s_nop 0
	v_max3_f32 v36, v28, v26, v27

; DI void cmp_item(const Params& p, int it, unsigned char* smem) {
;     ...
;       if ((s0 + wave * 16) - (mt * 256 + 271) >= 113) {
;         const float bf = bt[hh * 128 + 127];
; #pragma unroll
;         for (int j = 0; j < 4; ++j) { const float s2 = s[j] * sc2 + bf; s[j] = s2; mx = fmaxf(mx, s2); }
.LBB0_606:
	s_andn2_saveexec_b64 vcc, vcc
	s_cbranch_execz .LBB0_608
	s_nop 0
	v_mov_b32_e32 v28, s97
	ds_read_b32 v30, v28 offset:41468
	s_waitcnt lgkmcnt(0)
	v_fma_f32 v28, v32, s96, v30
	v_fma_f32 v29, v33, s96, v30
	s_nop 0
	v_max3_f32 v32, v36, v28, v29
	v_fma_f32 v31, v35, s96, v30
	v_fma_f32 v30, v34, s96, v30
	s_nop 0
	v_max3_f32 v135, v32, v30, v31

; DI void cmp_item(const Params& p, int it, unsigned char* smem) {
;     ...
;       if ((s0 + wave * 16) - (mt * 256 + 271) >= 113) {
;         const float bf = bt[hh * 128 + 127];
; #pragma unroll
;         for (int j = 0; j < 4; ++j) { const float s2 = s[j] * sc2 + bf; s[j] = s2; mx = fmaxf(mx, s2); }
.LBB0_618:
	s_andn2_saveexec_b64 vcc, vcc
	s_cbranch_execz .LBB0_620
	s_nop 0
	v_mov_b32_e32 v32, s97
	ds_read_b32 v34, v32 offset:41468
	s_waitcnt lgkmcnt(0)
	v_fma_f32 v32, v36, s96, v34
	v_fma_f32 v33, v37, s96, v34
	s_nop 0
	v_max3_f32 v36, v135, v32, v33
	v_fma_f32 v35, v39, s96, v34
	v_fma_f32 v34, v38, s96, v34
	s_nop 0
	v_max3_f32 v134, v36, v34, v35

; DI void cmp_item(const Params& p, int it, unsigned char* smem) {
;     ...
;       if ((s0 + wave * 16) - (mt * 256 + 271) >= 113) {
;         const float bf = bt[hh * 128 + 127];
; #pragma unroll
;         for (int j = 0; j < 4; ++j) { const float s2 = s[j] * sc2 + bf; s[j] = s2; mx = fmaxf(mx, s2); }
;     ...
;   float own[8];
;   {
;     float up[8];
; #pragma unroll
;     for (int mt = 0; mt < 8; ++mt) up[mt] = __shfl(Ps[mt][3], (lane + 48) & 63);
; #pragma unroll
;     for (int mt = 0; mt < 8; ++mt) {
;       const float prev = (lq >= 1) ? up[mt] : (mt >= 1 ? up[mt >= 1 ? mt - 1 : 0] : 0.f);
;       own[mt] = Ps[mt][0] + Ps[mt][1] + Ps[mt][2] + 0.5f * Ps[mt][3] + 0.5f * prev;
;     }
;   }
;   const int cur = tq >> 6;
;   float* myrow = scb + (wave * 16 + lr) * 33;
; #pragma unroll
;   for (int mt = 0; mt < 8; ++mt) {
;     const int jb = 4 * mt + lq;
;     float v = own[mt];
;     if (jb == 0 || jb == cur || jb == cur - 1) v = INFINITY; else if (jb > cur) v = -INFINITY;
;     own[mt] = v; myrow[jb] = v;
;   }
;   __syncthreads();
.LBB0_630:
	s_andn2_saveexec_b64 vcc, vcc
	s_cbranch_execz .LBB0_535
	v_mov_b32_e32 v8, s97
	ds_read_b32 v10, v8 offset:41468
	s_waitcnt lgkmcnt(0)
	v_fma_f32 v8, v12, s96, v10
	v_fma_f32 v9, v13, s96, v10
	s_nop 0
	v_max3_f32 v12, v134, v8, v9
	v_fma_f32 v11, v15, s96, v10
	v_fma_f32 v10, v14, s96, v10
	s_nop 0
	v_max3_f32 v36, v12, v10, v11
	s_branch .LBB0_535
.LBB0_632:
	v_add_u32_e32 v0, 48, v44
	v_and_b32_e32 v0, 63, v0
	v_and_or_b32 v0, v85, 64, v0
	v_lshlrev_b32_e32 v0, 2, v0
	ds_bpermute_b32 v24, v0, v69
	ds_bpermute_b32 v8, v0, v75
	ds_bpermute_b32 v10, v0, v77
	v_mov_b32_e32 v12, v80
	v_mov_b32_e32 v13, v78
	v_mov_b32_e32 v78, v81
	v_add_f32_e64 v12, v12, v78
	v_add_f32_e64 v13, v13, v79
	v_mov_b32_e32 v14, v76
	v_mov_b32_e32 v15, v74
	v_cmp_gt_u32_e32 vcc, 16, v94
	v_add_f32_e64 v12, v14, v12
	v_add_f32_e64 v13, v15, v13
	v_mov_b32_e32 v74, v77
	s_waitcnt lgkmcnt(1)
	v_cndmask_b32_e32 v11, v8, v24, vcc
	s_waitcnt lgkmcnt(0)
	v_cndmask_b32_e32 v10, v10, v8, vcc
	v_fma_f32 v12, v74, 0.5, v12
	v_fma_f32 v13, v75, 0.5, v13
	ds_bpermute_b32 v7, v0, v53
	v_fma_f32 v14, v10, 0.5, v12
	v_fma_f32 v15, v11, 0.5, v13
	v_mov_b32_e32 v10, v72
	v_mov_b32_e32 v11, v70
	v_mov_b32_e32 v70, v73
	v_add_f32_e64 v10, v10, v70
	v_add_f32_e64 v11, v11, v71
	v_mov_b32_e32 v12, v68
	v_mov_b32_e32 v13, v66
	ds_bpermute_b32 v20, v0, v55
	v_add_f32_e64 v10, v12, v10
	v_add_f32_e64 v11, v13, v11
	v_mov_b32_e32 v66, v69
	v_fma_f32 v12, v66, 0.5, v10
	v_fma_f32 v13, v67, 0.5, v11
	v_mov_b32_e32 v10, v64
	v_mov_b32_e32 v11, v62
	v_mov_b32_e32 v62, v65
	v_add_f32_e64 v10, v10, v62
	v_add_f32_e64 v11, v11, v63
	v_mov_b32_e32 v16, v60
	v_mov_b32_e32 v17, v58
	ds_bpermute_b32 v21, v0, v59
	ds_bpermute_b32 v22, v0, v61
	v_add_f32_e64 v10, v16, v10
	v_add_f32_e64 v11, v17, v11
	v_mov_b32_e32 v16, v56
	v_mov_b32_e32 v17, v50
	v_mov_b32_e32 v50, v57
	ds_bpermute_b32 v23, v0, v67
	s_waitcnt lgkmcnt(4)
	v_mul_f32_e32 v0, 0.5, v7
	v_add_f32_e64 v16, v16, v50
	v_add_f32_e64 v17, v17, v51
	v_mov_b32_e32 v18, v54
	v_mov_b32_e32 v19, v52
	v_cndmask_b32_e64 v9, v0, 0, vcc
	v_ashrrev_i32_e32 v25, 6, v96
	v_or_b32_e32 v0, v95, v92
	s_movk_i32 s0, 0x84
	s_waitcnt lgkmcnt(3)
	v_cndmask_b32_e32 v7, v20, v7, vcc
	v_add_f32_e64 v16, v18, v16
	v_add_f32_e64 v17, v19, v17
	v_mov_b32_e32 v52, v55
	v_mul_lo_u32 v26, v0, s0
	v_add_u32_e32 v27, -1, v25
	v_or_b32_e32 v0, 4, v45
	v_mul_f32_e32 v8, 0.5, v7
	v_fma_f32 v16, v52, 0.5, v16
	v_fma_f32 v17, v53, 0.5, v17
	v_cmp_eq_u32_e64 s[0:1], v45, v25
	v_cmp_eq_u32_e64 s[4:5], v45, v27
	v_mov_b32_e32 v58, v61
	v_add_f32_e64 v8, v16, v8
	v_add_f32_e64 v9, v17, v9
	v_cmp_le_i32_e64 s[6:7], v0, v25
	s_or_b64 s[8:9], s[0:1], s[4:5]
	v_cmp_eq_u32_e64 s[0:1], v0, v25
	v_cmp_eq_u32_e64 s[4:5], v0, v27
	v_or_b32_e32 v2, 12, v45
	v_fma_f32 v10, v58, 0.5, v10
	v_fma_f32 v11, v59, 0.5, v11
	v_cndmask_b32_e64 v8, v89, v8, s[6:7]
	v_cmp_le_i32_e64 s[6:7], v45, v25
	s_waitcnt lgkmcnt(2)
	v_cndmask_b32_e32 v17, v21, v20, vcc
	s_waitcnt lgkmcnt(1)
	v_cndmask_b32_e32 v16, v22, v21, vcc
	v_lshl_add_u32 v28, v45, 2, v26
	v_or_b32_e32 v1, 8, v45
	v_cndmask_b32_e64 v7, v89, v9, s[6:7]
	s_or_b64 s[6:7], vcc, s[8:9]
	s_or_b64 s[0:1], s[0:1], s[4:5]
	v_fma_f32 v10, v16, 0.5, v10
	v_fma_f32 v11, v17, 0.5, v11
	v_cmp_le_i32_e64 s[10:11], v2, v25
	v_cndmask_b32_e64 v7, v7, v90, s[6:7]
	v_cndmask_b32_e64 v8, v8, v90, s[0:1]
	v_add_u32_e32 v9, 0xa800, v28
	v_cmp_eq_u32_e64 s[0:1], v1, v25
	v_cmp_eq_u32_e64 s[6:7], v1, v27
	v_cndmask_b32_e64 v10, v89, v10, s[10:11]
	v_cmp_le_i32_e64 s[10:11], v1, v25
	v_or_b32_e32 v4, 20, v45
	ds_write2_b32 v9, v7, v8 offset1:4
	v_cmp_eq_u32_e64 s[4:5], v2, v25
	v_cmp_eq_u32_e64 s[8:9], v2, v27
	v_cndmask_b32_e64 v9, v89, v11, s[10:11]
	s_or_b64 s[0:1], s[0:1], s[6:7]
	s_waitcnt lgkmcnt(1)
	v_cndmask_b32_e32 v17, v23, v22, vcc
	v_cndmask_b32_e32 v16, v24, v23, vcc
	v_or_b32_e32 v3, 16, v45
	v_cndmask_b32_e64 v9, v9, v90, s[0:1]
	s_or_b64 s[0:1], s[4:5], s[8:9]
	v_fma_f32 v12, v16, 0.5, v12
	v_fma_f32 v13, v17, 0.5, v13
	v_cmp_le_i32_e64 s[10:11], v4, v25
	v_cndmask_b32_e64 v10, v10, v90, s[0:1]
	v_cmp_eq_u32_e64 s[0:1], v3, v25
	v_cmp_eq_u32_e64 s[6:7], v3, v27
	v_cndmask_b32_e64 v12, v89, v12, s[10:11]
	v_cmp_le_i32_e64 s[10:11], v3, v25
	v_or_b32_e32 v6, 28, v45
	v_cmp_eq_u32_e64 s[4:5], v4, v25
	v_cmp_eq_u32_e64 s[8:9], v4, v27
	v_cndmask_b32_e64 v11, v89, v13, s[10:11]
	s_or_b64 s[0:1], s[0:1], s[6:7]
	v_or_b32_e32 v5, 24, v45
	v_cndmask_b32_e64 v11, v11, v90, s[0:1]
	s_or_b64 s[0:1], s[4:5], s[8:9]
	v_cmp_le_i32_e64 s[10:11], v6, v25
	v_cndmask_b32_e64 v12, v12, v90, s[0:1]
	v_cmp_eq_u32_e64 s[0:1], v5, v25
	v_cmp_eq_u32_e64 s[6:7], v5, v27
	v_cndmask_b32_e64 v14, v89, v14, s[10:11]
	v_cmp_le_i32_e64 s[10:11], v5, v25
	v_cmp_eq_u32_e64 s[4:5], v6, v25
	v_cmp_eq_u32_e64 s[8:9], v6, v27
	v_cndmask_b32_e64 v13, v89, v15, s[10:11]
	s_or_b64 s[0:1], s[0:1], s[6:7]
	v_cndmask_b32_e64 v13, v13, v90, s[0:1]
	s_or_b64 s[0:1], s[4:5], s[8:9]
	v_lshl_add_u32 v29, v1, 2, v26
	v_lshl_add_u32 v31, v3, 2, v26
	v_cndmask_b32_e64 v14, v14, v90, s[0:1]
	v_lshl_add_u32 v15, v6, 2, v26
	v_lshl_add_u32 v30, v2, 2, v26
	v_lshl_add_u32 v32, v4, 2, v26
	ds_write_b32 v29, v9 offset:43008
	ds_write_b32 v30, v10 offset:43008
	ds_write_b32 v31, v11 offset:43008
	ds_write_b32 v32, v12 offset:43008
	ds_write_b32 v15, v14 offset:43008
	v_lshrrev_b32_e32 v15, 4, v93
	s_movk_i32 s0, 0x840
	v_mul_lo_u32 v15, v15, s0
	v_mul_u32_u24_e32 v16, 0x84, v92
	s_mov_b32 s0, 0xa800
	v_lshl_add_u32 v33, v5, 2, v26
	v_add3_u32 v15, v15, v16, s0
	s_mov_b32 s14, 0
	v_mov_b32_e32 v16, 0
	v_mov_b32_e32 v17, 0
	v_mov_b32_e32 v18, 0
	v_mov_b32_e32 v19, 0
	v_mov_b32_e32 v20, 0
	v_mov_b32_e32 v21, 0
	v_mov_b32_e32 v22, 0
	v_mov_b32_e32 v23, 0
	ds_write_b32 v33, v13 offset:43008
	s_waitcnt lgkmcnt(0)
	s_barrier

; DI float sigmoidf_(float x) { return 1.0f / (1.0f + __expf(-x)); }
; DI void store4(u16* dst, f32x4 v) { uint2 w; w.x = cvtpk(v[0], v[1]); w.y = cvtpk(v[2], v[3]); *(uint2*)dst = w; }
; DI f32x4 load4bf(const u16* src) { uint2 w = *(const uint2*)src; return (f32x4){bflo(w.x), bfhi(w.x), bflo(w.y), bfhi(w.y)}; }
; DI void selwin_item(const Params& p, int it, unsigned char* smem, u16* y_out) {
;     ...
;   const u16* ma = (const u16*)(p.ws + OFF_MA); const u16* mbp = (const u16*)(p.ws + OFF_MB); const u16* ab = (const u16*)(p.ws + OFF_HBUF);
; #pragma unroll
;   for (int nt = 0; nt < 2; ++nt) {
;     const size_t t = tb0 + s0 + nt * 16 + lr;
; #pragma unroll
;     for (int dt = 0; dt < 4; ++dt) {
;       const size_t idx = t * 1024 + h * 64 + dt * 16 + lq * 4;
;       const f32x4 a = load4bf(ab + idx), mav = load4bf(ma + idx), mbv = load4bf(mbp + idx);
;       f32x4 y;
; #pragma unroll
;       for (int j = 0; j < 4; ++j) y[j] = sigmoidf_(mav[j]) * (a[j] + Ores[dt][nt][j]) + mbv[j];
;       { const int col = h * 64 + dt * 16 + lq * 4; store4(y_out + ((size_t)(col >> 5) * Tn + t) * 32 + (col & 31), y); }
;     }
;   }
.LBB0_691:
	v_or_b32_e32 v136, v136, v151
	v_lshlrev_b64 v[0:1], 10, v[152:153]
	v_lshl_add_u64 v[0:1], v[0:1], 0, v[136:137]
	v_readlane_b32 s8, v245, 25
	v_lshlrev_b64 v[4:5], 1, v[0:1]
	v_readlane_b32 s9, v245, 26
	v_lshlrev_b64 v[2:3], 6, v[152:153]
	v_lshl_add_u64 v[6:7], s[16:17], 0, v[2:3]
	v_lshl_add_u64 v[0:1], s[8:9], 0, v[4:5]
	global_load_dwordx2 v[10:11], v[0:1], off
	v_lshl_add_u64 v[0:1], s[22:23], 0, v[4:5]
	global_load_dwordx2 v[12:13], v[0:1], off
	v_lshl_add_u64 v[0:1], s[2:3], 0, v[4:5]
	global_load_dwordx2 v[14:15], v[0:1], off
	v_lshlrev_b32_e32 v0, 1, v150
	v_ashrrev_i32_e32 v1, 31, v0
	v_lshlrev_b64 v[2:3], 22, v[0:1]
	v_add_f32_e64 v16, v160, v78
	v_add_f32_e64 v17, v161, v79
	v_add_f32_e64 v18, v162, v76
	v_add_f32_e64 v19, v163, v77
	v_lshlrev_b32_e32 v120, 1, v151
	v_lshl_add_u64 v[8:9], v[6:7], 0, v[2:3]
	v_or_b32_e32 v20, 32, v4
	v_mov_b32_e32 v21, v5
	v_lshl_add_u64 v[8:9], v[8:9], 0, v[120:121]
	v_lshl_add_u64 v[22:23], s[8:9], 0, v[20:21]
	v_or_b32_e32 v0, 1, v0
	s_add_i32 s58, s58, s92
	s_cmpk_lt_i32 s58, 0x2000
	s_waitcnt vmcnt(2)
	v_lshlrev_b32_e32 v24, 16, v10
	v_and_b32_e32 v25, 0xffff0000, v10
	s_waitcnt vmcnt(1)
	v_lshlrev_b32_e32 v1, 16, v12
	v_and_b32_e32 v26, 0xffff0000, v12
	v_lshlrev_b32_e32 v27, 16, v13
	v_mul_f32_e32 v1, 0xbfb8aa3b, v1
	v_mul_f32_e32 v29, 0xbfb8aa3b, v26
	v_and_b32_e32 v28, 0xffff0000, v13
	v_mul_f32_e32 v30, 0xbfb8aa3b, v27
	v_exp_f32_e32 v26, v1
	v_exp_f32_e32 v27, v29
	v_mul_f32_e32 v31, 0xbfb8aa3b, v28
	v_exp_f32_e32 v28, v30
	v_exp_f32_e32 v29, v31
	v_lshlrev_b32_e32 v10, 16, v11
	v_and_b32_e32 v11, 0xffff0000, v11
	v_add_f32_e64 v10, v16, v10
	v_add_f32_e64 v11, v17, v11
	v_add_f32_e64 v16, v26, 1.0
	v_add_f32_e64 v17, v27, 1.0
	v_add_f32_e64 v18, v18, v24
	v_add_f32_e64 v19, v19, v25
	v_add_f32_e64 v24, v28, 1.0
	v_add_f32_e64 v25, v29, 1.0
	s_mov_b64 vcc, s[0:1]
	v_rcp_f32_e32 v17, v17
	s_mov_b64 vcc, s[4:5]
	s_waitcnt vmcnt(0)
	v_lshlrev_b32_e32 v12, 16, v14
	v_and_b32_e32 v13, 0xffff0000, v14
	v_rcp_f32_e32 v16, v16
	s_mov_b64 vcc, s[6:7]
	v_fma_f32 v12, v18, v16, v12
	v_fma_f32 v13, v19, v17, v13
	v_rcp_f32_e32 v17, v25
	v_lshlrev_b32_e32 v14, 16, v15
	v_and_b32_e32 v15, 0xffff0000, v15
	v_rcp_f32_e32 v16, v24
	s_nop 0
	v_fma_f32 v10, v10, v16, v14
	v_fma_f32 v11, v11, v17, v15
	v_cvt_pk_bf16_f32 v12, v12, v13
	v_cvt_pk_bf16_f32 v13, v10, v11
	global_store_dwordx2 v[8:9], v[12:13], off
	v_lshl_add_u64 v[12:13], s[22:23], 0, v[20:21]
	global_load_dwordx2 v[12:13], v[12:13], off
	v_lshl_add_u64 v[14:15], s[2:3], 0, v[20:21]
	global_load_dwordx2 v[10:11], v[22:23], off
	v_add_f32_e64 v16, v154, v74
	v_add_f32_e64 v17, v155, v75
	global_load_dwordx2 v[14:15], v[14:15], off
	v_add_f32_e64 v18, v156, v72
	v_add_f32_e64 v19, v157, v73
	v_or_b32_e32 v20, 64, v4
	v_lshl_add_u64 v[22:23], s[8:9], 0, v[20:21]
	v_or_b32_e32 v4, 0x60, v4
	s_waitcnt vmcnt(2)
	v_lshlrev_b32_e32 v1, 16, v12
	v_and_b32_e32 v26, 0xffff0000, v12
	v_lshlrev_b32_e32 v27, 16, v13
	v_mul_f32_e32 v1, 0xbfb8aa3b, v1
	v_mul_f32_e32 v29, 0xbfb8aa3b, v26
	v_and_b32_e32 v28, 0xffff0000, v13
	v_mul_f32_e32 v30, 0xbfb8aa3b, v27
	v_exp_f32_e32 v26, v1
	v_exp_f32_e32 v27, v29
	v_mul_f32_e32 v31, 0xbfb8aa3b, v28
	v_exp_f32_e32 v28, v30
	v_exp_f32_e32 v29, v31
	s_waitcnt vmcnt(1)
	v_lshlrev_b32_e32 v24, 16, v10
	v_and_b32_e32 v25, 0xffff0000, v10
	v_lshlrev_b32_e32 v10, 16, v11
	v_and_b32_e32 v11, 0xffff0000, v11
	v_add_f32_e64 v10, v16, v10
	v_add_f32_e64 v11, v17, v11
	v_add_f32_e64 v16, v26, 1.0
	v_add_f32_e64 v17, v27, 1.0
	v_add_f32_e64 v18, v18, v24
	v_add_f32_e64 v19, v19, v25
	v_add_f32_e64 v24, v28, 1.0
	v_add_f32_e64 v25, v29, 1.0
	s_mov_b64 vcc, s[0:1]
	v_rcp_f32_e32 v17, v17
	s_mov_b64 vcc, s[4:5]
	s_waitcnt vmcnt(0)
	v_lshlrev_b32_e32 v12, 16, v14
	v_and_b32_e32 v13, 0xffff0000, v14
	v_rcp_f32_e32 v16, v16
	s_mov_b64 vcc, s[6:7]
	v_fma_f32 v12, v18, v16, v12
	v_fma_f32 v13, v19, v17, v13
	v_rcp_f32_e32 v17, v25
	v_lshlrev_b32_e32 v14, 16, v15
	v_and_b32_e32 v15, 0xffff0000, v15
	v_rcp_f32_e32 v16, v24
	s_nop 0
	v_fma_f32 v10, v10, v16, v14
	v_fma_f32 v11, v11, v17, v15
	v_cvt_pk_bf16_f32 v12, v12, v13
	v_cvt_pk_bf16_f32 v13, v10, v11
	global_store_dwordx2 v[8:9], v[12:13], off offset:32
	v_lshl_add_u64 v[10:11], s[22:23], 0, v[20:21]
	global_load_dwordx2 v[10:11], v[10:11], off
	v_lshl_add_u64 v[12:13], s[2:3], 0, v[20:21]
	global_load_dwordx2 v[8:9], v[22:23], off
	v_add_f32_e64 v14, v146, v70
	v_add_f32_e64 v15, v147, v71
	global_load_dwordx2 v[12:13], v[12:13], off
	v_add_f32_e64 v16, v148, v68
	v_add_f32_e64 v17, v149, v69
	v_ashrrev_i32_e32 v1, 31, v0
	v_lshlrev_b64 v[0:1], 22, v[0:1]
	v_lshl_add_u64 v[6:7], v[6:7], 0, v[0:1]
	v_lshl_add_u64 v[6:7], v[6:7], 0, v[120:121]
	v_lshl_add_u64 v[18:19], s[8:9], 0, v[4:5]
	s_waitcnt vmcnt(2)
	v_lshlrev_b32_e32 v22, 16, v10
	v_and_b32_e32 v23, 0xffff0000, v10
	v_mul_f32_e32 v22, 0xbfb8aa3b, v22
	v_mul_f32_e32 v23, 0xbfb8aa3b, v23
	v_lshlrev_b32_e32 v24, 16, v11
	v_and_b32_e32 v25, 0xffff0000, v11
	v_exp_f32_e32 v22, v22
	v_exp_f32_e32 v23, v23
	v_mul_f32_e32 v24, 0xbfb8aa3b, v24
	v_mul_f32_e32 v25, 0xbfb8aa3b, v25
	v_exp_f32_e32 v24, v24
	v_exp_f32_e32 v25, v25
	s_waitcnt vmcnt(1)
	v_lshlrev_b32_e32 v20, 16, v8
	v_and_b32_e32 v21, 0xffff0000, v8
	v_lshlrev_b32_e32 v8, 16, v9
	v_and_b32_e32 v9, 0xffff0000, v9
	v_add_f32_e64 v8, v14, v8
	v_add_f32_e64 v9, v15, v9
	v_add_f32_e64 v14, v22, 1.0
	v_add_f32_e64 v15, v23, 1.0
	v_add_f32_e64 v16, v16, v20
	v_add_f32_e64 v17, v17, v21
	v_add_f32_e64 v20, v24, 1.0
	v_add_f32_e64 v21, v25, 1.0
	s_mov_b64 vcc, s[0:1]
	v_rcp_f32_e32 v15, v15
	s_mov_b64 vcc, s[4:5]
	s_waitcnt vmcnt(0)
; DI float sigmoidf_(float x) { return 1.0f / (1.0f + __expf(-x)); }
; DI void store4(u16* dst, f32x4 v) { uint2 w; w.x = cvtpk(v[0], v[1]); w.y = cvtpk(v[2], v[3]); *(uint2*)dst = w; }
; DI f32x4 load4bf(const u16* src) { uint2 w = *(const uint2*)src; return (f32x4){bflo(w.x), bfhi(w.x), bflo(w.y), bfhi(w.y)}; }
; DI void selwin_item(const Params& p, int it, unsigned char* smem, u16* y_out) {
;     ...
;   const u16* ma = (const u16*)(p.ws + OFF_MA); const u16* mbp = (const u16*)(p.ws + OFF_MB); const u16* ab = (const u16*)(p.ws + OFF_HBUF);
; #pragma unroll
;   for (int nt = 0; nt < 2; ++nt) {
;     const size_t t = tb0 + s0 + nt * 16 + lr;
; #pragma unroll
;     for (int dt = 0; dt < 4; ++dt) {
;       const size_t idx = t * 1024 + h * 64 + dt * 16 + lq * 4;
;       const f32x4 a = load4bf(ab + idx), mav = load4bf(ma + idx), mbv = load4bf(mbp + idx);
;       f32x4 y;
; #pragma unroll
;       for (int j = 0; j < 4; ++j) y[j] = sigmoidf_(mav[j]) * (a[j] + Ores[dt][nt][j]) + mbv[j];
;       { const int col = h * 64 + dt * 16 + lq * 4; store4(y_out + ((size_t)(col >> 5) * Tn + t) * 32 + (col & 31), y); }
;     }
;   }
	v_lshlrev_b32_e32 v10, 16, v12
	v_and_b32_e32 v11, 0xffff0000, v12
	v_rcp_f32_e32 v14, v14
	s_mov_b64 vcc, s[6:7]
	v_fma_f32 v10, v16, v14, v10
	v_fma_f32 v11, v17, v15, v11
	v_lshlrev_b32_e32 v12, 16, v13
	v_and_b32_e32 v13, 0xffff0000, v13
	v_rcp_f32_e32 v15, v21
	v_rcp_f32_e32 v14, v20
	s_nop 0
	v_fma_f32 v8, v8, v14, v12
	v_fma_f32 v9, v9, v15, v13
	v_cvt_pk_bf16_f32 v10, v10, v11
	v_cvt_pk_bf16_f32 v11, v8, v9
	global_store_dwordx2 v[6:7], v[10:11], off
	v_lshl_add_u64 v[10:11], s[22:23], 0, v[4:5]
	global_load_dwordx2 v[10:11], v[10:11], off
	v_lshl_add_u64 v[4:5], s[2:3], 0, v[4:5]
	global_load_dwordx2 v[8:9], v[18:19], off
	global_load_dwordx2 v[12:13], v[4:5], off
	v_add_f32_e64 v14, v142, v66
	v_add_f32_e64 v15, v143, v67
	v_add_f32_e64 v16, v144, v64
	v_add_f32_e64 v17, v145, v65
	v_lshlrev_b64 v[4:5], 10, v[130:131]
	v_lshl_add_u64 v[4:5], v[4:5], 0, v[136:137]
	v_lshlrev_b64 v[4:5], 1, v[4:5]
	v_lshl_add_u64 v[18:19], s[8:9], 0, v[4:5]
	s_waitcnt vmcnt(2)
	v_lshlrev_b32_e32 v22, 16, v10
	v_and_b32_e32 v23, 0xffff0000, v10
	v_mul_f32_e32 v22, 0xbfb8aa3b, v22
	v_mul_f32_e32 v23, 0xbfb8aa3b, v23
	v_lshlrev_b32_e32 v24, 16, v11
	v_and_b32_e32 v25, 0xffff0000, v11
	v_exp_f32_e32 v22, v22
	v_exp_f32_e32 v23, v23
	v_mul_f32_e32 v24, 0xbfb8aa3b, v24
	v_mul_f32_e32 v25, 0xbfb8aa3b, v25
	v_exp_f32_e32 v24, v24
	v_exp_f32_e32 v25, v25
	s_waitcnt vmcnt(1)
	v_lshlrev_b32_e32 v20, 16, v8
	v_and_b32_e32 v21, 0xffff0000, v8
	v_lshlrev_b32_e32 v8, 16, v9
	v_and_b32_e32 v9, 0xffff0000, v9
	v_add_f32_e64 v8, v14, v8
	v_add_f32_e64 v9, v15, v9
	v_add_f32_e64 v14, v22, 1.0
	v_add_f32_e64 v15, v23, 1.0
	v_add_f32_e64 v16, v16, v20
	v_add_f32_e64 v17, v17, v21
	v_add_f32_e64 v20, v24, 1.0
	v_add_f32_e64 v21, v25, 1.0
	s_mov_b64 vcc, s[0:1]
	v_rcp_f32_e32 v15, v15
	s_mov_b64 vcc, s[4:5]
	s_waitcnt vmcnt(0)
	v_lshlrev_b32_e32 v10, 16, v12
	v_and_b32_e32 v11, 0xffff0000, v12
	v_rcp_f32_e32 v14, v14
	s_mov_b64 vcc, s[6:7]
	v_fma_f32 v10, v16, v14, v10
	v_fma_f32 v11, v17, v15, v11
	v_lshlrev_b32_e32 v12, 16, v13
	v_and_b32_e32 v13, 0xffff0000, v13
	v_rcp_f32_e32 v15, v21
	v_rcp_f32_e32 v14, v20
	s_nop 0
	v_fma_f32 v8, v8, v14, v12
	v_fma_f32 v9, v9, v15, v13
	v_cvt_pk_bf16_f32 v10, v10, v11
	v_cvt_pk_bf16_f32 v11, v8, v9
	global_store_dwordx2 v[6:7], v[10:11], off offset:32
	v_lshl_add_u64 v[6:7], s[22:23], 0, v[4:5]
	global_load_dwordx2 v[10:11], v[6:7], off
	global_load_dwordx2 v[8:9], v[18:19], off
	v_lshl_add_u64 v[6:7], s[2:3], 0, v[4:5]
	global_load_dwordx2 v[12:13], v[6:7], off
	v_add_f32_e64 v14, v138, v62
	v_add_f32_e64 v15, v139, v63
	v_add_f32_e64 v16, v140, v60
	v_add_f32_e64 v17, v141, v61
	v_lshlrev_b64 v[6:7], 6, v[130:131]
	v_lshl_add_u64 v[6:7], s[16:17], 0, v[6:7]
	v_lshl_add_u64 v[2:3], v[6:7], 0, v[2:3]
	v_or_b32_e32 v18, 32, v4
	v_mov_b32_e32 v19, v5
	v_lshl_add_u64 v[2:3], v[2:3], 0, v[120:121]
	v_lshl_add_u64 v[20:21], s[8:9], 0, v[18:19]
	v_lshl_add_u64 v[0:1], v[6:7], 0, v[0:1]
	v_lshl_add_u64 v[0:1], v[0:1], 0, v[120:121]
	s_waitcnt vmcnt(2)
	v_lshlrev_b32_e32 v24, 16, v10
	v_and_b32_e32 v25, 0xffff0000, v10
	v_mul_f32_e32 v24, 0xbfb8aa3b, v24
	v_mul_f32_e32 v25, 0xbfb8aa3b, v25
	v_lshlrev_b32_e32 v26, 16, v11
	v_and_b32_e32 v27, 0xffff0000, v11
	v_exp_f32_e32 v24, v24
	v_exp_f32_e32 v25, v25
	v_mul_f32_e32 v26, 0xbfb8aa3b, v26
	v_mul_f32_e32 v27, 0xbfb8aa3b, v27
	v_exp_f32_e32 v26, v26
	v_exp_f32_e32 v27, v27
	s_waitcnt vmcnt(1)
	v_lshlrev_b32_e32 v22, 16, v8
	v_and_b32_e32 v23, 0xffff0000, v8
	v_lshlrev_b32_e32 v8, 16, v9
	v_and_b32_e32 v9, 0xffff0000, v9
	v_add_f32_e64 v8, v14, v8
	v_add_f32_e64 v9, v15, v9
	v_add_f32_e64 v14, v24, 1.0
	v_add_f32_e64 v15, v25, 1.0
	v_add_f32_e64 v16, v16, v22
	v_add_f32_e64 v17, v17, v23
	v_add_f32_e64 v22, v26, 1.0
	v_add_f32_e64 v23, v27, 1.0
	s_mov_b64 vcc, s[0:1]
	v_rcp_f32_e32 v15, v15
	s_mov_b64 vcc, s[4:5]
	s_waitcnt vmcnt(0)
	v_lshlrev_b32_e32 v10, 16, v12
	v_and_b32_e32 v11, 0xffff0000, v12
	v_rcp_f32_e32 v14, v14
	s_mov_b64 vcc, s[6:7]
	v_fma_f32 v10, v16, v14, v10
	v_fma_f32 v11, v17, v15, v11
	v_lshlrev_b32_e32 v12, 16, v13
	v_and_b32_e32 v13, 0xffff0000, v13
	v_rcp_f32_e32 v15, v23
	v_rcp_f32_e32 v14, v22
	s_nop 0
	v_fma_f32 v8, v8, v14, v12
	v_fma_f32 v9, v9, v15, v13
	v_cvt_pk_bf16_f32 v10, v10, v11
	v_cvt_pk_bf16_f32 v11, v8, v9
	global_store_dwordx2 v[2:3], v[10:11], off
	v_lshl_add_u64 v[10:11], s[22:23], 0, v[18:19]
	global_load_dwordx2 v[10:11], v[10:11], off
	v_lshl_add_u64 v[12:13], s[2:3], 0, v[18:19]
	global_load_dwordx2 v[8:9], v[20:21], off
	v_add_f32_e64 v14, v132, v58
	v_add_f32_e64 v15, v133, v59
	global_load_dwordx2 v[12:13], v[12:13], off
	v_add_f32_e64 v16, v134, v56
	v_add_f32_e64 v17, v135, v57
	v_or_b32_e32 v18, 64, v4
	v_lshl_add_u64 v[20:21], s[8:9], 0, v[18:19]
	v_or_b32_e32 v4, 0x60, v4
	v_lshl_add_u64 v[6:7], s[8:9], 0, v[4:5]
	s_waitcnt vmcnt(2)
; DI float sigmoidf_(float x) { return 1.0f / (1.0f + __expf(-x)); }
; DI void store4(u16* dst, f32x4 v) { uint2 w; w.x = cvtpk(v[0], v[1]); w.y = cvtpk(v[2], v[3]); *(uint2*)dst = w; }
; DI f32x4 load4bf(const u16* src) { uint2 w = *(const uint2*)src; return (f32x4){bflo(w.x), bfhi(w.x), bflo(w.y), bfhi(w.y)}; }
; DI void selwin_item(const Params& p, int it, unsigned char* smem, u16* y_out) {
;     ...
;   const u16* ma = (const u16*)(p.ws + OFF_MA); const u16* mbp = (const u16*)(p.ws + OFF_MB); const u16* ab = (const u16*)(p.ws + OFF_HBUF);
; #pragma unroll
;   for (int nt = 0; nt < 2; ++nt) {
;     const size_t t = tb0 + s0 + nt * 16 + lr;
; #pragma unroll
;     for (int dt = 0; dt < 4; ++dt) {
;       const size_t idx = t * 1024 + h * 64 + dt * 16 + lq * 4;
;       const f32x4 a = load4bf(ab + idx), mav = load4bf(ma + idx), mbv = load4bf(mbp + idx);
;       f32x4 y;
; #pragma unroll
;       for (int j = 0; j < 4; ++j) y[j] = sigmoidf_(mav[j]) * (a[j] + Ores[dt][nt][j]) + mbv[j];
;       { const int col = h * 64 + dt * 16 + lq * 4; store4(y_out + ((size_t)(col >> 5) * Tn + t) * 32 + (col & 31), y); }
;     }
;   }
	v_lshlrev_b32_e32 v24, 16, v10
	v_and_b32_e32 v25, 0xffff0000, v10
	v_mul_f32_e32 v24, 0xbfb8aa3b, v24
	v_mul_f32_e32 v25, 0xbfb8aa3b, v25
	v_lshlrev_b32_e32 v26, 16, v11
	v_and_b32_e32 v27, 0xffff0000, v11
	v_exp_f32_e32 v24, v24
	v_exp_f32_e32 v25, v25
	v_mul_f32_e32 v26, 0xbfb8aa3b, v26
	v_mul_f32_e32 v27, 0xbfb8aa3b, v27
	v_exp_f32_e32 v26, v26
	v_exp_f32_e32 v27, v27
	s_waitcnt vmcnt(1)
	v_lshlrev_b32_e32 v22, 16, v8
	v_and_b32_e32 v23, 0xffff0000, v8
	v_lshlrev_b32_e32 v8, 16, v9
	v_and_b32_e32 v9, 0xffff0000, v9
	v_add_f32_e64 v8, v14, v8
	v_add_f32_e64 v9, v15, v9
	v_add_f32_e64 v14, v24, 1.0
	v_add_f32_e64 v15, v25, 1.0
	v_add_f32_e64 v16, v16, v22
	v_add_f32_e64 v17, v17, v23
	v_add_f32_e64 v22, v26, 1.0
	v_add_f32_e64 v23, v27, 1.0
	s_mov_b64 vcc, s[0:1]
	v_rcp_f32_e32 v15, v15
	s_mov_b64 vcc, s[4:5]
	s_waitcnt vmcnt(0)
	v_lshlrev_b32_e32 v10, 16, v12
	v_and_b32_e32 v11, 0xffff0000, v12
	v_rcp_f32_e32 v14, v14
	s_mov_b64 vcc, s[6:7]
	v_fma_f32 v10, v16, v14, v10
	v_fma_f32 v11, v17, v15, v11
	v_lshlrev_b32_e32 v12, 16, v13
	v_and_b32_e32 v13, 0xffff0000, v13
	v_rcp_f32_e32 v15, v23
	v_rcp_f32_e32 v14, v22
	s_nop 0
	v_fma_f32 v8, v8, v14, v12
	v_fma_f32 v9, v9, v15, v13
	v_cvt_pk_bf16_f32 v10, v10, v11
	v_cvt_pk_bf16_f32 v11, v8, v9
	global_store_dwordx2 v[2:3], v[10:11], off offset:32
	v_lshl_add_u64 v[8:9], s[22:23], 0, v[18:19]
	global_load_dwordx2 v[8:9], v[8:9], off
	v_lshl_add_u64 v[10:11], s[2:3], 0, v[18:19]
	global_load_dwordx2 v[2:3], v[20:21], off
	v_add_f32_e64 v12, v126, v54
	v_add_f32_e64 v13, v127, v55
	global_load_dwordx2 v[10:11], v[10:11], off
	v_add_f32_e64 v14, v128, v52
	v_add_f32_e64 v15, v129, v53
	s_waitcnt vmcnt(2)
	v_lshlrev_b32_e32 v18, 16, v8
	v_and_b32_e32 v19, 0xffff0000, v8
	v_mul_f32_e32 v18, 0xbfb8aa3b, v18
	v_mul_f32_e32 v19, 0xbfb8aa3b, v19
	v_lshlrev_b32_e32 v20, 16, v9
	v_and_b32_e32 v21, 0xffff0000, v9
	v_exp_f32_e32 v18, v18
	v_exp_f32_e32 v19, v19
	v_mul_f32_e32 v20, 0xbfb8aa3b, v20
	v_mul_f32_e32 v21, 0xbfb8aa3b, v21
	v_exp_f32_e32 v20, v20
	v_exp_f32_e32 v21, v21
	s_waitcnt vmcnt(1)
	v_lshlrev_b32_e32 v16, 16, v2
	v_and_b32_e32 v17, 0xffff0000, v2
	v_lshlrev_b32_e32 v2, 16, v3
	v_and_b32_e32 v3, 0xffff0000, v3
	v_add_f32_e64 v2, v12, v2
	v_add_f32_e64 v3, v13, v3
	v_add_f32_e64 v12, v18, 1.0
	v_add_f32_e64 v13, v19, 1.0
	v_add_f32_e64 v14, v14, v16
	v_add_f32_e64 v15, v15, v17
	v_add_f32_e64 v16, v20, 1.0
	v_add_f32_e64 v17, v21, 1.0
	s_mov_b64 vcc, s[0:1]
	v_rcp_f32_e32 v13, v13
	s_mov_b64 vcc, s[4:5]
	s_waitcnt vmcnt(0)
	v_lshlrev_b32_e32 v8, 16, v10
	v_and_b32_e32 v9, 0xffff0000, v10
	v_rcp_f32_e32 v12, v12
	s_mov_b64 vcc, s[6:7]
	v_fma_f32 v8, v14, v12, v8
	v_fma_f32 v9, v15, v13, v9
	v_lshlrev_b32_e32 v10, 16, v11
	v_and_b32_e32 v11, 0xffff0000, v11
	v_rcp_f32_e32 v13, v17
	v_rcp_f32_e32 v12, v16
	s_nop 0
	v_fma_f32 v2, v2, v12, v10
	v_fma_f32 v3, v3, v13, v11
	v_cvt_pk_bf16_f32 v8, v8, v9
	v_cvt_pk_bf16_f32 v9, v2, v3
	global_store_dwordx2 v[0:1], v[8:9], off
	global_load_dwordx2 v[2:3], v[6:7], off
	v_lshl_add_u64 v[6:7], s[22:23], 0, v[4:5]
	global_load_dwordx2 v[6:7], v[6:7], off
	v_lshl_add_u64 v[4:5], s[2:3], 0, v[4:5]
	global_load_dwordx2 v[4:5], v[4:5], off
	v_add_f32_e64 v8, v122, v50
	v_add_f32_e64 v9, v123, v51
	v_add_f32_e64 v10, v124, v48
	v_add_f32_e64 v11, v125, v49
	s_waitcnt vmcnt(2)
	v_lshlrev_b32_e32 v12, 16, v2
	v_and_b32_e32 v13, 0xffff0000, v2
	s_waitcnt vmcnt(1)
	v_lshlrev_b32_e32 v14, 16, v6
	v_and_b32_e32 v15, 0xffff0000, v6
	v_mul_f32_e32 v14, 0xbfb8aa3b, v14
	v_mul_f32_e32 v15, 0xbfb8aa3b, v15
	v_lshlrev_b32_e32 v16, 16, v7
	v_and_b32_e32 v17, 0xffff0000, v7
	v_exp_f32_e32 v14, v14
	v_exp_f32_e32 v15, v15
	v_mul_f32_e32 v16, 0xbfb8aa3b, v16
	v_mul_f32_e32 v17, 0xbfb8aa3b, v17
	v_exp_f32_e32 v16, v16
	v_exp_f32_e32 v17, v17
	v_lshlrev_b32_e32 v2, 16, v3
	v_and_b32_e32 v3, 0xffff0000, v3
	v_add_f32_e64 v2, v8, v2
	v_add_f32_e64 v3, v9, v3
	v_add_f32_e64 v8, v14, 1.0
	v_add_f32_e64 v9, v15, 1.0
	v_add_f32_e64 v10, v10, v12
	v_add_f32_e64 v11, v11, v13
	v_add_f32_e64 v12, v16, 1.0
	v_add_f32_e64 v13, v17, 1.0
	s_mov_b64 vcc, s[0:1]
	v_rcp_f32_e32 v9, v9
	s_mov_b64 vcc, s[4:5]
	s_waitcnt vmcnt(0)
	v_lshlrev_b32_e32 v6, 16, v4
	v_and_b32_e32 v7, 0xffff0000, v4
	v_rcp_f32_e32 v8, v8
	s_mov_b64 vcc, s[6:7]
	v_fma_f32 v6, v10, v8, v6
	v_fma_f32 v7, v11, v9, v7
	v_lshlrev_b32_e32 v4, 16, v5
	v_and_b32_e32 v5, 0xffff0000, v5
	v_rcp_f32_e32 v9, v13
	v_rcp_f32_e32 v8, v12
	s_nop 0
	v_fma_f32 v2, v2, v8, v4
	v_fma_f32 v3, v3, v9, v5
	v_cvt_pk_bf16_f32 v6, v6, v7
	v_cvt_pk_bf16_f32 v7, v2, v3
	global_store_dwordx2 v[0:1], v[6:7], off offset:32
	s_cbranch_scc0 .LBB0_754

; DI void selwin_item(const Params& p, int it, unsigned char* smem, u16* y_out) {
;     ...
;   __syncthreads();
;   for (int e = tid; e < 512; e += 256) { const int hh = e >> 7, d = e & 127; bt[e] = p.rel[t5_bucket(d) * 16 + g * 4 + hh] * LOG2E; }
.LBB0_696:
	v_ashrrev_i32_e32 v7, 7, v1
	v_add_u32_e32 v9, 0x200, v0
	v_add_u32_e32 v11, 0x200, v1
	v_ashrrev_i32_e32 v8, 7, v0
	v_add_u32_e32 v12, 0x400, v0
	v_add_u32_e32 v13, 0x400, v1
	v_add_u32_e32 v14, 0x600, v0
	v_add_u32_e32 v15, 0x600, v1
	v_add_u32_e32 v10, v2, v7
	v_ashrrev_i32_e32 v7, 7, v11
	v_ashrrev_i32_e32 v17, 7, v9
	v_add_u32_e32 v8, v2, v8
	v_ashrrev_i32_e32 v13, 7, v13
	v_ashrrev_i32_e32 v18, 7, v12
	v_ashrrev_i32_e32 v15, 7, v15
	v_ashrrev_i32_e32 v19, 7, v14
	v_add_u32_e32 v12, v2, v17
	v_add_u32_e32 v14, v2, v7
	v_ashrrev_i32_e32 v11, 31, v10
	v_ashrrev_i32_e32 v9, 31, v8
	v_add_u32_e32 v18, v2, v18
	v_add_u32_e32 v20, v2, v13
	v_add_u32_e32 v22, v2, v19
	v_add_u32_e32 v24, v2, v15
	v_ashrrev_i32_e32 v15, 31, v14
	v_ashrrev_i32_e32 v13, 31, v12
	v_lshl_add_u64 v[8:9], v[8:9], 2, s[82:83]
	v_lshl_add_u64 v[10:11], v[10:11], 2, s[82:83]
	v_ashrrev_i32_e32 v21, 31, v20
	v_ashrrev_i32_e32 v19, 31, v18
	v_ashrrev_i32_e32 v25, 31, v24
	v_ashrrev_i32_e32 v23, 31, v22
	v_lshl_add_u64 v[12:13], v[12:13], 2, s[82:83]
	v_lshl_add_u64 v[14:15], v[14:15], 2, s[82:83]
	v_lshl_add_u64 v[18:19], v[18:19], 2, s[82:83]
	v_lshl_add_u64 v[20:21], v[20:21], 2, s[82:83]
	v_lshl_add_u64 v[22:23], v[22:23], 2, s[82:83]
	v_lshl_add_u64 v[24:25], v[24:25], 2, s[82:83]
	global_load_dword v8, v[8:9], off
	s_nop 0
	global_load_dword v9, v[10:11], off
	s_nop 0
	global_load_dword v10, v[12:13], off
	global_load_dword v11, v[14:15], off
	s_nop 0
	global_load_dword v12, v[18:19], off
	global_load_dword v13, v[20:21], off
	global_load_dword v14, v[22:23], off
	global_load_dword v15, v[24:25], off
	v_add_u32_e32 v5, -4, v5
	s_add_i32 s12, s12, 8
	v_cmp_eq_u32_e32 vcc, 0, v5
	v_add_u32_e32 v1, 0x800, v1
	v_add_u32_e32 v0, 0x800, v0
	v_mov_b32_e32 v7, s12
	s_or_b64 s[8:9], vcc, s[8:9]
	s_waitcnt vmcnt(6)
	v_mul_f32_e64 v8, v8, s24
	v_mul_f32_e64 v9, v9, s24
	ds_write2st64_b32 v6, v8, v9 offset1:4
	s_waitcnt vmcnt(4)
	v_mul_f32_e64 v8, v10, s24
	v_mul_f32_e64 v9, v11, s24
	s_waitcnt vmcnt(2)
	v_mul_f32_e64 v10, v12, s24
	v_mul_f32_e64 v11, v13, s24
	s_waitcnt vmcnt(0)
	v_mul_f32_e64 v12, v14, s24
	v_mul_f32_e64 v13, v15, s24
	ds_write2st64_b32 v6, v8, v9 offset0:8 offset1:12
	ds_write2st64_b32 v6, v10, v11 offset0:16 offset1:20
	ds_write2st64_b32 v6, v12, v13 offset0:24 offset1:28
	v_add_u32_e32 v6, 0x2000, v6
	s_andn2_b64 exec, exec, s[8:9]
	s_cbranch_execnz .LBB0_696
	s_or_b64 exec, exec, s[8:9]

; DI void selwin_item(const Params& p, int it, unsigned char* smem, u16* y_out) {
;     ...
;   __syncthreads();
;   for (int e = tid; e < 512; e += 256) { const int hh = e >> 7, d = e & 127; bt[e] = p.rel[t5_bucket(d) * 16 + g * 4 + hh] * LOG2E; }
.LBB0_700:
	v_ashrrev_i32_e32 v6, 7, v0
	v_ashrrev_i32_e32 v7, 7, v1
	v_add_u32_e32 v6, v2, v6
	v_add_u32_e32 v8, v2, v7
	v_ashrrev_i32_e32 v7, 31, v6
	v_ashrrev_i32_e32 v9, 31, v8
	v_lshl_add_u64 v[6:7], v[6:7], 2, s[82:83]
	v_lshl_add_u64 v[8:9], v[8:9], 2, s[82:83]
	global_load_dword v6, v[6:7], off
	s_nop 0
	global_load_dword v7, v[8:9], off
	v_add_u32_e32 v4, -1, v4
	v_cmp_eq_u32_e32 vcc, 0, v4
	v_add_u32_e32 v1, 0x200, v1
	v_add_u32_e32 v0, 0x200, v0
	s_or_b64 s[8:9], vcc, s[8:9]
	s_waitcnt vmcnt(0)
	v_mul_f32_e64 v6, v6, s24
	v_mul_f32_e64 v7, v7, s24
	ds_write2st64_b32 v5, v6, v7 offset1:4
	v_add_u32_e32 v5, 0x800, v5
	s_andn2_b64 exec, exec, s[8:9]
	s_cbranch_execnz .LBB0_700

; DI float bf2f(u16 v) { return __uint_as_float(((unsigned)v) << 16); }
; DI float sigmoidf_(float x) { return 1.0f / (1.0f + __expf(-x)); }
; DI void selwin_item(const Params& p, int it, unsigned char* smem, u16* y_out) {
;     ...
; #pragma unroll
;     for (int nt = 0; nt < 2; ++nt) {
;       float lt = l[nt]; lt += __shfl_xor(lt, 16); lt += __shfl_xor(lt, 32);
;       const size_t t = tb0 + s0 + nt * 16 + lr;
;       const float gt = sigmoidf_(bf2f(((const u16*)(p.ws + OFF_MKV))[t * 256 + 160 + h * 3 + 1 + pass]));
;       const float f = gt / lt;
; #pragma unroll
;       for (int dt = 0; dt < 4; ++dt) { if (pass == 0) Ores[dt][nt] = O[dt][nt] * f; else Ores[dt][nt] = Ores[dt][nt] + O[dt][nt] * f; }
;     }
.LBB0_706:
	v_lshl_add_u64 v[80:81], s[30:31], 1, v[170:171]
	v_lshl_add_u64 v[82:83], v[80:81], 0, v[172:173]
	v_lshl_add_u64 v[80:81], v[80:81], 0, v[174:175]
	global_load_ushort v82, v[82:83], off
	s_nop 0
	global_load_ushort v80, v[80:81], off
	ds_bpermute_b32 v81, v213, v220
	ds_bpermute_b32 v83, v213, v225
	s_mov_b64 s[30:31], 1
	s_mov_b64 s[34:35], 0
	s_waitcnt lgkmcnt(1)
	v_add_f32_e32 v81, v220, v81
	ds_bpermute_b32 v84, v214, v81
	s_waitcnt lgkmcnt(1)
	v_add_f32_e32 v83, v225, v83
	ds_bpermute_b32 v85, v214, v83
	s_waitcnt lgkmcnt(1)
	v_add_f32_e32 v81, v81, v84
	s_waitcnt lgkmcnt(0)
	v_add_f32_e32 v83, v83, v85
	s_waitcnt vmcnt(1)
	v_lshlrev_b32_e32 v82, 16, v82
	s_waitcnt vmcnt(0)
	v_lshlrev_b32_e32 v80, 16, v80
	v_mul_f32_e32 v82, 0xbfb8aa3b, v82
	v_mul_f32_e32 v80, 0xbfb8aa3b, v80
	v_exp_f32_e32 v82, v82
	v_exp_f32_e32 v80, v80
	v_add_f32_e32 v82, 1.0, v82
	v_add_f32_e32 v84, 1.0, v80
	v_div_scale_f32 v86, s[0:1], v84, v84, 1.0
	v_rcp_f32_e32 v88, v86
	v_rcp_f32_e32 v80, v82
	v_fma_f32 v91, -v86, v88, 1.0
	v_div_scale_f32 v82, s[4:5], v81, v81, v80
	v_div_scale_f32 v89, s[0:1], 1.0, v84, 1.0
	v_fmac_f32_e32 v88, v91, v88
	v_rcp_f32_e32 v85, v82
	v_mul_f32_e32 v91, v89, v88
	v_fma_f32 v93, -v86, v91, v89
	v_fmac_f32_e32 v91, v93, v88
	v_fma_f32 v86, -v86, v91, v89
	v_fma_f32 v89, -v82, v85, 1.0
	v_div_scale_f32 v87, vcc, v80, v81, v80
	v_fmac_f32_e32 v85, v89, v85
	v_mul_f32_e32 v89, v87, v85
	v_fma_f32 v90, -v82, v89, v87
	v_fmac_f32_e32 v89, v90, v85
	v_fma_f32 v82, -v82, v89, v87
	v_div_fmas_f32 v82, v82, v85, v89
	s_mov_b64 vcc, s[0:1]
	v_div_fixup_f32 v80, v82, v81, v80
	v_div_fmas_f32 v81, v86, v88, v91
	v_mul_f32_e64 v78, v78, v80
	v_mul_f32_e64 v79, v79, v80
	v_mul_f32_e64 v76, v76, v80
	v_mul_f32_e64 v77, v77, v80
	v_mul_f32_e64 v74, v74, v80
	v_mul_f32_e64 v75, v75, v80
	v_mul_f32_e64 v72, v72, v80
	v_mul_f32_e64 v73, v73, v80
	v_mul_f32_e64 v70, v70, v80
	v_mul_f32_e64 v71, v71, v80
	v_mul_f32_e64 v68, v68, v80
	v_mul_f32_e64 v69, v69, v80
	v_mul_f32_e64 v66, v66, v80
	v_mul_f32_e64 v67, v67, v80
	v_rcp_f32_e32 v81, v84
	s_nop 0
	v_div_scale_f32 v82, s[0:1], v83, v83, v81
	v_rcp_f32_e32 v84, v82
	v_mul_f32_e64 v64, v64, v80
	v_mul_f32_e64 v65, v65, v80
	v_div_scale_f32 v80, vcc, v81, v83, v81
	v_fma_f32 v85, -v82, v84, 1.0
	v_fmac_f32_e32 v84, v85, v84
	v_mul_f32_e32 v85, v80, v84
	v_fma_f32 v86, -v82, v85, v80
	v_fmac_f32_e32 v85, v86, v84
	v_fma_f32 v80, -v82, v85, v80
	v_div_fmas_f32 v80, v80, v84, v85
	v_div_fixup_f32 v80, v80, v83, v81
	s_andn2_b64 vcc, exec, s[36:37]
	v_mul_f32_e64 v62, v62, v80
	v_mul_f32_e64 v63, v63, v80
	v_mul_f32_e64 v60, v60, v80
	v_mul_f32_e64 v61, v61, v80
	v_mul_f32_e64 v58, v58, v80
	v_mul_f32_e64 v59, v59, v80
	v_mul_f32_e64 v56, v56, v80
	v_mul_f32_e64 v57, v57, v80
	v_mul_f32_e64 v54, v54, v80
	v_mul_f32_e64 v55, v55, v80
	v_mul_f32_e64 v52, v52, v80
	v_mul_f32_e64 v53, v53, v80
	v_mul_f32_e64 v50, v50, v80
	v_mul_f32_e64 v51, v51, v80
	v_mul_f32_e64 v48, v48, v80
	v_mul_f32_e64 v49, v49, v80
	s_cbranch_vccz .LBB0_691

; DI float ex2(float x) { return __builtin_amdgcn_exp2f(x); }
; template <int NT> DI void softmax_fast(f32x4 (&S)[4][NT], float (&m)[NT], float (&l)[NT], float (&alpha)[NT], bf16x8 (&pb)[2][NT], float sc2, const float (&bias)[NT]) {
; #pragma unroll
;   for (int nt = 0; nt < NT; ++nt) {
;     float mxr = S[0][nt][0];
; #pragma unroll
;     for (int mt = 0; mt < 4; ++mt)
; #pragma unroll
;       for (int j = 0; j < 4; ++j) mxr = fmaxf(mxr, S[mt][nt][j]);
;     mxr = fmaxf(mxr, __shfl_xor(mxr, 16)); mxr = fmaxf(mxr, __shfl_xor(mxr, 32));
;     const float mx = (bias[nt] > -1e29f) ? (mxr * sc2 + bias[nt]) : -1e30f;
;     const float mn = (mx > m[nt] + 8.0f) ? mx : m[nt];
;     alpha[nt] = ex2(m[nt] - mn); m[nt] = mn;
;     const float c = bias[nt] - ((mn < -1e29f) ? 0.f : mn);
;     float sum = 0.f;
; #pragma unroll
;     for (int mt = 0; mt < 4; ++mt)
; #pragma unroll
;       for (int j = 0; j < 4; ++j) { const float pv = ex2(S[mt][nt][j] * sc2 + c); sum += pv; S[mt][nt][j] = pv; }
;     l[nt] = l[nt] * alpha[nt] + sum;
;     pb[0][nt] = pack8(S[0][nt], S[1][nt]);
;     pb[1][nt] = pack8(S[2][nt], S[3][nt]);
;   }
; DI void selwin_item(const Params& p, int it, unsigned char* smem, u16* y_out) {
;     ...
;       const bool far = (s0 - (k0 + 63)) >= 113;
;       if (far && (pass == 0 || (s0 + 31 - k0) < 512)) {
;         float bs[2];
; #pragma unroll
;         for (int nt = 0; nt < 2; ++nt) bs[nt] = (pass == 0 && !((mw[nt] >> j) & 1u)) ? -1e30f : bfar;
;         softmax_fast<2>(S, m, l, alpha, pb, sc2, bs);
.LBB0_719:
	s_and_b64 vcc, exec, s[4:5]
	s_cbranch_vccz .LBB0_731
	v_max_f32_e32 v112, v109, v109
	v_max_f32_e32 v113, v108, v108
	v_max_f32_e32 v112, v113, v112
	v_max3_f32 v112, v112, v110, v111
	v_max3_f32 v112, v112, v104, v105
	v_max3_f32 v112, v112, v106, v107
	v_max3_f32 v112, v112, v100, v101
	v_max3_f32 v112, v112, v102, v103
	v_max3_f32 v112, v112, v96, v97
	v_max3_f32 v112, v112, v98, v99
	ds_bpermute_b32 v113, v213, v112
	s_lshl_b32 s0, 1, s69
	v_and_b32_e32 v114, s0, v210
	v_cmp_eq_u32_e32 vcc, 0, v114
	s_and_b64 vcc, s[34:35], vcc
	s_waitcnt lgkmcnt(0)
	v_max_f32_e32 v113, v113, v113
	v_max_f32_e32 v112, v112, v113
	ds_bpermute_b32 v113, v214, v112
	v_and_b32_e32 v115, s0, v211
	v_cndmask_b32_e32 v114, v176, v209, vcc
	v_cmp_eq_u32_e32 vcc, 0, v115
	s_and_b64 vcc, s[34:35], vcc
	s_waitcnt lgkmcnt(0)
	v_max_f32_e32 v113, v113, v113
	v_max_f32_e32 v112, v112, v113
	v_cndmask_b32_e32 v184, v176, v209, vcc
	v_fmamk_f32 v112, v112, 0x3e38aa3b, v114
	v_cmp_lt_f32_e32 vcc, s57, v114
	v_add_f32_e32 v113, 0x41000000, v217
	s_nop 0
	v_cndmask_b32_e32 v112, v209, v112, vcc
	v_cmp_gt_f32_e32 vcc, v112, v113
	s_nop 1
	v_cndmask_b32_e32 v221, v217, v112, vcc
	v_sub_f32_e32 v112, v217, v221
	v_cmp_ngt_f32_e32 vcc, s57, v221
	v_exp_f32_e32 v182, v112
	s_nop 0
	v_cndmask_b32_e32 v112, 0, v221, vcc
	v_sub_f32_e32 v112, v114, v112
	v_fmamk_f32 v108, v108, 0x3e38aa3b, v112
	v_exp_f32_e32 v108, v108
	v_fmamk_f32 v109, v109, 0x3e38aa3b, v112
	v_exp_f32_e32 v109, v109
	v_fmamk_f32 v110, v110, 0x3e38aa3b, v112
	v_exp_f32_e32 v110, v110
	v_fmamk_f32 v111, v111, 0x3e38aa3b, v112
	v_exp_f32_e32 v111, v111
	v_fmamk_f32 v104, v104, 0x3e38aa3b, v112
	v_add_f32_e32 v113, 0, v108
	v_exp_f32_e32 v104, v104
	v_fmamk_f32 v105, v105, 0x3e38aa3b, v112
	v_add_f32_e32 v113, v109, v113
	v_exp_f32_e32 v105, v105
	v_fmamk_f32 v106, v106, 0x3e38aa3b, v112
	v_add_f32_e32 v113, v110, v113
	v_exp_f32_e32 v106, v106
	v_fmamk_f32 v107, v107, 0x3e38aa3b, v112
	v_add_f32_e32 v113, v111, v113
	v_exp_f32_e32 v107, v107
	v_fmamk_f32 v100, v100, 0x3e38aa3b, v112
	v_add_f32_e32 v113, v104, v113
	v_exp_f32_e32 v100, v100
	v_fmamk_f32 v101, v101, 0x3e38aa3b, v112
	v_add_f32_e32 v113, v105, v113
	v_exp_f32_e32 v101, v101
	v_fmamk_f32 v102, v102, 0x3e38aa3b, v112
	v_add_f32_e32 v113, v106, v113
	v_exp_f32_e32 v102, v102
	v_fmamk_f32 v103, v103, 0x3e38aa3b, v112
	v_add_f32_e32 v113, v107, v113
	v_exp_f32_e32 v103, v103
	v_fmamk_f32 v96, v96, 0x3e38aa3b, v112
	v_add_f32_e32 v113, v100, v113
	v_exp_f32_e32 v96, v96
	v_fmamk_f32 v97, v97, 0x3e38aa3b, v112
	v_add_f32_e32 v113, v101, v113
	v_exp_f32_e32 v97, v97
	v_fmamk_f32 v98, v98, 0x3e38aa3b, v112
	v_add_f32_e32 v113, v102, v113
	v_exp_f32_e32 v98, v98
	v_fmac_f32_e32 v112, 0x3e38aa3b, v99
	v_add_f32_e32 v113, v103, v113
	v_exp_f32_e32 v99, v112
	v_add_f32_e32 v112, v96, v113
	v_add_f32_e32 v112, v97, v112
	v_add_f32_e32 v112, v98, v112
	v_add_f32_e32 v222, v99, v112
	v_max_f32_e32 v112, v93, v93
	v_max_f32_e32 v113, v92, v92
	v_max_f32_e32 v112, v113, v112
	v_max3_f32 v112, v112, v94, v95
	v_max3_f32 v112, v112, v88, v89
	v_max3_f32 v112, v112, v90, v91
	v_max3_f32 v112, v112, v84, v85
	v_max3_f32 v112, v112, v86, v87
	v_max3_f32 v112, v112, v80, v81
	v_max3_f32 v116, v112, v82, v83
	ds_bpermute_b32 v117, v213, v116
	v_cvt_pk_bf16_f32 v114, v104, v105
	v_cvt_pk_bf16_f32 v118, v96, v97
	v_cmp_lt_f32_e32 vcc, s57, v184
	v_add_f32_e32 v97, 0x41000000, v223
	s_waitcnt lgkmcnt(0)
	v_max_f32_e32 v104, v117, v117
	v_max_f32_e32 v104, v116, v104
	ds_bpermute_b32 v105, v214, v104
	v_fmac_f32_e32 v222, v220, v182
	v_cvt_pk_bf16_f32 v112, v108, v109
	v_cvt_pk_bf16_f32 v113, v110, v111
	v_cvt_pk_bf16_f32 v115, v106, v107
	s_waitcnt lgkmcnt(0)
	v_max_f32_e32 v96, v105, v105
	v_max_f32_e32 v96, v104, v96
	v_fmamk_f32 v96, v96, 0x3e38aa3b, v184
	v_cndmask_b32_e32 v96, v209, v96, vcc
	v_cmp_gt_f32_e32 vcc, v96, v97
	v_cvt_pk_bf16_f32 v116, v100, v101
	v_cvt_pk_bf16_f32 v117, v102, v103
	v_cndmask_b32_e32 v224, v223, v96, vcc
	v_sub_f32_e32 v96, v223, v224
	v_cmp_ngt_f32_e32 vcc, s57, v224
	v_exp_f32_e32 v180, v96
	v_cvt_pk_bf16_f32 v119, v98, v99
	v_cndmask_b32_e32 v96, 0, v224, vcc
	v_sub_f32_e32 v193, v184, v96
	v_fmamk_f32 v92, v92, 0x3e38aa3b, v193
	v_exp_f32_e32 v184, v92
	v_fmamk_f32 v92, v93, 0x3e38aa3b, v193
	v_exp_f32_e32 v185, v92
	v_fmamk_f32 v92, v94, 0x3e38aa3b, v193
	v_exp_f32_e32 v186, v92
	v_fmamk_f32 v92, v95, 0x3e38aa3b, v193
	v_exp_f32_e32 v187, v92
	v_fmamk_f32 v88, v88, 0x3e38aa3b, v193
	v_add_f32_e32 v92, 0, v184
	v_exp_f32_e32 v188, v88
	v_fmamk_f32 v88, v89, 0x3e38aa3b, v193
	v_add_f32_e32 v92, v185, v92
	v_exp_f32_e32 v189, v88
	v_fmamk_f32 v88, v90, 0x3e38aa3b, v193
	v_add_f32_e32 v92, v186, v92
	v_exp_f32_e32 v190, v88
	v_fmamk_f32 v88, v91, 0x3e38aa3b, v193
	v_add_f32_e32 v92, v187, v92
	v_exp_f32_e32 v191, v88
	v_fmamk_f32 v84, v84, 0x3e38aa3b, v193
	v_add_f32_e32 v88, v188, v92
	v_exp_f32_e32 v200, v84
	v_fmamk_f32 v84, v85, 0x3e38aa3b, v193
	v_add_f32_e32 v88, v189, v88
	v_exp_f32_e32 v201, v84
	v_fmamk_f32 v84, v86, 0x3e38aa3b, v193
	v_add_f32_e32 v88, v190, v88
	v_exp_f32_e32 v194, v84
	v_fmamk_f32 v84, v87, 0x3e38aa3b, v193
	v_add_f32_e32 v88, v191, v88
	v_exp_f32_e32 v195, v84
	v_fmamk_f32 v80, v80, 0x3e38aa3b, v193
	v_add_f32_e32 v84, v200, v88
	v_exp_f32_e32 v196, v80
	v_fmamk_f32 v80, v81, 0x3e38aa3b, v193
	v_add_f32_e32 v84, v201, v84
	v_exp_f32_e32 v197, v80
	v_fmamk_f32 v80, v82, 0x3e38aa3b, v193
	v_add_f32_e32 v84, v194, v84
	v_exp_f32_e32 v192, v80
	v_add_f32_e32 v84, v195, v84
	v_add_f32_e32 v80, v196, v84
	v_add_f32_e32 v80, v197, v80
	v_mul_f32_e32 v81, 0x3e38aa3b, v83
	v_add_f32_e64 v198, v192, v80
	v_add_f32_e64 v199, v193, v81
	v_cmp_neq_f32_e32 vcc, 1.0, v182
	v_cmp_neq_f32_e64 s[0:1], 1.0, v180
	s_or_b64 vcc, s[0:1], vcc
	s_cbranch_vccnz .LBB0_732
	s_branch .LBB0_733

; DI float ex2(float x) { return __builtin_amdgcn_exp2f(x); }
; template <int NT, class F> DI void softmax_step(f32x4 (&S)[4][NT], float (&m)[NT], float (&l)[NT], float (&alpha)[NT], bf16x8 (&pb)[2][NT], F f) {
; #pragma unroll
;   for (int nt = 0; nt < NT; ++nt) {
;     float mx = -1e30f;
; #pragma unroll
;     for (int mt = 0; mt < 4; ++mt)
; #pragma unroll
;       for (int j = 0; j < 4; ++j) { const float s2 = f(mt, j, nt, S[mt][nt][j]); S[mt][nt][j] = s2; mx = fmaxf(mx, s2); }
;     mx = fmaxf(mx, __shfl_xor(mx, 16)); mx = fmaxf(mx, __shfl_xor(mx, 32));
;     const float mn = (mx > m[nt] + 8.0f) ? mx : m[nt];
;     alpha[nt] = ex2(m[nt] - mn); m[nt] = mn;
;     const float mexp = (mn < -1e29f) ? 0.f : mn;
;     float sum = 0.f;
; #pragma unroll
;     for (int mt = 0; mt < 4; ++mt)
; #pragma unroll
;       for (int j = 0; j < 4; ++j) { const float pv = ex2(S[mt][nt][j] - mexp); sum += pv; S[mt][nt][j] = pv; }
; DI void selwin_item(const Params& p, int it, unsigned char* smem, u16* y_out) {
;     ...
;         } else {
;           softmax_step<2>(S, m, l, alpha, pb, [&](int mt, int jj, int nt, float raw) {
;             const int dist = (dq + nt * 16) - (mt * 16 + jj);
;             const int di = dist > 127 ? 127 : dist;
;             return raw * sc2 + (btw[di] + cb[nt]);
;           });
.LBB0_722:
	s_lshl_b32 s4, 1, s69
	v_and_b32_e32 v112, s4, v210
	v_cmp_eq_u32_e32 vcc, 0, v112
	s_and_b64 vcc, s[34:35], vcc
	v_and_b32_e32 v112, s4, v211
	v_cndmask_b32_e32 v201, 0, v209, vcc
	v_cmp_eq_u32_e32 vcc, 0, v112
	s_and_b64 vcc, s[34:35], vcc
	v_add_u32_e32 v200, s8, v216
	v_cndmask_b32_e32 v180, 0, v209, vcc
	s_cmp_lg_u32 s69, s59
	s_mov_b64 s[4:5], -1
	s_cbranch_scc0 .LBB0_728
	s_and_b64 vcc, exec, s[0:1]
	s_cbranch_vccz .LBB0_725
	v_subrev_u32_e32 v118, 18, v200
	v_subrev_u32_e32 v196, 48, v200
	v_add_u32_e32 v114, -2, v200
	v_add_u32_e32 v115, -3, v200
	v_add_u32_e32 v116, -16, v200
	v_subrev_u32_e32 v117, 17, v200
	v_min_i32_e32 v118, 0x7f, v118
	v_min_i32_e32 v196, 0x7f, v196
	v_min_i32_e32 v112, 0x7f, v200
	v_add_u32_e32 v113, -1, v200
	v_min_i32_e32 v114, 0x7f, v114
	v_min_i32_e32 v115, 0x7f, v115
	v_min_i32_e32 v116, 0x7f, v116
	v_min_i32_e32 v117, 0x7f, v117
	v_lshl_add_u32 v182, v118, 2, v212
	v_subrev_u32_e32 v118, 19, v200
	v_lshl_add_u32 v221, v196, 2, v212
	v_subrev_u32_e32 v196, 49, v200
	v_lshl_add_u32 v112, v112, 2, v212
	v_min_i32_e32 v113, 0x7f, v113
	v_lshl_add_u32 v114, v114, 2, v212
	v_lshl_add_u32 v115, v115, 2, v212
	v_lshl_add_u32 v116, v116, 2, v212
	v_lshl_add_u32 v117, v117, 2, v212
	v_min_i32_e32 v118, 0x7f, v118
	v_min_i32_e32 v196, 0x7f, v196
	v_lshl_add_u32 v113, v113, 2, v212
	v_lshl_add_u32 v184, v118, 2, v212
	ds_read_b32 v188, v112 offset:20480
	ds_read_b32 v189, v113 offset:20480
	ds_read_b32 v118, v114 offset:20480
	ds_read_b32 v119, v115 offset:20480
	ds_read_b32 v116, v116 offset:20480
	ds_read_b32 v117, v117 offset:20480
	ds_read_b32 v114, v182 offset:20480
	ds_read_b32 v115, v184 offset:20480
	v_lshl_add_u32 v222, v196, 2, v212
	v_subrev_u32_e32 v196, 50, v200
	v_subrev_u32_e32 v192, 32, v200
	v_subrev_u32_e32 v193, 33, v200
	v_subrev_u32_e32 v194, 34, v200
	v_subrev_u32_e32 v195, 35, v200
	v_min_i32_e32 v196, 0x7f, v196
	s_waitcnt lgkmcnt(7)
	v_add_f32_e32 v112, v201, v188
	s_waitcnt lgkmcnt(6)
	v_add_f32_e32 v113, v201, v189
	v_min_i32_e32 v192, 0x7f, v192
	v_min_i32_e32 v193, 0x7f, v193
	v_min_i32_e32 v194, 0x7f, v194
	v_min_i32_e32 v195, 0x7f, v195
	v_lshl_add_u32 v224, v196, 2, v212
	v_subrev_u32_e32 v196, 51, v200
	v_fmac_f32_e32 v112, 0x3e38aa3b, v108
	v_fmac_f32_e32 v113, 0x3e38aa3b, v109
	s_waitcnt lgkmcnt(5)
	v_add_f32_e32 v184, v201, v118
	s_waitcnt lgkmcnt(4)
	v_add_f32_e32 v185, v201, v119
	v_lshl_add_u32 v192, v192, 2, v212
	v_lshl_add_u32 v193, v193, 2, v212
	v_lshl_add_u32 v194, v194, 2, v212
	v_lshl_add_u32 v195, v195, 2, v212
	v_min_i32_e32 v196, 0x7f, v196
	v_max3_f32 v182, v112, s56, v113
	v_fmac_f32_e32 v184, 0x3e38aa3b, v110
	v_fmac_f32_e32 v185, 0x3e38aa3b, v111
	s_waitcnt lgkmcnt(3)
	v_add_f32_e32 v186, v201, v116
	s_waitcnt lgkmcnt(2)
	v_add_f32_e32 v187, v201, v117
	v_lshl_add_u32 v226, v196, 2, v212
	ds_read_b32 v196, v192 offset:20480
	ds_read_b32 v197, v193 offset:20480
	ds_read_b32 v198, v194 offset:20480
	ds_read_b32 v199, v195 offset:20480
	ds_read_b32 v192, v221 offset:20480
	ds_read_b32 v193, v222 offset:20480
	ds_read_b32 v194, v224 offset:20480
	ds_read_b32 v195, v226 offset:20480
	v_max3_f32 v182, v182, v184, v185
	v_fmac_f32_e32 v186, 0x3e38aa3b, v104
	v_fmac_f32_e32 v187, 0x3e38aa3b, v105
	s_waitcnt lgkmcnt(9)
	v_add_f32_e32 v190, v201, v114
	s_waitcnt lgkmcnt(8)
	v_add_f32_e32 v191, v201, v115
	v_max3_f32 v182, v182, v186, v187
	v_fmac_f32_e32 v190, 0x3e38aa3b, v106
	v_fmac_f32_e32 v191, 0x3e38aa3b, v107
	s_waitcnt lgkmcnt(7)
	v_add_f32_e32 v222, v201, v196
	s_waitcnt lgkmcnt(6)
	v_add_f32_e32 v224, v201, v197
	v_max3_f32 v182, v182, v190, v191
	v_fmac_f32_e32 v222, 0x3e38aa3b, v100
	v_fmac_f32_e32 v224, 0x3e38aa3b, v101
	s_waitcnt lgkmcnt(5)
	v_add_f32_e32 v226, v201, v198
	s_waitcnt lgkmcnt(4)
	v_add_f32_e32 v227, v201, v199
	v_max3_f32 v182, v182, v222, v224
	v_fmac_f32_e32 v226, 0x3e38aa3b, v102
	v_fmac_f32_e32 v227, 0x3e38aa3b, v103
	s_waitcnt lgkmcnt(3)
	v_add_f32_e32 v192, v201, v192
	s_waitcnt lgkmcnt(2)
	v_add_f32_e32 v193, v201, v193
	v_max3_f32 v182, v182, v226, v227
	v_fmac_f32_e32 v192, 0x3e38aa3b, v96
	v_fmac_f32_e32 v193, 0x3e38aa3b, v97
	s_waitcnt lgkmcnt(1)
	v_add_f32_e32 v194, v201, v194
	s_waitcnt lgkmcnt(0)
	v_add_f32_e32 v195, v201, v195
	v_max3_f32 v182, v182, v192, v193
	v_fmac_f32_e32 v194, 0x3e38aa3b, v98
	v_fmac_f32_e32 v195, 0x3e38aa3b, v99
	v_max3_f32 v182, v182, v194, v195
	ds_bpermute_b32 v221, v213, v182
	v_add_f32_e64 v188, v180, v188
	v_add_f32_e64 v189, v180, v189
	v_fma_f32 v188, v88, s28, v188
	v_fma_f32 v189, v89, s28, v189
	v_add_f32_e64 v118, v180, v118
	v_add_f32_e64 v119, v180, v119
	v_add_f32_e64 v116, v180, v116
	v_add_f32_e64 v117, v180, v117
	s_waitcnt lgkmcnt(0)
	v_max_f32_e32 v221, v221, v221
	v_max_f32_e32 v182, v182, v221
	ds_bpermute_b32 v221, v214, v182
	v_add_f32_e64 v114, v180, v114
	v_add_f32_e64 v115, v180, v115
	s_mov_b64 s[4:5], 0
	s_waitcnt lgkmcnt(0)
; DI float ex2(float x) { return __builtin_amdgcn_exp2f(x); }
; template <int NT, class F> DI void softmax_step(f32x4 (&S)[4][NT], float (&m)[NT], float (&l)[NT], float (&alpha)[NT], bf16x8 (&pb)[2][NT], F f) {
; #pragma unroll
;   for (int nt = 0; nt < NT; ++nt) {
;     float mx = -1e30f;
; #pragma unroll
;     for (int mt = 0; mt < 4; ++mt)
; #pragma unroll
;       for (int j = 0; j < 4; ++j) { const float s2 = f(mt, j, nt, S[mt][nt][j]); S[mt][nt][j] = s2; mx = fmaxf(mx, s2); }
;     mx = fmaxf(mx, __shfl_xor(mx, 16)); mx = fmaxf(mx, __shfl_xor(mx, 32));
;     const float mn = (mx > m[nt] + 8.0f) ? mx : m[nt];
;     alpha[nt] = ex2(m[nt] - mn); m[nt] = mn;
;     const float mexp = (mn < -1e29f) ? 0.f : mn;
;     float sum = 0.f;
; #pragma unroll
;     for (int mt = 0; mt < 4; ++mt)
; #pragma unroll
;       for (int j = 0; j < 4; ++j) { const float pv = ex2(S[mt][nt][j] - mexp); sum += pv; S[mt][nt][j] = pv; }
;     l[nt] = l[nt] * alpha[nt] + sum;
;     pb[0][nt] = pack8(S[0][nt], S[1][nt]);
;     pb[1][nt] = pack8(S[2][nt], S[3][nt]);
;   }
; DI void selwin_item(const Params& p, int it, unsigned char* smem, u16* y_out) {
;     ...
;         } else {
;           softmax_step<2>(S, m, l, alpha, pb, [&](int mt, int jj, int nt, float raw) {
;             const int dist = (dq + nt * 16) - (mt * 16 + jj);
;             const int di = dist > 127 ? 127 : dist;
;             return raw * sc2 + (btw[di] + cb[nt]);
;           });
	v_max_f32_e32 v221, v221, v221
	v_max_f32_e32 v182, v182, v221
	v_add_f32_e32 v221, 0x41000000, v217
	v_cmp_gt_f32_e32 vcc, v182, v221
	s_nop 1
	v_cndmask_b32_e32 v221, v217, v182, vcc
	v_cmp_ngt_f32_e32 vcc, s57, v221
	v_sub_f32_e32 v182, v217, v221
	v_exp_f32_e32 v182, v182
	v_cndmask_b32_e32 v228, 0, v221, vcc
	v_sub_f32_e32 v112, v112, v228
	v_exp_f32_e32 v112, v112
	v_sub_f32_e32 v113, v113, v228
	v_exp_f32_e32 v113, v113
	v_sub_f32_e32 v184, v184, v228
	v_exp_f32_e32 v229, v184
	v_sub_f32_e32 v184, v185, v228
	v_exp_f32_e32 v230, v184
	v_sub_f32_e32 v185, v186, v228
	v_add_f32_e32 v184, 0, v112
	v_exp_f32_e32 v231, v185
	v_sub_f32_e32 v185, v187, v228
	v_add_f32_e32 v184, v113, v184
	v_exp_f32_e32 v232, v185
	v_sub_f32_e32 v185, v190, v228
	v_add_f32_e32 v184, v229, v184
	v_exp_f32_e32 v233, v185
	v_sub_f32_e32 v185, v191, v228
	v_add_f32_e32 v184, v230, v184
	v_exp_f32_e32 v234, v185
	v_sub_f32_e32 v185, v222, v228
	v_add_f32_e32 v184, v231, v184
	v_exp_f32_e32 v235, v185
	v_sub_f32_e32 v185, v224, v228
	v_add_f32_e32 v184, v232, v184
	v_exp_f32_e32 v224, v185
	v_sub_f32_e32 v185, v226, v228
	v_add_f32_e32 v184, v233, v184
	v_exp_f32_e32 v236, v185
	v_sub_f32_e32 v185, v227, v228
	v_add_f32_e32 v184, v234, v184
	v_exp_f32_e32 v227, v185
	v_sub_f32_e32 v185, v192, v228
	v_add_f32_e32 v184, v235, v184
	v_exp_f32_e32 v237, v185
	v_sub_f32_e32 v185, v193, v228
	v_add_f32_e32 v184, v224, v184
	v_exp_f32_e32 v238, v185
	v_sub_f32_e32 v185, v194, v228
	v_add_f32_e32 v184, v236, v184
	v_exp_f32_e32 v239, v185
	v_sub_f32_e32 v185, v195, v228
	v_add_f32_e32 v184, v227, v184
	v_exp_f32_e32 v228, v185
	v_add_f32_e32 v184, v237, v184
	v_add_f32_e32 v184, v238, v184
	v_add_f32_e32 v184, v239, v184
	v_add_f32_e32 v222, v228, v184
	v_add_u32_e32 v184, 16, v200
	v_add_u32_e32 v185, 15, v200
	v_min_i32_e32 v184, 0x7f, v184
	v_min_i32_e32 v185, 0x7f, v185
	v_add_u32_e32 v186, 14, v200
	v_add_u32_e32 v187, 13, v200
	v_lshl_add_u32 v184, v184, 2, v212
	v_lshl_add_u32 v185, v185, 2, v212
	v_min_i32_e32 v186, 0x7f, v186
	v_min_i32_e32 v187, 0x7f, v187
	ds_read_b32 v184, v184 offset:20480
	ds_read_b32 v185, v185 offset:20480
	v_lshl_add_u32 v186, v186, 2, v212
	v_lshl_add_u32 v187, v187, 2, v212
	ds_read_b32 v186, v186 offset:20480
	ds_read_b32 v187, v187 offset:20480
	v_cvt_pk_bf16_f32 v112, v112, v113
	s_waitcnt lgkmcnt(2)
	v_add_f32_e64 v184, v180, v184
	v_add_f32_e64 v185, v180, v185
	v_fma_f32 v184, v92, s28, v184
	v_fma_f32 v185, v93, s28, v185
	v_fma_f32 v190, v90, s28, v118
	v_fma_f32 v191, v91, s28, v119
	s_waitcnt lgkmcnt(0)
	v_add_f32_e64 v186, v180, v186
	v_add_f32_e64 v187, v180, v187
	v_max3_f32 v113, v184, s56, v185
	v_fma_f32 v186, v94, s28, v186
	v_fma_f32 v187, v95, s28, v187
	v_fma_f32 v192, v84, s28, v116
	v_fma_f32 v193, v85, s28, v117
	v_max3_f32 v113, v113, v186, v187
	v_max3_f32 v113, v113, v188, v189
	v_max3_f32 v113, v113, v190, v191
	v_max3_f32 v113, v113, v192, v193
	v_fma_f32 v194, v86, s28, v114
	v_fma_f32 v195, v87, s28, v115
	v_add_f32_e64 v114, v180, v196
	v_add_f32_e64 v115, v180, v197
	v_max3_f32 v113, v113, v194, v195
	v_fma_f32 v196, v80, s28, v114
	v_fma_f32 v197, v81, s28, v115
	v_add_f32_e64 v114, v180, v198
	v_add_f32_e64 v115, v180, v199
	v_max3_f32 v113, v113, v196, v197
	v_fma_f32 v198, v82, s28, v114
	v_fma_f32 v199, v83, s28, v115
	v_cvt_pk_bf16_f32 v116, v235, v224
	v_max3_f32 v117, v113, v198, v199
	ds_bpermute_b32 v118, v213, v117
	v_fmac_f32_e32 v222, v220, v182
	v_cvt_pk_bf16_f32 v113, v229, v230
	v_cvt_pk_bf16_f32 v114, v231, v232
	v_cvt_pk_bf16_f32 v115, v233, v234
	s_waitcnt lgkmcnt(0)
	v_max_f32_e32 v118, v118, v118
	v_max_f32_e32 v224, v117, v118
	ds_bpermute_b32 v226, v214, v224
	v_cvt_pk_bf16_f32 v117, v236, v227
	v_cvt_pk_bf16_f32 v118, v237, v238
	v_cvt_pk_bf16_f32 v119, v239, v228
; DI float ex2(float x) { return __builtin_amdgcn_exp2f(x); }
; template <int NT, class F> DI void softmax_step(f32x4 (&S)[4][NT], float (&m)[NT], float (&l)[NT], float (&alpha)[NT], bf16x8 (&pb)[2][NT], F f) {
; #pragma unroll
;   for (int nt = 0; nt < NT; ++nt) {
;     float mx = -1e30f;
; #pragma unroll
;     for (int mt = 0; mt < 4; ++mt)
; #pragma unroll
;       for (int j = 0; j < 4; ++j) { const float s2 = f(mt, j, nt, S[mt][nt][j]); S[mt][nt][j] = s2; mx = fmaxf(mx, s2); }
;     mx = fmaxf(mx, __shfl_xor(mx, 16)); mx = fmaxf(mx, __shfl_xor(mx, 32));
;     const float mn = (mx > m[nt] + 8.0f) ? mx : m[nt];
;     alpha[nt] = ex2(m[nt] - mn); m[nt] = mn;
;     const float mexp = (mn < -1e29f) ? 0.f : mn;
;     float sum = 0.f;
; #pragma unroll
;     for (int mt = 0; mt < 4; ++mt)
; #pragma unroll
;       for (int j = 0; j < 4; ++j) { const float pv = ex2(S[mt][nt][j] - mexp); sum += pv; S[mt][nt][j] = pv; }
;     l[nt] = l[nt] * alpha[nt] + sum;
;     pb[0][nt] = pack8(S[0][nt], S[1][nt]);
;     pb[1][nt] = pack8(S[2][nt], S[3][nt]);
;   }
; DI void selwin_item(const Params& p, int it, unsigned char* smem, u16* y_out) {
;     ...
;         } else if (far) {
;           softmax_step<2>(S, m, l, alpha, pb, [&](int mt, int jj, int nt, float raw) {
;             const int dist = (dq + nt * 16) - (mt * 16 + jj);
;             return dist < 512 ? (raw * sc2 + bfar) : -1e30f;
;           });
.LBB0_725:
	s_andn2_b64 vcc, exec, s[4:5]
	s_cbranch_vccnz .LBB0_727
	v_subrev_u32_e32 v112, 48, v200
	v_fmamk_f32 v113, v96, 0x3e38aa3b, v176
	v_cmp_gt_i32_e32 vcc, s46, v112
	v_subrev_u32_e32 v112, 49, v200
	v_add_u32_e32 v184, 16, v200
	v_cndmask_b32_e32 v231, v209, v113, vcc
	v_fmamk_f32 v113, v97, 0x3e38aa3b, v176
	v_cmp_gt_i32_e32 vcc, s46, v112
	v_subrev_u32_e32 v112, 50, v200
	v_add_u32_e32 v185, 15, v200
	v_cndmask_b32_e32 v232, v209, v113, vcc
	v_fmamk_f32 v113, v98, 0x3e38aa3b, v176
	v_cmp_gt_i32_e32 vcc, s46, v112
	v_subrev_u32_e32 v112, 51, v200
	v_add_u32_e32 v186, 14, v200
	v_cndmask_b32_e32 v233, v209, v113, vcc
	v_fmamk_f32 v113, v99, 0x3e38aa3b, v176
	v_cmp_gt_i32_e32 vcc, s46, v112
	v_add_u32_e32 v187, 13, v200
	v_add_u32_e32 v115, -1, v200
	v_cndmask_b32_e32 v234, v209, v113, vcc
	v_fma_f32 v112, v92, s28, v176
	v_fma_f32 v113, v93, s28, v177
	v_cmp_gt_i32_e32 vcc, s46, v184
	v_fmamk_f32 v114, v108, 0x3e38aa3b, v176
	v_fmamk_f32 v116, v109, 0x3e38aa3b, v176
	v_cndmask_b32_e32 v184, v209, v112, vcc
	v_cmp_gt_i32_e32 vcc, s46, v185
	v_add_u32_e32 v117, -2, v200
	v_add_u32_e32 v118, -3, v200
	v_cndmask_b32_e32 v185, v209, v113, vcc
	v_fma_f32 v112, v94, s28, v176
	v_fma_f32 v113, v95, s28, v177
	v_cmp_gt_i32_e32 vcc, s46, v186
	v_cmp_gt_i32_e64 s[0:1], s46, v115
	v_fmamk_f32 v119, v110, 0x3e38aa3b, v176
	v_cndmask_b32_e32 v186, v209, v112, vcc
	v_cmp_gt_i32_e32 vcc, s46, v187
	v_fmamk_f32 v182, v111, 0x3e38aa3b, v176
	v_add_u32_e32 v192, -16, v200
	v_cndmask_b32_e32 v187, v209, v113, vcc
	v_cmp_gt_i32_e32 vcc, s46, v200
	v_fma_f32 v112, v88, s28, v176
	v_fma_f32 v113, v89, s28, v177
	v_subrev_u32_e32 v193, 17, v200
	v_cndmask_b32_e32 v114, v209, v114, vcc
	v_cndmask_b32_e64 v115, v209, v116, s[0:1]
	v_cndmask_b32_e32 v188, v209, v112, vcc
	v_cndmask_b32_e64 v189, v209, v113, s[0:1]
	v_cmp_gt_i32_e32 vcc, s46, v117
	v_cmp_gt_i32_e64 s[0:1], s46, v118
	v_fmamk_f32 v194, v104, 0x3e38aa3b, v176
	v_fmamk_f32 v195, v105, 0x3e38aa3b, v176
	v_subrev_u32_e32 v196, 18, v200
	v_subrev_u32_e32 v197, 19, v200
	v_max3_f32 v116, v114, s56, v115
	v_cndmask_b32_e32 v117, v209, v119, vcc
	v_cndmask_b32_e64 v118, v209, v182, s[0:1]
	v_cmp_gt_i32_e64 s[4:5], s46, v192
	v_cmp_gt_i32_e64 s[6:7], s46, v193
	v_fmamk_f32 v198, v106, 0x3e38aa3b, v176
	v_fmamk_f32 v199, v107, 0x3e38aa3b, v176
	v_subrev_u32_e32 v221, 32, v200
	v_subrev_u32_e32 v222, 33, v200
	v_max3_f32 v116, v116, v117, v118
	v_cndmask_b32_e64 v119, v209, v194, s[4:5]
	v_cndmask_b32_e64 v236, v209, v195, s[6:7]
	v_cmp_gt_i32_e64 s[8:9], s46, v196
	v_cmp_gt_i32_e64 s[10:11], s46, v197
	v_fmamk_f32 v224, v100, 0x3e38aa3b, v176
	s_waitcnt lgkmcnt(0)
	v_fmamk_f32 v226, v101, 0x3e38aa3b, v176
	v_subrev_u32_e32 v227, 34, v200
	v_subrev_u32_e32 v228, 35, v200
	v_fma_f32 v112, v90, s28, v176
	v_fma_f32 v113, v91, s28, v177
	v_max3_f32 v116, v116, v119, v236
	v_cndmask_b32_e64 v198, v209, v198, s[8:9]
	v_cndmask_b32_e64 v199, v209, v199, s[10:11]
	v_cmp_gt_i32_e64 s[12:13], s46, v221
	v_cmp_gt_i32_e64 s[14:15], s46, v222
	v_fmamk_f32 v229, v102, 0x3e38aa3b, v176
	v_fmamk_f32 v230, v103, 0x3e38aa3b, v176
	v_cndmask_b32_e32 v190, v209, v112, vcc
	v_cndmask_b32_e64 v191, v209, v113, s[0:1]
	v_max3_f32 v116, v116, v198, v199
	v_cndmask_b32_e64 v224, v209, v224, s[12:13]
	v_cndmask_b32_e64 v222, v209, v226, s[14:15]
	v_cmp_gt_i32_e32 vcc, s46, v227
	v_cmp_gt_i32_e64 s[0:1], s46, v228
	v_max3_f32 v116, v116, v224, v222
	v_cndmask_b32_e32 v226, v209, v229, vcc
	v_cndmask_b32_e64 v227, v209, v230, s[0:1]
	v_max3_f32 v116, v116, v226, v227
	v_max3_f32 v116, v116, v231, v232
	v_max3_f32 v116, v116, v233, v234
	ds_bpermute_b32 v182, v213, v116
	v_fma_f32 v112, v84, s28, v176
	v_fma_f32 v113, v85, s28, v177
	v_add_f32_e32 v235, 0x41000000, v217
	v_cndmask_b32_e64 v192, v209, v112, s[4:5]
	v_cndmask_b32_e64 v193, v209, v113, s[6:7]
	v_fma_f32 v112, v86, s28, v176
	v_fma_f32 v113, v87, s28, v177
	s_nop 0
	v_cndmask_b32_e64 v194, v209, v112, s[8:9]
	s_waitcnt lgkmcnt(0)
	v_max_f32_e32 v112, v182, v182
	v_max_f32_e32 v116, v116, v112
	ds_bpermute_b32 v182, v214, v116
	v_cndmask_b32_e64 v195, v209, v113, s[10:11]
	v_fma_f32 v112, v80, s28, v176
	v_fma_f32 v113, v81, s28, v177
	s_nop 0
	v_cndmask_b32_e64 v196, v209, v112, s[12:13]
	s_waitcnt lgkmcnt(0)
	v_max_f32_e32 v112, v182, v182
	v_max_f32_e32 v112, v116, v112
	v_cmp_gt_f32_e64 s[4:5], v112, v235
	v_cndmask_b32_e64 v197, v209, v113, s[14:15]
	s_nop 0
	v_cndmask_b32_e64 v221, v217, v112, s[4:5]
	v_sub_f32_e32 v112, v217, v221
	v_cmp_ngt_f32_e64 s[4:5], s57, v221
	v_exp_f32_e32 v182, v112
	s_nop 0
	v_cndmask_b32_e64 v112, 0, v221, s[4:5]
	v_sub_f32_e32 v113, v114, v112
	v_exp_f32_e32 v114, v113
	v_sub_f32_e32 v113, v115, v112
	v_exp_f32_e32 v115, v113
	v_sub_f32_e32 v113, v117, v112
	v_exp_f32_e32 v116, v113
	v_sub_f32_e32 v113, v118, v112
	v_exp_f32_e32 v117, v113
	v_sub_f32_e32 v118, v119, v112
	v_add_f32_e32 v113, 0, v114
	v_exp_f32_e32 v118, v118
	v_sub_f32_e32 v119, v236, v112
	v_add_f32_e32 v113, v115, v113
	v_exp_f32_e32 v119, v119
	v_sub_f32_e32 v198, v198, v112
	v_add_f32_e32 v113, v116, v113
	v_exp_f32_e32 v228, v198
	v_sub_f32_e32 v198, v199, v112
	v_add_f32_e32 v113, v117, v113
	v_exp_f32_e32 v229, v198
	v_sub_f32_e32 v198, v224, v112
	v_add_f32_e32 v113, v118, v113
	v_exp_f32_e32 v230, v198
	v_sub_f32_e32 v198, v222, v112
	v_add_f32_e32 v113, v119, v113
	v_exp_f32_e32 v235, v198
	v_sub_f32_e32 v198, v226, v112
	v_add_f32_e32 v113, v228, v113
	v_exp_f32_e32 v236, v198
	v_sub_f32_e32 v198, v227, v112
	v_add_f32_e32 v113, v229, v113
	v_exp_f32_e32 v227, v198
	v_sub_f32_e32 v198, v231, v112
	v_add_f32_e32 v113, v230, v113
	v_exp_f32_e32 v231, v198
	v_sub_f32_e32 v198, v232, v112
	v_add_f32_e32 v113, v235, v113
	v_exp_f32_e32 v232, v198
	v_sub_f32_e32 v198, v233, v112
	v_add_f32_e32 v113, v236, v113
	v_exp_f32_e32 v233, v198
	v_sub_f32_e32 v112, v234, v112
	v_add_f32_e32 v113, v227, v113
	v_exp_f32_e32 v234, v112
	v_add_f32_e32 v112, v231, v113
	v_add_f32_e32 v112, v232, v112
	v_add_f32_e32 v112, v233, v112
	v_add_f32_e32 v222, v234, v112
	v_fma_f32 v112, v82, s28, v176
	v_fma_f32 v113, v83, s28, v177
	v_fmac_f32_e32 v222, v220, v182
	v_cndmask_b32_e32 v198, v209, v112, vcc
	v_max3_f32 v112, v184, s56, v185
	v_max3_f32 v112, v112, v186, v187
	v_max3_f32 v112, v112, v188, v189
	v_max3_f32 v112, v112, v190, v191
	v_max3_f32 v112, v112, v192, v193
	v_max3_f32 v112, v112, v194, v195
	v_cndmask_b32_e64 v199, v209, v113, s[0:1]
	v_max3_f32 v112, v112, v196, v197
	v_max3_f32 v224, v112, v198, v199
	ds_bpermute_b32 v226, v213, v224
	v_cvt_pk_bf16_f32 v113, v116, v117
	v_cvt_pk_bf16_f32 v112, v114, v115
	v_cvt_pk_bf16_f32 v114, v118, v119
	v_cvt_pk_bf16_f32 v115, v228, v229
	s_waitcnt lgkmcnt(0)
	v_max_f32_e32 v116, v226, v226
	v_max_f32_e32 v224, v224, v116
	ds_bpermute_b32 v226, v214, v224
	v_cvt_pk_bf16_f32 v116, v230, v235
	v_cvt_pk_bf16_f32 v117, v236, v227
	v_cvt_pk_bf16_f32 v118, v231, v232
	v_cvt_pk_bf16_f32 v119, v233, v234

; DI float ex2(float x) { return __builtin_amdgcn_exp2f(x); }
; template <int NT, class F> DI void softmax_step(f32x4 (&S)[4][NT], float (&m)[NT], float (&l)[NT], float (&alpha)[NT], bf16x8 (&pb)[2][NT], F f) {
; #pragma unroll
;   for (int nt = 0; nt < NT; ++nt) {
;     float mx = -1e30f;
; #pragma unroll
;     for (int mt = 0; mt < 4; ++mt)
; #pragma unroll
;       for (int j = 0; j < 4; ++j) { const float s2 = f(mt, j, nt, S[mt][nt][j]); S[mt][nt][j] = s2; mx = fmaxf(mx, s2); }
;     mx = fmaxf(mx, __shfl_xor(mx, 16)); mx = fmaxf(mx, __shfl_xor(mx, 32));
;     const float mn = (mx > m[nt] + 8.0f) ? mx : m[nt];
;     alpha[nt] = ex2(m[nt] - mn); m[nt] = mn;
;     const float mexp = (mn < -1e29f) ? 0.f : mn;
;     float sum = 0.f;
; #pragma unroll
;     for (int mt = 0; mt < 4; ++mt)
; #pragma unroll
;       for (int j = 0; j < 4; ++j) { const float pv = ex2(S[mt][nt][j] - mexp); sum += pv; S[mt][nt][j] = pv; }
; DI void selwin_item(const Params& p, int it, unsigned char* smem, u16* y_out) {
;     ...
;         if (j == cur) {
;           softmax_step<2>(S, m, l, alpha, pb, [&](int mt, int jj, int nt, float raw) {
;             const int dist = (dq + nt * 16) - (mt * 16 + jj);
;             const int di = dist < 0 ? 0 : dist;
;             const float s2 = raw * sc2 + (btw[di] + cb[nt]);
;             return dist >= 0 ? s2 : -1e30f;
;           });
.LBB0_728:
	s_andn2_b64 vcc, exec, s[4:5]
	s_cbranch_vccnz .LBB0_730
	v_add_u32_e32 v191, -2, v200
	v_add_u32_e32 v190, -3, v200
	v_max_i32_e32 v114, 0, v191
	v_lshl_add_u32 v116, v114, 2, v212
	v_max_i32_e32 v114, 0, v190
	v_add_u32_e32 v192, -16, v200
	v_lshl_add_u32 v117, v114, 2, v212
	v_subrev_u32_e32 v193, 17, v200
	v_max_i32_e32 v114, 0, v192
	v_lshl_add_u32 v118, v114, 2, v212
	v_max_i32_e32 v114, 0, v193
	v_subrev_u32_e32 v199, 18, v200
	v_add_u32_e32 v182, -1, v200
	v_lshl_add_u32 v119, v114, 2, v212
	v_subrev_u32_e32 v198, 19, v200
	v_max_i32_e32 v114, 0, v199
	v_max_i32_e32 v112, 0, v200
	v_max_i32_e32 v113, 0, v182
	v_lshl_add_u32 v184, v114, 2, v212
	v_max_i32_e32 v114, 0, v198
	v_subrev_u32_e32 v233, 49, v200
	v_lshl_add_u32 v112, v112, 2, v212
	v_lshl_add_u32 v113, v113, 2, v212
	v_lshl_add_u32 v185, v114, 2, v212
	v_subrev_u32_e32 v229, 33, v200
	v_subrev_u32_e32 v230, 32, v200
	v_subrev_u32_e32 v231, 35, v200
	v_subrev_u32_e32 v232, 34, v200
	v_subrev_u32_e32 v186, 48, v200
	v_max_i32_e32 v196, 0, v233
	v_subrev_u32_e32 v235, 50, v200
	ds_read_b32 v114, v112 offset:20480
	ds_read_b32 v115, v113 offset:20480
	ds_read_b32 v116, v116 offset:20480
	ds_read_b32 v117, v117 offset:20480
	ds_read_b32 v118, v118 offset:20480
	ds_read_b32 v119, v119 offset:20480
	ds_read_b32 v194, v184 offset:20480
	ds_read_b32 v195, v185 offset:20480
	v_max_i32_e32 v112, 0, v230
	v_max_i32_e32 v113, 0, v229
	v_max_i32_e32 v184, 0, v232
	v_max_i32_e32 v185, 0, v231
	v_max_i32_e32 v187, 0, v186
	v_lshl_add_u32 v234, v196, 2, v212
	v_max_i32_e32 v196, 0, v235
	v_subrev_u32_e32 v237, 51, v200
	v_lshl_add_u32 v112, v112, 2, v212
	v_lshl_add_u32 v113, v113, 2, v212
	v_lshl_add_u32 v184, v184, 2, v212
	v_lshl_add_u32 v185, v185, 2, v212
	v_lshl_add_u32 v187, v187, 2, v212
	v_lshl_add_u32 v236, v196, 2, v212
	v_max_i32_e32 v196, 0, v237
	v_lshl_add_u32 v238, v196, 2, v212
	ds_read_b32 v196, v112 offset:20480
	ds_read_b32 v197, v113 offset:20480
	ds_read_b32 v112, v184 offset:20480
	ds_read_b32 v113, v185 offset:20480
	ds_read_b32 v184, v187 offset:20480
	ds_read_b32 v185, v234 offset:20480
	ds_read_b32 v187, v236 offset:20480
	ds_read_b32 v234, v238 offset:20480
	v_cmp_lt_i32_e32 vcc, -1, v186
	s_waitcnt lgkmcnt(3)
	v_add_f32_e32 v184, v201, v184
	v_fmac_f32_e32 v184, 0x3e38aa3b, v96
	v_cndmask_b32_e32 v241, v209, v184, vcc
	s_waitcnt lgkmcnt(2)
	v_add_f32_e32 v184, v201, v185
	v_fmac_f32_e32 v184, 0x3e38aa3b, v97
	v_cmp_lt_i32_e32 vcc, -1, v233
	v_add_u32_e32 v242, 16, v200
	v_add_f32_e32 v188, v201, v114
	v_cndmask_b32_e32 v233, v209, v184, vcc
	s_waitcnt lgkmcnt(1)
	v_add_f32_e32 v184, v201, v187
	v_fmac_f32_e32 v184, 0x3e38aa3b, v98
	v_cmp_lt_i32_e32 vcc, -1, v235
	v_add_f32_e32 v189, v201, v115
	v_add_f32_e32 v221, v201, v116
	v_cndmask_b32_e32 v235, v209, v184, vcc
	s_waitcnt lgkmcnt(0)
	v_add_f32_e32 v184, v201, v234
	v_fmac_f32_e32 v184, 0x3e38aa3b, v99
	v_cmp_lt_i32_e32 vcc, -1, v237
	v_add_u32_e32 v237, 15, v200
	v_add_f32_e32 v222, v201, v117
	v_add_f32_e32 v224, v201, v118
	v_add_f32_e32 v226, v201, v119
	v_add_f32_e32 v227, v201, v194
	v_add_f32_e32 v228, v201, v195
	v_add_f32_e32 v236, v201, v196
	v_add_f32_e32 v238, v201, v197
	v_add_f32_e32 v239, v201, v112
	v_add_f32_e32 v240, v201, v113
	v_cndmask_b32_e32 v201, v209, v184, vcc
	v_max_i32_e32 v184, 0, v242
	v_max_i32_e32 v185, 0, v237
	v_lshl_add_u32 v184, v184, 2, v212
	v_lshl_add_u32 v185, v185, 2, v212
	v_add_u32_e32 v243, 13, v200
	v_add_u32_e32 v244, 14, v200
	ds_read_b32 v184, v184 offset:20480
	ds_read_b32 v185, v185 offset:20480
	v_max_i32_e32 v186, 0, v244
	v_max_i32_e32 v187, 0, v243
	v_lshl_add_u32 v186, v186, 2, v212
	v_lshl_add_u32 v187, v187, 2, v212
	ds_read_b32 v186, v186 offset:20480
	ds_read_b32 v187, v187 offset:20480
	s_waitcnt lgkmcnt(2)
	v_add_f32_e64 v184, v180, v184
	v_add_f32_e64 v185, v180, v185
	v_fma_f32 v184, v92, s28, v184
	v_fma_f32 v185, v93, s28, v185
	v_cmp_lt_i32_e32 vcc, -1, v242
	v_add_f32_e64 v114, v180, v114
	v_add_f32_e64 v115, v180, v115
	s_waitcnt lgkmcnt(0)
	v_add_f32_e64 v186, v180, v186
	v_add_f32_e64 v187, v180, v187
	v_cndmask_b32_e32 v184, v209, v184, vcc
	v_cmp_lt_i32_e32 vcc, -1, v237
	v_fma_f32 v186, v94, s28, v186
	v_fma_f32 v187, v95, s28, v187
	v_fmac_f32_e32 v188, 0x3e38aa3b, v108
	v_cndmask_b32_e32 v185, v209, v185, vcc
	v_cmp_lt_i32_e32 vcc, -1, v244
	v_fmac_f32_e32 v189, 0x3e38aa3b, v109
	v_cmp_lt_i32_e64 s[0:1], -1, v182
	v_cndmask_b32_e32 v186, v209, v186, vcc
	v_cmp_lt_i32_e32 vcc, -1, v243
	v_fma_f32 v114, v88, s28, v114
	v_fma_f32 v115, v89, s28, v115
	v_cndmask_b32_e64 v242, v209, v189, s[0:1]
	v_cndmask_b32_e32 v187, v209, v187, vcc
	v_cmp_lt_i32_e32 vcc, -1, v200
	v_cndmask_b32_e64 v189, v209, v115, s[0:1]
	v_fmac_f32_e32 v221, 0x3e38aa3b, v110
	v_cndmask_b32_e32 v200, v209, v188, vcc
	v_cndmask_b32_e32 v188, v209, v114, vcc
	v_add_f32_e64 v114, v180, v116
	v_add_f32_e64 v115, v180, v117
	v_fmac_f32_e32 v222, 0x3e38aa3b, v111
	v_cmp_lt_i32_e32 vcc, -1, v191
	v_cmp_lt_i32_e64 s[0:1], -1, v190
	v_fma_f32 v114, v90, s28, v114
	v_fma_f32 v115, v91, s28, v115
	v_fmac_f32_e32 v224, 0x3e38aa3b, v104
	v_fmac_f32_e32 v226, 0x3e38aa3b, v105
	v_max3_f32 v182, v200, s56, v242
	v_cndmask_b32_e32 v243, v209, v221, vcc
	v_cndmask_b32_e64 v222, v209, v222, s[0:1]
	v_cndmask_b32_e32 v190, v209, v114, vcc
	v_cndmask_b32_e64 v191, v209, v115, s[0:1]
	v_cmp_lt_i32_e32 vcc, -1, v192
	v_cmp_lt_i32_e64 s[0:1], -1, v193
	v_fmac_f32_e32 v227, 0x3e38aa3b, v106
	v_fmac_f32_e32 v228, 0x3e38aa3b, v107
	v_max3_f32 v182, v182, v243, v222
	v_cndmask_b32_e32 v117, v209, v224, vcc
	v_cndmask_b32_e64 v224, v209, v226, s[0:1]
	v_add_f32_e64 v114, v180, v118
	v_add_f32_e64 v115, v180, v119
	v_cmp_lt_i32_e64 s[4:5], -1, v199
	v_cmp_lt_i32_e64 s[6:7], -1, v198
	v_fmac_f32_e32 v236, 0x3e38aa3b, v100
	v_fmac_f32_e32 v238, 0x3e38aa3b, v101
	v_max3_f32 v182, v182, v117, v224
	v_fma_f32 v114, v84, s28, v114
	v_fma_f32 v115, v85, s28, v115
	v_cndmask_b32_e64 v118, v209, v227, s[4:5]
	v_cndmask_b32_e64 v119, v209, v228, s[6:7]
	v_cmp_lt_i32_e64 s[8:9], -1, v230
	v_cmp_lt_i32_e64 s[10:11], -1, v229
	v_fmac_f32_e32 v239, 0x3e38aa3b, v102
	v_fmac_f32_e32 v240, 0x3e38aa3b, v103
	v_cndmask_b32_e32 v192, v209, v114, vcc
	v_cndmask_b32_e64 v193, v209, v115, s[0:1]
	v_max3_f32 v182, v182, v118, v119
	v_cndmask_b32_e64 v198, v209, v236, s[8:9]
	v_cndmask_b32_e64 v199, v209, v238, s[10:11]
	v_cmp_lt_i32_e32 vcc, -1, v232
	v_cmp_lt_i32_e64 s[0:1], -1, v231
	v_max3_f32 v182, v182, v198, v199
	v_cndmask_b32_e32 v226, v209, v239, vcc
	v_cndmask_b32_e64 v227, v209, v240, s[0:1]
	v_max3_f32 v182, v182, v226, v227
	v_max3_f32 v182, v182, v241, v233
	v_max3_f32 v182, v182, v235, v201
	ds_bpermute_b32 v221, v213, v182
	v_add_f32_e64 v114, v180, v194
	v_add_f32_e64 v115, v180, v195
	v_fma_f32 v114, v86, s28, v114
	v_fma_f32 v115, v87, s28, v115
	v_max3_f32 v237, v184, s56, v185
	v_cndmask_b32_e64 v194, v209, v114, s[4:5]
	v_cndmask_b32_e64 v195, v209, v115, s[6:7]
	v_add_f32_e64 v114, v180, v196
	v_add_f32_e64 v115, v180, v197
	s_waitcnt lgkmcnt(0)
; DI float ex2(float x) { return __builtin_amdgcn_exp2f(x); }
; template <int NT, class F> DI void softmax_step(f32x4 (&S)[4][NT], float (&m)[NT], float (&l)[NT], float (&alpha)[NT], bf16x8 (&pb)[2][NT], F f) {
; #pragma unroll
;   for (int nt = 0; nt < NT; ++nt) {
;     float mx = -1e30f;
; #pragma unroll
;     for (int mt = 0; mt < 4; ++mt)
; #pragma unroll
;       for (int j = 0; j < 4; ++j) { const float s2 = f(mt, j, nt, S[mt][nt][j]); S[mt][nt][j] = s2; mx = fmaxf(mx, s2); }
;     mx = fmaxf(mx, __shfl_xor(mx, 16)); mx = fmaxf(mx, __shfl_xor(mx, 32));
;     const float mn = (mx > m[nt] + 8.0f) ? mx : m[nt];
;     alpha[nt] = ex2(m[nt] - mn); m[nt] = mn;
;     const float mexp = (mn < -1e29f) ? 0.f : mn;
;     float sum = 0.f;
; #pragma unroll
;     for (int mt = 0; mt < 4; ++mt)
; #pragma unroll
;       for (int j = 0; j < 4; ++j) { const float pv = ex2(S[mt][nt][j] - mexp); sum += pv; S[mt][nt][j] = pv; }
;     l[nt] = l[nt] * alpha[nt] + sum;
;     pb[0][nt] = pack8(S[0][nt], S[1][nt]);
;     pb[1][nt] = pack8(S[2][nt], S[3][nt]);
;   }
	v_max_f32_e32 v196, v221, v221
	v_max_f32_e32 v182, v182, v196
	ds_bpermute_b32 v221, v214, v182
	v_fma_f32 v114, v80, s28, v114
	v_fma_f32 v115, v81, s28, v115
	v_add_f32_e32 v234, 0x41000000, v217
	v_cndmask_b32_e64 v197, v209, v115, s[10:11]
	v_max3_f32 v237, v237, v186, v187
	s_waitcnt lgkmcnt(0)
	v_max_f32_e32 v115, v221, v221
	v_max_f32_e32 v115, v182, v115
	v_max3_f32 v237, v237, v188, v189
	v_cmp_gt_f32_e64 s[4:5], v115, v234
	v_max3_f32 v116, v237, v190, v191
	v_max3_f32 v116, v116, v192, v193
	v_cndmask_b32_e64 v221, v217, v115, s[4:5]
	v_sub_f32_e32 v115, v217, v221
	v_cmp_ngt_f32_e64 s[4:5], s57, v221
	v_max3_f32 v116, v116, v194, v195
	v_cndmask_b32_e64 v196, v209, v114, s[8:9]
	v_exp_f32_e32 v182, v115
	v_cndmask_b32_e64 v115, 0, v221, s[4:5]
	v_max3_f32 v114, v116, v196, v197
	v_sub_f32_e32 v116, v200, v115
	v_exp_f32_e32 v116, v116
	v_sub_f32_e32 v200, v242, v115
	v_exp_f32_e32 v200, v200
	v_sub_f32_e32 v228, v243, v115
	v_exp_f32_e32 v228, v228
	v_sub_f32_e32 v222, v222, v115
	v_exp_f32_e32 v229, v222
	v_sub_f32_e32 v117, v117, v115
	v_add_f32_e32 v222, 0, v116
	v_exp_f32_e32 v117, v117
	v_sub_f32_e32 v224, v224, v115
	v_add_f32_e32 v222, v200, v222
	v_exp_f32_e32 v224, v224
	v_sub_f32_e32 v118, v118, v115
	v_add_f32_e32 v222, v228, v222
	v_exp_f32_e32 v118, v118
	v_sub_f32_e32 v119, v119, v115
	v_add_f32_e32 v222, v229, v222
	v_exp_f32_e32 v119, v119
	v_sub_f32_e32 v198, v198, v115
	v_add_f32_e32 v222, v117, v222
	v_exp_f32_e32 v230, v198
	v_sub_f32_e32 v198, v199, v115
	v_add_f32_e32 v222, v224, v222
	v_exp_f32_e32 v231, v198
	v_sub_f32_e32 v198, v226, v115
	v_add_f32_e32 v222, v118, v222
	v_exp_f32_e32 v232, v198
	v_sub_f32_e32 v198, v227, v115
	v_add_f32_e32 v222, v119, v222
	v_exp_f32_e32 v227, v198
	v_sub_f32_e32 v199, v241, v115
	v_add_f32_e32 v198, v230, v222
	v_exp_f32_e32 v234, v199
	v_add_f32_e32 v198, v231, v198
	v_add_f32_e32 v198, v232, v198
	v_sub_f32_e32 v199, v233, v115
	v_add_f32_e64 v112, v180, v112
	v_add_f32_e64 v113, v180, v113
	v_add_f32_e32 v198, v227, v198
	v_exp_f32_e32 v233, v199
	v_sub_f32_e32 v199, v235, v115
	v_sub_f32_e32 v115, v201, v115
	v_fma_f32 v112, v82, s28, v112
	v_fma_f32 v113, v83, s28, v113
	v_exp_f32_e32 v235, v199
	v_exp_f32_e32 v201, v115
	v_add_f32_e32 v115, v234, v198
	v_cndmask_b32_e64 v199, v209, v113, s[0:1]
	v_cndmask_b32_e32 v198, v209, v112, vcc
	v_max3_f32 v180, v114, v198, v199
	ds_bpermute_b32 v226, v213, v180
	v_cvt_pk_bf16_f32 v112, v116, v200
	v_cvt_pk_bf16_f32 v114, v117, v224
	v_add_f32_e32 v115, v233, v115
	v_add_f32_e32 v115, v235, v115
	s_waitcnt lgkmcnt(0)
	v_max_f32_e32 v116, v226, v226
	v_max_f32_e32 v224, v180, v116
	ds_bpermute_b32 v226, v214, v224
	v_add_f32_e32 v222, v201, v115
	v_fmac_f32_e32 v222, v220, v182
	v_cvt_pk_bf16_f32 v113, v228, v229
	v_cvt_pk_bf16_f32 v115, v118, v119
	v_cvt_pk_bf16_f32 v116, v230, v231
	v_cvt_pk_bf16_f32 v117, v232, v227
	v_cvt_pk_bf16_f32 v118, v234, v233
	v_cvt_pk_bf16_f32 v119, v235, v201
.LBB0_730:
	s_waitcnt lgkmcnt(0)
	v_max_f32_e32 v180, v226, v226
	v_max_f32_e32 v200, v224, v224
	v_max_f32_e32 v180, v200, v180
	v_add_f32_e32 v200, 0x41000000, v223
	v_cmp_gt_f32_e32 vcc, v180, v200
	s_nop 1
	v_cndmask_b32_e32 v224, v223, v180, vcc
	v_cmp_ngt_f32_e32 vcc, s57, v224
	v_sub_f32_e32 v180, v223, v224
	v_exp_f32_e32 v180, v180
	v_cndmask_b32_e32 v227, 0, v224, vcc
	v_sub_f32_e32 v184, v184, v227
	v_exp_f32_e32 v184, v184
	v_sub_f32_e32 v185, v185, v227
	v_exp_f32_e32 v185, v185
	v_sub_f32_e32 v186, v186, v227
	v_exp_f32_e32 v186, v186
	v_sub_f32_e32 v187, v187, v227
	v_exp_f32_e32 v187, v187
	v_sub_f32_e32 v188, v188, v227
	v_add_f32_e32 v200, 0, v184
	v_exp_f32_e32 v188, v188
	v_sub_f32_e32 v189, v189, v227
	v_add_f32_e32 v200, v185, v200
	v_exp_f32_e32 v189, v189
	v_sub_f32_e32 v190, v190, v227
	v_add_f32_e32 v200, v186, v200
	v_exp_f32_e32 v190, v190
	v_sub_f32_e32 v191, v191, v227
	v_add_f32_e32 v200, v187, v200
	v_exp_f32_e32 v191, v191
	v_add_f32_e32 v200, v188, v200
	v_add_f32_e32 v200, v189, v200
	v_add_f32_e32 v200, v190, v200
	v_sub_f32_e32 v192, v192, v227
	v_add_f32_e32 v226, v191, v200
	v_exp_f32_e32 v200, v192
	v_sub_f32_e32 v192, v193, v227
	v_exp_f32_e32 v201, v192
	v_sub_f32_e32 v192, v194, v227
	v_exp_f32_e32 v194, v192
	v_sub_f32_e32 v192, v195, v227
	v_exp_f32_e32 v195, v192
	v_add_f32_e32 v192, v200, v226
	v_add_f32_e32 v192, v201, v192
	v_add_f32_e32 v192, v194, v192
	v_add_f32_e32 v193, v195, v192
	v_sub_f32_e32 v192, v196, v227
	v_exp_f32_e32 v196, v192
	v_sub_f32_e32 v192, v197, v227
	v_exp_f32_e32 v197, v192
	v_sub_f32_e32 v192, v198, v227
	v_exp_f32_e32 v192, v192
	v_add_f32_e32 v193, v196, v193
	v_add_f32_e32 v226, v197, v193
	v_add_f32_e64 v198, v198, -v226
	v_add_f32_e64 v199, v199, -v227
	s_nop 0
	v_add_f32_e32 v198, v192, v226

; DI void selwin_item(const Params& p, int it, unsigned char* smem, u16* y_out) {
;     ...
;       if (__any((alpha[0] != 1.0f) || (alpha[1] != 1.0f))) {
; #pragma unroll
;         for (int dt = 0; dt < 4; ++dt) { O[dt][0] = O[dt][0] * alpha[0]; O[dt][1] = O[dt][1] * alpha[1]; }
;       }
.LBB0_732:
	v_mul_f32_e64 v78, v78, v182
	v_mul_f32_e64 v79, v79, v182
	v_mul_f32_e64 v76, v76, v182
	v_mul_f32_e64 v77, v77, v182
	v_mul_f32_e64 v62, v62, v180
	v_mul_f32_e64 v63, v63, v180
	v_mul_f32_e64 v60, v60, v180
	v_mul_f32_e64 v61, v61, v180
	v_mul_f32_e64 v74, v74, v182
	v_mul_f32_e64 v75, v75, v182
	v_mul_f32_e64 v72, v72, v182
	v_mul_f32_e64 v73, v73, v182
	v_mul_f32_e64 v58, v58, v180
	v_mul_f32_e64 v59, v59, v180
	v_mul_f32_e64 v56, v56, v180
	v_mul_f32_e64 v57, v57, v180
	v_mul_f32_e64 v70, v70, v182
	v_mul_f32_e64 v71, v71, v182
	v_mul_f32_e64 v68, v68, v182
	v_mul_f32_e64 v69, v69, v182
	v_mul_f32_e64 v54, v54, v180
	v_mul_f32_e64 v55, v55, v180
	v_mul_f32_e64 v52, v52, v180
	v_mul_f32_e64 v53, v53, v180
	v_mul_f32_e64 v66, v66, v182
	v_mul_f32_e64 v67, v67, v182
	v_mul_f32_e64 v64, v64, v182
	v_mul_f32_e64 v65, v65, v182
	v_mul_f32_e64 v50, v50, v180
	v_mul_f32_e64 v51, v51, v180
	v_mul_f32_e64 v48, v48, v180
	v_mul_f32_e64 v49, v49, v180

; DI float ex2(float x) { return __builtin_amdgcn_exp2f(x); }
; template <int NT> DI void softmax_fast(f32x4 (&S)[4][NT], float (&m)[NT], float (&l)[NT], float (&alpha)[NT], bf16x8 (&pb)[2][NT], float sc2, const float (&bias)[NT]) {
; #pragma unroll
;   for (int nt = 0; nt < NT; ++nt) {
;     float mxr = S[0][nt][0];
; #pragma unroll
;     for (int mt = 0; mt < 4; ++mt)
; #pragma unroll
;       for (int j = 0; j < 4; ++j) mxr = fmaxf(mxr, S[mt][nt][j]);
;     mxr = fmaxf(mxr, __shfl_xor(mxr, 16)); mxr = fmaxf(mxr, __shfl_xor(mxr, 32));
;     const float mx = (bias[nt] > -1e29f) ? (mxr * sc2 + bias[nt]) : -1e30f;
;     const float mn = (mx > m[nt] + 8.0f) ? mx : m[nt];
;     alpha[nt] = ex2(m[nt] - mn); m[nt] = mn;
;     const float c = bias[nt] - ((mn < -1e29f) ? 0.f : mn);
;     float sum = 0.f;
; #pragma unroll
;     for (int mt = 0; mt < 4; ++mt)
; #pragma unroll
;       for (int j = 0; j < 4; ++j) { const float pv = ex2(S[mt][nt][j] * sc2 + c); sum += pv; S[mt][nt][j] = pv; }
;     l[nt] = l[nt] * alpha[nt] + sum;
;     pb[0][nt] = pack8(S[0][nt], S[1][nt]);
;     pb[1][nt] = pack8(S[2][nt], S[3][nt]);
;   }
; DI void selwin_item(const Params& p, int it, unsigned char* smem, u16* y_out) {
;     ...
;       const bool far = (s0 - (k0 + 63)) >= 113;
;       if (far && (pass == 0 || (s0 + 31 - k0) < 512)) {
;         float bs[2];
; #pragma unroll
;         for (int nt = 0; nt < 2; ++nt) bs[nt] = (pass == 0 && !((mw[nt] >> j) & 1u)) ? -1e30f : bfar;
;         softmax_fast<2>(S, m, l, alpha, pb, sc2, bs);
.LBB0_738:
	s_and_b64 vcc, exec, s[4:5]
	s_cbranch_vccz .LBB0_751
	v_max_f32_e32 v112, v109, v109
	v_max_f32_e32 v113, v108, v108
	v_max_f32_e32 v112, v113, v112
	v_max3_f32 v112, v112, v110, v111
	v_max3_f32 v112, v112, v104, v105
	v_max3_f32 v112, v112, v106, v107
	v_max3_f32 v112, v112, v100, v101
	v_max3_f32 v112, v112, v102, v103
	v_max3_f32 v112, v112, v96, v97
	v_max3_f32 v112, v112, v98, v99
	ds_bpermute_b32 v113, v213, v112
	s_lshl_b32 s0, 1, s68
	v_and_b32_e32 v114, s0, v210
	v_cmp_eq_u32_e32 vcc, 0, v114
	s_and_b64 vcc, s[34:35], vcc
	s_waitcnt lgkmcnt(0)
	v_max_f32_e32 v113, v113, v113
	v_max_f32_e32 v112, v112, v113
	ds_bpermute_b32 v113, v214, v112
	v_and_b32_e32 v115, s0, v211
	v_cndmask_b32_e32 v114, v176, v209, vcc
	v_cmp_eq_u32_e32 vcc, 0, v115
	s_and_b64 vcc, s[34:35], vcc
	s_waitcnt lgkmcnt(0)
	v_max_f32_e32 v113, v113, v113
	v_max_f32_e32 v112, v112, v113
	v_cndmask_b32_e32 v184, v176, v209, vcc
	v_fmamk_f32 v112, v112, 0x3e38aa3b, v114
	v_cmp_lt_f32_e32 vcc, s57, v114
	v_add_f32_e32 v113, 0x41000000, v221
	s_nop 0
	v_cndmask_b32_e32 v112, v209, v112, vcc
	v_cmp_gt_f32_e32 vcc, v112, v113
	s_nop 1
	v_cndmask_b32_e32 v217, v221, v112, vcc
	v_sub_f32_e32 v112, v221, v217
	v_cmp_ngt_f32_e32 vcc, s57, v217
	v_exp_f32_e32 v182, v112
	s_nop 0
	v_cndmask_b32_e32 v112, 0, v217, vcc
	v_sub_f32_e32 v112, v114, v112
	v_fmamk_f32 v108, v108, 0x3e38aa3b, v112
	v_exp_f32_e32 v108, v108
	v_fmamk_f32 v109, v109, 0x3e38aa3b, v112
	v_exp_f32_e32 v109, v109
	v_fmamk_f32 v110, v110, 0x3e38aa3b, v112
	v_exp_f32_e32 v110, v110
	v_fmamk_f32 v111, v111, 0x3e38aa3b, v112
	v_exp_f32_e32 v111, v111
	v_fmamk_f32 v104, v104, 0x3e38aa3b, v112
	v_add_f32_e32 v113, 0, v108
	v_exp_f32_e32 v104, v104
	v_fmamk_f32 v105, v105, 0x3e38aa3b, v112
	v_add_f32_e32 v113, v109, v113
	v_exp_f32_e32 v105, v105
	v_fmamk_f32 v106, v106, 0x3e38aa3b, v112
	v_add_f32_e32 v113, v110, v113
	v_exp_f32_e32 v106, v106
	v_fmamk_f32 v107, v107, 0x3e38aa3b, v112
	v_add_f32_e32 v113, v111, v113
	v_exp_f32_e32 v107, v107
	v_fmamk_f32 v100, v100, 0x3e38aa3b, v112
	v_add_f32_e32 v113, v104, v113
	v_exp_f32_e32 v100, v100
	v_fmamk_f32 v101, v101, 0x3e38aa3b, v112
	v_add_f32_e32 v113, v105, v113
	v_exp_f32_e32 v101, v101
	v_fmamk_f32 v102, v102, 0x3e38aa3b, v112
	v_add_f32_e32 v113, v106, v113
	v_exp_f32_e32 v102, v102
	v_fmamk_f32 v103, v103, 0x3e38aa3b, v112
	v_add_f32_e32 v113, v107, v113
	v_exp_f32_e32 v103, v103
	v_fmamk_f32 v96, v96, 0x3e38aa3b, v112
	v_add_f32_e32 v113, v100, v113
	v_exp_f32_e32 v96, v96
	v_fmamk_f32 v97, v97, 0x3e38aa3b, v112
	v_add_f32_e32 v113, v101, v113
	v_exp_f32_e32 v97, v97
	v_fmamk_f32 v98, v98, 0x3e38aa3b, v112
	v_add_f32_e32 v113, v102, v113
	v_exp_f32_e32 v98, v98
	v_fmac_f32_e32 v112, 0x3e38aa3b, v99
	v_add_f32_e32 v113, v103, v113
	v_exp_f32_e32 v99, v112
	v_add_f32_e32 v112, v96, v113
	v_add_f32_e32 v112, v97, v112
	v_add_f32_e32 v112, v98, v112
	v_add_f32_e32 v220, v99, v112
	v_max_f32_e32 v112, v93, v93
	v_max_f32_e32 v113, v92, v92
	v_max_f32_e32 v112, v113, v112
	v_max3_f32 v112, v112, v94, v95
	v_max3_f32 v112, v112, v88, v89
	v_max3_f32 v112, v112, v90, v91
	v_max3_f32 v112, v112, v84, v85
	v_max3_f32 v112, v112, v86, v87
	v_max3_f32 v112, v112, v80, v81
	v_max3_f32 v116, v112, v82, v83
	ds_bpermute_b32 v117, v213, v116
	v_cvt_pk_bf16_f32 v114, v104, v105
	v_cvt_pk_bf16_f32 v118, v96, v97
	v_cmp_lt_f32_e32 vcc, s57, v184
	v_add_f32_e32 v97, 0x41000000, v224
	s_waitcnt lgkmcnt(0)
	v_max_f32_e32 v104, v117, v117
	v_max_f32_e32 v104, v116, v104
	ds_bpermute_b32 v105, v214, v104
	v_fmac_f32_e32 v220, v222, v182
	v_cvt_pk_bf16_f32 v112, v108, v109
	v_cvt_pk_bf16_f32 v113, v110, v111
	v_cvt_pk_bf16_f32 v115, v106, v107
	s_waitcnt lgkmcnt(0)
	v_max_f32_e32 v96, v105, v105
	v_max_f32_e32 v96, v104, v96
	v_fmamk_f32 v96, v96, 0x3e38aa3b, v184
	v_cndmask_b32_e32 v96, v209, v96, vcc
	v_cmp_gt_f32_e32 vcc, v96, v97
	v_cvt_pk_bf16_f32 v116, v100, v101
	v_cvt_pk_bf16_f32 v117, v102, v103
	v_cndmask_b32_e32 v223, v224, v96, vcc
	v_sub_f32_e32 v96, v224, v223
	v_cmp_ngt_f32_e32 vcc, s57, v223
	v_exp_f32_e32 v180, v96
	v_cvt_pk_bf16_f32 v119, v98, v99
	v_cndmask_b32_e32 v96, 0, v223, vcc
	v_sub_f32_e32 v193, v184, v96
	v_fmamk_f32 v92, v92, 0x3e38aa3b, v193
	v_exp_f32_e32 v184, v92
	v_fmamk_f32 v92, v93, 0x3e38aa3b, v193
	v_exp_f32_e32 v185, v92
	v_fmamk_f32 v92, v94, 0x3e38aa3b, v193
	v_exp_f32_e32 v186, v92
	v_fmamk_f32 v92, v95, 0x3e38aa3b, v193
	v_exp_f32_e32 v187, v92
	v_fmamk_f32 v88, v88, 0x3e38aa3b, v193
	v_add_f32_e32 v92, 0, v184
	v_exp_f32_e32 v188, v88
	v_fmamk_f32 v88, v89, 0x3e38aa3b, v193
	v_add_f32_e32 v92, v185, v92
	v_exp_f32_e32 v189, v88
	v_fmamk_f32 v88, v90, 0x3e38aa3b, v193
	v_add_f32_e32 v92, v186, v92
	v_exp_f32_e32 v190, v88
	v_fmamk_f32 v88, v91, 0x3e38aa3b, v193
	v_add_f32_e32 v92, v187, v92
	v_exp_f32_e32 v191, v88
	v_fmamk_f32 v84, v84, 0x3e38aa3b, v193
	v_add_f32_e32 v88, v188, v92
	v_exp_f32_e32 v200, v84
	v_fmamk_f32 v84, v85, 0x3e38aa3b, v193
	v_add_f32_e32 v88, v189, v88
	v_exp_f32_e32 v201, v84
	v_fmamk_f32 v84, v86, 0x3e38aa3b, v193
	v_add_f32_e32 v88, v190, v88
	v_exp_f32_e32 v194, v84
	v_fmamk_f32 v84, v87, 0x3e38aa3b, v193
	v_add_f32_e32 v88, v191, v88
	v_exp_f32_e32 v195, v84
	v_fmamk_f32 v80, v80, 0x3e38aa3b, v193
	v_add_f32_e32 v84, v200, v88
	v_exp_f32_e32 v196, v80
	v_fmamk_f32 v80, v81, 0x3e38aa3b, v193
	v_add_f32_e32 v84, v201, v84
	v_exp_f32_e32 v197, v80
	v_fmamk_f32 v80, v82, 0x3e38aa3b, v193
	v_add_f32_e32 v84, v194, v84
	v_exp_f32_e32 v192, v80
	v_add_f32_e32 v84, v195, v84
	v_add_f32_e32 v80, v196, v84
	v_add_f32_e32 v80, v197, v80
	v_mul_f32_e32 v81, 0x3e38aa3b, v83
	v_add_f32_e64 v198, v192, v80
	v_add_f32_e64 v199, v193, v81
	v_cmp_neq_f32_e32 vcc, 1.0, v182
	v_cmp_neq_f32_e64 s[0:1], 1.0, v180
	s_or_b64 vcc, s[0:1], vcc
	s_cbranch_vccnz .LBB0_752
	s_branch .LBB0_753

; DI float ex2(float x) { return __builtin_amdgcn_exp2f(x); }
; template <int NT, class F> DI void softmax_step(f32x4 (&S)[4][NT], float (&m)[NT], float (&l)[NT], float (&alpha)[NT], bf16x8 (&pb)[2][NT], F f) {
; #pragma unroll
;   for (int nt = 0; nt < NT; ++nt) {
;     float mx = -1e30f;
; #pragma unroll
;     for (int mt = 0; mt < 4; ++mt)
; #pragma unroll
;       for (int j = 0; j < 4; ++j) { const float s2 = f(mt, j, nt, S[mt][nt][j]); S[mt][nt][j] = s2; mx = fmaxf(mx, s2); }
;     mx = fmaxf(mx, __shfl_xor(mx, 16)); mx = fmaxf(mx, __shfl_xor(mx, 32));
;     const float mn = (mx > m[nt] + 8.0f) ? mx : m[nt];
;     alpha[nt] = ex2(m[nt] - mn); m[nt] = mn;
;     const float mexp = (mn < -1e29f) ? 0.f : mn;
;     float sum = 0.f;
; #pragma unroll
;     for (int mt = 0; mt < 4; ++mt)
; #pragma unroll
;       for (int j = 0; j < 4; ++j) { const float pv = ex2(S[mt][nt][j] - mexp); sum += pv; S[mt][nt][j] = pv; }
; DI void selwin_item(const Params& p, int it, unsigned char* smem, u16* y_out) {
;     ...
;         } else {
;           softmax_step<2>(S, m, l, alpha, pb, [&](int mt, int jj, int nt, float raw) {
;             const int dist = (dq + nt * 16) - (mt * 16 + jj);
;             const int di = dist > 127 ? 127 : dist;
;             return raw * sc2 + (btw[di] + cb[nt]);
;           });
.LBB0_742:
	s_lshl_b32 s4, 1, s68
	v_and_b32_e32 v112, s4, v210
	v_cmp_eq_u32_e32 vcc, 0, v112
	s_and_b64 vcc, s[34:35], vcc
	v_and_b32_e32 v112, s4, v211
	v_cndmask_b32_e32 v201, 0, v209, vcc
	v_cmp_eq_u32_e32 vcc, 0, v112
	s_and_b64 vcc, s[34:35], vcc
	v_add_u32_e32 v200, s8, v216
	v_cndmask_b32_e32 v180, 0, v209, vcc
	s_cmp_lg_u32 s68, s59
	s_mov_b64 s[4:5], -1
	s_cbranch_scc0 .LBB0_748
	s_and_b64 vcc, exec, s[0:1]
	s_cbranch_vccz .LBB0_745
	v_subrev_u32_e32 v118, 18, v200
	v_subrev_u32_e32 v196, 48, v200
	v_add_u32_e32 v114, -2, v200
	v_add_u32_e32 v115, -3, v200
	v_add_u32_e32 v116, -16, v200
	v_subrev_u32_e32 v117, 17, v200
	v_min_i32_e32 v118, 0x7f, v118
	v_min_i32_e32 v196, 0x7f, v196
	v_min_i32_e32 v112, 0x7f, v200
	v_add_u32_e32 v113, -1, v200
	v_min_i32_e32 v114, 0x7f, v114
	v_min_i32_e32 v115, 0x7f, v115
	v_min_i32_e32 v116, 0x7f, v116
	v_min_i32_e32 v117, 0x7f, v117
	v_lshl_add_u32 v182, v118, 2, v212
	v_subrev_u32_e32 v118, 19, v200
	v_lshl_add_u32 v217, v196, 2, v212
	v_subrev_u32_e32 v196, 49, v200
	v_lshl_add_u32 v112, v112, 2, v212
	v_min_i32_e32 v113, 0x7f, v113
	v_lshl_add_u32 v114, v114, 2, v212
	v_lshl_add_u32 v115, v115, 2, v212
	v_lshl_add_u32 v116, v116, 2, v212
	v_lshl_add_u32 v117, v117, 2, v212
	v_min_i32_e32 v118, 0x7f, v118
	v_min_i32_e32 v196, 0x7f, v196
	v_lshl_add_u32 v113, v113, 2, v212
	v_lshl_add_u32 v184, v118, 2, v212
	ds_read_b32 v188, v112 offset:20480
	ds_read_b32 v189, v113 offset:20480
	ds_read_b32 v118, v114 offset:20480
	ds_read_b32 v119, v115 offset:20480
	ds_read_b32 v116, v116 offset:20480
	ds_read_b32 v117, v117 offset:20480
	ds_read_b32 v114, v182 offset:20480
	ds_read_b32 v115, v184 offset:20480
	v_lshl_add_u32 v220, v196, 2, v212
	v_subrev_u32_e32 v196, 50, v200
	v_subrev_u32_e32 v192, 32, v200
	v_subrev_u32_e32 v193, 33, v200
	v_subrev_u32_e32 v194, 34, v200
	v_subrev_u32_e32 v195, 35, v200
	v_min_i32_e32 v196, 0x7f, v196
	s_waitcnt lgkmcnt(7)
	v_add_f32_e32 v112, v201, v188
	s_waitcnt lgkmcnt(6)
	v_add_f32_e32 v113, v201, v189
	v_min_i32_e32 v192, 0x7f, v192
	v_min_i32_e32 v193, 0x7f, v193
	v_min_i32_e32 v194, 0x7f, v194
	v_min_i32_e32 v195, 0x7f, v195
	v_lshl_add_u32 v223, v196, 2, v212
	v_subrev_u32_e32 v196, 51, v200
	v_fmac_f32_e32 v112, 0x3e38aa3b, v108
	v_fmac_f32_e32 v113, 0x3e38aa3b, v109
	s_waitcnt lgkmcnt(5)
	v_add_f32_e32 v184, v201, v118
	s_waitcnt lgkmcnt(4)
	v_add_f32_e32 v185, v201, v119
	v_lshl_add_u32 v192, v192, 2, v212
	v_lshl_add_u32 v193, v193, 2, v212
	v_lshl_add_u32 v194, v194, 2, v212
	v_lshl_add_u32 v195, v195, 2, v212
	v_min_i32_e32 v196, 0x7f, v196
	v_max3_f32 v182, v112, s56, v113
	v_fmac_f32_e32 v184, 0x3e38aa3b, v110
	v_fmac_f32_e32 v185, 0x3e38aa3b, v111
	s_waitcnt lgkmcnt(3)
	v_add_f32_e32 v186, v201, v116
	s_waitcnt lgkmcnt(2)
	v_add_f32_e32 v187, v201, v117
	v_lshl_add_u32 v225, v196, 2, v212
	ds_read_b32 v196, v192 offset:20480
	ds_read_b32 v197, v193 offset:20480
	ds_read_b32 v198, v194 offset:20480
	ds_read_b32 v199, v195 offset:20480
	ds_read_b32 v192, v217 offset:20480
	ds_read_b32 v193, v220 offset:20480
	ds_read_b32 v194, v223 offset:20480
	ds_read_b32 v195, v225 offset:20480
	v_max3_f32 v182, v182, v184, v185
	v_fmac_f32_e32 v186, 0x3e38aa3b, v104
	v_fmac_f32_e32 v187, 0x3e38aa3b, v105
	s_waitcnt lgkmcnt(9)
	v_add_f32_e32 v190, v201, v114
	s_waitcnt lgkmcnt(8)
	v_add_f32_e32 v191, v201, v115
	v_max3_f32 v182, v182, v186, v187
	v_fmac_f32_e32 v190, 0x3e38aa3b, v106
	v_fmac_f32_e32 v191, 0x3e38aa3b, v107
	s_waitcnt lgkmcnt(7)
	v_add_f32_e32 v220, v201, v196
	s_waitcnt lgkmcnt(6)
	v_add_f32_e32 v223, v201, v197
	v_max3_f32 v182, v182, v190, v191
	v_fmac_f32_e32 v220, 0x3e38aa3b, v100
	v_fmac_f32_e32 v223, 0x3e38aa3b, v101
	s_waitcnt lgkmcnt(5)
	v_add_f32_e32 v225, v201, v198
	s_waitcnt lgkmcnt(4)
	v_add_f32_e32 v227, v201, v199
	v_max3_f32 v182, v182, v220, v223
	v_fmac_f32_e32 v225, 0x3e38aa3b, v102
	v_fmac_f32_e32 v227, 0x3e38aa3b, v103
	s_waitcnt lgkmcnt(3)
	v_add_f32_e32 v192, v201, v192
	s_waitcnt lgkmcnt(2)
	v_add_f32_e32 v193, v201, v193
	v_max3_f32 v182, v182, v225, v227
	v_fmac_f32_e32 v192, 0x3e38aa3b, v96
	v_fmac_f32_e32 v193, 0x3e38aa3b, v97
	s_waitcnt lgkmcnt(1)
	v_add_f32_e32 v194, v201, v194
	s_waitcnt lgkmcnt(0)
	v_add_f32_e32 v195, v201, v195
	v_max3_f32 v182, v182, v192, v193
	v_fmac_f32_e32 v194, 0x3e38aa3b, v98
	v_fmac_f32_e32 v195, 0x3e38aa3b, v99
	v_max3_f32 v182, v182, v194, v195
	ds_bpermute_b32 v217, v213, v182
	v_add_f32_e64 v188, v180, v188
	v_add_f32_e64 v189, v180, v189
	v_fma_f32 v188, v88, s28, v188
	v_fma_f32 v189, v89, s28, v189
	v_add_f32_e64 v118, v180, v118
	v_add_f32_e64 v119, v180, v119
	v_add_f32_e64 v116, v180, v116
	v_add_f32_e64 v117, v180, v117
	s_waitcnt lgkmcnt(0)
	v_max_f32_e32 v217, v217, v217
	v_max_f32_e32 v182, v182, v217
	ds_bpermute_b32 v217, v214, v182
	v_add_f32_e64 v114, v180, v114
	v_add_f32_e64 v115, v180, v115
	s_mov_b64 s[4:5], 0
	s_waitcnt lgkmcnt(0)
; DI float ex2(float x) { return __builtin_amdgcn_exp2f(x); }
; template <int NT, class F> DI void softmax_step(f32x4 (&S)[4][NT], float (&m)[NT], float (&l)[NT], float (&alpha)[NT], bf16x8 (&pb)[2][NT], F f) {
; #pragma unroll
;   for (int nt = 0; nt < NT; ++nt) {
;     float mx = -1e30f;
; #pragma unroll
;     for (int mt = 0; mt < 4; ++mt)
; #pragma unroll
;       for (int j = 0; j < 4; ++j) { const float s2 = f(mt, j, nt, S[mt][nt][j]); S[mt][nt][j] = s2; mx = fmaxf(mx, s2); }
;     mx = fmaxf(mx, __shfl_xor(mx, 16)); mx = fmaxf(mx, __shfl_xor(mx, 32));
;     const float mn = (mx > m[nt] + 8.0f) ? mx : m[nt];
;     alpha[nt] = ex2(m[nt] - mn); m[nt] = mn;
;     const float mexp = (mn < -1e29f) ? 0.f : mn;
;     float sum = 0.f;
; #pragma unroll
;     for (int mt = 0; mt < 4; ++mt)
; #pragma unroll
;       for (int j = 0; j < 4; ++j) { const float pv = ex2(S[mt][nt][j] - mexp); sum += pv; S[mt][nt][j] = pv; }
;     l[nt] = l[nt] * alpha[nt] + sum;
;     pb[0][nt] = pack8(S[0][nt], S[1][nt]);
;     pb[1][nt] = pack8(S[2][nt], S[3][nt]);
;   }
; DI void selwin_item(const Params& p, int it, unsigned char* smem, u16* y_out) {
;     ...
;         } else {
;           softmax_step<2>(S, m, l, alpha, pb, [&](int mt, int jj, int nt, float raw) {
;             const int dist = (dq + nt * 16) - (mt * 16 + jj);
;             const int di = dist > 127 ? 127 : dist;
;             return raw * sc2 + (btw[di] + cb[nt]);
;           });
	v_max_f32_e32 v217, v217, v217
	v_max_f32_e32 v182, v182, v217
	v_add_f32_e32 v217, 0x41000000, v221
	v_cmp_gt_f32_e32 vcc, v182, v217
	s_nop 1
	v_cndmask_b32_e32 v217, v221, v182, vcc
	v_cmp_ngt_f32_e32 vcc, s57, v217
	v_sub_f32_e32 v182, v221, v217
	v_exp_f32_e32 v182, v182
	v_cndmask_b32_e32 v228, 0, v217, vcc
	v_sub_f32_e32 v112, v112, v228
	v_exp_f32_e32 v112, v112
	v_sub_f32_e32 v113, v113, v228
	v_exp_f32_e32 v113, v113
	v_sub_f32_e32 v184, v184, v228
	v_exp_f32_e32 v229, v184
	v_sub_f32_e32 v184, v185, v228
	v_exp_f32_e32 v230, v184
	v_sub_f32_e32 v185, v186, v228
	v_add_f32_e32 v184, 0, v112
	v_exp_f32_e32 v231, v185
	v_sub_f32_e32 v185, v187, v228
	v_add_f32_e32 v184, v113, v184
	v_exp_f32_e32 v232, v185
	v_sub_f32_e32 v185, v190, v228
	v_add_f32_e32 v184, v229, v184
	v_exp_f32_e32 v233, v185
	v_sub_f32_e32 v185, v191, v228
	v_add_f32_e32 v184, v230, v184
	v_exp_f32_e32 v234, v185
	v_sub_f32_e32 v185, v220, v228
	v_add_f32_e32 v184, v231, v184
	v_exp_f32_e32 v235, v185
	v_sub_f32_e32 v185, v223, v228
	v_add_f32_e32 v184, v232, v184
	v_exp_f32_e32 v223, v185
	v_sub_f32_e32 v185, v225, v228
	v_add_f32_e32 v184, v233, v184
	v_exp_f32_e32 v236, v185
	v_sub_f32_e32 v185, v227, v228
	v_add_f32_e32 v184, v234, v184
	v_exp_f32_e32 v227, v185
	v_sub_f32_e32 v185, v192, v228
	v_add_f32_e32 v184, v235, v184
	v_exp_f32_e32 v237, v185
	v_sub_f32_e32 v185, v193, v228
	v_add_f32_e32 v184, v223, v184
	v_exp_f32_e32 v238, v185
	v_sub_f32_e32 v185, v194, v228
	v_add_f32_e32 v184, v236, v184
	v_exp_f32_e32 v239, v185
	v_sub_f32_e32 v185, v195, v228
	v_add_f32_e32 v184, v227, v184
	v_exp_f32_e32 v228, v185
	v_add_f32_e32 v184, v237, v184
	v_add_f32_e32 v184, v238, v184
	v_add_f32_e32 v184, v239, v184
	v_add_f32_e32 v220, v228, v184
	v_add_u32_e32 v184, 16, v200
	v_add_u32_e32 v185, 15, v200
	v_min_i32_e32 v184, 0x7f, v184
	v_min_i32_e32 v185, 0x7f, v185
	v_add_u32_e32 v186, 14, v200
	v_add_u32_e32 v187, 13, v200
	v_lshl_add_u32 v184, v184, 2, v212
	v_lshl_add_u32 v185, v185, 2, v212
	v_min_i32_e32 v186, 0x7f, v186
	v_min_i32_e32 v187, 0x7f, v187
	ds_read_b32 v184, v184 offset:20480
	ds_read_b32 v185, v185 offset:20480
	v_lshl_add_u32 v186, v186, 2, v212
	v_lshl_add_u32 v187, v187, 2, v212
	ds_read_b32 v186, v186 offset:20480
	ds_read_b32 v187, v187 offset:20480
	v_cvt_pk_bf16_f32 v112, v112, v113
	s_waitcnt lgkmcnt(2)
	v_add_f32_e64 v184, v180, v184
	v_add_f32_e64 v185, v180, v185
	v_fma_f32 v184, v92, s28, v184
	v_fma_f32 v185, v93, s28, v185
	v_fma_f32 v190, v90, s28, v118
	v_fma_f32 v191, v91, s28, v119
	s_waitcnt lgkmcnt(0)
	v_add_f32_e64 v186, v180, v186
	v_add_f32_e64 v187, v180, v187
	v_max3_f32 v113, v184, s56, v185
	v_fma_f32 v186, v94, s28, v186
	v_fma_f32 v187, v95, s28, v187
	v_fma_f32 v192, v84, s28, v116
	v_fma_f32 v193, v85, s28, v117
	v_max3_f32 v113, v113, v186, v187
	v_max3_f32 v113, v113, v188, v189
	v_max3_f32 v113, v113, v190, v191
	v_max3_f32 v113, v113, v192, v193
	v_fma_f32 v194, v86, s28, v114
	v_fma_f32 v195, v87, s28, v115
	v_add_f32_e64 v114, v180, v196
	v_add_f32_e64 v115, v180, v197
	v_max3_f32 v113, v113, v194, v195
	v_fma_f32 v196, v80, s28, v114
	v_fma_f32 v197, v81, s28, v115
	v_add_f32_e64 v114, v180, v198
	v_add_f32_e64 v115, v180, v199
	v_max3_f32 v113, v113, v196, v197
	v_fma_f32 v198, v82, s28, v114
	v_fma_f32 v199, v83, s28, v115
	v_cvt_pk_bf16_f32 v116, v235, v223
	v_max3_f32 v117, v113, v198, v199
	ds_bpermute_b32 v118, v213, v117
	v_fmac_f32_e32 v220, v222, v182
	v_cvt_pk_bf16_f32 v113, v229, v230
	v_cvt_pk_bf16_f32 v114, v231, v232
	v_cvt_pk_bf16_f32 v115, v233, v234
	s_waitcnt lgkmcnt(0)
	v_max_f32_e32 v118, v118, v118
	v_max_f32_e32 v223, v117, v118
	ds_bpermute_b32 v225, v214, v223
	v_cvt_pk_bf16_f32 v117, v236, v227
	v_cvt_pk_bf16_f32 v118, v237, v238
	v_cvt_pk_bf16_f32 v119, v239, v228
; DI float ex2(float x) { return __builtin_amdgcn_exp2f(x); }
; template <int NT, class F> DI void softmax_step(f32x4 (&S)[4][NT], float (&m)[NT], float (&l)[NT], float (&alpha)[NT], bf16x8 (&pb)[2][NT], F f) {
; #pragma unroll
;   for (int nt = 0; nt < NT; ++nt) {
;     float mx = -1e30f;
; #pragma unroll
;     for (int mt = 0; mt < 4; ++mt)
; #pragma unroll
;       for (int j = 0; j < 4; ++j) { const float s2 = f(mt, j, nt, S[mt][nt][j]); S[mt][nt][j] = s2; mx = fmaxf(mx, s2); }
;     mx = fmaxf(mx, __shfl_xor(mx, 16)); mx = fmaxf(mx, __shfl_xor(mx, 32));
;     const float mn = (mx > m[nt] + 8.0f) ? mx : m[nt];
;     alpha[nt] = ex2(m[nt] - mn); m[nt] = mn;
;     const float mexp = (mn < -1e29f) ? 0.f : mn;
;     float sum = 0.f;
; #pragma unroll
;     for (int mt = 0; mt < 4; ++mt)
; #pragma unroll
;       for (int j = 0; j < 4; ++j) { const float pv = ex2(S[mt][nt][j] - mexp); sum += pv; S[mt][nt][j] = pv; }
;     l[nt] = l[nt] * alpha[nt] + sum;
;     pb[0][nt] = pack8(S[0][nt], S[1][nt]);
;     pb[1][nt] = pack8(S[2][nt], S[3][nt]);
;   }
; DI void selwin_item(const Params& p, int it, unsigned char* smem, u16* y_out) {
;     ...
;         } else if (far) {
;           softmax_step<2>(S, m, l, alpha, pb, [&](int mt, int jj, int nt, float raw) {
;             const int dist = (dq + nt * 16) - (mt * 16 + jj);
;             return dist < 512 ? (raw * sc2 + bfar) : -1e30f;
;           });
.LBB0_745:
	s_andn2_b64 vcc, exec, s[4:5]
	s_cbranch_vccnz .LBB0_747
	v_subrev_u32_e32 v112, 48, v200
	v_cmp_gt_i32_e32 vcc, s46, v112
	v_fmamk_f32 v112, v96, 0x3e38aa3b, v176
	v_add_u32_e32 v113, 15, v200
	v_cndmask_b32_e32 v231, v209, v112, vcc
	v_subrev_u32_e32 v112, 49, v200
	v_cmp_gt_i32_e32 vcc, s46, v112
	v_fmamk_f32 v112, v97, 0x3e38aa3b, v176
	v_add_u32_e32 v115, -1, v200
	v_cndmask_b32_e32 v232, v209, v112, vcc
	v_subrev_u32_e32 v112, 50, v200
	v_cmp_gt_i32_e32 vcc, s46, v112
	v_fmamk_f32 v112, v98, 0x3e38aa3b, v176
	v_fmamk_f32 v114, v108, 0x3e38aa3b, v176
	v_cndmask_b32_e32 v233, v209, v112, vcc
	v_subrev_u32_e32 v112, 51, v200
	v_cmp_gt_i32_e32 vcc, s46, v112
	v_fmamk_f32 v112, v99, 0x3e38aa3b, v176
	v_fmamk_f32 v116, v109, 0x3e38aa3b, v176
	v_cndmask_b32_e32 v234, v209, v112, vcc
	v_add_u32_e32 v112, 16, v200
	v_cmp_gt_i32_e32 vcc, s46, v113
	v_cmp_gt_i32_e64 s[0:1], s46, v112
	v_fma_f32 v112, v92, s28, v176
	v_fma_f32 v113, v93, s28, v177
	v_add_u32_e32 v117, -2, v200
	v_cndmask_b32_e64 v184, v209, v112, s[0:1]
	v_cndmask_b32_e32 v185, v209, v113, vcc
	v_add_u32_e32 v112, 14, v200
	v_add_u32_e32 v113, 13, v200
	v_cmp_gt_i32_e32 vcc, s46, v113
	v_cmp_gt_i32_e64 s[0:1], s46, v112
	v_fma_f32 v112, v94, s28, v176
	v_fma_f32 v113, v95, s28, v177
	v_add_u32_e32 v118, -3, v200
	v_cndmask_b32_e64 v186, v209, v112, s[0:1]
	v_cndmask_b32_e32 v187, v209, v113, vcc
	v_cmp_gt_i32_e32 vcc, s46, v115
	v_cmp_gt_i32_e64 s[0:1], s46, v200
	v_fma_f32 v112, v88, s28, v176
	v_fma_f32 v113, v89, s28, v177
	v_fmamk_f32 v119, v110, 0x3e38aa3b, v176
	v_fmamk_f32 v182, v111, 0x3e38aa3b, v176
	v_add_u32_e32 v192, -16, v200
	v_subrev_u32_e32 v193, 17, v200
	v_cndmask_b32_e64 v114, v209, v114, s[0:1]
	v_cndmask_b32_e32 v115, v209, v116, vcc
	v_cndmask_b32_e64 v188, v209, v112, s[0:1]
	v_cndmask_b32_e32 v189, v209, v113, vcc
	v_cmp_gt_i32_e32 vcc, s46, v118
	v_cmp_gt_i32_e64 s[0:1], s46, v117
	v_fma_f32 v112, v90, s28, v176
	v_fma_f32 v113, v91, s28, v177
	v_fmamk_f32 v194, v104, 0x3e38aa3b, v176
	v_fmamk_f32 v195, v105, 0x3e38aa3b, v176
	v_subrev_u32_e32 v196, 18, v200
	v_subrev_u32_e32 v197, 19, v200
	v_max3_f32 v116, v114, s56, v115
	v_cndmask_b32_e64 v117, v209, v119, s[0:1]
	v_cndmask_b32_e32 v118, v209, v182, vcc
	v_cndmask_b32_e64 v190, v209, v112, s[0:1]
	v_cndmask_b32_e32 v191, v209, v113, vcc
	v_cmp_gt_i32_e32 vcc, s46, v193
	v_cmp_gt_i32_e64 s[0:1], s46, v192
	v_fma_f32 v112, v84, s28, v176
	v_fma_f32 v113, v85, s28, v177
	v_fmamk_f32 v198, v106, 0x3e38aa3b, v176
	v_fmamk_f32 v199, v107, 0x3e38aa3b, v176
	v_subrev_u32_e32 v217, 32, v200
	v_subrev_u32_e32 v220, 33, v200
	v_max3_f32 v116, v116, v117, v118
	v_cndmask_b32_e64 v119, v209, v194, s[0:1]
	v_cndmask_b32_e32 v236, v209, v195, vcc
	v_cndmask_b32_e64 v192, v209, v112, s[0:1]
	v_cndmask_b32_e32 v193, v209, v113, vcc
	v_cmp_gt_i32_e32 vcc, s46, v197
	v_cmp_gt_i32_e64 s[0:1], s46, v196
	v_fma_f32 v112, v86, s28, v176
	v_fma_f32 v113, v87, s28, v177
	v_fmamk_f32 v223, v100, 0x3e38aa3b, v176
	s_waitcnt lgkmcnt(0)
	v_fmamk_f32 v225, v101, 0x3e38aa3b, v176
	v_subrev_u32_e32 v227, 34, v200
	v_subrev_u32_e32 v228, 35, v200
	v_max3_f32 v116, v116, v119, v236
	v_cndmask_b32_e64 v198, v209, v198, s[0:1]
	v_cndmask_b32_e32 v199, v209, v199, vcc
	v_cndmask_b32_e64 v194, v209, v112, s[0:1]
	v_cndmask_b32_e32 v195, v209, v113, vcc
	v_cmp_gt_i32_e32 vcc, s46, v220
	v_cmp_gt_i32_e64 s[0:1], s46, v217
	v_fma_f32 v112, v80, s28, v176
	v_fma_f32 v113, v81, s28, v177
	v_fmamk_f32 v229, v102, 0x3e38aa3b, v176
	v_fmamk_f32 v230, v103, 0x3e38aa3b, v176
	v_max3_f32 v116, v116, v198, v199
	v_cndmask_b32_e64 v220, v209, v223, s[0:1]
	v_cndmask_b32_e32 v223, v209, v225, vcc
	v_cndmask_b32_e64 v196, v209, v112, s[0:1]
	v_cndmask_b32_e32 v197, v209, v113, vcc
	v_cmp_gt_i32_e32 vcc, s46, v228
	v_cmp_gt_i32_e64 s[0:1], s46, v227
	v_max3_f32 v116, v116, v220, v223
	v_cndmask_b32_e32 v113, v209, v230, vcc
	v_cndmask_b32_e64 v112, v209, v229, s[0:1]
	v_max3_f32 v116, v116, v112, v113
	v_max3_f32 v116, v116, v231, v232
	v_max3_f32 v116, v116, v233, v234
	ds_bpermute_b32 v182, v213, v116
	v_add_f32_e32 v235, 0x41000000, v221
	s_waitcnt lgkmcnt(0)
	v_max_f32_e32 v182, v182, v182
	v_max_f32_e32 v116, v116, v182
	ds_bpermute_b32 v182, v214, v116
	s_waitcnt lgkmcnt(0)
	v_max_f32_e32 v182, v182, v182
	v_max_f32_e32 v116, v116, v182
	v_cmp_gt_f32_e64 s[4:5], v116, v235
	s_nop 1
	v_cndmask_b32_e64 v217, v221, v116, s[4:5]
	v_sub_f32_e32 v116, v221, v217
	v_cmp_ngt_f32_e64 s[4:5], s57, v217
	v_exp_f32_e32 v182, v116
	s_nop 0
	v_cndmask_b32_e64 v116, 0, v217, s[4:5]
	v_sub_f32_e32 v114, v114, v116
	v_exp_f32_e32 v114, v114
	v_sub_f32_e32 v115, v115, v116
	v_exp_f32_e32 v115, v115
	v_sub_f32_e32 v117, v117, v116
	v_exp_f32_e32 v117, v117
	v_sub_f32_e32 v118, v118, v116
	v_exp_f32_e32 v118, v118
	v_sub_f32_e32 v119, v119, v116
	v_add_f32_e32 v225, 0, v114
	v_exp_f32_e32 v119, v119
	v_sub_f32_e32 v227, v236, v116
	v_add_f32_e32 v225, v115, v225
	v_exp_f32_e32 v227, v227
	v_sub_f32_e32 v198, v198, v116
	v_add_f32_e32 v225, v117, v225
	v_exp_f32_e32 v198, v198
	v_sub_f32_e32 v199, v199, v116
	v_add_f32_e32 v225, v118, v225
	v_exp_f32_e32 v199, v199
	v_sub_f32_e32 v220, v220, v116
	v_add_f32_e32 v225, v119, v225
	v_exp_f32_e32 v228, v220
	v_add_f32_e32 v225, v227, v225
	v_add_f32_e32 v225, v198, v225
	v_sub_f32_e32 v223, v223, v116
	v_add_f32_e32 v225, v199, v225
	v_exp_f32_e32 v223, v223
	v_sub_f32_e32 v112, v112, v116
	v_add_f32_e32 v220, v228, v225
	v_exp_f32_e32 v225, v112
	v_sub_f32_e32 v113, v113, v116
	v_exp_f32_e32 v229, v113
	v_sub_f32_e32 v113, v231, v116
	v_exp_f32_e32 v230, v113
	v_sub_f32_e32 v113, v232, v116
	v_add_f32_e32 v220, v223, v220
	v_exp_f32_e32 v231, v113
	v_sub_f32_e32 v113, v233, v116
	v_add_f32_e32 v112, v225, v220
	v_exp_f32_e32 v232, v113
	v_sub_f32_e32 v113, v234, v116
	v_cvt_pk_bf16_f32 v116, v228, v223
	v_max3_f32 v223, v184, s56, v185
	v_add_f32_e32 v112, v229, v112
	v_exp_f32_e32 v233, v113
	v_max3_f32 v223, v223, v186, v187
	v_add_f32_e32 v112, v230, v112
	v_max3_f32 v223, v223, v188, v189
	v_add_f32_e32 v112, v231, v112
	v_max3_f32 v223, v223, v190, v191
	v_add_f32_e32 v112, v232, v112
	v_max3_f32 v223, v223, v192, v193
	v_add_f32_e32 v220, v233, v112
	v_cvt_pk_bf16_f32 v112, v114, v115
	v_cvt_pk_bf16_f32 v115, v198, v199
	v_fma_f32 v198, v82, s28, v176
	v_fma_f32 v199, v83, s28, v177
	v_max3_f32 v223, v223, v194, v195
	v_cndmask_b32_e32 v199, v209, v199, vcc
	v_cndmask_b32_e64 v198, v209, v198, s[0:1]
	v_max3_f32 v223, v223, v196, v197
	v_max3_f32 v223, v223, v198, v199
	v_cvt_pk_bf16_f32 v113, v117, v118
	v_cvt_pk_bf16_f32 v117, v225, v229
	ds_bpermute_b32 v225, v213, v223
	v_fmac_f32_e32 v220, v222, v182
	v_cvt_pk_bf16_f32 v114, v119, v227
	v_cvt_pk_bf16_f32 v118, v230, v231
	v_cvt_pk_bf16_f32 v119, v232, v233
	s_waitcnt lgkmcnt(0)
	v_max_f32_e32 v225, v225, v225
	v_max_f32_e32 v223, v223, v225
	ds_bpermute_b32 v225, v214, v223

; DI float ex2(float x) { return __builtin_amdgcn_exp2f(x); }
; template <int NT, class F> DI void softmax_step(f32x4 (&S)[4][NT], float (&m)[NT], float (&l)[NT], float (&alpha)[NT], bf16x8 (&pb)[2][NT], F f) {
; #pragma unroll
;   for (int nt = 0; nt < NT; ++nt) {
;     float mx = -1e30f;
; #pragma unroll
;     for (int mt = 0; mt < 4; ++mt)
; #pragma unroll
;       for (int j = 0; j < 4; ++j) { const float s2 = f(mt, j, nt, S[mt][nt][j]); S[mt][nt][j] = s2; mx = fmaxf(mx, s2); }
;     mx = fmaxf(mx, __shfl_xor(mx, 16)); mx = fmaxf(mx, __shfl_xor(mx, 32));
;     const float mn = (mx > m[nt] + 8.0f) ? mx : m[nt];
;     alpha[nt] = ex2(m[nt] - mn); m[nt] = mn;
;     const float mexp = (mn < -1e29f) ? 0.f : mn;
;     float sum = 0.f;
; #pragma unroll
;     for (int mt = 0; mt < 4; ++mt)
; #pragma unroll
;       for (int j = 0; j < 4; ++j) { const float pv = ex2(S[mt][nt][j] - mexp); sum += pv; S[mt][nt][j] = pv; }
; DI void selwin_item(const Params& p, int it, unsigned char* smem, u16* y_out) {
;     ...
;         if (j == cur) {
;           softmax_step<2>(S, m, l, alpha, pb, [&](int mt, int jj, int nt, float raw) {
;             const int dist = (dq + nt * 16) - (mt * 16 + jj);
;             const int di = dist < 0 ? 0 : dist;
;             const float s2 = raw * sc2 + (btw[di] + cb[nt]);
;             return dist >= 0 ? s2 : -1e30f;
;           });
.LBB0_748:
	s_andn2_b64 vcc, exec, s[4:5]
	s_cbranch_vccnz .LBB0_750
	v_add_u32_e32 v191, -2, v200
	v_add_u32_e32 v190, -3, v200
	v_max_i32_e32 v114, 0, v191
	v_lshl_add_u32 v116, v114, 2, v212
	v_max_i32_e32 v114, 0, v190
	v_add_u32_e32 v192, -16, v200
	v_lshl_add_u32 v117, v114, 2, v212
	v_subrev_u32_e32 v193, 17, v200
	v_max_i32_e32 v114, 0, v192
	v_lshl_add_u32 v118, v114, 2, v212
	v_max_i32_e32 v114, 0, v193
	v_subrev_u32_e32 v199, 18, v200
	v_add_u32_e32 v182, -1, v200
	v_lshl_add_u32 v119, v114, 2, v212
	v_subrev_u32_e32 v198, 19, v200
	v_max_i32_e32 v114, 0, v199
	v_max_i32_e32 v112, 0, v200
	v_max_i32_e32 v113, 0, v182
	v_lshl_add_u32 v184, v114, 2, v212
	v_max_i32_e32 v114, 0, v198
	v_subrev_u32_e32 v233, 49, v200
	v_lshl_add_u32 v112, v112, 2, v212
	v_lshl_add_u32 v113, v113, 2, v212
	v_lshl_add_u32 v185, v114, 2, v212
	v_subrev_u32_e32 v229, 33, v200
	v_subrev_u32_e32 v230, 32, v200
	v_subrev_u32_e32 v231, 35, v200
	v_subrev_u32_e32 v232, 34, v200
	v_subrev_u32_e32 v186, 48, v200
	v_max_i32_e32 v196, 0, v233
	v_subrev_u32_e32 v235, 50, v200
	ds_read_b32 v114, v112 offset:20480
	ds_read_b32 v115, v113 offset:20480
	ds_read_b32 v116, v116 offset:20480
	ds_read_b32 v117, v117 offset:20480
	ds_read_b32 v118, v118 offset:20480
	ds_read_b32 v119, v119 offset:20480
	ds_read_b32 v194, v184 offset:20480
	ds_read_b32 v195, v185 offset:20480
	v_max_i32_e32 v112, 0, v230
	v_max_i32_e32 v113, 0, v229
	v_max_i32_e32 v184, 0, v232
	v_max_i32_e32 v185, 0, v231
	v_max_i32_e32 v187, 0, v186
	v_lshl_add_u32 v234, v196, 2, v212
	v_max_i32_e32 v196, 0, v235
	v_subrev_u32_e32 v237, 51, v200
	v_lshl_add_u32 v112, v112, 2, v212
	v_lshl_add_u32 v113, v113, 2, v212
	v_lshl_add_u32 v184, v184, 2, v212
	v_lshl_add_u32 v185, v185, 2, v212
	v_lshl_add_u32 v187, v187, 2, v212
	v_lshl_add_u32 v236, v196, 2, v212
	v_max_i32_e32 v196, 0, v237
	v_lshl_add_u32 v238, v196, 2, v212
	ds_read_b32 v196, v112 offset:20480
	ds_read_b32 v197, v113 offset:20480
	ds_read_b32 v112, v184 offset:20480
	ds_read_b32 v113, v185 offset:20480
	ds_read_b32 v184, v187 offset:20480
	ds_read_b32 v185, v234 offset:20480
	ds_read_b32 v187, v236 offset:20480
	ds_read_b32 v234, v238 offset:20480
	v_cmp_lt_i32_e32 vcc, -1, v186
	s_waitcnt lgkmcnt(3)
	v_add_f32_e32 v184, v201, v184
	v_fmac_f32_e32 v184, 0x3e38aa3b, v96
	v_cndmask_b32_e32 v241, v209, v184, vcc
	s_waitcnt lgkmcnt(2)
	v_add_f32_e32 v184, v201, v185
	v_fmac_f32_e32 v184, 0x3e38aa3b, v97
	v_cmp_lt_i32_e32 vcc, -1, v233
	v_add_u32_e32 v242, 16, v200
	v_add_f32_e32 v188, v201, v114
	v_cndmask_b32_e32 v233, v209, v184, vcc
	s_waitcnt lgkmcnt(1)
	v_add_f32_e32 v184, v201, v187
	v_fmac_f32_e32 v184, 0x3e38aa3b, v98
	v_cmp_lt_i32_e32 vcc, -1, v235
	v_add_f32_e32 v189, v201, v115
	v_add_f32_e32 v217, v201, v116
	v_cndmask_b32_e32 v235, v209, v184, vcc
	s_waitcnt lgkmcnt(0)
	v_add_f32_e32 v184, v201, v234
	v_fmac_f32_e32 v184, 0x3e38aa3b, v99
	v_cmp_lt_i32_e32 vcc, -1, v237
	v_add_u32_e32 v237, 15, v200
	v_add_f32_e32 v220, v201, v117
	v_add_f32_e32 v223, v201, v118
	v_add_f32_e32 v225, v201, v119
	v_add_f32_e32 v227, v201, v194
	v_add_f32_e32 v228, v201, v195
	v_add_f32_e32 v236, v201, v196
	v_add_f32_e32 v238, v201, v197
	v_add_f32_e32 v239, v201, v112
	v_add_f32_e32 v240, v201, v113
	v_cndmask_b32_e32 v201, v209, v184, vcc
	v_max_i32_e32 v184, 0, v242
	v_max_i32_e32 v185, 0, v237
	v_lshl_add_u32 v184, v184, 2, v212
	v_lshl_add_u32 v185, v185, 2, v212
	v_add_u32_e32 v243, 13, v200
	v_add_u32_e32 v244, 14, v200
	ds_read_b32 v184, v184 offset:20480
	ds_read_b32 v185, v185 offset:20480
	v_max_i32_e32 v186, 0, v244
	v_max_i32_e32 v187, 0, v243
	v_lshl_add_u32 v186, v186, 2, v212
	v_lshl_add_u32 v187, v187, 2, v212
	ds_read_b32 v186, v186 offset:20480
	ds_read_b32 v187, v187 offset:20480
	s_waitcnt lgkmcnt(2)
	v_add_f32_e64 v184, v180, v184
	v_add_f32_e64 v185, v180, v185
	v_fma_f32 v184, v92, s28, v184
	v_fma_f32 v185, v93, s28, v185
	v_cmp_lt_i32_e32 vcc, -1, v242
	v_add_f32_e64 v114, v180, v114
	v_add_f32_e64 v115, v180, v115
	s_waitcnt lgkmcnt(0)
	v_add_f32_e64 v186, v180, v186
	v_add_f32_e64 v187, v180, v187
	v_cndmask_b32_e32 v184, v209, v184, vcc
	v_cmp_lt_i32_e32 vcc, -1, v237
	v_fma_f32 v186, v94, s28, v186
	v_fma_f32 v187, v95, s28, v187
	v_fmac_f32_e32 v188, 0x3e38aa3b, v108
	v_cndmask_b32_e32 v185, v209, v185, vcc
	v_cmp_lt_i32_e32 vcc, -1, v244
	v_fmac_f32_e32 v189, 0x3e38aa3b, v109
	v_cmp_lt_i32_e64 s[0:1], -1, v182
	v_cndmask_b32_e32 v186, v209, v186, vcc
	v_cmp_lt_i32_e32 vcc, -1, v243
	v_fma_f32 v114, v88, s28, v114
	v_fma_f32 v115, v89, s28, v115
	v_cndmask_b32_e64 v242, v209, v189, s[0:1]
	v_cndmask_b32_e32 v187, v209, v187, vcc
	v_cmp_lt_i32_e32 vcc, -1, v200
	v_cndmask_b32_e64 v189, v209, v115, s[0:1]
	v_fmac_f32_e32 v217, 0x3e38aa3b, v110
	v_cndmask_b32_e32 v200, v209, v188, vcc
	v_cndmask_b32_e32 v188, v209, v114, vcc
	v_add_f32_e64 v114, v180, v116
	v_add_f32_e64 v115, v180, v117
	v_fmac_f32_e32 v220, 0x3e38aa3b, v111
	v_cmp_lt_i32_e32 vcc, -1, v191
	v_cmp_lt_i32_e64 s[0:1], -1, v190
	v_fma_f32 v114, v90, s28, v114
	v_fma_f32 v115, v91, s28, v115
	v_fmac_f32_e32 v223, 0x3e38aa3b, v104
	v_fmac_f32_e32 v225, 0x3e38aa3b, v105
	v_max3_f32 v182, v200, s56, v242
	v_cndmask_b32_e32 v243, v209, v217, vcc
	v_cndmask_b32_e64 v220, v209, v220, s[0:1]
	v_cndmask_b32_e32 v190, v209, v114, vcc
	v_cndmask_b32_e64 v191, v209, v115, s[0:1]
	v_cmp_lt_i32_e32 vcc, -1, v192
	v_cmp_lt_i32_e64 s[0:1], -1, v193
	v_fmac_f32_e32 v227, 0x3e38aa3b, v106
	v_fmac_f32_e32 v228, 0x3e38aa3b, v107
	v_max3_f32 v182, v182, v243, v220
	v_cndmask_b32_e32 v117, v209, v223, vcc
	v_cndmask_b32_e64 v223, v209, v225, s[0:1]
	v_add_f32_e64 v114, v180, v118
	v_add_f32_e64 v115, v180, v119
	v_cmp_lt_i32_e64 s[4:5], -1, v199
	v_cmp_lt_i32_e64 s[6:7], -1, v198
	v_fmac_f32_e32 v236, 0x3e38aa3b, v100
	v_fmac_f32_e32 v238, 0x3e38aa3b, v101
	v_max3_f32 v182, v182, v117, v223
	v_fma_f32 v114, v84, s28, v114
	v_fma_f32 v115, v85, s28, v115
	v_cndmask_b32_e64 v118, v209, v227, s[4:5]
	v_cndmask_b32_e64 v119, v209, v228, s[6:7]
	v_cmp_lt_i32_e64 s[8:9], -1, v230
	v_cmp_lt_i32_e64 s[10:11], -1, v229
	v_fmac_f32_e32 v239, 0x3e38aa3b, v102
	v_fmac_f32_e32 v240, 0x3e38aa3b, v103
	v_cndmask_b32_e32 v192, v209, v114, vcc
	v_cndmask_b32_e64 v193, v209, v115, s[0:1]
	v_max3_f32 v182, v182, v118, v119
	v_cndmask_b32_e64 v198, v209, v236, s[8:9]
	v_cndmask_b32_e64 v199, v209, v238, s[10:11]
	v_cmp_lt_i32_e32 vcc, -1, v232
	v_cmp_lt_i32_e64 s[0:1], -1, v231
	v_max3_f32 v182, v182, v198, v199
	v_cndmask_b32_e32 v225, v209, v239, vcc
	v_cndmask_b32_e64 v227, v209, v240, s[0:1]
	v_max3_f32 v182, v182, v225, v227
	v_max3_f32 v182, v182, v241, v233
	v_max3_f32 v182, v182, v235, v201
	ds_bpermute_b32 v217, v213, v182
	v_add_f32_e64 v114, v180, v194
	v_add_f32_e64 v115, v180, v195
	v_fma_f32 v114, v86, s28, v114
	v_fma_f32 v115, v87, s28, v115
	v_max3_f32 v237, v184, s56, v185
	v_cndmask_b32_e64 v194, v209, v114, s[4:5]
	v_cndmask_b32_e64 v195, v209, v115, s[6:7]
	v_add_f32_e64 v114, v180, v196
	v_add_f32_e64 v115, v180, v197
	s_waitcnt lgkmcnt(0)
; DI float ex2(float x) { return __builtin_amdgcn_exp2f(x); }
; template <int NT, class F> DI void softmax_step(f32x4 (&S)[4][NT], float (&m)[NT], float (&l)[NT], float (&alpha)[NT], bf16x8 (&pb)[2][NT], F f) {
; #pragma unroll
;   for (int nt = 0; nt < NT; ++nt) {
;     float mx = -1e30f;
; #pragma unroll
;     for (int mt = 0; mt < 4; ++mt)
; #pragma unroll
;       for (int j = 0; j < 4; ++j) { const float s2 = f(mt, j, nt, S[mt][nt][j]); S[mt][nt][j] = s2; mx = fmaxf(mx, s2); }
;     mx = fmaxf(mx, __shfl_xor(mx, 16)); mx = fmaxf(mx, __shfl_xor(mx, 32));
;     const float mn = (mx > m[nt] + 8.0f) ? mx : m[nt];
;     alpha[nt] = ex2(m[nt] - mn); m[nt] = mn;
;     const float mexp = (mn < -1e29f) ? 0.f : mn;
;     float sum = 0.f;
; #pragma unroll
;     for (int mt = 0; mt < 4; ++mt)
; #pragma unroll
;       for (int j = 0; j < 4; ++j) { const float pv = ex2(S[mt][nt][j] - mexp); sum += pv; S[mt][nt][j] = pv; }
;     l[nt] = l[nt] * alpha[nt] + sum;
;     pb[0][nt] = pack8(S[0][nt], S[1][nt]);
;     pb[1][nt] = pack8(S[2][nt], S[3][nt]);
;   }
	v_max_f32_e32 v196, v217, v217
	v_max_f32_e32 v182, v182, v196
	ds_bpermute_b32 v217, v214, v182
	v_fma_f32 v114, v80, s28, v114
	v_fma_f32 v115, v81, s28, v115
	v_add_f32_e32 v234, 0x41000000, v221
	v_cndmask_b32_e64 v197, v209, v115, s[10:11]
	v_max3_f32 v237, v237, v186, v187
	s_waitcnt lgkmcnt(0)
	v_max_f32_e32 v115, v217, v217
	v_max_f32_e32 v115, v182, v115
	v_max3_f32 v237, v237, v188, v189
	v_cmp_gt_f32_e64 s[4:5], v115, v234
	v_max3_f32 v116, v237, v190, v191
	v_max3_f32 v116, v116, v192, v193
	v_cndmask_b32_e64 v217, v221, v115, s[4:5]
	v_sub_f32_e32 v115, v221, v217
	v_cmp_ngt_f32_e64 s[4:5], s57, v217
	v_max3_f32 v116, v116, v194, v195
	v_cndmask_b32_e64 v196, v209, v114, s[8:9]
	v_exp_f32_e32 v182, v115
	v_cndmask_b32_e64 v115, 0, v217, s[4:5]
	v_max3_f32 v114, v116, v196, v197
	v_sub_f32_e32 v116, v200, v115
	v_exp_f32_e32 v116, v116
	v_sub_f32_e32 v200, v242, v115
	v_exp_f32_e32 v200, v200
	v_sub_f32_e32 v228, v243, v115
	v_exp_f32_e32 v228, v228
	v_sub_f32_e32 v220, v220, v115
	v_exp_f32_e32 v229, v220
	v_sub_f32_e32 v117, v117, v115
	v_add_f32_e32 v220, 0, v116
	v_exp_f32_e32 v117, v117
	v_sub_f32_e32 v223, v223, v115
	v_add_f32_e32 v220, v200, v220
	v_exp_f32_e32 v223, v223
	v_sub_f32_e32 v118, v118, v115
	v_add_f32_e32 v220, v228, v220
	v_exp_f32_e32 v118, v118
	v_sub_f32_e32 v119, v119, v115
	v_add_f32_e32 v220, v229, v220
	v_exp_f32_e32 v119, v119
	v_sub_f32_e32 v198, v198, v115
	v_add_f32_e32 v220, v117, v220
	v_exp_f32_e32 v230, v198
	v_sub_f32_e32 v198, v199, v115
	v_add_f32_e32 v220, v223, v220
	v_exp_f32_e32 v231, v198
	v_sub_f32_e32 v198, v225, v115
	v_add_f32_e32 v220, v118, v220
	v_exp_f32_e32 v232, v198
	v_sub_f32_e32 v198, v227, v115
	v_add_f32_e32 v220, v119, v220
	v_exp_f32_e32 v227, v198
	v_sub_f32_e32 v199, v241, v115
	v_add_f32_e32 v198, v230, v220
	v_exp_f32_e32 v234, v199
	v_add_f32_e32 v198, v231, v198
	v_add_f32_e32 v198, v232, v198
	v_sub_f32_e32 v199, v233, v115
	v_add_f32_e64 v112, v180, v112
	v_add_f32_e64 v113, v180, v113
	v_add_f32_e32 v198, v227, v198
	v_exp_f32_e32 v233, v199
	v_sub_f32_e32 v199, v235, v115
	v_sub_f32_e32 v115, v201, v115
	v_fma_f32 v112, v82, s28, v112
	v_fma_f32 v113, v83, s28, v113
	v_exp_f32_e32 v235, v199
	v_exp_f32_e32 v201, v115
	v_add_f32_e32 v115, v234, v198
	v_cndmask_b32_e64 v199, v209, v113, s[0:1]
	v_cndmask_b32_e32 v198, v209, v112, vcc
	v_max3_f32 v180, v114, v198, v199
	ds_bpermute_b32 v225, v213, v180
	v_cvt_pk_bf16_f32 v112, v116, v200
	v_cvt_pk_bf16_f32 v114, v117, v223
	v_add_f32_e32 v115, v233, v115
	v_add_f32_e32 v115, v235, v115
	s_waitcnt lgkmcnt(0)
	v_max_f32_e32 v116, v225, v225
	v_max_f32_e32 v223, v180, v116
	ds_bpermute_b32 v225, v214, v223
	v_add_f32_e32 v220, v201, v115
	v_fmac_f32_e32 v220, v222, v182
	v_cvt_pk_bf16_f32 v113, v228, v229
	v_cvt_pk_bf16_f32 v115, v118, v119
	v_cvt_pk_bf16_f32 v116, v230, v231
	v_cvt_pk_bf16_f32 v117, v232, v227
	v_cvt_pk_bf16_f32 v118, v234, v233
	v_cvt_pk_bf16_f32 v119, v235, v201
.LBB0_750:
	s_waitcnt lgkmcnt(0)
	v_max_f32_e32 v180, v225, v225
	v_max_f32_e32 v200, v223, v223
	v_max_f32_e32 v180, v200, v180
	v_add_f32_e32 v200, 0x41000000, v224
	v_cmp_gt_f32_e32 vcc, v180, v200
	s_nop 1
	v_cndmask_b32_e32 v223, v224, v180, vcc
	v_cmp_ngt_f32_e32 vcc, s57, v223
	v_sub_f32_e32 v180, v224, v223
	v_exp_f32_e32 v180, v180
	v_cndmask_b32_e32 v229, 0, v223, vcc
	v_sub_f32_e32 v184, v184, v229
	v_exp_f32_e32 v184, v184
	v_sub_f32_e32 v185, v185, v229
	v_exp_f32_e32 v185, v185
	v_sub_f32_e32 v186, v186, v229
	v_exp_f32_e32 v186, v186
	v_sub_f32_e32 v187, v187, v229
	v_exp_f32_e32 v187, v187
	v_sub_f32_e32 v188, v188, v229
	v_add_f32_e32 v200, 0, v184
	v_exp_f32_e32 v188, v188
	v_sub_f32_e32 v189, v189, v229
	v_add_f32_e32 v200, v185, v200
	v_exp_f32_e32 v189, v189
	v_sub_f32_e32 v190, v190, v229
	v_add_f32_e32 v200, v186, v200
	v_exp_f32_e32 v190, v190
	v_sub_f32_e32 v191, v191, v229
	v_add_f32_e32 v200, v187, v200
	v_exp_f32_e32 v191, v191
	v_add_f32_e32 v200, v188, v200
	v_add_f32_e32 v200, v189, v200
	v_add_f32_e32 v200, v190, v200
	v_sub_f32_e32 v192, v192, v229
	v_add_f32_e32 v225, v191, v200
	v_exp_f32_e32 v200, v192
	v_sub_f32_e32 v192, v193, v229
	v_exp_f32_e32 v201, v192
	v_sub_f32_e32 v192, v194, v229
	v_exp_f32_e32 v194, v192
	v_sub_f32_e32 v192, v195, v229
	v_exp_f32_e32 v195, v192
	v_add_f32_e32 v192, v200, v225
	v_add_f32_e32 v192, v201, v192
	v_add_f32_e32 v192, v194, v192
	v_add_f32_e32 v193, v195, v192
	v_sub_f32_e32 v192, v196, v229
	v_exp_f32_e32 v196, v192
	v_sub_f32_e32 v192, v197, v229
	v_exp_f32_e32 v197, v192
	v_sub_f32_e32 v192, v198, v229
	v_exp_f32_e32 v192, v192
	v_add_f32_e32 v193, v196, v193
	v_add_f32_e32 v228, v197, v193
	v_add_f32_e64 v198, v198, -v228
	v_add_f32_e64 v199, v199, -v229
	s_nop 0
	v_add_f32_e32 v198, v192, v228

; DI f32x4 mfma16(bf16x8 a, bf16x8 b, f32x4 c) { return __builtin_amdgcn_mfma_f32_16x16x32_bf16(a, b, c, 0, 0, 0); }
; template <int NI, class XL, class EP>
; DI void gemm_tile(const u16* __restrict__ W, int ldw, int f0, int t0, int K, XL xl, EP ep, unsigned char* smem) {
;     ...
;   for (int it = 0; it < nk; ++it) {
;     const u16* Ws = S0 + (it & 1) * BUF; const u16* Xs = Ws + 128 * LST;
;     __builtin_amdgcn_s_setprio(1);
;     bf16x8 a[4];
; #pragma unroll
;     for (int mi = 0; mi < 4; ++mi) a[mi] = *(const bf16x8*)(Ws + (wf * 64 + mi * 16 + lr) * LST + lq * 8);
; #pragma unroll
;     for (int ni = 0; ni < NI; ++ni) {
;       const bf16x8 b = *(const bf16x8*)(Xs + (wt * (NI * 16) + ni * 16 + lr) * LST + lq * 8);
; #pragma unroll
;       for (int mi = 0; mi < 4; ++mi) acc[mi][ni] = mfma16(a[mi], b, acc[mi][ni]);
;     }
;     __builtin_amdgcn_sched_group_barrier(0x100, 6, 0);
; #pragma unroll
;     for (int ni = 0; ni < NI; ++ni) { __builtin_amdgcn_sched_group_barrier(0x008, 4, 0); if (ni + 2 < NI) __builtin_amdgcn_sched_group_barrier(0x100, 1, 0); }
;     __builtin_amdgcn_s_setprio(0);
;     if (it + 1 < nk) lstore((it + 1) & 1);
;     if (it + 2 < nk) gload(it + 2);
;     __syncthreads();
;   }
.LBB0_812:
	s_setprio 1
	ds_read_b128 v[168:171], v228 offset:0
	ds_read_b128 v[172:175], v228 offset:1536
	ds_read_b128 v[180:183], v228 offset:3072
	ds_read_b128 v[184:187], v228 offset:4608
	ds_read_b128 v[176:179], v152 offset:12288
	ds_read_b128 v[188:191], v152 offset:13824
	s_waitcnt lgkmcnt(1)
	v_mfma_f32_16x16x32_bf16 v[148:151], v[168:171], v[176:179], v[148:151]
	v_mfma_f32_16x16x32_bf16 v[136:139], v[172:175], v[176:179], v[136:139]
	v_mfma_f32_16x16x32_bf16 v[112:115], v[180:183], v[176:179], v[112:115]
	v_mfma_f32_16x16x32_bf16 v[80:83], v[184:187], v[176:179], v[80:83]
	ds_read_b128 v[176:179], v152 offset:15360
	s_waitcnt vmcnt(6)
	ds_write_b128 v229, v[20:23] offset:36864
	s_waitcnt lgkmcnt(2)
	v_mfma_f32_16x16x32_bf16 v[144:147], v[168:171], v[188:191], v[144:147]
	v_mfma_f32_16x16x32_bf16 v[128:131], v[172:175], v[188:191], v[128:131]
	v_mfma_f32_16x16x32_bf16 v[100:103], v[180:183], v[188:191], v[100:103]
	v_mfma_f32_16x16x32_bf16 v[68:71], v[184:187], v[188:191], v[68:71]
	ds_read_b128 v[188:191], v152 offset:16896
	ds_write_b128 v229, v[16:19] offset:36960
	global_load_dwordx4 v[20:23], v154, s[98:99]
	global_load_dwordx4 v[16:19], v154, s[98:99] offset:64
	s_waitcnt lgkmcnt(3)
	v_mfma_f32_16x16x32_bf16 v[140:143], v[168:171], v[176:179], v[140:143]
	v_mfma_f32_16x16x32_bf16 v[120:123], v[172:175], v[176:179], v[120:123]
	v_mfma_f32_16x16x32_bf16 v[88:91], v[180:183], v[176:179], v[88:91]
	v_mfma_f32_16x16x32_bf16 v[44:47], v[184:187], v[176:179], v[44:47]
	ds_read_b128 v[176:179], v152 offset:18432
	ds_write_b128 v230, v[36:39] offset:49152
	global_load_dwordx4 v[36:39], v156, s[100:101] offset:2048
	s_waitcnt lgkmcnt(3)
	v_mfma_f32_16x16x32_bf16 v[132:135], v[168:171], v[188:191], v[132:135]
	v_mfma_f32_16x16x32_bf16 v[108:111], v[172:175], v[188:191], v[108:111]
	v_mfma_f32_16x16x32_bf16 v[76:79], v[180:183], v[188:191], v[76:79]
	v_mfma_f32_16x16x32_bf16 v[40:43], v[184:187], v[188:191], v[40:43]
	ds_read_b128 v[188:191], v152 offset:19968
	ds_write_b128 v230, v[32:35] offset:49248
	global_load_dwordx4 v[32:35], v156, s[100:101] offset:2112
	s_waitcnt lgkmcnt(3)
	v_mfma_f32_16x16x32_bf16 v[124:127], v[168:171], v[176:179], v[124:127]
	v_mfma_f32_16x16x32_bf16 v[96:99], v[172:175], v[176:179], v[96:99]
	v_mfma_f32_16x16x32_bf16 v[64:67], v[180:183], v[176:179], v[64:67]
	v_mfma_f32_16x16x32_bf16 v[12:15], v[184:187], v[176:179], v[12:15]
	ds_read_b128 v[176:179], v152 offset:21504
	ds_write_b128 v230, v[28:31] offset:49344
	global_load_dwordx4 v[28:31], v156, s[100:101] offset:2176
	s_waitcnt lgkmcnt(3)
	v_mfma_f32_16x16x32_bf16 v[116:119], v[168:171], v[188:191], v[116:119]
	v_mfma_f32_16x16x32_bf16 v[84:87], v[172:175], v[188:191], v[84:87]
	v_mfma_f32_16x16x32_bf16 v[56:59], v[180:183], v[188:191], v[56:59]
	v_mfma_f32_16x16x32_bf16 v[8:11], v[184:187], v[188:191], v[8:11]
	ds_read_b128 v[188:191], v152 offset:23040
	ds_write_b128 v230, v[24:27] offset:49440
	global_load_dwordx4 v[24:27], v156, s[100:101] offset:2240
	s_waitcnt lgkmcnt(3)
	v_mfma_f32_16x16x32_bf16 v[104:107], v[168:171], v[176:179], v[104:107]
	v_mfma_f32_16x16x32_bf16 v[72:75], v[172:175], v[176:179], v[72:75]
	v_mfma_f32_16x16x32_bf16 v[52:55], v[180:183], v[176:179], v[52:55]
	v_mfma_f32_16x16x32_bf16 v[4:7], v[184:187], v[176:179], v[4:7]
	s_add_u32 s98, s98, s18
	s_addc_u32 s99, s99, s19
	s_add_u32 s100, s100, s10
	s_addc_u32 s101, s101, s11
	s_waitcnt lgkmcnt(1)
	v_mfma_f32_16x16x32_bf16 v[92:95], v[168:171], v[188:191], v[92:95]
	v_mfma_f32_16x16x32_bf16 v[60:63], v[172:175], v[188:191], v[60:63]
	v_mfma_f32_16x16x32_bf16 v[48:51], v[180:183], v[188:191], v[48:51]
	v_mfma_f32_16x16x32_bf16 v[0:3], v[184:187], v[188:191], v[0:3]
	s_setprio 0
	s_waitcnt lgkmcnt(0)
	s_barrier
	s_setprio 1
	ds_read_b128 v[168:171], v228 offset:36864
	ds_read_b128 v[172:175], v228 offset:38400
	ds_read_b128 v[180:183], v228 offset:39936
	ds_read_b128 v[184:187], v228 offset:41472
	ds_read_b128 v[176:179], v152 offset:49152
	ds_read_b128 v[188:191], v152 offset:50688
	s_waitcnt lgkmcnt(1)
	v_mfma_f32_16x16x32_bf16 v[148:151], v[168:171], v[176:179], v[148:151]
	v_mfma_f32_16x16x32_bf16 v[136:139], v[172:175], v[176:179], v[136:139]
	v_mfma_f32_16x16x32_bf16 v[112:115], v[180:183], v[176:179], v[112:115]
	v_mfma_f32_16x16x32_bf16 v[80:83], v[184:187], v[176:179], v[80:83]
	ds_read_b128 v[176:179], v152 offset:52224
	s_waitcnt vmcnt(6)
	ds_write_b128 v229, v[200:203] offset:0
	s_waitcnt lgkmcnt(2)
	v_mfma_f32_16x16x32_bf16 v[144:147], v[168:171], v[188:191], v[144:147]
	v_mfma_f32_16x16x32_bf16 v[128:131], v[172:175], v[188:191], v[128:131]
	v_mfma_f32_16x16x32_bf16 v[100:103], v[180:183], v[188:191], v[100:103]
	v_mfma_f32_16x16x32_bf16 v[68:71], v[184:187], v[188:191], v[68:71]
	ds_read_b128 v[188:191], v152 offset:53760
	ds_write_b128 v229, v[204:207] offset:96
	global_load_dwordx4 v[200:203], v154, s[98:99]
	global_load_dwordx4 v[204:207], v154, s[98:99] offset:64
	s_waitcnt lgkmcnt(3)
	v_mfma_f32_16x16x32_bf16 v[140:143], v[168:171], v[176:179], v[140:143]
	v_mfma_f32_16x16x32_bf16 v[120:123], v[172:175], v[176:179], v[120:123]
	v_mfma_f32_16x16x32_bf16 v[88:91], v[180:183], v[176:179], v[88:91]
	v_mfma_f32_16x16x32_bf16 v[44:47], v[184:187], v[176:179], v[44:47]
	ds_read_b128 v[176:179], v152 offset:55296
	ds_write_b128 v230, v[208:211] offset:12288
	global_load_dwordx4 v[208:211], v156, s[100:101] offset:2048
	s_waitcnt lgkmcnt(3)
; DI f32x4 mfma16(bf16x8 a, bf16x8 b, f32x4 c) { return __builtin_amdgcn_mfma_f32_16x16x32_bf16(a, b, c, 0, 0, 0); }
; template <int NI, class XL, class EP>
; DI void gemm_tile(const u16* __restrict__ W, int ldw, int f0, int t0, int K, XL xl, EP ep, unsigned char* smem) {
;     ...
;   for (int it = 0; it < nk; ++it) {
;     const u16* Ws = S0 + (it & 1) * BUF; const u16* Xs = Ws + 128 * LST;
;     __builtin_amdgcn_s_setprio(1);
;     bf16x8 a[4];
; #pragma unroll
;     for (int mi = 0; mi < 4; ++mi) a[mi] = *(const bf16x8*)(Ws + (wf * 64 + mi * 16 + lr) * LST + lq * 8);
; #pragma unroll
;     for (int ni = 0; ni < NI; ++ni) {
;       const bf16x8 b = *(const bf16x8*)(Xs + (wt * (NI * 16) + ni * 16 + lr) * LST + lq * 8);
; #pragma unroll
;       for (int mi = 0; mi < 4; ++mi) acc[mi][ni] = mfma16(a[mi], b, acc[mi][ni]);
;     }
;     __builtin_amdgcn_sched_group_barrier(0x100, 6, 0);
; #pragma unroll
;     for (int ni = 0; ni < NI; ++ni) { __builtin_amdgcn_sched_group_barrier(0x008, 4, 0); if (ni + 2 < NI) __builtin_amdgcn_sched_group_barrier(0x100, 1, 0); }
;     __builtin_amdgcn_s_setprio(0);
;     if (it + 1 < nk) lstore((it + 1) & 1);
;     if (it + 2 < nk) gload(it + 2);
;     __syncthreads();
;   }
	v_mfma_f32_16x16x32_bf16 v[132:135], v[168:171], v[188:191], v[132:135]
	v_mfma_f32_16x16x32_bf16 v[108:111], v[172:175], v[188:191], v[108:111]
	v_mfma_f32_16x16x32_bf16 v[76:79], v[180:183], v[188:191], v[76:79]
	v_mfma_f32_16x16x32_bf16 v[40:43], v[184:187], v[188:191], v[40:43]
	ds_read_b128 v[188:191], v152 offset:56832
	ds_write_b128 v230, v[212:215] offset:12384
	global_load_dwordx4 v[212:215], v156, s[100:101] offset:2112
	s_waitcnt lgkmcnt(3)
	v_mfma_f32_16x16x32_bf16 v[124:127], v[168:171], v[176:179], v[124:127]
	v_mfma_f32_16x16x32_bf16 v[96:99], v[172:175], v[176:179], v[96:99]
	v_mfma_f32_16x16x32_bf16 v[64:67], v[180:183], v[176:179], v[64:67]
	v_mfma_f32_16x16x32_bf16 v[12:15], v[184:187], v[176:179], v[12:15]
	ds_read_b128 v[176:179], v152 offset:58368
	ds_write_b128 v230, v[220:223] offset:12480
	global_load_dwordx4 v[220:223], v156, s[100:101] offset:2176
	s_waitcnt lgkmcnt(3)
	v_mfma_f32_16x16x32_bf16 v[116:119], v[168:171], v[188:191], v[116:119]
	v_mfma_f32_16x16x32_bf16 v[84:87], v[172:175], v[188:191], v[84:87]
	v_mfma_f32_16x16x32_bf16 v[56:59], v[180:183], v[188:191], v[56:59]
	v_mfma_f32_16x16x32_bf16 v[8:11], v[184:187], v[188:191], v[8:11]
	ds_read_b128 v[188:191], v152 offset:59904
	ds_write_b128 v230, v[224:227] offset:12576
	global_load_dwordx4 v[224:227], v156, s[100:101] offset:2240
	s_waitcnt lgkmcnt(3)
	v_mfma_f32_16x16x32_bf16 v[104:107], v[168:171], v[176:179], v[104:107]
	v_mfma_f32_16x16x32_bf16 v[72:75], v[172:175], v[176:179], v[72:75]
	v_mfma_f32_16x16x32_bf16 v[52:55], v[180:183], v[176:179], v[52:55]
	v_mfma_f32_16x16x32_bf16 v[4:7], v[184:187], v[176:179], v[4:7]
	s_add_u32 s98, s98, s18
	s_addc_u32 s99, s99, s19
	s_add_u32 s100, s100, s10
	s_addc_u32 s101, s101, s11
	s_add_i32 s36, s36, 2
	s_waitcnt lgkmcnt(1)
	v_mfma_f32_16x16x32_bf16 v[92:95], v[168:171], v[188:191], v[92:95]
	v_mfma_f32_16x16x32_bf16 v[60:63], v[172:175], v[188:191], v[60:63]
	v_mfma_f32_16x16x32_bf16 v[48:51], v[180:183], v[188:191], v[48:51]
	v_mfma_f32_16x16x32_bf16 v[0:3], v[184:187], v[188:191], v[0:3]
	s_setprio 0
	s_cmp_lg_u32 s36, 29
	s_waitcnt lgkmcnt(0)
	s_barrier
	s_cbranch_scc1 .LBB0_812
	s_setprio 1
	ds_read_b128 v[168:171], v228 offset:0
	ds_read_b128 v[172:175], v228 offset:1536
	ds_read_b128 v[180:183], v228 offset:3072
	ds_read_b128 v[184:187], v228 offset:4608
	ds_read_b128 v[176:179], v152 offset:12288
	ds_read_b128 v[188:191], v152 offset:13824
	s_waitcnt lgkmcnt(1)
	v_mfma_f32_16x16x32_bf16 v[148:151], v[168:171], v[176:179], v[148:151]
	v_mfma_f32_16x16x32_bf16 v[136:139], v[172:175], v[176:179], v[136:139]
	v_mfma_f32_16x16x32_bf16 v[112:115], v[180:183], v[176:179], v[112:115]
	v_mfma_f32_16x16x32_bf16 v[80:83], v[184:187], v[176:179], v[80:83]
	ds_read_b128 v[176:179], v152 offset:15360
	s_waitcnt vmcnt(6)
	ds_write_b128 v229, v[20:23] offset:36864
	s_waitcnt lgkmcnt(2)
	v_mfma_f32_16x16x32_bf16 v[144:147], v[168:171], v[188:191], v[144:147]
	v_mfma_f32_16x16x32_bf16 v[128:131], v[172:175], v[188:191], v[128:131]
	v_mfma_f32_16x16x32_bf16 v[100:103], v[180:183], v[188:191], v[100:103]
	v_mfma_f32_16x16x32_bf16 v[68:71], v[184:187], v[188:191], v[68:71]
	ds_read_b128 v[188:191], v152 offset:16896
	ds_write_b128 v229, v[16:19] offset:36960
	global_load_dwordx4 v[20:23], v154, s[98:99]
	global_load_dwordx4 v[16:19], v154, s[98:99] offset:64
	s_waitcnt lgkmcnt(3)
	v_mfma_f32_16x16x32_bf16 v[140:143], v[168:171], v[176:179], v[140:143]
	v_mfma_f32_16x16x32_bf16 v[120:123], v[172:175], v[176:179], v[120:123]
	v_mfma_f32_16x16x32_bf16 v[88:91], v[180:183], v[176:179], v[88:91]
	v_mfma_f32_16x16x32_bf16 v[44:47], v[184:187], v[176:179], v[44:47]
	ds_read_b128 v[176:179], v152 offset:18432
	ds_write_b128 v230, v[36:39] offset:49152
	global_load_dwordx4 v[36:39], v156, s[100:101] offset:2048
	s_waitcnt lgkmcnt(3)
	v_mfma_f32_16x16x32_bf16 v[132:135], v[168:171], v[188:191], v[132:135]
	v_mfma_f32_16x16x32_bf16 v[108:111], v[172:175], v[188:191], v[108:111]
	v_mfma_f32_16x16x32_bf16 v[76:79], v[180:183], v[188:191], v[76:79]
	v_mfma_f32_16x16x32_bf16 v[40:43], v[184:187], v[188:191], v[40:43]
	ds_read_b128 v[188:191], v152 offset:19968
	ds_write_b128 v230, v[32:35] offset:49248
	global_load_dwordx4 v[32:35], v156, s[100:101] offset:2112
	s_waitcnt lgkmcnt(3)
	v_mfma_f32_16x16x32_bf16 v[124:127], v[168:171], v[176:179], v[124:127]
	v_mfma_f32_16x16x32_bf16 v[96:99], v[172:175], v[176:179], v[96:99]
	v_mfma_f32_16x16x32_bf16 v[64:67], v[180:183], v[176:179], v[64:67]
	v_mfma_f32_16x16x32_bf16 v[12:15], v[184:187], v[176:179], v[12:15]
	ds_read_b128 v[176:179], v152 offset:21504
	ds_write_b128 v230, v[28:31] offset:49344
	global_load_dwordx4 v[28:31], v156, s[100:101] offset:2176
	s_waitcnt lgkmcnt(3)
	v_mfma_f32_16x16x32_bf16 v[116:119], v[168:171], v[188:191], v[116:119]
	v_mfma_f32_16x16x32_bf16 v[84:87], v[172:175], v[188:191], v[84:87]
	v_mfma_f32_16x16x32_bf16 v[56:59], v[180:183], v[188:191], v[56:59]
	v_mfma_f32_16x16x32_bf16 v[8:11], v[184:187], v[188:191], v[8:11]
	ds_read_b128 v[188:191], v152 offset:23040
	ds_write_b128 v230, v[24:27] offset:49440
	global_load_dwordx4 v[24:27], v156, s[100:101] offset:2240
	s_waitcnt lgkmcnt(3)
	v_mfma_f32_16x16x32_bf16 v[104:107], v[168:171], v[176:179], v[104:107]
	v_mfma_f32_16x16x32_bf16 v[72:75], v[172:175], v[176:179], v[72:75]
	v_mfma_f32_16x16x32_bf16 v[52:55], v[180:183], v[176:179], v[52:55]
	v_mfma_f32_16x16x32_bf16 v[4:7], v[184:187], v[176:179], v[4:7]
	s_add_u32 s98, s98, s18
	s_addc_u32 s99, s99, s19
	s_add_u32 s100, s100, s10
	s_addc_u32 s101, s101, s11
	s_waitcnt lgkmcnt(1)
	v_mfma_f32_16x16x32_bf16 v[92:95], v[168:171], v[188:191], v[92:95]
	v_mfma_f32_16x16x32_bf16 v[60:63], v[172:175], v[188:191], v[60:63]
	v_mfma_f32_16x16x32_bf16 v[48:51], v[180:183], v[188:191], v[48:51]
	v_mfma_f32_16x16x32_bf16 v[0:3], v[184:187], v[188:191], v[0:3]
	s_setprio 0
	s_waitcnt lgkmcnt(0)
	s_barrier
; DI f32x4 mfma16(bf16x8 a, bf16x8 b, f32x4 c) { return __builtin_amdgcn_mfma_f32_16x16x32_bf16(a, b, c, 0, 0, 0); }
; template <int NI, class XL, class EP>
; DI void gemm_tile(const u16* __restrict__ W, int ldw, int f0, int t0, int K, XL xl, EP ep, unsigned char* smem) {
;     ...
;   for (int it = 0; it < nk; ++it) {
;     const u16* Ws = S0 + (it & 1) * BUF; const u16* Xs = Ws + 128 * LST;
;     __builtin_amdgcn_s_setprio(1);
;     bf16x8 a[4];
; #pragma unroll
;     for (int mi = 0; mi < 4; ++mi) a[mi] = *(const bf16x8*)(Ws + (wf * 64 + mi * 16 + lr) * LST + lq * 8);
; #pragma unroll
;     for (int ni = 0; ni < NI; ++ni) {
;       const bf16x8 b = *(const bf16x8*)(Xs + (wt * (NI * 16) + ni * 16 + lr) * LST + lq * 8);
; #pragma unroll
;       for (int mi = 0; mi < 4; ++mi) acc[mi][ni] = mfma16(a[mi], b, acc[mi][ni]);
;     }
;     __builtin_amdgcn_sched_group_barrier(0x100, 6, 0);
; #pragma unroll
;     for (int ni = 0; ni < NI; ++ni) { __builtin_amdgcn_sched_group_barrier(0x008, 4, 0); if (ni + 2 < NI) __builtin_amdgcn_sched_group_barrier(0x100, 1, 0); }
;     __builtin_amdgcn_s_setprio(0);
;     if (it + 1 < nk) lstore((it + 1) & 1);
;     if (it + 2 < nk) gload(it + 2);
;     __syncthreads();
;   }
	s_setprio 1
	ds_read_b128 v[168:171], v228 offset:36864
	ds_read_b128 v[172:175], v228 offset:38400
	ds_read_b128 v[180:183], v228 offset:39936
	ds_read_b128 v[184:187], v228 offset:41472
	ds_read_b128 v[176:179], v152 offset:49152
	ds_read_b128 v[188:191], v152 offset:50688
	s_waitcnt lgkmcnt(1)
	v_mfma_f32_16x16x32_bf16 v[148:151], v[168:171], v[176:179], v[148:151]
	v_mfma_f32_16x16x32_bf16 v[136:139], v[172:175], v[176:179], v[136:139]
	v_mfma_f32_16x16x32_bf16 v[112:115], v[180:183], v[176:179], v[112:115]
	v_mfma_f32_16x16x32_bf16 v[80:83], v[184:187], v[176:179], v[80:83]
	ds_read_b128 v[176:179], v152 offset:52224
	s_waitcnt vmcnt(6)
	ds_write_b128 v229, v[200:203] offset:0
	s_waitcnt lgkmcnt(2)
	v_mfma_f32_16x16x32_bf16 v[144:147], v[168:171], v[188:191], v[144:147]
	v_mfma_f32_16x16x32_bf16 v[128:131], v[172:175], v[188:191], v[128:131]
	v_mfma_f32_16x16x32_bf16 v[100:103], v[180:183], v[188:191], v[100:103]
	v_mfma_f32_16x16x32_bf16 v[68:71], v[184:187], v[188:191], v[68:71]
	ds_read_b128 v[188:191], v152 offset:53760
	ds_write_b128 v229, v[204:207] offset:96
	s_waitcnt lgkmcnt(3)
	v_mfma_f32_16x16x32_bf16 v[140:143], v[168:171], v[176:179], v[140:143]
	v_mfma_f32_16x16x32_bf16 v[120:123], v[172:175], v[176:179], v[120:123]
	v_mfma_f32_16x16x32_bf16 v[88:91], v[180:183], v[176:179], v[88:91]
	v_mfma_f32_16x16x32_bf16 v[44:47], v[184:187], v[176:179], v[44:47]
	ds_read_b128 v[176:179], v152 offset:55296
	ds_write_b128 v230, v[208:211] offset:12288
	s_waitcnt lgkmcnt(3)
	v_mfma_f32_16x16x32_bf16 v[132:135], v[168:171], v[188:191], v[132:135]
	v_mfma_f32_16x16x32_bf16 v[108:111], v[172:175], v[188:191], v[108:111]
	v_mfma_f32_16x16x32_bf16 v[76:79], v[180:183], v[188:191], v[76:79]
	v_mfma_f32_16x16x32_bf16 v[40:43], v[184:187], v[188:191], v[40:43]
	ds_read_b128 v[188:191], v152 offset:56832
	ds_write_b128 v230, v[212:215] offset:12384
	s_waitcnt lgkmcnt(3)
	v_mfma_f32_16x16x32_bf16 v[124:127], v[168:171], v[176:179], v[124:127]
	v_mfma_f32_16x16x32_bf16 v[96:99], v[172:175], v[176:179], v[96:99]
	v_mfma_f32_16x16x32_bf16 v[64:67], v[180:183], v[176:179], v[64:67]
	v_mfma_f32_16x16x32_bf16 v[12:15], v[184:187], v[176:179], v[12:15]
	ds_read_b128 v[176:179], v152 offset:58368
	ds_write_b128 v230, v[220:223] offset:12480
	s_waitcnt lgkmcnt(3)
	v_mfma_f32_16x16x32_bf16 v[116:119], v[168:171], v[188:191], v[116:119]
	v_mfma_f32_16x16x32_bf16 v[84:87], v[172:175], v[188:191], v[84:87]
	v_mfma_f32_16x16x32_bf16 v[56:59], v[180:183], v[188:191], v[56:59]
	v_mfma_f32_16x16x32_bf16 v[8:11], v[184:187], v[188:191], v[8:11]
	ds_read_b128 v[188:191], v152 offset:59904
	ds_write_b128 v230, v[224:227] offset:12576
	s_waitcnt lgkmcnt(3)
	v_mfma_f32_16x16x32_bf16 v[104:107], v[168:171], v[176:179], v[104:107]
	v_mfma_f32_16x16x32_bf16 v[72:75], v[172:175], v[176:179], v[72:75]
	v_mfma_f32_16x16x32_bf16 v[52:55], v[180:183], v[176:179], v[52:55]
	v_mfma_f32_16x16x32_bf16 v[4:7], v[184:187], v[176:179], v[4:7]
	s_add_i32 s36, s36, 2
	s_waitcnt lgkmcnt(1)
	v_mfma_f32_16x16x32_bf16 v[92:95], v[168:171], v[188:191], v[92:95]
	v_mfma_f32_16x16x32_bf16 v[60:63], v[172:175], v[188:191], v[60:63]
	v_mfma_f32_16x16x32_bf16 v[48:51], v[180:183], v[188:191], v[48:51]
	v_mfma_f32_16x16x32_bf16 v[0:3], v[184:187], v[188:191], v[0:3]
	s_setprio 0
	s_waitcnt lgkmcnt(0)
	s_barrier
	s_setprio 1
	v_lshl_add_u32 v152, v167, 1, v164
	ds_read_b128 v[154:157], v152
	v_lshl_add_u32 v161, v165, 1, v164
	ds_read_b128 v[164:167], v152 offset:1536
	ds_read_b128 v[172:175], v152 offset:3072
	ds_read_b128 v[176:179], v152 offset:4608
	ds_read_b128 v[168:171], v161 offset:12288
	ds_read_b128 v[180:183], v161 offset:13824
	s_waitcnt lgkmcnt(1)
	v_mfma_f32_16x16x32_bf16 v[148:151], v[154:157], v[168:171], v[148:151]
	v_mfma_f32_16x16x32_bf16 v[136:139], v[164:167], v[168:171], v[136:139]
	v_mfma_f32_16x16x32_bf16 v[112:115], v[172:175], v[168:171], v[112:115]
	v_mfma_f32_16x16x32_bf16 v[80:83], v[176:179], v[168:171], v[80:83]
	ds_read_b128 v[168:171], v161 offset:15360
	s_waitcnt vmcnt(5)
	ds_write_b128 v162, v[20:23] offset:36864
	s_waitcnt lgkmcnt(2)
	v_mfma_f32_16x16x32_bf16 v[144:147], v[154:157], v[180:183], v[144:147]
	v_mfma_f32_16x16x32_bf16 v[128:131], v[164:167], v[180:183], v[128:131]
	v_mfma_f32_16x16x32_bf16 v[100:103], v[172:175], v[180:183], v[100:103]
	v_mfma_f32_16x16x32_bf16 v[68:71], v[176:179], v[180:183], v[68:71]
	ds_read_b128 v[180:183], v161 offset:16896
	s_waitcnt vmcnt(4)
	ds_write_b128 v162, v[16:19] offset:36960
	s_waitcnt lgkmcnt(3)
	v_mfma_f32_16x16x32_bf16 v[140:143], v[154:157], v[168:171], v[140:143]
	v_mfma_f32_16x16x32_bf16 v[120:123], v[164:167], v[168:171], v[120:123]
	v_mfma_f32_16x16x32_bf16 v[184:187], v[172:175], v[168:171], v[88:91]
	v_mfma_f32_16x16x32_bf16 v[44:47], v[176:179], v[168:171], v[44:47]
	s_nop 1
	ds_read_b128 v[88:91], v161 offset:18432
	s_waitcnt vmcnt(3)
	ds_write_b128 v163, v[36:39] offset:49152
	s_waitcnt lgkmcnt(3)
	v_mfma_f32_16x16x32_bf16 v[132:135], v[154:157], v[180:183], v[132:135]
	v_mfma_f32_16x16x32_bf16 v[168:171], v[164:167], v[180:183], v[108:111]
	v_mfma_f32_16x16x32_bf16 v[188:191], v[172:175], v[180:183], v[76:79]
	v_mfma_f32_16x16x32_bf16 v[180:183], v[176:179], v[180:183], v[40:43]
	s_nop 2
	ds_read_b128 v[40:43], v161 offset:19968
	s_waitcnt vmcnt(2)
	ds_write_b128 v163, v[32:35] offset:49248
	s_waitcnt lgkmcnt(3)
	v_mfma_f32_16x16x32_bf16 v[124:127], v[154:157], v[88:91], v[124:127]
	v_mfma_f32_16x16x32_bf16 v[192:195], v[164:167], v[88:91], v[96:99]
	v_mfma_f32_16x16x32_bf16 v[196:199], v[172:175], v[88:91], v[64:67]
	v_mfma_f32_16x16x32_bf16 v[200:203], v[176:179], v[88:91], v[12:15]
	s_nop 2
	ds_read_b128 v[12:15], v161 offset:21504
	s_waitcnt vmcnt(1)
	ds_write_b128 v163, v[28:31] offset:49344
	s_waitcnt lgkmcnt(3)
	v_mfma_f32_16x16x32_bf16 v[116:119], v[154:157], v[40:43], v[116:119]
	v_mfma_f32_16x16x32_bf16 v[204:207], v[164:167], v[40:43], v[84:87]
	v_mfma_f32_16x16x32_bf16 v[56:59], v[172:175], v[40:43], v[56:59]
	v_mfma_f32_16x16x32_bf16 v[208:211], v[176:179], v[40:43], v[8:11]
	s_nop 2
	ds_read_b128 v[8:11], v161 offset:23040
	s_waitcnt vmcnt(0)
	ds_write_b128 v163, v[24:27] offset:49440
	s_waitcnt lgkmcnt(3)
	v_mfma_f32_16x16x32_bf16 v[212:215], v[154:157], v[12:15], v[104:107]
	v_mfma_f32_16x16x32_bf16 v[72:75], v[164:167], v[12:15], v[72:75]
	v_mfma_f32_16x16x32_bf16 v[220:223], v[172:175], v[12:15], v[52:55]
	v_mfma_f32_16x16x32_bf16 v[224:227], v[176:179], v[12:15], v[4:7]
	s_waitcnt lgkmcnt(1)
	v_mfma_f32_16x16x32_bf16 v[154:157], v[154:157], v[8:11], v[92:95]
	v_mfma_f32_16x16x32_bf16 v[60:63], v[164:167], v[8:11], v[60:63]
	v_mfma_f32_16x16x32_bf16 v[164:167], v[172:175], v[8:11], v[48:51]
	v_mfma_f32_16x16x32_bf16 v[172:175], v[176:179], v[8:11], v[0:3]
	s_setprio 0
	s_waitcnt lgkmcnt(0)
	s_barrier
; DI void store4(u16* dst, f32x4 v) { uint2 w; w.x = cvtpk(v[0], v[1]); w.y = cvtpk(v[2], v[3]); *(uint2*)dst = w; }
; DI f32x4 mfma16(bf16x8 a, bf16x8 b, f32x4 c) { return __builtin_amdgcn_mfma_f32_16x16x32_bf16(a, b, c, 0, 0, 0); }
; template <int NI, class XL, class EP>
; DI void gemm_tile(const u16* __restrict__ W, int ldw, int f0, int t0, int K, XL xl, EP ep, unsigned char* smem) {
;     ...
;   for (int it = 0; it < nk; ++it) {
;     const u16* Ws = S0 + (it & 1) * BUF; const u16* Xs = Ws + 128 * LST;
;     __builtin_amdgcn_s_setprio(1);
;     bf16x8 a[4];
; #pragma unroll
;     for (int mi = 0; mi < 4; ++mi) a[mi] = *(const bf16x8*)(Ws + (wf * 64 + mi * 16 + lr) * LST + lq * 8);
; #pragma unroll
;     for (int ni = 0; ni < NI; ++ni) {
;       const bf16x8 b = *(const bf16x8*)(Xs + (wt * (NI * 16) + ni * 16 + lr) * LST + lq * 8);
; #pragma unroll
;       for (int mi = 0; mi < 4; ++mi) acc[mi][ni] = mfma16(a[mi], b, acc[mi][ni]);
;     }
;     __builtin_amdgcn_sched_group_barrier(0x100, 6, 0);
; #pragma unroll
;     for (int ni = 0; ni < NI; ++ni) { __builtin_amdgcn_sched_group_barrier(0x008, 4, 0); if (ni + 2 < NI) __builtin_amdgcn_sched_group_barrier(0x100, 1, 0); }
;     __builtin_amdgcn_s_setprio(0);
;     if (it + 1 < nk) lstore((it + 1) & 1);
;     if (it + 2 < nk) gload(it + 2);
;     __syncthreads();
;   }
;   ep(acc, f0 + wf * 64, t0 + wt * (NI * 16), lr, lq, wf, wt);
; DI void phase6(const Params& p, const Sched& sched, unsigned char* smem) {
;     ...
; #pragma unroll
;       for (int mi = 0; mi < 4; ++mi) {
;         const int f = fb + mi * 16 + lq * 4; const float4 gm = *(const float4*)(mod + (size_t)b * 6144 + 2048 + f);
; #pragma unroll
;         for (int ni = 0; ni < 8; ++ni) {
;           const f32x4 o = {gm.x * acc[mi][ni][0], gm.y * acc[mi][ni][1], gm.z * acc[mi][ni][2], gm.w * acc[mi][ni][3]};
;           store4(Ls + (wt * 128 + ni * 16 + lr) * EST + wf * 64 + mi * 16 + lq * 4, o);
;         }
;       }
	s_lshl_b32 s34, s34, 7
	s_setprio 1
	ds_read_b128 v[28:31], v152 offset:36864
	ds_read_b128 v[176:179], v152 offset:38400
	ds_read_b128 v[228:231], v152 offset:39936
	ds_read_b128 v[232:235], v152 offset:41472
	ds_read_b128 v[0:3], v161 offset:49152
	ds_read_b128 v[4:7], v161 offset:50688
	s_waitcnt lgkmcnt(1)
	v_mfma_f32_16x16x32_bf16 v[88:91], v[28:31], v[0:3], v[148:151]
	v_mfma_f32_16x16x32_bf16 v[64:67], v[176:179], v[0:3], v[136:139]
	v_mfma_f32_16x16x32_bf16 v[32:35], v[228:231], v[0:3], v[112:115]
	v_mfma_f32_16x16x32_bf16 v[0:3], v[232:235], v[0:3], v[80:83]
	ds_read_b128 v[8:11], v161 offset:52224
	s_waitcnt lgkmcnt(1)
	v_mfma_f32_16x16x32_bf16 v[96:99], v[28:31], v[4:7], v[144:147]
	v_mfma_f32_16x16x32_bf16 v[76:79], v[176:179], v[4:7], v[128:131]
	v_mfma_f32_16x16x32_bf16 v[36:39], v[228:231], v[4:7], v[100:103]
	v_mfma_f32_16x16x32_bf16 v[4:7], v[232:235], v[4:7], v[68:71]
	ds_read_b128 v[12:15], v161 offset:53760
	s_waitcnt lgkmcnt(1)
	v_mfma_f32_16x16x32_bf16 v[104:107], v[28:31], v[8:11], v[140:143]
	v_mfma_f32_16x16x32_bf16 v[84:87], v[176:179], v[8:11], v[120:123]
	v_mfma_f32_16x16x32_bf16 v[40:43], v[228:231], v[8:11], v[184:187]
	v_mfma_f32_16x16x32_bf16 v[8:11], v[232:235], v[8:11], v[44:47]
	ds_read_b128 v[16:19], v161 offset:55296
	s_waitcnt lgkmcnt(1)
	v_mfma_f32_16x16x32_bf16 v[108:111], v[28:31], v[12:15], v[132:135]
	v_mfma_f32_16x16x32_bf16 v[92:95], v[176:179], v[12:15], v[168:171]
	v_mfma_f32_16x16x32_bf16 v[44:47], v[228:231], v[12:15], v[188:191]
	v_mfma_f32_16x16x32_bf16 v[12:15], v[232:235], v[12:15], v[180:183]
	ds_read_b128 v[20:23], v161 offset:56832
	s_waitcnt lgkmcnt(1)
	v_mfma_f32_16x16x32_bf16 v[112:115], v[28:31], v[16:19], v[124:127]
	v_mfma_f32_16x16x32_bf16 v[100:103], v[176:179], v[16:19], v[192:195]
	v_mfma_f32_16x16x32_bf16 v[48:51], v[228:231], v[16:19], v[196:199]
	v_mfma_f32_16x16x32_bf16 v[16:19], v[232:235], v[16:19], v[200:203]
	ds_read_b128 v[24:27], v161 offset:58368
	s_waitcnt lgkmcnt(1)
	v_mfma_f32_16x16x32_bf16 v[116:119], v[28:31], v[20:23], v[116:119]
	v_mfma_f32_16x16x32_bf16 v[68:71], v[176:179], v[20:23], v[204:207]
	v_mfma_f32_16x16x32_bf16 v[52:55], v[228:231], v[20:23], v[56:59]
	v_mfma_f32_16x16x32_bf16 v[20:23], v[232:235], v[20:23], v[208:211]
	ds_read_b128 v[128:131], v161 offset:59904
	s_waitcnt lgkmcnt(1)
	v_mfma_f32_16x16x32_bf16 v[120:123], v[28:31], v[24:27], v[212:215]
	v_mfma_f32_16x16x32_bf16 v[80:83], v[176:179], v[24:27], v[72:75]
	v_mfma_f32_16x16x32_bf16 v[56:59], v[228:231], v[24:27], v[220:223]
	v_mfma_f32_16x16x32_bf16 v[24:27], v[232:235], v[24:27], v[224:227]
	s_waitcnt lgkmcnt(0)
	v_mfma_f32_16x16x32_bf16 v[124:127], v[28:31], v[128:131], v[154:157]
	v_mfma_f32_16x16x32_bf16 v[72:75], v[176:179], v[128:131], v[60:63]
	v_mfma_f32_16x16x32_bf16 v[60:63], v[228:231], v[128:131], v[164:167]
	v_mfma_f32_16x16x32_bf16 v[28:31], v[232:235], v[128:131], v[172:175]
	s_setprio 0
	s_ashr_i32 s35, s35, 3
	v_add_u32_e32 v128, s34, v160
	s_mul_hi_i32 s37, s35, 0x6000
	s_mulk_i32 s35, 0x6000
	v_lshl_or_b32 v128, v158, 2, v128
	s_add_u32 s36, s72, s35
	s_addc_u32 s37, s73, s37
	v_ashrrev_i32_e32 v129, 31, v128
	v_lshl_add_u64 v[128:129], v[128:129], 2, s[36:37]
	v_add_co_u32_e32 v140, vcc, s26, v128
	v_mul_u32_u24_e32 v138, 0x88, v159
	s_nop 0
	v_addc_co_u32_e32 v141, vcc, 0, v129, vcc
	v_lshlrev_b32_e32 v136, 1, v160
	v_lshlrev_b32_e32 v137, 3, v158
	v_lshlrev_b32_e32 v138, 1, v138
	s_barrier
	global_load_dwordx4 v[128:131], v[140:141], off
	global_load_dwordx4 v[132:135], v[140:141], off offset:64
	v_add3_u32 v144, v136, v137, v138
	global_load_dwordx4 v[136:139], v[140:141], off offset:128
	v_add_u32_e32 v145, 0x1000, v144
	global_load_dwordx4 v[140:143], v[140:141], off offset:192
	v_add_u32_e32 v146, 0x2000, v144
	v_add_u32_e32 v147, 0x3000, v144
	v_add_u32_e32 v148, 0x4000, v144
	s_add_i32 s31, s31, s78
	s_add_i32 s30, s30, s78
	s_cmp_gt_i32 s31, 63
	s_waitcnt vmcnt(3)
	v_mul_f32_e64 v88, v88, v128
	v_mul_f32_e64 v89, v89, v129
	v_mul_f32_e64 v90, v90, v130
	v_mul_f32_e64 v91, v91, v131
	v_mul_f32_e64 v96, v96, v128
	v_mul_f32_e64 v97, v97, v129
	s_waitcnt vmcnt(1)
	v_mul_f32_e64 v32, v32, v136
	v_mul_f32_e64 v33, v33, v137
	v_mul_f32_e64 v34, v34, v138
	v_mul_f32_e64 v35, v35, v139
	s_waitcnt vmcnt(0)
; DI void store4(u16* dst, f32x4 v) { uint2 w; w.x = cvtpk(v[0], v[1]); w.y = cvtpk(v[2], v[3]); *(uint2*)dst = w; }
; DI void phase6(const Params& p, const Sched& sched, unsigned char* smem) {
;     ...
; #pragma unroll
;       for (int mi = 0; mi < 4; ++mi) {
;         const int f = fb + mi * 16 + lq * 4; const float4 gm = *(const float4*)(mod + (size_t)b * 6144 + 2048 + f);
; #pragma unroll
;         for (int ni = 0; ni < 8; ++ni) {
;           const f32x4 o = {gm.x * acc[mi][ni][0], gm.y * acc[mi][ni][1], gm.z * acc[mi][ni][2], gm.w * acc[mi][ni][3]};
;           store4(Ls + (wt * 128 + ni * 16 + lr) * EST + wf * 64 + mi * 16 + lq * 4, o);
;         }
;       }
;       __syncthreads();
	v_mul_f32_e64 v0, v0, v140
	v_mul_f32_e64 v1, v1, v141
	v_mul_f32_e64 v2, v2, v142
	v_mul_f32_e64 v3, v3, v143
	v_cvt_pk_bf16_f32 v32, v32, v33
	v_cvt_pk_bf16_f32 v33, v34, v35
	v_cvt_pk_bf16_f32 v0, v0, v1
	v_cvt_pk_bf16_f32 v1, v2, v3
	v_mul_f32_e64 v34, v36, v136
	v_mul_f32_e64 v35, v37, v137
	v_mul_f32_e64 v36, v38, v138
	v_mul_f32_e64 v37, v39, v139
	ds_write2_b64 v144, v[32:33], v[0:1] offset0:8 offset1:12
	v_mul_f32_e64 v0, v4, v140
	v_mul_f32_e64 v1, v5, v141
	v_mul_f32_e64 v2, v6, v142
	v_mul_f32_e64 v3, v7, v143
	v_cvt_pk_bf16_f32 v34, v34, v35
	v_cvt_pk_bf16_f32 v35, v36, v37
	v_cvt_pk_bf16_f32 v0, v0, v1
	v_cvt_pk_bf16_f32 v1, v2, v3
	v_mul_f32_e64 v36, v40, v136
	v_mul_f32_e64 v37, v41, v137
	v_mul_f32_e64 v38, v42, v138
	v_mul_f32_e64 v39, v43, v139
	ds_write2_b64 v145, v[34:35], v[0:1] offset0:40 offset1:44
	v_mul_f32_e64 v0, v8, v140
	v_mul_f32_e64 v1, v9, v141
	v_mul_f32_e64 v2, v10, v142
	v_mul_f32_e64 v3, v11, v143
	v_cvt_pk_bf16_f32 v36, v36, v37
	v_cvt_pk_bf16_f32 v37, v38, v39
	v_cvt_pk_bf16_f32 v0, v0, v1
	v_cvt_pk_bf16_f32 v1, v2, v3
	v_mul_f32_e64 v38, v44, v136
	v_mul_f32_e64 v39, v45, v137
	v_mul_f32_e64 v40, v46, v138
	v_mul_f32_e64 v41, v47, v139
	ds_write2_b64 v146, v[36:37], v[0:1] offset0:72 offset1:76
	v_mul_f32_e64 v0, v12, v140
	v_mul_f32_e64 v1, v13, v141
	v_mul_f32_e64 v2, v14, v142
	v_mul_f32_e64 v3, v15, v143
	v_cvt_pk_bf16_f32 v38, v38, v39
	v_cvt_pk_bf16_f32 v39, v40, v41
	v_cvt_pk_bf16_f32 v0, v0, v1
	v_cvt_pk_bf16_f32 v1, v2, v3
	v_mul_f32_e64 v98, v98, v130
	v_mul_f32_e64 v99, v99, v131
	v_mul_f32_e64 v64, v64, v132
	v_mul_f32_e64 v65, v65, v133
	v_mul_f32_e64 v66, v66, v134
	v_mul_f32_e64 v67, v67, v135
	v_mul_f32_e64 v76, v76, v132
	v_mul_f32_e64 v77, v77, v133
	v_mul_f32_e64 v78, v78, v134
	v_mul_f32_e64 v79, v79, v135
	v_mul_f32_e64 v40, v48, v136
	v_mul_f32_e64 v41, v49, v137
	v_mul_f32_e64 v42, v50, v138
	v_mul_f32_e64 v43, v51, v139
	ds_write2_b64 v147, v[38:39], v[0:1] offset0:104 offset1:108
	v_mul_f32_e64 v0, v16, v140
	v_mul_f32_e64 v1, v17, v141
	v_mul_f32_e64 v2, v18, v142
	v_mul_f32_e64 v3, v19, v143
	v_cvt_pk_bf16_f32 v88, v88, v89
	v_cvt_pk_bf16_f32 v89, v90, v91
	v_cvt_pk_bf16_f32 v90, v96, v97
	v_cvt_pk_bf16_f32 v91, v98, v99
	v_cvt_pk_bf16_f32 v64, v64, v65
	v_cvt_pk_bf16_f32 v65, v66, v67
	v_cvt_pk_bf16_f32 v66, v76, v77
	v_cvt_pk_bf16_f32 v67, v78, v79
	v_cvt_pk_bf16_f32 v40, v40, v41
	v_cvt_pk_bf16_f32 v41, v42, v43
	v_cvt_pk_bf16_f32 v0, v0, v1
	v_cvt_pk_bf16_f32 v1, v2, v3
	v_mul_f32_e64 v106, v106, v130
	v_mul_f32_e64 v107, v107, v131
	v_mul_f32_e64 v116, v116, v128
	v_mul_f32_e64 v117, v117, v129
	v_mul_f32_e64 v118, v118, v130
	v_mul_f32_e64 v119, v119, v131
	ds_write2_b64 v144, v[88:89], v[64:65] offset1:4
	ds_write2_b64 v145, v[90:91], v[66:67] offset0:32 offset1:36
	v_mul_f32_e64 v64, v68, v132
	v_mul_f32_e64 v65, v69, v133
	v_mul_f32_e64 v66, v70, v134
	v_mul_f32_e64 v67, v71, v135
	v_mul_f32_e64 v42, v52, v136
	v_mul_f32_e64 v43, v53, v137
	v_mul_f32_e64 v44, v54, v138
	v_mul_f32_e64 v45, v55, v139
	ds_write2_b64 v148, v[40:41], v[0:1] offset0:136 offset1:140
	v_mul_f32_e64 v0, v20, v140
	v_mul_f32_e64 v1, v21, v141
	v_mul_f32_e64 v2, v22, v142
	v_mul_f32_e64 v3, v23, v143
	v_cvt_pk_bf16_f32 v97, v106, v107
	v_cvt_pk_bf16_f32 v106, v116, v117
	v_cvt_pk_bf16_f32 v107, v118, v119
	v_cvt_pk_bf16_f32 v64, v64, v65
	v_cvt_pk_bf16_f32 v65, v66, v67
	v_add_u32_e32 v68, 0x5000, v144
	v_cvt_pk_bf16_f32 v42, v42, v43
	v_cvt_pk_bf16_f32 v43, v44, v45
	v_cvt_pk_bf16_f32 v0, v0, v1
	v_cvt_pk_bf16_f32 v1, v2, v3
	v_mul_f32_e64 v108, v108, v128
	v_mul_f32_e64 v109, v109, v129
	v_mul_f32_e64 v120, v120, v128
	v_mul_f32_e64 v121, v121, v129
	v_mul_f32_e64 v122, v122, v130
	v_mul_f32_e64 v123, v123, v131
	ds_write2_b64 v68, v[106:107], v[64:65] offset0:160 offset1:164
	v_mul_f32_e64 v64, v80, v132
	v_mul_f32_e64 v65, v81, v133
	v_mul_f32_e64 v66, v82, v134
	v_mul_f32_e64 v67, v83, v135
	v_mul_f32_e64 v44, v56, v136
	v_mul_f32_e64 v45, v57, v137
	v_mul_f32_e64 v46, v58, v138
	v_mul_f32_e64 v47, v59, v139
	ds_write2_b64 v68, v[42:43], v[0:1] offset0:168 offset1:172
	v_mul_f32_e64 v0, v24, v140
	v_mul_f32_e64 v1, v25, v141
	v_mul_f32_e64 v2, v26, v142
	v_mul_f32_e64 v3, v27, v143
	v_cvt_pk_bf16_f32 v98, v108, v109
	v_cvt_pk_bf16_f32 v108, v120, v121
	v_cvt_pk_bf16_f32 v109, v122, v123
	v_cvt_pk_bf16_f32 v64, v64, v65
	v_cvt_pk_bf16_f32 v65, v66, v67
	v_add_u32_e32 v69, 0x6000, v144
	v_cvt_pk_bf16_f32 v44, v44, v45
	v_cvt_pk_bf16_f32 v45, v46, v47
	v_cvt_pk_bf16_f32 v0, v0, v1
	v_cvt_pk_bf16_f32 v1, v2, v3
	v_mul_f32_e64 v104, v104, v128
	v_mul_f32_e64 v105, v105, v129
	v_mul_f32_e64 v110, v110, v130
	v_mul_f32_e64 v111, v111, v131
	v_mul_f32_e64 v112, v112, v128
	v_mul_f32_e64 v113, v113, v129
	v_mul_f32_e64 v114, v114, v130
	v_mul_f32_e64 v115, v115, v131
	v_mul_f32_e64 v124, v124, v128
	v_mul_f32_e64 v125, v125, v129
	v_mul_f32_e64 v126, v126, v130
	v_mul_f32_e64 v127, v127, v131
	v_mul_f32_e64 v84, v84, v132
	v_mul_f32_e64 v85, v85, v133
	v_mul_f32_e64 v86, v86, v134
	v_mul_f32_e64 v87, v87, v135
	v_mul_f32_e64 v92, v92, v132
	v_mul_f32_e64 v93, v93, v133
	v_mul_f32_e64 v94, v94, v134
	v_mul_f32_e64 v95, v95, v135
	v_mul_f32_e64 v100, v100, v132
	v_mul_f32_e64 v101, v101, v133
	v_mul_f32_e64 v102, v102, v134
	v_mul_f32_e64 v103, v103, v135
	ds_write2_b64 v69, v[108:109], v[64:65] offset0:192 offset1:196
	v_mul_f32_e64 v64, v72, v132
	v_mul_f32_e64 v65, v73, v133
	v_mul_f32_e64 v66, v74, v134
	v_mul_f32_e64 v67, v75, v135
	v_mul_f32_e64 v46, v60, v136
	v_mul_f32_e64 v47, v61, v137
	v_mul_f32_e64 v48, v62, v138
	v_mul_f32_e64 v49, v63, v139
	ds_write2_b64 v69, v[44:45], v[0:1] offset0:200 offset1:204
	v_mul_f32_e64 v0, v28, v140
	v_mul_f32_e64 v1, v29, v141
	v_mul_f32_e64 v2, v30, v142
	v_mul_f32_e64 v3, v31, v143
	v_cvt_pk_bf16_f32 v96, v104, v105
	v_cvt_pk_bf16_f32 v99, v110, v111
	v_cvt_pk_bf16_f32 v104, v112, v113
	v_cvt_pk_bf16_f32 v105, v114, v115
	v_cvt_pk_bf16_f32 v110, v124, v125
	v_cvt_pk_bf16_f32 v111, v126, v127
	v_cvt_pk_bf16_f32 v76, v84, v85
	v_cvt_pk_bf16_f32 v77, v86, v87
	v_cvt_pk_bf16_f32 v78, v92, v93
	v_cvt_pk_bf16_f32 v79, v94, v95
	v_cvt_pk_bf16_f32 v84, v100, v101
	v_cvt_pk_bf16_f32 v85, v102, v103
	v_cvt_pk_bf16_f32 v64, v64, v65
	v_cvt_pk_bf16_f32 v65, v66, v67
	v_add_u32_e32 v66, 0x7000, v144
	v_cvt_pk_bf16_f32 v46, v46, v47
	v_cvt_pk_bf16_f32 v47, v48, v49
	v_cvt_pk_bf16_f32 v0, v0, v1
	v_cvt_pk_bf16_f32 v1, v2, v3
	v_mov_b32_e32 v2, v218
	ds_write2_b64 v146, v[96:97], v[76:77] offset0:64 offset1:68
	ds_write2_b64 v147, v[98:99], v[78:79] offset0:96 offset1:100
	ds_write2_b64 v148, v[104:105], v[84:85] offset0:128 offset1:132
	ds_write2_b64 v66, v[110:111], v[64:65] offset0:224 offset1:228
	ds_write2_b64 v66, v[46:47], v[0:1] offset0:232 offset1:236
	s_waitcnt lgkmcnt(0)
	s_barrier
; DI int tidx() { int t = __builtin_amdgcn_workitem_id_x(); asm volatile("" : "+v"(t)); return t; }
; DI unsigned cvtpk(float lo, float hi) { const f32x2_ v = {lo, hi}; return __builtin_bit_cast(unsigned, __builtin_convertvector(v, bf16x2_)); }
; DI float bflo(unsigned w) { return __uint_as_float(w << 16); }
; DI float bfhi(unsigned w) { return __uint_as_float(w & 0xffff0000u); }
; DI void phase6(const Params& p, const Sched& sched, unsigned char* smem) {
;     ...
;       const int tid = tidx();
; #pragma unroll
;       for (int i = 0; i < 16; ++i) {
;         const int c = tid + 256 * i, row = c >> 4, ch = (c & 15) * 8;
;         const size_t gi = (size_t)(tm * 256 + row) * 1024 + tn * 128 + ch;
;         const u32x4 sv = *(const u32x4*)(Ls + row * EST + ch);
;         const f32x4 x0 = *(const f32x4*)(p.x + gi), x1 = *(const f32x4*)(p.x + gi + 4);
;         u32x4 w;
;         w.x = cvtpk(x0[0] + bflo(sv.x), x0[1] + bfhi(sv.x)); w.y = cvtpk(x0[2] + bflo(sv.y), x0[3] + bfhi(sv.y));
;         w.z = cvtpk(x1[0] + bflo(sv.z), x1[1] + bfhi(sv.z)); w.w = cvtpk(x1[2] + bflo(sv.w), x1[3] + bfhi(sv.w));
;         *(u32x4*)(x1b + gi) = w;
;       }
	s_nop 0
	v_ashrrev_i32_e32 v3, 4, v2
	v_add_u32_e32 v4, s33, v3
	v_lshlrev_b32_e32 v0, 3, v2
	v_ashrrev_i32_e32 v5, 31, v4
	v_and_b32_e32 v1, 0x78, v0
	v_lshlrev_b64 v[16:17], 10, v[4:5]
	v_or3_b32 v16, v16, s34, v1
	v_lshl_add_u64 v[8:9], v[16:17], 2, s[76:77]
	global_load_dwordx4 v[4:7], v[8:9], off
	v_lshlrev_b32_e32 v0, 1, v1
	global_load_dwordx4 v[8:11], v[8:9], off offset:16
	v_mad_u64_u32 v[12:13], s[36:37], v3, s27, v[0:1]
	ds_read_b128 v[12:15], v12
	v_add_u32_e32 v3, 0x100, v2
	v_ashrrev_i32_e32 v3, 4, v3
	s_waitcnt lgkmcnt(0)
	v_lshlrev_b32_e32 v18, 16, v12
	v_and_b32_e32 v19, 0xffff0000, v12
	v_lshlrev_b32_e32 v12, 16, v13
	v_and_b32_e32 v13, 0xffff0000, v13
	s_waitcnt vmcnt(1)
	v_add_f32_e64 v4, v4, v18
	v_add_f32_e64 v5, v5, v19
	v_add_f32_e64 v6, v6, v12
	v_add_f32_e64 v7, v7, v13
	v_cvt_pk_bf16_f32 v4, v4, v5
	v_cvt_pk_bf16_f32 v5, v6, v7
	v_lshlrev_b32_e32 v6, 16, v14
	v_and_b32_e32 v7, 0xffff0000, v14
	s_waitcnt vmcnt(0)
	v_add_f32_e64 v6, v8, v6
	v_add_f32_e64 v7, v9, v7
	v_lshlrev_b32_e32 v8, 16, v15
	v_and_b32_e32 v9, 0xffff0000, v15
	v_add_f32_e64 v8, v10, v8
	v_add_f32_e64 v9, v11, v9
	v_cvt_pk_bf16_f32 v6, v6, v7
	v_cvt_pk_bf16_f32 v7, v8, v9
	v_lshl_add_u64 v[8:9], v[16:17], 1, s[12:13]
	global_store_dwordx4 v[8:9], v[4:7], off
	v_add_u32_e32 v12, 0x200, v2
	v_ashrrev_i32_e32 v26, 4, v12
	v_add_u32_e32 v4, s33, v3
	v_ashrrev_i32_e32 v5, 31, v4
	v_lshlrev_b64 v[16:17], 10, v[4:5]
	v_or3_b32 v16, v16, s34, v1
	v_lshl_add_u64 v[8:9], v[16:17], 2, s[76:77]
	global_load_dwordx4 v[4:7], v[8:9], off
	v_mad_u64_u32 v[12:13], s[36:37], v3, s27, v[0:1]
	global_load_dwordx4 v[8:11], v[8:9], off offset:16
	ds_read_b128 v[12:15], v12
	v_add_u32_e32 v18, s33, v26
	v_ashrrev_i32_e32 v19, 31, v18
	v_lshlrev_b64 v[18:19], 10, v[18:19]
	v_or3_b32 v18, v18, s34, v1
	s_waitcnt lgkmcnt(0)
	v_lshlrev_b32_e32 v22, 16, v12
	v_and_b32_e32 v23, 0xffff0000, v12
	v_lshlrev_b32_e32 v12, 16, v13
	v_and_b32_e32 v13, 0xffff0000, v13
	v_lshlrev_b32_e32 v24, 16, v14
	v_and_b32_e32 v25, 0xffff0000, v14
	v_lshlrev_b32_e32 v14, 16, v15
	v_and_b32_e32 v15, 0xffff0000, v15
	v_lshl_add_u64 v[16:17], v[16:17], 1, s[12:13]
	v_lshl_add_u64 v[20:21], v[18:19], 2, s[76:77]
	v_add_u32_e32 v3, 0x300, v2
	v_ashrrev_i32_e32 v3, 4, v3
	v_lshl_add_u64 v[18:19], v[18:19], 1, s[12:13]
	s_waitcnt vmcnt(1)
	v_add_f32_e64 v4, v4, v22
	v_add_f32_e64 v5, v5, v23
	v_add_f32_e64 v6, v6, v12
	v_add_f32_e64 v7, v7, v13
	v_cvt_pk_bf16_f32 v4, v4, v5
	s_waitcnt vmcnt(0)
	v_add_f32_e64 v8, v8, v24
	v_add_f32_e64 v9, v9, v25
	v_add_f32_e64 v10, v10, v14
	v_add_f32_e64 v11, v11, v15
	v_cvt_pk_bf16_f32 v5, v6, v7
	v_cvt_pk_bf16_f32 v6, v8, v9
	v_cvt_pk_bf16_f32 v7, v10, v11
	global_store_dwordx4 v[16:17], v[4:7], off
	global_load_dwordx4 v[4:7], v[20:21], off
	v_mad_u64_u32 v[12:13], s[36:37], v26, s27, v[0:1]
	global_load_dwordx4 v[8:11], v[20:21], off offset:16
	ds_read_b128 v[12:15], v12
	v_add_u32_e32 v16, s33, v3
	v_ashrrev_i32_e32 v17, 31, v16
	v_lshlrev_b64 v[16:17], 10, v[16:17]
	v_or3_b32 v16, v16, s34, v1
	s_waitcnt lgkmcnt(0)
	v_lshlrev_b32_e32 v22, 16, v12
	v_and_b32_e32 v23, 0xffff0000, v12
	v_lshlrev_b32_e32 v12, 16, v13
	v_and_b32_e32 v13, 0xffff0000, v13
	v_lshlrev_b32_e32 v24, 16, v14
	v_and_b32_e32 v25, 0xffff0000, v14
	v_lshlrev_b32_e32 v14, 16, v15
	v_and_b32_e32 v15, 0xffff0000, v15
	v_lshl_add_u64 v[20:21], v[16:17], 2, s[76:77]
	v_lshl_add_u64 v[16:17], v[16:17], 1, s[12:13]
	s_waitcnt vmcnt(1)
	v_add_f32_e64 v4, v4, v22
	v_add_f32_e64 v5, v5, v23
	v_add_f32_e64 v6, v6, v12
	v_add_f32_e64 v7, v7, v13
	v_cvt_pk_bf16_f32 v4, v4, v5
	s_waitcnt vmcnt(0)
	v_add_f32_e64 v8, v8, v24
	v_add_f32_e64 v9, v9, v25
	v_add_f32_e64 v10, v10, v14
	v_add_f32_e64 v11, v11, v15
	v_cvt_pk_bf16_f32 v5, v6, v7
	v_cvt_pk_bf16_f32 v6, v8, v9
	v_cvt_pk_bf16_f32 v7, v10, v11
	global_store_dwordx4 v[18:19], v[4:7], off
	global_load_dwordx4 v[4:7], v[20:21], off
	v_add_u32_e32 v12, 0x400, v2
	global_load_dwordx4 v[8:11], v[20:21], off offset:16
	v_ashrrev_i32_e32 v26, 4, v12
	v_mad_u64_u32 v[12:13], s[36:37], v3, s27, v[0:1]
	ds_read_b128 v[12:15], v12
	v_add_u32_e32 v18, s33, v26
	v_ashrrev_i32_e32 v19, 31, v18
	v_lshlrev_b64 v[18:19], 10, v[18:19]
	v_or3_b32 v18, v18, s34, v1
	s_waitcnt lgkmcnt(0)
	v_lshlrev_b32_e32 v22, 16, v12
	v_and_b32_e32 v23, 0xffff0000, v12
	v_lshlrev_b32_e32 v12, 16, v13
	v_and_b32_e32 v13, 0xffff0000, v13
	v_lshlrev_b32_e32 v24, 16, v14
	v_and_b32_e32 v25, 0xffff0000, v14
	v_lshlrev_b32_e32 v14, 16, v15
	v_and_b32_e32 v15, 0xffff0000, v15
	v_lshl_add_u64 v[20:21], v[18:19], 2, s[76:77]
	v_add_u32_e32 v3, 0x500, v2
	v_ashrrev_i32_e32 v3, 4, v3
	v_lshl_add_u64 v[18:19], v[18:19], 1, s[12:13]
	s_waitcnt vmcnt(1)
	v_add_f32_e64 v4, v4, v22
	v_add_f32_e64 v5, v5, v23
	v_add_f32_e64 v6, v6, v12
	v_add_f32_e64 v7, v7, v13
	s_waitcnt vmcnt(0)
	v_add_f32_e64 v8, v8, v24
	v_add_f32_e64 v9, v9, v25
	v_add_f32_e64 v10, v10, v14
	v_add_f32_e64 v11, v11, v15
	v_cvt_pk_bf16_f32 v4, v4, v5
	v_cvt_pk_bf16_f32 v5, v6, v7
	v_cvt_pk_bf16_f32 v6, v8, v9
	v_cvt_pk_bf16_f32 v7, v10, v11
	global_store_dwordx4 v[16:17], v[4:7], off
	global_load_dwordx4 v[4:7], v[20:21], off
	v_mad_u64_u32 v[12:13], s[36:37], v26, s27, v[0:1]
	global_load_dwordx4 v[8:11], v[20:21], off offset:16
	ds_read_b128 v[12:15], v12
	v_add_u32_e32 v16, s33, v3
	v_ashrrev_i32_e32 v17, 31, v16
	v_lshlrev_b64 v[16:17], 10, v[16:17]
	v_or3_b32 v16, v16, s34, v1
	s_waitcnt lgkmcnt(0)
	v_lshlrev_b32_e32 v22, 16, v12
	v_and_b32_e32 v23, 0xffff0000, v12
	v_lshlrev_b32_e32 v12, 16, v13
	v_and_b32_e32 v13, 0xffff0000, v13
	v_lshlrev_b32_e32 v24, 16, v14
	v_and_b32_e32 v25, 0xffff0000, v14
	v_lshlrev_b32_e32 v14, 16, v15
	v_and_b32_e32 v15, 0xffff0000, v15
	v_lshl_add_u64 v[20:21], v[16:17], 2, s[76:77]
	v_lshl_add_u64 v[16:17], v[16:17], 1, s[12:13]
	s_waitcnt vmcnt(1)
; DI int tidx() { int t = __builtin_amdgcn_workitem_id_x(); asm volatile("" : "+v"(t)); return t; }
; DI unsigned cvtpk(float lo, float hi) { const f32x2_ v = {lo, hi}; return __builtin_bit_cast(unsigned, __builtin_convertvector(v, bf16x2_)); }
; DI float bflo(unsigned w) { return __uint_as_float(w << 16); }
; DI float bfhi(unsigned w) { return __uint_as_float(w & 0xffff0000u); }
; DI void phase6(const Params& p, const Sched& sched, unsigned char* smem) {
;     ...
;       const int tid = tidx();
; #pragma unroll
;       for (int i = 0; i < 16; ++i) {
;         const int c = tid + 256 * i, row = c >> 4, ch = (c & 15) * 8;
;         const size_t gi = (size_t)(tm * 256 + row) * 1024 + tn * 128 + ch;
;         const u32x4 sv = *(const u32x4*)(Ls + row * EST + ch);
;         const f32x4 x0 = *(const f32x4*)(p.x + gi), x1 = *(const f32x4*)(p.x + gi + 4);
;         u32x4 w;
;         w.x = cvtpk(x0[0] + bflo(sv.x), x0[1] + bfhi(sv.x)); w.y = cvtpk(x0[2] + bflo(sv.y), x0[3] + bfhi(sv.y));
;         w.z = cvtpk(x1[0] + bflo(sv.z), x1[1] + bfhi(sv.z)); w.w = cvtpk(x1[2] + bflo(sv.w), x1[3] + bfhi(sv.w));
;         *(u32x4*)(x1b + gi) = w;
;       }
	v_add_f32_e64 v4, v4, v22
	v_add_f32_e64 v5, v5, v23
	v_add_f32_e64 v6, v6, v12
	v_add_f32_e64 v7, v7, v13
	v_cvt_pk_bf16_f32 v4, v4, v5
	s_waitcnt vmcnt(0)
	v_add_f32_e64 v8, v8, v24
	v_add_f32_e64 v9, v9, v25
	v_add_f32_e64 v10, v10, v14
	v_add_f32_e64 v11, v11, v15
	v_cvt_pk_bf16_f32 v5, v6, v7
	v_cvt_pk_bf16_f32 v6, v8, v9
	v_cvt_pk_bf16_f32 v7, v10, v11
	global_store_dwordx4 v[18:19], v[4:7], off
	global_load_dwordx4 v[4:7], v[20:21], off
	v_add_u32_e32 v12, 0x600, v2
	global_load_dwordx4 v[8:11], v[20:21], off offset:16
	v_ashrrev_i32_e32 v26, 4, v12
	v_mad_u64_u32 v[12:13], s[36:37], v3, s27, v[0:1]
	ds_read_b128 v[12:15], v12
	v_add_u32_e32 v18, s33, v26
	v_ashrrev_i32_e32 v19, 31, v18
	v_lshlrev_b64 v[18:19], 10, v[18:19]
	v_or3_b32 v18, v18, s34, v1
	s_waitcnt lgkmcnt(0)
	v_lshlrev_b32_e32 v22, 16, v12
	v_and_b32_e32 v23, 0xffff0000, v12
	v_lshlrev_b32_e32 v12, 16, v13
	v_and_b32_e32 v13, 0xffff0000, v13
	v_lshlrev_b32_e32 v24, 16, v14
	v_and_b32_e32 v25, 0xffff0000, v14
	v_lshlrev_b32_e32 v14, 16, v15
	v_and_b32_e32 v15, 0xffff0000, v15
	v_lshl_add_u64 v[20:21], v[18:19], 2, s[76:77]
	v_add_u32_e32 v3, 0x700, v2
	v_ashrrev_i32_e32 v3, 4, v3
	v_lshl_add_u64 v[18:19], v[18:19], 1, s[12:13]
	s_waitcnt vmcnt(1)
	v_add_f32_e64 v4, v4, v22
	v_add_f32_e64 v5, v5, v23
	v_add_f32_e64 v6, v6, v12
	v_add_f32_e64 v7, v7, v13
	s_waitcnt vmcnt(0)
	v_add_f32_e64 v8, v8, v24
	v_add_f32_e64 v9, v9, v25
	v_add_f32_e64 v10, v10, v14
	v_add_f32_e64 v11, v11, v15
	v_cvt_pk_bf16_f32 v4, v4, v5
	v_cvt_pk_bf16_f32 v5, v6, v7
	v_cvt_pk_bf16_f32 v6, v8, v9
	v_cvt_pk_bf16_f32 v7, v10, v11
	global_store_dwordx4 v[16:17], v[4:7], off
	global_load_dwordx4 v[4:7], v[20:21], off
	v_mad_u64_u32 v[12:13], s[36:37], v26, s27, v[0:1]
	global_load_dwordx4 v[8:11], v[20:21], off offset:16
	ds_read_b128 v[12:15], v12
	v_add_u32_e32 v16, s33, v3
	v_ashrrev_i32_e32 v17, 31, v16
	v_lshlrev_b64 v[16:17], 10, v[16:17]
	v_or3_b32 v16, v16, s34, v1
	s_waitcnt lgkmcnt(0)
	v_lshlrev_b32_e32 v22, 16, v12
	v_and_b32_e32 v23, 0xffff0000, v12
	v_lshlrev_b32_e32 v12, 16, v13
	v_and_b32_e32 v13, 0xffff0000, v13
	v_lshlrev_b32_e32 v24, 16, v14
	v_and_b32_e32 v25, 0xffff0000, v14
	v_lshlrev_b32_e32 v14, 16, v15
	v_and_b32_e32 v15, 0xffff0000, v15
	v_lshl_add_u64 v[20:21], v[16:17], 2, s[76:77]
	v_lshl_add_u64 v[16:17], v[16:17], 1, s[12:13]
	s_waitcnt vmcnt(1)
	v_add_f32_e64 v4, v4, v22
	v_add_f32_e64 v5, v5, v23
	v_add_f32_e64 v6, v6, v12
	v_add_f32_e64 v7, v7, v13
	v_cvt_pk_bf16_f32 v4, v4, v5
	s_waitcnt vmcnt(0)
	v_add_f32_e64 v8, v8, v24
	v_add_f32_e64 v9, v9, v25
	v_add_f32_e64 v10, v10, v14
	v_add_f32_e64 v11, v11, v15
	v_cvt_pk_bf16_f32 v5, v6, v7
	v_cvt_pk_bf16_f32 v6, v8, v9
	v_cvt_pk_bf16_f32 v7, v10, v11
	global_store_dwordx4 v[18:19], v[4:7], off
	global_load_dwordx4 v[4:7], v[20:21], off
	v_add_u32_e32 v12, 0x800, v2
	global_load_dwordx4 v[8:11], v[20:21], off offset:16
	v_ashrrev_i32_e32 v26, 4, v12
	v_mad_u64_u32 v[12:13], s[36:37], v3, s27, v[0:1]
	ds_read_b128 v[12:15], v12
	v_add_u32_e32 v18, s33, v26
	v_ashrrev_i32_e32 v19, 31, v18
	v_lshlrev_b64 v[18:19], 10, v[18:19]
	v_or3_b32 v18, v18, s34, v1
	s_waitcnt lgkmcnt(0)
	v_lshlrev_b32_e32 v22, 16, v12
	v_and_b32_e32 v23, 0xffff0000, v12
	v_lshlrev_b32_e32 v12, 16, v13
	v_and_b32_e32 v13, 0xffff0000, v13
	v_lshlrev_b32_e32 v24, 16, v14
	v_and_b32_e32 v25, 0xffff0000, v14
	v_lshlrev_b32_e32 v14, 16, v15
	v_and_b32_e32 v15, 0xffff0000, v15
	v_lshl_add_u64 v[20:21], v[18:19], 2, s[76:77]
	v_add_u32_e32 v3, 0x900, v2
	v_ashrrev_i32_e32 v3, 4, v3
	v_lshl_add_u64 v[18:19], v[18:19], 1, s[12:13]
	s_waitcnt vmcnt(1)
	v_add_f32_e64 v4, v4, v22
	v_add_f32_e64 v5, v5, v23
	v_add_f32_e64 v6, v6, v12
	v_add_f32_e64 v7, v7, v13
	s_waitcnt vmcnt(0)
	v_add_f32_e64 v8, v8, v24
	v_add_f32_e64 v9, v9, v25
	v_add_f32_e64 v10, v10, v14
	v_add_f32_e64 v11, v11, v15
	v_cvt_pk_bf16_f32 v4, v4, v5
	v_cvt_pk_bf16_f32 v5, v6, v7
	v_cvt_pk_bf16_f32 v6, v8, v9
	v_cvt_pk_bf16_f32 v7, v10, v11
	global_store_dwordx4 v[16:17], v[4:7], off
	global_load_dwordx4 v[4:7], v[20:21], off
	v_mad_u64_u32 v[12:13], s[36:37], v26, s27, v[0:1]
	global_load_dwordx4 v[8:11], v[20:21], off offset:16
	ds_read_b128 v[12:15], v12
	v_add_u32_e32 v16, s33, v3
	v_ashrrev_i32_e32 v17, 31, v16
	v_lshlrev_b64 v[16:17], 10, v[16:17]
	v_or3_b32 v16, v16, s34, v1
	s_waitcnt lgkmcnt(0)
	v_lshlrev_b32_e32 v22, 16, v12
	v_and_b32_e32 v23, 0xffff0000, v12
	v_lshlrev_b32_e32 v12, 16, v13
	v_and_b32_e32 v13, 0xffff0000, v13
	v_lshlrev_b32_e32 v24, 16, v14
	v_and_b32_e32 v25, 0xffff0000, v14
	v_lshlrev_b32_e32 v14, 16, v15
	v_and_b32_e32 v15, 0xffff0000, v15
	v_lshl_add_u64 v[20:21], v[16:17], 2, s[76:77]
	v_lshl_add_u64 v[16:17], v[16:17], 1, s[12:13]
	s_waitcnt vmcnt(1)
	v_add_f32_e64 v4, v4, v22
	v_add_f32_e64 v5, v5, v23
	v_add_f32_e64 v6, v6, v12
	v_add_f32_e64 v7, v7, v13
	v_cvt_pk_bf16_f32 v4, v4, v5
	s_waitcnt vmcnt(0)
	v_add_f32_e64 v8, v8, v24
	v_add_f32_e64 v9, v9, v25
	v_add_f32_e64 v10, v10, v14
	v_add_f32_e64 v11, v11, v15
	v_cvt_pk_bf16_f32 v5, v6, v7
	v_cvt_pk_bf16_f32 v6, v8, v9
	v_cvt_pk_bf16_f32 v7, v10, v11
	global_store_dwordx4 v[18:19], v[4:7], off
	global_load_dwordx4 v[4:7], v[20:21], off
	v_add_u32_e32 v12, 0xa00, v2
	global_load_dwordx4 v[8:11], v[20:21], off offset:16
	v_ashrrev_i32_e32 v26, 4, v12
	v_mad_u64_u32 v[12:13], s[36:37], v3, s27, v[0:1]
	ds_read_b128 v[12:15], v12
	v_add_u32_e32 v18, s33, v26
	v_ashrrev_i32_e32 v19, 31, v18
	v_lshlrev_b64 v[18:19], 10, v[18:19]
	v_or3_b32 v18, v18, s34, v1
	s_waitcnt lgkmcnt(0)
; DI int tidx() { int t = __builtin_amdgcn_workitem_id_x(); asm volatile("" : "+v"(t)); return t; }
; DI unsigned cvtpk(float lo, float hi) { const f32x2_ v = {lo, hi}; return __builtin_bit_cast(unsigned, __builtin_convertvector(v, bf16x2_)); }
; DI float bflo(unsigned w) { return __uint_as_float(w << 16); }
; DI float bfhi(unsigned w) { return __uint_as_float(w & 0xffff0000u); }
; DI void phase6(const Params& p, const Sched& sched, unsigned char* smem) {
;     ...
;       const int tid = tidx();
; #pragma unroll
;       for (int i = 0; i < 16; ++i) {
;         const int c = tid + 256 * i, row = c >> 4, ch = (c & 15) * 8;
;         const size_t gi = (size_t)(tm * 256 + row) * 1024 + tn * 128 + ch;
;         const u32x4 sv = *(const u32x4*)(Ls + row * EST + ch);
;         const f32x4 x0 = *(const f32x4*)(p.x + gi), x1 = *(const f32x4*)(p.x + gi + 4);
;         u32x4 w;
;         w.x = cvtpk(x0[0] + bflo(sv.x), x0[1] + bfhi(sv.x)); w.y = cvtpk(x0[2] + bflo(sv.y), x0[3] + bfhi(sv.y));
;         w.z = cvtpk(x1[0] + bflo(sv.z), x1[1] + bfhi(sv.z)); w.w = cvtpk(x1[2] + bflo(sv.w), x1[3] + bfhi(sv.w));
;         *(u32x4*)(x1b + gi) = w;
;       }
	v_lshlrev_b32_e32 v22, 16, v12
	v_and_b32_e32 v23, 0xffff0000, v12
	v_lshlrev_b32_e32 v12, 16, v13
	v_and_b32_e32 v13, 0xffff0000, v13
	v_lshlrev_b32_e32 v24, 16, v14
	v_and_b32_e32 v25, 0xffff0000, v14
	v_lshlrev_b32_e32 v14, 16, v15
	v_and_b32_e32 v15, 0xffff0000, v15
	v_lshl_add_u64 v[20:21], v[18:19], 2, s[76:77]
	v_add_u32_e32 v3, 0xb00, v2
	v_ashrrev_i32_e32 v3, 4, v3
	v_lshl_add_u64 v[18:19], v[18:19], 1, s[12:13]
	s_waitcnt vmcnt(1)
	v_add_f32_e64 v4, v4, v22
	v_add_f32_e64 v5, v5, v23
	v_add_f32_e64 v6, v6, v12
	v_add_f32_e64 v7, v7, v13
	s_waitcnt vmcnt(0)
	v_add_f32_e64 v8, v8, v24
	v_add_f32_e64 v9, v9, v25
	v_add_f32_e64 v10, v10, v14
	v_add_f32_e64 v11, v11, v15
	v_cvt_pk_bf16_f32 v4, v4, v5
	v_cvt_pk_bf16_f32 v5, v6, v7
	v_cvt_pk_bf16_f32 v6, v8, v9
	v_cvt_pk_bf16_f32 v7, v10, v11
	global_store_dwordx4 v[16:17], v[4:7], off
	global_load_dwordx4 v[4:7], v[20:21], off
	v_mad_u64_u32 v[12:13], s[36:37], v26, s27, v[0:1]
	global_load_dwordx4 v[8:11], v[20:21], off offset:16
	ds_read_b128 v[12:15], v12
	v_add_u32_e32 v16, s33, v3
	v_ashrrev_i32_e32 v17, 31, v16
	v_lshlrev_b64 v[16:17], 10, v[16:17]
	v_or3_b32 v16, v16, s34, v1
	s_waitcnt lgkmcnt(0)
	v_lshlrev_b32_e32 v22, 16, v12
	v_and_b32_e32 v23, 0xffff0000, v12
	v_lshlrev_b32_e32 v12, 16, v13
	v_and_b32_e32 v13, 0xffff0000, v13
	v_lshlrev_b32_e32 v24, 16, v14
	v_and_b32_e32 v25, 0xffff0000, v14
	v_lshlrev_b32_e32 v14, 16, v15
	v_and_b32_e32 v15, 0xffff0000, v15
	v_lshl_add_u64 v[20:21], v[16:17], 2, s[76:77]
	v_lshl_add_u64 v[16:17], v[16:17], 1, s[12:13]
	s_waitcnt vmcnt(1)
	v_add_f32_e64 v4, v4, v22
	v_add_f32_e64 v5, v5, v23
	v_add_f32_e64 v6, v6, v12
	v_add_f32_e64 v7, v7, v13
	v_cvt_pk_bf16_f32 v4, v4, v5
	s_waitcnt vmcnt(0)
	v_add_f32_e64 v8, v8, v24
	v_add_f32_e64 v9, v9, v25
	v_add_f32_e64 v10, v10, v14
	v_add_f32_e64 v11, v11, v15
	v_cvt_pk_bf16_f32 v5, v6, v7
	v_cvt_pk_bf16_f32 v6, v8, v9
	v_cvt_pk_bf16_f32 v7, v10, v11
	global_store_dwordx4 v[18:19], v[4:7], off
	global_load_dwordx4 v[4:7], v[20:21], off
	v_add_u32_e32 v12, 0xc00, v2
	global_load_dwordx4 v[8:11], v[20:21], off offset:16
	v_ashrrev_i32_e32 v26, 4, v12
	v_mad_u64_u32 v[12:13], s[36:37], v3, s27, v[0:1]
	ds_read_b128 v[12:15], v12
	v_add_u32_e32 v18, s33, v26
	v_ashrrev_i32_e32 v19, 31, v18
	v_lshlrev_b64 v[18:19], 10, v[18:19]
	v_or3_b32 v18, v18, s34, v1
	s_waitcnt lgkmcnt(0)
	v_lshlrev_b32_e32 v22, 16, v12
	v_and_b32_e32 v23, 0xffff0000, v12
	v_lshlrev_b32_e32 v12, 16, v13
	v_and_b32_e32 v13, 0xffff0000, v13
	v_lshlrev_b32_e32 v24, 16, v14
	v_and_b32_e32 v25, 0xffff0000, v14
	v_lshlrev_b32_e32 v14, 16, v15
	v_and_b32_e32 v15, 0xffff0000, v15
	v_lshl_add_u64 v[20:21], v[18:19], 2, s[76:77]
	v_add_u32_e32 v3, 0xd00, v2
	v_ashrrev_i32_e32 v3, 4, v3
	v_lshl_add_u64 v[18:19], v[18:19], 1, s[12:13]
	s_waitcnt vmcnt(1)
	v_add_f32_e64 v4, v4, v22
	v_add_f32_e64 v5, v5, v23
	v_add_f32_e64 v6, v6, v12
	v_add_f32_e64 v7, v7, v13
	s_waitcnt vmcnt(0)
	v_add_f32_e64 v8, v8, v24
	v_add_f32_e64 v9, v9, v25
	v_add_f32_e64 v10, v10, v14
	v_add_f32_e64 v11, v11, v15
	v_cvt_pk_bf16_f32 v4, v4, v5
	v_cvt_pk_bf16_f32 v5, v6, v7
	v_cvt_pk_bf16_f32 v6, v8, v9
	v_cvt_pk_bf16_f32 v7, v10, v11
	global_store_dwordx4 v[16:17], v[4:7], off
	global_load_dwordx4 v[4:7], v[20:21], off
	v_mad_u64_u32 v[12:13], s[36:37], v26, s27, v[0:1]
	global_load_dwordx4 v[8:11], v[20:21], off offset:16
	ds_read_b128 v[12:15], v12
	v_add_u32_e32 v16, s33, v3
	v_ashrrev_i32_e32 v17, 31, v16
	v_lshlrev_b64 v[16:17], 10, v[16:17]
	v_or3_b32 v16, v16, s34, v1
	s_waitcnt lgkmcnt(0)
	v_lshlrev_b32_e32 v22, 16, v12
	v_and_b32_e32 v23, 0xffff0000, v12
	v_lshlrev_b32_e32 v12, 16, v13
	v_and_b32_e32 v13, 0xffff0000, v13
	v_lshlrev_b32_e32 v24, 16, v14
	v_and_b32_e32 v25, 0xffff0000, v14
	v_lshlrev_b32_e32 v14, 16, v15
	v_and_b32_e32 v15, 0xffff0000, v15
	v_lshl_add_u64 v[20:21], v[16:17], 2, s[76:77]
	v_lshl_add_u64 v[16:17], v[16:17], 1, s[12:13]
	s_waitcnt vmcnt(1)
; DI int tidx() { int t = __builtin_amdgcn_workitem_id_x(); asm volatile("" : "+v"(t)); return t; }
; DI unsigned cvtpk(float lo, float hi) { const f32x2_ v = {lo, hi}; return __builtin_bit_cast(unsigned, __builtin_convertvector(v, bf16x2_)); }
; DI float bflo(unsigned w) { return __uint_as_float(w << 16); }
; DI float bfhi(unsigned w) { return __uint_as_float(w & 0xffff0000u); }
; template <class F> DI void for_tiles_st(int ntm, int ntn, const Sched& sc, F f) {
;     ...
;     const int nsn = ntn >> 3, nsuper = (ntm >> 3) * nsn;
;     for (int sp = sc.xd; sp < nsuper; sp += sc.nx) {
;       const int sm = sp / nsn, sn = sp - sm * nsn;
;       for (int qq = sc.rank; qq < 64; qq += sc.nloc) f(sm * 8 + (qq >> 3), sn * 8 + (qq & 7));
;     }
; DI void phase6(const Params& p, const Sched& sched, unsigned char* smem) {
;     ...
;       const int tid = tidx();
; #pragma unroll
;       for (int i = 0; i < 16; ++i) {
;         const int c = tid + 256 * i, row = c >> 4, ch = (c & 15) * 8;
;         const size_t gi = (size_t)(tm * 256 + row) * 1024 + tn * 128 + ch;
;         const u32x4 sv = *(const u32x4*)(Ls + row * EST + ch);
;         const f32x4 x0 = *(const f32x4*)(p.x + gi), x1 = *(const f32x4*)(p.x + gi + 4);
;         u32x4 w;
;         w.x = cvtpk(x0[0] + bflo(sv.x), x0[1] + bfhi(sv.x)); w.y = cvtpk(x0[2] + bflo(sv.y), x0[3] + bfhi(sv.y));
;         w.z = cvtpk(x1[0] + bflo(sv.z), x1[1] + bfhi(sv.z)); w.w = cvtpk(x1[2] + bflo(sv.w), x1[3] + bfhi(sv.w));
;         *(u32x4*)(x1b + gi) = w;
;       }
	v_add_f32_e64 v4, v4, v22
	v_add_f32_e64 v5, v5, v23
	v_add_f32_e64 v6, v6, v12
	v_add_f32_e64 v7, v7, v13
	v_cvt_pk_bf16_f32 v4, v4, v5
	s_waitcnt vmcnt(0)
	v_add_f32_e64 v8, v8, v24
	v_add_f32_e64 v9, v9, v25
	v_add_f32_e64 v10, v10, v14
	v_add_f32_e64 v11, v11, v15
	v_cvt_pk_bf16_f32 v5, v6, v7
	v_cvt_pk_bf16_f32 v6, v8, v9
	v_cvt_pk_bf16_f32 v7, v10, v11
	global_store_dwordx4 v[18:19], v[4:7], off
	global_load_dwordx4 v[4:7], v[20:21], off
	v_add_u32_e32 v12, 0xe00, v2
	global_load_dwordx4 v[8:11], v[20:21], off offset:16
	v_ashrrev_i32_e32 v26, 4, v12
	v_mad_u64_u32 v[12:13], s[36:37], v3, s27, v[0:1]
	ds_read_b128 v[12:15], v12
	v_add_u32_e32 v18, s33, v26
	v_ashrrev_i32_e32 v19, 31, v18
	v_lshlrev_b64 v[18:19], 10, v[18:19]
	v_or3_b32 v18, v18, s34, v1
	s_waitcnt lgkmcnt(0)
	v_lshlrev_b32_e32 v22, 16, v12
	v_and_b32_e32 v23, 0xffff0000, v12
	v_lshlrev_b32_e32 v12, 16, v13
	v_and_b32_e32 v13, 0xffff0000, v13
	v_lshlrev_b32_e32 v24, 16, v14
	v_and_b32_e32 v25, 0xffff0000, v14
	v_lshlrev_b32_e32 v14, 16, v15
	v_and_b32_e32 v15, 0xffff0000, v15
	v_lshl_add_u64 v[20:21], v[18:19], 2, s[76:77]
	v_add_u32_e32 v2, 0xf00, v2
	v_lshl_add_u64 v[18:19], v[18:19], 1, s[12:13]
	s_waitcnt vmcnt(1)
	v_add_f32_e64 v4, v4, v22
	v_add_f32_e64 v5, v5, v23
	v_add_f32_e64 v6, v6, v12
	v_add_f32_e64 v7, v7, v13
	s_waitcnt vmcnt(0)
	v_add_f32_e64 v8, v8, v24
	v_add_f32_e64 v9, v9, v25
	v_add_f32_e64 v10, v10, v14
	v_add_f32_e64 v11, v11, v15
	v_cvt_pk_bf16_f32 v4, v4, v5
	v_cvt_pk_bf16_f32 v5, v6, v7
	v_cvt_pk_bf16_f32 v6, v8, v9
	v_cvt_pk_bf16_f32 v7, v10, v11
	global_store_dwordx4 v[16:17], v[4:7], off
	global_load_dwordx4 v[4:7], v[20:21], off
	v_mad_u64_u32 v[12:13], s[36:37], v26, s27, v[0:1]
	global_load_dwordx4 v[8:11], v[20:21], off offset:16
	ds_read_b128 v[12:15], v12
	v_ashrrev_i32_e32 v24, 4, v2
	v_add_u32_e32 v2, s33, v24
	v_ashrrev_i32_e32 v3, 31, v2
	v_lshlrev_b64 v[16:17], 10, v[2:3]
	s_waitcnt lgkmcnt(0)
	v_lshlrev_b32_e32 v2, 16, v12
	v_and_b32_e32 v3, 0xffff0000, v12
	v_lshlrev_b32_e32 v12, 16, v13
	v_and_b32_e32 v13, 0xffff0000, v13
	v_lshlrev_b32_e32 v22, 16, v14
	v_and_b32_e32 v23, 0xffff0000, v14
	v_lshlrev_b32_e32 v14, 16, v15
	v_and_b32_e32 v15, 0xffff0000, v15
	v_or3_b32 v16, v16, s34, v1
	v_lshl_add_u64 v[20:21], v[16:17], 2, s[76:77]
	v_mad_u64_u32 v[0:1], s[34:35], v24, s27, v[0:1]
	s_waitcnt vmcnt(1)
	v_add_f32_e64 v2, v4, v2
	v_add_f32_e64 v3, v5, v3
	v_add_f32_e64 v4, v6, v12
	v_add_f32_e64 v5, v7, v13
	v_cvt_pk_bf16_f32 v2, v2, v3
	s_waitcnt vmcnt(0)
	v_add_f32_e64 v6, v8, v22
	v_add_f32_e64 v7, v9, v23
	v_add_f32_e64 v8, v10, v14
	v_add_f32_e64 v9, v11, v15
	v_cvt_pk_bf16_f32 v3, v4, v5
	v_cvt_pk_bf16_f32 v4, v6, v7
	v_cvt_pk_bf16_f32 v5, v8, v9
	global_store_dwordx4 v[18:19], v[2:5], off
	global_load_dwordx4 v[2:5], v[20:21], off
	ds_read_b128 v[10:13], v0
	global_load_dwordx4 v[6:9], v[20:21], off offset:16
	v_lshl_add_u64 v[14:15], v[16:17], 1, s[12:13]
	s_waitcnt lgkmcnt(0)
	v_lshlrev_b32_e32 v0, 16, v10
	v_and_b32_e32 v1, 0xffff0000, v10
	v_lshlrev_b32_e32 v10, 16, v11
	v_and_b32_e32 v11, 0xffff0000, v11
	v_lshlrev_b32_e32 v16, 16, v12
	v_and_b32_e32 v17, 0xffff0000, v12
	v_lshlrev_b32_e32 v12, 16, v13
	v_and_b32_e32 v13, 0xffff0000, v13
	s_waitcnt vmcnt(1)
	v_add_f32_e64 v0, v2, v0
	v_add_f32_e64 v1, v3, v1
	v_add_f32_e64 v2, v4, v10
	v_add_f32_e64 v3, v5, v11
	s_waitcnt vmcnt(0)
	v_add_f32_e64 v4, v6, v16
	v_add_f32_e64 v5, v7, v17
	v_add_f32_e64 v6, v8, v12
	v_add_f32_e64 v7, v9, v13
	v_cvt_pk_bf16_f32 v0, v0, v1
	v_cvt_pk_bf16_f32 v1, v2, v3
	v_cvt_pk_bf16_f32 v2, v4, v5
	v_cvt_pk_bf16_f32 v3, v6, v7
	global_store_dwordx4 v[14:15], v[0:3], off
	s_cbranch_scc0 .LBB0_811
	s_branch .LBB0_808

; template <bool FIRST> DI void norm_pass(const Params& p, const float* __restrict__ src, const u16* __restrict__ srcb, const float* __restrict__ g, int shift_off, int scale_off,
;                                         int bid, int nblk, unsigned char* smem) {
;     ...
;     for (int k = tid; k < 1024; k += 256) {
;       gs[k] = g[k] * (1.0f + modval<FIRST>(p, b, scale_off + k));
;       sh[k] = modval<FIRST>(p, b, shift_off + k);
;     }
.LBB0_872:
	v_ashrrev_i32_e32 v5, 31, v1
	v_mov_b32_e32 v4, v1
	v_ashrrev_i32_e32 v7, 31, v0
	v_mov_b32_e32 v6, v0
	v_lshlrev_b64 v[6:7], 2, v[6:7]
	v_lshlrev_b64 v[4:5], 2, v[4:5]
	v_lshl_add_u64 v[20:21], s[62:63], 0, v[6:7]
	v_lshl_add_u64 v[22:23], s[62:63], 0, v[4:5]
	v_lshl_add_u64 v[6:7], s[34:35], 0, v[6:7]
	global_load_dword v20, v[20:21], off
	s_nop 0
	global_load_dword v21, v[22:23], off
	v_add_co_u32_e32 v22, vcc, s47, v6
	v_lshl_add_u64 v[4:5], s[34:35], 0, v[4:5]
	s_nop 0
	v_addc_co_u32_e32 v23, vcc, 0, v7, vcc
	v_add_co_u32_e32 v24, vcc, s47, v4
	v_add_u32_e32 v8, 0x200, v0
	s_nop 0
	v_addc_co_u32_e32 v25, vcc, 0, v5, vcc
	v_add_co_u32_e32 v6, vcc, s48, v6
	v_add_u32_e32 v10, 0x200, v1
	v_ashrrev_i32_e32 v9, 31, v8
	v_addc_co_u32_e32 v7, vcc, 0, v7, vcc
	v_ashrrev_i32_e32 v11, 31, v10
	v_lshlrev_b64 v[8:9], 2, v[8:9]
	v_add_co_u32_e32 v4, vcc, s48, v4
	v_lshlrev_b64 v[10:11], 2, v[10:11]
	s_nop 0
	v_addc_co_u32_e32 v5, vcc, 0, v5, vcc
	v_lshl_add_u64 v[26:27], s[62:63], 0, v[8:9]
	v_lshl_add_u64 v[8:9], s[34:35], 0, v[8:9]
	v_lshl_add_u64 v[28:29], s[62:63], 0, v[10:11]
	global_load_dword v22, v[22:23], off
	s_nop 0
	global_load_dword v23, v[24:25], off
	global_load_dword v66, v[6:7], off
	global_load_dword v67, v[4:5], off
	s_nop 0
	global_load_dword v6, v[26:27], off
	global_load_dword v7, v[28:29], off
	v_add_co_u32_e32 v4, vcc, s47, v8
	v_lshl_add_u64 v[10:11], s[34:35], 0, v[10:11]
	s_nop 0
	v_addc_co_u32_e32 v5, vcc, 0, v9, vcc
	v_add_co_u32_e32 v24, vcc, s47, v10
	v_add_u32_e32 v12, 0x400, v0
	s_nop 0
	v_addc_co_u32_e32 v25, vcc, 0, v11, vcc
	v_add_co_u32_e32 v8, vcc, s48, v8
	v_ashrrev_i32_e32 v13, 31, v12
	s_nop 0
	v_addc_co_u32_e32 v9, vcc, 0, v9, vcc
	v_add_u32_e32 v14, 0x400, v1
	v_lshlrev_b64 v[12:13], 2, v[12:13]
	v_add_co_u32_e32 v10, vcc, s48, v10
	v_ashrrev_i32_e32 v15, 31, v14
	v_lshl_add_u64 v[30:31], s[62:63], 0, v[12:13]
	v_lshl_add_u64 v[12:13], s[34:35], 0, v[12:13]
	v_addc_co_u32_e32 v11, vcc, 0, v11, vcc
	v_lshlrev_b64 v[14:15], 2, v[14:15]
	v_add_co_u32_e32 v28, vcc, s47, v12
	v_lshl_add_u64 v[58:59], s[62:63], 0, v[14:15]
	v_lshl_add_u64 v[14:15], s[34:35], 0, v[14:15]
	v_addc_co_u32_e32 v29, vcc, 0, v13, vcc
	global_load_dword v26, v[30:31], off
	global_load_dword v27, v[58:59], off
	v_add_co_u32_e32 v30, vcc, s47, v14
	v_add_u32_e32 v16, 0x600, v0
	s_nop 0
	v_addc_co_u32_e32 v31, vcc, 0, v15, vcc
	v_add_co_u32_e32 v12, vcc, s48, v12
	v_add_u32_e32 v18, 0x600, v1
	v_ashrrev_i32_e32 v17, 31, v16
	v_addc_co_u32_e32 v13, vcc, 0, v13, vcc
	v_ashrrev_i32_e32 v19, 31, v18
	v_lshlrev_b64 v[16:17], 2, v[16:17]
	v_add_co_u32_e32 v14, vcc, s48, v14
	v_lshlrev_b64 v[18:19], 2, v[18:19]
	v_lshl_add_u64 v[60:61], s[62:63], 0, v[16:17]
	v_lshl_add_u64 v[16:17], s[34:35], 0, v[16:17]
	v_addc_co_u32_e32 v15, vcc, 0, v15, vcc
	v_lshl_add_u64 v[62:63], s[62:63], 0, v[18:19]
	global_load_dword v58, v[60:61], off
	global_load_dword v59, v[62:63], off
	v_add_co_u32_e32 v60, vcc, s47, v16
	v_lshl_add_u64 v[18:19], s[34:35], 0, v[18:19]
	s_nop 0
	v_addc_co_u32_e32 v61, vcc, 0, v17, vcc
	v_add_co_u32_e32 v62, vcc, s47, v18
	v_add_u32_e32 v2, -4, v2
	s_nop 0
	v_addc_co_u32_e32 v63, vcc, 0, v19, vcc
	v_add_co_u32_e32 v16, vcc, s48, v16
	s_add_i32 s53, s53, 8
	s_nop 0
	v_addc_co_u32_e32 v17, vcc, 0, v17, vcc
	v_add_co_u32_e32 v18, vcc, s48, v18
	v_add_u32_e32 v1, 0x800, v1
	s_nop 0
	v_addc_co_u32_e32 v19, vcc, 0, v19, vcc
	global_load_dword v64, v[4:5], off
	global_load_dword v65, v[24:25], off
	s_nop 0
	global_load_dword v24, v[28:29], off
	global_load_dword v25, v[30:31], off
	global_load_dword v5, v[14:15], off
	s_nop 0
	global_load_dword v14, v[60:61], off
	global_load_dword v15, v[62:63], off
	s_nop 0
	global_load_dword v16, v[16:17], off
	s_nop 0
	global_load_dword v17, v[18:19], off
	s_nop 0
	global_load_dword v18, v[8:9], off
	global_load_dword v19, v[10:11], off
	global_load_dword v28, v[12:13], off
	s_waitcnt vmcnt(20)
	v_add_f32_e64 v8, v22, 1.0
	v_add_f32_e64 v9, v23, 1.0
	v_add_u32_e32 v29, 0x2000, v3
	v_cmp_eq_u32_e32 vcc, 0, v2
	v_mul_f32_e64 v8, v20, v8
	v_mul_f32_e64 v9, v21, v9
	v_add_u32_e32 v0, 0x800, v0
	v_mov_b32_e32 v4, s53
	s_or_b64 s[44:45], vcc, s[44:45]
	s_waitcnt vmcnt(19)
	ds_write_b32 v3, v66 offset:4096
	s_waitcnt vmcnt(4)
	ds_write2st64_b32 v3, v5, v16 offset0:36 offset1:40
	s_waitcnt vmcnt(3)
	ds_write_b32 v3, v17 offset:11264
	ds_write2st64_b32 v3, v8, v9 offset1:4
	v_add_f32_e64 v10, v64, 1.0
	v_add_f32_e64 v11, v65, 1.0
	v_add_f32_e64 v12, v24, 1.0
	v_add_f32_e64 v13, v25, 1.0
	v_add_f32_e64 v14, v14, 1.0
	v_add_f32_e64 v15, v15, 1.0
	v_mul_f32_e64 v6, v6, v10
	v_mul_f32_e64 v7, v7, v11
	v_mul_f32_e64 v8, v26, v12
	v_mul_f32_e64 v9, v27, v13
	v_mul_f32_e64 v10, v58, v14
	v_mul_f32_e64 v11, v59, v15
	ds_write2st64_b32 v3, v6, v7 offset0:8 offset1:12
	ds_write2st64_b32 v3, v8, v67 offset0:16 offset1:20
	s_waitcnt vmcnt(2)
	ds_write2st64_b32 v3, v9, v18 offset0:20 offset1:24
	s_waitcnt vmcnt(1)
	ds_write2st64_b32 v3, v10, v19 offset0:24 offset1:28
	s_waitcnt vmcnt(0)
	ds_write2st64_b32 v3, v11, v28 offset0:28 offset1:32
	v_mov_b32_e32 v3, v29
	s_andn2_b64 exec, exec, s[44:45]
	s_cbranch_execnz .LBB0_872
	s_or_b64 exec, exec, s[44:45]

; template <bool FIRST> DI void norm_pass(const Params& p, const float* __restrict__ src, const u16* __restrict__ srcb, const float* __restrict__ g, int shift_off, int scale_off,
;                                         int bid, int nblk, unsigned char* smem) {
;     ...
;     for (int k = tid; k < 1024; k += 256) {
;       gs[k] = g[k] * (1.0f + modval<FIRST>(p, b, scale_off + k));
;       sh[k] = modval<FIRST>(p, b, shift_off + k);
;     }
.LBB0_876:
	v_ashrrev_i32_e32 v5, 31, v1
	v_mov_b32_e32 v4, v1
	v_ashrrev_i32_e32 v7, 31, v0
	v_mov_b32_e32 v6, v0
	v_lshlrev_b64 v[6:7], 2, v[6:7]
	v_lshlrev_b64 v[4:5], 2, v[4:5]
	v_lshl_add_u64 v[8:9], s[62:63], 0, v[6:7]
	v_lshl_add_u64 v[10:11], s[62:63], 0, v[4:5]
	v_lshl_add_u64 v[6:7], s[34:35], 0, v[6:7]
	global_load_dword v8, v[8:9], off
	s_nop 0
	global_load_dword v9, v[10:11], off
	v_add_co_u32_e32 v10, vcc, s47, v6
	v_lshl_add_u64 v[4:5], s[34:35], 0, v[4:5]
	s_nop 0
	v_addc_co_u32_e32 v11, vcc, 0, v7, vcc
	v_add_co_u32_e32 v12, vcc, s47, v4
	v_add_u32_e32 v3, -1, v3
	s_nop 0
	v_addc_co_u32_e32 v13, vcc, 0, v5, vcc
	v_add_co_u32_e32 v6, vcc, s48, v6
	global_load_dword v10, v[10:11], off
	s_nop 0
	global_load_dword v11, v[12:13], off
	v_addc_co_u32_e32 v7, vcc, 0, v7, vcc
	v_add_co_u32_e32 v4, vcc, 0x3000, v4
	v_add_u32_e32 v1, 0x200, v1
	s_nop 0
	v_addc_co_u32_e32 v5, vcc, 0, v5, vcc
	global_load_dword v6, v[6:7], off
	s_nop 0
	global_load_dword v7, v[4:5], off
	v_cmp_eq_u32_e32 vcc, 0, v3
	v_add_u32_e32 v0, 0x200, v0
	s_or_b64 s[44:45], vcc, s[44:45]
	s_waitcnt vmcnt(2)
	v_add_f32_e64 v4, v10, 1.0
	v_add_f32_e64 v5, v11, 1.0
	s_nop 0
	v_mul_f32_e64 v4, v8, v4
	v_mul_f32_e64 v5, v9, v5
	ds_write2st64_b32 v2, v4, v5 offset1:4
	s_waitcnt vmcnt(0)
	ds_write2st64_b32 v2, v6, v7 offset0:16 offset1:20
	v_add_u32_e32 v2, 0x800, v2
	s_andn2_b64 exec, exec, s[44:45]
	s_cbranch_execnz .LBB0_876

; DI void store4(u16* dst, f32x4 v) { uint2 w; w.x = cvtpk(v[0], v[1]); w.y = cvtpk(v[2], v[3]); *(uint2*)dst = w; }
; template <bool FIRST> DI void norm_pass(const Params& p, const float* __restrict__ src, const u16* __restrict__ srcb, const float* __restrict__ g, int shift_off, int scale_off,
;                                         int bid, int nblk, unsigned char* smem) {
;     ...
;     for (int r = 0; r < 32; ++r) {
;       const size_t row = row0 + r;
;       if (r + 1 < 32) ldrow(nv, row + 1);
;       float ss = 0.f;
; #pragma unroll
;       for (int i = 0; i < 4; ++i) ss += v[i].x * v[i].x + v[i].y * v[i].y + v[i].z * v[i].z + v[i].w * v[i].w;
; #pragma unroll
;       for (int o = 32; o >= 1; o >>= 1) ss += __shfl_xor(ss, o);
;       const float rstd = rsqrtf(ss * (1.0f / 1024.0f) + 1e-6f);
; #pragma unroll
;       for (int i = 0; i < 4; ++i) {
;         const int k = (lane + 64 * i) * 4;
;         const float4 gg = *(const float4*)(gs + k), hh = *(const float4*)(sh + k);
;         f32x4 o = {v[i].x * rstd * gg.x + hh.x, v[i].y * rstd * gg.y + hh.y, v[i].z * rstd * gg.z + hh.z, v[i].w * rstd * gg.w + hh.w};
;         store4(dst + ((size_t)(k >> 5) * Tn + row) * 32 + (k & 31), o);
;       }
; #pragma unroll
;       for (int i = 0; i < 4; ++i) v[i] = nv[i];
;     }
.LBB0_884:
	v_lshl_add_u64 v[86:87], s[42:43], 0, v[60:61]
	global_load_dwordx2 v[126:127], v[86:87], off offset:512
	global_load_dwordx2 v[128:129], v[86:87], off
	global_load_dwordx2 v[130:131], v[86:87], off offset:-512
	global_load_dwordx2 v[132:133], v[86:87], off offset:-1024
	v_mov_b32_e32 v88, v74
	v_mov_b32_e32 v89, v70
	v_mov_b32_e32 v90, v75
	v_mov_b32_e32 v91, v71
	v_mov_b32_e32 v96, v82
	v_mov_b32_e32 v97, v78
	v_mul_f32_e64 v86, v88, v88
	v_mul_f32_e64 v87, v89, v89
	v_mov_b32_e32 v92, v76
	v_mov_b32_e32 v93, v72
	v_mov_b32_e32 v98, v83
	v_mov_b32_e32 v99, v79
	v_mul_f32_e64 v88, v96, v96
	v_mul_f32_e64 v89, v97, v97
	v_fma_f32 v86, v90, v90, v86
	v_fma_f32 v87, v91, v91, v87
	v_mov_b32_e32 v94, v77
	v_mov_b32_e32 v95, v73
	v_mov_b32_e32 v100, v84
	v_mov_b32_e32 v101, v80
	v_fma_f32 v88, v98, v98, v88
	v_fma_f32 v89, v99, v99, v89
	v_fma_f32 v86, v92, v92, v86
	v_fma_f32 v87, v93, v93, v87
	v_mov_b32_e32 v116, v85
	v_mov_b32_e32 v117, v81
	v_fma_f32 v88, v100, v100, v88
	v_fma_f32 v89, v101, v101, v89
	v_fma_f32 v86, v94, v94, v86
	v_fma_f32 v87, v95, v95, v87
	v_fma_f32 v88, v116, v116, v88
	v_fma_f32 v89, v117, v117, v89
	v_add_f32_e32 v86, v86, v87
	v_add_f32_e32 v86, v89, v86
	v_add_f32_e32 v86, v88, v86
	ds_bpermute_b32 v87, v103, v86
	v_lshl_add_u64 v[118:119], s[42:43], 0, v[68:69]
	v_add_co_u32_e32 v96, vcc, s51, v118
	v_lshl_add_u64 v[120:121], s[42:43], 0, v[66:67]
	s_waitcnt lgkmcnt(0)
	v_add_f32_e32 v86, v86, v87
	ds_bpermute_b32 v87, v104, v86
	v_addc_co_u32_e32 v97, vcc, 0, v119, vcc
	v_add_co_u32_e32 v118, vcc, s51, v120
	s_waitcnt lgkmcnt(0)
	v_add_f32_e32 v86, v86, v87
	ds_bpermute_b32 v87, v105, v86
	v_lshl_add_u64 v[122:123], s[42:43], 0, v[64:65]
	v_addc_co_u32_e32 v119, vcc, 0, v121, vcc
	v_add_co_u32_e32 v120, vcc, s51, v122
	s_waitcnt lgkmcnt(0)
	v_add_f32_e32 v86, v86, v87
	ds_bpermute_b32 v87, v106, v86
	v_lshl_add_u64 v[124:125], s[42:43], 0, v[62:63]
	v_addc_co_u32_e32 v121, vcc, 0, v123, vcc
	v_add_co_u32_e32 v122, vcc, s51, v124
	s_waitcnt lgkmcnt(0)
	v_add_f32_e32 v86, v86, v87
	ds_bpermute_b32 v87, v107, v86
	v_addc_co_u32_e32 v123, vcc, 0, v125, vcc
	s_add_i32 s27, s27, -1
	v_lshl_add_u64 v[68:69], v[68:69], 0, 64
	s_waitcnt lgkmcnt(0)
	v_add_f32_e32 v86, v86, v87
	ds_bpermute_b32 v87, v108, v86
	v_lshl_add_u64 v[66:67], v[66:67], 0, 64
	v_lshl_add_u64 v[64:65], v[64:65], 0, 64
	v_lshl_add_u64 v[62:63], v[62:63], 0, 64
	v_lshl_add_u64 v[60:61], v[60:61], 0, s[24:25]
	s_waitcnt lgkmcnt(0)
	v_add_f32_e32 v86, v86, v87
	v_fmamk_f32 v86, v86, 0x3a800000, v114
	v_mul_f32_e32 v87, 0x4b800000, v86
	v_cmp_gt_f32_e32 vcc, s50, v86
	s_cmp_eq_u32 s27, 0
	s_waitcnt vmcnt(3)
	v_and_b32_e32 v89, 0xffff0000, v126
	v_cndmask_b32_e32 v86, v86, v87, vcc
	v_rsq_f32_e32 v86, v86
	v_lshlrev_b32_e32 v88, 16, v126
	s_waitcnt vmcnt(2)
	v_and_b32_e32 v91, 0xffff0000, v129
	v_lshlrev_b32_e32 v90, 16, v129
	v_mul_f32_e32 v87, 0x45800000, v86
	v_cndmask_b32_e32 v86, v86, v87, vcc
	v_mul_f32_e64 v70, v70, v86
	v_mul_f32_e64 v71, v71, v86
	v_mul_f32_e64 v72, v72, v86
	v_mul_f32_e64 v73, v73, v86
	v_mul_f32_e64 v74, v74, v86
	v_mul_f32_e64 v75, v75, v86
	v_mul_f32_e64 v76, v76, v86
	v_mul_f32_e64 v77, v77, v86
	v_mul_f32_e64 v78, v78, v86
	v_mul_f32_e64 v79, v79, v86
	v_mul_f32_e64 v80, v80, v86
	v_mul_f32_e64 v81, v81, v86
	v_mul_f32_e64 v82, v82, v86
	v_mul_f32_e64 v83, v83, v86
	v_mul_f32_e64 v84, v84, v86
	v_mul_f32_e64 v85, v85, v86
	v_fma_f32 v70, v0, v70, v20
	v_fma_f32 v71, v1, v71, v21
	v_fma_f32 v72, v2, v72, v22
	v_fma_f32 v73, v3, v73, v23
	v_fma_f32 v74, v74, v4, v16
	v_fma_f32 v75, v75, v5, v17
	v_fma_f32 v76, v76, v6, v18
	v_fma_f32 v77, v77, v7, v19
	v_fma_f32 v78, v78, v8, v28
	v_fma_f32 v79, v79, v9, v29
	v_fma_f32 v80, v80, v10, v30
	v_fma_f32 v81, v81, v11, v31
	v_fma_f32 v82, v82, v12, v24
	v_fma_f32 v83, v83, v13, v25
	v_fma_f32 v84, v84, v14, v26
	v_fma_f32 v85, v85, v15, v27
	v_cvt_pk_bf16_f32 v70, v70, v71
	v_cvt_pk_bf16_f32 v71, v72, v73
	v_cvt_pk_bf16_f32 v72, v74, v75
	v_cvt_pk_bf16_f32 v73, v76, v77
	v_cvt_pk_bf16_f32 v74, v78, v79
	v_cvt_pk_bf16_f32 v75, v80, v81
	v_cvt_pk_bf16_f32 v76, v82, v83
	v_cvt_pk_bf16_f32 v77, v84, v85
	global_store_dwordx2 v[96:97], v[70:71], off offset:2048
	global_store_dwordx2 v[118:119], v[72:73], off offset:2048
	global_store_dwordx2 v[120:121], v[74:75], off offset:2048
	global_store_dwordx2 v[122:123], v[76:77], off offset:2048
	v_and_b32_e32 v87, 0xffff0000, v127
	v_lshlrev_b32_e32 v86, 16, v127
	v_and_b32_e32 v93, 0xffff0000, v128
	v_lshlrev_b32_e32 v92, 16, v128
	s_waitcnt vmcnt(5)
	v_and_b32_e32 v95, 0xffff0000, v131
	v_lshlrev_b32_e32 v94, 16, v131
	v_and_b32_e32 v97, 0xffff0000, v130
	v_lshlrev_b32_e32 v96, 16, v130
	s_waitcnt vmcnt(4)
	v_and_b32_e32 v99, 0xffff0000, v133
	v_lshlrev_b32_e32 v98, 16, v133
	v_and_b32_e32 v101, 0xffff0000, v132
	v_lshlrev_b32_e32 v100, 16, v132
	v_mov_b64_e32 v[70:71], v[100:101]
	v_mov_b64_e32 v[72:73], v[98:99]
	v_mov_b64_e32 v[74:75], v[96:97]
	v_mov_b64_e32 v[76:77], v[94:95]
	v_mov_b64_e32 v[78:79], v[92:93]
	v_mov_b64_e32 v[80:81], v[90:91]
	v_mov_b64_e32 v[82:83], v[88:89]
	v_mov_b64_e32 v[84:85], v[86:87]
	s_cbranch_scc0 .LBB0_884
; DI void store4(u16* dst, f32x4 v) { uint2 w; w.x = cvtpk(v[0], v[1]); w.y = cvtpk(v[2], v[3]); *(uint2*)dst = w; }
; template <bool FIRST> DI void norm_pass(const Params& p, const float* __restrict__ src, const u16* __restrict__ srcb, const float* __restrict__ g, int shift_off, int scale_off,
;                                         int bid, int nblk, unsigned char* smem) {
;     ...
;   for (int item = bid; item < 512; item += nblk) {
;     ...
;     for (int r = 0; r < 32; ++r) {
;       const size_t row = row0 + r;
;       if (r + 1 < 32) ldrow(nv, row + 1);
;       float ss = 0.f;
; #pragma unroll
;       for (int i = 0; i < 4; ++i) ss += v[i].x * v[i].x + v[i].y * v[i].y + v[i].z * v[i].z + v[i].w * v[i].w;
; #pragma unroll
;       for (int o = 32; o >= 1; o >>= 1) ss += __shfl_xor(ss, o);
;       const float rstd = rsqrtf(ss * (1.0f / 1024.0f) + 1e-6f);
; #pragma unroll
;       for (int i = 0; i < 4; ++i) {
;         const int k = (lane + 64 * i) * 4;
;         const float4 gg = *(const float4*)(gs + k), hh = *(const float4*)(sh + k);
;         f32x4 o = {v[i].x * rstd * gg.x + hh.x, v[i].y * rstd * gg.y + hh.y, v[i].z * rstd * gg.z + hh.z, v[i].w * rstd * gg.w + hh.w};
;         store4(dst + ((size_t)(k >> 5) * Tn + row) * 32 + (k & 31), o);
;       }
; #pragma unroll
;       for (int i = 0; i < 4; ++i) v[i] = nv[i];
;     }
	v_mov_b32_e32 v62, v97
	v_mov_b32_e32 v63, v101
	v_mov_b32_e32 v60, v96
	v_mov_b32_e32 v61, v100
	v_mul_f32_e64 v62, v62, v62
	v_mul_f32_e64 v63, v63, v63
	v_mov_b32_e32 v64, v89
	v_fma_f32 v60, v60, v60, v62
	v_fma_f32 v61, v61, v61, v63
	v_mov_b32_e32 v62, v94
	v_mov_b32_e32 v63, v98
	v_fma_f32 v60, v62, v62, v60
	v_fma_f32 v61, v63, v63, v61
	v_mov_b32_e32 v62, v95
	v_mov_b32_e32 v63, v99
	v_mov_b32_e32 v65, v93
	v_fma_f32 v60, v62, v62, v60
	v_fma_f32 v61, v63, v63, v61
	v_mov_b32_e32 v62, v88
	v_mov_b32_e32 v63, v92
	v_mul_f32_e64 v64, v64, v64
	v_mul_f32_e64 v65, v65, v65
	v_add_f32_e32 v60, v60, v61
	v_fma_f32 v62, v62, v62, v64
	v_fma_f32 v63, v63, v63, v65
	v_mov_b32_e32 v64, v86
	v_mov_b32_e32 v65, v90
	v_fma_f32 v62, v64, v64, v62
	v_fma_f32 v63, v65, v65, v63
	v_mov_b32_e32 v64, v87
	v_mov_b32_e32 v65, v91
	v_fma_f32 v62, v64, v64, v62
	v_fma_f32 v63, v65, v65, v63
	v_lshlrev_b64 v[58:59], 6, v[58:59]
	v_add_f32_e32 v60, v63, v60
	v_add_f32_e32 v60, v62, v60
	ds_bpermute_b32 v61, v103, v60
	v_lshl_add_u64 v[58:59], v[36:37], 0, v[58:59]
	s_add_i32 s26, s26, s92
	v_lshl_add_u64 v[48:49], v[48:49], 0, s[18:19]
	v_lshl_add_u64 v[50:51], v[50:51], 0, s[18:19]
	s_waitcnt lgkmcnt(0)
	v_add_f32_e32 v60, v60, v61
	ds_bpermute_b32 v61, v104, v60
	v_lshl_add_u64 v[52:53], v[52:53], 0, s[18:19]
	v_lshl_add_u64 v[54:55], v[54:55], 0, s[18:19]
	s_cmpk_gt_i32 s26, 0x1ff
	v_lshl_add_u64 v[56:57], v[56:57], 0, s[20:21]
	s_waitcnt lgkmcnt(0)
	v_add_f32_e32 v60, v60, v61
	ds_bpermute_b32 v61, v105, v60
	s_waitcnt lgkmcnt(0)
	v_add_f32_e32 v60, v60, v61
	ds_bpermute_b32 v61, v106, v60
	s_waitcnt lgkmcnt(0)
	v_add_f32_e32 v60, v60, v61
	ds_bpermute_b32 v61, v107, v60
	s_waitcnt lgkmcnt(0)
	v_add_f32_e32 v60, v60, v61
	ds_bpermute_b32 v61, v108, v60
	s_waitcnt lgkmcnt(0)
	v_add_f32_e32 v60, v60, v61
	v_fmamk_f32 v60, v60, 0x3a800000, v114
	v_mul_f32_e32 v61, 0x4b800000, v60
	v_cmp_gt_f32_e32 vcc, s50, v60
	s_nop 1
	v_cndmask_b32_e32 v60, v60, v61, vcc
	v_rsq_f32_e32 v62, v60
	v_lshl_add_u64 v[60:61], v[58:59], 0, v[38:39]
	v_mul_f32_e32 v63, 0x45800000, v62
	v_cndmask_b32_e32 v62, v62, v63, vcc
	v_mul_f32_e64 v64, v62, v100
	v_mul_f32_e64 v65, v62, v101
	v_mul_f32_e64 v66, v62, v98
	v_mul_f32_e64 v67, v62, v99
	v_fma_f32 v0, v0, v64, v20
	v_fma_f32 v1, v1, v65, v21
	v_fma_f32 v2, v2, v66, v22
	v_fma_f32 v3, v3, v67, v23
	v_mul_f32_e64 v68, v62, v96
	v_mul_f32_e64 v69, v62, v97
	v_cvt_pk_bf16_f32 v0, v0, v1
	v_cvt_pk_bf16_f32 v1, v2, v3
	v_mul_f32_e64 v2, v62, v94
	v_mul_f32_e64 v3, v62, v95
	global_store_dwordx2 v[60:61], v[0:1], off offset:1984
	v_fma_f32 v0, v4, v68, v16
	v_fma_f32 v1, v5, v69, v17
	v_fma_f32 v2, v6, v2, v18
	v_fma_f32 v3, v7, v3, v19
	v_lshl_add_u64 v[4:5], v[58:59], 0, v[40:41]
	v_cvt_pk_bf16_f32 v0, v0, v1
	v_cvt_pk_bf16_f32 v1, v2, v3
	global_store_dwordx2 v[4:5], v[0:1], off offset:1984
	v_mul_f32_e64 v0, v62, v92
	v_mul_f32_e64 v1, v62, v93
	v_mul_f32_e64 v2, v62, v90
	v_mul_f32_e64 v3, v62, v91
	v_fma_f32 v0, v8, v0, v28
	v_fma_f32 v1, v9, v1, v29
	v_fma_f32 v2, v10, v2, v30
	v_fma_f32 v3, v11, v3, v31
	v_lshl_add_u64 v[4:5], v[58:59], 0, v[42:43]
	v_cvt_pk_bf16_f32 v0, v0, v1
	v_cvt_pk_bf16_f32 v1, v2, v3
	global_store_dwordx2 v[4:5], v[0:1], off offset:1984
	v_mul_f32_e64 v0, v62, v88
	v_mul_f32_e64 v1, v62, v89
	v_mul_f32_e64 v2, v62, v86
	v_mul_f32_e64 v3, v62, v87
	v_fma_f32 v0, v12, v0, v24
	v_fma_f32 v1, v13, v1, v25
	v_fma_f32 v2, v14, v2, v26
	v_fma_f32 v3, v15, v3, v27
	v_lshl_add_u64 v[4:5], v[58:59], 0, v[44:45]
	v_cvt_pk_bf16_f32 v0, v0, v1
	v_cvt_pk_bf16_f32 v1, v2, v3
	global_store_dwordx2 v[4:5], v[0:1], off offset:1984
	s_cbranch_scc0 .LBB0_868

; DI float sigmoidf_(float x) { return 1.0f / (1.0f + __expf(-x)); }
; DI void store4(u16* dst, f32x4 v) { uint2 w; w.x = cvtpk(v[0], v[1]); w.y = cvtpk(v[2], v[3]); *(uint2*)dst = w; }
; DI void phase8(const Params& p, const Sched& sched, unsigned char* smem) {
;     ...
;         const int fl = wf * 16 + lq * 4, fc = (2 * wf + h2) * 16 + lq * 4, F = tn * 64 + fc;
;         __syncthreads();
; #pragma unroll
;         for (int ni = 0; ni < 8; ++ni) *(f32x4*)(gl + (wt * 128 + ni * 16 + lr) * 36 + fl) = acc[2 * h2][ni];
;         __syncthreads();
;         const float4 w0 = *(const float4*)(p.conv_w + F), w1 = *(const float4*)(p.conv_w + FF + F), w2 = *(const float4*)(p.conv_w + 2 * FF + F), cb = *(const float4*)(p.conv_b + F);
; #pragma unroll
;         for (int ni = 0; ni < 8; ++ni) {
;           const int row = wt * 128 + ni * 16 + lr;
;           const f32x4 gv = acc[2 * h2][ni], uv = acc[2 * h2 + 1][ni];
;           if (row >= 2) {
;             const f32x4 g1 = *(const f32x4*)(gl + (row - 1) * 36 + fl), g2 = *(const f32x4*)(gl + (row - 2) * 36 + fl);
;             f32x4 o;
;             o[0] = cb.x + w0.x * g2[0] + w1.x * g1[0] + w2.x * gv[0];
;             o[1] = cb.y + w0.y * g2[1] + w1.y * g1[1] + w2.y * gv[1];
;             o[2] = cb.z + w0.z * g2[2] + w1.z * g1[2] + w2.z * gv[2];
;             o[3] = cb.w + w0.w * g2[3] + w1.w * g1[3] + w2.w * gv[3];
; #pragma unroll
;             for (int j = 0; j < 4; ++j) o[j] = o[j] * sigmoidf_(o[j]) * uv[j];
;             store4(Ls + row * 72 + fc, o);
.LBB0_948:
	s_or_saveexec_b64 s[6:7], s[6:7]
	v_mul_u32_u24_e32 v174, 0x90, v154
	v_lshlrev_b32_e32 v155, 1, v156
	v_lshl_add_u32 v175, v152, 2, v174
	v_add_u32_e32 v152, v155, v174
	v_add_u32_e32 v174, 0xffffff70, v175
	v_add_u32_e32 v175, 0xfffffee0, v175
	s_xor_b64 exec, exec, s[6:7]
	s_cbranch_execz .LBB0_950
	ds_read_b128 v[176:179], v175
	ds_read_b128 v[180:183], v174
	s_waitcnt vmcnt(1) lgkmcnt(1)
	v_fma_f32 v176, v84, v176, v88
	v_fma_f32 v177, v85, v177, v89
	s_waitcnt lgkmcnt(0)
	v_fma_f32 v176, v80, v180, v176
	v_fma_f32 v177, v81, v181, v177
	v_fma_f32 v178, v86, v178, v90
	v_fma_f32 v179, v87, v179, v91
	s_waitcnt vmcnt(0)
	v_fma_f32 v140, v140, v76, v176
	v_fma_f32 v141, v141, v77, v177
	v_fma_f32 v178, v82, v182, v178
	v_fma_f32 v179, v83, v183, v179
	v_mul_f32_e32 v176, 0xbfb8aa3b, v140
	v_mul_f32_e32 v177, 0xbfb8aa3b, v141
	v_exp_f32_e32 v176, v176
	v_exp_f32_e32 v177, v177
	v_fma_f32 v142, v142, v78, v178
	v_fma_f32 v143, v143, v79, v179
	v_add_f32_e64 v176, v176, 1.0
	v_add_f32_e64 v177, v177, 1.0
	s_nop 0
	v_rcp_f32_e32 v177, v177
	v_mul_f32_e32 v178, 0xbfb8aa3b, v142
	v_mul_f32_e32 v179, 0xbfb8aa3b, v143
	v_exp_f32_e32 v178, v178
	v_exp_f32_e32 v179, v179
	s_nop 0
	v_add_f32_e64 v178, v178, 1.0
	v_add_f32_e64 v179, v179, 1.0
	v_rcp_f32_e32 v176, v176
	s_nop 0
	v_mul_f32_e64 v140, v140, v176
	v_mul_f32_e64 v141, v141, v177
	s_nop 0
	v_mul_f32_e64 v136, v136, v140
	v_mul_f32_e64 v137, v137, v141
	v_rcp_f32_e32 v141, v179
	v_rcp_f32_e32 v140, v178
	s_nop 0
	v_mul_f32_e64 v140, v142, v140
	v_mul_f32_e64 v141, v143, v141
	v_cvt_pk_bf16_f32 v136, v136, v137
	v_mul_f32_e64 v138, v138, v140
	v_mul_f32_e64 v139, v139, v141
	s_nop 0
	v_cvt_pk_bf16_f32 v137, v138, v139
	ds_write_b64 v152, v[136:137] offset:36864
.LBB0_950:
	s_or_b64 exec, exec, s[6:7]
	v_add_u32_e32 v137, 0xfffffee0, v159
	v_add_u32_e32 v136, 0xffffff70, v159
	ds_read_b128 v[138:141], v137
	ds_read_b128 v[176:179], v136
	v_or_b32_e32 v142, 16, v154
	s_waitcnt vmcnt(1) lgkmcnt(1)
	v_fma_f32 v138, v84, v138, v88
	v_fma_f32 v139, v85, v139, v89
	s_waitcnt lgkmcnt(0)
	v_fma_f32 v138, v80, v176, v138
	v_fma_f32 v139, v81, v177, v139
	v_fma_f32 v140, v86, v140, v90
	v_fma_f32 v141, v87, v141, v91
	s_waitcnt vmcnt(0)
	v_fma_f32 v132, v132, v76, v138
	v_fma_f32 v133, v133, v77, v139
	v_fma_f32 v140, v82, v178, v140
	v_fma_f32 v141, v83, v179, v141
	v_mul_f32_e32 v138, 0xbfb8aa3b, v132
	v_mul_f32_e32 v139, 0xbfb8aa3b, v133
	v_exp_f32_e32 v138, v138
	v_exp_f32_e32 v139, v139
	v_fma_f32 v134, v134, v78, v140
	v_fma_f32 v135, v135, v79, v141
	v_add_f32_e64 v138, v138, 1.0
	v_add_f32_e64 v139, v139, 1.0
	s_nop 0
	v_rcp_f32_e32 v139, v139
	v_mul_f32_e32 v140, 0xbfb8aa3b, v134
	v_mul_f32_e32 v141, 0xbfb8aa3b, v135
	v_exp_f32_e32 v140, v140
	v_exp_f32_e32 v141, v141
	s_nop 0
	v_add_f32_e64 v140, v140, 1.0
	v_add_f32_e64 v141, v141, 1.0
	v_rcp_f32_e32 v138, v138
	s_nop 0
	v_mul_f32_e64 v132, v132, v138
	v_mul_f32_e64 v133, v133, v139
	s_nop 0
	v_mul_f32_e64 v132, v128, v132
	v_mul_f32_e64 v133, v129, v133
	v_rcp_f32_e32 v129, v141
	v_rcp_f32_e32 v128, v140
	s_nop 0
	v_mul_f32_e64 v128, v134, v128
	v_mul_f32_e64 v129, v135, v129
	v_cvt_pk_bf16_f32 v132, v132, v133
	v_mul_f32_e64 v130, v130, v128
	v_mul_f32_e64 v131, v131, v129
	v_mul_u32_u24_e32 v128, 0x48, v142
	v_lshl_add_u32 v128, v128, 1, v155
	v_cvt_pk_bf16_f32 v133, v130, v131
	ds_write_b64 v128, v[132:133] offset:36864
	v_add_u32_e32 v130, 0xfffffee0, v168
	v_add_u32_e32 v129, 0xffffff70, v168
	ds_read_b128 v[132:135], v130
	ds_read_b128 v[138:141], v129
	s_waitcnt lgkmcnt(1)
	v_fma_f32 v132, v84, v132, v88
	v_fma_f32 v133, v85, v133, v89
	s_waitcnt lgkmcnt(0)
	v_fma_f32 v132, v80, v138, v132
	v_fma_f32 v133, v81, v139, v133
	v_fma_f32 v134, v86, v134, v90
	v_fma_f32 v135, v87, v135, v91
	v_fma_f32 v124, v124, v76, v132
	v_fma_f32 v125, v125, v77, v133
	v_fma_f32 v134, v82, v140, v134
	v_fma_f32 v135, v83, v141, v135
	v_mul_f32_e32 v131, 0xbfb8aa3b, v124
	v_exp_f32_e32 v132, v131
	v_mul_f32_e32 v131, 0xbfb8aa3b, v125
	v_exp_f32_e32 v133, v131
	v_fma_f32 v126, v126, v78, v134
	v_fma_f32 v127, v127, v79, v135
	v_add_f32_e64 v132, v132, 1.0
	v_add_f32_e64 v133, v133, 1.0
	s_nop 0
	v_mul_f32_e32 v134, 0xbfb8aa3b, v126
	v_mul_f32_e32 v135, 0xbfb8aa3b, v127
	v_exp_f32_e32 v134, v134
	v_rcp_f32_e32 v133, v133
	v_exp_f32_e32 v135, v135
	s_nop 0
	v_add_f32_e64 v134, v134, 1.0
	v_add_f32_e64 v135, v135, 1.0
	v_rcp_f32_e32 v132, v132
	s_nop 0
	v_mul_f32_e64 v124, v124, v132
	v_mul_f32_e64 v125, v125, v133
	s_nop 0
	v_mul_f32_e64 v120, v120, v124
	v_mul_f32_e64 v121, v121, v125
	v_rcp_f32_e32 v125, v135
	v_rcp_f32_e32 v124, v134
	s_nop 0
	v_mul_f32_e64 v124, v126, v124
	v_mul_f32_e64 v125, v127, v125
	v_cvt_pk_bf16_f32 v120, v120, v121
	v_mul_f32_e64 v122, v122, v124
	v_mul_f32_e64 v123, v123, v125
	s_nop 0
	v_cvt_pk_bf16_f32 v121, v122, v123
	ds_write_b64 v128, v[120:121] offset:39168
	v_add_u32_e32 v121, 0xfffffee0, v169
	v_add_u32_e32 v120, 0xffffff70, v169
	ds_read_b128 v[122:125], v121
	ds_read_b128 v[132:135], v120
	s_waitcnt lgkmcnt(1)
	v_fma_f32 v122, v84, v122, v88
	v_fma_f32 v123, v85, v123, v89
	s_waitcnt lgkmcnt(0)
; DI float sigmoidf_(float x) { return 1.0f / (1.0f + __expf(-x)); }
; DI void store4(u16* dst, f32x4 v) { uint2 w; w.x = cvtpk(v[0], v[1]); w.y = cvtpk(v[2], v[3]); *(uint2*)dst = w; }
; DI void phase8(const Params& p, const Sched& sched, unsigned char* smem) {
;     ...
; #pragma unroll
;         for (int ni = 0; ni < 8; ++ni) {
;           const int row = wt * 128 + ni * 16 + lr;
;           const f32x4 gv = acc[2 * h2][ni], uv = acc[2 * h2 + 1][ni];
;           if (row >= 2) {
;             const f32x4 g1 = *(const f32x4*)(gl + (row - 1) * 36 + fl), g2 = *(const f32x4*)(gl + (row - 2) * 36 + fl);
;             f32x4 o;
;             o[0] = cb.x + w0.x * g2[0] + w1.x * g1[0] + w2.x * gv[0];
;             o[1] = cb.y + w0.y * g2[1] + w1.y * g1[1] + w2.y * gv[1];
;             o[2] = cb.z + w0.z * g2[2] + w1.z * g1[2] + w2.z * gv[2];
;             o[3] = cb.w + w0.w * g2[3] + w1.w * g1[3] + w2.w * gv[3];
; #pragma unroll
;             for (int j = 0; j < 4; ++j) o[j] = o[j] * sigmoidf_(o[j]) * uv[j];
;             store4(Ls + row * 72 + fc, o);
	v_fma_f32 v122, v80, v132, v122
	v_fma_f32 v123, v81, v133, v123
	v_fma_f32 v124, v86, v124, v90
	v_fma_f32 v125, v87, v125, v91
	v_fma_f32 v116, v116, v76, v122
	v_fma_f32 v117, v117, v77, v123
	v_fma_f32 v124, v82, v134, v124
	v_fma_f32 v125, v83, v135, v125
	v_mul_f32_e32 v122, 0xbfb8aa3b, v116
	v_mul_f32_e32 v123, 0xbfb8aa3b, v117
	v_exp_f32_e32 v122, v122
	v_exp_f32_e32 v123, v123
	v_fma_f32 v118, v118, v78, v124
	v_fma_f32 v119, v119, v79, v125
	v_add_f32_e64 v122, v122, 1.0
	v_add_f32_e64 v123, v123, 1.0
	s_nop 0
	v_mul_f32_e32 v124, 0xbfb8aa3b, v118
	v_mul_f32_e32 v125, 0xbfb8aa3b, v119
	v_exp_f32_e32 v124, v124
	v_rcp_f32_e32 v123, v123
	v_exp_f32_e32 v125, v125
	s_nop 0
	v_add_f32_e64 v124, v124, 1.0
	v_add_f32_e64 v125, v125, 1.0
	v_rcp_f32_e32 v122, v122
	s_nop 0
	v_mul_f32_e64 v116, v116, v122
	v_mul_f32_e64 v117, v117, v123
	s_nop 0
	v_mul_f32_e64 v112, v112, v116
	v_mul_f32_e64 v113, v113, v117
	v_rcp_f32_e32 v117, v125
	v_rcp_f32_e32 v116, v124
	s_nop 0
	v_mul_f32_e64 v116, v118, v116
	v_mul_f32_e64 v117, v119, v117
	v_cvt_pk_bf16_f32 v112, v112, v113
	v_mul_f32_e64 v114, v114, v116
	v_mul_f32_e64 v115, v115, v117
	s_nop 0
	v_cvt_pk_bf16_f32 v113, v114, v115
	ds_write_b64 v128, v[112:113] offset:41472
	v_add_u32_e32 v113, 0xfffffee0, v170
	v_add_u32_e32 v112, 0xffffff70, v170
	ds_read_b128 v[114:117], v113
	ds_read_b128 v[122:125], v112
	s_waitcnt lgkmcnt(1)
	v_fma_f32 v114, v84, v114, v88
	v_fma_f32 v115, v85, v115, v89
	s_waitcnt lgkmcnt(0)
	v_fma_f32 v114, v80, v122, v114
	v_fma_f32 v115, v81, v123, v115
	v_fma_f32 v116, v86, v116, v90
	v_fma_f32 v117, v87, v117, v91
	v_fma_f32 v108, v108, v76, v114
	v_fma_f32 v109, v109, v77, v115
	v_fma_f32 v116, v82, v124, v116
	v_fma_f32 v117, v83, v125, v117
	v_mul_f32_e32 v114, 0xbfb8aa3b, v108
	v_mul_f32_e32 v115, 0xbfb8aa3b, v109
	v_exp_f32_e32 v114, v114
	v_exp_f32_e32 v115, v115
	v_fma_f32 v110, v110, v78, v116
	v_fma_f32 v111, v111, v79, v117
	v_add_f32_e64 v114, v114, 1.0
	v_add_f32_e64 v115, v115, 1.0
	s_nop 0
	v_mul_f32_e32 v116, 0xbfb8aa3b, v110
	v_mul_f32_e32 v117, 0xbfb8aa3b, v111
	v_exp_f32_e32 v116, v116
	v_rcp_f32_e32 v115, v115
	v_exp_f32_e32 v117, v117
	s_nop 0
	v_add_f32_e64 v116, v116, 1.0
	v_add_f32_e64 v117, v117, 1.0
	v_rcp_f32_e32 v114, v114
	s_nop 0
	v_mul_f32_e64 v108, v108, v114
	v_mul_f32_e64 v109, v109, v115
	s_nop 0
	v_mul_f32_e64 v104, v104, v108
	v_mul_f32_e64 v105, v105, v109
	v_rcp_f32_e32 v109, v117
	v_rcp_f32_e32 v108, v116
	s_nop 0
	v_mul_f32_e64 v108, v110, v108
	v_mul_f32_e64 v109, v111, v109
	v_cvt_pk_bf16_f32 v104, v104, v105
	v_mul_f32_e64 v106, v106, v108
	v_mul_f32_e64 v107, v107, v109
	s_nop 0
	v_cvt_pk_bf16_f32 v105, v106, v107
	ds_write_b64 v128, v[104:105] offset:43776
	v_add_u32_e32 v105, 0xfffffee0, v171
	v_add_u32_e32 v104, 0xffffff70, v171
	ds_read_b128 v[106:109], v105
	ds_read_b128 v[114:117], v104
	s_waitcnt lgkmcnt(1)
	v_fma_f32 v106, v84, v106, v88
	v_fma_f32 v107, v85, v107, v89
	s_waitcnt lgkmcnt(0)
	v_fma_f32 v106, v80, v114, v106
	v_fma_f32 v107, v81, v115, v107
	v_fma_f32 v108, v86, v108, v90
	v_fma_f32 v109, v87, v109, v91
	v_fma_f32 v100, v100, v76, v106
	v_fma_f32 v101, v101, v77, v107
	v_fma_f32 v108, v82, v116, v108
	v_fma_f32 v109, v83, v117, v109
	v_mul_f32_e32 v106, 0xbfb8aa3b, v100
	v_mul_f32_e32 v107, 0xbfb8aa3b, v101
	v_exp_f32_e32 v106, v106
	v_exp_f32_e32 v107, v107
	v_fma_f32 v102, v102, v78, v108
	v_fma_f32 v103, v103, v79, v109
	v_add_f32_e64 v106, v106, 1.0
	v_add_f32_e64 v107, v107, 1.0
	s_nop 0
	v_mul_f32_e32 v108, 0xbfb8aa3b, v102
	v_mul_f32_e32 v109, 0xbfb8aa3b, v103
	v_exp_f32_e32 v108, v108
	v_rcp_f32_e32 v107, v107
	v_exp_f32_e32 v109, v109
	s_nop 0
	v_add_f32_e64 v108, v108, 1.0
	v_add_f32_e64 v109, v109, 1.0
	v_rcp_f32_e32 v106, v106
	s_nop 0
	v_mul_f32_e64 v100, v100, v106
	v_mul_f32_e64 v101, v101, v107
	s_nop 0
	v_mul_f32_e64 v96, v96, v100
	v_mul_f32_e64 v97, v97, v101
	v_rcp_f32_e32 v101, v109
	v_rcp_f32_e32 v100, v108
	s_nop 0
	v_mul_f32_e64 v100, v102, v100
	v_mul_f32_e64 v101, v103, v101
	v_cvt_pk_bf16_f32 v96, v96, v97
	v_mul_f32_e64 v98, v98, v100
	v_mul_f32_e64 v99, v99, v101
	s_nop 0
	v_cvt_pk_bf16_f32 v97, v98, v99
	ds_write_b64 v128, v[96:97] offset:46080
	v_add_u32_e32 v97, 0xfffffee0, v172
	v_add_u32_e32 v96, 0xffffff70, v172
	ds_read_b128 v[98:101], v97
	ds_read_b128 v[106:109], v96
	s_waitcnt lgkmcnt(1)
; DI float sigmoidf_(float x) { return 1.0f / (1.0f + __expf(-x)); }
; DI void store4(u16* dst, f32x4 v) { uint2 w; w.x = cvtpk(v[0], v[1]); w.y = cvtpk(v[2], v[3]); *(uint2*)dst = w; }
; DI void phase8(const Params& p, const Sched& sched, unsigned char* smem) {
;     ...
; #pragma unroll
;         for (int ni = 0; ni < 8; ++ni) {
;           const int row = wt * 128 + ni * 16 + lr;
;           const f32x4 gv = acc[2 * h2][ni], uv = acc[2 * h2 + 1][ni];
;           if (row >= 2) {
;             const f32x4 g1 = *(const f32x4*)(gl + (row - 1) * 36 + fl), g2 = *(const f32x4*)(gl + (row - 2) * 36 + fl);
;             f32x4 o;
;             o[0] = cb.x + w0.x * g2[0] + w1.x * g1[0] + w2.x * gv[0];
;             o[1] = cb.y + w0.y * g2[1] + w1.y * g1[1] + w2.y * gv[1];
;             o[2] = cb.z + w0.z * g2[2] + w1.z * g1[2] + w2.z * gv[2];
;             o[3] = cb.w + w0.w * g2[3] + w1.w * g1[3] + w2.w * gv[3];
; #pragma unroll
;             for (int j = 0; j < 4; ++j) o[j] = o[j] * sigmoidf_(o[j]) * uv[j];
;             store4(Ls + row * 72 + fc, o);
;           } else {
;             *(f32x4*)(gside + ((size_t)tm * 4 + row) * FF + F) = gv;
;             *(f32x4*)(uside + ((size_t)tm * 2 + row) * FF + F) = uv;
;           }
;           if (row >= 254) *(f32x4*)(gside + ((size_t)tm * 4 + 2 + (row - 254)) * FF + F) = gv;
	v_fma_f32 v98, v84, v98, v88
	v_fma_f32 v99, v85, v99, v89
	s_waitcnt lgkmcnt(0)
	v_fma_f32 v98, v80, v106, v98
	v_fma_f32 v99, v81, v107, v99
	v_fma_f32 v100, v86, v100, v90
	v_fma_f32 v101, v87, v101, v91
	v_fma_f32 v92, v92, v76, v98
	v_fma_f32 v93, v93, v77, v99
	v_fma_f32 v100, v82, v108, v100
	v_fma_f32 v101, v83, v109, v101
	v_mul_f32_e32 v98, 0xbfb8aa3b, v92
	v_mul_f32_e32 v99, 0xbfb8aa3b, v93
	v_exp_f32_e32 v98, v98
	v_exp_f32_e32 v99, v99
	v_fma_f32 v94, v94, v78, v100
	v_fma_f32 v95, v95, v79, v101
	v_add_f32_e64 v98, v98, 1.0
	v_add_f32_e64 v99, v99, 1.0
	s_nop 0
	v_mul_f32_e32 v100, 0xbfb8aa3b, v94
	v_mul_f32_e32 v101, 0xbfb8aa3b, v95
	v_exp_f32_e32 v100, v100
	v_rcp_f32_e32 v99, v99
	v_exp_f32_e32 v101, v101
	s_nop 0
	v_add_f32_e64 v100, v100, 1.0
	v_add_f32_e64 v101, v101, 1.0
	v_rcp_f32_e32 v98, v98
	s_nop 0
	v_mul_f32_e64 v92, v92, v98
	v_mul_f32_e64 v93, v93, v99
	s_nop 0
	v_mul_f32_e64 v72, v72, v92
	v_mul_f32_e64 v73, v73, v93
	v_rcp_f32_e32 v93, v101
	v_rcp_f32_e32 v92, v100
	s_nop 0
	v_mul_f32_e64 v92, v94, v92
	v_mul_f32_e64 v93, v95, v93
	v_cvt_pk_bf16_f32 v72, v72, v73
	v_mul_f32_e64 v74, v74, v92
	v_mul_f32_e64 v75, v75, v93
	v_add_u32_e32 v93, 0xfffffee0, v173
	v_cvt_pk_bf16_f32 v73, v74, v75
	ds_write_b64 v128, v[72:73] offset:48384
	v_add_u32_e32 v92, 0xffffff70, v173
	ds_read_b128 v[72:75], v93
	ds_read_b128 v[98:101], v92
	s_waitcnt lgkmcnt(1)
	v_fma_f32 v72, v84, v72, v88
	v_fma_f32 v73, v85, v73, v89
	s_waitcnt lgkmcnt(0)
	v_fma_f32 v72, v80, v98, v72
	v_fma_f32 v73, v81, v99, v73
	v_fma_f32 v74, v86, v74, v90
	v_fma_f32 v75, v87, v75, v91
	v_fma_f32 v72, v64, v76, v72
	v_fma_f32 v73, v65, v77, v73
	v_fma_f32 v74, v82, v100, v74
	v_fma_f32 v75, v83, v101, v75
	v_mul_f32_e32 v76, 0xbfb8aa3b, v72
	v_mul_f32_e32 v77, 0xbfb8aa3b, v73
	v_exp_f32_e32 v76, v76
	v_exp_f32_e32 v77, v77
	v_fma_f32 v74, v66, v78, v74
	v_fma_f32 v75, v67, v79, v75
	v_or_b32_e32 v84, 0x70, v154
	v_mul_f32_e32 v78, 0xbfb8aa3b, v74
	v_add_f32_e64 v76, v76, 1.0
	v_add_f32_e64 v77, v77, 1.0
	v_mul_f32_e32 v79, 0xbfb8aa3b, v75
	v_exp_f32_e32 v78, v78
	v_exp_f32_e32 v79, v79
	v_rcp_f32_e32 v77, v77
	v_add_f32_e64 v78, v78, 1.0
	v_add_f32_e64 v79, v79, 1.0
	v_rcp_f32_e32 v76, v76
	s_nop 0
	v_mul_f32_e64 v72, v72, v76
	v_mul_f32_e64 v73, v73, v77
	s_nop 0
	v_mul_f32_e64 v68, v68, v72
	v_mul_f32_e64 v69, v69, v73
	v_rcp_f32_e32 v73, v79
	v_rcp_f32_e32 v72, v78
	s_nop 0
	v_mul_f32_e64 v72, v74, v72
	v_mul_f32_e64 v73, v75, v73
	v_cvt_pk_bf16_f32 v68, v68, v69
	v_mul_f32_e64 v70, v70, v72
	v_mul_f32_e64 v71, v71, v73
	v_cmp_lt_u32_e64 s[6:7], s49, v84
	v_cvt_pk_bf16_f32 v69, v70, v71
	ds_write_b64 v128, v[68:69] offset:50688
	s_and_saveexec_b64 s[34:35], s[6:7]
	s_cbranch_execz .LBB0_952
	s_ashr_i32 s31, s30, 31
	s_lshl_b64 s[58:59], s[30:31], 2
	s_add_u32 s58, s58, 0xffffff74
	v_mov_b32_e32 v155, v153
	s_addc_u32 s59, s59, -1
	v_lshl_add_u64 v[68:69], s[58:59], 0, v[154:155]
	v_mov_b64_e32 v[70:71], s[16:17]
	v_mad_u64_u32 v[70:71], s[58:59], v68, s48, v[70:71]
	v_mad_i32_i24 v71, v69, s48, v71
	v_lshl_add_u64 v[68:69], v[144:145], 2, v[70:71]
	global_store_dwordx4 v[68:69], v[64:67], off

; DI float sigmoidf_(float x) { return 1.0f / (1.0f + __expf(-x)); }
; DI void store4(u16* dst, f32x4 v) { uint2 w; w.x = cvtpk(v[0], v[1]); w.y = cvtpk(v[2], v[3]); *(uint2*)dst = w; }
; DI void phase8(const Params& p, const Sched& sched, unsigned char* smem) {
;     ...
;       for (int h2 = 0; h2 < 2; ++h2) {
;         const int fl = wf * 16 + lq * 4, fc = (2 * wf + h2) * 16 + lq * 4, F = tn * 64 + fc;
;         __syncthreads();
; #pragma unroll
;         for (int ni = 0; ni < 8; ++ni) *(f32x4*)(gl + (wt * 128 + ni * 16 + lr) * 36 + fl) = acc[2 * h2][ni];
;         __syncthreads();
;         const float4 w0 = *(const float4*)(p.conv_w + F), w1 = *(const float4*)(p.conv_w + FF + F), w2 = *(const float4*)(p.conv_w + 2 * FF + F), cb = *(const float4*)(p.conv_b + F);
; #pragma unroll
;         for (int ni = 0; ni < 8; ++ni) {
;           const int row = wt * 128 + ni * 16 + lr;
;           const f32x4 gv = acc[2 * h2][ni], uv = acc[2 * h2 + 1][ni];
;           if (row >= 2) {
;             const f32x4 g1 = *(const f32x4*)(gl + (row - 1) * 36 + fl), g2 = *(const f32x4*)(gl + (row - 2) * 36 + fl);
;             f32x4 o;
;             o[0] = cb.x + w0.x * g2[0] + w1.x * g1[0] + w2.x * gv[0];
;             o[1] = cb.y + w0.y * g2[1] + w1.y * g1[1] + w2.y * gv[1];
;             o[2] = cb.z + w0.z * g2[2] + w1.z * g1[2] + w2.z * gv[2];
;             o[3] = cb.w + w0.w * g2[3] + w1.w * g1[3] + w2.w * gv[3];
; #pragma unroll
;             for (int j = 0; j < 4; ++j) o[j] = o[j] * sigmoidf_(o[j]) * uv[j];
;             store4(Ls + row * 72 + fc, o);
.LBB0_954:
	s_andn2_saveexec_b64 s[4:5], s[4:5]
	s_cbranch_execz .LBB0_956
	ds_read_b128 v[80:83], v175
	ds_read_b128 v[84:87], v174
	s_waitcnt vmcnt(0) lgkmcnt(1)
	v_fma_f32 v80, v72, v80, v76
	v_fma_f32 v81, v73, v81, v77
	s_waitcnt lgkmcnt(0)
	v_fma_f32 v80, v68, v84, v80
	v_fma_f32 v81, v69, v85, v81
	v_fma_f32 v82, v74, v82, v78
	v_fma_f32 v83, v75, v83, v79
	v_fma_f32 v60, v60, v64, v80
	v_fma_f32 v61, v61, v65, v81
	v_fma_f32 v82, v70, v86, v82
	v_fma_f32 v83, v71, v87, v83
	v_mul_f32_e32 v80, 0xbfb8aa3b, v60
	v_mul_f32_e32 v81, 0xbfb8aa3b, v61
	v_exp_f32_e32 v80, v80
	v_exp_f32_e32 v81, v81
	v_fma_f32 v62, v62, v66, v82
	v_fma_f32 v63, v63, v67, v83
	v_add_f32_e64 v80, v80, 1.0
	v_add_f32_e64 v81, v81, 1.0
	s_nop 0
	v_rcp_f32_e32 v81, v81
	v_mul_f32_e32 v82, 0xbfb8aa3b, v62
	v_mul_f32_e32 v83, 0xbfb8aa3b, v63
	v_exp_f32_e32 v82, v82
	v_exp_f32_e32 v83, v83
	s_nop 0
	v_add_f32_e64 v82, v82, 1.0
	v_add_f32_e64 v83, v83, 1.0
	v_rcp_f32_e32 v80, v80
	s_nop 0
	v_mul_f32_e64 v60, v60, v80
	v_mul_f32_e64 v61, v61, v81
	s_nop 0
	v_mul_f32_e64 v56, v56, v60
	v_mul_f32_e64 v57, v57, v61
	v_rcp_f32_e32 v61, v83
	v_rcp_f32_e32 v60, v82
	s_nop 0
	v_mul_f32_e64 v60, v62, v60
	v_mul_f32_e64 v61, v63, v61
	v_cvt_pk_bf16_f32 v56, v56, v57
	v_mul_f32_e64 v58, v58, v60
	v_mul_f32_e64 v59, v59, v61
	s_nop 0
	v_cvt_pk_bf16_f32 v57, v58, v59
	ds_write_b64 v152, v[56:57] offset:36896
.LBB0_956:
	s_or_b64 exec, exec, s[4:5]
	ds_read_b128 v[56:59], v137
	ds_read_b128 v[60:63], v136
	s_waitcnt vmcnt(0) lgkmcnt(1)
	v_fma_f32 v56, v72, v56, v76
	v_fma_f32 v57, v73, v57, v77
	s_waitcnt lgkmcnt(0)
	v_fma_f32 v56, v68, v60, v56
	v_fma_f32 v57, v69, v61, v57
	v_fma_f32 v58, v74, v58, v78
	v_fma_f32 v59, v75, v59, v79
	v_fma_f32 v52, v52, v64, v56
	v_fma_f32 v53, v53, v65, v57
	v_fma_f32 v58, v70, v62, v58
	v_fma_f32 v59, v71, v63, v59
	v_mul_f32_e32 v56, 0xbfb8aa3b, v52
	v_mul_f32_e32 v57, 0xbfb8aa3b, v53
	v_exp_f32_e32 v56, v56
	v_exp_f32_e32 v57, v57
	v_fma_f32 v54, v54, v66, v58
	v_fma_f32 v55, v55, v67, v59
	v_add_f32_e64 v56, v56, 1.0
	v_add_f32_e64 v57, v57, 1.0
	s_nop 0
	v_rcp_f32_e32 v57, v57
	v_mul_f32_e32 v58, 0xbfb8aa3b, v54
	v_mul_f32_e32 v59, 0xbfb8aa3b, v55
	v_exp_f32_e32 v58, v58
	v_exp_f32_e32 v59, v59
	s_nop 0
	v_add_f32_e64 v58, v58, 1.0
	v_add_f32_e64 v59, v59, 1.0
	v_rcp_f32_e32 v56, v56
	s_nop 0
	v_mul_f32_e64 v52, v52, v56
	v_mul_f32_e64 v53, v53, v57
	s_nop 0
	v_mul_f32_e64 v48, v48, v52
	v_mul_f32_e64 v49, v49, v53
	v_rcp_f32_e32 v53, v59
	v_rcp_f32_e32 v52, v58
	s_nop 0
	v_mul_f32_e64 v52, v54, v52
	v_mul_f32_e64 v53, v55, v53
	v_cvt_pk_bf16_f32 v48, v48, v49
	v_mul_f32_e64 v50, v50, v52
	v_mul_f32_e64 v51, v51, v53
	s_nop 0
	v_cvt_pk_bf16_f32 v49, v50, v51
	ds_write_b64 v128, v[48:49] offset:36896
	ds_read_b128 v[48:51], v130
	ds_read_b128 v[52:55], v129
	s_waitcnt lgkmcnt(1)
	v_fma_f32 v48, v72, v48, v76
	v_fma_f32 v49, v73, v49, v77
	s_waitcnt lgkmcnt(0)
	v_fma_f32 v48, v68, v52, v48
	v_fma_f32 v49, v69, v53, v49
	v_fma_f32 v50, v74, v50, v78
	v_fma_f32 v51, v75, v51, v79
	v_fma_f32 v44, v44, v64, v48
	v_fma_f32 v45, v45, v65, v49
	v_fma_f32 v50, v70, v54, v50
	v_fma_f32 v51, v71, v55, v51
	v_mul_f32_e32 v48, 0xbfb8aa3b, v44
	v_mul_f32_e32 v49, 0xbfb8aa3b, v45
	v_exp_f32_e32 v48, v48
	v_exp_f32_e32 v49, v49
	v_fma_f32 v46, v46, v66, v50
	v_fma_f32 v47, v47, v67, v51
	v_add_f32_e64 v48, v48, 1.0
	v_add_f32_e64 v49, v49, 1.0
	s_nop 0
	v_mul_f32_e32 v50, 0xbfb8aa3b, v46
	v_mul_f32_e32 v51, 0xbfb8aa3b, v47
	v_exp_f32_e32 v50, v50
	v_rcp_f32_e32 v49, v49
	v_exp_f32_e32 v51, v51
	s_nop 0
	v_add_f32_e64 v50, v50, 1.0
	v_add_f32_e64 v51, v51, 1.0
	v_rcp_f32_e32 v48, v48
	s_nop 0
	v_mul_f32_e64 v44, v44, v48
	v_mul_f32_e64 v45, v45, v49
	s_nop 0
	v_mul_f32_e64 v40, v40, v44
	v_mul_f32_e64 v41, v41, v45
	v_rcp_f32_e32 v45, v51
	v_rcp_f32_e32 v44, v50
	s_nop 0
	v_mul_f32_e64 v44, v46, v44
	v_mul_f32_e64 v45, v47, v45
	v_cvt_pk_bf16_f32 v40, v40, v41
	v_mul_f32_e64 v42, v42, v44
	v_mul_f32_e64 v43, v43, v45
	s_nop 0
	v_cvt_pk_bf16_f32 v41, v42, v43
	ds_write_b64 v128, v[40:41] offset:39200
	ds_read_b128 v[40:43], v121
	ds_read_b128 v[44:47], v120
	s_waitcnt lgkmcnt(1)
	v_fma_f32 v40, v72, v40, v76
	v_fma_f32 v41, v73, v41, v77
	s_waitcnt lgkmcnt(0)
	v_fma_f32 v40, v68, v44, v40
	v_fma_f32 v41, v69, v45, v41
	v_fma_f32 v42, v74, v42, v78
	v_fma_f32 v43, v75, v43, v79
	v_fma_f32 v36, v36, v64, v40
	v_fma_f32 v37, v37, v65, v41
	v_fma_f32 v42, v70, v46, v42
	v_fma_f32 v43, v71, v47, v43
	v_mul_f32_e32 v40, 0xbfb8aa3b, v36
	v_mul_f32_e32 v41, 0xbfb8aa3b, v37
	v_exp_f32_e32 v40, v40
	v_exp_f32_e32 v41, v41
	v_fma_f32 v38, v38, v66, v42
	v_fma_f32 v39, v39, v67, v43
	v_add_f32_e64 v40, v40, 1.0
	v_add_f32_e64 v41, v41, 1.0
	s_nop 0
	v_mul_f32_e32 v42, 0xbfb8aa3b, v38
	v_mul_f32_e32 v43, 0xbfb8aa3b, v39
	v_exp_f32_e32 v42, v42
	v_rcp_f32_e32 v41, v41
	v_exp_f32_e32 v43, v43
	s_nop 0
	v_add_f32_e64 v42, v42, 1.0
	v_add_f32_e64 v43, v43, 1.0
	v_rcp_f32_e32 v40, v40
	s_nop 0
	v_mul_f32_e64 v36, v36, v40
	v_mul_f32_e64 v37, v37, v41
	s_nop 0
	v_mul_f32_e64 v32, v32, v36
	v_mul_f32_e64 v33, v33, v37
	v_rcp_f32_e32 v37, v43
	v_rcp_f32_e32 v36, v42
	s_nop 0
	v_mul_f32_e64 v36, v38, v36
	v_mul_f32_e64 v37, v39, v37
	v_cvt_pk_bf16_f32 v32, v32, v33
	v_mul_f32_e64 v34, v34, v36
	v_mul_f32_e64 v35, v35, v37
	s_nop 0
	v_cvt_pk_bf16_f32 v33, v34, v35
	ds_write_b64 v128, v[32:33] offset:41504
	ds_read_b128 v[32:35], v113
	ds_read_b128 v[36:39], v112
	s_waitcnt lgkmcnt(1)
	v_fma_f32 v32, v72, v32, v76
	v_fma_f32 v33, v73, v33, v77
	s_waitcnt lgkmcnt(0)
; DI float sigmoidf_(float x) { return 1.0f / (1.0f + __expf(-x)); }
; DI void store4(u16* dst, f32x4 v) { uint2 w; w.x = cvtpk(v[0], v[1]); w.y = cvtpk(v[2], v[3]); *(uint2*)dst = w; }
; DI void phase8(const Params& p, const Sched& sched, unsigned char* smem) {
;     ...
; #pragma unroll
;         for (int ni = 0; ni < 8; ++ni) {
;           const int row = wt * 128 + ni * 16 + lr;
;           const f32x4 gv = acc[2 * h2][ni], uv = acc[2 * h2 + 1][ni];
;           if (row >= 2) {
;             const f32x4 g1 = *(const f32x4*)(gl + (row - 1) * 36 + fl), g2 = *(const f32x4*)(gl + (row - 2) * 36 + fl);
;             f32x4 o;
;             o[0] = cb.x + w0.x * g2[0] + w1.x * g1[0] + w2.x * gv[0];
;             o[1] = cb.y + w0.y * g2[1] + w1.y * g1[1] + w2.y * gv[1];
;             o[2] = cb.z + w0.z * g2[2] + w1.z * g1[2] + w2.z * gv[2];
;             o[3] = cb.w + w0.w * g2[3] + w1.w * g1[3] + w2.w * gv[3];
; #pragma unroll
;             for (int j = 0; j < 4; ++j) o[j] = o[j] * sigmoidf_(o[j]) * uv[j];
;             store4(Ls + row * 72 + fc, o);
;           } else {
;             *(f32x4*)(gside + ((size_t)tm * 4 + row) * FF + F) = gv;
;             *(f32x4*)(uside + ((size_t)tm * 2 + row) * FF + F) = uv;
;           }
;           if (row >= 254) *(f32x4*)(gside + ((size_t)tm * 4 + 2 + (row - 254)) * FF + F) = gv;
	v_fma_f32 v32, v68, v36, v32
	v_fma_f32 v33, v69, v37, v33
	v_fma_f32 v34, v74, v34, v78
	v_fma_f32 v35, v75, v35, v79
	v_fma_f32 v28, v28, v64, v32
	v_fma_f32 v29, v29, v65, v33
	v_fma_f32 v34, v70, v38, v34
	v_fma_f32 v35, v71, v39, v35
	v_mul_f32_e32 v32, 0xbfb8aa3b, v28
	v_mul_f32_e32 v33, 0xbfb8aa3b, v29
	v_exp_f32_e32 v32, v32
	v_exp_f32_e32 v33, v33
	v_fma_f32 v30, v30, v66, v34
	v_fma_f32 v31, v31, v67, v35
	v_add_f32_e64 v32, v32, 1.0
	v_add_f32_e64 v33, v33, 1.0
	s_nop 0
	v_mul_f32_e32 v34, 0xbfb8aa3b, v30
	v_mul_f32_e32 v35, 0xbfb8aa3b, v31
	v_exp_f32_e32 v34, v34
	v_rcp_f32_e32 v33, v33
	v_exp_f32_e32 v35, v35
	s_nop 0
	v_add_f32_e64 v34, v34, 1.0
	v_add_f32_e64 v35, v35, 1.0
	v_rcp_f32_e32 v32, v32
	s_nop 0
	v_mul_f32_e64 v28, v28, v32
	v_mul_f32_e64 v29, v29, v33
	s_nop 0
	v_mul_f32_e64 v24, v24, v28
	v_mul_f32_e64 v25, v25, v29
	v_rcp_f32_e32 v29, v35
	v_rcp_f32_e32 v28, v34
	s_nop 0
	v_mul_f32_e64 v28, v30, v28
	v_mul_f32_e64 v29, v31, v29
	v_cvt_pk_bf16_f32 v24, v24, v25
	v_mul_f32_e64 v26, v26, v28
	v_mul_f32_e64 v27, v27, v29
	s_nop 0
	v_cvt_pk_bf16_f32 v25, v26, v27
	ds_write_b64 v128, v[24:25] offset:43808
	ds_read_b128 v[24:27], v105
	ds_read_b128 v[28:31], v104
	s_waitcnt lgkmcnt(1)
	v_fma_f32 v24, v72, v24, v76
	v_fma_f32 v25, v73, v25, v77
	s_waitcnt lgkmcnt(0)
	v_fma_f32 v24, v68, v28, v24
	v_fma_f32 v25, v69, v29, v25
	v_fma_f32 v26, v74, v26, v78
	v_fma_f32 v27, v75, v27, v79
	v_fma_f32 v20, v20, v64, v24
	v_fma_f32 v21, v21, v65, v25
	v_fma_f32 v26, v70, v30, v26
	v_fma_f32 v27, v71, v31, v27
	v_mul_f32_e32 v24, 0xbfb8aa3b, v20
	v_mul_f32_e32 v25, 0xbfb8aa3b, v21
	v_exp_f32_e32 v24, v24
	v_exp_f32_e32 v25, v25
	v_fma_f32 v22, v22, v66, v26
	v_fma_f32 v23, v23, v67, v27
	v_add_f32_e64 v24, v24, 1.0
	v_add_f32_e64 v25, v25, 1.0
	s_nop 0
	v_mul_f32_e32 v26, 0xbfb8aa3b, v22
	v_mul_f32_e32 v27, 0xbfb8aa3b, v23
	v_exp_f32_e32 v26, v26
	v_rcp_f32_e32 v25, v25
	v_exp_f32_e32 v27, v27
	s_nop 0
	v_add_f32_e64 v26, v26, 1.0
	v_add_f32_e64 v27, v27, 1.0
	v_rcp_f32_e32 v24, v24
	s_nop 0
	v_mul_f32_e64 v20, v20, v24
	v_mul_f32_e64 v21, v21, v25
	s_nop 0
	v_mul_f32_e64 v16, v16, v20
	v_mul_f32_e64 v17, v17, v21
	v_rcp_f32_e32 v21, v27
	v_rcp_f32_e32 v20, v26
	s_nop 0
	v_mul_f32_e64 v20, v22, v20
	v_mul_f32_e64 v21, v23, v21
	v_cvt_pk_bf16_f32 v16, v16, v17
	v_mul_f32_e64 v18, v18, v20
	v_mul_f32_e64 v19, v19, v21
	s_nop 0
	v_cvt_pk_bf16_f32 v17, v18, v19
	ds_write_b64 v128, v[16:17] offset:46112
	ds_read_b128 v[16:19], v97
	ds_read_b128 v[20:23], v96
	s_waitcnt lgkmcnt(1)
	v_fma_f32 v16, v72, v16, v76
	v_fma_f32 v17, v73, v17, v77
	s_waitcnt lgkmcnt(0)
	v_fma_f32 v16, v68, v20, v16
	v_fma_f32 v17, v69, v21, v17
	v_fma_f32 v18, v74, v18, v78
	v_fma_f32 v19, v75, v19, v79
	v_fma_f32 v12, v12, v64, v16
	v_fma_f32 v13, v13, v65, v17
	v_fma_f32 v18, v70, v22, v18
	v_fma_f32 v19, v71, v23, v19
	v_mul_f32_e32 v16, 0xbfb8aa3b, v12
	v_mul_f32_e32 v17, 0xbfb8aa3b, v13
	v_exp_f32_e32 v16, v16
	v_exp_f32_e32 v17, v17
	v_fma_f32 v14, v14, v66, v18
	v_fma_f32 v15, v15, v67, v19
	v_add_f32_e64 v16, v16, 1.0
	v_add_f32_e64 v17, v17, 1.0
	s_nop 0
	v_mul_f32_e32 v18, 0xbfb8aa3b, v14
	v_mul_f32_e32 v19, 0xbfb8aa3b, v15
	v_exp_f32_e32 v18, v18
	v_rcp_f32_e32 v17, v17
	v_exp_f32_e32 v19, v19
	s_nop 0
	v_add_f32_e64 v18, v18, 1.0
	v_add_f32_e64 v19, v19, 1.0
	v_rcp_f32_e32 v16, v16
	s_nop 0
	v_mul_f32_e64 v12, v12, v16
	v_mul_f32_e64 v13, v13, v17
	s_nop 0
	v_mul_f32_e64 v8, v8, v12
	v_mul_f32_e64 v9, v9, v13
	v_rcp_f32_e32 v13, v19
	v_rcp_f32_e32 v12, v18
	s_nop 0
	v_mul_f32_e64 v12, v14, v12
	v_mul_f32_e64 v13, v15, v13
	v_cvt_pk_bf16_f32 v8, v8, v9
	v_mul_f32_e64 v10, v10, v12
	v_mul_f32_e64 v11, v11, v13
	s_nop 0
	v_cvt_pk_bf16_f32 v9, v10, v11
	ds_write_b64 v128, v[8:9] offset:48416
	ds_read_b128 v[8:11], v93
	ds_read_b128 v[12:15], v92
	s_waitcnt lgkmcnt(1)
	v_fma_f32 v8, v72, v8, v76
	v_fma_f32 v9, v73, v9, v77
	s_waitcnt lgkmcnt(0)
	v_fma_f32 v8, v68, v12, v8
	v_fma_f32 v9, v69, v13, v9
	v_fma_f32 v10, v74, v10, v78
	v_fma_f32 v11, v75, v11, v79
	v_fma_f32 v8, v0, v64, v8
	v_fma_f32 v9, v1, v65, v9
	v_fma_f32 v10, v70, v14, v10
	v_fma_f32 v11, v71, v15, v11
	v_mul_f32_e32 v12, 0xbfb8aa3b, v8
	v_mul_f32_e32 v13, 0xbfb8aa3b, v9
	v_exp_f32_e32 v12, v12
	v_exp_f32_e32 v13, v13
	v_fma_f32 v10, v2, v66, v10
	v_fma_f32 v11, v3, v67, v11
	v_add_f32_e64 v12, v12, 1.0
	v_add_f32_e64 v13, v13, 1.0
	s_nop 0
	v_mul_f32_e32 v14, 0xbfb8aa3b, v10
	v_mul_f32_e32 v15, 0xbfb8aa3b, v11
	v_exp_f32_e32 v14, v14
	v_rcp_f32_e32 v13, v13
	v_exp_f32_e32 v15, v15
	s_nop 0
	v_add_f32_e64 v14, v14, 1.0
	v_add_f32_e64 v15, v15, 1.0
	v_rcp_f32_e32 v12, v12
	s_nop 0
	v_mul_f32_e64 v8, v8, v12
	v_mul_f32_e64 v9, v9, v13
	s_nop 0
	v_mul_f32_e64 v4, v4, v8
	v_mul_f32_e64 v5, v5, v9
	v_rcp_f32_e32 v9, v15
	v_rcp_f32_e32 v8, v14
	s_nop 0
	v_mul_f32_e64 v8, v10, v8
	v_mul_f32_e64 v9, v11, v9
	v_cvt_pk_bf16_f32 v4, v4, v5
	v_mul_f32_e64 v6, v6, v8
	v_mul_f32_e64 v7, v7, v9
	s_nop 0
	v_cvt_pk_bf16_f32 v5, v6, v7
	ds_write_b64 v128, v[4:5] offset:50720
	s_and_saveexec_b64 s[4:5], s[6:7]
	s_cbranch_execz .LBB0_958
	s_ashr_i32 s31, s30, 31
	s_lshl_b64 s[6:7], s[30:31], 2
	s_add_u32 s6, s6, 0xffffff74
	v_mov_b32_e32 v155, v153
	s_addc_u32 s7, s7, -1
	v_lshl_add_u64 v[4:5], s[6:7], 0, v[154:155]
	v_mov_b64_e32 v[6:7], s[16:17]
	v_mad_u64_u32 v[6:7], s[6:7], v4, s48, v[6:7]
	v_mad_i32_i24 v7, v5, s48, v7
	v_lshl_add_u64 v[4:5], v[144:145], 2, v[6:7]
	global_store_dwordx4 v[4:5], v[0:3], off offset:64

; DI int tidx() { int t = __builtin_amdgcn_workitem_id_x(); asm volatile("" : "+v"(t)); return t; }
; DI float sigmoidf_(float x) { return 1.0f / (1.0f + __expf(-x)); }
; DI void store4(u16* dst, f32x4 v) { uint2 w; w.x = cvtpk(v[0], v[1]); w.y = cvtpk(v[2], v[3]); *(uint2*)dst = w; }
; DI void phase8b(const Params& p, int bid, int nblk) {
;     ...
;   for (int i = bid * 256 + tidx(); i < total; i += nblk * 256) {
;     const int f4 = i % (FF / 4), rr = i / (FF / 4), r = rr & 1, tm = rr >> 1, F = f4 * 4;
;     const bool first = (tm & 7) == 0;
;     const f32x4 z = {0.f, 0.f, 0.f, 0.f};
;     const f32x4 gv = *(const f32x4*)(gside + ((size_t)tm * 4 + r) * FF + F);
;     f32x4 g1, g2;
;     if (r == 1) { g1 = *(const f32x4*)(gside + ((size_t)tm * 4 + 0) * FF + F); g2 = first ? z : *(const f32x4*)(gside + ((size_t)(tm - 1) * 4 + 3) * FF + F); }
;     else { g1 = first ? z : *(const f32x4*)(gside + ((size_t)(tm - 1) * 4 + 3) * FF + F); g2 = first ? z : *(const f32x4*)(gside + ((size_t)(tm - 1) * 4 + 2) * FF + F); }
;     const f32x4 uv = *(const f32x4*)(uside + ((size_t)tm * 2 + r) * FF + F);
;     const f32x4 w0 = *(const f32x4*)(p.conv_w + F), w1 = *(const f32x4*)(p.conv_w + FF + F), w2 = *(const f32x4*)(p.conv_w + 2 * FF + F), cb = *(const f32x4*)(p.conv_b + F);
;     f32x4 o = cb + w0 * g2 + w1 * g1 + w2 * gv;
; #pragma unroll
;     for (int j = 0; j < 4; ++j) o[j] = o[j] * sigmoidf_(o[j]) * uv[j];
;     store4(act + ((size_t)(F >> 5) * Tn + (size_t)tm * 256 + r) * 32 + (F & 31), o);
;   }
.LBB0_1028:
	s_or_b64 exec, exec, s[0:1]
	v_lshlrev_b64 v[2:3], 2, v[16:17]
	v_lshl_add_u64 v[24:25], s[68:69], 0, v[2:3]
	v_lshl_add_u64 v[28:29], s[70:71], 0, v[2:3]
	global_load_dwordx4 v[24:27], v[24:25], off
	v_lshl_add_u64 v[32:33], s[20:21], 0, v[2:3]
	global_load_dwordx4 v[28:31], v[28:29], off
	v_lshl_add_u64 v[36:37], s[22:23], 0, v[2:3]
	global_load_dwordx4 v[32:35], v[32:33], off
	v_sub_u32_e32 v0, v20, v23
	global_load_dwordx4 v[36:39], v[36:37], off
	v_lshl_or_b32 v23, v18, 1, v22
	v_lshlrev_b64 v[40:41], 8, v[18:19]
	v_and_b32_e32 v18, 28, v16
	v_mul_hi_i32_i24_e32 v17, 0x2c00, v23
	v_mul_i32_i24_e32 v16, 0x2c00, v23
	v_lshl_add_u64 v[16:17], s[10:11], 0, v[16:17]
	v_lshl_add_u64 v[2:3], v[16:17], 0, v[2:3]
	v_ashrrev_i32_e32 v42, 3, v0
	v_lshlrev_b32_e32 v0, 1, v18
	global_load_dwordx4 v[16:19], v[2:3], off
	v_ashrrev_i32_e32 v43, 31, v42
	v_lshlrev_b64 v[2:3], 16, v[42:43]
	v_lshl_add_u64 v[2:3], v[2:3], 0, v[40:41]
	v_or_b32_e32 v2, v2, v22
	v_lshlrev_b64 v[2:3], 6, v[2:3]
	v_lshl_add_u64 v[2:3], s[8:9], 0, v[2:3]
	v_lshl_add_u64 v[2:3], v[2:3], 0, v[0:1]
	v_add_u32_e32 v20, s64, v20
	v_cmp_lt_i32_e32 vcc, s30, v20
	s_or_b64 s[24:25], vcc, s[24:25]
	v_add_u32_e32 v21, s28, v21
	s_waitcnt vmcnt(3)
	v_fma_f32 v12, v12, v24, v28
	v_fma_f32 v13, v13, v25, v29
	v_fma_f32 v14, v14, v26, v30
	v_fma_f32 v15, v15, v27, v31
	s_waitcnt vmcnt(2)
	v_fma_f32 v8, v8, v32, v12
	v_fma_f32 v9, v9, v33, v13
	v_fma_f32 v10, v10, v34, v14
	v_fma_f32 v11, v11, v35, v15
	s_waitcnt vmcnt(1)
	v_fma_f32 v4, v4, v36, v8
	v_fma_f32 v5, v5, v37, v9
	v_fma_f32 v6, v6, v38, v10
	v_fma_f32 v7, v7, v39, v11
	v_mul_f32_e32 v8, 0xbfb8aa3b, v4
	v_mul_f32_e32 v9, 0xbfb8aa3b, v5
	v_exp_f32_e32 v8, v8
	v_exp_f32_e32 v9, v9
	v_mul_f32_e32 v10, 0xbfb8aa3b, v6
	v_mul_f32_e32 v11, 0xbfb8aa3b, v7
	v_exp_f32_e32 v10, v10
	v_exp_f32_e32 v11, v11
	v_add_f32_e64 v8, v8, 1.0
	v_add_f32_e64 v9, v9, 1.0
	v_add_f32_e64 v10, v10, 1.0
	v_add_f32_e64 v11, v11, 1.0
	s_mov_b64 vcc, s[0:1]
	v_rcp_f32_e32 v9, v9
	s_mov_b64 vcc, s[4:5]
	v_rcp_f32_e32 v8, v8
	s_mov_b64 vcc, s[6:7]
	v_mul_f32_e64 v4, v4, v8
	v_mul_f32_e64 v5, v5, v9
	v_rcp_f32_e32 v9, v11
	v_rcp_f32_e32 v8, v10
	s_nop 0
	v_mul_f32_e64 v6, v6, v8
	v_mul_f32_e64 v7, v7, v9
	s_waitcnt vmcnt(0)
	v_mul_f32_e64 v4, v16, v4
	v_mul_f32_e64 v5, v17, v5
	v_mul_f32_e64 v6, v18, v6
	v_mul_f32_e64 v7, v19, v7
	v_cvt_pk_bf16_f32 v4, v4, v5
	v_cvt_pk_bf16_f32 v5, v6, v7
	global_store_dwordx2 v[2:3], v[4:5], off
	s_andn2_b64 exec, exec, s[24:25]
	s_cbranch_execz .LBB0_1037

; DI f32x4 mfma16(bf16x8 a, bf16x8 b, f32x4 c) { return __builtin_amdgcn_mfma_f32_16x16x32_bf16(a, b, c, 0, 0, 0); }
; template <int NI, class XL, class EP>
; DI void gemm_tile(const u16* __restrict__ W, int ldw, int f0, int t0, int K, XL xl, EP ep, unsigned char* smem) {
;     ...
;   for (int it = 0; it < nk; ++it) {
;     const u16* Ws = S0 + (it & 1) * BUF; const u16* Xs = Ws + 128 * LST;
;     __builtin_amdgcn_s_setprio(1);
;     bf16x8 a[4];
; #pragma unroll
;     for (int mi = 0; mi < 4; ++mi) a[mi] = *(const bf16x8*)(Ws + (wf * 64 + mi * 16 + lr) * LST + lq * 8);
; #pragma unroll
;     for (int ni = 0; ni < NI; ++ni) {
;       const bf16x8 b = *(const bf16x8*)(Xs + (wt * (NI * 16) + ni * 16 + lr) * LST + lq * 8);
; #pragma unroll
;       for (int mi = 0; mi < 4; ++mi) acc[mi][ni] = mfma16(a[mi], b, acc[mi][ni]);
;     }
;     __builtin_amdgcn_sched_group_barrier(0x100, 6, 0);
; #pragma unroll
;     for (int ni = 0; ni < NI; ++ni) { __builtin_amdgcn_sched_group_barrier(0x008, 4, 0); if (ni + 2 < NI) __builtin_amdgcn_sched_group_barrier(0x100, 1, 0); }
;     __builtin_amdgcn_s_setprio(0);
;     if (it + 1 < nk) lstore((it + 1) & 1);
;     if (it + 2 < nk) gload(it + 2);
;     __syncthreads();
;   }
.LBB0_1095:
	s_setprio 1
	ds_read_b128 v[168:171], v228 offset:0
	ds_read_b128 v[172:175], v228 offset:1536
	ds_read_b128 v[180:183], v228 offset:3072
	ds_read_b128 v[184:187], v228 offset:4608
	ds_read_b128 v[176:179], v152 offset:12288
	ds_read_b128 v[188:191], v152 offset:13824
	s_waitcnt lgkmcnt(1)
	v_mfma_f32_16x16x32_bf16 v[148:151], v[168:171], v[176:179], v[148:151]
	v_mfma_f32_16x16x32_bf16 v[136:139], v[172:175], v[176:179], v[136:139]
	v_mfma_f32_16x16x32_bf16 v[112:115], v[180:183], v[176:179], v[112:115]
	v_mfma_f32_16x16x32_bf16 v[80:83], v[184:187], v[176:179], v[80:83]
	ds_read_b128 v[176:179], v152 offset:15360
	s_waitcnt vmcnt(6)
	ds_write_b128 v229, v[20:23] offset:36864
	s_waitcnt lgkmcnt(2)
	v_mfma_f32_16x16x32_bf16 v[144:147], v[168:171], v[188:191], v[144:147]
	v_mfma_f32_16x16x32_bf16 v[128:131], v[172:175], v[188:191], v[128:131]
	v_mfma_f32_16x16x32_bf16 v[100:103], v[180:183], v[188:191], v[100:103]
	v_mfma_f32_16x16x32_bf16 v[68:71], v[184:187], v[188:191], v[68:71]
	ds_read_b128 v[188:191], v152 offset:16896
	ds_write_b128 v229, v[16:19] offset:36960
	global_load_dwordx4 v[20:23], v154, s[98:99]
	global_load_dwordx4 v[16:19], v154, s[98:99] offset:64
	s_waitcnt lgkmcnt(3)
	v_mfma_f32_16x16x32_bf16 v[140:143], v[168:171], v[176:179], v[140:143]
	v_mfma_f32_16x16x32_bf16 v[120:123], v[172:175], v[176:179], v[120:123]
	v_mfma_f32_16x16x32_bf16 v[88:91], v[180:183], v[176:179], v[88:91]
	v_mfma_f32_16x16x32_bf16 v[44:47], v[184:187], v[176:179], v[44:47]
	ds_read_b128 v[176:179], v152 offset:18432
	ds_write_b128 v230, v[36:39] offset:49152
	global_load_dwordx4 v[36:39], v156, s[100:101] offset:2048
	s_waitcnt lgkmcnt(3)
	v_mfma_f32_16x16x32_bf16 v[132:135], v[168:171], v[188:191], v[132:135]
	v_mfma_f32_16x16x32_bf16 v[108:111], v[172:175], v[188:191], v[108:111]
	v_mfma_f32_16x16x32_bf16 v[76:79], v[180:183], v[188:191], v[76:79]
	v_mfma_f32_16x16x32_bf16 v[40:43], v[184:187], v[188:191], v[40:43]
	ds_read_b128 v[188:191], v152 offset:19968
	ds_write_b128 v230, v[32:35] offset:49248
	global_load_dwordx4 v[32:35], v156, s[100:101] offset:2112
	s_waitcnt lgkmcnt(3)
	v_mfma_f32_16x16x32_bf16 v[124:127], v[168:171], v[176:179], v[124:127]
	v_mfma_f32_16x16x32_bf16 v[96:99], v[172:175], v[176:179], v[96:99]
	v_mfma_f32_16x16x32_bf16 v[64:67], v[180:183], v[176:179], v[64:67]
	v_mfma_f32_16x16x32_bf16 v[12:15], v[184:187], v[176:179], v[12:15]
	ds_read_b128 v[176:179], v152 offset:21504
	ds_write_b128 v230, v[28:31] offset:49344
	global_load_dwordx4 v[28:31], v156, s[100:101] offset:2176
	s_waitcnt lgkmcnt(3)
	v_mfma_f32_16x16x32_bf16 v[116:119], v[168:171], v[188:191], v[116:119]
	v_mfma_f32_16x16x32_bf16 v[84:87], v[172:175], v[188:191], v[84:87]
	v_mfma_f32_16x16x32_bf16 v[56:59], v[180:183], v[188:191], v[56:59]
	v_mfma_f32_16x16x32_bf16 v[8:11], v[184:187], v[188:191], v[8:11]
	ds_read_b128 v[188:191], v152 offset:23040
	ds_write_b128 v230, v[24:27] offset:49440
	global_load_dwordx4 v[24:27], v156, s[100:101] offset:2240
	s_waitcnt lgkmcnt(3)
	v_mfma_f32_16x16x32_bf16 v[104:107], v[168:171], v[176:179], v[104:107]
	v_mfma_f32_16x16x32_bf16 v[72:75], v[172:175], v[176:179], v[72:75]
	v_mfma_f32_16x16x32_bf16 v[52:55], v[180:183], v[176:179], v[52:55]
	v_mfma_f32_16x16x32_bf16 v[4:7], v[184:187], v[176:179], v[4:7]
	s_add_u32 s98, s98, s16
	s_addc_u32 s99, s99, s17
	s_add_u32 s100, s100, s14
	s_addc_u32 s101, s101, s15
	s_waitcnt lgkmcnt(1)
	v_mfma_f32_16x16x32_bf16 v[92:95], v[168:171], v[188:191], v[92:95]
	v_mfma_f32_16x16x32_bf16 v[60:63], v[172:175], v[188:191], v[60:63]
	v_mfma_f32_16x16x32_bf16 v[48:51], v[180:183], v[188:191], v[48:51]
	v_mfma_f32_16x16x32_bf16 v[0:3], v[184:187], v[188:191], v[0:3]
	s_setprio 0
	s_waitcnt lgkmcnt(0)
	s_barrier
	s_setprio 1
	ds_read_b128 v[168:171], v228 offset:36864
	ds_read_b128 v[172:175], v228 offset:38400
	ds_read_b128 v[180:183], v228 offset:39936
	ds_read_b128 v[184:187], v228 offset:41472
	ds_read_b128 v[176:179], v152 offset:49152
	ds_read_b128 v[188:191], v152 offset:50688
	s_waitcnt lgkmcnt(1)
	v_mfma_f32_16x16x32_bf16 v[148:151], v[168:171], v[176:179], v[148:151]
	v_mfma_f32_16x16x32_bf16 v[136:139], v[172:175], v[176:179], v[136:139]
	v_mfma_f32_16x16x32_bf16 v[112:115], v[180:183], v[176:179], v[112:115]
	v_mfma_f32_16x16x32_bf16 v[80:83], v[184:187], v[176:179], v[80:83]
	ds_read_b128 v[176:179], v152 offset:52224
	s_waitcnt vmcnt(6)
	ds_write_b128 v229, v[200:203] offset:0
	s_waitcnt lgkmcnt(2)
	v_mfma_f32_16x16x32_bf16 v[144:147], v[168:171], v[188:191], v[144:147]
	v_mfma_f32_16x16x32_bf16 v[128:131], v[172:175], v[188:191], v[128:131]
	v_mfma_f32_16x16x32_bf16 v[100:103], v[180:183], v[188:191], v[100:103]
	v_mfma_f32_16x16x32_bf16 v[68:71], v[184:187], v[188:191], v[68:71]
	ds_read_b128 v[188:191], v152 offset:53760
	ds_write_b128 v229, v[204:207] offset:96
	global_load_dwordx4 v[200:203], v154, s[98:99]
	global_load_dwordx4 v[204:207], v154, s[98:99] offset:64
	s_waitcnt lgkmcnt(3)
	v_mfma_f32_16x16x32_bf16 v[140:143], v[168:171], v[176:179], v[140:143]
	v_mfma_f32_16x16x32_bf16 v[120:123], v[172:175], v[176:179], v[120:123]
	v_mfma_f32_16x16x32_bf16 v[88:91], v[180:183], v[176:179], v[88:91]
	v_mfma_f32_16x16x32_bf16 v[44:47], v[184:187], v[176:179], v[44:47]
	ds_read_b128 v[176:179], v152 offset:55296
	ds_write_b128 v230, v[208:211] offset:12288
	global_load_dwordx4 v[208:211], v156, s[100:101] offset:2048
	s_waitcnt lgkmcnt(3)
; DI f32x4 mfma16(bf16x8 a, bf16x8 b, f32x4 c) { return __builtin_amdgcn_mfma_f32_16x16x32_bf16(a, b, c, 0, 0, 0); }
; template <int NI, class XL, class EP>
; DI void gemm_tile(const u16* __restrict__ W, int ldw, int f0, int t0, int K, XL xl, EP ep, unsigned char* smem) {
;     ...
;   for (int it = 0; it < nk; ++it) {
;     const u16* Ws = S0 + (it & 1) * BUF; const u16* Xs = Ws + 128 * LST;
;     __builtin_amdgcn_s_setprio(1);
;     bf16x8 a[4];
; #pragma unroll
;     for (int mi = 0; mi < 4; ++mi) a[mi] = *(const bf16x8*)(Ws + (wf * 64 + mi * 16 + lr) * LST + lq * 8);
; #pragma unroll
;     for (int ni = 0; ni < NI; ++ni) {
;       const bf16x8 b = *(const bf16x8*)(Xs + (wt * (NI * 16) + ni * 16 + lr) * LST + lq * 8);
; #pragma unroll
;       for (int mi = 0; mi < 4; ++mi) acc[mi][ni] = mfma16(a[mi], b, acc[mi][ni]);
;     }
;     __builtin_amdgcn_sched_group_barrier(0x100, 6, 0);
; #pragma unroll
;     for (int ni = 0; ni < NI; ++ni) { __builtin_amdgcn_sched_group_barrier(0x008, 4, 0); if (ni + 2 < NI) __builtin_amdgcn_sched_group_barrier(0x100, 1, 0); }
;     __builtin_amdgcn_s_setprio(0);
;     if (it + 1 < nk) lstore((it + 1) & 1);
;     if (it + 2 < nk) gload(it + 2);
;     __syncthreads();
;   }
	v_mfma_f32_16x16x32_bf16 v[132:135], v[168:171], v[188:191], v[132:135]
	v_mfma_f32_16x16x32_bf16 v[108:111], v[172:175], v[188:191], v[108:111]
	v_mfma_f32_16x16x32_bf16 v[76:79], v[180:183], v[188:191], v[76:79]
	v_mfma_f32_16x16x32_bf16 v[40:43], v[184:187], v[188:191], v[40:43]
	ds_read_b128 v[188:191], v152 offset:56832
	ds_write_b128 v230, v[212:215] offset:12384
	global_load_dwordx4 v[212:215], v156, s[100:101] offset:2112
	s_waitcnt lgkmcnt(3)
	v_mfma_f32_16x16x32_bf16 v[124:127], v[168:171], v[176:179], v[124:127]
	v_mfma_f32_16x16x32_bf16 v[96:99], v[172:175], v[176:179], v[96:99]
	v_mfma_f32_16x16x32_bf16 v[64:67], v[180:183], v[176:179], v[64:67]
	v_mfma_f32_16x16x32_bf16 v[12:15], v[184:187], v[176:179], v[12:15]
	ds_read_b128 v[176:179], v152 offset:58368
	ds_write_b128 v230, v[220:223] offset:12480
	global_load_dwordx4 v[220:223], v156, s[100:101] offset:2176
	s_waitcnt lgkmcnt(3)
	v_mfma_f32_16x16x32_bf16 v[116:119], v[168:171], v[188:191], v[116:119]
	v_mfma_f32_16x16x32_bf16 v[84:87], v[172:175], v[188:191], v[84:87]
	v_mfma_f32_16x16x32_bf16 v[56:59], v[180:183], v[188:191], v[56:59]
	v_mfma_f32_16x16x32_bf16 v[8:11], v[184:187], v[188:191], v[8:11]
	ds_read_b128 v[188:191], v152 offset:59904
	ds_write_b128 v230, v[224:227] offset:12576
	global_load_dwordx4 v[224:227], v156, s[100:101] offset:2240
	s_waitcnt lgkmcnt(3)
	v_mfma_f32_16x16x32_bf16 v[104:107], v[168:171], v[176:179], v[104:107]
	v_mfma_f32_16x16x32_bf16 v[72:75], v[172:175], v[176:179], v[72:75]
	v_mfma_f32_16x16x32_bf16 v[52:55], v[180:183], v[176:179], v[52:55]
	v_mfma_f32_16x16x32_bf16 v[4:7], v[184:187], v[176:179], v[4:7]
	s_add_u32 s98, s98, s16
	s_addc_u32 s99, s99, s17
	s_add_u32 s100, s100, s14
	s_addc_u32 s101, s101, s15
	s_add_i32 s33, s33, 2
	s_waitcnt lgkmcnt(1)
	v_mfma_f32_16x16x32_bf16 v[92:95], v[168:171], v[188:191], v[92:95]
	v_mfma_f32_16x16x32_bf16 v[60:63], v[172:175], v[188:191], v[60:63]
	v_mfma_f32_16x16x32_bf16 v[48:51], v[180:183], v[188:191], v[48:51]
	v_mfma_f32_16x16x32_bf16 v[0:3], v[184:187], v[188:191], v[0:3]
	s_setprio 0
	s_cmpk_lg_i32 s33, 85
	s_waitcnt lgkmcnt(0)
	s_barrier
	s_cbranch_scc1 .LBB0_1095
	s_setprio 1
	ds_read_b128 v[168:171], v228 offset:0
	ds_read_b128 v[172:175], v228 offset:1536
	ds_read_b128 v[180:183], v228 offset:3072
	ds_read_b128 v[184:187], v228 offset:4608
	ds_read_b128 v[176:179], v152 offset:12288
	ds_read_b128 v[188:191], v152 offset:13824
	s_waitcnt lgkmcnt(1)
	v_mfma_f32_16x16x32_bf16 v[148:151], v[168:171], v[176:179], v[148:151]
	v_mfma_f32_16x16x32_bf16 v[136:139], v[172:175], v[176:179], v[136:139]
	v_mfma_f32_16x16x32_bf16 v[112:115], v[180:183], v[176:179], v[112:115]
	v_mfma_f32_16x16x32_bf16 v[80:83], v[184:187], v[176:179], v[80:83]
	ds_read_b128 v[176:179], v152 offset:15360
	s_waitcnt vmcnt(6)
	ds_write_b128 v229, v[20:23] offset:36864
	s_waitcnt lgkmcnt(2)
	v_mfma_f32_16x16x32_bf16 v[144:147], v[168:171], v[188:191], v[144:147]
	v_mfma_f32_16x16x32_bf16 v[128:131], v[172:175], v[188:191], v[128:131]
	v_mfma_f32_16x16x32_bf16 v[100:103], v[180:183], v[188:191], v[100:103]
	v_mfma_f32_16x16x32_bf16 v[68:71], v[184:187], v[188:191], v[68:71]
	ds_read_b128 v[188:191], v152 offset:16896
	ds_write_b128 v229, v[16:19] offset:36960
	global_load_dwordx4 v[20:23], v154, s[98:99]
	global_load_dwordx4 v[16:19], v154, s[98:99] offset:64
	s_waitcnt lgkmcnt(3)
	v_mfma_f32_16x16x32_bf16 v[140:143], v[168:171], v[176:179], v[140:143]
	v_mfma_f32_16x16x32_bf16 v[120:123], v[172:175], v[176:179], v[120:123]
	v_mfma_f32_16x16x32_bf16 v[88:91], v[180:183], v[176:179], v[88:91]
	v_mfma_f32_16x16x32_bf16 v[44:47], v[184:187], v[176:179], v[44:47]
	ds_read_b128 v[176:179], v152 offset:18432
	ds_write_b128 v230, v[36:39] offset:49152
	global_load_dwordx4 v[36:39], v156, s[100:101] offset:2048
	s_waitcnt lgkmcnt(3)
	v_mfma_f32_16x16x32_bf16 v[132:135], v[168:171], v[188:191], v[132:135]
	v_mfma_f32_16x16x32_bf16 v[108:111], v[172:175], v[188:191], v[108:111]
	v_mfma_f32_16x16x32_bf16 v[76:79], v[180:183], v[188:191], v[76:79]
	v_mfma_f32_16x16x32_bf16 v[40:43], v[184:187], v[188:191], v[40:43]
	ds_read_b128 v[188:191], v152 offset:19968
	ds_write_b128 v230, v[32:35] offset:49248
	global_load_dwordx4 v[32:35], v156, s[100:101] offset:2112
	s_waitcnt lgkmcnt(3)
	v_mfma_f32_16x16x32_bf16 v[124:127], v[168:171], v[176:179], v[124:127]
	v_mfma_f32_16x16x32_bf16 v[96:99], v[172:175], v[176:179], v[96:99]
	v_mfma_f32_16x16x32_bf16 v[64:67], v[180:183], v[176:179], v[64:67]
	v_mfma_f32_16x16x32_bf16 v[12:15], v[184:187], v[176:179], v[12:15]
	ds_read_b128 v[176:179], v152 offset:21504
	ds_write_b128 v230, v[28:31] offset:49344
	global_load_dwordx4 v[28:31], v156, s[100:101] offset:2176
	s_waitcnt lgkmcnt(3)
	v_mfma_f32_16x16x32_bf16 v[116:119], v[168:171], v[188:191], v[116:119]
	v_mfma_f32_16x16x32_bf16 v[84:87], v[172:175], v[188:191], v[84:87]
	v_mfma_f32_16x16x32_bf16 v[56:59], v[180:183], v[188:191], v[56:59]
	v_mfma_f32_16x16x32_bf16 v[8:11], v[184:187], v[188:191], v[8:11]
	ds_read_b128 v[188:191], v152 offset:23040
	ds_write_b128 v230, v[24:27] offset:49440
	global_load_dwordx4 v[24:27], v156, s[100:101] offset:2240
	s_waitcnt lgkmcnt(3)
	v_mfma_f32_16x16x32_bf16 v[104:107], v[168:171], v[176:179], v[104:107]
	v_mfma_f32_16x16x32_bf16 v[72:75], v[172:175], v[176:179], v[72:75]
	v_mfma_f32_16x16x32_bf16 v[52:55], v[180:183], v[176:179], v[52:55]
	v_mfma_f32_16x16x32_bf16 v[4:7], v[184:187], v[176:179], v[4:7]
	s_add_u32 s98, s98, s16
	s_addc_u32 s99, s99, s17
	s_add_u32 s100, s100, s14
	s_addc_u32 s101, s101, s15
	s_waitcnt lgkmcnt(1)
	v_mfma_f32_16x16x32_bf16 v[92:95], v[168:171], v[188:191], v[92:95]
	v_mfma_f32_16x16x32_bf16 v[60:63], v[172:175], v[188:191], v[60:63]
	v_mfma_f32_16x16x32_bf16 v[48:51], v[180:183], v[188:191], v[48:51]
	v_mfma_f32_16x16x32_bf16 v[0:3], v[184:187], v[188:191], v[0:3]
	s_setprio 0
	s_waitcnt lgkmcnt(0)
	s_barrier
; DI f32x4 mfma16(bf16x8 a, bf16x8 b, f32x4 c) { return __builtin_amdgcn_mfma_f32_16x16x32_bf16(a, b, c, 0, 0, 0); }
; template <int NI, class XL, class EP>
; DI void gemm_tile(const u16* __restrict__ W, int ldw, int f0, int t0, int K, XL xl, EP ep, unsigned char* smem) {
;     ...
;   for (int it = 0; it < nk; ++it) {
;     const u16* Ws = S0 + (it & 1) * BUF; const u16* Xs = Ws + 128 * LST;
;     __builtin_amdgcn_s_setprio(1);
;     bf16x8 a[4];
; #pragma unroll
;     for (int mi = 0; mi < 4; ++mi) a[mi] = *(const bf16x8*)(Ws + (wf * 64 + mi * 16 + lr) * LST + lq * 8);
; #pragma unroll
;     for (int ni = 0; ni < NI; ++ni) {
;       const bf16x8 b = *(const bf16x8*)(Xs + (wt * (NI * 16) + ni * 16 + lr) * LST + lq * 8);
; #pragma unroll
;       for (int mi = 0; mi < 4; ++mi) acc[mi][ni] = mfma16(a[mi], b, acc[mi][ni]);
;     }
;     __builtin_amdgcn_sched_group_barrier(0x100, 6, 0);
; #pragma unroll
;     for (int ni = 0; ni < NI; ++ni) { __builtin_amdgcn_sched_group_barrier(0x008, 4, 0); if (ni + 2 < NI) __builtin_amdgcn_sched_group_barrier(0x100, 1, 0); }
;     __builtin_amdgcn_s_setprio(0);
;     if (it + 1 < nk) lstore((it + 1) & 1);
;     if (it + 2 < nk) gload(it + 2);
;     __syncthreads();
;   }
	s_setprio 1
	ds_read_b128 v[168:171], v228 offset:36864
	ds_read_b128 v[172:175], v228 offset:38400
	ds_read_b128 v[180:183], v228 offset:39936
	ds_read_b128 v[184:187], v228 offset:41472
	ds_read_b128 v[176:179], v152 offset:49152
	ds_read_b128 v[188:191], v152 offset:50688
	s_waitcnt lgkmcnt(1)
	v_mfma_f32_16x16x32_bf16 v[148:151], v[168:171], v[176:179], v[148:151]
	v_mfma_f32_16x16x32_bf16 v[136:139], v[172:175], v[176:179], v[136:139]
	v_mfma_f32_16x16x32_bf16 v[112:115], v[180:183], v[176:179], v[112:115]
	v_mfma_f32_16x16x32_bf16 v[80:83], v[184:187], v[176:179], v[80:83]
	ds_read_b128 v[176:179], v152 offset:52224
	s_waitcnt vmcnt(6)
	ds_write_b128 v229, v[200:203] offset:0
	s_waitcnt lgkmcnt(2)
	v_mfma_f32_16x16x32_bf16 v[144:147], v[168:171], v[188:191], v[144:147]
	v_mfma_f32_16x16x32_bf16 v[128:131], v[172:175], v[188:191], v[128:131]
	v_mfma_f32_16x16x32_bf16 v[100:103], v[180:183], v[188:191], v[100:103]
	v_mfma_f32_16x16x32_bf16 v[68:71], v[184:187], v[188:191], v[68:71]
	ds_read_b128 v[188:191], v152 offset:53760
	ds_write_b128 v229, v[204:207] offset:96
	s_waitcnt lgkmcnt(3)
	v_mfma_f32_16x16x32_bf16 v[140:143], v[168:171], v[176:179], v[140:143]
	v_mfma_f32_16x16x32_bf16 v[120:123], v[172:175], v[176:179], v[120:123]
	v_mfma_f32_16x16x32_bf16 v[88:91], v[180:183], v[176:179], v[88:91]
	v_mfma_f32_16x16x32_bf16 v[44:47], v[184:187], v[176:179], v[44:47]
	ds_read_b128 v[176:179], v152 offset:55296
	ds_write_b128 v230, v[208:211] offset:12288
	s_waitcnt lgkmcnt(3)
	v_mfma_f32_16x16x32_bf16 v[132:135], v[168:171], v[188:191], v[132:135]
	v_mfma_f32_16x16x32_bf16 v[108:111], v[172:175], v[188:191], v[108:111]
	v_mfma_f32_16x16x32_bf16 v[76:79], v[180:183], v[188:191], v[76:79]
	v_mfma_f32_16x16x32_bf16 v[40:43], v[184:187], v[188:191], v[40:43]
	ds_read_b128 v[188:191], v152 offset:56832
	ds_write_b128 v230, v[212:215] offset:12384
	s_waitcnt lgkmcnt(3)
	v_mfma_f32_16x16x32_bf16 v[124:127], v[168:171], v[176:179], v[124:127]
	v_mfma_f32_16x16x32_bf16 v[96:99], v[172:175], v[176:179], v[96:99]
	v_mfma_f32_16x16x32_bf16 v[64:67], v[180:183], v[176:179], v[64:67]
	v_mfma_f32_16x16x32_bf16 v[12:15], v[184:187], v[176:179], v[12:15]
	ds_read_b128 v[176:179], v152 offset:58368
	ds_write_b128 v230, v[220:223] offset:12480
	s_waitcnt lgkmcnt(3)
	v_mfma_f32_16x16x32_bf16 v[116:119], v[168:171], v[188:191], v[116:119]
	v_mfma_f32_16x16x32_bf16 v[84:87], v[172:175], v[188:191], v[84:87]
	v_mfma_f32_16x16x32_bf16 v[56:59], v[180:183], v[188:191], v[56:59]
	v_mfma_f32_16x16x32_bf16 v[8:11], v[184:187], v[188:191], v[8:11]
	ds_read_b128 v[188:191], v152 offset:59904
	ds_write_b128 v230, v[224:227] offset:12576
	s_waitcnt lgkmcnt(3)
	v_mfma_f32_16x16x32_bf16 v[104:107], v[168:171], v[176:179], v[104:107]
	v_mfma_f32_16x16x32_bf16 v[72:75], v[172:175], v[176:179], v[72:75]
	v_mfma_f32_16x16x32_bf16 v[52:55], v[180:183], v[176:179], v[52:55]
	v_mfma_f32_16x16x32_bf16 v[4:7], v[184:187], v[176:179], v[4:7]
	s_add_i32 s33, s33, 2
	s_waitcnt lgkmcnt(1)
	v_mfma_f32_16x16x32_bf16 v[92:95], v[168:171], v[188:191], v[92:95]
	v_mfma_f32_16x16x32_bf16 v[60:63], v[172:175], v[188:191], v[60:63]
	v_mfma_f32_16x16x32_bf16 v[48:51], v[180:183], v[188:191], v[48:51]
	v_mfma_f32_16x16x32_bf16 v[0:3], v[184:187], v[188:191], v[0:3]
	s_setprio 0
	s_waitcnt lgkmcnt(0)
	s_barrier
	s_setprio 1
	v_lshl_add_u32 v152, v167, 1, v164
	ds_read_b128 v[154:157], v152
	v_lshl_add_u32 v161, v165, 1, v164
	ds_read_b128 v[164:167], v152 offset:1536
	ds_read_b128 v[172:175], v152 offset:3072
	ds_read_b128 v[176:179], v152 offset:4608
	ds_read_b128 v[168:171], v161 offset:12288
	ds_read_b128 v[180:183], v161 offset:13824
	s_waitcnt lgkmcnt(1)
	v_mfma_f32_16x16x32_bf16 v[148:151], v[154:157], v[168:171], v[148:151]
	v_mfma_f32_16x16x32_bf16 v[136:139], v[164:167], v[168:171], v[136:139]
	v_mfma_f32_16x16x32_bf16 v[112:115], v[172:175], v[168:171], v[112:115]
	v_mfma_f32_16x16x32_bf16 v[80:83], v[176:179], v[168:171], v[80:83]
	ds_read_b128 v[168:171], v161 offset:15360
	s_waitcnt vmcnt(5)
	ds_write_b128 v162, v[20:23] offset:36864
	s_waitcnt lgkmcnt(2)
	v_mfma_f32_16x16x32_bf16 v[144:147], v[154:157], v[180:183], v[144:147]
	v_mfma_f32_16x16x32_bf16 v[128:131], v[164:167], v[180:183], v[128:131]
	v_mfma_f32_16x16x32_bf16 v[100:103], v[172:175], v[180:183], v[100:103]
	v_mfma_f32_16x16x32_bf16 v[68:71], v[176:179], v[180:183], v[68:71]
	ds_read_b128 v[180:183], v161 offset:16896
	s_waitcnt vmcnt(4)
	ds_write_b128 v162, v[16:19] offset:36960
	s_waitcnt lgkmcnt(3)
	v_mfma_f32_16x16x32_bf16 v[140:143], v[154:157], v[168:171], v[140:143]
	v_mfma_f32_16x16x32_bf16 v[120:123], v[164:167], v[168:171], v[120:123]
	v_mfma_f32_16x16x32_bf16 v[184:187], v[172:175], v[168:171], v[88:91]
	v_mfma_f32_16x16x32_bf16 v[44:47], v[176:179], v[168:171], v[44:47]
	s_nop 1
	ds_read_b128 v[88:91], v161 offset:18432
	s_waitcnt vmcnt(3)
	ds_write_b128 v163, v[36:39] offset:49152
	s_waitcnt lgkmcnt(3)
	v_mfma_f32_16x16x32_bf16 v[132:135], v[154:157], v[180:183], v[132:135]
	v_mfma_f32_16x16x32_bf16 v[168:171], v[164:167], v[180:183], v[108:111]
	v_mfma_f32_16x16x32_bf16 v[188:191], v[172:175], v[180:183], v[76:79]
	v_mfma_f32_16x16x32_bf16 v[180:183], v[176:179], v[180:183], v[40:43]
	s_nop 2
	ds_read_b128 v[40:43], v161 offset:19968
	s_waitcnt vmcnt(2)
	ds_write_b128 v163, v[32:35] offset:49248
	s_waitcnt lgkmcnt(3)
	v_mfma_f32_16x16x32_bf16 v[124:127], v[154:157], v[88:91], v[124:127]
	v_mfma_f32_16x16x32_bf16 v[192:195], v[164:167], v[88:91], v[96:99]
	v_mfma_f32_16x16x32_bf16 v[196:199], v[172:175], v[88:91], v[64:67]
	v_mfma_f32_16x16x32_bf16 v[200:203], v[176:179], v[88:91], v[12:15]
	s_nop 2
	ds_read_b128 v[12:15], v161 offset:21504
	s_waitcnt vmcnt(1)
	ds_write_b128 v163, v[28:31] offset:49344
	s_waitcnt lgkmcnt(3)
	v_mfma_f32_16x16x32_bf16 v[116:119], v[154:157], v[40:43], v[116:119]
	v_mfma_f32_16x16x32_bf16 v[204:207], v[164:167], v[40:43], v[84:87]
	v_mfma_f32_16x16x32_bf16 v[56:59], v[172:175], v[40:43], v[56:59]
	v_mfma_f32_16x16x32_bf16 v[208:211], v[176:179], v[40:43], v[8:11]
	s_nop 2
	ds_read_b128 v[8:11], v161 offset:23040
	s_waitcnt vmcnt(0)
	ds_write_b128 v163, v[24:27] offset:49440
	s_waitcnt lgkmcnt(3)
	v_mfma_f32_16x16x32_bf16 v[212:215], v[154:157], v[12:15], v[104:107]
	v_mfma_f32_16x16x32_bf16 v[72:75], v[164:167], v[12:15], v[72:75]
	v_mfma_f32_16x16x32_bf16 v[220:223], v[172:175], v[12:15], v[52:55]
	v_mfma_f32_16x16x32_bf16 v[224:227], v[176:179], v[12:15], v[4:7]
	s_waitcnt lgkmcnt(1)
	v_mfma_f32_16x16x32_bf16 v[154:157], v[154:157], v[8:11], v[92:95]
	v_mfma_f32_16x16x32_bf16 v[60:63], v[164:167], v[8:11], v[60:63]
	v_mfma_f32_16x16x32_bf16 v[164:167], v[172:175], v[8:11], v[48:51]
	v_mfma_f32_16x16x32_bf16 v[172:175], v[176:179], v[8:11], v[0:3]
	s_setprio 0
	s_waitcnt lgkmcnt(0)
	s_barrier
; DI void store4(u16* dst, f32x4 v) { uint2 w; w.x = cvtpk(v[0], v[1]); w.y = cvtpk(v[2], v[3]); *(uint2*)dst = w; }
; DI f32x4 mfma16(bf16x8 a, bf16x8 b, f32x4 c) { return __builtin_amdgcn_mfma_f32_16x16x32_bf16(a, b, c, 0, 0, 0); }
; template <int NI, class XL, class EP>
; DI void gemm_tile(const u16* __restrict__ W, int ldw, int f0, int t0, int K, XL xl, EP ep, unsigned char* smem) {
;     ...
;   for (int it = 0; it < nk; ++it) {
;     const u16* Ws = S0 + (it & 1) * BUF; const u16* Xs = Ws + 128 * LST;
;     __builtin_amdgcn_s_setprio(1);
;     bf16x8 a[4];
; #pragma unroll
;     for (int mi = 0; mi < 4; ++mi) a[mi] = *(const bf16x8*)(Ws + (wf * 64 + mi * 16 + lr) * LST + lq * 8);
; #pragma unroll
;     for (int ni = 0; ni < NI; ++ni) {
;       const bf16x8 b = *(const bf16x8*)(Xs + (wt * (NI * 16) + ni * 16 + lr) * LST + lq * 8);
; #pragma unroll
;       for (int mi = 0; mi < 4; ++mi) acc[mi][ni] = mfma16(a[mi], b, acc[mi][ni]);
;     }
;     __builtin_amdgcn_sched_group_barrier(0x100, 6, 0);
; #pragma unroll
;     for (int ni = 0; ni < NI; ++ni) { __builtin_amdgcn_sched_group_barrier(0x008, 4, 0); if (ni + 2 < NI) __builtin_amdgcn_sched_group_barrier(0x100, 1, 0); }
;     __builtin_amdgcn_s_setprio(0);
;     if (it + 1 < nk) lstore((it + 1) & 1);
;     if (it + 2 < nk) gload(it + 2);
;     __syncthreads();
;   }
; DI void phase9(const Params& p, const Sched& sched, unsigned char* smem) {
;     ...
;       const int b = tb >> 11;
;       __syncthreads();
; #pragma unroll
;       for (int mi = 0; mi < 4; ++mi) {
;         const int f = fb + mi * 16 + lq * 4; const float4 gm = *(const float4*)(mod + (size_t)b * 6144 + 5120 + f);
; #pragma unroll
;         for (int ni = 0; ni < 8; ++ni) {
;           const f32x4 o = {gm.x * acc[mi][ni][0], gm.y * acc[mi][ni][1], gm.z * acc[mi][ni][2], gm.w * acc[mi][ni][3]};
;           store4(Ls + (wt * 128 + ni * 16 + lr) * EST + wf * 64 + mi * 16 + lq * 4, o);
;         }
	s_lshl_b32 s30, s30, 7
	s_setprio 1
	ds_read_b128 v[28:31], v152 offset:36864
	ds_read_b128 v[176:179], v152 offset:38400
	ds_read_b128 v[228:231], v152 offset:39936
	ds_read_b128 v[232:235], v152 offset:41472
	ds_read_b128 v[0:3], v161 offset:49152
	ds_read_b128 v[4:7], v161 offset:50688
	s_waitcnt lgkmcnt(1)
	v_mfma_f32_16x16x32_bf16 v[88:91], v[28:31], v[0:3], v[148:151]
	v_mfma_f32_16x16x32_bf16 v[64:67], v[176:179], v[0:3], v[136:139]
	v_mfma_f32_16x16x32_bf16 v[32:35], v[228:231], v[0:3], v[112:115]
	v_mfma_f32_16x16x32_bf16 v[0:3], v[232:235], v[0:3], v[80:83]
	ds_read_b128 v[8:11], v161 offset:52224
	s_waitcnt lgkmcnt(1)
	v_mfma_f32_16x16x32_bf16 v[96:99], v[28:31], v[4:7], v[144:147]
	v_mfma_f32_16x16x32_bf16 v[76:79], v[176:179], v[4:7], v[128:131]
	v_mfma_f32_16x16x32_bf16 v[36:39], v[228:231], v[4:7], v[100:103]
	v_mfma_f32_16x16x32_bf16 v[4:7], v[232:235], v[4:7], v[68:71]
	ds_read_b128 v[12:15], v161 offset:53760
	s_waitcnt lgkmcnt(1)
	v_mfma_f32_16x16x32_bf16 v[104:107], v[28:31], v[8:11], v[140:143]
	v_mfma_f32_16x16x32_bf16 v[84:87], v[176:179], v[8:11], v[120:123]
	v_mfma_f32_16x16x32_bf16 v[40:43], v[228:231], v[8:11], v[184:187]
	v_mfma_f32_16x16x32_bf16 v[8:11], v[232:235], v[8:11], v[44:47]
	ds_read_b128 v[16:19], v161 offset:55296
	s_waitcnt lgkmcnt(1)
	v_mfma_f32_16x16x32_bf16 v[108:111], v[28:31], v[12:15], v[132:135]
	v_mfma_f32_16x16x32_bf16 v[92:95], v[176:179], v[12:15], v[168:171]
	v_mfma_f32_16x16x32_bf16 v[44:47], v[228:231], v[12:15], v[188:191]
	v_mfma_f32_16x16x32_bf16 v[12:15], v[232:235], v[12:15], v[180:183]
	ds_read_b128 v[20:23], v161 offset:56832
	s_waitcnt lgkmcnt(1)
	v_mfma_f32_16x16x32_bf16 v[112:115], v[28:31], v[16:19], v[124:127]
	v_mfma_f32_16x16x32_bf16 v[100:103], v[176:179], v[16:19], v[192:195]
	v_mfma_f32_16x16x32_bf16 v[48:51], v[228:231], v[16:19], v[196:199]
	v_mfma_f32_16x16x32_bf16 v[16:19], v[232:235], v[16:19], v[200:203]
	ds_read_b128 v[24:27], v161 offset:58368
	s_waitcnt lgkmcnt(1)
	v_mfma_f32_16x16x32_bf16 v[116:119], v[28:31], v[20:23], v[116:119]
	v_mfma_f32_16x16x32_bf16 v[68:71], v[176:179], v[20:23], v[204:207]
	v_mfma_f32_16x16x32_bf16 v[52:55], v[228:231], v[20:23], v[56:59]
	v_mfma_f32_16x16x32_bf16 v[20:23], v[232:235], v[20:23], v[208:211]
	ds_read_b128 v[128:131], v161 offset:59904
	s_waitcnt lgkmcnt(1)
	v_mfma_f32_16x16x32_bf16 v[120:123], v[28:31], v[24:27], v[212:215]
	v_mfma_f32_16x16x32_bf16 v[80:83], v[176:179], v[24:27], v[72:75]
	v_mfma_f32_16x16x32_bf16 v[56:59], v[228:231], v[24:27], v[220:223]
	v_mfma_f32_16x16x32_bf16 v[24:27], v[232:235], v[24:27], v[224:227]
	s_waitcnt lgkmcnt(0)
	v_mfma_f32_16x16x32_bf16 v[124:127], v[28:31], v[128:131], v[154:157]
	v_mfma_f32_16x16x32_bf16 v[72:75], v[176:179], v[128:131], v[60:63]
	v_mfma_f32_16x16x32_bf16 v[60:63], v[228:231], v[128:131], v[164:167]
	v_mfma_f32_16x16x32_bf16 v[28:31], v[232:235], v[128:131], v[172:175]
	s_setprio 0
	s_ashr_i32 s31, s31, 3
	v_add_u32_e32 v128, s30, v160
	s_mul_hi_i32 s33, s31, 0x6000
	s_mulk_i32 s31, 0x6000
	v_lshl_or_b32 v128, v158, 2, v128
	s_add_u32 s34, s72, s31
	s_addc_u32 s35, s73, s33
	v_ashrrev_i32_e32 v129, 31, v128
	v_lshl_add_u64 v[128:129], v[128:129], 2, s[34:35]
	v_add_co_u32_e32 v140, vcc, s24, v128
	v_mul_u32_u24_e32 v138, 0x88, v159
	s_nop 0
	v_addc_co_u32_e32 v141, vcc, 0, v129, vcc
	v_lshlrev_b32_e32 v136, 1, v160
	v_lshlrev_b32_e32 v137, 3, v158
	v_lshlrev_b32_e32 v138, 1, v138
	s_barrier
	global_load_dwordx4 v[128:131], v[140:141], off
	global_load_dwordx4 v[132:135], v[140:141], off offset:64
	v_add3_u32 v144, v136, v137, v138
	global_load_dwordx4 v[136:139], v[140:141], off offset:128
	v_add_u32_e32 v145, 0x1000, v144
	global_load_dwordx4 v[140:143], v[140:141], off offset:192
	v_add_u32_e32 v146, 0x2000, v144
	v_add_u32_e32 v147, 0x3000, v144
	v_add_u32_e32 v148, 0x4000, v144
	s_add_i32 s28, s28, s78
	s_add_i32 s27, s27, s78
	s_cmp_gt_i32 s28, 63
	s_waitcnt vmcnt(3)
	v_mul_f32_e64 v88, v88, v128
	v_mul_f32_e64 v89, v89, v129
	v_mul_f32_e64 v90, v90, v130
	v_mul_f32_e64 v91, v91, v131
	v_mul_f32_e64 v96, v96, v128
	v_mul_f32_e64 v97, v97, v129
	s_waitcnt vmcnt(1)
	v_mul_f32_e64 v32, v32, v136
	v_mul_f32_e64 v33, v33, v137
	v_mul_f32_e64 v34, v34, v138
	v_mul_f32_e64 v35, v35, v139
	s_waitcnt vmcnt(0)
; DI void store4(u16* dst, f32x4 v) { uint2 w; w.x = cvtpk(v[0], v[1]); w.y = cvtpk(v[2], v[3]); *(uint2*)dst = w; }
; DI void phase9(const Params& p, const Sched& sched, unsigned char* smem) {
;     ...
; #pragma unroll
;       for (int mi = 0; mi < 4; ++mi) {
;         const int f = fb + mi * 16 + lq * 4; const float4 gm = *(const float4*)(mod + (size_t)b * 6144 + 5120 + f);
; #pragma unroll
;         for (int ni = 0; ni < 8; ++ni) {
;           const f32x4 o = {gm.x * acc[mi][ni][0], gm.y * acc[mi][ni][1], gm.z * acc[mi][ni][2], gm.w * acc[mi][ni][3]};
;           store4(Ls + (wt * 128 + ni * 16 + lr) * EST + wf * 64 + mi * 16 + lq * 4, o);
;         }
;       }
;       __syncthreads();
	v_mul_f32_e64 v0, v0, v140
	v_mul_f32_e64 v1, v1, v141
	v_mul_f32_e64 v2, v2, v142
	v_mul_f32_e64 v3, v3, v143
	v_cvt_pk_bf16_f32 v32, v32, v33
	v_cvt_pk_bf16_f32 v33, v34, v35
	v_cvt_pk_bf16_f32 v0, v0, v1
	v_cvt_pk_bf16_f32 v1, v2, v3
	v_mul_f32_e64 v34, v36, v136
	v_mul_f32_e64 v35, v37, v137
	v_mul_f32_e64 v36, v38, v138
	v_mul_f32_e64 v37, v39, v139
	ds_write2_b64 v144, v[32:33], v[0:1] offset0:8 offset1:12
	v_mul_f32_e64 v0, v4, v140
	v_mul_f32_e64 v1, v5, v141
	v_mul_f32_e64 v2, v6, v142
	v_mul_f32_e64 v3, v7, v143
	v_cvt_pk_bf16_f32 v34, v34, v35
	v_cvt_pk_bf16_f32 v35, v36, v37
	v_cvt_pk_bf16_f32 v0, v0, v1
	v_cvt_pk_bf16_f32 v1, v2, v3
	v_mul_f32_e64 v36, v40, v136
	v_mul_f32_e64 v37, v41, v137
	v_mul_f32_e64 v38, v42, v138
	v_mul_f32_e64 v39, v43, v139
	ds_write2_b64 v145, v[34:35], v[0:1] offset0:40 offset1:44
	v_mul_f32_e64 v0, v8, v140
	v_mul_f32_e64 v1, v9, v141
	v_mul_f32_e64 v2, v10, v142
	v_mul_f32_e64 v3, v11, v143
	v_cvt_pk_bf16_f32 v36, v36, v37
	v_cvt_pk_bf16_f32 v37, v38, v39
	v_cvt_pk_bf16_f32 v0, v0, v1
	v_cvt_pk_bf16_f32 v1, v2, v3
	v_mul_f32_e64 v38, v44, v136
	v_mul_f32_e64 v39, v45, v137
	v_mul_f32_e64 v40, v46, v138
	v_mul_f32_e64 v41, v47, v139
	ds_write2_b64 v146, v[36:37], v[0:1] offset0:72 offset1:76
	v_mul_f32_e64 v0, v12, v140
	v_mul_f32_e64 v1, v13, v141
	v_mul_f32_e64 v2, v14, v142
	v_mul_f32_e64 v3, v15, v143
	v_cvt_pk_bf16_f32 v38, v38, v39
	v_cvt_pk_bf16_f32 v39, v40, v41
	v_cvt_pk_bf16_f32 v0, v0, v1
	v_cvt_pk_bf16_f32 v1, v2, v3
	v_mul_f32_e64 v98, v98, v130
	v_mul_f32_e64 v99, v99, v131
	v_mul_f32_e64 v64, v64, v132
	v_mul_f32_e64 v65, v65, v133
	v_mul_f32_e64 v66, v66, v134
	v_mul_f32_e64 v67, v67, v135
	v_mul_f32_e64 v76, v76, v132
	v_mul_f32_e64 v77, v77, v133
	v_mul_f32_e64 v78, v78, v134
	v_mul_f32_e64 v79, v79, v135
	v_mul_f32_e64 v40, v48, v136
	v_mul_f32_e64 v41, v49, v137
	v_mul_f32_e64 v42, v50, v138
	v_mul_f32_e64 v43, v51, v139
	ds_write2_b64 v147, v[38:39], v[0:1] offset0:104 offset1:108
	v_mul_f32_e64 v0, v16, v140
	v_mul_f32_e64 v1, v17, v141
	v_mul_f32_e64 v2, v18, v142
	v_mul_f32_e64 v3, v19, v143
	v_cvt_pk_bf16_f32 v88, v88, v89
	v_cvt_pk_bf16_f32 v89, v90, v91
	v_cvt_pk_bf16_f32 v90, v96, v97
	v_cvt_pk_bf16_f32 v91, v98, v99
	v_cvt_pk_bf16_f32 v64, v64, v65
	v_cvt_pk_bf16_f32 v65, v66, v67
	v_cvt_pk_bf16_f32 v66, v76, v77
	v_cvt_pk_bf16_f32 v67, v78, v79
	v_cvt_pk_bf16_f32 v40, v40, v41
	v_cvt_pk_bf16_f32 v41, v42, v43
	v_cvt_pk_bf16_f32 v0, v0, v1
	v_cvt_pk_bf16_f32 v1, v2, v3
	v_mul_f32_e64 v106, v106, v130
	v_mul_f32_e64 v107, v107, v131
	v_mul_f32_e64 v116, v116, v128
	v_mul_f32_e64 v117, v117, v129
	v_mul_f32_e64 v118, v118, v130
	v_mul_f32_e64 v119, v119, v131
	ds_write2_b64 v144, v[88:89], v[64:65] offset1:4
	ds_write2_b64 v145, v[90:91], v[66:67] offset0:32 offset1:36
	v_mul_f32_e64 v64, v68, v132
	v_mul_f32_e64 v65, v69, v133
	v_mul_f32_e64 v66, v70, v134
	v_mul_f32_e64 v67, v71, v135
	v_mul_f32_e64 v42, v52, v136
	v_mul_f32_e64 v43, v53, v137
	v_mul_f32_e64 v44, v54, v138
	v_mul_f32_e64 v45, v55, v139
	ds_write2_b64 v148, v[40:41], v[0:1] offset0:136 offset1:140
	v_mul_f32_e64 v0, v20, v140
	v_mul_f32_e64 v1, v21, v141
	v_mul_f32_e64 v2, v22, v142
	v_mul_f32_e64 v3, v23, v143
	v_cvt_pk_bf16_f32 v97, v106, v107
	v_cvt_pk_bf16_f32 v106, v116, v117
	v_cvt_pk_bf16_f32 v107, v118, v119
	v_cvt_pk_bf16_f32 v64, v64, v65
	v_cvt_pk_bf16_f32 v65, v66, v67
	v_add_u32_e32 v68, 0x5000, v144
	v_cvt_pk_bf16_f32 v42, v42, v43
	v_cvt_pk_bf16_f32 v43, v44, v45
	v_cvt_pk_bf16_f32 v0, v0, v1
	v_cvt_pk_bf16_f32 v1, v2, v3
	v_mul_f32_e64 v108, v108, v128
	v_mul_f32_e64 v109, v109, v129
	v_mul_f32_e64 v120, v120, v128
	v_mul_f32_e64 v121, v121, v129
	v_mul_f32_e64 v122, v122, v130
	v_mul_f32_e64 v123, v123, v131
	ds_write2_b64 v68, v[106:107], v[64:65] offset0:160 offset1:164
	v_mul_f32_e64 v64, v80, v132
	v_mul_f32_e64 v65, v81, v133
	v_mul_f32_e64 v66, v82, v134
	v_mul_f32_e64 v67, v83, v135
	v_mul_f32_e64 v44, v56, v136
	v_mul_f32_e64 v45, v57, v137
	v_mul_f32_e64 v46, v58, v138
	v_mul_f32_e64 v47, v59, v139
	ds_write2_b64 v68, v[42:43], v[0:1] offset0:168 offset1:172
	v_mul_f32_e64 v0, v24, v140
	v_mul_f32_e64 v1, v25, v141
	v_mul_f32_e64 v2, v26, v142
	v_mul_f32_e64 v3, v27, v143
	v_cvt_pk_bf16_f32 v98, v108, v109
	v_cvt_pk_bf16_f32 v108, v120, v121
	v_cvt_pk_bf16_f32 v109, v122, v123
	v_cvt_pk_bf16_f32 v64, v64, v65
	v_cvt_pk_bf16_f32 v65, v66, v67
	v_add_u32_e32 v69, 0x6000, v144
	v_cvt_pk_bf16_f32 v44, v44, v45
	v_cvt_pk_bf16_f32 v45, v46, v47
	v_cvt_pk_bf16_f32 v0, v0, v1
	v_cvt_pk_bf16_f32 v1, v2, v3
	v_mul_f32_e64 v104, v104, v128
	v_mul_f32_e64 v105, v105, v129
	v_mul_f32_e64 v110, v110, v130
	v_mul_f32_e64 v111, v111, v131
	v_mul_f32_e64 v112, v112, v128
	v_mul_f32_e64 v113, v113, v129
	v_mul_f32_e64 v114, v114, v130
	v_mul_f32_e64 v115, v115, v131
	v_mul_f32_e64 v124, v124, v128
	v_mul_f32_e64 v125, v125, v129
	v_mul_f32_e64 v126, v126, v130
	v_mul_f32_e64 v127, v127, v131
	v_mul_f32_e64 v84, v84, v132
	v_mul_f32_e64 v85, v85, v133
	v_mul_f32_e64 v86, v86, v134
	v_mul_f32_e64 v87, v87, v135
	v_mul_f32_e64 v92, v92, v132
	v_mul_f32_e64 v93, v93, v133
	v_mul_f32_e64 v94, v94, v134
	v_mul_f32_e64 v95, v95, v135
	v_mul_f32_e64 v100, v100, v132
	v_mul_f32_e64 v101, v101, v133
	v_mul_f32_e64 v102, v102, v134
	v_mul_f32_e64 v103, v103, v135
	ds_write2_b64 v69, v[108:109], v[64:65] offset0:192 offset1:196
	v_mul_f32_e64 v64, v72, v132
	v_mul_f32_e64 v65, v73, v133
	v_mul_f32_e64 v66, v74, v134
	v_mul_f32_e64 v67, v75, v135
	v_mul_f32_e64 v46, v60, v136
	v_mul_f32_e64 v47, v61, v137
	v_mul_f32_e64 v48, v62, v138
	v_mul_f32_e64 v49, v63, v139
	ds_write2_b64 v69, v[44:45], v[0:1] offset0:200 offset1:204
	v_mul_f32_e64 v0, v28, v140
	v_mul_f32_e64 v1, v29, v141
	v_mul_f32_e64 v2, v30, v142
	v_mul_f32_e64 v3, v31, v143
	v_cvt_pk_bf16_f32 v96, v104, v105
	v_cvt_pk_bf16_f32 v99, v110, v111
	v_cvt_pk_bf16_f32 v104, v112, v113
	v_cvt_pk_bf16_f32 v105, v114, v115
	v_cvt_pk_bf16_f32 v110, v124, v125
	v_cvt_pk_bf16_f32 v111, v126, v127
	v_cvt_pk_bf16_f32 v76, v84, v85
	v_cvt_pk_bf16_f32 v77, v86, v87
	v_cvt_pk_bf16_f32 v78, v92, v93
	v_cvt_pk_bf16_f32 v79, v94, v95
	v_cvt_pk_bf16_f32 v84, v100, v101
	v_cvt_pk_bf16_f32 v85, v102, v103
	v_cvt_pk_bf16_f32 v64, v64, v65
	v_cvt_pk_bf16_f32 v65, v66, v67
	v_add_u32_e32 v66, 0x7000, v144
	v_cvt_pk_bf16_f32 v46, v46, v47
	v_cvt_pk_bf16_f32 v47, v48, v49
	v_cvt_pk_bf16_f32 v0, v0, v1
	v_cvt_pk_bf16_f32 v1, v2, v3
	v_mov_b32_e32 v2, v218
	ds_write2_b64 v146, v[96:97], v[76:77] offset0:64 offset1:68
	ds_write2_b64 v147, v[98:99], v[78:79] offset0:96 offset1:100
	ds_write2_b64 v148, v[104:105], v[84:85] offset0:128 offset1:132
	ds_write2_b64 v66, v[110:111], v[64:65] offset0:224 offset1:228
	ds_write2_b64 v66, v[46:47], v[0:1] offset0:232 offset1:236
	s_waitcnt lgkmcnt(0)
	s_barrier
; DI int tidx() { int t = __builtin_amdgcn_workitem_id_x(); asm volatile("" : "+v"(t)); return t; }
; DI unsigned cvtpk(float lo, float hi) { const f32x2_ v = {lo, hi}; return __builtin_bit_cast(unsigned, __builtin_convertvector(v, bf16x2_)); }
; DI float bflo(unsigned w) { return __uint_as_float(w << 16); }
; DI float bfhi(unsigned w) { return __uint_as_float(w & 0xffff0000u); }
; DI void phase9(const Params& p, const Sched& sched, unsigned char* smem) {
;     ...
;       const int tid = tidx();
; #pragma unroll
;       for (int i = 0; i < 16; ++i) {
;         const int c = tid + 256 * i, row = c >> 4, ch = (c & 15) * 8;
;         const size_t gi = (size_t)(tm * 256 + row) * 1024 + tn * 128 + ch;
;         const u32x4 sv = *(const u32x4*)(Ls + row * EST + ch), xv = *(const u32x4*)(x1b + gi);
;         u32x4 w;
;         w.x = cvtpk(bflo(xv.x) + bflo(sv.x), bfhi(xv.x) + bfhi(sv.x)); w.y = cvtpk(bflo(xv.y) + bflo(sv.y), bfhi(xv.y) + bfhi(sv.y));
;         w.z = cvtpk(bflo(xv.z) + bflo(sv.z), bfhi(xv.z) + bfhi(sv.z)); w.w = cvtpk(bflo(xv.w) + bflo(sv.w), bfhi(xv.w) + bfhi(sv.w));
;         *(u32x4*)(x2b + gi) = w;
;       }
	s_nop 0
	v_ashrrev_i32_e32 v3, 4, v2
	v_add_u32_e32 v4, s29, v3
	v_lshlrev_b32_e32 v0, 3, v2
	v_ashrrev_i32_e32 v5, 31, v4
	v_and_b32_e32 v1, 0x78, v0
	v_lshlrev_b64 v[4:5], 10, v[4:5]
	v_or3_b32 v4, v4, s30, v1
	v_lshlrev_b64 v[12:13], 1, v[4:5]
	v_lshl_add_u64 v[4:5], s[12:13], 0, v[12:13]
	global_load_dwordx4 v[4:7], v[4:5], off
	v_lshlrev_b32_e32 v0, 1, v1
	v_mad_u64_u32 v[8:9], s[34:35], v3, s25, v[0:1]
	ds_read_b128 v[8:11], v8
	v_add_u32_e32 v3, 0x100, v2
	v_ashrrev_i32_e32 v3, 4, v3
	s_waitcnt lgkmcnt(0)
	v_lshlrev_b32_e32 v16, 16, v8
	v_and_b32_e32 v17, 0xffff0000, v8
	v_lshlrev_b32_e32 v8, 16, v9
	v_and_b32_e32 v9, 0xffff0000, v9
	s_waitcnt vmcnt(0)
	v_lshlrev_b32_e32 v14, 16, v4
	v_and_b32_e32 v15, 0xffff0000, v4
	v_add_f32_e64 v14, v16, v14
	v_add_f32_e64 v15, v17, v15
	s_nop 0
	v_cvt_pk_bf16_f32 v4, v14, v15
	v_lshlrev_b32_e32 v14, 16, v5
	v_and_b32_e32 v15, 0xffff0000, v5
	v_add_f32_e64 v8, v8, v14
	v_add_f32_e64 v9, v9, v15
	v_lshlrev_b32_e32 v14, 16, v10
	v_cvt_pk_bf16_f32 v5, v8, v9
	v_lshlrev_b32_e32 v8, 16, v6
	v_and_b32_e32 v9, 0xffff0000, v6
	v_and_b32_e32 v15, 0xffff0000, v10
	v_add_f32_e64 v8, v14, v8
	v_add_f32_e64 v9, v15, v9
	v_lshlrev_b32_e32 v10, 16, v11
	v_cvt_pk_bf16_f32 v6, v8, v9
	v_lshlrev_b32_e32 v8, 16, v7
	v_and_b32_e32 v9, 0xffff0000, v7
	v_and_b32_e32 v11, 0xffff0000, v11
	v_add_f32_e64 v8, v10, v8
	v_add_f32_e64 v9, v11, v9
	s_nop 0
	v_cvt_pk_bf16_f32 v7, v8, v9
	v_lshl_add_u64 v[8:9], s[2:3], 0, v[12:13]
	global_store_dwordx4 v[8:9], v[4:7], off
	v_mad_u64_u32 v[8:9], s[34:35], v3, s25, v[0:1]
	s_nop 0
	v_add_u32_e32 v4, s29, v3
	v_ashrrev_i32_e32 v5, 31, v4
	v_lshlrev_b64 v[4:5], 10, v[4:5]
	v_or3_b32 v4, v4, s30, v1
	v_lshlrev_b64 v[12:13], 1, v[4:5]
	v_lshl_add_u64 v[4:5], s[12:13], 0, v[12:13]
	global_load_dwordx4 v[4:7], v[4:5], off
	ds_read_b128 v[8:11], v8
	v_add_u32_e32 v3, 0x200, v2
	v_ashrrev_i32_e32 v3, 4, v3
	v_lshl_add_u64 v[12:13], s[2:3], 0, v[12:13]
	s_waitcnt lgkmcnt(0)
	v_lshlrev_b32_e32 v14, 16, v8
	v_and_b32_e32 v15, 0xffff0000, v8
	v_lshlrev_b32_e32 v8, 16, v9
	v_and_b32_e32 v9, 0xffff0000, v9
	v_lshlrev_b32_e32 v16, 16, v10
	v_and_b32_e32 v17, 0xffff0000, v10
	v_lshlrev_b32_e32 v10, 16, v11
	v_and_b32_e32 v11, 0xffff0000, v11
	s_waitcnt vmcnt(0)
	v_lshlrev_b32_e32 v18, 16, v4
	v_and_b32_e32 v19, 0xffff0000, v4
	v_lshlrev_b32_e32 v4, 16, v5
	v_and_b32_e32 v5, 0xffff0000, v5
	v_lshlrev_b32_e32 v20, 16, v6
	v_and_b32_e32 v21, 0xffff0000, v6
	v_lshlrev_b32_e32 v6, 16, v7
	v_and_b32_e32 v7, 0xffff0000, v7
	v_add_f32_e64 v14, v14, v18
	v_add_f32_e64 v15, v15, v19
	v_add_f32_e64 v8, v8, v4
	v_add_f32_e64 v9, v9, v5
	v_add_f32_e64 v16, v16, v20
	v_add_f32_e64 v17, v17, v21
	v_add_f32_e64 v10, v10, v6
	v_add_f32_e64 v11, v11, v7
	v_cvt_pk_bf16_f32 v4, v14, v15
	v_cvt_pk_bf16_f32 v5, v8, v9
	v_cvt_pk_bf16_f32 v6, v16, v17
	v_cvt_pk_bf16_f32 v7, v10, v11
	global_store_dwordx4 v[12:13], v[4:7], off
	v_add_u32_e32 v8, 0x300, v2
	v_ashrrev_i32_e32 v26, 4, v8
	v_add_u32_e32 v4, s29, v3
	v_ashrrev_i32_e32 v5, 31, v4
	v_lshlrev_b64 v[4:5], 10, v[4:5]
	v_or3_b32 v4, v4, s30, v1
	v_lshlrev_b64 v[12:13], 1, v[4:5]
	v_lshl_add_u64 v[4:5], s[12:13], 0, v[12:13]
	global_load_dwordx4 v[4:7], v[4:5], off
	v_mad_u64_u32 v[8:9], s[34:35], v3, s25, v[0:1]
	ds_read_b128 v[8:11], v8
	v_add_u32_e32 v14, s29, v26
	v_ashrrev_i32_e32 v15, 31, v14
	v_lshlrev_b64 v[14:15], 10, v[14:15]
	v_or3_b32 v14, v14, s30, v1
	s_waitcnt lgkmcnt(0)
	v_lshlrev_b32_e32 v18, 16, v8
	v_and_b32_e32 v19, 0xffff0000, v8
	v_lshlrev_b32_e32 v8, 16, v9
	v_and_b32_e32 v9, 0xffff0000, v9
	v_lshlrev_b32_e32 v20, 16, v10
	v_and_b32_e32 v21, 0xffff0000, v10
	v_lshlrev_b32_e32 v10, 16, v11
	v_and_b32_e32 v11, 0xffff0000, v11
	v_lshlrev_b64 v[14:15], 1, v[14:15]
	v_lshl_add_u64 v[12:13], s[2:3], 0, v[12:13]
	v_lshl_add_u64 v[16:17], s[12:13], 0, v[14:15]
	v_add_u32_e32 v3, 0x400, v2
	v_ashrrev_i32_e32 v3, 4, v3
	v_lshl_add_u64 v[14:15], s[2:3], 0, v[14:15]
	s_waitcnt vmcnt(0)
	v_lshlrev_b32_e32 v22, 16, v4
	v_and_b32_e32 v23, 0xffff0000, v4
	v_lshlrev_b32_e32 v4, 16, v5
	v_and_b32_e32 v5, 0xffff0000, v5
	v_lshlrev_b32_e32 v24, 16, v6
	v_and_b32_e32 v25, 0xffff0000, v6
	v_lshlrev_b32_e32 v6, 16, v7
	v_and_b32_e32 v7, 0xffff0000, v7
	v_add_f32_e64 v18, v18, v22
	v_add_f32_e64 v19, v19, v23
	v_add_f32_e64 v8, v8, v4
	v_add_f32_e64 v9, v9, v5
	v_add_f32_e64 v20, v20, v24
	v_add_f32_e64 v21, v21, v25
	v_add_f32_e64 v10, v10, v6
	v_add_f32_e64 v11, v11, v7
	v_cvt_pk_bf16_f32 v4, v18, v19
	v_cvt_pk_bf16_f32 v5, v8, v9
	v_cvt_pk_bf16_f32 v6, v20, v21
	v_cvt_pk_bf16_f32 v7, v10, v11
	global_store_dwordx4 v[12:13], v[4:7], off
	global_load_dwordx4 v[4:7], v[16:17], off
	v_mad_u64_u32 v[8:9], s[34:35], v26, s25, v[0:1]
	ds_read_b128 v[8:11], v8
	v_add_u32_e32 v12, s29, v3
	v_ashrrev_i32_e32 v13, 31, v12
	v_lshlrev_b64 v[12:13], 10, v[12:13]
	v_or3_b32 v12, v12, s30, v1
	s_waitcnt lgkmcnt(0)
	v_lshlrev_b32_e32 v18, 16, v8
	v_and_b32_e32 v19, 0xffff0000, v8
	v_lshlrev_b32_e32 v8, 16, v9
	v_and_b32_e32 v9, 0xffff0000, v9
	v_lshlrev_b32_e32 v20, 16, v10
	v_and_b32_e32 v21, 0xffff0000, v10
	v_lshlrev_b32_e32 v10, 16, v11
	v_and_b32_e32 v11, 0xffff0000, v11
	v_lshlrev_b64 v[12:13], 1, v[12:13]
	v_lshl_add_u64 v[16:17], s[12:13], 0, v[12:13]
	v_lshl_add_u64 v[12:13], s[2:3], 0, v[12:13]
	s_waitcnt vmcnt(0)
; DI int tidx() { int t = __builtin_amdgcn_workitem_id_x(); asm volatile("" : "+v"(t)); return t; }
; DI unsigned cvtpk(float lo, float hi) { const f32x2_ v = {lo, hi}; return __builtin_bit_cast(unsigned, __builtin_convertvector(v, bf16x2_)); }
; DI float bflo(unsigned w) { return __uint_as_float(w << 16); }
; DI float bfhi(unsigned w) { return __uint_as_float(w & 0xffff0000u); }
; DI void phase9(const Params& p, const Sched& sched, unsigned char* smem) {
;     ...
;       const int tid = tidx();
; #pragma unroll
;       for (int i = 0; i < 16; ++i) {
;         const int c = tid + 256 * i, row = c >> 4, ch = (c & 15) * 8;
;         const size_t gi = (size_t)(tm * 256 + row) * 1024 + tn * 128 + ch;
;         const u32x4 sv = *(const u32x4*)(Ls + row * EST + ch), xv = *(const u32x4*)(x1b + gi);
;         u32x4 w;
;         w.x = cvtpk(bflo(xv.x) + bflo(sv.x), bfhi(xv.x) + bfhi(sv.x)); w.y = cvtpk(bflo(xv.y) + bflo(sv.y), bfhi(xv.y) + bfhi(sv.y));
;         w.z = cvtpk(bflo(xv.z) + bflo(sv.z), bfhi(xv.z) + bfhi(sv.z)); w.w = cvtpk(bflo(xv.w) + bflo(sv.w), bfhi(xv.w) + bfhi(sv.w));
;         *(u32x4*)(x2b + gi) = w;
;       }
	v_lshlrev_b32_e32 v22, 16, v4
	v_and_b32_e32 v23, 0xffff0000, v4
	v_lshlrev_b32_e32 v4, 16, v5
	v_and_b32_e32 v5, 0xffff0000, v5
	v_lshlrev_b32_e32 v24, 16, v6
	v_and_b32_e32 v25, 0xffff0000, v6
	v_lshlrev_b32_e32 v6, 16, v7
	v_and_b32_e32 v7, 0xffff0000, v7
	v_add_f32_e64 v18, v18, v22
	v_add_f32_e64 v19, v19, v23
	v_add_f32_e64 v8, v8, v4
	v_add_f32_e64 v9, v9, v5
	v_add_f32_e64 v20, v20, v24
	v_add_f32_e64 v21, v21, v25
	v_add_f32_e64 v10, v10, v6
	v_add_f32_e64 v11, v11, v7
	v_cvt_pk_bf16_f32 v4, v18, v19
	v_cvt_pk_bf16_f32 v5, v8, v9
	v_cvt_pk_bf16_f32 v6, v20, v21
	v_cvt_pk_bf16_f32 v7, v10, v11
	global_store_dwordx4 v[14:15], v[4:7], off
	global_load_dwordx4 v[4:7], v[16:17], off
	v_add_u32_e32 v8, 0x500, v2
	v_ashrrev_i32_e32 v26, 4, v8
	v_mad_u64_u32 v[8:9], s[34:35], v3, s25, v[0:1]
	ds_read_b128 v[8:11], v8
	v_add_u32_e32 v14, s29, v26
	v_ashrrev_i32_e32 v15, 31, v14
	v_lshlrev_b64 v[14:15], 10, v[14:15]
	v_or3_b32 v14, v14, s30, v1
	s_waitcnt lgkmcnt(0)
	v_lshlrev_b32_e32 v18, 16, v8
	v_and_b32_e32 v19, 0xffff0000, v8
	v_lshlrev_b32_e32 v8, 16, v9
	v_and_b32_e32 v9, 0xffff0000, v9
	v_lshlrev_b32_e32 v20, 16, v10
	v_and_b32_e32 v21, 0xffff0000, v10
	v_lshlrev_b32_e32 v10, 16, v11
	v_and_b32_e32 v11, 0xffff0000, v11
	v_lshlrev_b64 v[14:15], 1, v[14:15]
	v_lshl_add_u64 v[16:17], s[12:13], 0, v[14:15]
	v_add_u32_e32 v3, 0x600, v2
	v_ashrrev_i32_e32 v3, 4, v3
	v_lshl_add_u64 v[14:15], s[2:3], 0, v[14:15]
	s_waitcnt vmcnt(0)
	v_lshlrev_b32_e32 v22, 16, v4
	v_and_b32_e32 v23, 0xffff0000, v4
	v_lshlrev_b32_e32 v4, 16, v5
	v_and_b32_e32 v5, 0xffff0000, v5
	v_lshlrev_b32_e32 v24, 16, v6
	v_and_b32_e32 v25, 0xffff0000, v6
	v_lshlrev_b32_e32 v6, 16, v7
	v_and_b32_e32 v7, 0xffff0000, v7
	v_add_f32_e64 v18, v18, v22
	v_add_f32_e64 v19, v19, v23
	v_add_f32_e64 v8, v8, v4
	v_add_f32_e64 v9, v9, v5
	v_add_f32_e64 v20, v20, v24
	v_add_f32_e64 v21, v21, v25
	v_add_f32_e64 v10, v10, v6
	v_add_f32_e64 v11, v11, v7
	v_cvt_pk_bf16_f32 v4, v18, v19
	v_cvt_pk_bf16_f32 v5, v8, v9
	v_cvt_pk_bf16_f32 v6, v20, v21
	v_cvt_pk_bf16_f32 v7, v10, v11
	global_store_dwordx4 v[12:13], v[4:7], off
	global_load_dwordx4 v[4:7], v[16:17], off
	v_mad_u64_u32 v[8:9], s[34:35], v26, s25, v[0:1]
	ds_read_b128 v[8:11], v8
	v_add_u32_e32 v12, s29, v3
	v_ashrrev_i32_e32 v13, 31, v12
	v_lshlrev_b64 v[12:13], 10, v[12:13]
	v_or3_b32 v12, v12, s30, v1
	s_waitcnt lgkmcnt(0)
	v_lshlrev_b32_e32 v18, 16, v8
	v_and_b32_e32 v19, 0xffff0000, v8
	v_lshlrev_b32_e32 v8, 16, v9
	v_and_b32_e32 v9, 0xffff0000, v9
	v_lshlrev_b32_e32 v20, 16, v10
	v_and_b32_e32 v21, 0xffff0000, v10
	v_lshlrev_b32_e32 v10, 16, v11
	v_and_b32_e32 v11, 0xffff0000, v11
	v_lshlrev_b64 v[12:13], 1, v[12:13]
	v_lshl_add_u64 v[16:17], s[12:13], 0, v[12:13]
	v_lshl_add_u64 v[12:13], s[2:3], 0, v[12:13]
	s_waitcnt vmcnt(0)
	v_lshlrev_b32_e32 v22, 16, v4
	v_and_b32_e32 v23, 0xffff0000, v4
	v_lshlrev_b32_e32 v4, 16, v5
	v_and_b32_e32 v5, 0xffff0000, v5
	v_lshlrev_b32_e32 v24, 16, v6
	v_and_b32_e32 v25, 0xffff0000, v6
	v_lshlrev_b32_e32 v6, 16, v7
	v_and_b32_e32 v7, 0xffff0000, v7
	v_add_f32_e64 v18, v18, v22
	v_add_f32_e64 v19, v19, v23
	v_add_f32_e64 v8, v8, v4
	v_add_f32_e64 v9, v9, v5
	v_add_f32_e64 v20, v20, v24
	v_add_f32_e64 v21, v21, v25
	v_add_f32_e64 v10, v10, v6
	v_add_f32_e64 v11, v11, v7
	v_cvt_pk_bf16_f32 v4, v18, v19
	v_cvt_pk_bf16_f32 v5, v8, v9
	v_cvt_pk_bf16_f32 v6, v20, v21
	v_cvt_pk_bf16_f32 v7, v10, v11
	global_store_dwordx4 v[14:15], v[4:7], off
	global_load_dwordx4 v[4:7], v[16:17], off
	v_add_u32_e32 v8, 0x700, v2
	v_ashrrev_i32_e32 v26, 4, v8
	v_mad_u64_u32 v[8:9], s[34:35], v3, s25, v[0:1]
	ds_read_b128 v[8:11], v8
	v_add_u32_e32 v14, s29, v26
	v_ashrrev_i32_e32 v15, 31, v14
	v_lshlrev_b64 v[14:15], 10, v[14:15]
	v_or3_b32 v14, v14, s30, v1
	s_waitcnt lgkmcnt(0)
	v_lshlrev_b32_e32 v18, 16, v8
	v_and_b32_e32 v19, 0xffff0000, v8
	v_lshlrev_b32_e32 v8, 16, v9
	v_and_b32_e32 v9, 0xffff0000, v9
	v_lshlrev_b32_e32 v20, 16, v10
	v_and_b32_e32 v21, 0xffff0000, v10
	v_lshlrev_b32_e32 v10, 16, v11
	v_and_b32_e32 v11, 0xffff0000, v11
	v_lshlrev_b64 v[14:15], 1, v[14:15]
	v_lshl_add_u64 v[16:17], s[12:13], 0, v[14:15]
	v_add_u32_e32 v3, 0x800, v2
	v_ashrrev_i32_e32 v3, 4, v3
	v_lshl_add_u64 v[14:15], s[2:3], 0, v[14:15]
	s_waitcnt vmcnt(0)
	v_lshlrev_b32_e32 v22, 16, v4
	v_and_b32_e32 v23, 0xffff0000, v4
	v_lshlrev_b32_e32 v4, 16, v5
	v_and_b32_e32 v5, 0xffff0000, v5
	v_lshlrev_b32_e32 v24, 16, v6
	v_and_b32_e32 v25, 0xffff0000, v6
	v_lshlrev_b32_e32 v6, 16, v7
	v_and_b32_e32 v7, 0xffff0000, v7
	v_add_f32_e64 v18, v18, v22
	v_add_f32_e64 v19, v19, v23
	v_add_f32_e64 v8, v8, v4
	v_add_f32_e64 v9, v9, v5
	v_add_f32_e64 v20, v20, v24
	v_add_f32_e64 v21, v21, v25
	v_add_f32_e64 v10, v10, v6
	v_add_f32_e64 v11, v11, v7
	v_cvt_pk_bf16_f32 v4, v18, v19
	v_cvt_pk_bf16_f32 v5, v8, v9
	v_cvt_pk_bf16_f32 v6, v20, v21
	v_cvt_pk_bf16_f32 v7, v10, v11
	global_store_dwordx4 v[12:13], v[4:7], off
	global_load_dwordx4 v[4:7], v[16:17], off
	v_mad_u64_u32 v[8:9], s[34:35], v26, s25, v[0:1]
	ds_read_b128 v[8:11], v8
	v_add_u32_e32 v12, s29, v3
	v_ashrrev_i32_e32 v13, 31, v12
	v_lshlrev_b64 v[12:13], 10, v[12:13]
	v_or3_b32 v12, v12, s30, v1
	s_waitcnt lgkmcnt(0)
	v_lshlrev_b32_e32 v18, 16, v8
	v_and_b32_e32 v19, 0xffff0000, v8
	v_lshlrev_b32_e32 v8, 16, v9
	v_and_b32_e32 v9, 0xffff0000, v9
	v_lshlrev_b32_e32 v20, 16, v10
	v_and_b32_e32 v21, 0xffff0000, v10
	v_lshlrev_b32_e32 v10, 16, v11
	v_and_b32_e32 v11, 0xffff0000, v11
	v_lshlrev_b64 v[12:13], 1, v[12:13]
	v_lshl_add_u64 v[16:17], s[12:13], 0, v[12:13]
	v_lshl_add_u64 v[12:13], s[2:3], 0, v[12:13]
	s_waitcnt vmcnt(0)
; DI int tidx() { int t = __builtin_amdgcn_workitem_id_x(); asm volatile("" : "+v"(t)); return t; }
; DI unsigned cvtpk(float lo, float hi) { const f32x2_ v = {lo, hi}; return __builtin_bit_cast(unsigned, __builtin_convertvector(v, bf16x2_)); }
; DI float bflo(unsigned w) { return __uint_as_float(w << 16); }
; DI float bfhi(unsigned w) { return __uint_as_float(w & 0xffff0000u); }
; DI void phase9(const Params& p, const Sched& sched, unsigned char* smem) {
;     ...
;       const int tid = tidx();
; #pragma unroll
;       for (int i = 0; i < 16; ++i) {
;         const int c = tid + 256 * i, row = c >> 4, ch = (c & 15) * 8;
;         const size_t gi = (size_t)(tm * 256 + row) * 1024 + tn * 128 + ch;
;         const u32x4 sv = *(const u32x4*)(Ls + row * EST + ch), xv = *(const u32x4*)(x1b + gi);
;         u32x4 w;
;         w.x = cvtpk(bflo(xv.x) + bflo(sv.x), bfhi(xv.x) + bfhi(sv.x)); w.y = cvtpk(bflo(xv.y) + bflo(sv.y), bfhi(xv.y) + bfhi(sv.y));
;         w.z = cvtpk(bflo(xv.z) + bflo(sv.z), bfhi(xv.z) + bfhi(sv.z)); w.w = cvtpk(bflo(xv.w) + bflo(sv.w), bfhi(xv.w) + bfhi(sv.w));
;         *(u32x4*)(x2b + gi) = w;
;       }
	v_lshlrev_b32_e32 v22, 16, v4
	v_and_b32_e32 v23, 0xffff0000, v4
	v_lshlrev_b32_e32 v4, 16, v5
	v_and_b32_e32 v5, 0xffff0000, v5
	v_lshlrev_b32_e32 v24, 16, v6
	v_and_b32_e32 v25, 0xffff0000, v6
	v_lshlrev_b32_e32 v6, 16, v7
	v_and_b32_e32 v7, 0xffff0000, v7
	v_add_f32_e64 v18, v18, v22
	v_add_f32_e64 v19, v19, v23
	v_add_f32_e64 v8, v8, v4
	v_add_f32_e64 v9, v9, v5
	v_add_f32_e64 v20, v20, v24
	v_add_f32_e64 v21, v21, v25
	v_add_f32_e64 v10, v10, v6
	v_add_f32_e64 v11, v11, v7
	v_cvt_pk_bf16_f32 v4, v18, v19
	v_cvt_pk_bf16_f32 v5, v8, v9
	v_cvt_pk_bf16_f32 v6, v20, v21
	v_cvt_pk_bf16_f32 v7, v10, v11
	global_store_dwordx4 v[14:15], v[4:7], off
	global_load_dwordx4 v[4:7], v[16:17], off
	v_add_u32_e32 v8, 0x900, v2
	v_ashrrev_i32_e32 v26, 4, v8
	v_mad_u64_u32 v[8:9], s[34:35], v3, s25, v[0:1]
	ds_read_b128 v[8:11], v8
	v_add_u32_e32 v14, s29, v26
	v_ashrrev_i32_e32 v15, 31, v14
	v_lshlrev_b64 v[14:15], 10, v[14:15]
	v_or3_b32 v14, v14, s30, v1
	s_waitcnt lgkmcnt(0)
	v_lshlrev_b32_e32 v18, 16, v8
	v_and_b32_e32 v19, 0xffff0000, v8
	v_lshlrev_b32_e32 v8, 16, v9
	v_and_b32_e32 v9, 0xffff0000, v9
	v_lshlrev_b32_e32 v20, 16, v10
	v_and_b32_e32 v21, 0xffff0000, v10
	v_lshlrev_b32_e32 v10, 16, v11
	v_and_b32_e32 v11, 0xffff0000, v11
	v_lshlrev_b64 v[14:15], 1, v[14:15]
	v_lshl_add_u64 v[16:17], s[12:13], 0, v[14:15]
	v_add_u32_e32 v3, 0xa00, v2
	v_ashrrev_i32_e32 v3, 4, v3
	v_lshl_add_u64 v[14:15], s[2:3], 0, v[14:15]
	s_waitcnt vmcnt(0)
	v_lshlrev_b32_e32 v22, 16, v4
	v_and_b32_e32 v23, 0xffff0000, v4
	v_lshlrev_b32_e32 v4, 16, v5
	v_and_b32_e32 v5, 0xffff0000, v5
	v_lshlrev_b32_e32 v24, 16, v6
	v_and_b32_e32 v25, 0xffff0000, v6
	v_lshlrev_b32_e32 v6, 16, v7
	v_and_b32_e32 v7, 0xffff0000, v7
	v_add_f32_e64 v18, v18, v22
	v_add_f32_e64 v19, v19, v23
	v_add_f32_e64 v8, v8, v4
	v_add_f32_e64 v9, v9, v5
	v_add_f32_e64 v20, v20, v24
	v_add_f32_e64 v21, v21, v25
	v_add_f32_e64 v10, v10, v6
	v_add_f32_e64 v11, v11, v7
	v_cvt_pk_bf16_f32 v4, v18, v19
	v_cvt_pk_bf16_f32 v5, v8, v9
	v_cvt_pk_bf16_f32 v6, v20, v21
	v_cvt_pk_bf16_f32 v7, v10, v11
	global_store_dwordx4 v[12:13], v[4:7], off
	global_load_dwordx4 v[4:7], v[16:17], off
	v_mad_u64_u32 v[8:9], s[34:35], v26, s25, v[0:1]
	ds_read_b128 v[8:11], v8
	v_add_u32_e32 v12, s29, v3
	v_ashrrev_i32_e32 v13, 31, v12
	v_lshlrev_b64 v[12:13], 10, v[12:13]
	v_or3_b32 v12, v12, s30, v1
	s_waitcnt lgkmcnt(0)
	v_lshlrev_b32_e32 v18, 16, v8
	v_and_b32_e32 v19, 0xffff0000, v8
	v_lshlrev_b32_e32 v8, 16, v9
	v_and_b32_e32 v9, 0xffff0000, v9
	v_lshlrev_b32_e32 v20, 16, v10
	v_and_b32_e32 v21, 0xffff0000, v10
	v_lshlrev_b32_e32 v10, 16, v11
	v_and_b32_e32 v11, 0xffff0000, v11
	v_lshlrev_b64 v[12:13], 1, v[12:13]
	v_lshl_add_u64 v[16:17], s[12:13], 0, v[12:13]
	v_lshl_add_u64 v[12:13], s[2:3], 0, v[12:13]
	s_waitcnt vmcnt(0)
	v_lshlrev_b32_e32 v22, 16, v4
	v_and_b32_e32 v23, 0xffff0000, v4
	v_lshlrev_b32_e32 v4, 16, v5
	v_and_b32_e32 v5, 0xffff0000, v5
	v_lshlrev_b32_e32 v24, 16, v6
	v_and_b32_e32 v25, 0xffff0000, v6
	v_lshlrev_b32_e32 v6, 16, v7
	v_and_b32_e32 v7, 0xffff0000, v7
	v_add_f32_e64 v18, v18, v22
	v_add_f32_e64 v19, v19, v23
	v_add_f32_e64 v8, v8, v4
	v_add_f32_e64 v9, v9, v5
	v_add_f32_e64 v20, v20, v24
	v_add_f32_e64 v21, v21, v25
	v_add_f32_e64 v10, v10, v6
	v_add_f32_e64 v11, v11, v7
	v_cvt_pk_bf16_f32 v4, v18, v19
	v_cvt_pk_bf16_f32 v5, v8, v9
	v_cvt_pk_bf16_f32 v6, v20, v21
	v_cvt_pk_bf16_f32 v7, v10, v11
	global_store_dwordx4 v[14:15], v[4:7], off
	global_load_dwordx4 v[4:7], v[16:17], off
	v_add_u32_e32 v8, 0xb00, v2
	v_ashrrev_i32_e32 v26, 4, v8
	v_mad_u64_u32 v[8:9], s[34:35], v3, s25, v[0:1]
	ds_read_b128 v[8:11], v8
	v_add_u32_e32 v14, s29, v26
	v_ashrrev_i32_e32 v15, 31, v14
	v_lshlrev_b64 v[14:15], 10, v[14:15]
	v_or3_b32 v14, v14, s30, v1
	s_waitcnt lgkmcnt(0)
	v_lshlrev_b32_e32 v18, 16, v8
	v_and_b32_e32 v19, 0xffff0000, v8
	v_lshlrev_b32_e32 v8, 16, v9
	v_and_b32_e32 v9, 0xffff0000, v9
	v_lshlrev_b32_e32 v20, 16, v10
	v_and_b32_e32 v21, 0xffff0000, v10
	v_lshlrev_b32_e32 v10, 16, v11
	v_and_b32_e32 v11, 0xffff0000, v11
	v_lshlrev_b64 v[14:15], 1, v[14:15]
	v_lshl_add_u64 v[16:17], s[12:13], 0, v[14:15]
	v_add_u32_e32 v3, 0xc00, v2
	v_ashrrev_i32_e32 v3, 4, v3
	v_lshl_add_u64 v[14:15], s[2:3], 0, v[14:15]
	s_waitcnt vmcnt(0)
	v_lshlrev_b32_e32 v22, 16, v4
	v_and_b32_e32 v23, 0xffff0000, v4
	v_lshlrev_b32_e32 v4, 16, v5
	v_and_b32_e32 v5, 0xffff0000, v5
	v_lshlrev_b32_e32 v24, 16, v6
	v_and_b32_e32 v25, 0xffff0000, v6
	v_lshlrev_b32_e32 v6, 16, v7
	v_and_b32_e32 v7, 0xffff0000, v7
	v_add_f32_e64 v18, v18, v22
	v_add_f32_e64 v19, v19, v23
	v_add_f32_e64 v8, v8, v4
	v_add_f32_e64 v9, v9, v5
	v_add_f32_e64 v20, v20, v24
	v_add_f32_e64 v21, v21, v25
	v_add_f32_e64 v10, v10, v6
	v_add_f32_e64 v11, v11, v7
	v_cvt_pk_bf16_f32 v4, v18, v19
	v_cvt_pk_bf16_f32 v5, v8, v9
	v_cvt_pk_bf16_f32 v6, v20, v21
	v_cvt_pk_bf16_f32 v7, v10, v11
	global_store_dwordx4 v[12:13], v[4:7], off
	global_load_dwordx4 v[4:7], v[16:17], off
	v_mad_u64_u32 v[8:9], s[34:35], v26, s25, v[0:1]
	ds_read_b128 v[8:11], v8
	v_add_u32_e32 v12, s29, v3
	v_ashrrev_i32_e32 v13, 31, v12
	v_lshlrev_b64 v[12:13], 10, v[12:13]
	v_or3_b32 v12, v12, s30, v1
	s_waitcnt lgkmcnt(0)
	v_lshlrev_b32_e32 v18, 16, v8
	v_and_b32_e32 v19, 0xffff0000, v8
	v_lshlrev_b32_e32 v8, 16, v9
	v_and_b32_e32 v9, 0xffff0000, v9
	v_lshlrev_b32_e32 v20, 16, v10
	v_and_b32_e32 v21, 0xffff0000, v10
	v_lshlrev_b32_e32 v10, 16, v11
	v_and_b32_e32 v11, 0xffff0000, v11
	v_lshlrev_b64 v[12:13], 1, v[12:13]
	v_lshl_add_u64 v[16:17], s[12:13], 0, v[12:13]
	v_lshl_add_u64 v[12:13], s[2:3], 0, v[12:13]
	s_waitcnt vmcnt(0)
; DI int tidx() { int t = __builtin_amdgcn_workitem_id_x(); asm volatile("" : "+v"(t)); return t; }
; DI unsigned cvtpk(float lo, float hi) { const f32x2_ v = {lo, hi}; return __builtin_bit_cast(unsigned, __builtin_convertvector(v, bf16x2_)); }
; DI float bflo(unsigned w) { return __uint_as_float(w << 16); }
; DI float bfhi(unsigned w) { return __uint_as_float(w & 0xffff0000u); }
; DI void phase9(const Params& p, const Sched& sched, unsigned char* smem) {
;     ...
;       const int tid = tidx();
; #pragma unroll
;       for (int i = 0; i < 16; ++i) {
;         const int c = tid + 256 * i, row = c >> 4, ch = (c & 15) * 8;
;         const size_t gi = (size_t)(tm * 256 + row) * 1024 + tn * 128 + ch;
;         const u32x4 sv = *(const u32x4*)(Ls + row * EST + ch), xv = *(const u32x4*)(x1b + gi);
;         u32x4 w;
;         w.x = cvtpk(bflo(xv.x) + bflo(sv.x), bfhi(xv.x) + bfhi(sv.x)); w.y = cvtpk(bflo(xv.y) + bflo(sv.y), bfhi(xv.y) + bfhi(sv.y));
;         w.z = cvtpk(bflo(xv.z) + bflo(sv.z), bfhi(xv.z) + bfhi(sv.z)); w.w = cvtpk(bflo(xv.w) + bflo(sv.w), bfhi(xv.w) + bfhi(sv.w));
;         *(u32x4*)(x2b + gi) = w;
;       }
	v_lshlrev_b32_e32 v22, 16, v4
	v_and_b32_e32 v23, 0xffff0000, v4
	v_lshlrev_b32_e32 v4, 16, v5
	v_and_b32_e32 v5, 0xffff0000, v5
	v_lshlrev_b32_e32 v24, 16, v6
	v_and_b32_e32 v25, 0xffff0000, v6
	v_lshlrev_b32_e32 v6, 16, v7
	v_and_b32_e32 v7, 0xffff0000, v7
	v_add_f32_e64 v18, v18, v22
	v_add_f32_e64 v19, v19, v23
	v_add_f32_e64 v8, v8, v4
	v_add_f32_e64 v9, v9, v5
	v_add_f32_e64 v20, v20, v24
	v_add_f32_e64 v21, v21, v25
	v_add_f32_e64 v10, v10, v6
	v_add_f32_e64 v11, v11, v7
	v_cvt_pk_bf16_f32 v4, v18, v19
	v_cvt_pk_bf16_f32 v5, v8, v9
	v_cvt_pk_bf16_f32 v6, v20, v21
	v_cvt_pk_bf16_f32 v7, v10, v11
	global_store_dwordx4 v[14:15], v[4:7], off
	global_load_dwordx4 v[4:7], v[16:17], off
	v_add_u32_e32 v8, 0xd00, v2
	v_ashrrev_i32_e32 v26, 4, v8
	v_mad_u64_u32 v[8:9], s[34:35], v3, s25, v[0:1]
	ds_read_b128 v[8:11], v8
	v_add_u32_e32 v14, s29, v26
	v_ashrrev_i32_e32 v15, 31, v14
	v_lshlrev_b64 v[14:15], 10, v[14:15]
	v_or3_b32 v14, v14, s30, v1
	s_waitcnt lgkmcnt(0)
	v_lshlrev_b32_e32 v18, 16, v8
	v_and_b32_e32 v19, 0xffff0000, v8
	v_lshlrev_b32_e32 v8, 16, v9
	v_and_b32_e32 v9, 0xffff0000, v9
	v_lshlrev_b32_e32 v20, 16, v10
	v_and_b32_e32 v21, 0xffff0000, v10
	v_lshlrev_b32_e32 v10, 16, v11
	v_and_b32_e32 v11, 0xffff0000, v11
	v_lshlrev_b64 v[14:15], 1, v[14:15]
	v_lshl_add_u64 v[16:17], s[12:13], 0, v[14:15]
	v_add_u32_e32 v3, 0xe00, v2
	v_ashrrev_i32_e32 v3, 4, v3
	v_lshl_add_u64 v[14:15], s[2:3], 0, v[14:15]
	v_add_u32_e32 v2, 0xf00, v2
	s_waitcnt vmcnt(0)
	v_lshlrev_b32_e32 v22, 16, v4
	v_and_b32_e32 v23, 0xffff0000, v4
	v_lshlrev_b32_e32 v4, 16, v5
	v_and_b32_e32 v5, 0xffff0000, v5
	v_lshlrev_b32_e32 v24, 16, v6
	v_and_b32_e32 v25, 0xffff0000, v6
	v_lshlrev_b32_e32 v6, 16, v7
	v_and_b32_e32 v7, 0xffff0000, v7
	v_add_f32_e64 v18, v18, v22
	v_add_f32_e64 v19, v19, v23
	v_add_f32_e64 v8, v8, v4
	v_add_f32_e64 v9, v9, v5
	v_add_f32_e64 v20, v20, v24
	v_add_f32_e64 v21, v21, v25
	v_add_f32_e64 v10, v10, v6
	v_add_f32_e64 v11, v11, v7
	v_cvt_pk_bf16_f32 v4, v18, v19
	v_cvt_pk_bf16_f32 v5, v8, v9
	v_cvt_pk_bf16_f32 v6, v20, v21
	v_cvt_pk_bf16_f32 v7, v10, v11
	global_store_dwordx4 v[12:13], v[4:7], off
	global_load_dwordx4 v[4:7], v[16:17], off
	v_mad_u64_u32 v[8:9], s[34:35], v26, s25, v[0:1]
	ds_read_b128 v[8:11], v8
	v_add_u32_e32 v12, s29, v3
	v_ashrrev_i32_e32 v13, 31, v12
	v_lshlrev_b64 v[12:13], 10, v[12:13]
	v_or3_b32 v12, v12, s30, v1
	s_waitcnt lgkmcnt(0)
	v_lshlrev_b32_e32 v18, 16, v8
	v_and_b32_e32 v19, 0xffff0000, v8
	v_lshlrev_b32_e32 v8, 16, v9
	v_and_b32_e32 v9, 0xffff0000, v9
	v_lshlrev_b32_e32 v20, 16, v10
	v_and_b32_e32 v21, 0xffff0000, v10
	v_lshlrev_b32_e32 v10, 16, v11
	v_and_b32_e32 v11, 0xffff0000, v11
	v_lshlrev_b64 v[12:13], 1, v[12:13]
	v_lshl_add_u64 v[16:17], s[12:13], 0, v[12:13]
	v_lshl_add_u64 v[12:13], s[2:3], 0, v[12:13]
	s_waitcnt vmcnt(0)
	v_lshlrev_b32_e32 v22, 16, v4
	v_and_b32_e32 v23, 0xffff0000, v4
	v_lshlrev_b32_e32 v4, 16, v5
	v_and_b32_e32 v5, 0xffff0000, v5
	v_lshlrev_b32_e32 v24, 16, v6
	v_and_b32_e32 v25, 0xffff0000, v6
	v_lshlrev_b32_e32 v6, 16, v7
	v_and_b32_e32 v7, 0xffff0000, v7
	v_add_f32_e64 v18, v18, v22
	v_add_f32_e64 v19, v19, v23
	v_add_f32_e64 v8, v8, v4
	v_add_f32_e64 v9, v9, v5
	v_add_f32_e64 v20, v20, v24
	v_add_f32_e64 v21, v21, v25
	v_add_f32_e64 v10, v10, v6
	v_add_f32_e64 v11, v11, v7
	v_cvt_pk_bf16_f32 v4, v18, v19
	v_cvt_pk_bf16_f32 v5, v8, v9
	v_cvt_pk_bf16_f32 v6, v20, v21
	v_cvt_pk_bf16_f32 v7, v10, v11
	global_store_dwordx4 v[14:15], v[4:7], off
	global_load_dwordx4 v[4:7], v[16:17], off
	v_mad_u64_u32 v[8:9], s[34:35], v3, s25, v[0:1]
	v_ashrrev_i32_e32 v24, 4, v2
	ds_read_b128 v[8:11], v8
	v_add_u32_e32 v2, s29, v24
	v_ashrrev_i32_e32 v3, 31, v2
	v_lshlrev_b64 v[2:3], 10, v[2:3]
	v_or3_b32 v2, v2, s30, v1
	v_lshlrev_b64 v[14:15], 1, v[2:3]
	s_waitcnt lgkmcnt(0)
	v_lshlrev_b32_e32 v2, 16, v8
	v_and_b32_e32 v3, 0xffff0000, v8
	v_lshlrev_b32_e32 v8, 16, v9
	v_and_b32_e32 v9, 0xffff0000, v9
	v_lshlrev_b32_e32 v18, 16, v10
	v_and_b32_e32 v19, 0xffff0000, v10
	v_lshlrev_b32_e32 v10, 16, v11
	v_and_b32_e32 v11, 0xffff0000, v11
	v_lshl_add_u64 v[16:17], s[12:13], 0, v[14:15]
	v_mad_u64_u32 v[0:1], s[30:31], v24, s25, v[0:1]
	s_waitcnt vmcnt(0)
	v_lshlrev_b32_e32 v20, 16, v4
	v_and_b32_e32 v21, 0xffff0000, v4
	v_lshlrev_b32_e32 v4, 16, v5
	v_and_b32_e32 v5, 0xffff0000, v5
	v_lshlrev_b32_e32 v22, 16, v6
	v_and_b32_e32 v23, 0xffff0000, v6
	v_lshlrev_b32_e32 v6, 16, v7
	v_and_b32_e32 v7, 0xffff0000, v7
	v_add_f32_e64 v2, v2, v20
	v_add_f32_e64 v3, v3, v21
	v_add_f32_e64 v4, v8, v4
	v_add_f32_e64 v5, v9, v5
	v_add_f32_e64 v8, v18, v22
	v_add_f32_e64 v9, v19, v23
	v_add_f32_e64 v6, v10, v6
	v_add_f32_e64 v7, v11, v7
	v_cvt_pk_bf16_f32 v2, v2, v3
	v_cvt_pk_bf16_f32 v3, v4, v5
	v_cvt_pk_bf16_f32 v4, v8, v9
	v_cvt_pk_bf16_f32 v5, v6, v7
	global_store_dwordx4 v[12:13], v[2:5], off
	global_load_dwordx4 v[2:5], v[16:17], off
	ds_read_b128 v[6:9], v0
	v_lshl_add_u64 v[10:11], s[2:3], 0, v[14:15]
	s_waitcnt lgkmcnt(0)
	v_lshlrev_b32_e32 v0, 16, v6
	v_and_b32_e32 v1, 0xffff0000, v6
	v_lshlrev_b32_e32 v6, 16, v7
	v_and_b32_e32 v7, 0xffff0000, v7
	v_lshlrev_b32_e32 v12, 16, v8
	v_and_b32_e32 v13, 0xffff0000, v8
	v_lshlrev_b32_e32 v8, 16, v9
	v_and_b32_e32 v9, 0xffff0000, v9
	s_waitcnt vmcnt(0)
	v_lshlrev_b32_e32 v14, 16, v2
	v_and_b32_e32 v15, 0xffff0000, v2
	v_lshlrev_b32_e32 v2, 16, v3
	v_and_b32_e32 v3, 0xffff0000, v3
	v_lshlrev_b32_e32 v16, 16, v4
	v_and_b32_e32 v17, 0xffff0000, v4
	v_lshlrev_b32_e32 v4, 16, v5
	v_and_b32_e32 v5, 0xffff0000, v5
	v_add_f32_e64 v0, v0, v14
	v_add_f32_e64 v1, v1, v15
	v_add_f32_e64 v2, v6, v2
	v_add_f32_e64 v3, v7, v3
	v_add_f32_e64 v6, v12, v16
	v_add_f32_e64 v7, v13, v17
	v_add_f32_e64 v4, v8, v4
	v_add_f32_e64 v5, v9, v5
	v_cvt_pk_bf16_f32 v0, v0, v1
	v_cvt_pk_bf16_f32 v1, v2, v3
	v_cvt_pk_bf16_f32 v2, v6, v7
	v_cvt_pk_bf16_f32 v3, v4, v5
	global_store_dwordx4 v[10:11], v[0:3], off
	s_cbranch_scc0 .LBB0_1094
	s_branch .LBB0_1091

; DI float bflo(unsigned w) { return __uint_as_float(w << 16); }
; DI float bfhi(unsigned w) { return __uint_as_float(w & 0xffff0000u); }
; DI void phase10(const Params& p, int bid, int nblk) {
;     ...
;   for (; row < Tn; row += step) {
;     if (row + step < Tn) ldrow(nxt, row + step);
;     f32x4 v[4]; float ss = 0.f;
; #pragma unroll
;     for (int i = 0; i < 4; ++i) { v[i] = (f32x4){bflo(cur[i].x), bfhi(cur[i].x), bflo(cur[i].y), bfhi(cur[i].y)}; ss += v[i][0] * v[i][0] + v[i][1] * v[i][1] + v[i][2] * v[i][2] + v[i][3] * v[i][3]; }
; #pragma unroll
;     for (int o = 32; o >= 1; o >>= 1) ss += __shfl_xor(ss, o);
;     const float rstd = rsqrtf(ss * (1.0f / 1024.0f) + 1e-6f);
;     f32x4* xr = (f32x4*)(p.out + (size_t)row * 1024);
; #pragma unroll
;     for (int i = 0; i < 4; ++i) xr[lane + 64 * i] = v[i] * rstd * g4[i];
; #pragma unroll
;     for (int i = 0; i < 4; ++i) cur[i] = nxt[i];
;   }
.LBB0_1151:
	s_or_b64 exec, exec, s[10:11]
	s_waitcnt vmcnt(2)
	v_and_b32_e32 v51, 0xffff0000, v34
	v_and_b32_e32 v47, 0xffff0000, v36
	v_lshlrev_b32_e32 v50, 16, v34
	v_mov_b32_e32 v46, v51
	s_waitcnt vmcnt(0)
	v_and_b32_e32 v63, 0xffff0000, v30
	v_lshlrev_b32_e32 v45, 16, v36
	v_lshlrev_b32_e32 v34, 16, v35
	v_mov_b32_e32 v44, v50
	v_mul_f32_e64 v52, v46, v46
	v_mul_f32_e64 v53, v47, v47
	v_and_b32_e32 v57, 0xffff0000, v32
	v_lshlrev_b32_e32 v62, 16, v30
	v_mov_b32_e32 v56, v63
	v_lshlrev_b32_e32 v49, 16, v37
	v_and_b32_e32 v35, 0xffff0000, v35
	v_fma_f32 v52, v44, v44, v52
	v_fma_f32 v53, v45, v45, v53
	v_mov_b32_e32 v48, v34
	v_lshlrev_b32_e32 v55, 16, v32
	v_lshlrev_b32_e32 v64, 16, v31
	v_and_b32_e32 v65, 0xffff0000, v31
	v_mov_b32_e32 v54, v62
	v_mul_f32_e64 v30, v56, v56
	v_mul_f32_e64 v31, v57, v57
	v_and_b32_e32 v37, 0xffff0000, v37
	v_fma_f32 v52, v48, v48, v52
	v_fma_f32 v53, v49, v49, v53
	v_mov_b32_e32 v36, v35
	v_lshlrev_b32_e32 v59, 16, v33
	v_fma_f32 v30, v54, v54, v30
	v_fma_f32 v31, v55, v55, v31
	v_mov_b32_e32 v58, v64
	v_fma_f32 v52, v36, v36, v52
	v_fma_f32 v53, v37, v37, v53
	v_and_b32_e32 v61, 0xffff0000, v33
	v_fma_f32 v30, v58, v58, v30
	v_fma_f32 v31, v59, v59, v31
	v_mov_b32_e32 v60, v65
	v_fma_f32 v30, v60, v60, v30
	v_fma_f32 v31, v61, v61, v31
	v_add_f32_e32 v32, v52, v53
	v_add_f32_e32 v31, v31, v32
	v_add_f32_e32 v30, v30, v31
	ds_bpermute_b32 v31, v17, v30
	v_mov_b32_e32 v46, v45
	v_mov_b32_e32 v36, v49
	v_mov_b32_e32 v56, v55
	v_mov_b32_e32 v60, v59
	s_waitcnt lgkmcnt(0)
	v_add_f32_e32 v30, v30, v31
	ds_bpermute_b32 v31, v38, v30
	s_and_b64 s[10:11], exec, vcc
	s_or_b64 s[8:9], s[10:11], s[8:9]
	v_lshl_add_u64 v[20:21], v[20:21], 0, s[6:7]
	s_waitcnt lgkmcnt(0)
	v_add_f32_e32 v30, v30, v31
	ds_bpermute_b32 v31, v39, v30
	s_waitcnt lgkmcnt(0)
	v_add_f32_e32 v30, v30, v31
	ds_bpermute_b32 v31, v40, v30
	s_waitcnt lgkmcnt(0)
	v_add_f32_e32 v30, v30, v31
	ds_bpermute_b32 v31, v41, v30
	s_waitcnt lgkmcnt(0)
	v_add_f32_e32 v30, v30, v31
	ds_bpermute_b32 v31, v42, v30
	s_waitcnt lgkmcnt(0)
	v_add_f32_e32 v30, v30, v31
	v_fmamk_f32 v30, v30, 0x3a800000, v43
	v_mul_f32_e32 v31, 0x4b800000, v30
	v_cmp_gt_f32_e64 s[0:1], s13, v30
	s_nop 1
	v_cndmask_b32_e64 v30, v30, v31, s[0:1]
	v_rsq_f32_e32 v30, v30
	s_nop 0
	v_mul_f32_e32 v31, 0x45800000, v30
	v_cndmask_b32_e64 v44, v30, v31, s[0:1]
	v_mul_f32_e64 v30, v44, v46
	v_mul_f32_e64 v31, v44, v47
	v_mul_f32_e64 v32, v44, v36
	v_mul_f32_e64 v33, v44, v37
	v_mul_f32_e64 v32, v2, v32
	v_mul_f32_e64 v33, v3, v33
	v_mul_f32_e64 v30, v0, v30
	v_mul_f32_e64 v31, v1, v31
	global_store_dwordx4 v[18:19], v[30:33], off
	v_mov_b64_e32 v[36:37], v[28:29]
	s_nop 0
	v_mul_f32_e64 v30, v44, v50
	v_mul_f32_e64 v31, v44, v51
	v_mul_f32_e64 v32, v44, v34
	v_mul_f32_e64 v33, v44, v35
	v_mul_f32_e64 v32, v6, v32
	v_mul_f32_e64 v33, v7, v33
	v_mul_f32_e64 v30, v4, v30
	v_mul_f32_e64 v31, v5, v31
	global_store_dwordx4 v[18:19], v[30:33], off offset:1024
	v_mov_b64_e32 v[34:35], v[26:27]
	s_nop 0
	v_mul_f32_e64 v30, v44, v56
	v_mul_f32_e64 v31, v44, v57
	v_mul_f32_e64 v32, v44, v60
	v_mul_f32_e64 v33, v44, v61
	v_mul_f32_e64 v32, v10, v32
	v_mul_f32_e64 v33, v11, v33
	v_mul_f32_e64 v30, v8, v30
	v_mul_f32_e64 v31, v9, v31
	global_store_dwordx4 v[18:19], v[30:33], off offset:2048
	s_nop 1
	v_mul_f32_e64 v30, v44, v62
	v_mul_f32_e64 v31, v44, v63
	v_mul_f32_e64 v32, v44, v64
	v_mul_f32_e64 v33, v44, v65
	v_mul_f32_e64 v32, v14, v32
	v_mul_f32_e64 v33, v15, v33
	v_mul_f32_e64 v30, v12, v30
	v_mul_f32_e64 v31, v13, v31
	global_store_dwordx4 v[18:19], v[30:33], off offset:3072
	v_lshl_add_u64 v[18:19], v[18:19], 0, s[4:5]
	s_nop 0
	v_mov_b64_e32 v[30:31], v[22:23]
	v_mov_b64_e32 v[32:33], v[24:25]
	s_andn2_b64 exec, exec, s[8:9]
	s_cbranch_execz .LBB0_1154
